# v-phase token groups of 4 (8 slice passes instead of 16), single norm register set, 3 tail tokens
# baseline (speedup 1.0000x reference)
; __device__ __forceinline__ void peer_v_tokens(int j, const LAS unsigned short* EL, const LAS unsigned char* AL  , const LAS float* ASC  , const LAS int* SAL  , ...
;     ...
;     const int BUF[3] = {vslot(3 * wave), vslot(3 * wave + 1), vslot(3 * wave + 2)};
;     const int g = lane >> 3, j8 = lane & 7, s16 = lane & 15, grp = lane >> 4;
;     *(LAS unsigned long long*)(ldsb + BUF[0] + 8 * s16) = 0xFEDCBA9876543210ull;
;     CFENCE();
;     const v2i cal = TR4(ldsb + BUF[0] + 8 * s16);
;     const int pc = cal.x & 15;
;     asm volatile("s_waitcnt lgkmcnt(0)" ::: "memory");
;     const unsigned cx0 = 16u * (unsigned)(j8 ^ (g >> 1)), cx1 = 16u * (unsigned)(j8 ^ (4 + (g >> 1)));
;     const int fr = (4 * (s16 >> 3) + ((s16 & 7) >> 1)) & 7;
;     int roff[4];
; #pragma unroll
;     for (int r = 0; r < 4; ++r) roff[r] = 128 * s16 + 16 * ((((grp >> 1) + 2 * r)) ^ fr) + 8 * (grp & 1);
;     ...
; #pragma unroll 1
;     for (int it = 0; it < 8; ++it) {
;         const int tl = it * 8 + wave, t = j * 64 + tl;
;         unsigned E[8];
;         { const LAS v4u* ep = (const LAS v4u*)(EL + tl * 128 + 16 * g); const v4u e0 = ep[0], e1 = ep[1];
;           E[0] = e0.x; E[1] = e0.y; E[2] = e0.z; E[3] = e0.w; E[4] = e1.x; E[5] = e1.y; E[6] = e1.z; E[7] = e1.w; }
;         uint2 hv[4]; float4 gv[4];
;         { unsigned ho = (unsigned)t * (D / 4) + (unsigned)lane; asm volatile("" : "+v"(ho)); const uint2* hp = (const uint2*)HB + ho; const float4* gp = (const float4*)fng + lane;
; #pragma unroll
;           for (int jq = 0; jq < 4; ++jq) { hv[jq] = hp[64 * jq]; gv[jq] = gp[64 * jq]; } }
;         VDMA(0, 0); VDMA(1, 1);
; #pragma unroll
;         for (int m = 0; m < 2; ++m) {
;             const int idx = lane + 64 * m, tau = idx >> 4, sr = idx & 15, k = 16 * (sr & 7) + 2 * tau + (sr >> 3);
;             const int aq = (int)*(const LAS signed char*)(AL + tl * 128 + k); const int tq = aq + 8;
;             const unsigned lo = (((unsigned)tq & 15u) ^ 8u) * 0x11111111u, hi = ((unsigned)(tq >> 4) & 15u) * 0x11111111u;
;             typedef unsigned u2v __attribute__((ext_vector_type(2)));
;             u2v l2; l2.x = lo; l2.y = lo; u2v h2; h2.x = hi; h2.y = hi;
;             *(LAS u2v*)(ATL + 8 * idx) = l2; *(LAS u2v*)(ATL + 1024 + 8 * idx) = h2;
;         }
;         const float asc = ASC[tl]; const int sa = SAL[tl];
;         CFENCE();
;         int accH[4], accL[4];
; #pragma unroll
.LBB0_691:
	s_or_b64 exec, exec, s[10:11]
	v_mov_b32_e32 v18, v1
	s_waitcnt lgkmcnt(0)
	s_barrier
	v_readlane_b32 s70, v235, 50
	v_and_b32_e32 v19, 15, v18
	v_lshlrev_b32_e32 v58, 3, v19
	v_add_u32_e32 v20, s60, v58
	ds_write_b64 v20, v[84:85]
	v_lshrrev_b32_e32 v23, 1, v18
	v_ashrrev_i32_e32 v24, 5, v18
	v_and_b32_e32 v25, 8, v23
	ds_read_b64_tr_b4 v[20:21], v20
	v_lshl_or_b32 v19, v19, 7, v25
	v_bitop3_b32 v25, v23, v24, 7 bitop3:0x6c
	v_lshl_add_u32 v59, v25, 4, v19
	v_add_u32_e32 v25, 2, v24
	v_bitop3_b32 v25, v25, v23, 7 bitop3:0x78
	v_lshl_add_u32 v60, v25, 4, v19
	v_add_u32_e32 v25, 4, v24
	v_add_u32_e32 v24, 6, v24
	s_waitcnt lgkmcnt(0)
	v_ashrrev_i32_e32 v21, 4, v18
	v_bitop3_b32 v25, v25, v23, 7 bitop3:0x78
	v_bitop3_b32 v23, v24, v23, 7 bitop3:0x78
	v_bitop3_b32 v22, v18, v21, 7 bitop3:0x6c
	v_add_u32_e32 v21, 4, v21
	v_lshl_add_u32 v61, v25, 4, v19
	v_lshl_add_u32 v62, v23, 4, v19
	v_and_b32_e32 v19, 15, v20
	v_bitop3_b32 v21, v21, v18, 7 bitop3:0x78
	v_lshlrev_b32_e32 v63, 4, v22
	v_lshlrev_b32_e32 v22, 1, v19
	v_ashrrev_i32_e32 v19, 31, v18
	v_lshlrev_b32_e32 v64, 4, v21
	v_lshlrev_b64 v[20:21], 4, v[18:19]
	v_and_b32_e32 v25, 0x7ffffff0, v18
	v_lshl_add_u64 v[34:35], s[86:87], 0, v[20:21]
	v_lshlrev_b32_e32 v19, 4, v18
	v_lshlrev_b32_e32 v25, 1, v25
	v_lshl_add_u64 v[36:37], s[88:89], 0, v[20:21]
	v_add_u32_e32 v21, 64, v18
	s_waitcnt lgkmcnt(0)
	v_and_b32_e32 v19, 0x70, v19
	v_add3_u32 v65, s58, v22, v25
	v_ashrrev_i32_e32 v20, 3, v18
	v_ashrrev_i32_e32 v22, 3, v21
	v_lshrrev_b32_e32 v23, 3, v18
	v_bfe_u32 v24, v18, 3, 1
	v_and_b32_e32 v20, -2, v20
	v_and_b32_e32 v22, -2, v22
	v_lshlrev_b32_e32 v21, 3, v21
	v_add_u32_e32 v19, s72, v19
	v_lshlrev_b32_e32 v66, 3, v18
	v_add_u32_e32 v67, 0x200000, v63
	v_add_u32_e32 v68, 0x200000, v64
	v_add_u32_e32 v69, 0x400000, v63
	v_add_u32_e32 v70, 0x400000, v64
	v_add_u32_e32 v71, 0x600000, v63
	v_add_u32_e32 v72, 0x600000, v64
	v_add3_u32 v73, v19, v22, v24
	v_add3_u32 v74, v19, v20, v24
	v_lshl_add_u32 v75, v23, 5, s65
	v_add_u32_e32 v76, s73, v18
	s_mov_b32 s12, 0
	v_add_u32_e32 v77, s59, v21
	s_mov_b32 s13, s67
	v_readlane_b32 s71, v235, 51
	s_mov_b32 s76, s60
	s_add_i32 s77, s60, 0x800
	s_mov_b32 s78, s61
	s_add_i32 s79, s61, 0x800
	s_mov_b32 s98, s62
	s_add_i32 s99, s62, 0x800
	v_add_u32_e32 v159, s59, v66
	v_add_u32_e32 v160, s59, v58
	v_add_u32_e32 v154, s58, v66
	v_add_u32_e32 v227, 0x12000, v75
	v_lshlrev_b32_e32 v138, 1, v66
	v_add_u32_e32 v155, 0x11200, v138
	v_add_u32_e32 v156, 0x27400, v138
	global_load_dwordx4 v[210:213], v[34:35], off
	global_load_dwordx4 v[214:217], v[34:35], off offset:1024
	global_load_dwordx4 v[218:221], v[34:35], off offset:2048
	global_load_dwordx4 v[222:225], v[34:35], off offset:3072
	ds_read_b128 v[18:21], v227
	ds_read_b128 v[22:25], v227 offset:16
	v_mov_b32_e32 v138, v74
	ds_read_u8 v139, v138
	v_mov_b32_e32 v141, v73
	ds_read_u8 v140, v141
	v_mov_b32_e32 v150, v63
	v_mov_b32_e32 v151, v64
	s_waitcnt lgkmcnt(0)
	v_and_b32_e32 v78, 0xffff, v18
	v_lshrrev_b32_e32 v79, 16, v18
	v_lshl_add_u32 v78, v78, 7, v150
	v_lshl_add_u32 v79, v79, 7, v151
	s_mov_b32 m0, s76
	s_add_i32 s43, s76, 0x400
	global_load_lds_dwordx4 v78, s[50:51]
	s_mov_b32 m0, s43
	s_nop 0
	global_load_lds_dwordx4 v79, s[50:51]
	v_and_b32_e32 v78, 0xffff, v19
	v_lshrrev_b32_e32 v79, 16, v19
	v_lshl_add_u32 v78, v78, 7, v150
	v_lshl_add_u32 v79, v79, 7, v151
	s_mov_b32 m0, s77
	s_add_i32 s43, s77, 0x400
	global_load_lds_dwordx4 v78, s[50:51]
	s_mov_b32 m0, s43
	s_nop 0
	global_load_lds_dwordx4 v79, s[50:51]
	v_and_b32_e32 v78, 0xffff, v20
	v_lshrrev_b32_e32 v79, 16, v20
	v_lshl_add_u32 v78, v78, 7, v150
	v_lshl_add_u32 v79, v79, 7, v151
	s_mov_b32 m0, s78
	s_add_i32 s43, s78, 0x400
	global_load_lds_dwordx4 v78, s[50:51]
	s_mov_b32 m0, s43
	s_nop 0
	global_load_lds_dwordx4 v79, s[50:51]
	v_and_b32_e32 v78, 0xffff, v21
	v_lshrrev_b32_e32 v79, 16, v21
	v_lshl_add_u32 v78, v78, 7, v150
	v_lshl_add_u32 v79, v79, 7, v151
	s_mov_b32 m0, s79
	s_add_i32 s43, s79, 0x400
	global_load_lds_dwordx4 v78, s[50:51]
	s_mov_b32 m0, s43
	s_nop 0
	global_load_lds_dwordx4 v79, s[50:51]
	v_and_b32_e32 v78, 0xffff, v22
	v_lshrrev_b32_e32 v79, 16, v22
	v_lshl_add_u32 v78, v78, 7, v150
	v_lshl_add_u32 v79, v79, 7, v151
	s_mov_b32 m0, s98
	s_add_i32 s43, s98, 0x400
	global_load_lds_dwordx4 v78, s[50:51]
	s_mov_b32 m0, s43
	s_nop 0
	global_load_lds_dwordx4 v79, s[50:51]
	v_add_u32_e32 v143, 8, v139
	v_and_b32_e32 v142, 15, v143
	v_xor_b32_e32 v142, 8, v142
	v_bfe_u32 v144, v143, 4, 4
	v_mul_lo_u32 v142, v142, s92
	v_mul_lo_u32 v144, v144, s92
	v_mov_b32_e32 v143, v142
	v_mov_b32_e32 v145, v144
	ds_write2st64_b64 v159, v[142:143], v[144:145] offset1:2
	s_waitcnt vmcnt(10)
	ds_write_b128 v155, v[210:213]
	ds_write_b128 v155, v[214:217] offset:1024
	ds_write_b128 v156, v[218:221]
	ds_write_b128 v156, v[222:225] offset:1024
	s_waitcnt vmcnt(8)
	v_add_u32_e32 v54, s76, v59
	v_add_u32_e32 v55, s76, v60
	v_add_u32_e32 v56, s76, v61
	v_add_u32_e32 v57, s76, v62
	ds_read_b64_tr_b4 v[46:47], v160
	ds_read_b64_tr_b4 v[48:49], v160 offset:1024
	ds_read_b64_tr_b4 v[122:123], v54
	ds_read_b64_tr_b4 v[124:125], v55
	ds_read_b64_tr_b4 v[126:127], v56
	ds_read_b64_tr_b4 v[128:129], v57
	v_add_u32_e32 v147, 8, v140
	v_and_b32_e32 v146, 15, v147
	v_xor_b32_e32 v146, 8, v146
	v_bfe_u32 v148, v147, 4, 4
	v_mul_lo_u32 v146, v146, s92
	v_mul_lo_u32 v148, v148, s92
	v_mov_b32_e32 v147, v146
	v_mov_b32_e32 v149, v148
	ds_write2st64_b64 v77, v[146:147], v[148:149] offset1:2
	v_add_u32_e32 v138, 0x400, v74
	ds_read_u8 v139, v138
	v_add_u32_e32 v141, 0x400, v73
	ds_read_u8 v140, v141
	s_mov_b32 s43, s67
	v_mov_b32_e32 v138, s43
	ds_read2st64_b32 v[228:229], v138 offset1:1
	ds_read_b128 v[26:29], v227 offset:2048
	ds_read_b128 v[30:33], v227 offset:2064
	v_mov_b32_e32 v38, 0
	v_mov_b32_e32 v39, 0
	v_mov_b32_e32 v40, 0
	v_mov_b32_e32 v41, 0
	v_mov_b32_e32 v42, 0
	v_mov_b32_e32 v43, 0
	v_mov_b32_e32 v44, 0
	v_mov_b32_e32 v45, 0
	v_and_b32_e32 v78, 0xffff, v23
	v_lshrrev_b32_e32 v79, 16, v23
	v_lshl_add_u32 v78, v78, 7, v150
	v_lshl_add_u32 v79, v79, 7, v151
	s_mov_b32 m0, s99
	s_add_i32 s43, s99, 0x400
	global_load_lds_dwordx4 v78, s[50:51]
	s_mov_b32 m0, s43
	s_nop 0
	global_load_lds_dwordx4 v79, s[50:51]
	s_waitcnt vmcnt(8)
; #define TR4(p_) __builtin_amdgcn_ds_read_tr4_b64_v2i32((LAS v2i*)(p_))
; #define VDMA(st_, k_) do { _Pragma("unroll") for (int i_ = 0; i_ < 4; ++i_) { \
;         const unsigned off_ = (unsigned)((st_) >> 2) * (16384u * 128u) + (PE_ID(E, 4 * ((st_) & 3) + i_) << 7) + ((i_ & 1) ? cx1 : cx0); \
;         __builtin_amdgcn_global_load_lds((const unsigned*)(V4 + off_), (LAS unsigned*)(ldsb + BUF[k_] + 1024 * i_), 16, 0, 0); } } while (0)
; __device__ __forceinline__ void peer_v_tokens(int j, const LAS unsigned short* EL, const LAS unsigned char* AL  , const LAS float* ASC  , const LAS int* SAL  , ...
;     ...
;         for (int st = 0; st < 16; ++st) {
;             const int p = st >> 2, q = st & 3;
;             if (st < 14) VDMA(st + 2, (st + 2) % 3);
;             if (st < 14) asm volatile("s_waitcnt vmcnt(8)" ::: "memory");
;             else if (st == 14) asm volatile("s_waitcnt vmcnt(4)" ::: "memory");
;             else asm volatile("s_waitcnt vmcnt(0)" ::: "memory");
;             if (q == 0) {
; #pragma unroll
;                 for (int r = 0; r < 4; ++r) { accH[r] = 0; accL[r] = 0; } }
; #pragma unroll
;             for (int tp = 0; tp < 2; ++tp) {
;                 const v2i ao = TR4(ATL + (2 * q + tp) * 128 + 8 * s16), ah = TR4(ATL + 1024 + (2 * q + tp) * 128 + 8 * s16);
; #pragma unroll
;                 for (int r = 0; r < 4; ++r) {
;                     const v2i d = TR4(ldsb + BUF[st % 3] + 2048 * tp + roff[r]);
;                     accH[r] = __builtin_amdgcn_sdot8(d.x, ah.x, accH[r], false); accH[r] = __builtin_amdgcn_sdot8(d.y, ah.y, accH[r], false);
;                     accL[r] = __builtin_amdgcn_sdot8(d.x, ao.x, accL[r], false); accL[r] = __builtin_amdgcn_sdot8(d.y, ao.y, accL[r], false);
;                 }
;             }
	v_add_u32_e32 v54, s77, v59
	v_add_u32_e32 v55, s77, v60
	v_add_u32_e32 v56, s77, v61
	v_add_u32_e32 v57, s77, v62
	ds_read_b64_tr_b4 v[50:51], v160 offset:128
	ds_read_b64_tr_b4 v[52:53], v160 offset:1152
	ds_read_b64_tr_b4 v[130:131], v54
	ds_read_b64_tr_b4 v[132:133], v55
	ds_read_b64_tr_b4 v[134:135], v56
	ds_read_b64_tr_b4 v[136:137], v57
	s_waitcnt lgkmcnt(12)
	v_dot8c_i32_i4_e32 v38, v122, v48
	v_dot8c_i32_i4_e32 v39, v122, v46
	v_dot8c_i32_i4_e32 v40, v124, v48
	v_dot8c_i32_i4_e32 v41, v124, v46
	v_dot8c_i32_i4_e32 v42, v126, v48
	v_dot8c_i32_i4_e32 v43, v126, v46
	v_dot8c_i32_i4_e32 v44, v128, v48
	v_dot8c_i32_i4_e32 v45, v128, v46
	v_dot8c_i32_i4_e32 v38, v123, v49
	v_dot8c_i32_i4_e32 v39, v123, v47
	v_dot8c_i32_i4_e32 v40, v125, v49
	v_dot8c_i32_i4_e32 v41, v125, v47
	v_dot8c_i32_i4_e32 v42, v127, v49
	v_dot8c_i32_i4_e32 v43, v127, v47
	v_dot8c_i32_i4_e32 v44, v129, v49
	v_dot8c_i32_i4_e32 v45, v129, v47
	v_and_b32_e32 v78, 0xffff, v24
	v_lshrrev_b32_e32 v79, 16, v24
	v_lshl_add_u32 v78, v78, 7, v150
	v_lshl_add_u32 v79, v79, 7, v151
	s_mov_b32 m0, s76
	s_add_i32 s43, s76, 0x400
	global_load_lds_dwordx4 v78, s[50:51]
	s_mov_b32 m0, s43
	s_nop 0
	global_load_lds_dwordx4 v79, s[50:51]
	s_waitcnt vmcnt(8)
	v_add_u32_e32 v54, s78, v59
	v_add_u32_e32 v55, s78, v60
	v_add_u32_e32 v56, s78, v61
	v_add_u32_e32 v57, s78, v62
	ds_read_b64_tr_b4 v[46:47], v160 offset:256
	ds_read_b64_tr_b4 v[48:49], v160 offset:1280
	ds_read_b64_tr_b4 v[122:123], v54
	ds_read_b64_tr_b4 v[124:125], v55
	ds_read_b64_tr_b4 v[126:127], v56
	ds_read_b64_tr_b4 v[128:129], v57
	s_waitcnt lgkmcnt(6)
	v_dot8c_i32_i4_e32 v38, v130, v52
	v_dot8c_i32_i4_e32 v39, v130, v50
	v_dot8c_i32_i4_e32 v40, v132, v52
	v_dot8c_i32_i4_e32 v41, v132, v50
	v_dot8c_i32_i4_e32 v42, v134, v52
	v_dot8c_i32_i4_e32 v43, v134, v50
	v_dot8c_i32_i4_e32 v44, v136, v52
	v_dot8c_i32_i4_e32 v45, v136, v50
	v_dot8c_i32_i4_e32 v38, v131, v53
	v_dot8c_i32_i4_e32 v39, v131, v51
	v_dot8c_i32_i4_e32 v40, v133, v53
	v_dot8c_i32_i4_e32 v41, v133, v51
	v_dot8c_i32_i4_e32 v42, v135, v53
	v_dot8c_i32_i4_e32 v43, v135, v51
	v_dot8c_i32_i4_e32 v44, v137, v53
	v_dot8c_i32_i4_e32 v45, v137, v51
	v_and_b32_e32 v78, 0xffff, v25
	v_lshrrev_b32_e32 v79, 16, v25
	v_lshl_add_u32 v78, v78, 7, v150
	v_lshl_add_u32 v79, v79, 7, v151
	s_mov_b32 m0, s77
	s_add_i32 s43, s77, 0x400
	global_load_lds_dwordx4 v78, s[50:51]
	s_mov_b32 m0, s43
	s_nop 0
	global_load_lds_dwordx4 v79, s[50:51]
	s_waitcnt vmcnt(8)
	v_add_u32_e32 v54, s79, v59
	v_add_u32_e32 v55, s79, v60
	v_add_u32_e32 v56, s79, v61
	v_add_u32_e32 v57, s79, v62
	ds_read_b64_tr_b4 v[50:51], v160 offset:384
	ds_read_b64_tr_b4 v[52:53], v160 offset:1408
	ds_read_b64_tr_b4 v[130:131], v54
	ds_read_b64_tr_b4 v[132:133], v55
	ds_read_b64_tr_b4 v[134:135], v56
	ds_read_b64_tr_b4 v[136:137], v57
	s_waitcnt lgkmcnt(6)
	v_dot8c_i32_i4_e32 v38, v122, v48
	v_dot8c_i32_i4_e32 v39, v122, v46
	v_dot8c_i32_i4_e32 v40, v124, v48
	v_dot8c_i32_i4_e32 v41, v124, v46
	v_dot8c_i32_i4_e32 v42, v126, v48
	v_dot8c_i32_i4_e32 v43, v126, v46
	v_dot8c_i32_i4_e32 v44, v128, v48
	v_dot8c_i32_i4_e32 v45, v128, v46
	v_dot8c_i32_i4_e32 v38, v123, v49
	v_dot8c_i32_i4_e32 v39, v123, v47
	v_dot8c_i32_i4_e32 v40, v125, v49
	v_dot8c_i32_i4_e32 v41, v125, v47
	v_dot8c_i32_i4_e32 v42, v127, v49
	v_dot8c_i32_i4_e32 v43, v127, v47
	v_dot8c_i32_i4_e32 v44, v129, v49
	v_dot8c_i32_i4_e32 v45, v129, v47
	s_waitcnt lgkmcnt(15)
	v_and_b32_e32 v78, 0xffff, v26
	v_lshrrev_b32_e32 v79, 16, v26
	v_lshl_add_u32 v78, v78, 7, v150
	v_lshl_add_u32 v79, v79, 7, v151
	s_mov_b32 m0, s78
	s_add_i32 s43, s78, 0x400
	global_load_lds_dwordx4 v78, s[50:51]
	s_mov_b32 m0, s43
	s_nop 0
	global_load_lds_dwordx4 v79, s[50:51]
	s_waitcnt vmcnt(8)
	v_add_u32_e32 v54, s98, v59
	v_add_u32_e32 v55, s98, v60
	v_add_u32_e32 v56, s98, v61
	v_add_u32_e32 v57, s98, v62
	ds_read_b64_tr_b4 v[46:47], v160 offset:512
	ds_read_b64_tr_b4 v[48:49], v160 offset:1536
	ds_read_b64_tr_b4 v[122:123], v54
	ds_read_b64_tr_b4 v[124:125], v55
	ds_read_b64_tr_b4 v[126:127], v56
	ds_read_b64_tr_b4 v[128:129], v57
	s_waitcnt lgkmcnt(6)
	v_dot8c_i32_i4_e32 v38, v130, v52
	v_dot8c_i32_i4_e32 v39, v130, v50
	v_dot8c_i32_i4_e32 v40, v132, v52
	v_dot8c_i32_i4_e32 v41, v132, v50
	v_dot8c_i32_i4_e32 v42, v134, v52
	v_dot8c_i32_i4_e32 v43, v134, v50
	v_dot8c_i32_i4_e32 v44, v136, v52
	v_dot8c_i32_i4_e32 v45, v136, v50
	v_dot8c_i32_i4_e32 v38, v131, v53
	v_dot8c_i32_i4_e32 v39, v131, v51
	v_dot8c_i32_i4_e32 v40, v133, v53
	v_dot8c_i32_i4_e32 v41, v133, v51
	v_dot8c_i32_i4_e32 v42, v135, v53
	v_dot8c_i32_i4_e32 v43, v135, v51
	v_dot8c_i32_i4_e32 v44, v137, v53
	v_dot8c_i32_i4_e32 v45, v137, v51
	v_and_b32_e32 v78, 0xffff, v27
	v_lshrrev_b32_e32 v79, 16, v27
	v_lshl_add_u32 v78, v78, 7, v150
	v_lshl_add_u32 v79, v79, 7, v151
	s_mov_b32 m0, s79
	s_add_i32 s43, s79, 0x400
	global_load_lds_dwordx4 v78, s[50:51]
	s_mov_b32 m0, s43
	s_nop 0
	global_load_lds_dwordx4 v79, s[50:51]
	s_waitcnt vmcnt(8)
	v_add_u32_e32 v54, s99, v59
	v_add_u32_e32 v55, s99, v60
	v_add_u32_e32 v56, s99, v61
	v_add_u32_e32 v57, s99, v62
	ds_read_b64_tr_b4 v[50:51], v160 offset:640
	ds_read_b64_tr_b4 v[52:53], v160 offset:1664
	ds_read_b64_tr_b4 v[130:131], v54
	ds_read_b64_tr_b4 v[132:133], v55
	ds_read_b64_tr_b4 v[134:135], v56
	ds_read_b64_tr_b4 v[136:137], v57
	s_waitcnt lgkmcnt(6)
	v_dot8c_i32_i4_e32 v38, v122, v48
	v_dot8c_i32_i4_e32 v39, v122, v46
	v_dot8c_i32_i4_e32 v40, v124, v48
	v_dot8c_i32_i4_e32 v41, v124, v46
	v_dot8c_i32_i4_e32 v42, v126, v48
	v_dot8c_i32_i4_e32 v43, v126, v46
	v_dot8c_i32_i4_e32 v44, v128, v48
	v_dot8c_i32_i4_e32 v45, v128, v46
	v_dot8c_i32_i4_e32 v38, v123, v49
	v_dot8c_i32_i4_e32 v39, v123, v47
	v_dot8c_i32_i4_e32 v40, v125, v49
	v_dot8c_i32_i4_e32 v41, v125, v47
	v_dot8c_i32_i4_e32 v42, v127, v49
	v_dot8c_i32_i4_e32 v43, v127, v47
	v_dot8c_i32_i4_e32 v44, v129, v49
	v_dot8c_i32_i4_e32 v45, v129, v47
	s_waitcnt lgkmcnt(15)
; #define LAS __attribute__((address_space(3)))
; __device__ __forceinline__ bf16 f2bf(float f) { return (bf16)f2bfu(f); }
; __device__ __forceinline__ void peer_v_tokens(int j, const LAS unsigned short* EL, const LAS unsigned char* AL  , const LAS float* ASC  , const LAS int* SAL  , ...
;     ...
;             const int idx = lane + 64 * m, tau = idx >> 4, sr = idx & 15, k = 16 * (sr & 7) + 2 * tau + (sr >> 3);
;             const int aq = (int)*(const LAS signed char*)(AL + tl * 128 + k); const int tq = aq + 8;
;             const unsigned lo = (((unsigned)tq & 15u) ^ 8u) * 0x11111111u, hi = ((unsigned)(tq >> 4) & 15u) * 0x11111111u;
;             typedef unsigned u2v __attribute__((ext_vector_type(2)));
;             u2v l2; l2.x = lo; l2.y = lo; u2v h2; h2.x = hi; h2.y = hi;
;             *(LAS u2v*)(ATL + 8 * idx) = l2; *(LAS u2v*)(ATL + 1024 + 8 * idx) = h2;
;         }
;         const float asc = ASC[tl]; const int sa = SAL[tl];
;     ...
;         for (int st = 0; st < 16; ++st) {
;             const int p = st >> 2, q = st & 3;
;             if (st < 14) VDMA(st + 2, (st + 2) % 3);
;             if (st < 14) asm volatile("s_waitcnt vmcnt(8)" ::: "memory");
;             else if (st == 14) asm volatile("s_waitcnt vmcnt(4)" ::: "memory");
;             else asm volatile("s_waitcnt vmcnt(0)" ::: "memory");
;             if (q == 0) {
; #pragma unroll
;                 for (int r = 0; r < 4; ++r) { accH[r] = 0; accL[r] = 0; } }
; #pragma unroll
;             for (int tp = 0; tp < 2; ++tp) {
;                 const v2i ao = TR4(ATL + (2 * q + tp) * 128 + 8 * s16), ah = TR4(ATL + 1024 + (2 * q + tp) * 128 + 8 * s16);
; #pragma unroll
;                 for (int r = 0; r < 4; ++r) {
;                     const v2i d = TR4(ldsb + BUF[st % 3] + 2048 * tp + roff[r]);
;                     accH[r] = __builtin_amdgcn_sdot8(d.x, ah.x, accH[r], false); accH[r] = __builtin_amdgcn_sdot8(d.y, ah.y, accH[r], false);
;                     accL[r] = __builtin_amdgcn_sdot8(d.x, ao.x, accL[r], false); accL[r] = __builtin_amdgcn_sdot8(d.y, ao.y, accL[r], false);
;                 }
;             }
;             asm volatile("s_waitcnt lgkmcnt(0)" ::: "memory");
;             if (q == 3) {
; #pragma unroll
;                 for (int r = 0; r < 4; ++r) STASH[256 * p + 16 * (grp + 4 * r) + pc] = f2bf(asc * (float)(2 * ((accH[r] << 4) + accL[r]) + sa));
	v_add_u32_e32 v143, 8, v139
	v_and_b32_e32 v142, 15, v143
	v_xor_b32_e32 v142, 8, v142
	v_bfe_u32 v144, v143, 4, 4
	v_mul_lo_u32 v142, v142, s92
	v_mul_lo_u32 v144, v144, s92
	v_mov_b32_e32 v143, v142
	v_mov_b32_e32 v145, v144
	ds_write2st64_b64 v159, v[142:143], v[144:145] offset1:2
	v_and_b32_e32 v78, 0xffff, v28
	v_lshrrev_b32_e32 v79, 16, v28
	v_lshl_add_u32 v78, v78, 7, v150
	v_lshl_add_u32 v79, v79, 7, v151
	s_mov_b32 m0, s98
	s_add_i32 s43, s98, 0x400
	global_load_lds_dwordx4 v78, s[50:51]
	s_mov_b32 m0, s43
	s_nop 0
	global_load_lds_dwordx4 v79, s[50:51]
	s_waitcnt vmcnt(8)
	v_add_u32_e32 v54, s76, v59
	v_add_u32_e32 v55, s76, v60
	v_add_u32_e32 v56, s76, v61
	v_add_u32_e32 v57, s76, v62
	ds_read_b64_tr_b4 v[46:47], v160 offset:768
	ds_read_b64_tr_b4 v[48:49], v160 offset:1792
	ds_read_b64_tr_b4 v[122:123], v54
	ds_read_b64_tr_b4 v[124:125], v55
	ds_read_b64_tr_b4 v[126:127], v56
	ds_read_b64_tr_b4 v[128:129], v57
	s_waitcnt lgkmcnt(7)
	v_dot8c_i32_i4_e32 v38, v130, v52
	v_dot8c_i32_i4_e32 v39, v130, v50
	v_dot8c_i32_i4_e32 v40, v132, v52
	v_dot8c_i32_i4_e32 v41, v132, v50
	v_dot8c_i32_i4_e32 v42, v134, v52
	v_dot8c_i32_i4_e32 v43, v134, v50
	v_dot8c_i32_i4_e32 v44, v136, v52
	v_dot8c_i32_i4_e32 v45, v136, v50
	v_dot8c_i32_i4_e32 v38, v131, v53
	v_dot8c_i32_i4_e32 v39, v131, v51
	v_dot8c_i32_i4_e32 v40, v133, v53
	v_dot8c_i32_i4_e32 v41, v133, v51
	v_dot8c_i32_i4_e32 v42, v135, v53
	v_dot8c_i32_i4_e32 v43, v135, v51
	v_dot8c_i32_i4_e32 v44, v137, v53
	v_dot8c_i32_i4_e32 v45, v137, v51
	v_and_b32_e32 v78, 0xffff, v29
	v_lshrrev_b32_e32 v79, 16, v29
	v_lshl_add_u32 v78, v78, 7, v150
	v_lshl_add_u32 v79, v79, 7, v151
	s_mov_b32 m0, s99
	s_add_i32 s43, s99, 0x400
	global_load_lds_dwordx4 v78, s[50:51]
	s_mov_b32 m0, s43
	s_nop 0
	global_load_lds_dwordx4 v79, s[50:51]
	s_waitcnt vmcnt(8)
	v_add_u32_e32 v54, s77, v59
	v_add_u32_e32 v55, s77, v60
	v_add_u32_e32 v56, s77, v61
	v_add_u32_e32 v57, s77, v62
	ds_read_b64_tr_b4 v[50:51], v160 offset:896
	ds_read_b64_tr_b4 v[52:53], v160 offset:1920
	ds_read_b64_tr_b4 v[130:131], v54
	ds_read_b64_tr_b4 v[132:133], v55
	ds_read_b64_tr_b4 v[134:135], v56
	ds_read_b64_tr_b4 v[136:137], v57
	s_waitcnt lgkmcnt(6)
	v_dot8c_i32_i4_e32 v38, v122, v48
	v_dot8c_i32_i4_e32 v39, v122, v46
	v_dot8c_i32_i4_e32 v40, v124, v48
	v_dot8c_i32_i4_e32 v41, v124, v46
	v_dot8c_i32_i4_e32 v42, v126, v48
	v_dot8c_i32_i4_e32 v43, v126, v46
	v_dot8c_i32_i4_e32 v44, v128, v48
	v_dot8c_i32_i4_e32 v45, v128, v46
	v_dot8c_i32_i4_e32 v38, v123, v49
	v_dot8c_i32_i4_e32 v39, v123, v47
	v_dot8c_i32_i4_e32 v40, v125, v49
	v_dot8c_i32_i4_e32 v41, v125, v47
	v_dot8c_i32_i4_e32 v42, v127, v49
	v_dot8c_i32_i4_e32 v43, v127, v47
	v_dot8c_i32_i4_e32 v44, v129, v49
	v_dot8c_i32_i4_e32 v45, v129, v47
	v_and_b32_e32 v78, 0xffff, v30
	v_lshrrev_b32_e32 v79, 16, v30
	v_lshl_add_u32 v78, v78, 7, v150
	v_lshl_add_u32 v79, v79, 7, v151
	s_mov_b32 m0, s76
	s_add_i32 s43, s76, 0x400
	global_load_lds_dwordx4 v78, s[50:51]
	s_mov_b32 m0, s43
	s_nop 0
	global_load_lds_dwordx4 v79, s[50:51]
	s_waitcnt vmcnt(8)
	v_add_u32_e32 v54, s78, v59
	v_add_u32_e32 v55, s78, v60
	v_add_u32_e32 v56, s78, v61
	v_add_u32_e32 v57, s78, v62
	ds_read_b64_tr_b4 v[46:47], v160
	ds_read_b64_tr_b4 v[48:49], v160 offset:1024
	ds_read_b64_tr_b4 v[122:123], v54
	ds_read_b64_tr_b4 v[124:125], v55
	ds_read_b64_tr_b4 v[126:127], v56
	ds_read_b64_tr_b4 v[128:129], v57
	s_waitcnt lgkmcnt(6)
	v_dot8c_i32_i4_e32 v38, v130, v52
	v_dot8c_i32_i4_e32 v39, v130, v50
	v_dot8c_i32_i4_e32 v40, v132, v52
	v_dot8c_i32_i4_e32 v41, v132, v50
	v_dot8c_i32_i4_e32 v42, v134, v52
	v_dot8c_i32_i4_e32 v43, v134, v50
	v_dot8c_i32_i4_e32 v44, v136, v52
	v_dot8c_i32_i4_e32 v45, v136, v50
	v_dot8c_i32_i4_e32 v38, v131, v53
	v_dot8c_i32_i4_e32 v39, v131, v51
	v_dot8c_i32_i4_e32 v40, v133, v53
	v_dot8c_i32_i4_e32 v41, v133, v51
	v_dot8c_i32_i4_e32 v42, v135, v53
	v_dot8c_i32_i4_e32 v43, v135, v51
	v_dot8c_i32_i4_e32 v44, v137, v53
	v_dot8c_i32_i4_e32 v45, v137, v51
	s_nop 3
	s_waitcnt lgkmcnt(15)
	v_lshlrev_b32_e32 v38, 5, v38
	v_lshlrev_b32_e32 v39, 1, v39
	v_add3_u32 v38, v39, v229, v38
	v_cvt_f32_i32_e32 v38, v38
	v_mul_f32_e32 v38, v228, v38
	v_lshlrev_b32_e32 v40, 5, v40
	v_lshlrev_b32_e32 v41, 1, v41
	v_add3_u32 v40, v41, v229, v40
	v_cvt_f32_i32_e32 v40, v40
	v_mul_f32_e32 v40, v228, v40
	v_lshlrev_b32_e32 v42, 5, v42
	v_lshlrev_b32_e32 v43, 1, v43
	v_add3_u32 v42, v43, v229, v42
	v_cvt_f32_i32_e32 v42, v42
	v_mul_f32_e32 v42, v228, v42
	v_lshlrev_b32_e32 v44, 5, v44
	v_lshlrev_b32_e32 v45, 1, v45
	v_add3_u32 v44, v45, v229, v44
	v_cvt_f32_i32_e32 v44, v44
	v_mul_f32_e32 v44, v228, v44
	v_cvt_pk_bf16_f32 v162, v38, v40
	v_cvt_pk_bf16_f32 v163, v42, v44
	v_add_u32_e32 v147, 8, v140
	v_and_b32_e32 v146, 15, v147
	v_xor_b32_e32 v146, 8, v146
	v_bfe_u32 v148, v147, 4, 4
	v_mul_lo_u32 v146, v146, s92
	v_mul_lo_u32 v148, v148, s92
	v_mov_b32_e32 v147, v146
	v_mov_b32_e32 v149, v148
	ds_write2st64_b64 v77, v[146:147], v[148:149] offset1:2
	v_add_u32_e32 v138, 0x800, v74
	ds_read_u8 v139, v138
	v_add_u32_e32 v141, 0x800, v73
	ds_read_u8 v140, v141
	s_add_i32 s43, s67, 32
	v_mov_b32_e32 v138, s43
	ds_read2st64_b32 v[228:229], v138 offset1:1
	ds_read_b128 v[18:21], v227 offset:4096
	ds_read_b128 v[22:25], v227 offset:4112
	v_mov_b32_e32 v38, 0
	v_mov_b32_e32 v39, 0
	v_mov_b32_e32 v40, 0
	v_mov_b32_e32 v41, 0
	v_mov_b32_e32 v42, 0
	v_mov_b32_e32 v43, 0
	v_mov_b32_e32 v44, 0
	v_mov_b32_e32 v45, 0
	v_and_b32_e32 v78, 0xffff, v31
	v_lshrrev_b32_e32 v79, 16, v31
	v_lshl_add_u32 v78, v78, 7, v150
	v_lshl_add_u32 v79, v79, 7, v151
	s_mov_b32 m0, s77
	s_add_i32 s43, s77, 0x400
	global_load_lds_dwordx4 v78, s[50:51]
	s_mov_b32 m0, s43
	s_nop 0
	global_load_lds_dwordx4 v79, s[50:51]
	s_waitcnt vmcnt(8)
; #define TR4(p_) __builtin_amdgcn_ds_read_tr4_b64_v2i32((LAS v2i*)(p_))
; #define VDMA(st_, k_) do { _Pragma("unroll") for (int i_ = 0; i_ < 4; ++i_) { \
;         const unsigned off_ = (unsigned)((st_) >> 2) * (16384u * 128u) + (PE_ID(E, 4 * ((st_) & 3) + i_) << 7) + ((i_ & 1) ? cx1 : cx0); \
;         __builtin_amdgcn_global_load_lds((const unsigned*)(V4 + off_), (LAS unsigned*)(ldsb + BUF[k_] + 1024 * i_), 16, 0, 0); } } while (0)
; __device__ __forceinline__ void peer_v_tokens(int j, const LAS unsigned short* EL, const LAS unsigned char* AL  , const LAS float* ASC  , const LAS int* SAL  , ...
;     ...
;         for (int st = 0; st < 16; ++st) {
;             const int p = st >> 2, q = st & 3;
;             if (st < 14) VDMA(st + 2, (st + 2) % 3);
;             if (st < 14) asm volatile("s_waitcnt vmcnt(8)" ::: "memory");
;             else if (st == 14) asm volatile("s_waitcnt vmcnt(4)" ::: "memory");
;             else asm volatile("s_waitcnt vmcnt(0)" ::: "memory");
;             if (q == 0) {
; #pragma unroll
;                 for (int r = 0; r < 4; ++r) { accH[r] = 0; accL[r] = 0; } }
; #pragma unroll
;             for (int tp = 0; tp < 2; ++tp) {
;                 const v2i ao = TR4(ATL + (2 * q + tp) * 128 + 8 * s16), ah = TR4(ATL + 1024 + (2 * q + tp) * 128 + 8 * s16);
; #pragma unroll
;                 for (int r = 0; r < 4; ++r) {
;                     const v2i d = TR4(ldsb + BUF[st % 3] + 2048 * tp + roff[r]);
;                     accH[r] = __builtin_amdgcn_sdot8(d.x, ah.x, accH[r], false); accH[r] = __builtin_amdgcn_sdot8(d.y, ah.y, accH[r], false);
;                     accL[r] = __builtin_amdgcn_sdot8(d.x, ao.x, accL[r], false); accL[r] = __builtin_amdgcn_sdot8(d.y, ao.y, accL[r], false);
;                 }
;             }
	v_add_u32_e32 v54, s79, v59
	v_add_u32_e32 v55, s79, v60
	v_add_u32_e32 v56, s79, v61
	v_add_u32_e32 v57, s79, v62
	ds_read_b64_tr_b4 v[50:51], v160 offset:128
	ds_read_b64_tr_b4 v[52:53], v160 offset:1152
	ds_read_b64_tr_b4 v[130:131], v54
	ds_read_b64_tr_b4 v[132:133], v55
	ds_read_b64_tr_b4 v[134:135], v56
	ds_read_b64_tr_b4 v[136:137], v57
	s_waitcnt lgkmcnt(12)
	v_dot8c_i32_i4_e32 v38, v122, v48
	v_dot8c_i32_i4_e32 v39, v122, v46
	v_dot8c_i32_i4_e32 v40, v124, v48
	v_dot8c_i32_i4_e32 v41, v124, v46
	v_dot8c_i32_i4_e32 v42, v126, v48
	v_dot8c_i32_i4_e32 v43, v126, v46
	v_dot8c_i32_i4_e32 v44, v128, v48
	v_dot8c_i32_i4_e32 v45, v128, v46
	v_dot8c_i32_i4_e32 v38, v123, v49
	v_dot8c_i32_i4_e32 v39, v123, v47
	v_dot8c_i32_i4_e32 v40, v125, v49
	v_dot8c_i32_i4_e32 v41, v125, v47
	v_dot8c_i32_i4_e32 v42, v127, v49
	v_dot8c_i32_i4_e32 v43, v127, v47
	v_dot8c_i32_i4_e32 v44, v129, v49
	v_dot8c_i32_i4_e32 v45, v129, v47
	v_and_b32_e32 v78, 0xffff, v32
	v_lshrrev_b32_e32 v79, 16, v32
	v_lshl_add_u32 v78, v78, 7, v150
	v_lshl_add_u32 v79, v79, 7, v151
	s_mov_b32 m0, s78
	s_add_i32 s43, s78, 0x400
	global_load_lds_dwordx4 v78, s[50:51]
	s_mov_b32 m0, s43
	s_nop 0
	global_load_lds_dwordx4 v79, s[50:51]
	s_waitcnt vmcnt(8)
	v_add_u32_e32 v54, s98, v59
	v_add_u32_e32 v55, s98, v60
	v_add_u32_e32 v56, s98, v61
	v_add_u32_e32 v57, s98, v62
	ds_read_b64_tr_b4 v[46:47], v160 offset:256
	ds_read_b64_tr_b4 v[48:49], v160 offset:1280
	ds_read_b64_tr_b4 v[122:123], v54
	ds_read_b64_tr_b4 v[124:125], v55
	ds_read_b64_tr_b4 v[126:127], v56
	ds_read_b64_tr_b4 v[128:129], v57
	s_waitcnt lgkmcnt(6)
	v_dot8c_i32_i4_e32 v38, v130, v52
	v_dot8c_i32_i4_e32 v39, v130, v50
	v_dot8c_i32_i4_e32 v40, v132, v52
	v_dot8c_i32_i4_e32 v41, v132, v50
	v_dot8c_i32_i4_e32 v42, v134, v52
	v_dot8c_i32_i4_e32 v43, v134, v50
	v_dot8c_i32_i4_e32 v44, v136, v52
	v_dot8c_i32_i4_e32 v45, v136, v50
	v_dot8c_i32_i4_e32 v38, v131, v53
	v_dot8c_i32_i4_e32 v39, v131, v51
	v_dot8c_i32_i4_e32 v40, v133, v53
	v_dot8c_i32_i4_e32 v41, v133, v51
	v_dot8c_i32_i4_e32 v42, v135, v53
	v_dot8c_i32_i4_e32 v43, v135, v51
	v_dot8c_i32_i4_e32 v44, v137, v53
	v_dot8c_i32_i4_e32 v45, v137, v51
	v_and_b32_e32 v78, 0xffff, v33
	v_lshrrev_b32_e32 v79, 16, v33
	v_lshl_add_u32 v78, v78, 7, v150
	v_lshl_add_u32 v79, v79, 7, v151
	s_mov_b32 m0, s79
	s_add_i32 s43, s79, 0x400
	global_load_lds_dwordx4 v78, s[50:51]
	s_mov_b32 m0, s43
	s_nop 0
	global_load_lds_dwordx4 v79, s[50:51]
	s_waitcnt vmcnt(8)
	v_add_u32_e32 v54, s99, v59
	v_add_u32_e32 v55, s99, v60
	v_add_u32_e32 v56, s99, v61
	v_add_u32_e32 v57, s99, v62
	ds_read_b64_tr_b4 v[50:51], v160 offset:384
	ds_read_b64_tr_b4 v[52:53], v160 offset:1408
	ds_read_b64_tr_b4 v[130:131], v54
	ds_read_b64_tr_b4 v[132:133], v55
	ds_read_b64_tr_b4 v[134:135], v56
	ds_read_b64_tr_b4 v[136:137], v57
	s_waitcnt lgkmcnt(6)
	v_dot8c_i32_i4_e32 v38, v122, v48
	v_dot8c_i32_i4_e32 v39, v122, v46
	v_dot8c_i32_i4_e32 v40, v124, v48
	v_dot8c_i32_i4_e32 v41, v124, v46
	v_dot8c_i32_i4_e32 v42, v126, v48
	v_dot8c_i32_i4_e32 v43, v126, v46
	v_dot8c_i32_i4_e32 v44, v128, v48
	v_dot8c_i32_i4_e32 v45, v128, v46
	v_dot8c_i32_i4_e32 v38, v123, v49
	v_dot8c_i32_i4_e32 v39, v123, v47
	v_dot8c_i32_i4_e32 v40, v125, v49
	v_dot8c_i32_i4_e32 v41, v125, v47
	v_dot8c_i32_i4_e32 v42, v127, v49
	v_dot8c_i32_i4_e32 v43, v127, v47
	v_dot8c_i32_i4_e32 v44, v129, v49
	v_dot8c_i32_i4_e32 v45, v129, v47
	s_waitcnt lgkmcnt(15)
	v_and_b32_e32 v78, 0xffff, v18
	v_lshrrev_b32_e32 v79, 16, v18
	v_lshl_add_u32 v78, v78, 7, v150
	v_lshl_add_u32 v79, v79, 7, v151
	s_mov_b32 m0, s98
	s_add_i32 s43, s98, 0x400
	global_load_lds_dwordx4 v78, s[50:51]
	s_mov_b32 m0, s43
	s_nop 0
	global_load_lds_dwordx4 v79, s[50:51]
	s_waitcnt vmcnt(8)
	v_add_u32_e32 v54, s76, v59
	v_add_u32_e32 v55, s76, v60
	v_add_u32_e32 v56, s76, v61
	v_add_u32_e32 v57, s76, v62
	ds_read_b64_tr_b4 v[46:47], v160 offset:512
	ds_read_b64_tr_b4 v[48:49], v160 offset:1536
	ds_read_b64_tr_b4 v[122:123], v54
	ds_read_b64_tr_b4 v[124:125], v55
	ds_read_b64_tr_b4 v[126:127], v56
	ds_read_b64_tr_b4 v[128:129], v57
	s_waitcnt lgkmcnt(6)
	v_dot8c_i32_i4_e32 v38, v130, v52
	v_dot8c_i32_i4_e32 v39, v130, v50
	v_dot8c_i32_i4_e32 v40, v132, v52
	v_dot8c_i32_i4_e32 v41, v132, v50
	v_dot8c_i32_i4_e32 v42, v134, v52
	v_dot8c_i32_i4_e32 v43, v134, v50
	v_dot8c_i32_i4_e32 v44, v136, v52
	v_dot8c_i32_i4_e32 v45, v136, v50
	v_dot8c_i32_i4_e32 v38, v131, v53
	v_dot8c_i32_i4_e32 v39, v131, v51
	v_dot8c_i32_i4_e32 v40, v133, v53
	v_dot8c_i32_i4_e32 v41, v133, v51
	v_dot8c_i32_i4_e32 v42, v135, v53
	v_dot8c_i32_i4_e32 v43, v135, v51
	v_dot8c_i32_i4_e32 v44, v137, v53
	v_dot8c_i32_i4_e32 v45, v137, v51
	v_and_b32_e32 v78, 0xffff, v19
	v_lshrrev_b32_e32 v79, 16, v19
	v_lshl_add_u32 v78, v78, 7, v150
	v_lshl_add_u32 v79, v79, 7, v151
	s_mov_b32 m0, s99
	s_add_i32 s43, s99, 0x400
	global_load_lds_dwordx4 v78, s[50:51]
	s_mov_b32 m0, s43
	s_nop 0
	global_load_lds_dwordx4 v79, s[50:51]
	s_waitcnt vmcnt(8)
	v_add_u32_e32 v54, s77, v59
	v_add_u32_e32 v55, s77, v60
	v_add_u32_e32 v56, s77, v61
	v_add_u32_e32 v57, s77, v62
	ds_read_b64_tr_b4 v[50:51], v160 offset:640
	ds_read_b64_tr_b4 v[52:53], v160 offset:1664
	ds_read_b64_tr_b4 v[130:131], v54
	ds_read_b64_tr_b4 v[132:133], v55
	ds_read_b64_tr_b4 v[134:135], v56
	ds_read_b64_tr_b4 v[136:137], v57
	s_waitcnt lgkmcnt(6)
	v_dot8c_i32_i4_e32 v38, v122, v48
	v_dot8c_i32_i4_e32 v39, v122, v46
	v_dot8c_i32_i4_e32 v40, v124, v48
	v_dot8c_i32_i4_e32 v41, v124, v46
	v_dot8c_i32_i4_e32 v42, v126, v48
	v_dot8c_i32_i4_e32 v43, v126, v46
	v_dot8c_i32_i4_e32 v44, v128, v48
	v_dot8c_i32_i4_e32 v45, v128, v46
	v_dot8c_i32_i4_e32 v38, v123, v49
	v_dot8c_i32_i4_e32 v39, v123, v47
	v_dot8c_i32_i4_e32 v40, v125, v49
	v_dot8c_i32_i4_e32 v41, v125, v47
	v_dot8c_i32_i4_e32 v42, v127, v49
	v_dot8c_i32_i4_e32 v43, v127, v47
	v_dot8c_i32_i4_e32 v44, v129, v49
	v_dot8c_i32_i4_e32 v45, v129, v47
	s_waitcnt lgkmcnt(15)
; #define LAS __attribute__((address_space(3)))
; __device__ __forceinline__ void peer_v_tokens(int j, const LAS unsigned short* EL, const LAS unsigned char* AL  , const LAS float* ASC  , const LAS int* SAL  , ...
;     ...
;         { const LAS v4u* ep = (const LAS v4u*)(EL + tl * 128 + 16 * g); const v4u e0 = ep[0], e1 = ep[1];
;           E[0] = e0.x; E[1] = e0.y; E[2] = e0.z; E[3] = e0.w; E[4] = e1.x; E[5] = e1.y; E[6] = e1.z; E[7] = e1.w; }
;         uint2 hv[4]; float4 gv[4];
;         { unsigned ho = (unsigned)t * (D / 4) + (unsigned)lane; asm volatile("" : "+v"(ho)); const uint2* hp = (const uint2*)HB + ho; const float4* gp = (const float4*)fng + lane;
; #pragma unroll
;           for (int jq = 0; jq < 4; ++jq) { hv[jq] = hp[64 * jq]; gv[jq] = gp[64 * jq]; } }
;         VDMA(0, 0); VDMA(1, 1);
; #pragma unroll
;         for (int m = 0; m < 2; ++m) {
;             const int idx = lane + 64 * m, tau = idx >> 4, sr = idx & 15, k = 16 * (sr & 7) + 2 * tau + (sr >> 3);
;     ...
;         for (int st = 0; st < 16; ++st) {
;             const int p = st >> 2, q = st & 3;
;             if (st < 14) VDMA(st + 2, (st + 2) % 3);
;             if (st < 14) asm volatile("s_waitcnt vmcnt(8)" ::: "memory");
;             else if (st == 14) asm volatile("s_waitcnt vmcnt(4)" ::: "memory");
;             else asm volatile("s_waitcnt vmcnt(0)" ::: "memory");
;             if (q == 0) {
; #pragma unroll
;                 for (int r = 0; r < 4; ++r) { accH[r] = 0; accL[r] = 0; } }
; #pragma unroll
;             for (int tp = 0; tp < 2; ++tp) {
;                 const v2i ao = TR4(ATL + (2 * q + tp) * 128 + 8 * s16), ah = TR4(ATL + 1024 + (2 * q + tp) * 128 + 8 * s16);
; #pragma unroll
;                 for (int r = 0; r < 4; ++r) {
;                     const v2i d = TR4(ldsb + BUF[st % 3] + 2048 * tp + roff[r]);
;                     accH[r] = __builtin_amdgcn_sdot8(d.x, ah.x, accH[r], false); accH[r] = __builtin_amdgcn_sdot8(d.y, ah.y, accH[r], false);
;                     accL[r] = __builtin_amdgcn_sdot8(d.x, ao.x, accL[r], false); accL[r] = __builtin_amdgcn_sdot8(d.y, ao.y, accL[r], false);
;                 }
;             }
;             asm volatile("s_waitcnt lgkmcnt(0)" ::: "memory");
;             if (q == 3) {
; #pragma unroll
;                 for (int r = 0; r < 4; ++r) STASH[256 * p + 16 * (grp + 4 * r) + pc] = f2bf(asc * (float)(2 * ((accH[r] << 4) + accL[r]) + sa));
	v_add_u32_e32 v143, 8, v139
	v_and_b32_e32 v142, 15, v143
	v_xor_b32_e32 v142, 8, v142
	v_bfe_u32 v144, v143, 4, 4
	v_mul_lo_u32 v142, v142, s92
	v_mul_lo_u32 v144, v144, s92
	v_mov_b32_e32 v143, v142
	v_mov_b32_e32 v145, v144
	ds_write2st64_b64 v159, v[142:143], v[144:145] offset1:2
	v_and_b32_e32 v78, 0xffff, v20
	v_lshrrev_b32_e32 v79, 16, v20
	v_lshl_add_u32 v78, v78, 7, v150
	v_lshl_add_u32 v79, v79, 7, v151
	s_mov_b32 m0, s76
	s_add_i32 s43, s76, 0x400
	global_load_lds_dwordx4 v78, s[50:51]
	s_mov_b32 m0, s43
	s_nop 0
	global_load_lds_dwordx4 v79, s[50:51]
	s_waitcnt vmcnt(8)
	v_add_u32_e32 v54, s78, v59
	v_add_u32_e32 v55, s78, v60
	v_add_u32_e32 v56, s78, v61
	v_add_u32_e32 v57, s78, v62
	ds_read_b64_tr_b4 v[46:47], v160 offset:768
	ds_read_b64_tr_b4 v[48:49], v160 offset:1792
	ds_read_b64_tr_b4 v[122:123], v54
	ds_read_b64_tr_b4 v[124:125], v55
	ds_read_b64_tr_b4 v[126:127], v56
	ds_read_b64_tr_b4 v[128:129], v57
	s_waitcnt lgkmcnt(7)
	v_dot8c_i32_i4_e32 v38, v130, v52
	v_dot8c_i32_i4_e32 v39, v130, v50
	v_dot8c_i32_i4_e32 v40, v132, v52
	v_dot8c_i32_i4_e32 v41, v132, v50
	v_dot8c_i32_i4_e32 v42, v134, v52
	v_dot8c_i32_i4_e32 v43, v134, v50
	v_dot8c_i32_i4_e32 v44, v136, v52
	v_dot8c_i32_i4_e32 v45, v136, v50
	v_dot8c_i32_i4_e32 v38, v131, v53
	v_dot8c_i32_i4_e32 v39, v131, v51
	v_dot8c_i32_i4_e32 v40, v133, v53
	v_dot8c_i32_i4_e32 v41, v133, v51
	v_dot8c_i32_i4_e32 v42, v135, v53
	v_dot8c_i32_i4_e32 v43, v135, v51
	v_dot8c_i32_i4_e32 v44, v137, v53
	v_dot8c_i32_i4_e32 v45, v137, v51
	v_and_b32_e32 v78, 0xffff, v21
	v_lshrrev_b32_e32 v79, 16, v21
	v_lshl_add_u32 v78, v78, 7, v150
	v_lshl_add_u32 v79, v79, 7, v151
	s_mov_b32 m0, s77
	s_add_i32 s43, s77, 0x400
	global_load_lds_dwordx4 v78, s[50:51]
	s_mov_b32 m0, s43
	s_nop 0
	global_load_lds_dwordx4 v79, s[50:51]
	s_waitcnt vmcnt(8)
	v_add_u32_e32 v54, s79, v59
	v_add_u32_e32 v55, s79, v60
	v_add_u32_e32 v56, s79, v61
	v_add_u32_e32 v57, s79, v62
	ds_read_b64_tr_b4 v[50:51], v160 offset:896
	ds_read_b64_tr_b4 v[52:53], v160 offset:1920
	ds_read_b64_tr_b4 v[130:131], v54
	ds_read_b64_tr_b4 v[132:133], v55
	ds_read_b64_tr_b4 v[134:135], v56
	ds_read_b64_tr_b4 v[136:137], v57
	s_waitcnt lgkmcnt(6)
	v_dot8c_i32_i4_e32 v38, v122, v48
	v_dot8c_i32_i4_e32 v39, v122, v46
	v_dot8c_i32_i4_e32 v40, v124, v48
	v_dot8c_i32_i4_e32 v41, v124, v46
	v_dot8c_i32_i4_e32 v42, v126, v48
	v_dot8c_i32_i4_e32 v43, v126, v46
	v_dot8c_i32_i4_e32 v44, v128, v48
	v_dot8c_i32_i4_e32 v45, v128, v46
	v_dot8c_i32_i4_e32 v38, v123, v49
	v_dot8c_i32_i4_e32 v39, v123, v47
	v_dot8c_i32_i4_e32 v40, v125, v49
	v_dot8c_i32_i4_e32 v41, v125, v47
	v_dot8c_i32_i4_e32 v42, v127, v49
	v_dot8c_i32_i4_e32 v43, v127, v47
	v_dot8c_i32_i4_e32 v44, v129, v49
	v_dot8c_i32_i4_e32 v45, v129, v47
	v_and_b32_e32 v78, 0xffff, v22
	v_lshrrev_b32_e32 v79, 16, v22
	v_lshl_add_u32 v78, v78, 7, v150
	v_lshl_add_u32 v79, v79, 7, v151
	s_mov_b32 m0, s78
	s_add_i32 s43, s78, 0x400
	global_load_lds_dwordx4 v78, s[50:51]
	s_mov_b32 m0, s43
	s_nop 0
	global_load_lds_dwordx4 v79, s[50:51]
	s_waitcnt vmcnt(8)
	v_add_u32_e32 v54, s98, v59
	v_add_u32_e32 v55, s98, v60
	v_add_u32_e32 v56, s98, v61
	v_add_u32_e32 v57, s98, v62
	ds_read_b64_tr_b4 v[46:47], v160
	ds_read_b64_tr_b4 v[48:49], v160 offset:1024
	ds_read_b64_tr_b4 v[122:123], v54
	ds_read_b64_tr_b4 v[124:125], v55
	ds_read_b64_tr_b4 v[126:127], v56
	ds_read_b64_tr_b4 v[128:129], v57
	s_waitcnt lgkmcnt(6)
	v_dot8c_i32_i4_e32 v38, v130, v52
	v_dot8c_i32_i4_e32 v39, v130, v50
	v_dot8c_i32_i4_e32 v40, v132, v52
	v_dot8c_i32_i4_e32 v41, v132, v50
	v_dot8c_i32_i4_e32 v42, v134, v52
	v_dot8c_i32_i4_e32 v43, v134, v50
	v_dot8c_i32_i4_e32 v44, v136, v52
	v_dot8c_i32_i4_e32 v45, v136, v50
	v_dot8c_i32_i4_e32 v38, v131, v53
	v_dot8c_i32_i4_e32 v39, v131, v51
	v_dot8c_i32_i4_e32 v40, v133, v53
	v_dot8c_i32_i4_e32 v41, v133, v51
	v_dot8c_i32_i4_e32 v42, v135, v53
	v_dot8c_i32_i4_e32 v43, v135, v51
	v_dot8c_i32_i4_e32 v44, v137, v53
	v_dot8c_i32_i4_e32 v45, v137, v51
	s_nop 3
	s_waitcnt lgkmcnt(15)
	v_lshlrev_b32_e32 v38, 5, v38
	v_lshlrev_b32_e32 v39, 1, v39
	v_add3_u32 v38, v39, v229, v38
	v_cvt_f32_i32_e32 v38, v38
	v_mul_f32_e32 v38, v228, v38
	v_lshlrev_b32_e32 v40, 5, v40
	v_lshlrev_b32_e32 v41, 1, v41
	v_add3_u32 v40, v41, v229, v40
	v_cvt_f32_i32_e32 v40, v40
	v_mul_f32_e32 v40, v228, v40
	v_lshlrev_b32_e32 v42, 5, v42
	v_lshlrev_b32_e32 v43, 1, v43
	v_add3_u32 v42, v43, v229, v42
	v_cvt_f32_i32_e32 v42, v42
	v_mul_f32_e32 v42, v228, v42
	v_lshlrev_b32_e32 v44, 5, v44
	v_lshlrev_b32_e32 v45, 1, v45
	v_add3_u32 v44, v45, v229, v44
	v_cvt_f32_i32_e32 v44, v44
	v_mul_f32_e32 v44, v228, v44
	v_cvt_pk_bf16_f32 v170, v38, v40
	v_cvt_pk_bf16_f32 v171, v42, v44
	v_add_u32_e32 v147, 8, v140
	v_and_b32_e32 v146, 15, v147
	v_xor_b32_e32 v146, 8, v146
	v_bfe_u32 v148, v147, 4, 4
	v_mul_lo_u32 v146, v146, s92
	v_mul_lo_u32 v148, v148, s92
	v_mov_b32_e32 v147, v146
	v_mov_b32_e32 v149, v148
	ds_write2st64_b64 v77, v[146:147], v[148:149] offset1:2
	v_add_u32_e32 v138, 0xc00, v74
	ds_read_u8 v139, v138
	v_add_u32_e32 v141, 0xc00, v73
	ds_read_u8 v140, v141
	s_add_i32 s43, s67, 64
	v_mov_b32_e32 v138, s43
	ds_read2st64_b32 v[228:229], v138 offset1:1
	ds_read_b128 v[26:29], v227 offset:6144
	ds_read_b128 v[30:33], v227 offset:6160
	v_mov_b32_e32 v38, 0
	v_mov_b32_e32 v39, 0
	v_mov_b32_e32 v40, 0
	v_mov_b32_e32 v41, 0
	v_mov_b32_e32 v42, 0
	v_mov_b32_e32 v43, 0
	v_mov_b32_e32 v44, 0
	v_mov_b32_e32 v45, 0
	v_and_b32_e32 v78, 0xffff, v23
	v_lshrrev_b32_e32 v79, 16, v23
	v_lshl_add_u32 v78, v78, 7, v150
	v_lshl_add_u32 v79, v79, 7, v151
	s_mov_b32 m0, s79
	s_add_i32 s43, s79, 0x400
	global_load_lds_dwordx4 v78, s[50:51]
	s_mov_b32 m0, s43
	s_nop 0
	global_load_lds_dwordx4 v79, s[50:51]
	s_waitcnt vmcnt(8)
; #define TR4(p_) __builtin_amdgcn_ds_read_tr4_b64_v2i32((LAS v2i*)(p_))
; #define VDMA(st_, k_) do { _Pragma("unroll") for (int i_ = 0; i_ < 4; ++i_) { \
;         const unsigned off_ = (unsigned)((st_) >> 2) * (16384u * 128u) + (PE_ID(E, 4 * ((st_) & 3) + i_) << 7) + ((i_ & 1) ? cx1 : cx0); \
;         __builtin_amdgcn_global_load_lds((const unsigned*)(V4 + off_), (LAS unsigned*)(ldsb + BUF[k_] + 1024 * i_), 16, 0, 0); } } while (0)
; __device__ __forceinline__ void peer_v_tokens(int j, const LAS unsigned short* EL, const LAS unsigned char* AL  , const LAS float* ASC  , const LAS int* SAL  , ...
;     ...
;         for (int st = 0; st < 16; ++st) {
;             const int p = st >> 2, q = st & 3;
;             if (st < 14) VDMA(st + 2, (st + 2) % 3);
;             if (st < 14) asm volatile("s_waitcnt vmcnt(8)" ::: "memory");
;             else if (st == 14) asm volatile("s_waitcnt vmcnt(4)" ::: "memory");
;             else asm volatile("s_waitcnt vmcnt(0)" ::: "memory");
;             if (q == 0) {
; #pragma unroll
;                 for (int r = 0; r < 4; ++r) { accH[r] = 0; accL[r] = 0; } }
; #pragma unroll
;             for (int tp = 0; tp < 2; ++tp) {
;                 const v2i ao = TR4(ATL + (2 * q + tp) * 128 + 8 * s16), ah = TR4(ATL + 1024 + (2 * q + tp) * 128 + 8 * s16);
; #pragma unroll
;                 for (int r = 0; r < 4; ++r) {
;                     const v2i d = TR4(ldsb + BUF[st % 3] + 2048 * tp + roff[r]);
;                     accH[r] = __builtin_amdgcn_sdot8(d.x, ah.x, accH[r], false); accH[r] = __builtin_amdgcn_sdot8(d.y, ah.y, accH[r], false);
;                     accL[r] = __builtin_amdgcn_sdot8(d.x, ao.x, accL[r], false); accL[r] = __builtin_amdgcn_sdot8(d.y, ao.y, accL[r], false);
;                 }
;             }
	v_add_u32_e32 v54, s99, v59
	v_add_u32_e32 v55, s99, v60
	v_add_u32_e32 v56, s99, v61
	v_add_u32_e32 v57, s99, v62
	ds_read_b64_tr_b4 v[50:51], v160 offset:128
	ds_read_b64_tr_b4 v[52:53], v160 offset:1152
	ds_read_b64_tr_b4 v[130:131], v54
	ds_read_b64_tr_b4 v[132:133], v55
	ds_read_b64_tr_b4 v[134:135], v56
	ds_read_b64_tr_b4 v[136:137], v57
	s_waitcnt lgkmcnt(12)
	v_dot8c_i32_i4_e32 v38, v122, v48
	v_dot8c_i32_i4_e32 v39, v122, v46
	v_dot8c_i32_i4_e32 v40, v124, v48
	v_dot8c_i32_i4_e32 v41, v124, v46
	v_dot8c_i32_i4_e32 v42, v126, v48
	v_dot8c_i32_i4_e32 v43, v126, v46
	v_dot8c_i32_i4_e32 v44, v128, v48
	v_dot8c_i32_i4_e32 v45, v128, v46
	v_dot8c_i32_i4_e32 v38, v123, v49
	v_dot8c_i32_i4_e32 v39, v123, v47
	v_dot8c_i32_i4_e32 v40, v125, v49
	v_dot8c_i32_i4_e32 v41, v125, v47
	v_dot8c_i32_i4_e32 v42, v127, v49
	v_dot8c_i32_i4_e32 v43, v127, v47
	v_dot8c_i32_i4_e32 v44, v129, v49
	v_dot8c_i32_i4_e32 v45, v129, v47
	v_and_b32_e32 v78, 0xffff, v24
	v_lshrrev_b32_e32 v79, 16, v24
	v_lshl_add_u32 v78, v78, 7, v150
	v_lshl_add_u32 v79, v79, 7, v151
	s_mov_b32 m0, s98
	s_add_i32 s43, s98, 0x400
	global_load_lds_dwordx4 v78, s[50:51]
	s_mov_b32 m0, s43
	s_nop 0
	global_load_lds_dwordx4 v79, s[50:51]
	s_waitcnt vmcnt(8)
	v_add_u32_e32 v54, s76, v59
	v_add_u32_e32 v55, s76, v60
	v_add_u32_e32 v56, s76, v61
	v_add_u32_e32 v57, s76, v62
	ds_read_b64_tr_b4 v[46:47], v160 offset:256
	ds_read_b64_tr_b4 v[48:49], v160 offset:1280
	ds_read_b64_tr_b4 v[122:123], v54
	ds_read_b64_tr_b4 v[124:125], v55
	ds_read_b64_tr_b4 v[126:127], v56
	ds_read_b64_tr_b4 v[128:129], v57
	s_waitcnt lgkmcnt(6)
	v_dot8c_i32_i4_e32 v38, v130, v52
	v_dot8c_i32_i4_e32 v39, v130, v50
	v_dot8c_i32_i4_e32 v40, v132, v52
	v_dot8c_i32_i4_e32 v41, v132, v50
	v_dot8c_i32_i4_e32 v42, v134, v52
	v_dot8c_i32_i4_e32 v43, v134, v50
	v_dot8c_i32_i4_e32 v44, v136, v52
	v_dot8c_i32_i4_e32 v45, v136, v50
	v_dot8c_i32_i4_e32 v38, v131, v53
	v_dot8c_i32_i4_e32 v39, v131, v51
	v_dot8c_i32_i4_e32 v40, v133, v53
	v_dot8c_i32_i4_e32 v41, v133, v51
	v_dot8c_i32_i4_e32 v42, v135, v53
	v_dot8c_i32_i4_e32 v43, v135, v51
	v_dot8c_i32_i4_e32 v44, v137, v53
	v_dot8c_i32_i4_e32 v45, v137, v51
	v_and_b32_e32 v78, 0xffff, v25
	v_lshrrev_b32_e32 v79, 16, v25
	v_lshl_add_u32 v78, v78, 7, v150
	v_lshl_add_u32 v79, v79, 7, v151
	s_mov_b32 m0, s99
	s_add_i32 s43, s99, 0x400
	global_load_lds_dwordx4 v78, s[50:51]
	s_mov_b32 m0, s43
	s_nop 0
	global_load_lds_dwordx4 v79, s[50:51]
	s_waitcnt vmcnt(8)
	v_add_u32_e32 v54, s77, v59
	v_add_u32_e32 v55, s77, v60
	v_add_u32_e32 v56, s77, v61
	v_add_u32_e32 v57, s77, v62
	ds_read_b64_tr_b4 v[50:51], v160 offset:384
	ds_read_b64_tr_b4 v[52:53], v160 offset:1408
	ds_read_b64_tr_b4 v[130:131], v54
	ds_read_b64_tr_b4 v[132:133], v55
	ds_read_b64_tr_b4 v[134:135], v56
	ds_read_b64_tr_b4 v[136:137], v57
	s_waitcnt lgkmcnt(6)
	v_dot8c_i32_i4_e32 v38, v122, v48
	v_dot8c_i32_i4_e32 v39, v122, v46
	v_dot8c_i32_i4_e32 v40, v124, v48
	v_dot8c_i32_i4_e32 v41, v124, v46
	v_dot8c_i32_i4_e32 v42, v126, v48
	v_dot8c_i32_i4_e32 v43, v126, v46
	v_dot8c_i32_i4_e32 v44, v128, v48
	v_dot8c_i32_i4_e32 v45, v128, v46
	v_dot8c_i32_i4_e32 v38, v123, v49
	v_dot8c_i32_i4_e32 v39, v123, v47
	v_dot8c_i32_i4_e32 v40, v125, v49
	v_dot8c_i32_i4_e32 v41, v125, v47
	v_dot8c_i32_i4_e32 v42, v127, v49
	v_dot8c_i32_i4_e32 v43, v127, v47
	v_dot8c_i32_i4_e32 v44, v129, v49
	v_dot8c_i32_i4_e32 v45, v129, v47
	s_waitcnt lgkmcnt(15)
	v_and_b32_e32 v78, 0xffff, v26
	v_lshrrev_b32_e32 v79, 16, v26
	v_lshl_add_u32 v78, v78, 7, v150
	v_lshl_add_u32 v79, v79, 7, v151
	s_mov_b32 m0, s76
	s_add_i32 s43, s76, 0x400
	global_load_lds_dwordx4 v78, s[50:51]
	s_mov_b32 m0, s43
	s_nop 0
	global_load_lds_dwordx4 v79, s[50:51]
	s_waitcnt vmcnt(8)
	v_add_u32_e32 v54, s78, v59
	v_add_u32_e32 v55, s78, v60
	v_add_u32_e32 v56, s78, v61
	v_add_u32_e32 v57, s78, v62
	ds_read_b64_tr_b4 v[46:47], v160 offset:512
	ds_read_b64_tr_b4 v[48:49], v160 offset:1536
	ds_read_b64_tr_b4 v[122:123], v54
	ds_read_b64_tr_b4 v[124:125], v55
	ds_read_b64_tr_b4 v[126:127], v56
	ds_read_b64_tr_b4 v[128:129], v57
	s_waitcnt lgkmcnt(6)
	v_dot8c_i32_i4_e32 v38, v130, v52
	v_dot8c_i32_i4_e32 v39, v130, v50
	v_dot8c_i32_i4_e32 v40, v132, v52
	v_dot8c_i32_i4_e32 v41, v132, v50
	v_dot8c_i32_i4_e32 v42, v134, v52
	v_dot8c_i32_i4_e32 v43, v134, v50
	v_dot8c_i32_i4_e32 v44, v136, v52
	v_dot8c_i32_i4_e32 v45, v136, v50
	v_dot8c_i32_i4_e32 v38, v131, v53
	v_dot8c_i32_i4_e32 v39, v131, v51
	v_dot8c_i32_i4_e32 v40, v133, v53
	v_dot8c_i32_i4_e32 v41, v133, v51
	v_dot8c_i32_i4_e32 v42, v135, v53
	v_dot8c_i32_i4_e32 v43, v135, v51
	v_dot8c_i32_i4_e32 v44, v137, v53
	v_dot8c_i32_i4_e32 v45, v137, v51
	v_and_b32_e32 v78, 0xffff, v27
	v_lshrrev_b32_e32 v79, 16, v27
	v_lshl_add_u32 v78, v78, 7, v150
	v_lshl_add_u32 v79, v79, 7, v151
	s_mov_b32 m0, s77
	s_add_i32 s43, s77, 0x400
	global_load_lds_dwordx4 v78, s[50:51]
	s_mov_b32 m0, s43
	s_nop 0
	global_load_lds_dwordx4 v79, s[50:51]
	s_waitcnt vmcnt(8)
	v_add_u32_e32 v54, s79, v59
	v_add_u32_e32 v55, s79, v60
	v_add_u32_e32 v56, s79, v61
	v_add_u32_e32 v57, s79, v62
	ds_read_b64_tr_b4 v[50:51], v160 offset:640
	ds_read_b64_tr_b4 v[52:53], v160 offset:1664
	ds_read_b64_tr_b4 v[130:131], v54
	ds_read_b64_tr_b4 v[132:133], v55
	ds_read_b64_tr_b4 v[134:135], v56
	ds_read_b64_tr_b4 v[136:137], v57
	s_waitcnt lgkmcnt(6)
	v_dot8c_i32_i4_e32 v38, v122, v48
	v_dot8c_i32_i4_e32 v39, v122, v46
	v_dot8c_i32_i4_e32 v40, v124, v48
	v_dot8c_i32_i4_e32 v41, v124, v46
	v_dot8c_i32_i4_e32 v42, v126, v48
	v_dot8c_i32_i4_e32 v43, v126, v46
	v_dot8c_i32_i4_e32 v44, v128, v48
	v_dot8c_i32_i4_e32 v45, v128, v46
	v_dot8c_i32_i4_e32 v38, v123, v49
	v_dot8c_i32_i4_e32 v39, v123, v47
	v_dot8c_i32_i4_e32 v40, v125, v49
	v_dot8c_i32_i4_e32 v41, v125, v47
	v_dot8c_i32_i4_e32 v42, v127, v49
	v_dot8c_i32_i4_e32 v43, v127, v47
	v_dot8c_i32_i4_e32 v44, v129, v49
	v_dot8c_i32_i4_e32 v45, v129, v47
	s_waitcnt lgkmcnt(15)
; #define LAS __attribute__((address_space(3)))
; __device__ __forceinline__ void peer_v_tokens(int j, const LAS unsigned short* EL, const LAS unsigned char* AL  , const LAS float* ASC  , const LAS int* SAL  , ...
;     ...
;         { const LAS v4u* ep = (const LAS v4u*)(EL + tl * 128 + 16 * g); const v4u e0 = ep[0], e1 = ep[1];
;           E[0] = e0.x; E[1] = e0.y; E[2] = e0.z; E[3] = e0.w; E[4] = e1.x; E[5] = e1.y; E[6] = e1.z; E[7] = e1.w; }
;         uint2 hv[4]; float4 gv[4];
;         { unsigned ho = (unsigned)t * (D / 4) + (unsigned)lane; asm volatile("" : "+v"(ho)); const uint2* hp = (const uint2*)HB + ho; const float4* gp = (const float4*)fng + lane;
; #pragma unroll
;           for (int jq = 0; jq < 4; ++jq) { hv[jq] = hp[64 * jq]; gv[jq] = gp[64 * jq]; } }
;         VDMA(0, 0); VDMA(1, 1);
; #pragma unroll
;         for (int m = 0; m < 2; ++m) {
;             const int idx = lane + 64 * m, tau = idx >> 4, sr = idx & 15, k = 16 * (sr & 7) + 2 * tau + (sr >> 3);
;     ...
;         for (int st = 0; st < 16; ++st) {
;             const int p = st >> 2, q = st & 3;
;             if (st < 14) VDMA(st + 2, (st + 2) % 3);
;             if (st < 14) asm volatile("s_waitcnt vmcnt(8)" ::: "memory");
;             else if (st == 14) asm volatile("s_waitcnt vmcnt(4)" ::: "memory");
;             else asm volatile("s_waitcnt vmcnt(0)" ::: "memory");
;             if (q == 0) {
; #pragma unroll
;                 for (int r = 0; r < 4; ++r) { accH[r] = 0; accL[r] = 0; } }
; #pragma unroll
;             for (int tp = 0; tp < 2; ++tp) {
;                 const v2i ao = TR4(ATL + (2 * q + tp) * 128 + 8 * s16), ah = TR4(ATL + 1024 + (2 * q + tp) * 128 + 8 * s16);
; #pragma unroll
;                 for (int r = 0; r < 4; ++r) {
;                     const v2i d = TR4(ldsb + BUF[st % 3] + 2048 * tp + roff[r]);
;                     accH[r] = __builtin_amdgcn_sdot8(d.x, ah.x, accH[r], false); accH[r] = __builtin_amdgcn_sdot8(d.y, ah.y, accH[r], false);
;                     accL[r] = __builtin_amdgcn_sdot8(d.x, ao.x, accL[r], false); accL[r] = __builtin_amdgcn_sdot8(d.y, ao.y, accL[r], false);
;                 }
;             }
;             asm volatile("s_waitcnt lgkmcnt(0)" ::: "memory");
;             if (q == 3) {
; #pragma unroll
;                 for (int r = 0; r < 4; ++r) STASH[256 * p + 16 * (grp + 4 * r) + pc] = f2bf(asc * (float)(2 * ((accH[r] << 4) + accL[r]) + sa));
	v_add_u32_e32 v143, 8, v139
	v_and_b32_e32 v142, 15, v143
	v_xor_b32_e32 v142, 8, v142
	v_bfe_u32 v144, v143, 4, 4
	v_mul_lo_u32 v142, v142, s92
	v_mul_lo_u32 v144, v144, s92
	v_mov_b32_e32 v143, v142
	v_mov_b32_e32 v145, v144
	ds_write2st64_b64 v159, v[142:143], v[144:145] offset1:2
	v_and_b32_e32 v78, 0xffff, v28
	v_lshrrev_b32_e32 v79, 16, v28
	v_lshl_add_u32 v78, v78, 7, v150
	v_lshl_add_u32 v79, v79, 7, v151
	s_mov_b32 m0, s78
	s_add_i32 s43, s78, 0x400
	global_load_lds_dwordx4 v78, s[50:51]
	s_mov_b32 m0, s43
	s_nop 0
	global_load_lds_dwordx4 v79, s[50:51]
	s_waitcnt vmcnt(8)
	v_add_u32_e32 v54, s98, v59
	v_add_u32_e32 v55, s98, v60
	v_add_u32_e32 v56, s98, v61
	v_add_u32_e32 v57, s98, v62
	ds_read_b64_tr_b4 v[46:47], v160 offset:768
	ds_read_b64_tr_b4 v[48:49], v160 offset:1792
	ds_read_b64_tr_b4 v[122:123], v54
	ds_read_b64_tr_b4 v[124:125], v55
	ds_read_b64_tr_b4 v[126:127], v56
	ds_read_b64_tr_b4 v[128:129], v57
	s_waitcnt lgkmcnt(7)
	v_dot8c_i32_i4_e32 v38, v130, v52
	v_dot8c_i32_i4_e32 v39, v130, v50
	v_dot8c_i32_i4_e32 v40, v132, v52
	v_dot8c_i32_i4_e32 v41, v132, v50
	v_dot8c_i32_i4_e32 v42, v134, v52
	v_dot8c_i32_i4_e32 v43, v134, v50
	v_dot8c_i32_i4_e32 v44, v136, v52
	v_dot8c_i32_i4_e32 v45, v136, v50
	v_dot8c_i32_i4_e32 v38, v131, v53
	v_dot8c_i32_i4_e32 v39, v131, v51
	v_dot8c_i32_i4_e32 v40, v133, v53
	v_dot8c_i32_i4_e32 v41, v133, v51
	v_dot8c_i32_i4_e32 v42, v135, v53
	v_dot8c_i32_i4_e32 v43, v135, v51
	v_dot8c_i32_i4_e32 v44, v137, v53
	v_dot8c_i32_i4_e32 v45, v137, v51
	v_and_b32_e32 v78, 0xffff, v29
	v_lshrrev_b32_e32 v79, 16, v29
	v_lshl_add_u32 v78, v78, 7, v150
	v_lshl_add_u32 v79, v79, 7, v151
	s_mov_b32 m0, s79
	s_add_i32 s43, s79, 0x400
	global_load_lds_dwordx4 v78, s[50:51]
	s_mov_b32 m0, s43
	s_nop 0
	global_load_lds_dwordx4 v79, s[50:51]
	s_waitcnt vmcnt(8)
	v_add_u32_e32 v54, s99, v59
	v_add_u32_e32 v55, s99, v60
	v_add_u32_e32 v56, s99, v61
	v_add_u32_e32 v57, s99, v62
	ds_read_b64_tr_b4 v[50:51], v160 offset:896
	ds_read_b64_tr_b4 v[52:53], v160 offset:1920
	ds_read_b64_tr_b4 v[130:131], v54
	ds_read_b64_tr_b4 v[132:133], v55
	ds_read_b64_tr_b4 v[134:135], v56
	ds_read_b64_tr_b4 v[136:137], v57
	s_waitcnt lgkmcnt(6)
	v_dot8c_i32_i4_e32 v38, v122, v48
	v_dot8c_i32_i4_e32 v39, v122, v46
	v_dot8c_i32_i4_e32 v40, v124, v48
	v_dot8c_i32_i4_e32 v41, v124, v46
	v_dot8c_i32_i4_e32 v42, v126, v48
	v_dot8c_i32_i4_e32 v43, v126, v46
	v_dot8c_i32_i4_e32 v44, v128, v48
	v_dot8c_i32_i4_e32 v45, v128, v46
	v_dot8c_i32_i4_e32 v38, v123, v49
	v_dot8c_i32_i4_e32 v39, v123, v47
	v_dot8c_i32_i4_e32 v40, v125, v49
	v_dot8c_i32_i4_e32 v41, v125, v47
	v_dot8c_i32_i4_e32 v42, v127, v49
	v_dot8c_i32_i4_e32 v43, v127, v47
	v_dot8c_i32_i4_e32 v44, v129, v49
	v_dot8c_i32_i4_e32 v45, v129, v47
	v_and_b32_e32 v78, 0xffff, v30
	v_lshrrev_b32_e32 v79, 16, v30
	v_lshl_add_u32 v78, v78, 7, v150
	v_lshl_add_u32 v79, v79, 7, v151
	s_mov_b32 m0, s98
	s_add_i32 s43, s98, 0x400
	global_load_lds_dwordx4 v78, s[50:51]
	s_mov_b32 m0, s43
	s_nop 0
	global_load_lds_dwordx4 v79, s[50:51]
	s_waitcnt vmcnt(8)
	v_add_u32_e32 v54, s76, v59
	v_add_u32_e32 v55, s76, v60
	v_add_u32_e32 v56, s76, v61
	v_add_u32_e32 v57, s76, v62
	ds_read_b64_tr_b4 v[46:47], v160
	ds_read_b64_tr_b4 v[48:49], v160 offset:1024
	ds_read_b64_tr_b4 v[122:123], v54
	ds_read_b64_tr_b4 v[124:125], v55
	ds_read_b64_tr_b4 v[126:127], v56
	ds_read_b64_tr_b4 v[128:129], v57
	s_waitcnt lgkmcnt(6)
	v_dot8c_i32_i4_e32 v38, v130, v52
	v_dot8c_i32_i4_e32 v39, v130, v50
	v_dot8c_i32_i4_e32 v40, v132, v52
	v_dot8c_i32_i4_e32 v41, v132, v50
	v_dot8c_i32_i4_e32 v42, v134, v52
	v_dot8c_i32_i4_e32 v43, v134, v50
	v_dot8c_i32_i4_e32 v44, v136, v52
	v_dot8c_i32_i4_e32 v45, v136, v50
	v_dot8c_i32_i4_e32 v38, v131, v53
	v_dot8c_i32_i4_e32 v39, v131, v51
	v_dot8c_i32_i4_e32 v40, v133, v53
	v_dot8c_i32_i4_e32 v41, v133, v51
	v_dot8c_i32_i4_e32 v42, v135, v53
	v_dot8c_i32_i4_e32 v43, v135, v51
	v_dot8c_i32_i4_e32 v44, v137, v53
	v_dot8c_i32_i4_e32 v45, v137, v51
	s_nop 3
	s_waitcnt lgkmcnt(15)
	v_lshlrev_b32_e32 v38, 5, v38
	v_lshlrev_b32_e32 v39, 1, v39
	v_add3_u32 v38, v39, v229, v38
	v_cvt_f32_i32_e32 v38, v38
	v_mul_f32_e32 v38, v228, v38
	v_lshlrev_b32_e32 v40, 5, v40
	v_lshlrev_b32_e32 v41, 1, v41
	v_add3_u32 v40, v41, v229, v40
	v_cvt_f32_i32_e32 v40, v40
	v_mul_f32_e32 v40, v228, v40
	v_lshlrev_b32_e32 v42, 5, v42
	v_lshlrev_b32_e32 v43, 1, v43
	v_add3_u32 v42, v43, v229, v42
	v_cvt_f32_i32_e32 v42, v42
	v_mul_f32_e32 v42, v228, v42
	v_lshlrev_b32_e32 v44, 5, v44
	v_lshlrev_b32_e32 v45, 1, v45
	v_add3_u32 v44, v45, v229, v44
	v_cvt_f32_i32_e32 v44, v44
	v_mul_f32_e32 v44, v228, v44
	v_cvt_pk_bf16_f32 v178, v38, v40
	v_cvt_pk_bf16_f32 v179, v42, v44
	v_add_u32_e32 v147, 8, v140
	v_and_b32_e32 v146, 15, v147
	v_xor_b32_e32 v146, 8, v146
	v_bfe_u32 v148, v147, 4, 4
	v_mul_lo_u32 v146, v146, s92
	v_mul_lo_u32 v148, v148, s92
	v_mov_b32_e32 v147, v146
	v_mov_b32_e32 v149, v148
	ds_write2st64_b64 v77, v[146:147], v[148:149] offset1:2
	v_mov_b32_e32 v138, v74
	ds_read_u8 v139, v138
	v_mov_b32_e32 v141, v73
	ds_read_u8 v140, v141
	s_add_i32 s43, s67, 96
	v_mov_b32_e32 v138, s43
	ds_read2st64_b32 v[228:229], v138 offset1:1
	ds_read_b128 v[18:21], v227
	ds_read_b128 v[22:25], v227 offset:16
	v_add_u32_e32 v152, 0x200000, v63
	v_add_u32_e32 v153, 0x200000, v64
	v_mov_b32_e32 v38, 0
	v_mov_b32_e32 v39, 0
	v_mov_b32_e32 v40, 0
	v_mov_b32_e32 v41, 0
	v_mov_b32_e32 v42, 0
	v_mov_b32_e32 v43, 0
	v_mov_b32_e32 v44, 0
	v_mov_b32_e32 v45, 0
	v_and_b32_e32 v78, 0xffff, v31
	v_lshrrev_b32_e32 v79, 16, v31
	v_lshl_add_u32 v78, v78, 7, v150
	v_lshl_add_u32 v79, v79, 7, v151
	s_mov_b32 m0, s99
	s_add_i32 s43, s99, 0x400
	global_load_lds_dwordx4 v78, s[50:51]
	s_mov_b32 m0, s43
	s_nop 0
	global_load_lds_dwordx4 v79, s[50:51]
	s_waitcnt vmcnt(8)
; #define TR4(p_) __builtin_amdgcn_ds_read_tr4_b64_v2i32((LAS v2i*)(p_))
; #define VDMA(st_, k_) do { _Pragma("unroll") for (int i_ = 0; i_ < 4; ++i_) { \
;         const unsigned off_ = (unsigned)((st_) >> 2) * (16384u * 128u) + (PE_ID(E, 4 * ((st_) & 3) + i_) << 7) + ((i_ & 1) ? cx1 : cx0); \
;         __builtin_amdgcn_global_load_lds((const unsigned*)(V4 + off_), (LAS unsigned*)(ldsb + BUF[k_] + 1024 * i_), 16, 0, 0); } } while (0)
; __device__ __forceinline__ void peer_v_tokens(int j, const LAS unsigned short* EL, const LAS unsigned char* AL  , const LAS float* ASC  , const LAS int* SAL  , ...
;     ...
;         for (int st = 0; st < 16; ++st) {
;             const int p = st >> 2, q = st & 3;
;             if (st < 14) VDMA(st + 2, (st + 2) % 3);
;             if (st < 14) asm volatile("s_waitcnt vmcnt(8)" ::: "memory");
;             else if (st == 14) asm volatile("s_waitcnt vmcnt(4)" ::: "memory");
;             else asm volatile("s_waitcnt vmcnt(0)" ::: "memory");
;             if (q == 0) {
; #pragma unroll
;                 for (int r = 0; r < 4; ++r) { accH[r] = 0; accL[r] = 0; } }
; #pragma unroll
;             for (int tp = 0; tp < 2; ++tp) {
;                 const v2i ao = TR4(ATL + (2 * q + tp) * 128 + 8 * s16), ah = TR4(ATL + 1024 + (2 * q + tp) * 128 + 8 * s16);
; #pragma unroll
;                 for (int r = 0; r < 4; ++r) {
;                     const v2i d = TR4(ldsb + BUF[st % 3] + 2048 * tp + roff[r]);
;                     accH[r] = __builtin_amdgcn_sdot8(d.x, ah.x, accH[r], false); accH[r] = __builtin_amdgcn_sdot8(d.y, ah.y, accH[r], false);
;                     accL[r] = __builtin_amdgcn_sdot8(d.x, ao.x, accL[r], false); accL[r] = __builtin_amdgcn_sdot8(d.y, ao.y, accL[r], false);
;                 }
;             }
	v_add_u32_e32 v54, s77, v59
	v_add_u32_e32 v55, s77, v60
	v_add_u32_e32 v56, s77, v61
	v_add_u32_e32 v57, s77, v62
	ds_read_b64_tr_b4 v[50:51], v160 offset:128
	ds_read_b64_tr_b4 v[52:53], v160 offset:1152
	ds_read_b64_tr_b4 v[130:131], v54
	ds_read_b64_tr_b4 v[132:133], v55
	ds_read_b64_tr_b4 v[134:135], v56
	ds_read_b64_tr_b4 v[136:137], v57
	s_waitcnt lgkmcnt(12)
	v_dot8c_i32_i4_e32 v38, v122, v48
	v_dot8c_i32_i4_e32 v39, v122, v46
	v_dot8c_i32_i4_e32 v40, v124, v48
	v_dot8c_i32_i4_e32 v41, v124, v46
	v_dot8c_i32_i4_e32 v42, v126, v48
	v_dot8c_i32_i4_e32 v43, v126, v46
	v_dot8c_i32_i4_e32 v44, v128, v48
	v_dot8c_i32_i4_e32 v45, v128, v46
	v_dot8c_i32_i4_e32 v38, v123, v49
	v_dot8c_i32_i4_e32 v39, v123, v47
	v_dot8c_i32_i4_e32 v40, v125, v49
	v_dot8c_i32_i4_e32 v41, v125, v47
	v_dot8c_i32_i4_e32 v42, v127, v49
	v_dot8c_i32_i4_e32 v43, v127, v47
	v_dot8c_i32_i4_e32 v44, v129, v49
	v_dot8c_i32_i4_e32 v45, v129, v47
	v_and_b32_e32 v78, 0xffff, v32
	v_lshrrev_b32_e32 v79, 16, v32
	v_lshl_add_u32 v78, v78, 7, v150
	v_lshl_add_u32 v79, v79, 7, v151
	s_mov_b32 m0, s76
	s_add_i32 s43, s76, 0x400
	global_load_lds_dwordx4 v78, s[50:51]
	s_mov_b32 m0, s43
	s_nop 0
	global_load_lds_dwordx4 v79, s[50:51]
	s_waitcnt vmcnt(8)
	v_add_u32_e32 v54, s78, v59
	v_add_u32_e32 v55, s78, v60
	v_add_u32_e32 v56, s78, v61
	v_add_u32_e32 v57, s78, v62
	ds_read_b64_tr_b4 v[46:47], v160 offset:256
	ds_read_b64_tr_b4 v[48:49], v160 offset:1280
	ds_read_b64_tr_b4 v[122:123], v54
	ds_read_b64_tr_b4 v[124:125], v55
	ds_read_b64_tr_b4 v[126:127], v56
	ds_read_b64_tr_b4 v[128:129], v57
	s_waitcnt lgkmcnt(6)
	v_dot8c_i32_i4_e32 v38, v130, v52
	v_dot8c_i32_i4_e32 v39, v130, v50
	v_dot8c_i32_i4_e32 v40, v132, v52
	v_dot8c_i32_i4_e32 v41, v132, v50
	v_dot8c_i32_i4_e32 v42, v134, v52
	v_dot8c_i32_i4_e32 v43, v134, v50
	v_dot8c_i32_i4_e32 v44, v136, v52
	v_dot8c_i32_i4_e32 v45, v136, v50
	v_dot8c_i32_i4_e32 v38, v131, v53
	v_dot8c_i32_i4_e32 v39, v131, v51
	v_dot8c_i32_i4_e32 v40, v133, v53
	v_dot8c_i32_i4_e32 v41, v133, v51
	v_dot8c_i32_i4_e32 v42, v135, v53
	v_dot8c_i32_i4_e32 v43, v135, v51
	v_dot8c_i32_i4_e32 v44, v137, v53
	v_dot8c_i32_i4_e32 v45, v137, v51
	v_and_b32_e32 v78, 0xffff, v33
	v_lshrrev_b32_e32 v79, 16, v33
	v_lshl_add_u32 v78, v78, 7, v150
	v_lshl_add_u32 v79, v79, 7, v151
	s_mov_b32 m0, s77
	s_add_i32 s43, s77, 0x400
	global_load_lds_dwordx4 v78, s[50:51]
	s_mov_b32 m0, s43
	s_nop 0
	global_load_lds_dwordx4 v79, s[50:51]
	s_waitcnt vmcnt(8)
	v_add_u32_e32 v54, s79, v59
	v_add_u32_e32 v55, s79, v60
	v_add_u32_e32 v56, s79, v61
	v_add_u32_e32 v57, s79, v62
	ds_read_b64_tr_b4 v[50:51], v160 offset:384
	ds_read_b64_tr_b4 v[52:53], v160 offset:1408
	ds_read_b64_tr_b4 v[130:131], v54
	ds_read_b64_tr_b4 v[132:133], v55
	ds_read_b64_tr_b4 v[134:135], v56
	ds_read_b64_tr_b4 v[136:137], v57
	s_waitcnt lgkmcnt(6)
	v_dot8c_i32_i4_e32 v38, v122, v48
	v_dot8c_i32_i4_e32 v39, v122, v46
	v_dot8c_i32_i4_e32 v40, v124, v48
	v_dot8c_i32_i4_e32 v41, v124, v46
	v_dot8c_i32_i4_e32 v42, v126, v48
	v_dot8c_i32_i4_e32 v43, v126, v46
	v_dot8c_i32_i4_e32 v44, v128, v48
	v_dot8c_i32_i4_e32 v45, v128, v46
	v_dot8c_i32_i4_e32 v38, v123, v49
	v_dot8c_i32_i4_e32 v39, v123, v47
	v_dot8c_i32_i4_e32 v40, v125, v49
	v_dot8c_i32_i4_e32 v41, v125, v47
	v_dot8c_i32_i4_e32 v42, v127, v49
	v_dot8c_i32_i4_e32 v43, v127, v47
	v_dot8c_i32_i4_e32 v44, v129, v49
	v_dot8c_i32_i4_e32 v45, v129, v47
	s_waitcnt lgkmcnt(15)
	v_and_b32_e32 v78, 0xffff, v18
	v_lshrrev_b32_e32 v79, 16, v18
	v_lshl_add_u32 v78, v78, 7, v152
	v_lshl_add_u32 v79, v79, 7, v153
	s_mov_b32 m0, s78
	s_add_i32 s43, s78, 0x400
	global_load_lds_dwordx4 v78, s[50:51]
	s_mov_b32 m0, s43
	s_nop 0
	global_load_lds_dwordx4 v79, s[50:51]
	s_waitcnt vmcnt(8)
	v_add_u32_e32 v54, s98, v59
	v_add_u32_e32 v55, s98, v60
	v_add_u32_e32 v56, s98, v61
	v_add_u32_e32 v57, s98, v62
	ds_read_b64_tr_b4 v[46:47], v160 offset:512
	ds_read_b64_tr_b4 v[48:49], v160 offset:1536
	ds_read_b64_tr_b4 v[122:123], v54
	ds_read_b64_tr_b4 v[124:125], v55
	ds_read_b64_tr_b4 v[126:127], v56
	ds_read_b64_tr_b4 v[128:129], v57
	s_waitcnt lgkmcnt(6)
	v_dot8c_i32_i4_e32 v38, v130, v52
	v_dot8c_i32_i4_e32 v39, v130, v50
	v_dot8c_i32_i4_e32 v40, v132, v52
	v_dot8c_i32_i4_e32 v41, v132, v50
	v_dot8c_i32_i4_e32 v42, v134, v52
	v_dot8c_i32_i4_e32 v43, v134, v50
	v_dot8c_i32_i4_e32 v44, v136, v52
	v_dot8c_i32_i4_e32 v45, v136, v50
	v_dot8c_i32_i4_e32 v38, v131, v53
	v_dot8c_i32_i4_e32 v39, v131, v51
	v_dot8c_i32_i4_e32 v40, v133, v53
	v_dot8c_i32_i4_e32 v41, v133, v51
	v_dot8c_i32_i4_e32 v42, v135, v53
	v_dot8c_i32_i4_e32 v43, v135, v51
	v_dot8c_i32_i4_e32 v44, v137, v53
	v_dot8c_i32_i4_e32 v45, v137, v51
	v_and_b32_e32 v78, 0xffff, v19
	v_lshrrev_b32_e32 v79, 16, v19
	v_lshl_add_u32 v78, v78, 7, v152
	v_lshl_add_u32 v79, v79, 7, v153
	s_mov_b32 m0, s79
	s_add_i32 s43, s79, 0x400
	global_load_lds_dwordx4 v78, s[50:51]
	s_mov_b32 m0, s43
	s_nop 0
	global_load_lds_dwordx4 v79, s[50:51]
	s_waitcnt vmcnt(8)
	v_add_u32_e32 v54, s99, v59
	v_add_u32_e32 v55, s99, v60
	v_add_u32_e32 v56, s99, v61
	v_add_u32_e32 v57, s99, v62
	ds_read_b64_tr_b4 v[50:51], v160 offset:640
	ds_read_b64_tr_b4 v[52:53], v160 offset:1664
	ds_read_b64_tr_b4 v[130:131], v54
	ds_read_b64_tr_b4 v[132:133], v55
	ds_read_b64_tr_b4 v[134:135], v56
	ds_read_b64_tr_b4 v[136:137], v57
	s_waitcnt lgkmcnt(6)
	v_dot8c_i32_i4_e32 v38, v122, v48
	v_dot8c_i32_i4_e32 v39, v122, v46
	v_dot8c_i32_i4_e32 v40, v124, v48
	v_dot8c_i32_i4_e32 v41, v124, v46
	v_dot8c_i32_i4_e32 v42, v126, v48
	v_dot8c_i32_i4_e32 v43, v126, v46
	v_dot8c_i32_i4_e32 v44, v128, v48
	v_dot8c_i32_i4_e32 v45, v128, v46
	v_dot8c_i32_i4_e32 v38, v123, v49
	v_dot8c_i32_i4_e32 v39, v123, v47
	v_dot8c_i32_i4_e32 v40, v125, v49
	v_dot8c_i32_i4_e32 v41, v125, v47
	v_dot8c_i32_i4_e32 v42, v127, v49
	v_dot8c_i32_i4_e32 v43, v127, v47
	v_dot8c_i32_i4_e32 v44, v129, v49
	v_dot8c_i32_i4_e32 v45, v129, v47
	s_waitcnt lgkmcnt(15)
; #define LAS __attribute__((address_space(3)))
; __device__ __forceinline__ void peer_v_tokens(int j, const LAS unsigned short* EL, const LAS unsigned char* AL  , const LAS float* ASC  , const LAS int* SAL  , ...
;     ...
;         { const LAS v4u* ep = (const LAS v4u*)(EL + tl * 128 + 16 * g); const v4u e0 = ep[0], e1 = ep[1];
;           E[0] = e0.x; E[1] = e0.y; E[2] = e0.z; E[3] = e0.w; E[4] = e1.x; E[5] = e1.y; E[6] = e1.z; E[7] = e1.w; }
;         uint2 hv[4]; float4 gv[4];
;         { unsigned ho = (unsigned)t * (D / 4) + (unsigned)lane; asm volatile("" : "+v"(ho)); const uint2* hp = (const uint2*)HB + ho; const float4* gp = (const float4*)fng + lane;
; #pragma unroll
;           for (int jq = 0; jq < 4; ++jq) { hv[jq] = hp[64 * jq]; gv[jq] = gp[64 * jq]; } }
;         VDMA(0, 0); VDMA(1, 1);
; #pragma unroll
;         for (int m = 0; m < 2; ++m) {
;             const int idx = lane + 64 * m, tau = idx >> 4, sr = idx & 15, k = 16 * (sr & 7) + 2 * tau + (sr >> 3);
;     ...
;         for (int st = 0; st < 16; ++st) {
;             const int p = st >> 2, q = st & 3;
;             if (st < 14) VDMA(st + 2, (st + 2) % 3);
;             if (st < 14) asm volatile("s_waitcnt vmcnt(8)" ::: "memory");
;             else if (st == 14) asm volatile("s_waitcnt vmcnt(4)" ::: "memory");
;             else asm volatile("s_waitcnt vmcnt(0)" ::: "memory");
;             if (q == 0) {
; #pragma unroll
;                 for (int r = 0; r < 4; ++r) { accH[r] = 0; accL[r] = 0; } }
; #pragma unroll
;             for (int tp = 0; tp < 2; ++tp) {
;                 const v2i ao = TR4(ATL + (2 * q + tp) * 128 + 8 * s16), ah = TR4(ATL + 1024 + (2 * q + tp) * 128 + 8 * s16);
; #pragma unroll
;                 for (int r = 0; r < 4; ++r) {
;                     const v2i d = TR4(ldsb + BUF[st % 3] + 2048 * tp + roff[r]);
;                     accH[r] = __builtin_amdgcn_sdot8(d.x, ah.x, accH[r], false); accH[r] = __builtin_amdgcn_sdot8(d.y, ah.y, accH[r], false);
;                     accL[r] = __builtin_amdgcn_sdot8(d.x, ao.x, accL[r], false); accL[r] = __builtin_amdgcn_sdot8(d.y, ao.y, accL[r], false);
;                 }
;             }
;             asm volatile("s_waitcnt lgkmcnt(0)" ::: "memory");
;             if (q == 3) {
; #pragma unroll
;                 for (int r = 0; r < 4; ++r) STASH[256 * p + 16 * (grp + 4 * r) + pc] = f2bf(asc * (float)(2 * ((accH[r] << 4) + accL[r]) + sa));
	v_add_u32_e32 v143, 8, v139
	v_and_b32_e32 v142, 15, v143
	v_xor_b32_e32 v142, 8, v142
	v_bfe_u32 v144, v143, 4, 4
	v_mul_lo_u32 v142, v142, s92
	v_mul_lo_u32 v144, v144, s92
	v_mov_b32_e32 v143, v142
	v_mov_b32_e32 v145, v144
	ds_write2st64_b64 v159, v[142:143], v[144:145] offset1:2
	v_and_b32_e32 v78, 0xffff, v20
	v_lshrrev_b32_e32 v79, 16, v20
	v_lshl_add_u32 v78, v78, 7, v152
	v_lshl_add_u32 v79, v79, 7, v153
	s_mov_b32 m0, s98
	s_add_i32 s43, s98, 0x400
	global_load_lds_dwordx4 v78, s[50:51]
	s_mov_b32 m0, s43
	s_nop 0
	global_load_lds_dwordx4 v79, s[50:51]
	s_waitcnt vmcnt(8)
	v_add_u32_e32 v54, s76, v59
	v_add_u32_e32 v55, s76, v60
	v_add_u32_e32 v56, s76, v61
	v_add_u32_e32 v57, s76, v62
	ds_read_b64_tr_b4 v[46:47], v160 offset:768
	ds_read_b64_tr_b4 v[48:49], v160 offset:1792
	ds_read_b64_tr_b4 v[122:123], v54
	ds_read_b64_tr_b4 v[124:125], v55
	ds_read_b64_tr_b4 v[126:127], v56
	ds_read_b64_tr_b4 v[128:129], v57
	s_waitcnt lgkmcnt(7)
	v_dot8c_i32_i4_e32 v38, v130, v52
	v_dot8c_i32_i4_e32 v39, v130, v50
	v_dot8c_i32_i4_e32 v40, v132, v52
	v_dot8c_i32_i4_e32 v41, v132, v50
	v_dot8c_i32_i4_e32 v42, v134, v52
	v_dot8c_i32_i4_e32 v43, v134, v50
	v_dot8c_i32_i4_e32 v44, v136, v52
	v_dot8c_i32_i4_e32 v45, v136, v50
	v_dot8c_i32_i4_e32 v38, v131, v53
	v_dot8c_i32_i4_e32 v39, v131, v51
	v_dot8c_i32_i4_e32 v40, v133, v53
	v_dot8c_i32_i4_e32 v41, v133, v51
	v_dot8c_i32_i4_e32 v42, v135, v53
	v_dot8c_i32_i4_e32 v43, v135, v51
	v_dot8c_i32_i4_e32 v44, v137, v53
	v_dot8c_i32_i4_e32 v45, v137, v51
	v_and_b32_e32 v78, 0xffff, v21
	v_lshrrev_b32_e32 v79, 16, v21
	v_lshl_add_u32 v78, v78, 7, v152
	v_lshl_add_u32 v79, v79, 7, v153
	s_mov_b32 m0, s99
	s_add_i32 s43, s99, 0x400
	global_load_lds_dwordx4 v78, s[50:51]
	s_mov_b32 m0, s43
	s_nop 0
	global_load_lds_dwordx4 v79, s[50:51]
	s_waitcnt vmcnt(8)
	v_add_u32_e32 v54, s77, v59
	v_add_u32_e32 v55, s77, v60
	v_add_u32_e32 v56, s77, v61
	v_add_u32_e32 v57, s77, v62
	ds_read_b64_tr_b4 v[50:51], v160 offset:896
	ds_read_b64_tr_b4 v[52:53], v160 offset:1920
	ds_read_b64_tr_b4 v[130:131], v54
	ds_read_b64_tr_b4 v[132:133], v55
	ds_read_b64_tr_b4 v[134:135], v56
	ds_read_b64_tr_b4 v[136:137], v57
	s_waitcnt lgkmcnt(6)
	v_dot8c_i32_i4_e32 v38, v122, v48
	v_dot8c_i32_i4_e32 v39, v122, v46
	v_dot8c_i32_i4_e32 v40, v124, v48
	v_dot8c_i32_i4_e32 v41, v124, v46
	v_dot8c_i32_i4_e32 v42, v126, v48
	v_dot8c_i32_i4_e32 v43, v126, v46
	v_dot8c_i32_i4_e32 v44, v128, v48
	v_dot8c_i32_i4_e32 v45, v128, v46
	v_dot8c_i32_i4_e32 v38, v123, v49
	v_dot8c_i32_i4_e32 v39, v123, v47
	v_dot8c_i32_i4_e32 v40, v125, v49
	v_dot8c_i32_i4_e32 v41, v125, v47
	v_dot8c_i32_i4_e32 v42, v127, v49
	v_dot8c_i32_i4_e32 v43, v127, v47
	v_dot8c_i32_i4_e32 v44, v129, v49
	v_dot8c_i32_i4_e32 v45, v129, v47
	v_and_b32_e32 v78, 0xffff, v22
	v_lshrrev_b32_e32 v79, 16, v22
	v_lshl_add_u32 v78, v78, 7, v152
	v_lshl_add_u32 v79, v79, 7, v153
	s_mov_b32 m0, s76
	s_add_i32 s43, s76, 0x400
	global_load_lds_dwordx4 v78, s[50:51]
	s_mov_b32 m0, s43
	s_nop 0
	global_load_lds_dwordx4 v79, s[50:51]
	s_waitcnt vmcnt(8)
	v_add_u32_e32 v54, s78, v59
	v_add_u32_e32 v55, s78, v60
	v_add_u32_e32 v56, s78, v61
	v_add_u32_e32 v57, s78, v62
	ds_read_b64_tr_b4 v[46:47], v160
	ds_read_b64_tr_b4 v[48:49], v160 offset:1024
	ds_read_b64_tr_b4 v[122:123], v54
	ds_read_b64_tr_b4 v[124:125], v55
	ds_read_b64_tr_b4 v[126:127], v56
	ds_read_b64_tr_b4 v[128:129], v57
	s_waitcnt lgkmcnt(6)
	v_dot8c_i32_i4_e32 v38, v130, v52
	v_dot8c_i32_i4_e32 v39, v130, v50
	v_dot8c_i32_i4_e32 v40, v132, v52
	v_dot8c_i32_i4_e32 v41, v132, v50
	v_dot8c_i32_i4_e32 v42, v134, v52
	v_dot8c_i32_i4_e32 v43, v134, v50
	v_dot8c_i32_i4_e32 v44, v136, v52
	v_dot8c_i32_i4_e32 v45, v136, v50
	v_dot8c_i32_i4_e32 v38, v131, v53
	v_dot8c_i32_i4_e32 v39, v131, v51
	v_dot8c_i32_i4_e32 v40, v133, v53
	v_dot8c_i32_i4_e32 v41, v133, v51
	v_dot8c_i32_i4_e32 v42, v135, v53
	v_dot8c_i32_i4_e32 v43, v135, v51
	v_dot8c_i32_i4_e32 v44, v137, v53
	v_dot8c_i32_i4_e32 v45, v137, v51
	s_nop 3
	s_waitcnt lgkmcnt(15)
	v_lshlrev_b32_e32 v38, 5, v38
	v_lshlrev_b32_e32 v39, 1, v39
	v_add3_u32 v38, v39, v229, v38
	v_cvt_f32_i32_e32 v38, v38
	v_mul_f32_e32 v38, v228, v38
	v_lshlrev_b32_e32 v40, 5, v40
	v_lshlrev_b32_e32 v41, 1, v41
	v_add3_u32 v40, v41, v229, v40
	v_cvt_f32_i32_e32 v40, v40
	v_mul_f32_e32 v40, v228, v40
	v_lshlrev_b32_e32 v42, 5, v42
	v_lshlrev_b32_e32 v43, 1, v43
	v_add3_u32 v42, v43, v229, v42
	v_cvt_f32_i32_e32 v42, v42
	v_mul_f32_e32 v42, v228, v42
	v_lshlrev_b32_e32 v44, 5, v44
	v_lshlrev_b32_e32 v45, 1, v45
	v_add3_u32 v44, v45, v229, v44
	v_cvt_f32_i32_e32 v44, v44
	v_mul_f32_e32 v44, v228, v44
	v_cvt_pk_bf16_f32 v186, v38, v40
	v_cvt_pk_bf16_f32 v187, v42, v44
	v_add_u32_e32 v147, 8, v140
	v_and_b32_e32 v146, 15, v147
	v_xor_b32_e32 v146, 8, v146
	v_bfe_u32 v148, v147, 4, 4
	v_mul_lo_u32 v146, v146, s92
	v_mul_lo_u32 v148, v148, s92
	v_mov_b32_e32 v147, v146
	v_mov_b32_e32 v149, v148
	ds_write2st64_b64 v77, v[146:147], v[148:149] offset1:2
	v_add_u32_e32 v138, 0x400, v74
	ds_read_u8 v139, v138
	v_add_u32_e32 v141, 0x400, v73
	ds_read_u8 v140, v141
	s_mov_b32 s43, s67
	v_mov_b32_e32 v138, s43
	ds_read2st64_b32 v[228:229], v138 offset1:1
	ds_read_b128 v[26:29], v227 offset:2048
	ds_read_b128 v[30:33], v227 offset:2064
	v_mov_b32_e32 v38, 0
	v_mov_b32_e32 v39, 0
	v_mov_b32_e32 v40, 0
	v_mov_b32_e32 v41, 0
	v_mov_b32_e32 v42, 0
	v_mov_b32_e32 v43, 0
	v_mov_b32_e32 v44, 0
	v_mov_b32_e32 v45, 0
	v_and_b32_e32 v78, 0xffff, v23
	v_lshrrev_b32_e32 v79, 16, v23
	v_lshl_add_u32 v78, v78, 7, v152
	v_lshl_add_u32 v79, v79, 7, v153
	s_mov_b32 m0, s77
	s_add_i32 s43, s77, 0x400
	global_load_lds_dwordx4 v78, s[50:51]
	s_mov_b32 m0, s43
	s_nop 0
	global_load_lds_dwordx4 v79, s[50:51]
	s_waitcnt vmcnt(8)
; #define TR4(p_) __builtin_amdgcn_ds_read_tr4_b64_v2i32((LAS v2i*)(p_))
; #define VDMA(st_, k_) do { _Pragma("unroll") for (int i_ = 0; i_ < 4; ++i_) { \
;         const unsigned off_ = (unsigned)((st_) >> 2) * (16384u * 128u) + (PE_ID(E, 4 * ((st_) & 3) + i_) << 7) + ((i_ & 1) ? cx1 : cx0); \
;         __builtin_amdgcn_global_load_lds((const unsigned*)(V4 + off_), (LAS unsigned*)(ldsb + BUF[k_] + 1024 * i_), 16, 0, 0); } } while (0)
; __device__ __forceinline__ void peer_v_tokens(int j, const LAS unsigned short* EL, const LAS unsigned char* AL  , const LAS float* ASC  , const LAS int* SAL  , ...
;     ...
;         for (int st = 0; st < 16; ++st) {
;             const int p = st >> 2, q = st & 3;
;             if (st < 14) VDMA(st + 2, (st + 2) % 3);
;             if (st < 14) asm volatile("s_waitcnt vmcnt(8)" ::: "memory");
;             else if (st == 14) asm volatile("s_waitcnt vmcnt(4)" ::: "memory");
;             else asm volatile("s_waitcnt vmcnt(0)" ::: "memory");
;             if (q == 0) {
; #pragma unroll
;                 for (int r = 0; r < 4; ++r) { accH[r] = 0; accL[r] = 0; } }
; #pragma unroll
;             for (int tp = 0; tp < 2; ++tp) {
;                 const v2i ao = TR4(ATL + (2 * q + tp) * 128 + 8 * s16), ah = TR4(ATL + 1024 + (2 * q + tp) * 128 + 8 * s16);
; #pragma unroll
;                 for (int r = 0; r < 4; ++r) {
;                     const v2i d = TR4(ldsb + BUF[st % 3] + 2048 * tp + roff[r]);
;                     accH[r] = __builtin_amdgcn_sdot8(d.x, ah.x, accH[r], false); accH[r] = __builtin_amdgcn_sdot8(d.y, ah.y, accH[r], false);
;                     accL[r] = __builtin_amdgcn_sdot8(d.x, ao.x, accL[r], false); accL[r] = __builtin_amdgcn_sdot8(d.y, ao.y, accL[r], false);
;                 }
;             }
	v_add_u32_e32 v54, s79, v59
	v_add_u32_e32 v55, s79, v60
	v_add_u32_e32 v56, s79, v61
	v_add_u32_e32 v57, s79, v62
	ds_read_b64_tr_b4 v[50:51], v160 offset:128
	ds_read_b64_tr_b4 v[52:53], v160 offset:1152
	ds_read_b64_tr_b4 v[130:131], v54
	ds_read_b64_tr_b4 v[132:133], v55
	ds_read_b64_tr_b4 v[134:135], v56
	ds_read_b64_tr_b4 v[136:137], v57
	s_waitcnt lgkmcnt(12)
	v_dot8c_i32_i4_e32 v38, v122, v48
	v_dot8c_i32_i4_e32 v39, v122, v46
	v_dot8c_i32_i4_e32 v40, v124, v48
	v_dot8c_i32_i4_e32 v41, v124, v46
	v_dot8c_i32_i4_e32 v42, v126, v48
	v_dot8c_i32_i4_e32 v43, v126, v46
	v_dot8c_i32_i4_e32 v44, v128, v48
	v_dot8c_i32_i4_e32 v45, v128, v46
	v_dot8c_i32_i4_e32 v38, v123, v49
	v_dot8c_i32_i4_e32 v39, v123, v47
	v_dot8c_i32_i4_e32 v40, v125, v49
	v_dot8c_i32_i4_e32 v41, v125, v47
	v_dot8c_i32_i4_e32 v42, v127, v49
	v_dot8c_i32_i4_e32 v43, v127, v47
	v_dot8c_i32_i4_e32 v44, v129, v49
	v_dot8c_i32_i4_e32 v45, v129, v47
	v_and_b32_e32 v78, 0xffff, v24
	v_lshrrev_b32_e32 v79, 16, v24
	v_lshl_add_u32 v78, v78, 7, v152
	v_lshl_add_u32 v79, v79, 7, v153
	s_mov_b32 m0, s78
	s_add_i32 s43, s78, 0x400
	global_load_lds_dwordx4 v78, s[50:51]
	s_mov_b32 m0, s43
	s_nop 0
	global_load_lds_dwordx4 v79, s[50:51]
	s_waitcnt vmcnt(8)
	v_add_u32_e32 v54, s98, v59
	v_add_u32_e32 v55, s98, v60
	v_add_u32_e32 v56, s98, v61
	v_add_u32_e32 v57, s98, v62
	ds_read_b64_tr_b4 v[46:47], v160 offset:256
	ds_read_b64_tr_b4 v[48:49], v160 offset:1280
	ds_read_b64_tr_b4 v[122:123], v54
	ds_read_b64_tr_b4 v[124:125], v55
	ds_read_b64_tr_b4 v[126:127], v56
	ds_read_b64_tr_b4 v[128:129], v57
	s_waitcnt lgkmcnt(6)
	v_dot8c_i32_i4_e32 v38, v130, v52
	v_dot8c_i32_i4_e32 v39, v130, v50
	v_dot8c_i32_i4_e32 v40, v132, v52
	v_dot8c_i32_i4_e32 v41, v132, v50
	v_dot8c_i32_i4_e32 v42, v134, v52
	v_dot8c_i32_i4_e32 v43, v134, v50
	v_dot8c_i32_i4_e32 v44, v136, v52
	v_dot8c_i32_i4_e32 v45, v136, v50
	v_dot8c_i32_i4_e32 v38, v131, v53
	v_dot8c_i32_i4_e32 v39, v131, v51
	v_dot8c_i32_i4_e32 v40, v133, v53
	v_dot8c_i32_i4_e32 v41, v133, v51
	v_dot8c_i32_i4_e32 v42, v135, v53
	v_dot8c_i32_i4_e32 v43, v135, v51
	v_dot8c_i32_i4_e32 v44, v137, v53
	v_dot8c_i32_i4_e32 v45, v137, v51
	v_and_b32_e32 v78, 0xffff, v25
	v_lshrrev_b32_e32 v79, 16, v25
	v_lshl_add_u32 v78, v78, 7, v152
	v_lshl_add_u32 v79, v79, 7, v153
	s_mov_b32 m0, s79
	s_add_i32 s43, s79, 0x400
	global_load_lds_dwordx4 v78, s[50:51]
	s_mov_b32 m0, s43
	s_nop 0
	global_load_lds_dwordx4 v79, s[50:51]
	s_waitcnt vmcnt(8)
	v_add_u32_e32 v54, s99, v59
	v_add_u32_e32 v55, s99, v60
	v_add_u32_e32 v56, s99, v61
	v_add_u32_e32 v57, s99, v62
	ds_read_b64_tr_b4 v[50:51], v160 offset:384
	ds_read_b64_tr_b4 v[52:53], v160 offset:1408
	ds_read_b64_tr_b4 v[130:131], v54
	ds_read_b64_tr_b4 v[132:133], v55
	ds_read_b64_tr_b4 v[134:135], v56
	ds_read_b64_tr_b4 v[136:137], v57
	s_waitcnt lgkmcnt(6)
	v_dot8c_i32_i4_e32 v38, v122, v48
	v_dot8c_i32_i4_e32 v39, v122, v46
	v_dot8c_i32_i4_e32 v40, v124, v48
	v_dot8c_i32_i4_e32 v41, v124, v46
	v_dot8c_i32_i4_e32 v42, v126, v48
	v_dot8c_i32_i4_e32 v43, v126, v46
	v_dot8c_i32_i4_e32 v44, v128, v48
	v_dot8c_i32_i4_e32 v45, v128, v46
	v_dot8c_i32_i4_e32 v38, v123, v49
	v_dot8c_i32_i4_e32 v39, v123, v47
	v_dot8c_i32_i4_e32 v40, v125, v49
	v_dot8c_i32_i4_e32 v41, v125, v47
	v_dot8c_i32_i4_e32 v42, v127, v49
	v_dot8c_i32_i4_e32 v43, v127, v47
	v_dot8c_i32_i4_e32 v44, v129, v49
	v_dot8c_i32_i4_e32 v45, v129, v47
	s_waitcnt lgkmcnt(15)
	v_and_b32_e32 v78, 0xffff, v26
	v_lshrrev_b32_e32 v79, 16, v26
	v_lshl_add_u32 v78, v78, 7, v152
	v_lshl_add_u32 v79, v79, 7, v153
	s_mov_b32 m0, s98
	s_add_i32 s43, s98, 0x400
	global_load_lds_dwordx4 v78, s[50:51]
	s_mov_b32 m0, s43
	s_nop 0
	global_load_lds_dwordx4 v79, s[50:51]
	s_waitcnt vmcnt(8)
	v_add_u32_e32 v54, s76, v59
	v_add_u32_e32 v55, s76, v60
	v_add_u32_e32 v56, s76, v61
	v_add_u32_e32 v57, s76, v62
	ds_read_b64_tr_b4 v[46:47], v160 offset:512
	ds_read_b64_tr_b4 v[48:49], v160 offset:1536
	ds_read_b64_tr_b4 v[122:123], v54
	ds_read_b64_tr_b4 v[124:125], v55
	ds_read_b64_tr_b4 v[126:127], v56
	ds_read_b64_tr_b4 v[128:129], v57
	s_waitcnt lgkmcnt(6)
	v_dot8c_i32_i4_e32 v38, v130, v52
	v_dot8c_i32_i4_e32 v39, v130, v50
	v_dot8c_i32_i4_e32 v40, v132, v52
	v_dot8c_i32_i4_e32 v41, v132, v50
	v_dot8c_i32_i4_e32 v42, v134, v52
	v_dot8c_i32_i4_e32 v43, v134, v50
	v_dot8c_i32_i4_e32 v44, v136, v52
	v_dot8c_i32_i4_e32 v45, v136, v50
	v_dot8c_i32_i4_e32 v38, v131, v53
	v_dot8c_i32_i4_e32 v39, v131, v51
	v_dot8c_i32_i4_e32 v40, v133, v53
	v_dot8c_i32_i4_e32 v41, v133, v51
	v_dot8c_i32_i4_e32 v42, v135, v53
	v_dot8c_i32_i4_e32 v43, v135, v51
	v_dot8c_i32_i4_e32 v44, v137, v53
	v_dot8c_i32_i4_e32 v45, v137, v51
	v_and_b32_e32 v78, 0xffff, v27
	v_lshrrev_b32_e32 v79, 16, v27
	v_lshl_add_u32 v78, v78, 7, v152
	v_lshl_add_u32 v79, v79, 7, v153
	s_mov_b32 m0, s99
	s_add_i32 s43, s99, 0x400
	global_load_lds_dwordx4 v78, s[50:51]
	s_mov_b32 m0, s43
	s_nop 0
	global_load_lds_dwordx4 v79, s[50:51]
	s_waitcnt vmcnt(8)
	v_add_u32_e32 v54, s77, v59
	v_add_u32_e32 v55, s77, v60
	v_add_u32_e32 v56, s77, v61
	v_add_u32_e32 v57, s77, v62
	ds_read_b64_tr_b4 v[50:51], v160 offset:640
	ds_read_b64_tr_b4 v[52:53], v160 offset:1664
	ds_read_b64_tr_b4 v[130:131], v54
	ds_read_b64_tr_b4 v[132:133], v55
	ds_read_b64_tr_b4 v[134:135], v56
	ds_read_b64_tr_b4 v[136:137], v57
	s_waitcnt lgkmcnt(6)
	v_dot8c_i32_i4_e32 v38, v122, v48
	v_dot8c_i32_i4_e32 v39, v122, v46
	v_dot8c_i32_i4_e32 v40, v124, v48
	v_dot8c_i32_i4_e32 v41, v124, v46
	v_dot8c_i32_i4_e32 v42, v126, v48
	v_dot8c_i32_i4_e32 v43, v126, v46
	v_dot8c_i32_i4_e32 v44, v128, v48
	v_dot8c_i32_i4_e32 v45, v128, v46
	v_dot8c_i32_i4_e32 v38, v123, v49
	v_dot8c_i32_i4_e32 v39, v123, v47
	v_dot8c_i32_i4_e32 v40, v125, v49
	v_dot8c_i32_i4_e32 v41, v125, v47
	v_dot8c_i32_i4_e32 v42, v127, v49
	v_dot8c_i32_i4_e32 v43, v127, v47
	v_dot8c_i32_i4_e32 v44, v129, v49
	v_dot8c_i32_i4_e32 v45, v129, v47
	s_waitcnt lgkmcnt(15)
; #define LAS __attribute__((address_space(3)))
; __device__ __forceinline__ void peer_v_tokens(int j, const LAS unsigned short* EL, const LAS unsigned char* AL  , const LAS float* ASC  , const LAS int* SAL  , ...
;     ...
;         { const LAS v4u* ep = (const LAS v4u*)(EL + tl * 128 + 16 * g); const v4u e0 = ep[0], e1 = ep[1];
;           E[0] = e0.x; E[1] = e0.y; E[2] = e0.z; E[3] = e0.w; E[4] = e1.x; E[5] = e1.y; E[6] = e1.z; E[7] = e1.w; }
;         uint2 hv[4]; float4 gv[4];
;         { unsigned ho = (unsigned)t * (D / 4) + (unsigned)lane; asm volatile("" : "+v"(ho)); const uint2* hp = (const uint2*)HB + ho; const float4* gp = (const float4*)fng + lane;
; #pragma unroll
;           for (int jq = 0; jq < 4; ++jq) { hv[jq] = hp[64 * jq]; gv[jq] = gp[64 * jq]; } }
;         VDMA(0, 0); VDMA(1, 1);
; #pragma unroll
;         for (int m = 0; m < 2; ++m) {
;             const int idx = lane + 64 * m, tau = idx >> 4, sr = idx & 15, k = 16 * (sr & 7) + 2 * tau + (sr >> 3);
;     ...
;         for (int st = 0; st < 16; ++st) {
;             const int p = st >> 2, q = st & 3;
;             if (st < 14) VDMA(st + 2, (st + 2) % 3);
;             if (st < 14) asm volatile("s_waitcnt vmcnt(8)" ::: "memory");
;             else if (st == 14) asm volatile("s_waitcnt vmcnt(4)" ::: "memory");
;             else asm volatile("s_waitcnt vmcnt(0)" ::: "memory");
;             if (q == 0) {
; #pragma unroll
;                 for (int r = 0; r < 4; ++r) { accH[r] = 0; accL[r] = 0; } }
; #pragma unroll
;             for (int tp = 0; tp < 2; ++tp) {
;                 const v2i ao = TR4(ATL + (2 * q + tp) * 128 + 8 * s16), ah = TR4(ATL + 1024 + (2 * q + tp) * 128 + 8 * s16);
; #pragma unroll
;                 for (int r = 0; r < 4; ++r) {
;                     const v2i d = TR4(ldsb + BUF[st % 3] + 2048 * tp + roff[r]);
;                     accH[r] = __builtin_amdgcn_sdot8(d.x, ah.x, accH[r], false); accH[r] = __builtin_amdgcn_sdot8(d.y, ah.y, accH[r], false);
;                     accL[r] = __builtin_amdgcn_sdot8(d.x, ao.x, accL[r], false); accL[r] = __builtin_amdgcn_sdot8(d.y, ao.y, accL[r], false);
;                 }
;             }
;             asm volatile("s_waitcnt lgkmcnt(0)" ::: "memory");
;             if (q == 3) {
; #pragma unroll
;                 for (int r = 0; r < 4; ++r) STASH[256 * p + 16 * (grp + 4 * r) + pc] = f2bf(asc * (float)(2 * ((accH[r] << 4) + accL[r]) + sa));
	v_add_u32_e32 v143, 8, v139
	v_and_b32_e32 v142, 15, v143
	v_xor_b32_e32 v142, 8, v142
	v_bfe_u32 v144, v143, 4, 4
	v_mul_lo_u32 v142, v142, s92
	v_mul_lo_u32 v144, v144, s92
	v_mov_b32_e32 v143, v142
	v_mov_b32_e32 v145, v144
	ds_write2st64_b64 v159, v[142:143], v[144:145] offset1:2
	v_and_b32_e32 v78, 0xffff, v28
	v_lshrrev_b32_e32 v79, 16, v28
	v_lshl_add_u32 v78, v78, 7, v152
	v_lshl_add_u32 v79, v79, 7, v153
	s_mov_b32 m0, s76
	s_add_i32 s43, s76, 0x400
	global_load_lds_dwordx4 v78, s[50:51]
	s_mov_b32 m0, s43
	s_nop 0
	global_load_lds_dwordx4 v79, s[50:51]
	s_waitcnt vmcnt(8)
	v_add_u32_e32 v54, s78, v59
	v_add_u32_e32 v55, s78, v60
	v_add_u32_e32 v56, s78, v61
	v_add_u32_e32 v57, s78, v62
	ds_read_b64_tr_b4 v[46:47], v160 offset:768
	ds_read_b64_tr_b4 v[48:49], v160 offset:1792
	ds_read_b64_tr_b4 v[122:123], v54
	ds_read_b64_tr_b4 v[124:125], v55
	ds_read_b64_tr_b4 v[126:127], v56
	ds_read_b64_tr_b4 v[128:129], v57
	s_waitcnt lgkmcnt(7)
	v_dot8c_i32_i4_e32 v38, v130, v52
	v_dot8c_i32_i4_e32 v39, v130, v50
	v_dot8c_i32_i4_e32 v40, v132, v52
	v_dot8c_i32_i4_e32 v41, v132, v50
	v_dot8c_i32_i4_e32 v42, v134, v52
	v_dot8c_i32_i4_e32 v43, v134, v50
	v_dot8c_i32_i4_e32 v44, v136, v52
	v_dot8c_i32_i4_e32 v45, v136, v50
	v_dot8c_i32_i4_e32 v38, v131, v53
	v_dot8c_i32_i4_e32 v39, v131, v51
	v_dot8c_i32_i4_e32 v40, v133, v53
	v_dot8c_i32_i4_e32 v41, v133, v51
	v_dot8c_i32_i4_e32 v42, v135, v53
	v_dot8c_i32_i4_e32 v43, v135, v51
	v_dot8c_i32_i4_e32 v44, v137, v53
	v_dot8c_i32_i4_e32 v45, v137, v51
	v_and_b32_e32 v78, 0xffff, v29
	v_lshrrev_b32_e32 v79, 16, v29
	v_lshl_add_u32 v78, v78, 7, v152
	v_lshl_add_u32 v79, v79, 7, v153
	s_mov_b32 m0, s77
	s_add_i32 s43, s77, 0x400
	global_load_lds_dwordx4 v78, s[50:51]
	s_mov_b32 m0, s43
	s_nop 0
	global_load_lds_dwordx4 v79, s[50:51]
	s_waitcnt vmcnt(8)
	v_add_u32_e32 v54, s79, v59
	v_add_u32_e32 v55, s79, v60
	v_add_u32_e32 v56, s79, v61
	v_add_u32_e32 v57, s79, v62
	ds_read_b64_tr_b4 v[50:51], v160 offset:896
	ds_read_b64_tr_b4 v[52:53], v160 offset:1920
	ds_read_b64_tr_b4 v[130:131], v54
	ds_read_b64_tr_b4 v[132:133], v55
	ds_read_b64_tr_b4 v[134:135], v56
	ds_read_b64_tr_b4 v[136:137], v57
	s_waitcnt lgkmcnt(6)
	v_dot8c_i32_i4_e32 v38, v122, v48
	v_dot8c_i32_i4_e32 v39, v122, v46
	v_dot8c_i32_i4_e32 v40, v124, v48
	v_dot8c_i32_i4_e32 v41, v124, v46
	v_dot8c_i32_i4_e32 v42, v126, v48
	v_dot8c_i32_i4_e32 v43, v126, v46
	v_dot8c_i32_i4_e32 v44, v128, v48
	v_dot8c_i32_i4_e32 v45, v128, v46
	v_dot8c_i32_i4_e32 v38, v123, v49
	v_dot8c_i32_i4_e32 v39, v123, v47
	v_dot8c_i32_i4_e32 v40, v125, v49
	v_dot8c_i32_i4_e32 v41, v125, v47
	v_dot8c_i32_i4_e32 v42, v127, v49
	v_dot8c_i32_i4_e32 v43, v127, v47
	v_dot8c_i32_i4_e32 v44, v129, v49
	v_dot8c_i32_i4_e32 v45, v129, v47
	v_and_b32_e32 v78, 0xffff, v30
	v_lshrrev_b32_e32 v79, 16, v30
	v_lshl_add_u32 v78, v78, 7, v152
	v_lshl_add_u32 v79, v79, 7, v153
	s_mov_b32 m0, s78
	s_add_i32 s43, s78, 0x400
	global_load_lds_dwordx4 v78, s[50:51]
	s_mov_b32 m0, s43
	s_nop 0
	global_load_lds_dwordx4 v79, s[50:51]
	s_waitcnt vmcnt(8)
	v_add_u32_e32 v54, s98, v59
	v_add_u32_e32 v55, s98, v60
	v_add_u32_e32 v56, s98, v61
	v_add_u32_e32 v57, s98, v62
	ds_read_b64_tr_b4 v[46:47], v160
	ds_read_b64_tr_b4 v[48:49], v160 offset:1024
	ds_read_b64_tr_b4 v[122:123], v54
	ds_read_b64_tr_b4 v[124:125], v55
	ds_read_b64_tr_b4 v[126:127], v56
	ds_read_b64_tr_b4 v[128:129], v57
	s_waitcnt lgkmcnt(6)
	v_dot8c_i32_i4_e32 v38, v130, v52
	v_dot8c_i32_i4_e32 v39, v130, v50
	v_dot8c_i32_i4_e32 v40, v132, v52
	v_dot8c_i32_i4_e32 v41, v132, v50
	v_dot8c_i32_i4_e32 v42, v134, v52
	v_dot8c_i32_i4_e32 v43, v134, v50
	v_dot8c_i32_i4_e32 v44, v136, v52
	v_dot8c_i32_i4_e32 v45, v136, v50
	v_dot8c_i32_i4_e32 v38, v131, v53
	v_dot8c_i32_i4_e32 v39, v131, v51
	v_dot8c_i32_i4_e32 v40, v133, v53
	v_dot8c_i32_i4_e32 v41, v133, v51
	v_dot8c_i32_i4_e32 v42, v135, v53
	v_dot8c_i32_i4_e32 v43, v135, v51
	v_dot8c_i32_i4_e32 v44, v137, v53
	v_dot8c_i32_i4_e32 v45, v137, v51
	s_nop 3
	s_waitcnt lgkmcnt(15)
	v_lshlrev_b32_e32 v38, 5, v38
	v_lshlrev_b32_e32 v39, 1, v39
	v_add3_u32 v38, v39, v229, v38
	v_cvt_f32_i32_e32 v38, v38
	v_mul_f32_e32 v38, v228, v38
	v_lshlrev_b32_e32 v40, 5, v40
	v_lshlrev_b32_e32 v41, 1, v41
	v_add3_u32 v40, v41, v229, v40
	v_cvt_f32_i32_e32 v40, v40
	v_mul_f32_e32 v40, v228, v40
	v_lshlrev_b32_e32 v42, 5, v42
	v_lshlrev_b32_e32 v43, 1, v43
	v_add3_u32 v42, v43, v229, v42
	v_cvt_f32_i32_e32 v42, v42
	v_mul_f32_e32 v42, v228, v42
	v_lshlrev_b32_e32 v44, 5, v44
	v_lshlrev_b32_e32 v45, 1, v45
	v_add3_u32 v44, v45, v229, v44
	v_cvt_f32_i32_e32 v44, v44
	v_mul_f32_e32 v44, v228, v44
	v_cvt_pk_bf16_f32 v164, v38, v40
	v_cvt_pk_bf16_f32 v165, v42, v44
	v_add_u32_e32 v147, 8, v140
	v_and_b32_e32 v146, 15, v147
	v_xor_b32_e32 v146, 8, v146
	v_bfe_u32 v148, v147, 4, 4
	v_mul_lo_u32 v146, v146, s92
	v_mul_lo_u32 v148, v148, s92
	v_mov_b32_e32 v147, v146
	v_mov_b32_e32 v149, v148
	ds_write2st64_b64 v77, v[146:147], v[148:149] offset1:2
	v_add_u32_e32 v138, 0x800, v74
	ds_read_u8 v139, v138
	v_add_u32_e32 v141, 0x800, v73
	ds_read_u8 v140, v141
	s_add_i32 s43, s67, 32
	v_mov_b32_e32 v138, s43
	ds_read2st64_b32 v[228:229], v138 offset1:1
	ds_read_b128 v[18:21], v227 offset:4096
	ds_read_b128 v[22:25], v227 offset:4112
	v_mov_b32_e32 v38, 0
	v_mov_b32_e32 v39, 0
	v_mov_b32_e32 v40, 0
	v_mov_b32_e32 v41, 0
	v_mov_b32_e32 v42, 0
	v_mov_b32_e32 v43, 0
	v_mov_b32_e32 v44, 0
	v_mov_b32_e32 v45, 0
	v_and_b32_e32 v78, 0xffff, v31
	v_lshrrev_b32_e32 v79, 16, v31
	v_lshl_add_u32 v78, v78, 7, v152
	v_lshl_add_u32 v79, v79, 7, v153
	s_mov_b32 m0, s79
	s_add_i32 s43, s79, 0x400
	global_load_lds_dwordx4 v78, s[50:51]
	s_mov_b32 m0, s43
	s_nop 0
	global_load_lds_dwordx4 v79, s[50:51]
	s_waitcnt vmcnt(8)
; #define TR4(p_) __builtin_amdgcn_ds_read_tr4_b64_v2i32((LAS v2i*)(p_))
; #define VDMA(st_, k_) do { _Pragma("unroll") for (int i_ = 0; i_ < 4; ++i_) { \
;         const unsigned off_ = (unsigned)((st_) >> 2) * (16384u * 128u) + (PE_ID(E, 4 * ((st_) & 3) + i_) << 7) + ((i_ & 1) ? cx1 : cx0); \
;         __builtin_amdgcn_global_load_lds((const unsigned*)(V4 + off_), (LAS unsigned*)(ldsb + BUF[k_] + 1024 * i_), 16, 0, 0); } } while (0)
; __device__ __forceinline__ void peer_v_tokens(int j, const LAS unsigned short* EL, const LAS unsigned char* AL  , const LAS float* ASC  , const LAS int* SAL  , ...
;     ...
;         for (int st = 0; st < 16; ++st) {
;             const int p = st >> 2, q = st & 3;
;             if (st < 14) VDMA(st + 2, (st + 2) % 3);
;             if (st < 14) asm volatile("s_waitcnt vmcnt(8)" ::: "memory");
;             else if (st == 14) asm volatile("s_waitcnt vmcnt(4)" ::: "memory");
;             else asm volatile("s_waitcnt vmcnt(0)" ::: "memory");
;             if (q == 0) {
; #pragma unroll
;                 for (int r = 0; r < 4; ++r) { accH[r] = 0; accL[r] = 0; } }
; #pragma unroll
;             for (int tp = 0; tp < 2; ++tp) {
;                 const v2i ao = TR4(ATL + (2 * q + tp) * 128 + 8 * s16), ah = TR4(ATL + 1024 + (2 * q + tp) * 128 + 8 * s16);
; #pragma unroll
;                 for (int r = 0; r < 4; ++r) {
;                     const v2i d = TR4(ldsb + BUF[st % 3] + 2048 * tp + roff[r]);
;                     accH[r] = __builtin_amdgcn_sdot8(d.x, ah.x, accH[r], false); accH[r] = __builtin_amdgcn_sdot8(d.y, ah.y, accH[r], false);
;                     accL[r] = __builtin_amdgcn_sdot8(d.x, ao.x, accL[r], false); accL[r] = __builtin_amdgcn_sdot8(d.y, ao.y, accL[r], false);
;                 }
;             }
	v_add_u32_e32 v54, s99, v59
	v_add_u32_e32 v55, s99, v60
	v_add_u32_e32 v56, s99, v61
	v_add_u32_e32 v57, s99, v62
	ds_read_b64_tr_b4 v[50:51], v160 offset:128
	ds_read_b64_tr_b4 v[52:53], v160 offset:1152
	ds_read_b64_tr_b4 v[130:131], v54
	ds_read_b64_tr_b4 v[132:133], v55
	ds_read_b64_tr_b4 v[134:135], v56
	ds_read_b64_tr_b4 v[136:137], v57
	s_waitcnt lgkmcnt(12)
	v_dot8c_i32_i4_e32 v38, v122, v48
	v_dot8c_i32_i4_e32 v39, v122, v46
	v_dot8c_i32_i4_e32 v40, v124, v48
	v_dot8c_i32_i4_e32 v41, v124, v46
	v_dot8c_i32_i4_e32 v42, v126, v48
	v_dot8c_i32_i4_e32 v43, v126, v46
	v_dot8c_i32_i4_e32 v44, v128, v48
	v_dot8c_i32_i4_e32 v45, v128, v46
	v_dot8c_i32_i4_e32 v38, v123, v49
	v_dot8c_i32_i4_e32 v39, v123, v47
	v_dot8c_i32_i4_e32 v40, v125, v49
	v_dot8c_i32_i4_e32 v41, v125, v47
	v_dot8c_i32_i4_e32 v42, v127, v49
	v_dot8c_i32_i4_e32 v43, v127, v47
	v_dot8c_i32_i4_e32 v44, v129, v49
	v_dot8c_i32_i4_e32 v45, v129, v47
	v_and_b32_e32 v78, 0xffff, v32
	v_lshrrev_b32_e32 v79, 16, v32
	v_lshl_add_u32 v78, v78, 7, v152
	v_lshl_add_u32 v79, v79, 7, v153
	s_mov_b32 m0, s98
	s_add_i32 s43, s98, 0x400
	global_load_lds_dwordx4 v78, s[50:51]
	s_mov_b32 m0, s43
	s_nop 0
	global_load_lds_dwordx4 v79, s[50:51]
	s_waitcnt vmcnt(8)
	v_add_u32_e32 v54, s76, v59
	v_add_u32_e32 v55, s76, v60
	v_add_u32_e32 v56, s76, v61
	v_add_u32_e32 v57, s76, v62
	ds_read_b64_tr_b4 v[46:47], v160 offset:256
	ds_read_b64_tr_b4 v[48:49], v160 offset:1280
	ds_read_b64_tr_b4 v[122:123], v54
	ds_read_b64_tr_b4 v[124:125], v55
	ds_read_b64_tr_b4 v[126:127], v56
	ds_read_b64_tr_b4 v[128:129], v57
	s_waitcnt lgkmcnt(6)
	v_dot8c_i32_i4_e32 v38, v130, v52
	v_dot8c_i32_i4_e32 v39, v130, v50
	v_dot8c_i32_i4_e32 v40, v132, v52
	v_dot8c_i32_i4_e32 v41, v132, v50
	v_dot8c_i32_i4_e32 v42, v134, v52
	v_dot8c_i32_i4_e32 v43, v134, v50
	v_dot8c_i32_i4_e32 v44, v136, v52
	v_dot8c_i32_i4_e32 v45, v136, v50
	v_dot8c_i32_i4_e32 v38, v131, v53
	v_dot8c_i32_i4_e32 v39, v131, v51
	v_dot8c_i32_i4_e32 v40, v133, v53
	v_dot8c_i32_i4_e32 v41, v133, v51
	v_dot8c_i32_i4_e32 v42, v135, v53
	v_dot8c_i32_i4_e32 v43, v135, v51
	v_dot8c_i32_i4_e32 v44, v137, v53
	v_dot8c_i32_i4_e32 v45, v137, v51
	v_and_b32_e32 v78, 0xffff, v33
	v_lshrrev_b32_e32 v79, 16, v33
	v_lshl_add_u32 v78, v78, 7, v152
	v_lshl_add_u32 v79, v79, 7, v153
	s_mov_b32 m0, s99
	s_add_i32 s43, s99, 0x400
	global_load_lds_dwordx4 v78, s[50:51]
	s_mov_b32 m0, s43
	s_nop 0
	global_load_lds_dwordx4 v79, s[50:51]
	s_waitcnt vmcnt(8)
	v_add_u32_e32 v54, s77, v59
	v_add_u32_e32 v55, s77, v60
	v_add_u32_e32 v56, s77, v61
	v_add_u32_e32 v57, s77, v62
	ds_read_b64_tr_b4 v[50:51], v160 offset:384
	ds_read_b64_tr_b4 v[52:53], v160 offset:1408
	ds_read_b64_tr_b4 v[130:131], v54
	ds_read_b64_tr_b4 v[132:133], v55
	ds_read_b64_tr_b4 v[134:135], v56
	ds_read_b64_tr_b4 v[136:137], v57
	s_waitcnt lgkmcnt(6)
	v_dot8c_i32_i4_e32 v38, v122, v48
	v_dot8c_i32_i4_e32 v39, v122, v46
	v_dot8c_i32_i4_e32 v40, v124, v48
	v_dot8c_i32_i4_e32 v41, v124, v46
	v_dot8c_i32_i4_e32 v42, v126, v48
	v_dot8c_i32_i4_e32 v43, v126, v46
	v_dot8c_i32_i4_e32 v44, v128, v48
	v_dot8c_i32_i4_e32 v45, v128, v46
	v_dot8c_i32_i4_e32 v38, v123, v49
	v_dot8c_i32_i4_e32 v39, v123, v47
	v_dot8c_i32_i4_e32 v40, v125, v49
	v_dot8c_i32_i4_e32 v41, v125, v47
	v_dot8c_i32_i4_e32 v42, v127, v49
	v_dot8c_i32_i4_e32 v43, v127, v47
	v_dot8c_i32_i4_e32 v44, v129, v49
	v_dot8c_i32_i4_e32 v45, v129, v47
	s_waitcnt lgkmcnt(15)
	v_and_b32_e32 v78, 0xffff, v18
	v_lshrrev_b32_e32 v79, 16, v18
	v_lshl_add_u32 v78, v78, 7, v152
	v_lshl_add_u32 v79, v79, 7, v153
	s_mov_b32 m0, s76
	s_add_i32 s43, s76, 0x400
	global_load_lds_dwordx4 v78, s[50:51]
	s_mov_b32 m0, s43
	s_nop 0
	global_load_lds_dwordx4 v79, s[50:51]
	s_waitcnt vmcnt(8)
	v_add_u32_e32 v54, s78, v59
	v_add_u32_e32 v55, s78, v60
	v_add_u32_e32 v56, s78, v61
	v_add_u32_e32 v57, s78, v62
	ds_read_b64_tr_b4 v[46:47], v160 offset:512
	ds_read_b64_tr_b4 v[48:49], v160 offset:1536
	ds_read_b64_tr_b4 v[122:123], v54
	ds_read_b64_tr_b4 v[124:125], v55
	ds_read_b64_tr_b4 v[126:127], v56
	ds_read_b64_tr_b4 v[128:129], v57
	s_waitcnt lgkmcnt(6)
	v_dot8c_i32_i4_e32 v38, v130, v52
	v_dot8c_i32_i4_e32 v39, v130, v50
	v_dot8c_i32_i4_e32 v40, v132, v52
	v_dot8c_i32_i4_e32 v41, v132, v50
	v_dot8c_i32_i4_e32 v42, v134, v52
	v_dot8c_i32_i4_e32 v43, v134, v50
	v_dot8c_i32_i4_e32 v44, v136, v52
	v_dot8c_i32_i4_e32 v45, v136, v50
	v_dot8c_i32_i4_e32 v38, v131, v53
	v_dot8c_i32_i4_e32 v39, v131, v51
	v_dot8c_i32_i4_e32 v40, v133, v53
	v_dot8c_i32_i4_e32 v41, v133, v51
	v_dot8c_i32_i4_e32 v42, v135, v53
	v_dot8c_i32_i4_e32 v43, v135, v51
	v_dot8c_i32_i4_e32 v44, v137, v53
	v_dot8c_i32_i4_e32 v45, v137, v51
	v_and_b32_e32 v78, 0xffff, v19
	v_lshrrev_b32_e32 v79, 16, v19
	v_lshl_add_u32 v78, v78, 7, v152
	v_lshl_add_u32 v79, v79, 7, v153
	s_mov_b32 m0, s77
	s_add_i32 s43, s77, 0x400
	global_load_lds_dwordx4 v78, s[50:51]
	s_mov_b32 m0, s43
	s_nop 0
	global_load_lds_dwordx4 v79, s[50:51]
	s_waitcnt vmcnt(8)
	v_add_u32_e32 v54, s79, v59
	v_add_u32_e32 v55, s79, v60
	v_add_u32_e32 v56, s79, v61
	v_add_u32_e32 v57, s79, v62
	ds_read_b64_tr_b4 v[50:51], v160 offset:640
	ds_read_b64_tr_b4 v[52:53], v160 offset:1664
	ds_read_b64_tr_b4 v[130:131], v54
	ds_read_b64_tr_b4 v[132:133], v55
	ds_read_b64_tr_b4 v[134:135], v56
	ds_read_b64_tr_b4 v[136:137], v57
	s_waitcnt lgkmcnt(6)
	v_dot8c_i32_i4_e32 v38, v122, v48
	v_dot8c_i32_i4_e32 v39, v122, v46
	v_dot8c_i32_i4_e32 v40, v124, v48
	v_dot8c_i32_i4_e32 v41, v124, v46
	v_dot8c_i32_i4_e32 v42, v126, v48
	v_dot8c_i32_i4_e32 v43, v126, v46
	v_dot8c_i32_i4_e32 v44, v128, v48
	v_dot8c_i32_i4_e32 v45, v128, v46
	v_dot8c_i32_i4_e32 v38, v123, v49
	v_dot8c_i32_i4_e32 v39, v123, v47
	v_dot8c_i32_i4_e32 v40, v125, v49
	v_dot8c_i32_i4_e32 v41, v125, v47
	v_dot8c_i32_i4_e32 v42, v127, v49
	v_dot8c_i32_i4_e32 v43, v127, v47
	v_dot8c_i32_i4_e32 v44, v129, v49
	v_dot8c_i32_i4_e32 v45, v129, v47
	s_waitcnt lgkmcnt(15)
; #define LAS __attribute__((address_space(3)))
; __device__ __forceinline__ void peer_v_tokens(int j, const LAS unsigned short* EL, const LAS unsigned char* AL  , const LAS float* ASC  , const LAS int* SAL  , ...
;     ...
;         { const LAS v4u* ep = (const LAS v4u*)(EL + tl * 128 + 16 * g); const v4u e0 = ep[0], e1 = ep[1];
;           E[0] = e0.x; E[1] = e0.y; E[2] = e0.z; E[3] = e0.w; E[4] = e1.x; E[5] = e1.y; E[6] = e1.z; E[7] = e1.w; }
;         uint2 hv[4]; float4 gv[4];
;         { unsigned ho = (unsigned)t * (D / 4) + (unsigned)lane; asm volatile("" : "+v"(ho)); const uint2* hp = (const uint2*)HB + ho; const float4* gp = (const float4*)fng + lane;
; #pragma unroll
;           for (int jq = 0; jq < 4; ++jq) { hv[jq] = hp[64 * jq]; gv[jq] = gp[64 * jq]; } }
;         VDMA(0, 0); VDMA(1, 1);
; #pragma unroll
;         for (int m = 0; m < 2; ++m) {
;             const int idx = lane + 64 * m, tau = idx >> 4, sr = idx & 15, k = 16 * (sr & 7) + 2 * tau + (sr >> 3);
;     ...
;         for (int st = 0; st < 16; ++st) {
;             const int p = st >> 2, q = st & 3;
;             if (st < 14) VDMA(st + 2, (st + 2) % 3);
;             if (st < 14) asm volatile("s_waitcnt vmcnt(8)" ::: "memory");
;             else if (st == 14) asm volatile("s_waitcnt vmcnt(4)" ::: "memory");
;             else asm volatile("s_waitcnt vmcnt(0)" ::: "memory");
;             if (q == 0) {
; #pragma unroll
;                 for (int r = 0; r < 4; ++r) { accH[r] = 0; accL[r] = 0; } }
; #pragma unroll
;             for (int tp = 0; tp < 2; ++tp) {
;                 const v2i ao = TR4(ATL + (2 * q + tp) * 128 + 8 * s16), ah = TR4(ATL + 1024 + (2 * q + tp) * 128 + 8 * s16);
; #pragma unroll
;                 for (int r = 0; r < 4; ++r) {
;                     const v2i d = TR4(ldsb + BUF[st % 3] + 2048 * tp + roff[r]);
;                     accH[r] = __builtin_amdgcn_sdot8(d.x, ah.x, accH[r], false); accH[r] = __builtin_amdgcn_sdot8(d.y, ah.y, accH[r], false);
;                     accL[r] = __builtin_amdgcn_sdot8(d.x, ao.x, accL[r], false); accL[r] = __builtin_amdgcn_sdot8(d.y, ao.y, accL[r], false);
;                 }
;             }
;             asm volatile("s_waitcnt lgkmcnt(0)" ::: "memory");
;             if (q == 3) {
; #pragma unroll
;                 for (int r = 0; r < 4; ++r) STASH[256 * p + 16 * (grp + 4 * r) + pc] = f2bf(asc * (float)(2 * ((accH[r] << 4) + accL[r]) + sa));
	v_add_u32_e32 v143, 8, v139
	v_and_b32_e32 v142, 15, v143
	v_xor_b32_e32 v142, 8, v142
	v_bfe_u32 v144, v143, 4, 4
	v_mul_lo_u32 v142, v142, s92
	v_mul_lo_u32 v144, v144, s92
	v_mov_b32_e32 v143, v142
	v_mov_b32_e32 v145, v144
	ds_write2st64_b64 v159, v[142:143], v[144:145] offset1:2
	v_and_b32_e32 v78, 0xffff, v20
	v_lshrrev_b32_e32 v79, 16, v20
	v_lshl_add_u32 v78, v78, 7, v152
	v_lshl_add_u32 v79, v79, 7, v153
	s_mov_b32 m0, s78
	s_add_i32 s43, s78, 0x400
	global_load_lds_dwordx4 v78, s[50:51]
	s_mov_b32 m0, s43
	s_nop 0
	global_load_lds_dwordx4 v79, s[50:51]
	s_waitcnt vmcnt(8)
	v_add_u32_e32 v54, s98, v59
	v_add_u32_e32 v55, s98, v60
	v_add_u32_e32 v56, s98, v61
	v_add_u32_e32 v57, s98, v62
	ds_read_b64_tr_b4 v[46:47], v160 offset:768
	ds_read_b64_tr_b4 v[48:49], v160 offset:1792
	ds_read_b64_tr_b4 v[122:123], v54
	ds_read_b64_tr_b4 v[124:125], v55
	ds_read_b64_tr_b4 v[126:127], v56
	ds_read_b64_tr_b4 v[128:129], v57
	s_waitcnt lgkmcnt(7)
	v_dot8c_i32_i4_e32 v38, v130, v52
	v_dot8c_i32_i4_e32 v39, v130, v50
	v_dot8c_i32_i4_e32 v40, v132, v52
	v_dot8c_i32_i4_e32 v41, v132, v50
	v_dot8c_i32_i4_e32 v42, v134, v52
	v_dot8c_i32_i4_e32 v43, v134, v50
	v_dot8c_i32_i4_e32 v44, v136, v52
	v_dot8c_i32_i4_e32 v45, v136, v50
	v_dot8c_i32_i4_e32 v38, v131, v53
	v_dot8c_i32_i4_e32 v39, v131, v51
	v_dot8c_i32_i4_e32 v40, v133, v53
	v_dot8c_i32_i4_e32 v41, v133, v51
	v_dot8c_i32_i4_e32 v42, v135, v53
	v_dot8c_i32_i4_e32 v43, v135, v51
	v_dot8c_i32_i4_e32 v44, v137, v53
	v_dot8c_i32_i4_e32 v45, v137, v51
	v_and_b32_e32 v78, 0xffff, v21
	v_lshrrev_b32_e32 v79, 16, v21
	v_lshl_add_u32 v78, v78, 7, v152
	v_lshl_add_u32 v79, v79, 7, v153
	s_mov_b32 m0, s79
	s_add_i32 s43, s79, 0x400
	global_load_lds_dwordx4 v78, s[50:51]
	s_mov_b32 m0, s43
	s_nop 0
	global_load_lds_dwordx4 v79, s[50:51]
	s_waitcnt vmcnt(8)
	v_add_u32_e32 v54, s99, v59
	v_add_u32_e32 v55, s99, v60
	v_add_u32_e32 v56, s99, v61
	v_add_u32_e32 v57, s99, v62
	ds_read_b64_tr_b4 v[50:51], v160 offset:896
	ds_read_b64_tr_b4 v[52:53], v160 offset:1920
	ds_read_b64_tr_b4 v[130:131], v54
	ds_read_b64_tr_b4 v[132:133], v55
	ds_read_b64_tr_b4 v[134:135], v56
	ds_read_b64_tr_b4 v[136:137], v57
	s_waitcnt lgkmcnt(6)
	v_dot8c_i32_i4_e32 v38, v122, v48
	v_dot8c_i32_i4_e32 v39, v122, v46
	v_dot8c_i32_i4_e32 v40, v124, v48
	v_dot8c_i32_i4_e32 v41, v124, v46
	v_dot8c_i32_i4_e32 v42, v126, v48
	v_dot8c_i32_i4_e32 v43, v126, v46
	v_dot8c_i32_i4_e32 v44, v128, v48
	v_dot8c_i32_i4_e32 v45, v128, v46
	v_dot8c_i32_i4_e32 v38, v123, v49
	v_dot8c_i32_i4_e32 v39, v123, v47
	v_dot8c_i32_i4_e32 v40, v125, v49
	v_dot8c_i32_i4_e32 v41, v125, v47
	v_dot8c_i32_i4_e32 v42, v127, v49
	v_dot8c_i32_i4_e32 v43, v127, v47
	v_dot8c_i32_i4_e32 v44, v129, v49
	v_dot8c_i32_i4_e32 v45, v129, v47
	v_and_b32_e32 v78, 0xffff, v22
	v_lshrrev_b32_e32 v79, 16, v22
	v_lshl_add_u32 v78, v78, 7, v152
	v_lshl_add_u32 v79, v79, 7, v153
	s_mov_b32 m0, s98
	s_add_i32 s43, s98, 0x400
	global_load_lds_dwordx4 v78, s[50:51]
	s_mov_b32 m0, s43
	s_nop 0
	global_load_lds_dwordx4 v79, s[50:51]
	s_waitcnt vmcnt(8)
	v_add_u32_e32 v54, s76, v59
	v_add_u32_e32 v55, s76, v60
	v_add_u32_e32 v56, s76, v61
	v_add_u32_e32 v57, s76, v62
	ds_read_b64_tr_b4 v[46:47], v160
	ds_read_b64_tr_b4 v[48:49], v160 offset:1024
	ds_read_b64_tr_b4 v[122:123], v54
	ds_read_b64_tr_b4 v[124:125], v55
	ds_read_b64_tr_b4 v[126:127], v56
	ds_read_b64_tr_b4 v[128:129], v57
	s_waitcnt lgkmcnt(6)
	v_dot8c_i32_i4_e32 v38, v130, v52
	v_dot8c_i32_i4_e32 v39, v130, v50
	v_dot8c_i32_i4_e32 v40, v132, v52
	v_dot8c_i32_i4_e32 v41, v132, v50
	v_dot8c_i32_i4_e32 v42, v134, v52
	v_dot8c_i32_i4_e32 v43, v134, v50
	v_dot8c_i32_i4_e32 v44, v136, v52
	v_dot8c_i32_i4_e32 v45, v136, v50
	v_dot8c_i32_i4_e32 v38, v131, v53
	v_dot8c_i32_i4_e32 v39, v131, v51
	v_dot8c_i32_i4_e32 v40, v133, v53
	v_dot8c_i32_i4_e32 v41, v133, v51
	v_dot8c_i32_i4_e32 v42, v135, v53
	v_dot8c_i32_i4_e32 v43, v135, v51
	v_dot8c_i32_i4_e32 v44, v137, v53
	v_dot8c_i32_i4_e32 v45, v137, v51
	s_nop 3
	s_waitcnt lgkmcnt(15)
	v_lshlrev_b32_e32 v38, 5, v38
	v_lshlrev_b32_e32 v39, 1, v39
	v_add3_u32 v38, v39, v229, v38
	v_cvt_f32_i32_e32 v38, v38
	v_mul_f32_e32 v38, v228, v38
	v_lshlrev_b32_e32 v40, 5, v40
	v_lshlrev_b32_e32 v41, 1, v41
	v_add3_u32 v40, v41, v229, v40
	v_cvt_f32_i32_e32 v40, v40
	v_mul_f32_e32 v40, v228, v40
	v_lshlrev_b32_e32 v42, 5, v42
	v_lshlrev_b32_e32 v43, 1, v43
	v_add3_u32 v42, v43, v229, v42
	v_cvt_f32_i32_e32 v42, v42
	v_mul_f32_e32 v42, v228, v42
	v_lshlrev_b32_e32 v44, 5, v44
	v_lshlrev_b32_e32 v45, 1, v45
	v_add3_u32 v44, v45, v229, v44
	v_cvt_f32_i32_e32 v44, v44
	v_mul_f32_e32 v44, v228, v44
	v_cvt_pk_bf16_f32 v172, v38, v40
	v_cvt_pk_bf16_f32 v173, v42, v44
	v_add_u32_e32 v147, 8, v140
	v_and_b32_e32 v146, 15, v147
	v_xor_b32_e32 v146, 8, v146
	v_bfe_u32 v148, v147, 4, 4
	v_mul_lo_u32 v146, v146, s92
	v_mul_lo_u32 v148, v148, s92
	v_mov_b32_e32 v147, v146
	v_mov_b32_e32 v149, v148
	ds_write2st64_b64 v77, v[146:147], v[148:149] offset1:2
	v_add_u32_e32 v138, 0xc00, v74
	ds_read_u8 v139, v138
	v_add_u32_e32 v141, 0xc00, v73
	ds_read_u8 v140, v141
	s_add_i32 s43, s67, 64
	v_mov_b32_e32 v138, s43
	ds_read2st64_b32 v[228:229], v138 offset1:1
	ds_read_b128 v[26:29], v227 offset:6144
	ds_read_b128 v[30:33], v227 offset:6160
	v_mov_b32_e32 v38, 0
	v_mov_b32_e32 v39, 0
	v_mov_b32_e32 v40, 0
	v_mov_b32_e32 v41, 0
	v_mov_b32_e32 v42, 0
	v_mov_b32_e32 v43, 0
	v_mov_b32_e32 v44, 0
	v_mov_b32_e32 v45, 0
	v_and_b32_e32 v78, 0xffff, v23
	v_lshrrev_b32_e32 v79, 16, v23
	v_lshl_add_u32 v78, v78, 7, v152
	v_lshl_add_u32 v79, v79, 7, v153
	s_mov_b32 m0, s99
	s_add_i32 s43, s99, 0x400
	global_load_lds_dwordx4 v78, s[50:51]
	s_mov_b32 m0, s43
	s_nop 0
	global_load_lds_dwordx4 v79, s[50:51]
	s_waitcnt vmcnt(8)
; #define TR4(p_) __builtin_amdgcn_ds_read_tr4_b64_v2i32((LAS v2i*)(p_))
; #define VDMA(st_, k_) do { _Pragma("unroll") for (int i_ = 0; i_ < 4; ++i_) { \
;         const unsigned off_ = (unsigned)((st_) >> 2) * (16384u * 128u) + (PE_ID(E, 4 * ((st_) & 3) + i_) << 7) + ((i_ & 1) ? cx1 : cx0); \
;         __builtin_amdgcn_global_load_lds((const unsigned*)(V4 + off_), (LAS unsigned*)(ldsb + BUF[k_] + 1024 * i_), 16, 0, 0); } } while (0)
; __device__ __forceinline__ void peer_v_tokens(int j, const LAS unsigned short* EL, const LAS unsigned char* AL  , const LAS float* ASC  , const LAS int* SAL  , ...
;     ...
;         for (int st = 0; st < 16; ++st) {
;             const int p = st >> 2, q = st & 3;
;             if (st < 14) VDMA(st + 2, (st + 2) % 3);
;             if (st < 14) asm volatile("s_waitcnt vmcnt(8)" ::: "memory");
;             else if (st == 14) asm volatile("s_waitcnt vmcnt(4)" ::: "memory");
;             else asm volatile("s_waitcnt vmcnt(0)" ::: "memory");
;             if (q == 0) {
; #pragma unroll
;                 for (int r = 0; r < 4; ++r) { accH[r] = 0; accL[r] = 0; } }
; #pragma unroll
;             for (int tp = 0; tp < 2; ++tp) {
;                 const v2i ao = TR4(ATL + (2 * q + tp) * 128 + 8 * s16), ah = TR4(ATL + 1024 + (2 * q + tp) * 128 + 8 * s16);
; #pragma unroll
;                 for (int r = 0; r < 4; ++r) {
;                     const v2i d = TR4(ldsb + BUF[st % 3] + 2048 * tp + roff[r]);
;                     accH[r] = __builtin_amdgcn_sdot8(d.x, ah.x, accH[r], false); accH[r] = __builtin_amdgcn_sdot8(d.y, ah.y, accH[r], false);
;                     accL[r] = __builtin_amdgcn_sdot8(d.x, ao.x, accL[r], false); accL[r] = __builtin_amdgcn_sdot8(d.y, ao.y, accL[r], false);
;                 }
;             }
	v_add_u32_e32 v54, s77, v59
	v_add_u32_e32 v55, s77, v60
	v_add_u32_e32 v56, s77, v61
	v_add_u32_e32 v57, s77, v62
	ds_read_b64_tr_b4 v[50:51], v160 offset:128
	ds_read_b64_tr_b4 v[52:53], v160 offset:1152
	ds_read_b64_tr_b4 v[130:131], v54
	ds_read_b64_tr_b4 v[132:133], v55
	ds_read_b64_tr_b4 v[134:135], v56
	ds_read_b64_tr_b4 v[136:137], v57
	s_waitcnt lgkmcnt(12)
	v_dot8c_i32_i4_e32 v38, v122, v48
	v_dot8c_i32_i4_e32 v39, v122, v46
	v_dot8c_i32_i4_e32 v40, v124, v48
	v_dot8c_i32_i4_e32 v41, v124, v46
	v_dot8c_i32_i4_e32 v42, v126, v48
	v_dot8c_i32_i4_e32 v43, v126, v46
	v_dot8c_i32_i4_e32 v44, v128, v48
	v_dot8c_i32_i4_e32 v45, v128, v46
	v_dot8c_i32_i4_e32 v38, v123, v49
	v_dot8c_i32_i4_e32 v39, v123, v47
	v_dot8c_i32_i4_e32 v40, v125, v49
	v_dot8c_i32_i4_e32 v41, v125, v47
	v_dot8c_i32_i4_e32 v42, v127, v49
	v_dot8c_i32_i4_e32 v43, v127, v47
	v_dot8c_i32_i4_e32 v44, v129, v49
	v_dot8c_i32_i4_e32 v45, v129, v47
	v_and_b32_e32 v78, 0xffff, v24
	v_lshrrev_b32_e32 v79, 16, v24
	v_lshl_add_u32 v78, v78, 7, v152
	v_lshl_add_u32 v79, v79, 7, v153
	s_mov_b32 m0, s76
	s_add_i32 s43, s76, 0x400
	global_load_lds_dwordx4 v78, s[50:51]
	s_mov_b32 m0, s43
	s_nop 0
	global_load_lds_dwordx4 v79, s[50:51]
	s_waitcnt vmcnt(8)
	v_add_u32_e32 v54, s78, v59
	v_add_u32_e32 v55, s78, v60
	v_add_u32_e32 v56, s78, v61
	v_add_u32_e32 v57, s78, v62
	ds_read_b64_tr_b4 v[46:47], v160 offset:256
	ds_read_b64_tr_b4 v[48:49], v160 offset:1280
	ds_read_b64_tr_b4 v[122:123], v54
	ds_read_b64_tr_b4 v[124:125], v55
	ds_read_b64_tr_b4 v[126:127], v56
	ds_read_b64_tr_b4 v[128:129], v57
	s_waitcnt lgkmcnt(6)
	v_dot8c_i32_i4_e32 v38, v130, v52
	v_dot8c_i32_i4_e32 v39, v130, v50
	v_dot8c_i32_i4_e32 v40, v132, v52
	v_dot8c_i32_i4_e32 v41, v132, v50
	v_dot8c_i32_i4_e32 v42, v134, v52
	v_dot8c_i32_i4_e32 v43, v134, v50
	v_dot8c_i32_i4_e32 v44, v136, v52
	v_dot8c_i32_i4_e32 v45, v136, v50
	v_dot8c_i32_i4_e32 v38, v131, v53
	v_dot8c_i32_i4_e32 v39, v131, v51
	v_dot8c_i32_i4_e32 v40, v133, v53
	v_dot8c_i32_i4_e32 v41, v133, v51
	v_dot8c_i32_i4_e32 v42, v135, v53
	v_dot8c_i32_i4_e32 v43, v135, v51
	v_dot8c_i32_i4_e32 v44, v137, v53
	v_dot8c_i32_i4_e32 v45, v137, v51
	v_and_b32_e32 v78, 0xffff, v25
	v_lshrrev_b32_e32 v79, 16, v25
	v_lshl_add_u32 v78, v78, 7, v152
	v_lshl_add_u32 v79, v79, 7, v153
	s_mov_b32 m0, s77
	s_add_i32 s43, s77, 0x400
	global_load_lds_dwordx4 v78, s[50:51]
	s_mov_b32 m0, s43
	s_nop 0
	global_load_lds_dwordx4 v79, s[50:51]
	s_waitcnt vmcnt(8)
	v_add_u32_e32 v54, s79, v59
	v_add_u32_e32 v55, s79, v60
	v_add_u32_e32 v56, s79, v61
	v_add_u32_e32 v57, s79, v62
	ds_read_b64_tr_b4 v[50:51], v160 offset:384
	ds_read_b64_tr_b4 v[52:53], v160 offset:1408
	ds_read_b64_tr_b4 v[130:131], v54
	ds_read_b64_tr_b4 v[132:133], v55
	ds_read_b64_tr_b4 v[134:135], v56
	ds_read_b64_tr_b4 v[136:137], v57
	s_waitcnt lgkmcnt(6)
	v_dot8c_i32_i4_e32 v38, v122, v48
	v_dot8c_i32_i4_e32 v39, v122, v46
	v_dot8c_i32_i4_e32 v40, v124, v48
	v_dot8c_i32_i4_e32 v41, v124, v46
	v_dot8c_i32_i4_e32 v42, v126, v48
	v_dot8c_i32_i4_e32 v43, v126, v46
	v_dot8c_i32_i4_e32 v44, v128, v48
	v_dot8c_i32_i4_e32 v45, v128, v46
	v_dot8c_i32_i4_e32 v38, v123, v49
	v_dot8c_i32_i4_e32 v39, v123, v47
	v_dot8c_i32_i4_e32 v40, v125, v49
	v_dot8c_i32_i4_e32 v41, v125, v47
	v_dot8c_i32_i4_e32 v42, v127, v49
	v_dot8c_i32_i4_e32 v43, v127, v47
	v_dot8c_i32_i4_e32 v44, v129, v49
	v_dot8c_i32_i4_e32 v45, v129, v47
	s_waitcnt lgkmcnt(15)
	v_and_b32_e32 v78, 0xffff, v26
	v_lshrrev_b32_e32 v79, 16, v26
	v_lshl_add_u32 v78, v78, 7, v152
	v_lshl_add_u32 v79, v79, 7, v153
	s_mov_b32 m0, s78
	s_add_i32 s43, s78, 0x400
	global_load_lds_dwordx4 v78, s[50:51]
	s_mov_b32 m0, s43
	s_nop 0
	global_load_lds_dwordx4 v79, s[50:51]
	s_waitcnt vmcnt(8)
	v_add_u32_e32 v54, s98, v59
	v_add_u32_e32 v55, s98, v60
	v_add_u32_e32 v56, s98, v61
	v_add_u32_e32 v57, s98, v62
	ds_read_b64_tr_b4 v[46:47], v160 offset:512
	ds_read_b64_tr_b4 v[48:49], v160 offset:1536
	ds_read_b64_tr_b4 v[122:123], v54
	ds_read_b64_tr_b4 v[124:125], v55
	ds_read_b64_tr_b4 v[126:127], v56
	ds_read_b64_tr_b4 v[128:129], v57
	s_waitcnt lgkmcnt(6)
	v_dot8c_i32_i4_e32 v38, v130, v52
	v_dot8c_i32_i4_e32 v39, v130, v50
	v_dot8c_i32_i4_e32 v40, v132, v52
	v_dot8c_i32_i4_e32 v41, v132, v50
	v_dot8c_i32_i4_e32 v42, v134, v52
	v_dot8c_i32_i4_e32 v43, v134, v50
	v_dot8c_i32_i4_e32 v44, v136, v52
	v_dot8c_i32_i4_e32 v45, v136, v50
	v_dot8c_i32_i4_e32 v38, v131, v53
	v_dot8c_i32_i4_e32 v39, v131, v51
	v_dot8c_i32_i4_e32 v40, v133, v53
	v_dot8c_i32_i4_e32 v41, v133, v51
	v_dot8c_i32_i4_e32 v42, v135, v53
	v_dot8c_i32_i4_e32 v43, v135, v51
	v_dot8c_i32_i4_e32 v44, v137, v53
	v_dot8c_i32_i4_e32 v45, v137, v51
	v_and_b32_e32 v78, 0xffff, v27
	v_lshrrev_b32_e32 v79, 16, v27
	v_lshl_add_u32 v78, v78, 7, v152
	v_lshl_add_u32 v79, v79, 7, v153
	s_mov_b32 m0, s79
	s_add_i32 s43, s79, 0x400
	global_load_lds_dwordx4 v78, s[50:51]
	s_mov_b32 m0, s43
	s_nop 0
	global_load_lds_dwordx4 v79, s[50:51]
	s_waitcnt vmcnt(8)
	v_add_u32_e32 v54, s99, v59
	v_add_u32_e32 v55, s99, v60
	v_add_u32_e32 v56, s99, v61
	v_add_u32_e32 v57, s99, v62
	ds_read_b64_tr_b4 v[50:51], v160 offset:640
	ds_read_b64_tr_b4 v[52:53], v160 offset:1664
	ds_read_b64_tr_b4 v[130:131], v54
	ds_read_b64_tr_b4 v[132:133], v55
	ds_read_b64_tr_b4 v[134:135], v56
	ds_read_b64_tr_b4 v[136:137], v57
	s_waitcnt lgkmcnt(6)
	v_dot8c_i32_i4_e32 v38, v122, v48
	v_dot8c_i32_i4_e32 v39, v122, v46
	v_dot8c_i32_i4_e32 v40, v124, v48
	v_dot8c_i32_i4_e32 v41, v124, v46
	v_dot8c_i32_i4_e32 v42, v126, v48
	v_dot8c_i32_i4_e32 v43, v126, v46
	v_dot8c_i32_i4_e32 v44, v128, v48
	v_dot8c_i32_i4_e32 v45, v128, v46
	v_dot8c_i32_i4_e32 v38, v123, v49
	v_dot8c_i32_i4_e32 v39, v123, v47
	v_dot8c_i32_i4_e32 v40, v125, v49
	v_dot8c_i32_i4_e32 v41, v125, v47
	v_dot8c_i32_i4_e32 v42, v127, v49
	v_dot8c_i32_i4_e32 v43, v127, v47
	v_dot8c_i32_i4_e32 v44, v129, v49
	v_dot8c_i32_i4_e32 v45, v129, v47
	s_waitcnt lgkmcnt(15)
; #define LAS __attribute__((address_space(3)))
; __device__ __forceinline__ void peer_v_tokens(int j, const LAS unsigned short* EL, const LAS unsigned char* AL  , const LAS float* ASC  , const LAS int* SAL  , ...
;     ...
;         { const LAS v4u* ep = (const LAS v4u*)(EL + tl * 128 + 16 * g); const v4u e0 = ep[0], e1 = ep[1];
;           E[0] = e0.x; E[1] = e0.y; E[2] = e0.z; E[3] = e0.w; E[4] = e1.x; E[5] = e1.y; E[6] = e1.z; E[7] = e1.w; }
;         uint2 hv[4]; float4 gv[4];
;         { unsigned ho = (unsigned)t * (D / 4) + (unsigned)lane; asm volatile("" : "+v"(ho)); const uint2* hp = (const uint2*)HB + ho; const float4* gp = (const float4*)fng + lane;
; #pragma unroll
;           for (int jq = 0; jq < 4; ++jq) { hv[jq] = hp[64 * jq]; gv[jq] = gp[64 * jq]; } }
;         VDMA(0, 0); VDMA(1, 1);
; #pragma unroll
;         for (int m = 0; m < 2; ++m) {
;             const int idx = lane + 64 * m, tau = idx >> 4, sr = idx & 15, k = 16 * (sr & 7) + 2 * tau + (sr >> 3);
;     ...
;         for (int st = 0; st < 16; ++st) {
;             const int p = st >> 2, q = st & 3;
;             if (st < 14) VDMA(st + 2, (st + 2) % 3);
;             if (st < 14) asm volatile("s_waitcnt vmcnt(8)" ::: "memory");
;             else if (st == 14) asm volatile("s_waitcnt vmcnt(4)" ::: "memory");
;             else asm volatile("s_waitcnt vmcnt(0)" ::: "memory");
;             if (q == 0) {
; #pragma unroll
;                 for (int r = 0; r < 4; ++r) { accH[r] = 0; accL[r] = 0; } }
; #pragma unroll
;             for (int tp = 0; tp < 2; ++tp) {
;                 const v2i ao = TR4(ATL + (2 * q + tp) * 128 + 8 * s16), ah = TR4(ATL + 1024 + (2 * q + tp) * 128 + 8 * s16);
; #pragma unroll
;                 for (int r = 0; r < 4; ++r) {
;                     const v2i d = TR4(ldsb + BUF[st % 3] + 2048 * tp + roff[r]);
;                     accH[r] = __builtin_amdgcn_sdot8(d.x, ah.x, accH[r], false); accH[r] = __builtin_amdgcn_sdot8(d.y, ah.y, accH[r], false);
;                     accL[r] = __builtin_amdgcn_sdot8(d.x, ao.x, accL[r], false); accL[r] = __builtin_amdgcn_sdot8(d.y, ao.y, accL[r], false);
;                 }
;             }
;             asm volatile("s_waitcnt lgkmcnt(0)" ::: "memory");
;             if (q == 3) {
; #pragma unroll
;                 for (int r = 0; r < 4; ++r) STASH[256 * p + 16 * (grp + 4 * r) + pc] = f2bf(asc * (float)(2 * ((accH[r] << 4) + accL[r]) + sa));
	v_add_u32_e32 v143, 8, v139
	v_and_b32_e32 v142, 15, v143
	v_xor_b32_e32 v142, 8, v142
	v_bfe_u32 v144, v143, 4, 4
	v_mul_lo_u32 v142, v142, s92
	v_mul_lo_u32 v144, v144, s92
	v_mov_b32_e32 v143, v142
	v_mov_b32_e32 v145, v144
	ds_write2st64_b64 v159, v[142:143], v[144:145] offset1:2
	v_and_b32_e32 v78, 0xffff, v28
	v_lshrrev_b32_e32 v79, 16, v28
	v_lshl_add_u32 v78, v78, 7, v152
	v_lshl_add_u32 v79, v79, 7, v153
	s_mov_b32 m0, s98
	s_add_i32 s43, s98, 0x400
	global_load_lds_dwordx4 v78, s[50:51]
	s_mov_b32 m0, s43
	s_nop 0
	global_load_lds_dwordx4 v79, s[50:51]
	s_waitcnt vmcnt(8)
	v_add_u32_e32 v54, s76, v59
	v_add_u32_e32 v55, s76, v60
	v_add_u32_e32 v56, s76, v61
	v_add_u32_e32 v57, s76, v62
	ds_read_b64_tr_b4 v[46:47], v160 offset:768
	ds_read_b64_tr_b4 v[48:49], v160 offset:1792
	ds_read_b64_tr_b4 v[122:123], v54
	ds_read_b64_tr_b4 v[124:125], v55
	ds_read_b64_tr_b4 v[126:127], v56
	ds_read_b64_tr_b4 v[128:129], v57
	s_waitcnt lgkmcnt(7)
	v_dot8c_i32_i4_e32 v38, v130, v52
	v_dot8c_i32_i4_e32 v39, v130, v50
	v_dot8c_i32_i4_e32 v40, v132, v52
	v_dot8c_i32_i4_e32 v41, v132, v50
	v_dot8c_i32_i4_e32 v42, v134, v52
	v_dot8c_i32_i4_e32 v43, v134, v50
	v_dot8c_i32_i4_e32 v44, v136, v52
	v_dot8c_i32_i4_e32 v45, v136, v50
	v_dot8c_i32_i4_e32 v38, v131, v53
	v_dot8c_i32_i4_e32 v39, v131, v51
	v_dot8c_i32_i4_e32 v40, v133, v53
	v_dot8c_i32_i4_e32 v41, v133, v51
	v_dot8c_i32_i4_e32 v42, v135, v53
	v_dot8c_i32_i4_e32 v43, v135, v51
	v_dot8c_i32_i4_e32 v44, v137, v53
	v_dot8c_i32_i4_e32 v45, v137, v51
	v_and_b32_e32 v78, 0xffff, v29
	v_lshrrev_b32_e32 v79, 16, v29
	v_lshl_add_u32 v78, v78, 7, v152
	v_lshl_add_u32 v79, v79, 7, v153
	s_mov_b32 m0, s99
	s_add_i32 s43, s99, 0x400
	global_load_lds_dwordx4 v78, s[50:51]
	s_mov_b32 m0, s43
	s_nop 0
	global_load_lds_dwordx4 v79, s[50:51]
	s_waitcnt vmcnt(8)
	v_add_u32_e32 v54, s77, v59
	v_add_u32_e32 v55, s77, v60
	v_add_u32_e32 v56, s77, v61
	v_add_u32_e32 v57, s77, v62
	ds_read_b64_tr_b4 v[50:51], v160 offset:896
	ds_read_b64_tr_b4 v[52:53], v160 offset:1920
	ds_read_b64_tr_b4 v[130:131], v54
	ds_read_b64_tr_b4 v[132:133], v55
	ds_read_b64_tr_b4 v[134:135], v56
	ds_read_b64_tr_b4 v[136:137], v57
	s_waitcnt lgkmcnt(6)
	v_dot8c_i32_i4_e32 v38, v122, v48
	v_dot8c_i32_i4_e32 v39, v122, v46
	v_dot8c_i32_i4_e32 v40, v124, v48
	v_dot8c_i32_i4_e32 v41, v124, v46
	v_dot8c_i32_i4_e32 v42, v126, v48
	v_dot8c_i32_i4_e32 v43, v126, v46
	v_dot8c_i32_i4_e32 v44, v128, v48
	v_dot8c_i32_i4_e32 v45, v128, v46
	v_dot8c_i32_i4_e32 v38, v123, v49
	v_dot8c_i32_i4_e32 v39, v123, v47
	v_dot8c_i32_i4_e32 v40, v125, v49
	v_dot8c_i32_i4_e32 v41, v125, v47
	v_dot8c_i32_i4_e32 v42, v127, v49
	v_dot8c_i32_i4_e32 v43, v127, v47
	v_dot8c_i32_i4_e32 v44, v129, v49
	v_dot8c_i32_i4_e32 v45, v129, v47
	v_and_b32_e32 v78, 0xffff, v30
	v_lshrrev_b32_e32 v79, 16, v30
	v_lshl_add_u32 v78, v78, 7, v152
	v_lshl_add_u32 v79, v79, 7, v153
	s_mov_b32 m0, s76
	s_add_i32 s43, s76, 0x400
	global_load_lds_dwordx4 v78, s[50:51]
	s_mov_b32 m0, s43
	s_nop 0
	global_load_lds_dwordx4 v79, s[50:51]
	s_waitcnt vmcnt(8)
	v_add_u32_e32 v54, s78, v59
	v_add_u32_e32 v55, s78, v60
	v_add_u32_e32 v56, s78, v61
	v_add_u32_e32 v57, s78, v62
	ds_read_b64_tr_b4 v[46:47], v160
	ds_read_b64_tr_b4 v[48:49], v160 offset:1024
	ds_read_b64_tr_b4 v[122:123], v54
	ds_read_b64_tr_b4 v[124:125], v55
	ds_read_b64_tr_b4 v[126:127], v56
	ds_read_b64_tr_b4 v[128:129], v57
	s_waitcnt lgkmcnt(6)
	v_dot8c_i32_i4_e32 v38, v130, v52
	v_dot8c_i32_i4_e32 v39, v130, v50
	v_dot8c_i32_i4_e32 v40, v132, v52
	v_dot8c_i32_i4_e32 v41, v132, v50
	v_dot8c_i32_i4_e32 v42, v134, v52
	v_dot8c_i32_i4_e32 v43, v134, v50
	v_dot8c_i32_i4_e32 v44, v136, v52
	v_dot8c_i32_i4_e32 v45, v136, v50
	v_dot8c_i32_i4_e32 v38, v131, v53
	v_dot8c_i32_i4_e32 v39, v131, v51
	v_dot8c_i32_i4_e32 v40, v133, v53
	v_dot8c_i32_i4_e32 v41, v133, v51
	v_dot8c_i32_i4_e32 v42, v135, v53
	v_dot8c_i32_i4_e32 v43, v135, v51
	v_dot8c_i32_i4_e32 v44, v137, v53
	v_dot8c_i32_i4_e32 v45, v137, v51
	s_nop 3
	s_waitcnt lgkmcnt(15)
	v_lshlrev_b32_e32 v38, 5, v38
	v_lshlrev_b32_e32 v39, 1, v39
	v_add3_u32 v38, v39, v229, v38
	v_cvt_f32_i32_e32 v38, v38
	v_mul_f32_e32 v38, v228, v38
	v_lshlrev_b32_e32 v40, 5, v40
	v_lshlrev_b32_e32 v41, 1, v41
	v_add3_u32 v40, v41, v229, v40
	v_cvt_f32_i32_e32 v40, v40
	v_mul_f32_e32 v40, v228, v40
	v_lshlrev_b32_e32 v42, 5, v42
	v_lshlrev_b32_e32 v43, 1, v43
	v_add3_u32 v42, v43, v229, v42
	v_cvt_f32_i32_e32 v42, v42
	v_mul_f32_e32 v42, v228, v42
	v_lshlrev_b32_e32 v44, 5, v44
	v_lshlrev_b32_e32 v45, 1, v45
	v_add3_u32 v44, v45, v229, v44
	v_cvt_f32_i32_e32 v44, v44
	v_mul_f32_e32 v44, v228, v44
	v_cvt_pk_bf16_f32 v180, v38, v40
	v_cvt_pk_bf16_f32 v181, v42, v44
	v_add_u32_e32 v147, 8, v140
	v_and_b32_e32 v146, 15, v147
	v_xor_b32_e32 v146, 8, v146
	v_bfe_u32 v148, v147, 4, 4
	v_mul_lo_u32 v146, v146, s92
	v_mul_lo_u32 v148, v148, s92
	v_mov_b32_e32 v147, v146
	v_mov_b32_e32 v149, v148
	ds_write2st64_b64 v77, v[146:147], v[148:149] offset1:2
	v_mov_b32_e32 v138, v74
	ds_read_u8 v139, v138
	v_mov_b32_e32 v141, v73
	ds_read_u8 v140, v141
	s_add_i32 s43, s67, 96
	v_mov_b32_e32 v138, s43
	ds_read2st64_b32 v[228:229], v138 offset1:1
	ds_read_b128 v[18:21], v227
	ds_read_b128 v[22:25], v227 offset:16
	v_add_u32_e32 v150, 0x400000, v63
	v_add_u32_e32 v151, 0x400000, v64
	v_mov_b32_e32 v38, 0
	v_mov_b32_e32 v39, 0
	v_mov_b32_e32 v40, 0
	v_mov_b32_e32 v41, 0
	v_mov_b32_e32 v42, 0
	v_mov_b32_e32 v43, 0
	v_mov_b32_e32 v44, 0
	v_mov_b32_e32 v45, 0
	v_and_b32_e32 v78, 0xffff, v31
	v_lshrrev_b32_e32 v79, 16, v31
	v_lshl_add_u32 v78, v78, 7, v152
	v_lshl_add_u32 v79, v79, 7, v153
	s_mov_b32 m0, s77
	s_add_i32 s43, s77, 0x400
	global_load_lds_dwordx4 v78, s[50:51]
	s_mov_b32 m0, s43
	s_nop 0
	global_load_lds_dwordx4 v79, s[50:51]
	s_waitcnt vmcnt(8)
; #define TR4(p_) __builtin_amdgcn_ds_read_tr4_b64_v2i32((LAS v2i*)(p_))
; #define VDMA(st_, k_) do { _Pragma("unroll") for (int i_ = 0; i_ < 4; ++i_) { \
;         const unsigned off_ = (unsigned)((st_) >> 2) * (16384u * 128u) + (PE_ID(E, 4 * ((st_) & 3) + i_) << 7) + ((i_ & 1) ? cx1 : cx0); \
;         __builtin_amdgcn_global_load_lds((const unsigned*)(V4 + off_), (LAS unsigned*)(ldsb + BUF[k_] + 1024 * i_), 16, 0, 0); } } while (0)
; __device__ __forceinline__ void peer_v_tokens(int j, const LAS unsigned short* EL, const LAS unsigned char* AL  , const LAS float* ASC  , const LAS int* SAL  , ...
;     ...
;         for (int st = 0; st < 16; ++st) {
;             const int p = st >> 2, q = st & 3;
;             if (st < 14) VDMA(st + 2, (st + 2) % 3);
;             if (st < 14) asm volatile("s_waitcnt vmcnt(8)" ::: "memory");
;             else if (st == 14) asm volatile("s_waitcnt vmcnt(4)" ::: "memory");
;             else asm volatile("s_waitcnt vmcnt(0)" ::: "memory");
;             if (q == 0) {
; #pragma unroll
;                 for (int r = 0; r < 4; ++r) { accH[r] = 0; accL[r] = 0; } }
; #pragma unroll
;             for (int tp = 0; tp < 2; ++tp) {
;                 const v2i ao = TR4(ATL + (2 * q + tp) * 128 + 8 * s16), ah = TR4(ATL + 1024 + (2 * q + tp) * 128 + 8 * s16);
; #pragma unroll
;                 for (int r = 0; r < 4; ++r) {
;                     const v2i d = TR4(ldsb + BUF[st % 3] + 2048 * tp + roff[r]);
;                     accH[r] = __builtin_amdgcn_sdot8(d.x, ah.x, accH[r], false); accH[r] = __builtin_amdgcn_sdot8(d.y, ah.y, accH[r], false);
;                     accL[r] = __builtin_amdgcn_sdot8(d.x, ao.x, accL[r], false); accL[r] = __builtin_amdgcn_sdot8(d.y, ao.y, accL[r], false);
;                 }
;             }
	v_add_u32_e32 v54, s79, v59
	v_add_u32_e32 v55, s79, v60
	v_add_u32_e32 v56, s79, v61
	v_add_u32_e32 v57, s79, v62
	ds_read_b64_tr_b4 v[50:51], v160 offset:128
	ds_read_b64_tr_b4 v[52:53], v160 offset:1152
	ds_read_b64_tr_b4 v[130:131], v54
	ds_read_b64_tr_b4 v[132:133], v55
	ds_read_b64_tr_b4 v[134:135], v56
	ds_read_b64_tr_b4 v[136:137], v57
	s_waitcnt lgkmcnt(12)
	v_dot8c_i32_i4_e32 v38, v122, v48
	v_dot8c_i32_i4_e32 v39, v122, v46
	v_dot8c_i32_i4_e32 v40, v124, v48
	v_dot8c_i32_i4_e32 v41, v124, v46
	v_dot8c_i32_i4_e32 v42, v126, v48
	v_dot8c_i32_i4_e32 v43, v126, v46
	v_dot8c_i32_i4_e32 v44, v128, v48
	v_dot8c_i32_i4_e32 v45, v128, v46
	v_dot8c_i32_i4_e32 v38, v123, v49
	v_dot8c_i32_i4_e32 v39, v123, v47
	v_dot8c_i32_i4_e32 v40, v125, v49
	v_dot8c_i32_i4_e32 v41, v125, v47
	v_dot8c_i32_i4_e32 v42, v127, v49
	v_dot8c_i32_i4_e32 v43, v127, v47
	v_dot8c_i32_i4_e32 v44, v129, v49
	v_dot8c_i32_i4_e32 v45, v129, v47
	v_and_b32_e32 v78, 0xffff, v32
	v_lshrrev_b32_e32 v79, 16, v32
	v_lshl_add_u32 v78, v78, 7, v152
	v_lshl_add_u32 v79, v79, 7, v153
	s_mov_b32 m0, s78
	s_add_i32 s43, s78, 0x400
	global_load_lds_dwordx4 v78, s[50:51]
	s_mov_b32 m0, s43
	s_nop 0
	global_load_lds_dwordx4 v79, s[50:51]
	s_waitcnt vmcnt(8)
	v_add_u32_e32 v54, s98, v59
	v_add_u32_e32 v55, s98, v60
	v_add_u32_e32 v56, s98, v61
	v_add_u32_e32 v57, s98, v62
	ds_read_b64_tr_b4 v[46:47], v160 offset:256
	ds_read_b64_tr_b4 v[48:49], v160 offset:1280
	ds_read_b64_tr_b4 v[122:123], v54
	ds_read_b64_tr_b4 v[124:125], v55
	ds_read_b64_tr_b4 v[126:127], v56
	ds_read_b64_tr_b4 v[128:129], v57
	s_waitcnt lgkmcnt(6)
	v_dot8c_i32_i4_e32 v38, v130, v52
	v_dot8c_i32_i4_e32 v39, v130, v50
	v_dot8c_i32_i4_e32 v40, v132, v52
	v_dot8c_i32_i4_e32 v41, v132, v50
	v_dot8c_i32_i4_e32 v42, v134, v52
	v_dot8c_i32_i4_e32 v43, v134, v50
	v_dot8c_i32_i4_e32 v44, v136, v52
	v_dot8c_i32_i4_e32 v45, v136, v50
	v_dot8c_i32_i4_e32 v38, v131, v53
	v_dot8c_i32_i4_e32 v39, v131, v51
	v_dot8c_i32_i4_e32 v40, v133, v53
	v_dot8c_i32_i4_e32 v41, v133, v51
	v_dot8c_i32_i4_e32 v42, v135, v53
	v_dot8c_i32_i4_e32 v43, v135, v51
	v_dot8c_i32_i4_e32 v44, v137, v53
	v_dot8c_i32_i4_e32 v45, v137, v51
	v_and_b32_e32 v78, 0xffff, v33
	v_lshrrev_b32_e32 v79, 16, v33
	v_lshl_add_u32 v78, v78, 7, v152
	v_lshl_add_u32 v79, v79, 7, v153
	s_mov_b32 m0, s79
	s_add_i32 s43, s79, 0x400
	global_load_lds_dwordx4 v78, s[50:51]
	s_mov_b32 m0, s43
	s_nop 0
	global_load_lds_dwordx4 v79, s[50:51]
	s_waitcnt vmcnt(8)
	v_add_u32_e32 v54, s99, v59
	v_add_u32_e32 v55, s99, v60
	v_add_u32_e32 v56, s99, v61
	v_add_u32_e32 v57, s99, v62
	ds_read_b64_tr_b4 v[50:51], v160 offset:384
	ds_read_b64_tr_b4 v[52:53], v160 offset:1408
	ds_read_b64_tr_b4 v[130:131], v54
	ds_read_b64_tr_b4 v[132:133], v55
	ds_read_b64_tr_b4 v[134:135], v56
	ds_read_b64_tr_b4 v[136:137], v57
	s_waitcnt lgkmcnt(6)
	v_dot8c_i32_i4_e32 v38, v122, v48
	v_dot8c_i32_i4_e32 v39, v122, v46
	v_dot8c_i32_i4_e32 v40, v124, v48
	v_dot8c_i32_i4_e32 v41, v124, v46
	v_dot8c_i32_i4_e32 v42, v126, v48
	v_dot8c_i32_i4_e32 v43, v126, v46
	v_dot8c_i32_i4_e32 v44, v128, v48
	v_dot8c_i32_i4_e32 v45, v128, v46
	v_dot8c_i32_i4_e32 v38, v123, v49
	v_dot8c_i32_i4_e32 v39, v123, v47
	v_dot8c_i32_i4_e32 v40, v125, v49
	v_dot8c_i32_i4_e32 v41, v125, v47
	v_dot8c_i32_i4_e32 v42, v127, v49
	v_dot8c_i32_i4_e32 v43, v127, v47
	v_dot8c_i32_i4_e32 v44, v129, v49
	v_dot8c_i32_i4_e32 v45, v129, v47
	s_waitcnt lgkmcnt(15)
	v_and_b32_e32 v78, 0xffff, v18
	v_lshrrev_b32_e32 v79, 16, v18
	v_lshl_add_u32 v78, v78, 7, v150
	v_lshl_add_u32 v79, v79, 7, v151
	s_mov_b32 m0, s98
	s_add_i32 s43, s98, 0x400
	global_load_lds_dwordx4 v78, s[50:51]
	s_mov_b32 m0, s43
	s_nop 0
	global_load_lds_dwordx4 v79, s[50:51]
	s_waitcnt vmcnt(8)
	v_add_u32_e32 v54, s76, v59
	v_add_u32_e32 v55, s76, v60
	v_add_u32_e32 v56, s76, v61
	v_add_u32_e32 v57, s76, v62
	ds_read_b64_tr_b4 v[46:47], v160 offset:512
	ds_read_b64_tr_b4 v[48:49], v160 offset:1536
	ds_read_b64_tr_b4 v[122:123], v54
	ds_read_b64_tr_b4 v[124:125], v55
	ds_read_b64_tr_b4 v[126:127], v56
	ds_read_b64_tr_b4 v[128:129], v57
	s_waitcnt lgkmcnt(6)
	v_dot8c_i32_i4_e32 v38, v130, v52
	v_dot8c_i32_i4_e32 v39, v130, v50
	v_dot8c_i32_i4_e32 v40, v132, v52
	v_dot8c_i32_i4_e32 v41, v132, v50
	v_dot8c_i32_i4_e32 v42, v134, v52
	v_dot8c_i32_i4_e32 v43, v134, v50
	v_dot8c_i32_i4_e32 v44, v136, v52
	v_dot8c_i32_i4_e32 v45, v136, v50
	v_dot8c_i32_i4_e32 v38, v131, v53
	v_dot8c_i32_i4_e32 v39, v131, v51
	v_dot8c_i32_i4_e32 v40, v133, v53
	v_dot8c_i32_i4_e32 v41, v133, v51
	v_dot8c_i32_i4_e32 v42, v135, v53
	v_dot8c_i32_i4_e32 v43, v135, v51
	v_dot8c_i32_i4_e32 v44, v137, v53
	v_dot8c_i32_i4_e32 v45, v137, v51
	v_and_b32_e32 v78, 0xffff, v19
	v_lshrrev_b32_e32 v79, 16, v19
	v_lshl_add_u32 v78, v78, 7, v150
	v_lshl_add_u32 v79, v79, 7, v151
	s_mov_b32 m0, s99
	s_add_i32 s43, s99, 0x400
	global_load_lds_dwordx4 v78, s[50:51]
	s_mov_b32 m0, s43
	s_nop 0
	global_load_lds_dwordx4 v79, s[50:51]
	s_waitcnt vmcnt(8)
	v_add_u32_e32 v54, s77, v59
	v_add_u32_e32 v55, s77, v60
	v_add_u32_e32 v56, s77, v61
	v_add_u32_e32 v57, s77, v62
	ds_read_b64_tr_b4 v[50:51], v160 offset:640
	ds_read_b64_tr_b4 v[52:53], v160 offset:1664
	ds_read_b64_tr_b4 v[130:131], v54
	ds_read_b64_tr_b4 v[132:133], v55
	ds_read_b64_tr_b4 v[134:135], v56
	ds_read_b64_tr_b4 v[136:137], v57
	s_waitcnt lgkmcnt(6)
	v_dot8c_i32_i4_e32 v38, v122, v48
	v_dot8c_i32_i4_e32 v39, v122, v46
	v_dot8c_i32_i4_e32 v40, v124, v48
	v_dot8c_i32_i4_e32 v41, v124, v46
	v_dot8c_i32_i4_e32 v42, v126, v48
	v_dot8c_i32_i4_e32 v43, v126, v46
	v_dot8c_i32_i4_e32 v44, v128, v48
	v_dot8c_i32_i4_e32 v45, v128, v46
	v_dot8c_i32_i4_e32 v38, v123, v49
	v_dot8c_i32_i4_e32 v39, v123, v47
	v_dot8c_i32_i4_e32 v40, v125, v49
	v_dot8c_i32_i4_e32 v41, v125, v47
	v_dot8c_i32_i4_e32 v42, v127, v49
	v_dot8c_i32_i4_e32 v43, v127, v47
	v_dot8c_i32_i4_e32 v44, v129, v49
	v_dot8c_i32_i4_e32 v45, v129, v47
	s_waitcnt lgkmcnt(15)
; #define LAS __attribute__((address_space(3)))
; __device__ __forceinline__ void peer_v_tokens(int j, const LAS unsigned short* EL, const LAS unsigned char* AL  , const LAS float* ASC  , const LAS int* SAL  , ...
;     ...
;         { const LAS v4u* ep = (const LAS v4u*)(EL + tl * 128 + 16 * g); const v4u e0 = ep[0], e1 = ep[1];
;           E[0] = e0.x; E[1] = e0.y; E[2] = e0.z; E[3] = e0.w; E[4] = e1.x; E[5] = e1.y; E[6] = e1.z; E[7] = e1.w; }
;         uint2 hv[4]; float4 gv[4];
;         { unsigned ho = (unsigned)t * (D / 4) + (unsigned)lane; asm volatile("" : "+v"(ho)); const uint2* hp = (const uint2*)HB + ho; const float4* gp = (const float4*)fng + lane;
; #pragma unroll
;           for (int jq = 0; jq < 4; ++jq) { hv[jq] = hp[64 * jq]; gv[jq] = gp[64 * jq]; } }
;         VDMA(0, 0); VDMA(1, 1);
; #pragma unroll
;         for (int m = 0; m < 2; ++m) {
;             const int idx = lane + 64 * m, tau = idx >> 4, sr = idx & 15, k = 16 * (sr & 7) + 2 * tau + (sr >> 3);
;     ...
;         for (int st = 0; st < 16; ++st) {
;             const int p = st >> 2, q = st & 3;
;             if (st < 14) VDMA(st + 2, (st + 2) % 3);
;             if (st < 14) asm volatile("s_waitcnt vmcnt(8)" ::: "memory");
;             else if (st == 14) asm volatile("s_waitcnt vmcnt(4)" ::: "memory");
;             else asm volatile("s_waitcnt vmcnt(0)" ::: "memory");
;             if (q == 0) {
; #pragma unroll
;                 for (int r = 0; r < 4; ++r) { accH[r] = 0; accL[r] = 0; } }
; #pragma unroll
;             for (int tp = 0; tp < 2; ++tp) {
;                 const v2i ao = TR4(ATL + (2 * q + tp) * 128 + 8 * s16), ah = TR4(ATL + 1024 + (2 * q + tp) * 128 + 8 * s16);
; #pragma unroll
;                 for (int r = 0; r < 4; ++r) {
;                     const v2i d = TR4(ldsb + BUF[st % 3] + 2048 * tp + roff[r]);
;                     accH[r] = __builtin_amdgcn_sdot8(d.x, ah.x, accH[r], false); accH[r] = __builtin_amdgcn_sdot8(d.y, ah.y, accH[r], false);
;                     accL[r] = __builtin_amdgcn_sdot8(d.x, ao.x, accL[r], false); accL[r] = __builtin_amdgcn_sdot8(d.y, ao.y, accL[r], false);
;                 }
;             }
;             asm volatile("s_waitcnt lgkmcnt(0)" ::: "memory");
;             if (q == 3) {
; #pragma unroll
;                 for (int r = 0; r < 4; ++r) STASH[256 * p + 16 * (grp + 4 * r) + pc] = f2bf(asc * (float)(2 * ((accH[r] << 4) + accL[r]) + sa));
	v_add_u32_e32 v143, 8, v139
	v_and_b32_e32 v142, 15, v143
	v_xor_b32_e32 v142, 8, v142
	v_bfe_u32 v144, v143, 4, 4
	v_mul_lo_u32 v142, v142, s92
	v_mul_lo_u32 v144, v144, s92
	v_mov_b32_e32 v143, v142
	v_mov_b32_e32 v145, v144
	ds_write2st64_b64 v159, v[142:143], v[144:145] offset1:2
	v_and_b32_e32 v78, 0xffff, v20
	v_lshrrev_b32_e32 v79, 16, v20
	v_lshl_add_u32 v78, v78, 7, v150
	v_lshl_add_u32 v79, v79, 7, v151
	s_mov_b32 m0, s76
	s_add_i32 s43, s76, 0x400
	global_load_lds_dwordx4 v78, s[50:51]
	s_mov_b32 m0, s43
	s_nop 0
	global_load_lds_dwordx4 v79, s[50:51]
	s_waitcnt vmcnt(8)
	v_add_u32_e32 v54, s78, v59
	v_add_u32_e32 v55, s78, v60
	v_add_u32_e32 v56, s78, v61
	v_add_u32_e32 v57, s78, v62
	ds_read_b64_tr_b4 v[46:47], v160 offset:768
	ds_read_b64_tr_b4 v[48:49], v160 offset:1792
	ds_read_b64_tr_b4 v[122:123], v54
	ds_read_b64_tr_b4 v[124:125], v55
	ds_read_b64_tr_b4 v[126:127], v56
	ds_read_b64_tr_b4 v[128:129], v57
	s_waitcnt lgkmcnt(7)
	v_dot8c_i32_i4_e32 v38, v130, v52
	v_dot8c_i32_i4_e32 v39, v130, v50
	v_dot8c_i32_i4_e32 v40, v132, v52
	v_dot8c_i32_i4_e32 v41, v132, v50
	v_dot8c_i32_i4_e32 v42, v134, v52
	v_dot8c_i32_i4_e32 v43, v134, v50
	v_dot8c_i32_i4_e32 v44, v136, v52
	v_dot8c_i32_i4_e32 v45, v136, v50
	v_dot8c_i32_i4_e32 v38, v131, v53
	v_dot8c_i32_i4_e32 v39, v131, v51
	v_dot8c_i32_i4_e32 v40, v133, v53
	v_dot8c_i32_i4_e32 v41, v133, v51
	v_dot8c_i32_i4_e32 v42, v135, v53
	v_dot8c_i32_i4_e32 v43, v135, v51
	v_dot8c_i32_i4_e32 v44, v137, v53
	v_dot8c_i32_i4_e32 v45, v137, v51
	v_and_b32_e32 v78, 0xffff, v21
	v_lshrrev_b32_e32 v79, 16, v21
	v_lshl_add_u32 v78, v78, 7, v150
	v_lshl_add_u32 v79, v79, 7, v151
	s_mov_b32 m0, s77
	s_add_i32 s43, s77, 0x400
	global_load_lds_dwordx4 v78, s[50:51]
	s_mov_b32 m0, s43
	s_nop 0
	global_load_lds_dwordx4 v79, s[50:51]
	s_waitcnt vmcnt(8)
	v_add_u32_e32 v54, s79, v59
	v_add_u32_e32 v55, s79, v60
	v_add_u32_e32 v56, s79, v61
	v_add_u32_e32 v57, s79, v62
	ds_read_b64_tr_b4 v[50:51], v160 offset:896
	ds_read_b64_tr_b4 v[52:53], v160 offset:1920
	ds_read_b64_tr_b4 v[130:131], v54
	ds_read_b64_tr_b4 v[132:133], v55
	ds_read_b64_tr_b4 v[134:135], v56
	ds_read_b64_tr_b4 v[136:137], v57
	s_waitcnt lgkmcnt(6)
	v_dot8c_i32_i4_e32 v38, v122, v48
	v_dot8c_i32_i4_e32 v39, v122, v46
	v_dot8c_i32_i4_e32 v40, v124, v48
	v_dot8c_i32_i4_e32 v41, v124, v46
	v_dot8c_i32_i4_e32 v42, v126, v48
	v_dot8c_i32_i4_e32 v43, v126, v46
	v_dot8c_i32_i4_e32 v44, v128, v48
	v_dot8c_i32_i4_e32 v45, v128, v46
	v_dot8c_i32_i4_e32 v38, v123, v49
	v_dot8c_i32_i4_e32 v39, v123, v47
	v_dot8c_i32_i4_e32 v40, v125, v49
	v_dot8c_i32_i4_e32 v41, v125, v47
	v_dot8c_i32_i4_e32 v42, v127, v49
	v_dot8c_i32_i4_e32 v43, v127, v47
	v_dot8c_i32_i4_e32 v44, v129, v49
	v_dot8c_i32_i4_e32 v45, v129, v47
	v_and_b32_e32 v78, 0xffff, v22
	v_lshrrev_b32_e32 v79, 16, v22
	v_lshl_add_u32 v78, v78, 7, v150
	v_lshl_add_u32 v79, v79, 7, v151
	s_mov_b32 m0, s78
	s_add_i32 s43, s78, 0x400
	global_load_lds_dwordx4 v78, s[50:51]
	s_mov_b32 m0, s43
	s_nop 0
	global_load_lds_dwordx4 v79, s[50:51]
	s_waitcnt vmcnt(8)
	v_add_u32_e32 v54, s98, v59
	v_add_u32_e32 v55, s98, v60
	v_add_u32_e32 v56, s98, v61
	v_add_u32_e32 v57, s98, v62
	ds_read_b64_tr_b4 v[46:47], v160
	ds_read_b64_tr_b4 v[48:49], v160 offset:1024
	ds_read_b64_tr_b4 v[122:123], v54
	ds_read_b64_tr_b4 v[124:125], v55
	ds_read_b64_tr_b4 v[126:127], v56
	ds_read_b64_tr_b4 v[128:129], v57
	s_waitcnt lgkmcnt(6)
	v_dot8c_i32_i4_e32 v38, v130, v52
	v_dot8c_i32_i4_e32 v39, v130, v50
	v_dot8c_i32_i4_e32 v40, v132, v52
	v_dot8c_i32_i4_e32 v41, v132, v50
	v_dot8c_i32_i4_e32 v42, v134, v52
	v_dot8c_i32_i4_e32 v43, v134, v50
	v_dot8c_i32_i4_e32 v44, v136, v52
	v_dot8c_i32_i4_e32 v45, v136, v50
	v_dot8c_i32_i4_e32 v38, v131, v53
	v_dot8c_i32_i4_e32 v39, v131, v51
	v_dot8c_i32_i4_e32 v40, v133, v53
	v_dot8c_i32_i4_e32 v41, v133, v51
	v_dot8c_i32_i4_e32 v42, v135, v53
	v_dot8c_i32_i4_e32 v43, v135, v51
	v_dot8c_i32_i4_e32 v44, v137, v53
	v_dot8c_i32_i4_e32 v45, v137, v51
	s_nop 3
	s_waitcnt lgkmcnt(15)
	v_lshlrev_b32_e32 v38, 5, v38
	v_lshlrev_b32_e32 v39, 1, v39
	v_add3_u32 v38, v39, v229, v38
	v_cvt_f32_i32_e32 v38, v38
	v_mul_f32_e32 v38, v228, v38
	v_lshlrev_b32_e32 v40, 5, v40
	v_lshlrev_b32_e32 v41, 1, v41
	v_add3_u32 v40, v41, v229, v40
	v_cvt_f32_i32_e32 v40, v40
	v_mul_f32_e32 v40, v228, v40
	v_lshlrev_b32_e32 v42, 5, v42
	v_lshlrev_b32_e32 v43, 1, v43
	v_add3_u32 v42, v43, v229, v42
	v_cvt_f32_i32_e32 v42, v42
	v_mul_f32_e32 v42, v228, v42
	v_lshlrev_b32_e32 v44, 5, v44
	v_lshlrev_b32_e32 v45, 1, v45
	v_add3_u32 v44, v45, v229, v44
	v_cvt_f32_i32_e32 v44, v44
	v_mul_f32_e32 v44, v228, v44
	v_cvt_pk_bf16_f32 v188, v38, v40
	v_cvt_pk_bf16_f32 v189, v42, v44
	v_add_u32_e32 v147, 8, v140
	v_and_b32_e32 v146, 15, v147
	v_xor_b32_e32 v146, 8, v146
	v_bfe_u32 v148, v147, 4, 4
	v_mul_lo_u32 v146, v146, s92
	v_mul_lo_u32 v148, v148, s92
	v_mov_b32_e32 v147, v146
	v_mov_b32_e32 v149, v148
	ds_write2st64_b64 v77, v[146:147], v[148:149] offset1:2
	v_add_u32_e32 v138, 0x400, v74
	ds_read_u8 v139, v138
	v_add_u32_e32 v141, 0x400, v73
	ds_read_u8 v140, v141
	s_mov_b32 s43, s67
	v_mov_b32_e32 v138, s43
	ds_read2st64_b32 v[228:229], v138 offset1:1
	ds_read_b128 v[26:29], v227 offset:2048
	ds_read_b128 v[30:33], v227 offset:2064
	v_mov_b32_e32 v38, 0
	v_mov_b32_e32 v39, 0
	v_mov_b32_e32 v40, 0
	v_mov_b32_e32 v41, 0
	v_mov_b32_e32 v42, 0
	v_mov_b32_e32 v43, 0
	v_mov_b32_e32 v44, 0
	v_mov_b32_e32 v45, 0
	v_and_b32_e32 v78, 0xffff, v23
	v_lshrrev_b32_e32 v79, 16, v23
	v_lshl_add_u32 v78, v78, 7, v150
	v_lshl_add_u32 v79, v79, 7, v151
	s_mov_b32 m0, s79
	s_add_i32 s43, s79, 0x400
	global_load_lds_dwordx4 v78, s[50:51]
	s_mov_b32 m0, s43
	s_nop 0
	global_load_lds_dwordx4 v79, s[50:51]
	s_waitcnt vmcnt(8)
; __device__ __forceinline__ bf16 f2bf(float f) { return (bf16)f2bfu(f); }
; #define TR4(p_) __builtin_amdgcn_ds_read_tr4_b64_v2i32((LAS v2i*)(p_))
; #define VDMA(st_, k_) do { _Pragma("unroll") for (int i_ = 0; i_ < 4; ++i_) { \
;         const unsigned off_ = (unsigned)((st_) >> 2) * (16384u * 128u) + (PE_ID(E, 4 * ((st_) & 3) + i_) << 7) + ((i_ & 1) ? cx1 : cx0); \
;         __builtin_amdgcn_global_load_lds((const unsigned*)(V4 + off_), (LAS unsigned*)(ldsb + BUF[k_] + 1024 * i_), 16, 0, 0); } } while (0)
; __device__ __forceinline__ void peer_v_tokens(int j, const LAS unsigned short* EL, const LAS unsigned char* AL  , const LAS float* ASC  , const LAS int* SAL  , ...
;     ...
;         for (int st = 0; st < 16; ++st) {
;             const int p = st >> 2, q = st & 3;
;             if (st < 14) VDMA(st + 2, (st + 2) % 3);
;             if (st < 14) asm volatile("s_waitcnt vmcnt(8)" ::: "memory");
;             else if (st == 14) asm volatile("s_waitcnt vmcnt(4)" ::: "memory");
;             else asm volatile("s_waitcnt vmcnt(0)" ::: "memory");
;             if (q == 0) {
; #pragma unroll
;                 for (int r = 0; r < 4; ++r) { accH[r] = 0; accL[r] = 0; } }
; #pragma unroll
;             for (int tp = 0; tp < 2; ++tp) {
;                 const v2i ao = TR4(ATL + (2 * q + tp) * 128 + 8 * s16), ah = TR4(ATL + 1024 + (2 * q + tp) * 128 + 8 * s16);
; #pragma unroll
;                 for (int r = 0; r < 4; ++r) {
;                     const v2i d = TR4(ldsb + BUF[st % 3] + 2048 * tp + roff[r]);
;                     accH[r] = __builtin_amdgcn_sdot8(d.x, ah.x, accH[r], false); accH[r] = __builtin_amdgcn_sdot8(d.y, ah.y, accH[r], false);
;                     accL[r] = __builtin_amdgcn_sdot8(d.x, ao.x, accL[r], false); accL[r] = __builtin_amdgcn_sdot8(d.y, ao.y, accL[r], false);
;                 }
;             }
;             asm volatile("s_waitcnt lgkmcnt(0)" ::: "memory");
;             if (q == 3) {
; #pragma unroll
;                 for (int r = 0; r < 4; ++r) STASH[256 * p + 16 * (grp + 4 * r) + pc] = f2bf(asc * (float)(2 * ((accH[r] << 4) + accL[r]) + sa));
;             }
;         }
	v_add_u32_e32 v54, s99, v59
	v_add_u32_e32 v55, s99, v60
	v_add_u32_e32 v56, s99, v61
	v_add_u32_e32 v57, s99, v62
	ds_read_b64_tr_b4 v[50:51], v160 offset:128
	ds_read_b64_tr_b4 v[52:53], v160 offset:1152
	ds_read_b64_tr_b4 v[130:131], v54
	ds_read_b64_tr_b4 v[132:133], v55
	ds_read_b64_tr_b4 v[134:135], v56
	ds_read_b64_tr_b4 v[136:137], v57
	s_waitcnt lgkmcnt(12)
	v_dot8c_i32_i4_e32 v38, v122, v48
	v_dot8c_i32_i4_e32 v39, v122, v46
	v_dot8c_i32_i4_e32 v40, v124, v48
	v_dot8c_i32_i4_e32 v41, v124, v46
	v_dot8c_i32_i4_e32 v42, v126, v48
	v_dot8c_i32_i4_e32 v43, v126, v46
	v_dot8c_i32_i4_e32 v44, v128, v48
	v_dot8c_i32_i4_e32 v45, v128, v46
	v_dot8c_i32_i4_e32 v38, v123, v49
	v_dot8c_i32_i4_e32 v39, v123, v47
	v_dot8c_i32_i4_e32 v40, v125, v49
	v_dot8c_i32_i4_e32 v41, v125, v47
	v_dot8c_i32_i4_e32 v42, v127, v49
	v_dot8c_i32_i4_e32 v43, v127, v47
	v_dot8c_i32_i4_e32 v44, v129, v49
	v_dot8c_i32_i4_e32 v45, v129, v47
	v_and_b32_e32 v78, 0xffff, v24
	v_lshrrev_b32_e32 v79, 16, v24
	v_lshl_add_u32 v78, v78, 7, v150
	v_lshl_add_u32 v79, v79, 7, v151
	s_mov_b32 m0, s98
	s_add_i32 s43, s98, 0x400
	global_load_lds_dwordx4 v78, s[50:51]
	s_mov_b32 m0, s43
	s_nop 0
	global_load_lds_dwordx4 v79, s[50:51]
	s_waitcnt vmcnt(8)
	v_add_u32_e32 v54, s76, v59
	v_add_u32_e32 v55, s76, v60
	v_add_u32_e32 v56, s76, v61
	v_add_u32_e32 v57, s76, v62
	ds_read_b64_tr_b4 v[46:47], v160 offset:256
	ds_read_b64_tr_b4 v[48:49], v160 offset:1280
	ds_read_b64_tr_b4 v[122:123], v54
	ds_read_b64_tr_b4 v[124:125], v55
	ds_read_b64_tr_b4 v[126:127], v56
	ds_read_b64_tr_b4 v[128:129], v57
	s_waitcnt lgkmcnt(6)
	v_dot8c_i32_i4_e32 v38, v130, v52
	v_dot8c_i32_i4_e32 v39, v130, v50
	v_dot8c_i32_i4_e32 v40, v132, v52
	v_dot8c_i32_i4_e32 v41, v132, v50
	v_dot8c_i32_i4_e32 v42, v134, v52
	v_dot8c_i32_i4_e32 v43, v134, v50
	v_dot8c_i32_i4_e32 v44, v136, v52
	v_dot8c_i32_i4_e32 v45, v136, v50
	v_dot8c_i32_i4_e32 v38, v131, v53
	v_dot8c_i32_i4_e32 v39, v131, v51
	v_dot8c_i32_i4_e32 v40, v133, v53
	v_dot8c_i32_i4_e32 v41, v133, v51
	v_dot8c_i32_i4_e32 v42, v135, v53
	v_dot8c_i32_i4_e32 v43, v135, v51
	v_dot8c_i32_i4_e32 v44, v137, v53
	v_dot8c_i32_i4_e32 v45, v137, v51
	v_and_b32_e32 v78, 0xffff, v25
	v_lshrrev_b32_e32 v79, 16, v25
	v_lshl_add_u32 v78, v78, 7, v150
	v_lshl_add_u32 v79, v79, 7, v151
	s_mov_b32 m0, s99
	s_add_i32 s43, s99, 0x400
	global_load_lds_dwordx4 v78, s[50:51]
	s_mov_b32 m0, s43
	s_nop 0
	global_load_lds_dwordx4 v79, s[50:51]
	s_waitcnt vmcnt(8)
	v_add_u32_e32 v54, s77, v59
	v_add_u32_e32 v55, s77, v60
	v_add_u32_e32 v56, s77, v61
	v_add_u32_e32 v57, s77, v62
	ds_read_b64_tr_b4 v[50:51], v160 offset:384
	ds_read_b64_tr_b4 v[52:53], v160 offset:1408
	ds_read_b64_tr_b4 v[130:131], v54
	ds_read_b64_tr_b4 v[132:133], v55
	ds_read_b64_tr_b4 v[134:135], v56
	ds_read_b64_tr_b4 v[136:137], v57
	s_waitcnt lgkmcnt(6)
	v_dot8c_i32_i4_e32 v38, v122, v48
	v_dot8c_i32_i4_e32 v39, v122, v46
	v_dot8c_i32_i4_e32 v40, v124, v48
	v_dot8c_i32_i4_e32 v41, v124, v46
	v_dot8c_i32_i4_e32 v42, v126, v48
	v_dot8c_i32_i4_e32 v43, v126, v46
	v_dot8c_i32_i4_e32 v44, v128, v48
	v_dot8c_i32_i4_e32 v45, v128, v46
	v_dot8c_i32_i4_e32 v38, v123, v49
	v_dot8c_i32_i4_e32 v39, v123, v47
	v_dot8c_i32_i4_e32 v40, v125, v49
	v_dot8c_i32_i4_e32 v41, v125, v47
	v_dot8c_i32_i4_e32 v42, v127, v49
	v_dot8c_i32_i4_e32 v43, v127, v47
	v_dot8c_i32_i4_e32 v44, v129, v49
	v_dot8c_i32_i4_e32 v45, v129, v47
	s_waitcnt lgkmcnt(15)
	v_and_b32_e32 v78, 0xffff, v26
	v_lshrrev_b32_e32 v79, 16, v26
	v_lshl_add_u32 v78, v78, 7, v150
	v_lshl_add_u32 v79, v79, 7, v151
	s_mov_b32 m0, s76
	s_add_i32 s43, s76, 0x400
	global_load_lds_dwordx4 v78, s[50:51]
	s_mov_b32 m0, s43
	s_nop 0
	global_load_lds_dwordx4 v79, s[50:51]
	s_waitcnt vmcnt(8)
	v_add_u32_e32 v54, s78, v59
	v_add_u32_e32 v55, s78, v60
	v_add_u32_e32 v56, s78, v61
	v_add_u32_e32 v57, s78, v62
	ds_read_b64_tr_b4 v[46:47], v160 offset:512
	ds_read_b64_tr_b4 v[48:49], v160 offset:1536
	ds_read_b64_tr_b4 v[122:123], v54
	ds_read_b64_tr_b4 v[124:125], v55
	ds_read_b64_tr_b4 v[126:127], v56
	ds_read_b64_tr_b4 v[128:129], v57
	s_waitcnt lgkmcnt(6)
	v_dot8c_i32_i4_e32 v38, v130, v52
	v_dot8c_i32_i4_e32 v39, v130, v50
	v_dot8c_i32_i4_e32 v40, v132, v52
	v_dot8c_i32_i4_e32 v41, v132, v50
	v_dot8c_i32_i4_e32 v42, v134, v52
	v_dot8c_i32_i4_e32 v43, v134, v50
	v_dot8c_i32_i4_e32 v44, v136, v52
	v_dot8c_i32_i4_e32 v45, v136, v50
	v_dot8c_i32_i4_e32 v38, v131, v53
	v_dot8c_i32_i4_e32 v39, v131, v51
	v_dot8c_i32_i4_e32 v40, v133, v53
	v_dot8c_i32_i4_e32 v41, v133, v51
	v_dot8c_i32_i4_e32 v42, v135, v53
	v_dot8c_i32_i4_e32 v43, v135, v51
	v_dot8c_i32_i4_e32 v44, v137, v53
	v_dot8c_i32_i4_e32 v45, v137, v51
	v_and_b32_e32 v78, 0xffff, v27
	v_lshrrev_b32_e32 v79, 16, v27
	v_lshl_add_u32 v78, v78, 7, v150
	v_lshl_add_u32 v79, v79, 7, v151
	s_mov_b32 m0, s77
	s_add_i32 s43, s77, 0x400
	global_load_lds_dwordx4 v78, s[50:51]
	s_mov_b32 m0, s43
	s_nop 0
	global_load_lds_dwordx4 v79, s[50:51]
	s_waitcnt vmcnt(8)
	v_add_u32_e32 v54, s79, v59
	v_add_u32_e32 v55, s79, v60
	v_add_u32_e32 v56, s79, v61
	v_add_u32_e32 v57, s79, v62
	ds_read_b64_tr_b4 v[50:51], v160 offset:640
	ds_read_b64_tr_b4 v[52:53], v160 offset:1664
	ds_read_b64_tr_b4 v[130:131], v54
	ds_read_b64_tr_b4 v[132:133], v55
	ds_read_b64_tr_b4 v[134:135], v56
	ds_read_b64_tr_b4 v[136:137], v57
	s_waitcnt lgkmcnt(6)
	v_dot8c_i32_i4_e32 v38, v122, v48
	v_dot8c_i32_i4_e32 v39, v122, v46
	v_dot8c_i32_i4_e32 v40, v124, v48
	v_dot8c_i32_i4_e32 v41, v124, v46
	v_dot8c_i32_i4_e32 v42, v126, v48
	v_dot8c_i32_i4_e32 v43, v126, v46
	v_dot8c_i32_i4_e32 v44, v128, v48
	v_dot8c_i32_i4_e32 v45, v128, v46
	v_dot8c_i32_i4_e32 v38, v123, v49
	v_dot8c_i32_i4_e32 v39, v123, v47
	v_dot8c_i32_i4_e32 v40, v125, v49
	v_dot8c_i32_i4_e32 v41, v125, v47
	v_dot8c_i32_i4_e32 v42, v127, v49
	v_dot8c_i32_i4_e32 v43, v127, v47
	v_dot8c_i32_i4_e32 v44, v129, v49
	v_dot8c_i32_i4_e32 v45, v129, v47
	s_waitcnt lgkmcnt(15)
; #define LAS __attribute__((address_space(3)))
; __device__ __forceinline__ void peer_v_tokens(int j, const LAS unsigned short* EL, const LAS unsigned char* AL  , const LAS float* ASC  , const LAS int* SAL  , ...
;     ...
;         for (int m = 0; m < 2; ++m) {
;             const int idx = lane + 64 * m, tau = idx >> 4, sr = idx & 15, k = 16 * (sr & 7) + 2 * tau + (sr >> 3);
;             const int aq = (int)*(const LAS signed char*)(AL + tl * 128 + k); const int tq = aq + 8;
;             const unsigned lo = (((unsigned)tq & 15u) ^ 8u) * 0x11111111u, hi = ((unsigned)(tq >> 4) & 15u) * 0x11111111u;
;             typedef unsigned u2v __attribute__((ext_vector_type(2)));
;             u2v l2; l2.x = lo; l2.y = lo; u2v h2; h2.x = hi; h2.y = hi;
;             *(LAS u2v*)(ATL + 8 * idx) = l2; *(LAS u2v*)(ATL + 1024 + 8 * idx) = h2;
;         }
;         const float asc = ASC[tl]; const int sa = SAL[tl];
;     ...
;         for (int st = 0; st < 16; ++st) {
;             const int p = st >> 2, q = st & 3;
;             if (st < 14) VDMA(st + 2, (st + 2) % 3);
;             if (st < 14) asm volatile("s_waitcnt vmcnt(8)" ::: "memory");
;             else if (st == 14) asm volatile("s_waitcnt vmcnt(4)" ::: "memory");
;             else asm volatile("s_waitcnt vmcnt(0)" ::: "memory");
;             if (q == 0) {
; #pragma unroll
;                 for (int r = 0; r < 4; ++r) { accH[r] = 0; accL[r] = 0; } }
; #pragma unroll
;             for (int tp = 0; tp < 2; ++tp) {
;                 const v2i ao = TR4(ATL + (2 * q + tp) * 128 + 8 * s16), ah = TR4(ATL + 1024 + (2 * q + tp) * 128 + 8 * s16);
; #pragma unroll
;                 for (int r = 0; r < 4; ++r) {
;                     const v2i d = TR4(ldsb + BUF[st % 3] + 2048 * tp + roff[r]);
;                     accH[r] = __builtin_amdgcn_sdot8(d.x, ah.x, accH[r], false); accH[r] = __builtin_amdgcn_sdot8(d.y, ah.y, accH[r], false);
;                     accL[r] = __builtin_amdgcn_sdot8(d.x, ao.x, accL[r], false); accL[r] = __builtin_amdgcn_sdot8(d.y, ao.y, accL[r], false);
;                 }
;             }
;             asm volatile("s_waitcnt lgkmcnt(0)" ::: "memory");
;             if (q == 3) {
; #pragma unroll
;                 for (int r = 0; r < 4; ++r) STASH[256 * p + 16 * (grp + 4 * r) + pc] = f2bf(asc * (float)(2 * ((accH[r] << 4) + accL[r]) + sa));
;             }
;         }
	v_add_u32_e32 v143, 8, v139
	v_and_b32_e32 v142, 15, v143
	v_xor_b32_e32 v142, 8, v142
	v_bfe_u32 v144, v143, 4, 4
	v_mul_lo_u32 v142, v142, s92
	v_mul_lo_u32 v144, v144, s92
	v_mov_b32_e32 v143, v142
	v_mov_b32_e32 v145, v144
	ds_write2st64_b64 v159, v[142:143], v[144:145] offset1:2
	v_and_b32_e32 v78, 0xffff, v28
	v_lshrrev_b32_e32 v79, 16, v28
	v_lshl_add_u32 v78, v78, 7, v150
	v_lshl_add_u32 v79, v79, 7, v151
	s_mov_b32 m0, s78
	s_add_i32 s43, s78, 0x400
	global_load_lds_dwordx4 v78, s[50:51]
	s_mov_b32 m0, s43
	s_nop 0
	global_load_lds_dwordx4 v79, s[50:51]
	s_waitcnt vmcnt(8)
	v_add_u32_e32 v54, s98, v59
	v_add_u32_e32 v55, s98, v60
	v_add_u32_e32 v56, s98, v61
	v_add_u32_e32 v57, s98, v62
	ds_read_b64_tr_b4 v[46:47], v160 offset:768
	ds_read_b64_tr_b4 v[48:49], v160 offset:1792
	ds_read_b64_tr_b4 v[122:123], v54
	ds_read_b64_tr_b4 v[124:125], v55
	ds_read_b64_tr_b4 v[126:127], v56
	ds_read_b64_tr_b4 v[128:129], v57
	s_waitcnt lgkmcnt(7)
	v_dot8c_i32_i4_e32 v38, v130, v52
	v_dot8c_i32_i4_e32 v39, v130, v50
	v_dot8c_i32_i4_e32 v40, v132, v52
	v_dot8c_i32_i4_e32 v41, v132, v50
	v_dot8c_i32_i4_e32 v42, v134, v52
	v_dot8c_i32_i4_e32 v43, v134, v50
	v_dot8c_i32_i4_e32 v44, v136, v52
	v_dot8c_i32_i4_e32 v45, v136, v50
	v_dot8c_i32_i4_e32 v38, v131, v53
	v_dot8c_i32_i4_e32 v39, v131, v51
	v_dot8c_i32_i4_e32 v40, v133, v53
	v_dot8c_i32_i4_e32 v41, v133, v51
	v_dot8c_i32_i4_e32 v42, v135, v53
	v_dot8c_i32_i4_e32 v43, v135, v51
	v_dot8c_i32_i4_e32 v44, v137, v53
	v_dot8c_i32_i4_e32 v45, v137, v51
	v_and_b32_e32 v78, 0xffff, v29
	v_lshrrev_b32_e32 v79, 16, v29
	v_lshl_add_u32 v78, v78, 7, v150
	v_lshl_add_u32 v79, v79, 7, v151
	s_mov_b32 m0, s79
	s_add_i32 s43, s79, 0x400
	global_load_lds_dwordx4 v78, s[50:51]
	s_mov_b32 m0, s43
	s_nop 0
	global_load_lds_dwordx4 v79, s[50:51]
	s_waitcnt vmcnt(8)
	v_add_u32_e32 v54, s99, v59
	v_add_u32_e32 v55, s99, v60
	v_add_u32_e32 v56, s99, v61
	v_add_u32_e32 v57, s99, v62
	ds_read_b64_tr_b4 v[50:51], v160 offset:896
	ds_read_b64_tr_b4 v[52:53], v160 offset:1920
	ds_read_b64_tr_b4 v[130:131], v54
	ds_read_b64_tr_b4 v[132:133], v55
	ds_read_b64_tr_b4 v[134:135], v56
	ds_read_b64_tr_b4 v[136:137], v57
	s_waitcnt lgkmcnt(6)
	v_dot8c_i32_i4_e32 v38, v122, v48
	v_dot8c_i32_i4_e32 v39, v122, v46
	v_dot8c_i32_i4_e32 v40, v124, v48
	v_dot8c_i32_i4_e32 v41, v124, v46
	v_dot8c_i32_i4_e32 v42, v126, v48
	v_dot8c_i32_i4_e32 v43, v126, v46
	v_dot8c_i32_i4_e32 v44, v128, v48
	v_dot8c_i32_i4_e32 v45, v128, v46
	v_dot8c_i32_i4_e32 v38, v123, v49
	v_dot8c_i32_i4_e32 v39, v123, v47
	v_dot8c_i32_i4_e32 v40, v125, v49
	v_dot8c_i32_i4_e32 v41, v125, v47
	v_dot8c_i32_i4_e32 v42, v127, v49
	v_dot8c_i32_i4_e32 v43, v127, v47
	v_dot8c_i32_i4_e32 v44, v129, v49
	v_dot8c_i32_i4_e32 v45, v129, v47
	v_and_b32_e32 v78, 0xffff, v30
	v_lshrrev_b32_e32 v79, 16, v30
	v_lshl_add_u32 v78, v78, 7, v150
	v_lshl_add_u32 v79, v79, 7, v151
	s_mov_b32 m0, s98
	s_add_i32 s43, s98, 0x400
	global_load_lds_dwordx4 v78, s[50:51]
	s_mov_b32 m0, s43
	s_nop 0
	global_load_lds_dwordx4 v79, s[50:51]
	s_waitcnt vmcnt(8)
	v_add_u32_e32 v54, s76, v59
	v_add_u32_e32 v55, s76, v60
	v_add_u32_e32 v56, s76, v61
	v_add_u32_e32 v57, s76, v62
	ds_read_b64_tr_b4 v[46:47], v160
	ds_read_b64_tr_b4 v[48:49], v160 offset:1024
	ds_read_b64_tr_b4 v[122:123], v54
	ds_read_b64_tr_b4 v[124:125], v55
	ds_read_b64_tr_b4 v[126:127], v56
	ds_read_b64_tr_b4 v[128:129], v57
	s_waitcnt lgkmcnt(6)
	v_dot8c_i32_i4_e32 v38, v130, v52
	v_dot8c_i32_i4_e32 v39, v130, v50
	v_dot8c_i32_i4_e32 v40, v132, v52
	v_dot8c_i32_i4_e32 v41, v132, v50
	v_dot8c_i32_i4_e32 v42, v134, v52
	v_dot8c_i32_i4_e32 v43, v134, v50
	v_dot8c_i32_i4_e32 v44, v136, v52
	v_dot8c_i32_i4_e32 v45, v136, v50
	v_dot8c_i32_i4_e32 v38, v131, v53
	v_dot8c_i32_i4_e32 v39, v131, v51
	v_dot8c_i32_i4_e32 v40, v133, v53
	v_dot8c_i32_i4_e32 v41, v133, v51
	v_dot8c_i32_i4_e32 v42, v135, v53
	v_dot8c_i32_i4_e32 v43, v135, v51
	v_dot8c_i32_i4_e32 v44, v137, v53
	v_dot8c_i32_i4_e32 v45, v137, v51
	s_nop 3
	s_waitcnt lgkmcnt(15)
	v_lshlrev_b32_e32 v38, 5, v38
	v_lshlrev_b32_e32 v39, 1, v39
	v_add3_u32 v38, v39, v229, v38
	v_cvt_f32_i32_e32 v38, v38
	v_mul_f32_e32 v38, v228, v38
	v_lshlrev_b32_e32 v40, 5, v40
	v_lshlrev_b32_e32 v41, 1, v41
	v_add3_u32 v40, v41, v229, v40
	v_cvt_f32_i32_e32 v40, v40
	v_mul_f32_e32 v40, v228, v40
	v_lshlrev_b32_e32 v42, 5, v42
	v_lshlrev_b32_e32 v43, 1, v43
	v_add3_u32 v42, v43, v229, v42
	v_cvt_f32_i32_e32 v42, v42
	v_mul_f32_e32 v42, v228, v42
	v_lshlrev_b32_e32 v44, 5, v44
	v_lshlrev_b32_e32 v45, 1, v45
	v_add3_u32 v44, v45, v229, v44
	v_cvt_f32_i32_e32 v44, v44
	v_mul_f32_e32 v44, v228, v44
	v_cvt_pk_bf16_f32 v166, v38, v40
	v_cvt_pk_bf16_f32 v167, v42, v44
	v_add_u32_e32 v147, 8, v140
	v_and_b32_e32 v146, 15, v147
	v_xor_b32_e32 v146, 8, v146
	v_bfe_u32 v148, v147, 4, 4
	v_mul_lo_u32 v146, v146, s92
	v_mul_lo_u32 v148, v148, s92
	v_mov_b32_e32 v147, v146
	v_mov_b32_e32 v149, v148
	ds_write2st64_b64 v77, v[146:147], v[148:149] offset1:2
	v_add_u32_e32 v138, 0x800, v74
	ds_read_u8 v139, v138
	v_add_u32_e32 v141, 0x800, v73
	ds_read_u8 v140, v141
	s_add_i32 s43, s67, 32
	v_mov_b32_e32 v138, s43
	ds_read2st64_b32 v[228:229], v138 offset1:1
	ds_read_b128 v[18:21], v227 offset:4096
	ds_read_b128 v[22:25], v227 offset:4112
	v_mov_b32_e32 v38, 0
	v_mov_b32_e32 v39, 0
	v_mov_b32_e32 v40, 0
	v_mov_b32_e32 v41, 0
	v_mov_b32_e32 v42, 0
	v_mov_b32_e32 v43, 0
	v_mov_b32_e32 v44, 0
	v_mov_b32_e32 v45, 0
	v_and_b32_e32 v78, 0xffff, v31
	v_lshrrev_b32_e32 v79, 16, v31
	v_lshl_add_u32 v78, v78, 7, v150
	v_lshl_add_u32 v79, v79, 7, v151
	s_mov_b32 m0, s99
	s_add_i32 s43, s99, 0x400
	global_load_lds_dwordx4 v78, s[50:51]
	s_mov_b32 m0, s43
	s_nop 0
	global_load_lds_dwordx4 v79, s[50:51]
	s_waitcnt vmcnt(8)
; __device__ __forceinline__ bf16 f2bf(float f) { return (bf16)f2bfu(f); }
; #define TR4(p_) __builtin_amdgcn_ds_read_tr4_b64_v2i32((LAS v2i*)(p_))
; #define VDMA(st_, k_) do { _Pragma("unroll") for (int i_ = 0; i_ < 4; ++i_) { \
;         const unsigned off_ = (unsigned)((st_) >> 2) * (16384u * 128u) + (PE_ID(E, 4 * ((st_) & 3) + i_) << 7) + ((i_ & 1) ? cx1 : cx0); \
;         __builtin_amdgcn_global_load_lds((const unsigned*)(V4 + off_), (LAS unsigned*)(ldsb + BUF[k_] + 1024 * i_), 16, 0, 0); } } while (0)
; __device__ __forceinline__ void peer_v_tokens(int j, const LAS unsigned short* EL, const LAS unsigned char* AL  , const LAS float* ASC  , const LAS int* SAL  , ...
;     ...
;         for (int st = 0; st < 16; ++st) {
;             const int p = st >> 2, q = st & 3;
;             if (st < 14) VDMA(st + 2, (st + 2) % 3);
;             if (st < 14) asm volatile("s_waitcnt vmcnt(8)" ::: "memory");
;             else if (st == 14) asm volatile("s_waitcnt vmcnt(4)" ::: "memory");
;             else asm volatile("s_waitcnt vmcnt(0)" ::: "memory");
;             if (q == 0) {
; #pragma unroll
;                 for (int r = 0; r < 4; ++r) { accH[r] = 0; accL[r] = 0; } }
; #pragma unroll
;             for (int tp = 0; tp < 2; ++tp) {
;                 const v2i ao = TR4(ATL + (2 * q + tp) * 128 + 8 * s16), ah = TR4(ATL + 1024 + (2 * q + tp) * 128 + 8 * s16);
; #pragma unroll
;                 for (int r = 0; r < 4; ++r) {
;                     const v2i d = TR4(ldsb + BUF[st % 3] + 2048 * tp + roff[r]);
;                     accH[r] = __builtin_amdgcn_sdot8(d.x, ah.x, accH[r], false); accH[r] = __builtin_amdgcn_sdot8(d.y, ah.y, accH[r], false);
;                     accL[r] = __builtin_amdgcn_sdot8(d.x, ao.x, accL[r], false); accL[r] = __builtin_amdgcn_sdot8(d.y, ao.y, accL[r], false);
;                 }
;             }
;             asm volatile("s_waitcnt lgkmcnt(0)" ::: "memory");
;             if (q == 3) {
; #pragma unroll
;                 for (int r = 0; r < 4; ++r) STASH[256 * p + 16 * (grp + 4 * r) + pc] = f2bf(asc * (float)(2 * ((accH[r] << 4) + accL[r]) + sa));
;             }
;         }
	v_add_u32_e32 v54, s77, v59
	v_add_u32_e32 v55, s77, v60
	v_add_u32_e32 v56, s77, v61
	v_add_u32_e32 v57, s77, v62
	ds_read_b64_tr_b4 v[50:51], v160 offset:128
	ds_read_b64_tr_b4 v[52:53], v160 offset:1152
	ds_read_b64_tr_b4 v[130:131], v54
	ds_read_b64_tr_b4 v[132:133], v55
	ds_read_b64_tr_b4 v[134:135], v56
	ds_read_b64_tr_b4 v[136:137], v57
	s_waitcnt lgkmcnt(12)
	v_dot8c_i32_i4_e32 v38, v122, v48
	v_dot8c_i32_i4_e32 v39, v122, v46
	v_dot8c_i32_i4_e32 v40, v124, v48
	v_dot8c_i32_i4_e32 v41, v124, v46
	v_dot8c_i32_i4_e32 v42, v126, v48
	v_dot8c_i32_i4_e32 v43, v126, v46
	v_dot8c_i32_i4_e32 v44, v128, v48
	v_dot8c_i32_i4_e32 v45, v128, v46
	v_dot8c_i32_i4_e32 v38, v123, v49
	v_dot8c_i32_i4_e32 v39, v123, v47
	v_dot8c_i32_i4_e32 v40, v125, v49
	v_dot8c_i32_i4_e32 v41, v125, v47
	v_dot8c_i32_i4_e32 v42, v127, v49
	v_dot8c_i32_i4_e32 v43, v127, v47
	v_dot8c_i32_i4_e32 v44, v129, v49
	v_dot8c_i32_i4_e32 v45, v129, v47
	v_and_b32_e32 v78, 0xffff, v32
	v_lshrrev_b32_e32 v79, 16, v32
	v_lshl_add_u32 v78, v78, 7, v150
	v_lshl_add_u32 v79, v79, 7, v151
	s_mov_b32 m0, s76
	s_add_i32 s43, s76, 0x400
	global_load_lds_dwordx4 v78, s[50:51]
	s_mov_b32 m0, s43
	s_nop 0
	global_load_lds_dwordx4 v79, s[50:51]
	s_waitcnt vmcnt(8)
	v_add_u32_e32 v54, s78, v59
	v_add_u32_e32 v55, s78, v60
	v_add_u32_e32 v56, s78, v61
	v_add_u32_e32 v57, s78, v62
	ds_read_b64_tr_b4 v[46:47], v160 offset:256
	ds_read_b64_tr_b4 v[48:49], v160 offset:1280
	ds_read_b64_tr_b4 v[122:123], v54
	ds_read_b64_tr_b4 v[124:125], v55
	ds_read_b64_tr_b4 v[126:127], v56
	ds_read_b64_tr_b4 v[128:129], v57
	s_waitcnt lgkmcnt(6)
	v_dot8c_i32_i4_e32 v38, v130, v52
	v_dot8c_i32_i4_e32 v39, v130, v50
	v_dot8c_i32_i4_e32 v40, v132, v52
	v_dot8c_i32_i4_e32 v41, v132, v50
	v_dot8c_i32_i4_e32 v42, v134, v52
	v_dot8c_i32_i4_e32 v43, v134, v50
	v_dot8c_i32_i4_e32 v44, v136, v52
	v_dot8c_i32_i4_e32 v45, v136, v50
	v_dot8c_i32_i4_e32 v38, v131, v53
	v_dot8c_i32_i4_e32 v39, v131, v51
	v_dot8c_i32_i4_e32 v40, v133, v53
	v_dot8c_i32_i4_e32 v41, v133, v51
	v_dot8c_i32_i4_e32 v42, v135, v53
	v_dot8c_i32_i4_e32 v43, v135, v51
	v_dot8c_i32_i4_e32 v44, v137, v53
	v_dot8c_i32_i4_e32 v45, v137, v51
	v_and_b32_e32 v78, 0xffff, v33
	v_lshrrev_b32_e32 v79, 16, v33
	v_lshl_add_u32 v78, v78, 7, v150
	v_lshl_add_u32 v79, v79, 7, v151
	s_mov_b32 m0, s77
	s_add_i32 s43, s77, 0x400
	global_load_lds_dwordx4 v78, s[50:51]
	s_mov_b32 m0, s43
	s_nop 0
	global_load_lds_dwordx4 v79, s[50:51]
	s_waitcnt vmcnt(8)
	v_add_u32_e32 v54, s79, v59
	v_add_u32_e32 v55, s79, v60
	v_add_u32_e32 v56, s79, v61
	v_add_u32_e32 v57, s79, v62
	ds_read_b64_tr_b4 v[50:51], v160 offset:384
	ds_read_b64_tr_b4 v[52:53], v160 offset:1408
	ds_read_b64_tr_b4 v[130:131], v54
	ds_read_b64_tr_b4 v[132:133], v55
	ds_read_b64_tr_b4 v[134:135], v56
	ds_read_b64_tr_b4 v[136:137], v57
	s_waitcnt lgkmcnt(6)
	v_dot8c_i32_i4_e32 v38, v122, v48
	v_dot8c_i32_i4_e32 v39, v122, v46
	v_dot8c_i32_i4_e32 v40, v124, v48
	v_dot8c_i32_i4_e32 v41, v124, v46
	v_dot8c_i32_i4_e32 v42, v126, v48
	v_dot8c_i32_i4_e32 v43, v126, v46
	v_dot8c_i32_i4_e32 v44, v128, v48
	v_dot8c_i32_i4_e32 v45, v128, v46
	v_dot8c_i32_i4_e32 v38, v123, v49
	v_dot8c_i32_i4_e32 v39, v123, v47
	v_dot8c_i32_i4_e32 v40, v125, v49
	v_dot8c_i32_i4_e32 v41, v125, v47
	v_dot8c_i32_i4_e32 v42, v127, v49
	v_dot8c_i32_i4_e32 v43, v127, v47
	v_dot8c_i32_i4_e32 v44, v129, v49
	v_dot8c_i32_i4_e32 v45, v129, v47
	s_waitcnt lgkmcnt(15)
	v_and_b32_e32 v78, 0xffff, v18
	v_lshrrev_b32_e32 v79, 16, v18
	v_lshl_add_u32 v78, v78, 7, v150
	v_lshl_add_u32 v79, v79, 7, v151
	s_mov_b32 m0, s78
	s_add_i32 s43, s78, 0x400
	global_load_lds_dwordx4 v78, s[50:51]
	s_mov_b32 m0, s43
	s_nop 0
	global_load_lds_dwordx4 v79, s[50:51]
	s_waitcnt vmcnt(8)
	v_add_u32_e32 v54, s98, v59
	v_add_u32_e32 v55, s98, v60
	v_add_u32_e32 v56, s98, v61
	v_add_u32_e32 v57, s98, v62
	ds_read_b64_tr_b4 v[46:47], v160 offset:512
	ds_read_b64_tr_b4 v[48:49], v160 offset:1536
	ds_read_b64_tr_b4 v[122:123], v54
	ds_read_b64_tr_b4 v[124:125], v55
	ds_read_b64_tr_b4 v[126:127], v56
	ds_read_b64_tr_b4 v[128:129], v57
	s_waitcnt lgkmcnt(6)
	v_dot8c_i32_i4_e32 v38, v130, v52
	v_dot8c_i32_i4_e32 v39, v130, v50
	v_dot8c_i32_i4_e32 v40, v132, v52
	v_dot8c_i32_i4_e32 v41, v132, v50
	v_dot8c_i32_i4_e32 v42, v134, v52
	v_dot8c_i32_i4_e32 v43, v134, v50
	v_dot8c_i32_i4_e32 v44, v136, v52
	v_dot8c_i32_i4_e32 v45, v136, v50
	v_dot8c_i32_i4_e32 v38, v131, v53
	v_dot8c_i32_i4_e32 v39, v131, v51
	v_dot8c_i32_i4_e32 v40, v133, v53
	v_dot8c_i32_i4_e32 v41, v133, v51
	v_dot8c_i32_i4_e32 v42, v135, v53
	v_dot8c_i32_i4_e32 v43, v135, v51
	v_dot8c_i32_i4_e32 v44, v137, v53
	v_dot8c_i32_i4_e32 v45, v137, v51
	v_and_b32_e32 v78, 0xffff, v19
	v_lshrrev_b32_e32 v79, 16, v19
	v_lshl_add_u32 v78, v78, 7, v150
	v_lshl_add_u32 v79, v79, 7, v151
	s_mov_b32 m0, s79
	s_add_i32 s43, s79, 0x400
	global_load_lds_dwordx4 v78, s[50:51]
	s_mov_b32 m0, s43
	s_nop 0
	global_load_lds_dwordx4 v79, s[50:51]
	s_waitcnt vmcnt(8)
	v_add_u32_e32 v54, s99, v59
	v_add_u32_e32 v55, s99, v60
	v_add_u32_e32 v56, s99, v61
	v_add_u32_e32 v57, s99, v62
	ds_read_b64_tr_b4 v[50:51], v160 offset:640
	ds_read_b64_tr_b4 v[52:53], v160 offset:1664
	ds_read_b64_tr_b4 v[130:131], v54
	ds_read_b64_tr_b4 v[132:133], v55
	ds_read_b64_tr_b4 v[134:135], v56
	ds_read_b64_tr_b4 v[136:137], v57
	s_waitcnt lgkmcnt(6)
	v_dot8c_i32_i4_e32 v38, v122, v48
	v_dot8c_i32_i4_e32 v39, v122, v46
	v_dot8c_i32_i4_e32 v40, v124, v48
	v_dot8c_i32_i4_e32 v41, v124, v46
	v_dot8c_i32_i4_e32 v42, v126, v48
	v_dot8c_i32_i4_e32 v43, v126, v46
	v_dot8c_i32_i4_e32 v44, v128, v48
	v_dot8c_i32_i4_e32 v45, v128, v46
	v_dot8c_i32_i4_e32 v38, v123, v49
	v_dot8c_i32_i4_e32 v39, v123, v47
	v_dot8c_i32_i4_e32 v40, v125, v49
	v_dot8c_i32_i4_e32 v41, v125, v47
	v_dot8c_i32_i4_e32 v42, v127, v49
	v_dot8c_i32_i4_e32 v43, v127, v47
	v_dot8c_i32_i4_e32 v44, v129, v49
	v_dot8c_i32_i4_e32 v45, v129, v47
	s_waitcnt lgkmcnt(15)
; #define LAS __attribute__((address_space(3)))
; __device__ __forceinline__ void peer_v_tokens(int j, const LAS unsigned short* EL, const LAS unsigned char* AL  , const LAS float* ASC  , const LAS int* SAL  , ...
;     ...
;         for (int m = 0; m < 2; ++m) {
;             const int idx = lane + 64 * m, tau = idx >> 4, sr = idx & 15, k = 16 * (sr & 7) + 2 * tau + (sr >> 3);
;             const int aq = (int)*(const LAS signed char*)(AL + tl * 128 + k); const int tq = aq + 8;
;             const unsigned lo = (((unsigned)tq & 15u) ^ 8u) * 0x11111111u, hi = ((unsigned)(tq >> 4) & 15u) * 0x11111111u;
;             typedef unsigned u2v __attribute__((ext_vector_type(2)));
;             u2v l2; l2.x = lo; l2.y = lo; u2v h2; h2.x = hi; h2.y = hi;
;             *(LAS u2v*)(ATL + 8 * idx) = l2; *(LAS u2v*)(ATL + 1024 + 8 * idx) = h2;
;         }
;         const float asc = ASC[tl]; const int sa = SAL[tl];
;     ...
;         for (int st = 0; st < 16; ++st) {
;             const int p = st >> 2, q = st & 3;
;             if (st < 14) VDMA(st + 2, (st + 2) % 3);
;             if (st < 14) asm volatile("s_waitcnt vmcnt(8)" ::: "memory");
;             else if (st == 14) asm volatile("s_waitcnt vmcnt(4)" ::: "memory");
;             else asm volatile("s_waitcnt vmcnt(0)" ::: "memory");
;             if (q == 0) {
; #pragma unroll
;                 for (int r = 0; r < 4; ++r) { accH[r] = 0; accL[r] = 0; } }
; #pragma unroll
;             for (int tp = 0; tp < 2; ++tp) {
;                 const v2i ao = TR4(ATL + (2 * q + tp) * 128 + 8 * s16), ah = TR4(ATL + 1024 + (2 * q + tp) * 128 + 8 * s16);
; #pragma unroll
;                 for (int r = 0; r < 4; ++r) {
;                     const v2i d = TR4(ldsb + BUF[st % 3] + 2048 * tp + roff[r]);
;                     accH[r] = __builtin_amdgcn_sdot8(d.x, ah.x, accH[r], false); accH[r] = __builtin_amdgcn_sdot8(d.y, ah.y, accH[r], false);
;                     accL[r] = __builtin_amdgcn_sdot8(d.x, ao.x, accL[r], false); accL[r] = __builtin_amdgcn_sdot8(d.y, ao.y, accL[r], false);
;                 }
;             }
;             asm volatile("s_waitcnt lgkmcnt(0)" ::: "memory");
;             if (q == 3) {
; #pragma unroll
;                 for (int r = 0; r < 4; ++r) STASH[256 * p + 16 * (grp + 4 * r) + pc] = f2bf(asc * (float)(2 * ((accH[r] << 4) + accL[r]) + sa));
;             }
;         }
	v_add_u32_e32 v143, 8, v139
	v_and_b32_e32 v142, 15, v143
	v_xor_b32_e32 v142, 8, v142
	v_bfe_u32 v144, v143, 4, 4
	v_mul_lo_u32 v142, v142, s92
	v_mul_lo_u32 v144, v144, s92
	v_mov_b32_e32 v143, v142
	v_mov_b32_e32 v145, v144
	ds_write2st64_b64 v159, v[142:143], v[144:145] offset1:2
	v_and_b32_e32 v78, 0xffff, v20
	v_lshrrev_b32_e32 v79, 16, v20
	v_lshl_add_u32 v78, v78, 7, v150
	v_lshl_add_u32 v79, v79, 7, v151
	s_mov_b32 m0, s98
	s_add_i32 s43, s98, 0x400
	global_load_lds_dwordx4 v78, s[50:51]
	s_mov_b32 m0, s43
	s_nop 0
	global_load_lds_dwordx4 v79, s[50:51]
	s_waitcnt vmcnt(8)
	v_add_u32_e32 v54, s76, v59
	v_add_u32_e32 v55, s76, v60
	v_add_u32_e32 v56, s76, v61
	v_add_u32_e32 v57, s76, v62
	ds_read_b64_tr_b4 v[46:47], v160 offset:768
	ds_read_b64_tr_b4 v[48:49], v160 offset:1792
	ds_read_b64_tr_b4 v[122:123], v54
	ds_read_b64_tr_b4 v[124:125], v55
	ds_read_b64_tr_b4 v[126:127], v56
	ds_read_b64_tr_b4 v[128:129], v57
	s_waitcnt lgkmcnt(7)
	v_dot8c_i32_i4_e32 v38, v130, v52
	v_dot8c_i32_i4_e32 v39, v130, v50
	v_dot8c_i32_i4_e32 v40, v132, v52
	v_dot8c_i32_i4_e32 v41, v132, v50
	v_dot8c_i32_i4_e32 v42, v134, v52
	v_dot8c_i32_i4_e32 v43, v134, v50
	v_dot8c_i32_i4_e32 v44, v136, v52
	v_dot8c_i32_i4_e32 v45, v136, v50
	v_dot8c_i32_i4_e32 v38, v131, v53
	v_dot8c_i32_i4_e32 v39, v131, v51
	v_dot8c_i32_i4_e32 v40, v133, v53
	v_dot8c_i32_i4_e32 v41, v133, v51
	v_dot8c_i32_i4_e32 v42, v135, v53
	v_dot8c_i32_i4_e32 v43, v135, v51
	v_dot8c_i32_i4_e32 v44, v137, v53
	v_dot8c_i32_i4_e32 v45, v137, v51
	v_and_b32_e32 v78, 0xffff, v21
	v_lshrrev_b32_e32 v79, 16, v21
	v_lshl_add_u32 v78, v78, 7, v150
	v_lshl_add_u32 v79, v79, 7, v151
	s_mov_b32 m0, s99
	s_add_i32 s43, s99, 0x400
	global_load_lds_dwordx4 v78, s[50:51]
	s_mov_b32 m0, s43
	s_nop 0
	global_load_lds_dwordx4 v79, s[50:51]
	s_waitcnt vmcnt(8)
	v_add_u32_e32 v54, s77, v59
	v_add_u32_e32 v55, s77, v60
	v_add_u32_e32 v56, s77, v61
	v_add_u32_e32 v57, s77, v62
	ds_read_b64_tr_b4 v[50:51], v160 offset:896
	ds_read_b64_tr_b4 v[52:53], v160 offset:1920
	ds_read_b64_tr_b4 v[130:131], v54
	ds_read_b64_tr_b4 v[132:133], v55
	ds_read_b64_tr_b4 v[134:135], v56
	ds_read_b64_tr_b4 v[136:137], v57
	s_waitcnt lgkmcnt(6)
	v_dot8c_i32_i4_e32 v38, v122, v48
	v_dot8c_i32_i4_e32 v39, v122, v46
	v_dot8c_i32_i4_e32 v40, v124, v48
	v_dot8c_i32_i4_e32 v41, v124, v46
	v_dot8c_i32_i4_e32 v42, v126, v48
	v_dot8c_i32_i4_e32 v43, v126, v46
	v_dot8c_i32_i4_e32 v44, v128, v48
	v_dot8c_i32_i4_e32 v45, v128, v46
	v_dot8c_i32_i4_e32 v38, v123, v49
	v_dot8c_i32_i4_e32 v39, v123, v47
	v_dot8c_i32_i4_e32 v40, v125, v49
	v_dot8c_i32_i4_e32 v41, v125, v47
	v_dot8c_i32_i4_e32 v42, v127, v49
	v_dot8c_i32_i4_e32 v43, v127, v47
	v_dot8c_i32_i4_e32 v44, v129, v49
	v_dot8c_i32_i4_e32 v45, v129, v47
	v_and_b32_e32 v78, 0xffff, v22
	v_lshrrev_b32_e32 v79, 16, v22
	v_lshl_add_u32 v78, v78, 7, v150
	v_lshl_add_u32 v79, v79, 7, v151
	s_mov_b32 m0, s76
	s_add_i32 s43, s76, 0x400
	global_load_lds_dwordx4 v78, s[50:51]
	s_mov_b32 m0, s43
	s_nop 0
	global_load_lds_dwordx4 v79, s[50:51]
	s_waitcnt vmcnt(8)
	v_add_u32_e32 v54, s78, v59
	v_add_u32_e32 v55, s78, v60
	v_add_u32_e32 v56, s78, v61
	v_add_u32_e32 v57, s78, v62
	ds_read_b64_tr_b4 v[46:47], v160
	ds_read_b64_tr_b4 v[48:49], v160 offset:1024
	ds_read_b64_tr_b4 v[122:123], v54
	ds_read_b64_tr_b4 v[124:125], v55
	ds_read_b64_tr_b4 v[126:127], v56
	ds_read_b64_tr_b4 v[128:129], v57
	s_waitcnt lgkmcnt(6)
	v_dot8c_i32_i4_e32 v38, v130, v52
	v_dot8c_i32_i4_e32 v39, v130, v50
	v_dot8c_i32_i4_e32 v40, v132, v52
	v_dot8c_i32_i4_e32 v41, v132, v50
	v_dot8c_i32_i4_e32 v42, v134, v52
	v_dot8c_i32_i4_e32 v43, v134, v50
	v_dot8c_i32_i4_e32 v44, v136, v52
	v_dot8c_i32_i4_e32 v45, v136, v50
	v_dot8c_i32_i4_e32 v38, v131, v53
	v_dot8c_i32_i4_e32 v39, v131, v51
	v_dot8c_i32_i4_e32 v40, v133, v53
	v_dot8c_i32_i4_e32 v41, v133, v51
	v_dot8c_i32_i4_e32 v42, v135, v53
	v_dot8c_i32_i4_e32 v43, v135, v51
	v_dot8c_i32_i4_e32 v44, v137, v53
	v_dot8c_i32_i4_e32 v45, v137, v51
	s_nop 3
	s_waitcnt lgkmcnt(15)
	v_lshlrev_b32_e32 v38, 5, v38
	v_lshlrev_b32_e32 v39, 1, v39
	v_add3_u32 v38, v39, v229, v38
	v_cvt_f32_i32_e32 v38, v38
	v_mul_f32_e32 v38, v228, v38
	v_lshlrev_b32_e32 v40, 5, v40
	v_lshlrev_b32_e32 v41, 1, v41
	v_add3_u32 v40, v41, v229, v40
	v_cvt_f32_i32_e32 v40, v40
	v_mul_f32_e32 v40, v228, v40
	v_lshlrev_b32_e32 v42, 5, v42
	v_lshlrev_b32_e32 v43, 1, v43
	v_add3_u32 v42, v43, v229, v42
	v_cvt_f32_i32_e32 v42, v42
	v_mul_f32_e32 v42, v228, v42
	v_lshlrev_b32_e32 v44, 5, v44
	v_lshlrev_b32_e32 v45, 1, v45
	v_add3_u32 v44, v45, v229, v44
	v_cvt_f32_i32_e32 v44, v44
	v_mul_f32_e32 v44, v228, v44
	v_cvt_pk_bf16_f32 v174, v38, v40
	v_cvt_pk_bf16_f32 v175, v42, v44
	v_add_u32_e32 v147, 8, v140
	v_and_b32_e32 v146, 15, v147
	v_xor_b32_e32 v146, 8, v146
	v_bfe_u32 v148, v147, 4, 4
	v_mul_lo_u32 v146, v146, s92
	v_mul_lo_u32 v148, v148, s92
	v_mov_b32_e32 v147, v146
	v_mov_b32_e32 v149, v148
	ds_write2st64_b64 v77, v[146:147], v[148:149] offset1:2
	v_add_u32_e32 v138, 0xc00, v74
	ds_read_u8 v139, v138
	v_add_u32_e32 v141, 0xc00, v73
	ds_read_u8 v140, v141
	s_add_i32 s43, s67, 64
	v_mov_b32_e32 v138, s43
	ds_read2st64_b32 v[228:229], v138 offset1:1
	ds_read_b128 v[26:29], v227 offset:6144
	ds_read_b128 v[30:33], v227 offset:6160
	v_mov_b32_e32 v38, 0
	v_mov_b32_e32 v39, 0
	v_mov_b32_e32 v40, 0
	v_mov_b32_e32 v41, 0
	v_mov_b32_e32 v42, 0
	v_mov_b32_e32 v43, 0
	v_mov_b32_e32 v44, 0
	v_mov_b32_e32 v45, 0
	v_and_b32_e32 v78, 0xffff, v23
	v_lshrrev_b32_e32 v79, 16, v23
	v_lshl_add_u32 v78, v78, 7, v150
	v_lshl_add_u32 v79, v79, 7, v151
	s_mov_b32 m0, s77
	s_add_i32 s43, s77, 0x400
	global_load_lds_dwordx4 v78, s[50:51]
	s_mov_b32 m0, s43
	s_nop 0
	global_load_lds_dwordx4 v79, s[50:51]
	s_waitcnt vmcnt(8)
; __device__ __forceinline__ bf16 f2bf(float f) { return (bf16)f2bfu(f); }
; #define TR4(p_) __builtin_amdgcn_ds_read_tr4_b64_v2i32((LAS v2i*)(p_))
; #define VDMA(st_, k_) do { _Pragma("unroll") for (int i_ = 0; i_ < 4; ++i_) { \
;         const unsigned off_ = (unsigned)((st_) >> 2) * (16384u * 128u) + (PE_ID(E, 4 * ((st_) & 3) + i_) << 7) + ((i_ & 1) ? cx1 : cx0); \
;         __builtin_amdgcn_global_load_lds((const unsigned*)(V4 + off_), (LAS unsigned*)(ldsb + BUF[k_] + 1024 * i_), 16, 0, 0); } } while (0)
; __device__ __forceinline__ void peer_v_tokens(int j, const LAS unsigned short* EL, const LAS unsigned char* AL  , const LAS float* ASC  , const LAS int* SAL  , ...
;     ...
;         for (int st = 0; st < 16; ++st) {
;             const int p = st >> 2, q = st & 3;
;             if (st < 14) VDMA(st + 2, (st + 2) % 3);
;             if (st < 14) asm volatile("s_waitcnt vmcnt(8)" ::: "memory");
;             else if (st == 14) asm volatile("s_waitcnt vmcnt(4)" ::: "memory");
;             else asm volatile("s_waitcnt vmcnt(0)" ::: "memory");
;             if (q == 0) {
; #pragma unroll
;                 for (int r = 0; r < 4; ++r) { accH[r] = 0; accL[r] = 0; } }
; #pragma unroll
;             for (int tp = 0; tp < 2; ++tp) {
;                 const v2i ao = TR4(ATL + (2 * q + tp) * 128 + 8 * s16), ah = TR4(ATL + 1024 + (2 * q + tp) * 128 + 8 * s16);
; #pragma unroll
;                 for (int r = 0; r < 4; ++r) {
;                     const v2i d = TR4(ldsb + BUF[st % 3] + 2048 * tp + roff[r]);
;                     accH[r] = __builtin_amdgcn_sdot8(d.x, ah.x, accH[r], false); accH[r] = __builtin_amdgcn_sdot8(d.y, ah.y, accH[r], false);
;                     accL[r] = __builtin_amdgcn_sdot8(d.x, ao.x, accL[r], false); accL[r] = __builtin_amdgcn_sdot8(d.y, ao.y, accL[r], false);
;                 }
;             }
;             asm volatile("s_waitcnt lgkmcnt(0)" ::: "memory");
;             if (q == 3) {
; #pragma unroll
;                 for (int r = 0; r < 4; ++r) STASH[256 * p + 16 * (grp + 4 * r) + pc] = f2bf(asc * (float)(2 * ((accH[r] << 4) + accL[r]) + sa));
;             }
;         }
	v_add_u32_e32 v54, s79, v59
	v_add_u32_e32 v55, s79, v60
	v_add_u32_e32 v56, s79, v61
	v_add_u32_e32 v57, s79, v62
	ds_read_b64_tr_b4 v[50:51], v160 offset:128
	ds_read_b64_tr_b4 v[52:53], v160 offset:1152
	ds_read_b64_tr_b4 v[130:131], v54
	ds_read_b64_tr_b4 v[132:133], v55
	ds_read_b64_tr_b4 v[134:135], v56
	ds_read_b64_tr_b4 v[136:137], v57
	s_waitcnt lgkmcnt(12)
	v_dot8c_i32_i4_e32 v38, v122, v48
	v_dot8c_i32_i4_e32 v39, v122, v46
	v_dot8c_i32_i4_e32 v40, v124, v48
	v_dot8c_i32_i4_e32 v41, v124, v46
	v_dot8c_i32_i4_e32 v42, v126, v48
	v_dot8c_i32_i4_e32 v43, v126, v46
	v_dot8c_i32_i4_e32 v44, v128, v48
	v_dot8c_i32_i4_e32 v45, v128, v46
	v_dot8c_i32_i4_e32 v38, v123, v49
	v_dot8c_i32_i4_e32 v39, v123, v47
	v_dot8c_i32_i4_e32 v40, v125, v49
	v_dot8c_i32_i4_e32 v41, v125, v47
	v_dot8c_i32_i4_e32 v42, v127, v49
	v_dot8c_i32_i4_e32 v43, v127, v47
	v_dot8c_i32_i4_e32 v44, v129, v49
	v_dot8c_i32_i4_e32 v45, v129, v47
	v_and_b32_e32 v78, 0xffff, v24
	v_lshrrev_b32_e32 v79, 16, v24
	v_lshl_add_u32 v78, v78, 7, v150
	v_lshl_add_u32 v79, v79, 7, v151
	s_mov_b32 m0, s78
	s_add_i32 s43, s78, 0x400
	global_load_lds_dwordx4 v78, s[50:51]
	s_mov_b32 m0, s43
	s_nop 0
	global_load_lds_dwordx4 v79, s[50:51]
	s_waitcnt vmcnt(8)
	v_add_u32_e32 v54, s98, v59
	v_add_u32_e32 v55, s98, v60
	v_add_u32_e32 v56, s98, v61
	v_add_u32_e32 v57, s98, v62
	ds_read_b64_tr_b4 v[46:47], v160 offset:256
	ds_read_b64_tr_b4 v[48:49], v160 offset:1280
	ds_read_b64_tr_b4 v[122:123], v54
	ds_read_b64_tr_b4 v[124:125], v55
	ds_read_b64_tr_b4 v[126:127], v56
	ds_read_b64_tr_b4 v[128:129], v57
	s_waitcnt lgkmcnt(6)
	v_dot8c_i32_i4_e32 v38, v130, v52
	v_dot8c_i32_i4_e32 v39, v130, v50
	v_dot8c_i32_i4_e32 v40, v132, v52
	v_dot8c_i32_i4_e32 v41, v132, v50
	v_dot8c_i32_i4_e32 v42, v134, v52
	v_dot8c_i32_i4_e32 v43, v134, v50
	v_dot8c_i32_i4_e32 v44, v136, v52
	v_dot8c_i32_i4_e32 v45, v136, v50
	v_dot8c_i32_i4_e32 v38, v131, v53
	v_dot8c_i32_i4_e32 v39, v131, v51
	v_dot8c_i32_i4_e32 v40, v133, v53
	v_dot8c_i32_i4_e32 v41, v133, v51
	v_dot8c_i32_i4_e32 v42, v135, v53
	v_dot8c_i32_i4_e32 v43, v135, v51
	v_dot8c_i32_i4_e32 v44, v137, v53
	v_dot8c_i32_i4_e32 v45, v137, v51
	v_and_b32_e32 v78, 0xffff, v25
	v_lshrrev_b32_e32 v79, 16, v25
	v_lshl_add_u32 v78, v78, 7, v150
	v_lshl_add_u32 v79, v79, 7, v151
	s_mov_b32 m0, s79
	s_add_i32 s43, s79, 0x400
	global_load_lds_dwordx4 v78, s[50:51]
	s_mov_b32 m0, s43
	s_nop 0
	global_load_lds_dwordx4 v79, s[50:51]
	s_waitcnt vmcnt(8)
	v_add_u32_e32 v54, s99, v59
	v_add_u32_e32 v55, s99, v60
	v_add_u32_e32 v56, s99, v61
	v_add_u32_e32 v57, s99, v62
	ds_read_b64_tr_b4 v[50:51], v160 offset:384
	ds_read_b64_tr_b4 v[52:53], v160 offset:1408
	ds_read_b64_tr_b4 v[130:131], v54
	ds_read_b64_tr_b4 v[132:133], v55
	ds_read_b64_tr_b4 v[134:135], v56
	ds_read_b64_tr_b4 v[136:137], v57
	s_waitcnt lgkmcnt(6)
	v_dot8c_i32_i4_e32 v38, v122, v48
	v_dot8c_i32_i4_e32 v39, v122, v46
	v_dot8c_i32_i4_e32 v40, v124, v48
	v_dot8c_i32_i4_e32 v41, v124, v46
	v_dot8c_i32_i4_e32 v42, v126, v48
	v_dot8c_i32_i4_e32 v43, v126, v46
	v_dot8c_i32_i4_e32 v44, v128, v48
	v_dot8c_i32_i4_e32 v45, v128, v46
	v_dot8c_i32_i4_e32 v38, v123, v49
	v_dot8c_i32_i4_e32 v39, v123, v47
	v_dot8c_i32_i4_e32 v40, v125, v49
	v_dot8c_i32_i4_e32 v41, v125, v47
	v_dot8c_i32_i4_e32 v42, v127, v49
	v_dot8c_i32_i4_e32 v43, v127, v47
	v_dot8c_i32_i4_e32 v44, v129, v49
	v_dot8c_i32_i4_e32 v45, v129, v47
	s_waitcnt lgkmcnt(15)
	v_and_b32_e32 v78, 0xffff, v26
	v_lshrrev_b32_e32 v79, 16, v26
	v_lshl_add_u32 v78, v78, 7, v150
	v_lshl_add_u32 v79, v79, 7, v151
	s_mov_b32 m0, s98
	s_add_i32 s43, s98, 0x400
	global_load_lds_dwordx4 v78, s[50:51]
	s_mov_b32 m0, s43
	s_nop 0
	global_load_lds_dwordx4 v79, s[50:51]
	s_waitcnt vmcnt(8)
	v_add_u32_e32 v54, s76, v59
	v_add_u32_e32 v55, s76, v60
	v_add_u32_e32 v56, s76, v61
	v_add_u32_e32 v57, s76, v62
	ds_read_b64_tr_b4 v[46:47], v160 offset:512
	ds_read_b64_tr_b4 v[48:49], v160 offset:1536
	ds_read_b64_tr_b4 v[122:123], v54
	ds_read_b64_tr_b4 v[124:125], v55
	ds_read_b64_tr_b4 v[126:127], v56
	ds_read_b64_tr_b4 v[128:129], v57
	s_waitcnt lgkmcnt(6)
	v_dot8c_i32_i4_e32 v38, v130, v52
	v_dot8c_i32_i4_e32 v39, v130, v50
	v_dot8c_i32_i4_e32 v40, v132, v52
	v_dot8c_i32_i4_e32 v41, v132, v50
	v_dot8c_i32_i4_e32 v42, v134, v52
	v_dot8c_i32_i4_e32 v43, v134, v50
	v_dot8c_i32_i4_e32 v44, v136, v52
	v_dot8c_i32_i4_e32 v45, v136, v50
	v_dot8c_i32_i4_e32 v38, v131, v53
	v_dot8c_i32_i4_e32 v39, v131, v51
	v_dot8c_i32_i4_e32 v40, v133, v53
	v_dot8c_i32_i4_e32 v41, v133, v51
	v_dot8c_i32_i4_e32 v42, v135, v53
	v_dot8c_i32_i4_e32 v43, v135, v51
	v_dot8c_i32_i4_e32 v44, v137, v53
	v_dot8c_i32_i4_e32 v45, v137, v51
	v_and_b32_e32 v78, 0xffff, v27
	v_lshrrev_b32_e32 v79, 16, v27
	v_lshl_add_u32 v78, v78, 7, v150
	v_lshl_add_u32 v79, v79, 7, v151
	s_mov_b32 m0, s99
	s_add_i32 s43, s99, 0x400
	global_load_lds_dwordx4 v78, s[50:51]
	s_mov_b32 m0, s43
	s_nop 0
	global_load_lds_dwordx4 v79, s[50:51]
	s_waitcnt vmcnt(8)
	v_add_u32_e32 v54, s77, v59
	v_add_u32_e32 v55, s77, v60
	v_add_u32_e32 v56, s77, v61
	v_add_u32_e32 v57, s77, v62
	ds_read_b64_tr_b4 v[50:51], v160 offset:640
	ds_read_b64_tr_b4 v[52:53], v160 offset:1664
	ds_read_b64_tr_b4 v[130:131], v54
	ds_read_b64_tr_b4 v[132:133], v55
	ds_read_b64_tr_b4 v[134:135], v56
	ds_read_b64_tr_b4 v[136:137], v57
	s_waitcnt lgkmcnt(6)
	v_dot8c_i32_i4_e32 v38, v122, v48
	v_dot8c_i32_i4_e32 v39, v122, v46
	v_dot8c_i32_i4_e32 v40, v124, v48
	v_dot8c_i32_i4_e32 v41, v124, v46
	v_dot8c_i32_i4_e32 v42, v126, v48
	v_dot8c_i32_i4_e32 v43, v126, v46
	v_dot8c_i32_i4_e32 v44, v128, v48
	v_dot8c_i32_i4_e32 v45, v128, v46
	v_dot8c_i32_i4_e32 v38, v123, v49
	v_dot8c_i32_i4_e32 v39, v123, v47
	v_dot8c_i32_i4_e32 v40, v125, v49
	v_dot8c_i32_i4_e32 v41, v125, v47
	v_dot8c_i32_i4_e32 v42, v127, v49
	v_dot8c_i32_i4_e32 v43, v127, v47
	v_dot8c_i32_i4_e32 v44, v129, v49
	v_dot8c_i32_i4_e32 v45, v129, v47
	s_waitcnt lgkmcnt(15)
; #define LAS __attribute__((address_space(3)))
; __device__ __forceinline__ void peer_v_tokens(int j, const LAS unsigned short* EL, const LAS unsigned char* AL  , const LAS float* ASC  , const LAS int* SAL  , ...
;     ...
;         for (int m = 0; m < 2; ++m) {
;             const int idx = lane + 64 * m, tau = idx >> 4, sr = idx & 15, k = 16 * (sr & 7) + 2 * tau + (sr >> 3);
;             const int aq = (int)*(const LAS signed char*)(AL + tl * 128 + k); const int tq = aq + 8;
;             const unsigned lo = (((unsigned)tq & 15u) ^ 8u) * 0x11111111u, hi = ((unsigned)(tq >> 4) & 15u) * 0x11111111u;
;             typedef unsigned u2v __attribute__((ext_vector_type(2)));
;             u2v l2; l2.x = lo; l2.y = lo; u2v h2; h2.x = hi; h2.y = hi;
;             *(LAS u2v*)(ATL + 8 * idx) = l2; *(LAS u2v*)(ATL + 1024 + 8 * idx) = h2;
;         }
;         const float asc = ASC[tl]; const int sa = SAL[tl];
;     ...
;         for (int st = 0; st < 16; ++st) {
;             const int p = st >> 2, q = st & 3;
;             if (st < 14) VDMA(st + 2, (st + 2) % 3);
;             if (st < 14) asm volatile("s_waitcnt vmcnt(8)" ::: "memory");
;             else if (st == 14) asm volatile("s_waitcnt vmcnt(4)" ::: "memory");
;             else asm volatile("s_waitcnt vmcnt(0)" ::: "memory");
;             if (q == 0) {
; #pragma unroll
;                 for (int r = 0; r < 4; ++r) { accH[r] = 0; accL[r] = 0; } }
; #pragma unroll
;             for (int tp = 0; tp < 2; ++tp) {
;                 const v2i ao = TR4(ATL + (2 * q + tp) * 128 + 8 * s16), ah = TR4(ATL + 1024 + (2 * q + tp) * 128 + 8 * s16);
; #pragma unroll
;                 for (int r = 0; r < 4; ++r) {
;                     const v2i d = TR4(ldsb + BUF[st % 3] + 2048 * tp + roff[r]);
;                     accH[r] = __builtin_amdgcn_sdot8(d.x, ah.x, accH[r], false); accH[r] = __builtin_amdgcn_sdot8(d.y, ah.y, accH[r], false);
;                     accL[r] = __builtin_amdgcn_sdot8(d.x, ao.x, accL[r], false); accL[r] = __builtin_amdgcn_sdot8(d.y, ao.y, accL[r], false);
;                 }
;             }
;             asm volatile("s_waitcnt lgkmcnt(0)" ::: "memory");
;             if (q == 3) {
; #pragma unroll
;                 for (int r = 0; r < 4; ++r) STASH[256 * p + 16 * (grp + 4 * r) + pc] = f2bf(asc * (float)(2 * ((accH[r] << 4) + accL[r]) + sa));
;             }
;         }
	v_add_u32_e32 v143, 8, v139
	v_and_b32_e32 v142, 15, v143
	v_xor_b32_e32 v142, 8, v142
	v_bfe_u32 v144, v143, 4, 4
	v_mul_lo_u32 v142, v142, s92
	v_mul_lo_u32 v144, v144, s92
	v_mov_b32_e32 v143, v142
	v_mov_b32_e32 v145, v144
	ds_write2st64_b64 v159, v[142:143], v[144:145] offset1:2
	v_and_b32_e32 v78, 0xffff, v28
	v_lshrrev_b32_e32 v79, 16, v28
	v_lshl_add_u32 v78, v78, 7, v150
	v_lshl_add_u32 v79, v79, 7, v151
	s_mov_b32 m0, s76
	s_add_i32 s43, s76, 0x400
	global_load_lds_dwordx4 v78, s[50:51]
	s_mov_b32 m0, s43
	s_nop 0
	global_load_lds_dwordx4 v79, s[50:51]
	s_waitcnt vmcnt(8)
	v_add_u32_e32 v54, s78, v59
	v_add_u32_e32 v55, s78, v60
	v_add_u32_e32 v56, s78, v61
	v_add_u32_e32 v57, s78, v62
	ds_read_b64_tr_b4 v[46:47], v160 offset:768
	ds_read_b64_tr_b4 v[48:49], v160 offset:1792
	ds_read_b64_tr_b4 v[122:123], v54
	ds_read_b64_tr_b4 v[124:125], v55
	ds_read_b64_tr_b4 v[126:127], v56
	ds_read_b64_tr_b4 v[128:129], v57
	s_waitcnt lgkmcnt(7)
	v_dot8c_i32_i4_e32 v38, v130, v52
	v_dot8c_i32_i4_e32 v39, v130, v50
	v_dot8c_i32_i4_e32 v40, v132, v52
	v_dot8c_i32_i4_e32 v41, v132, v50
	v_dot8c_i32_i4_e32 v42, v134, v52
	v_dot8c_i32_i4_e32 v43, v134, v50
	v_dot8c_i32_i4_e32 v44, v136, v52
	v_dot8c_i32_i4_e32 v45, v136, v50
	v_dot8c_i32_i4_e32 v38, v131, v53
	v_dot8c_i32_i4_e32 v39, v131, v51
	v_dot8c_i32_i4_e32 v40, v133, v53
	v_dot8c_i32_i4_e32 v41, v133, v51
	v_dot8c_i32_i4_e32 v42, v135, v53
	v_dot8c_i32_i4_e32 v43, v135, v51
	v_dot8c_i32_i4_e32 v44, v137, v53
	v_dot8c_i32_i4_e32 v45, v137, v51
	v_and_b32_e32 v78, 0xffff, v29
	v_lshrrev_b32_e32 v79, 16, v29
	v_lshl_add_u32 v78, v78, 7, v150
	v_lshl_add_u32 v79, v79, 7, v151
	s_mov_b32 m0, s77
	s_add_i32 s43, s77, 0x400
	global_load_lds_dwordx4 v78, s[50:51]
	s_mov_b32 m0, s43
	s_nop 0
	global_load_lds_dwordx4 v79, s[50:51]
	s_waitcnt vmcnt(8)
	v_add_u32_e32 v54, s79, v59
	v_add_u32_e32 v55, s79, v60
	v_add_u32_e32 v56, s79, v61
	v_add_u32_e32 v57, s79, v62
	ds_read_b64_tr_b4 v[50:51], v160 offset:896
	ds_read_b64_tr_b4 v[52:53], v160 offset:1920
	ds_read_b64_tr_b4 v[130:131], v54
	ds_read_b64_tr_b4 v[132:133], v55
	ds_read_b64_tr_b4 v[134:135], v56
	ds_read_b64_tr_b4 v[136:137], v57
	s_waitcnt lgkmcnt(6)
	v_dot8c_i32_i4_e32 v38, v122, v48
	v_dot8c_i32_i4_e32 v39, v122, v46
	v_dot8c_i32_i4_e32 v40, v124, v48
	v_dot8c_i32_i4_e32 v41, v124, v46
	v_dot8c_i32_i4_e32 v42, v126, v48
	v_dot8c_i32_i4_e32 v43, v126, v46
	v_dot8c_i32_i4_e32 v44, v128, v48
	v_dot8c_i32_i4_e32 v45, v128, v46
	v_dot8c_i32_i4_e32 v38, v123, v49
	v_dot8c_i32_i4_e32 v39, v123, v47
	v_dot8c_i32_i4_e32 v40, v125, v49
	v_dot8c_i32_i4_e32 v41, v125, v47
	v_dot8c_i32_i4_e32 v42, v127, v49
	v_dot8c_i32_i4_e32 v43, v127, v47
	v_dot8c_i32_i4_e32 v44, v129, v49
	v_dot8c_i32_i4_e32 v45, v129, v47
	v_and_b32_e32 v78, 0xffff, v30
	v_lshrrev_b32_e32 v79, 16, v30
	v_lshl_add_u32 v78, v78, 7, v150
	v_lshl_add_u32 v79, v79, 7, v151
	s_mov_b32 m0, s78
	s_add_i32 s43, s78, 0x400
	global_load_lds_dwordx4 v78, s[50:51]
	s_mov_b32 m0, s43
	s_nop 0
	global_load_lds_dwordx4 v79, s[50:51]
	s_waitcnt vmcnt(8)
	v_add_u32_e32 v54, s98, v59
	v_add_u32_e32 v55, s98, v60
	v_add_u32_e32 v56, s98, v61
	v_add_u32_e32 v57, s98, v62
	ds_read_b64_tr_b4 v[46:47], v160
	ds_read_b64_tr_b4 v[48:49], v160 offset:1024
	ds_read_b64_tr_b4 v[122:123], v54
	ds_read_b64_tr_b4 v[124:125], v55
	ds_read_b64_tr_b4 v[126:127], v56
	ds_read_b64_tr_b4 v[128:129], v57
	s_waitcnt lgkmcnt(6)
	v_dot8c_i32_i4_e32 v38, v130, v52
	v_dot8c_i32_i4_e32 v39, v130, v50
	v_dot8c_i32_i4_e32 v40, v132, v52
	v_dot8c_i32_i4_e32 v41, v132, v50
	v_dot8c_i32_i4_e32 v42, v134, v52
	v_dot8c_i32_i4_e32 v43, v134, v50
	v_dot8c_i32_i4_e32 v44, v136, v52
	v_dot8c_i32_i4_e32 v45, v136, v50
	v_dot8c_i32_i4_e32 v38, v131, v53
	v_dot8c_i32_i4_e32 v39, v131, v51
	v_dot8c_i32_i4_e32 v40, v133, v53
	v_dot8c_i32_i4_e32 v41, v133, v51
	v_dot8c_i32_i4_e32 v42, v135, v53
	v_dot8c_i32_i4_e32 v43, v135, v51
	v_dot8c_i32_i4_e32 v44, v137, v53
	v_dot8c_i32_i4_e32 v45, v137, v51
	s_nop 3
	s_waitcnt lgkmcnt(15)
	v_lshlrev_b32_e32 v38, 5, v38
	v_lshlrev_b32_e32 v39, 1, v39
	v_add3_u32 v38, v39, v229, v38
	v_cvt_f32_i32_e32 v38, v38
	v_mul_f32_e32 v38, v228, v38
	v_lshlrev_b32_e32 v40, 5, v40
	v_lshlrev_b32_e32 v41, 1, v41
	v_add3_u32 v40, v41, v229, v40
	v_cvt_f32_i32_e32 v40, v40
	v_mul_f32_e32 v40, v228, v40
	v_lshlrev_b32_e32 v42, 5, v42
	v_lshlrev_b32_e32 v43, 1, v43
	v_add3_u32 v42, v43, v229, v42
	v_cvt_f32_i32_e32 v42, v42
	v_mul_f32_e32 v42, v228, v42
	v_lshlrev_b32_e32 v44, 5, v44
	v_lshlrev_b32_e32 v45, 1, v45
	v_add3_u32 v44, v45, v229, v44
	v_cvt_f32_i32_e32 v44, v44
	v_mul_f32_e32 v44, v228, v44
	v_cvt_pk_bf16_f32 v182, v38, v40
	v_cvt_pk_bf16_f32 v183, v42, v44
	v_add_u32_e32 v147, 8, v140
	v_and_b32_e32 v146, 15, v147
	v_xor_b32_e32 v146, 8, v146
	v_bfe_u32 v148, v147, 4, 4
	v_mul_lo_u32 v146, v146, s92
	v_mul_lo_u32 v148, v148, s92
	v_mov_b32_e32 v147, v146
	v_mov_b32_e32 v149, v148
	ds_write2st64_b64 v77, v[146:147], v[148:149] offset1:2
	v_mov_b32_e32 v138, v74
	ds_read_u8 v139, v138
	v_mov_b32_e32 v141, v73
	ds_read_u8 v140, v141
	s_add_i32 s43, s67, 96
	v_mov_b32_e32 v138, s43
	ds_read2st64_b32 v[228:229], v138 offset1:1
	ds_read_b128 v[18:21], v227
	ds_read_b128 v[22:25], v227 offset:16
	v_add_u32_e32 v152, 0x600000, v63
	v_add_u32_e32 v153, 0x600000, v64
	v_mov_b32_e32 v38, 0
	v_mov_b32_e32 v39, 0
	v_mov_b32_e32 v40, 0
	v_mov_b32_e32 v41, 0
	v_mov_b32_e32 v42, 0
	v_mov_b32_e32 v43, 0
	v_mov_b32_e32 v44, 0
	v_mov_b32_e32 v45, 0
	v_and_b32_e32 v78, 0xffff, v31
	v_lshrrev_b32_e32 v79, 16, v31
	v_lshl_add_u32 v78, v78, 7, v150
	v_lshl_add_u32 v79, v79, 7, v151
	s_mov_b32 m0, s79
	s_add_i32 s43, s79, 0x400
	global_load_lds_dwordx4 v78, s[50:51]
	s_mov_b32 m0, s43
	s_nop 0
	global_load_lds_dwordx4 v79, s[50:51]
	s_waitcnt vmcnt(8)
; __device__ __forceinline__ bf16 f2bf(float f) { return (bf16)f2bfu(f); }
; #define TR4(p_) __builtin_amdgcn_ds_read_tr4_b64_v2i32((LAS v2i*)(p_))
; #define VDMA(st_, k_) do { _Pragma("unroll") for (int i_ = 0; i_ < 4; ++i_) { \
;         const unsigned off_ = (unsigned)((st_) >> 2) * (16384u * 128u) + (PE_ID(E, 4 * ((st_) & 3) + i_) << 7) + ((i_ & 1) ? cx1 : cx0); \
;         __builtin_amdgcn_global_load_lds((const unsigned*)(V4 + off_), (LAS unsigned*)(ldsb + BUF[k_] + 1024 * i_), 16, 0, 0); } } while (0)
; __device__ __forceinline__ void peer_v_tokens(int j, const LAS unsigned short* EL, const LAS unsigned char* AL  , const LAS float* ASC  , const LAS int* SAL  , ...
;     ...
;         for (int st = 0; st < 16; ++st) {
;             const int p = st >> 2, q = st & 3;
;             if (st < 14) VDMA(st + 2, (st + 2) % 3);
;             if (st < 14) asm volatile("s_waitcnt vmcnt(8)" ::: "memory");
;             else if (st == 14) asm volatile("s_waitcnt vmcnt(4)" ::: "memory");
;             else asm volatile("s_waitcnt vmcnt(0)" ::: "memory");
;             if (q == 0) {
; #pragma unroll
;                 for (int r = 0; r < 4; ++r) { accH[r] = 0; accL[r] = 0; } }
; #pragma unroll
;             for (int tp = 0; tp < 2; ++tp) {
;                 const v2i ao = TR4(ATL + (2 * q + tp) * 128 + 8 * s16), ah = TR4(ATL + 1024 + (2 * q + tp) * 128 + 8 * s16);
; #pragma unroll
;                 for (int r = 0; r < 4; ++r) {
;                     const v2i d = TR4(ldsb + BUF[st % 3] + 2048 * tp + roff[r]);
;                     accH[r] = __builtin_amdgcn_sdot8(d.x, ah.x, accH[r], false); accH[r] = __builtin_amdgcn_sdot8(d.y, ah.y, accH[r], false);
;                     accL[r] = __builtin_amdgcn_sdot8(d.x, ao.x, accL[r], false); accL[r] = __builtin_amdgcn_sdot8(d.y, ao.y, accL[r], false);
;                 }
;             }
;             asm volatile("s_waitcnt lgkmcnt(0)" ::: "memory");
;             if (q == 3) {
; #pragma unroll
;                 for (int r = 0; r < 4; ++r) STASH[256 * p + 16 * (grp + 4 * r) + pc] = f2bf(asc * (float)(2 * ((accH[r] << 4) + accL[r]) + sa));
;             }
;         }
	v_add_u32_e32 v54, s99, v59
	v_add_u32_e32 v55, s99, v60
	v_add_u32_e32 v56, s99, v61
	v_add_u32_e32 v57, s99, v62
	ds_read_b64_tr_b4 v[50:51], v160 offset:128
	ds_read_b64_tr_b4 v[52:53], v160 offset:1152
	ds_read_b64_tr_b4 v[130:131], v54
	ds_read_b64_tr_b4 v[132:133], v55
	ds_read_b64_tr_b4 v[134:135], v56
	ds_read_b64_tr_b4 v[136:137], v57
	s_waitcnt lgkmcnt(12)
	v_dot8c_i32_i4_e32 v38, v122, v48
	v_dot8c_i32_i4_e32 v39, v122, v46
	v_dot8c_i32_i4_e32 v40, v124, v48
	v_dot8c_i32_i4_e32 v41, v124, v46
	v_dot8c_i32_i4_e32 v42, v126, v48
	v_dot8c_i32_i4_e32 v43, v126, v46
	v_dot8c_i32_i4_e32 v44, v128, v48
	v_dot8c_i32_i4_e32 v45, v128, v46
	v_dot8c_i32_i4_e32 v38, v123, v49
	v_dot8c_i32_i4_e32 v39, v123, v47
	v_dot8c_i32_i4_e32 v40, v125, v49
	v_dot8c_i32_i4_e32 v41, v125, v47
	v_dot8c_i32_i4_e32 v42, v127, v49
	v_dot8c_i32_i4_e32 v43, v127, v47
	v_dot8c_i32_i4_e32 v44, v129, v49
	v_dot8c_i32_i4_e32 v45, v129, v47
	v_and_b32_e32 v78, 0xffff, v32
	v_lshrrev_b32_e32 v79, 16, v32
	v_lshl_add_u32 v78, v78, 7, v150
	v_lshl_add_u32 v79, v79, 7, v151
	s_mov_b32 m0, s98
	s_add_i32 s43, s98, 0x400
	global_load_lds_dwordx4 v78, s[50:51]
	s_mov_b32 m0, s43
	s_nop 0
	global_load_lds_dwordx4 v79, s[50:51]
	s_waitcnt vmcnt(8)
	v_add_u32_e32 v54, s76, v59
	v_add_u32_e32 v55, s76, v60
	v_add_u32_e32 v56, s76, v61
	v_add_u32_e32 v57, s76, v62
	ds_read_b64_tr_b4 v[46:47], v160 offset:256
	ds_read_b64_tr_b4 v[48:49], v160 offset:1280
	ds_read_b64_tr_b4 v[122:123], v54
	ds_read_b64_tr_b4 v[124:125], v55
	ds_read_b64_tr_b4 v[126:127], v56
	ds_read_b64_tr_b4 v[128:129], v57
	s_waitcnt lgkmcnt(6)
	v_dot8c_i32_i4_e32 v38, v130, v52
	v_dot8c_i32_i4_e32 v39, v130, v50
	v_dot8c_i32_i4_e32 v40, v132, v52
	v_dot8c_i32_i4_e32 v41, v132, v50
	v_dot8c_i32_i4_e32 v42, v134, v52
	v_dot8c_i32_i4_e32 v43, v134, v50
	v_dot8c_i32_i4_e32 v44, v136, v52
	v_dot8c_i32_i4_e32 v45, v136, v50
	v_dot8c_i32_i4_e32 v38, v131, v53
	v_dot8c_i32_i4_e32 v39, v131, v51
	v_dot8c_i32_i4_e32 v40, v133, v53
	v_dot8c_i32_i4_e32 v41, v133, v51
	v_dot8c_i32_i4_e32 v42, v135, v53
	v_dot8c_i32_i4_e32 v43, v135, v51
	v_dot8c_i32_i4_e32 v44, v137, v53
	v_dot8c_i32_i4_e32 v45, v137, v51
	v_and_b32_e32 v78, 0xffff, v33
	v_lshrrev_b32_e32 v79, 16, v33
	v_lshl_add_u32 v78, v78, 7, v150
	v_lshl_add_u32 v79, v79, 7, v151
	s_mov_b32 m0, s99
	s_add_i32 s43, s99, 0x400
	global_load_lds_dwordx4 v78, s[50:51]
	s_mov_b32 m0, s43
	s_nop 0
	global_load_lds_dwordx4 v79, s[50:51]
	s_waitcnt vmcnt(8)
	v_add_u32_e32 v54, s77, v59
	v_add_u32_e32 v55, s77, v60
	v_add_u32_e32 v56, s77, v61
	v_add_u32_e32 v57, s77, v62
	ds_read_b64_tr_b4 v[50:51], v160 offset:384
	ds_read_b64_tr_b4 v[52:53], v160 offset:1408
	ds_read_b64_tr_b4 v[130:131], v54
	ds_read_b64_tr_b4 v[132:133], v55
	ds_read_b64_tr_b4 v[134:135], v56
	ds_read_b64_tr_b4 v[136:137], v57
	s_waitcnt lgkmcnt(6)
	v_dot8c_i32_i4_e32 v38, v122, v48
	v_dot8c_i32_i4_e32 v39, v122, v46
	v_dot8c_i32_i4_e32 v40, v124, v48
	v_dot8c_i32_i4_e32 v41, v124, v46
	v_dot8c_i32_i4_e32 v42, v126, v48
	v_dot8c_i32_i4_e32 v43, v126, v46
	v_dot8c_i32_i4_e32 v44, v128, v48
	v_dot8c_i32_i4_e32 v45, v128, v46
	v_dot8c_i32_i4_e32 v38, v123, v49
	v_dot8c_i32_i4_e32 v39, v123, v47
	v_dot8c_i32_i4_e32 v40, v125, v49
	v_dot8c_i32_i4_e32 v41, v125, v47
	v_dot8c_i32_i4_e32 v42, v127, v49
	v_dot8c_i32_i4_e32 v43, v127, v47
	v_dot8c_i32_i4_e32 v44, v129, v49
	v_dot8c_i32_i4_e32 v45, v129, v47
	s_waitcnt lgkmcnt(15)
	v_and_b32_e32 v78, 0xffff, v18
	v_lshrrev_b32_e32 v79, 16, v18
	v_lshl_add_u32 v78, v78, 7, v152
	v_lshl_add_u32 v79, v79, 7, v153
	s_mov_b32 m0, s76
	s_add_i32 s43, s76, 0x400
	global_load_lds_dwordx4 v78, s[50:51]
	s_mov_b32 m0, s43
	s_nop 0
	global_load_lds_dwordx4 v79, s[50:51]
	s_waitcnt vmcnt(8)
	v_add_u32_e32 v54, s78, v59
	v_add_u32_e32 v55, s78, v60
	v_add_u32_e32 v56, s78, v61
	v_add_u32_e32 v57, s78, v62
	ds_read_b64_tr_b4 v[46:47], v160 offset:512
	ds_read_b64_tr_b4 v[48:49], v160 offset:1536
	ds_read_b64_tr_b4 v[122:123], v54
	ds_read_b64_tr_b4 v[124:125], v55
	ds_read_b64_tr_b4 v[126:127], v56
	ds_read_b64_tr_b4 v[128:129], v57
	s_waitcnt lgkmcnt(6)
	v_dot8c_i32_i4_e32 v38, v130, v52
	v_dot8c_i32_i4_e32 v39, v130, v50
	v_dot8c_i32_i4_e32 v40, v132, v52
	v_dot8c_i32_i4_e32 v41, v132, v50
	v_dot8c_i32_i4_e32 v42, v134, v52
	v_dot8c_i32_i4_e32 v43, v134, v50
	v_dot8c_i32_i4_e32 v44, v136, v52
	v_dot8c_i32_i4_e32 v45, v136, v50
	v_dot8c_i32_i4_e32 v38, v131, v53
	v_dot8c_i32_i4_e32 v39, v131, v51
	v_dot8c_i32_i4_e32 v40, v133, v53
	v_dot8c_i32_i4_e32 v41, v133, v51
	v_dot8c_i32_i4_e32 v42, v135, v53
	v_dot8c_i32_i4_e32 v43, v135, v51
	v_dot8c_i32_i4_e32 v44, v137, v53
	v_dot8c_i32_i4_e32 v45, v137, v51
	v_and_b32_e32 v78, 0xffff, v19
	v_lshrrev_b32_e32 v79, 16, v19
	v_lshl_add_u32 v78, v78, 7, v152
	v_lshl_add_u32 v79, v79, 7, v153
	s_mov_b32 m0, s77
	s_add_i32 s43, s77, 0x400
	global_load_lds_dwordx4 v78, s[50:51]
	s_mov_b32 m0, s43
	s_nop 0
	global_load_lds_dwordx4 v79, s[50:51]
	s_waitcnt vmcnt(8)
	v_add_u32_e32 v54, s79, v59
	v_add_u32_e32 v55, s79, v60
	v_add_u32_e32 v56, s79, v61
	v_add_u32_e32 v57, s79, v62
	ds_read_b64_tr_b4 v[50:51], v160 offset:640
	ds_read_b64_tr_b4 v[52:53], v160 offset:1664
	ds_read_b64_tr_b4 v[130:131], v54
	ds_read_b64_tr_b4 v[132:133], v55
	ds_read_b64_tr_b4 v[134:135], v56
	ds_read_b64_tr_b4 v[136:137], v57
	s_waitcnt lgkmcnt(6)
	v_dot8c_i32_i4_e32 v38, v122, v48
	v_dot8c_i32_i4_e32 v39, v122, v46
	v_dot8c_i32_i4_e32 v40, v124, v48
	v_dot8c_i32_i4_e32 v41, v124, v46
	v_dot8c_i32_i4_e32 v42, v126, v48
	v_dot8c_i32_i4_e32 v43, v126, v46
	v_dot8c_i32_i4_e32 v44, v128, v48
	v_dot8c_i32_i4_e32 v45, v128, v46
	v_dot8c_i32_i4_e32 v38, v123, v49
	v_dot8c_i32_i4_e32 v39, v123, v47
	v_dot8c_i32_i4_e32 v40, v125, v49
	v_dot8c_i32_i4_e32 v41, v125, v47
	v_dot8c_i32_i4_e32 v42, v127, v49
	v_dot8c_i32_i4_e32 v43, v127, v47
	v_dot8c_i32_i4_e32 v44, v129, v49
	v_dot8c_i32_i4_e32 v45, v129, v47
	s_waitcnt lgkmcnt(15)
; #define LAS __attribute__((address_space(3)))
; __device__ __forceinline__ void peer_v_tokens(int j, const LAS unsigned short* EL, const LAS unsigned char* AL  , const LAS float* ASC  , const LAS int* SAL  , ...
;     ...
;         for (int m = 0; m < 2; ++m) {
;             const int idx = lane + 64 * m, tau = idx >> 4, sr = idx & 15, k = 16 * (sr & 7) + 2 * tau + (sr >> 3);
;             const int aq = (int)*(const LAS signed char*)(AL + tl * 128 + k); const int tq = aq + 8;
;             const unsigned lo = (((unsigned)tq & 15u) ^ 8u) * 0x11111111u, hi = ((unsigned)(tq >> 4) & 15u) * 0x11111111u;
;             typedef unsigned u2v __attribute__((ext_vector_type(2)));
;             u2v l2; l2.x = lo; l2.y = lo; u2v h2; h2.x = hi; h2.y = hi;
;             *(LAS u2v*)(ATL + 8 * idx) = l2; *(LAS u2v*)(ATL + 1024 + 8 * idx) = h2;
;         }
;         const float asc = ASC[tl]; const int sa = SAL[tl];
;     ...
;         for (int st = 0; st < 16; ++st) {
;             const int p = st >> 2, q = st & 3;
;             if (st < 14) VDMA(st + 2, (st + 2) % 3);
;             if (st < 14) asm volatile("s_waitcnt vmcnt(8)" ::: "memory");
;             else if (st == 14) asm volatile("s_waitcnt vmcnt(4)" ::: "memory");
;             else asm volatile("s_waitcnt vmcnt(0)" ::: "memory");
;             if (q == 0) {
; #pragma unroll
;                 for (int r = 0; r < 4; ++r) { accH[r] = 0; accL[r] = 0; } }
; #pragma unroll
;             for (int tp = 0; tp < 2; ++tp) {
;                 const v2i ao = TR4(ATL + (2 * q + tp) * 128 + 8 * s16), ah = TR4(ATL + 1024 + (2 * q + tp) * 128 + 8 * s16);
; #pragma unroll
;                 for (int r = 0; r < 4; ++r) {
;                     const v2i d = TR4(ldsb + BUF[st % 3] + 2048 * tp + roff[r]);
;                     accH[r] = __builtin_amdgcn_sdot8(d.x, ah.x, accH[r], false); accH[r] = __builtin_amdgcn_sdot8(d.y, ah.y, accH[r], false);
;                     accL[r] = __builtin_amdgcn_sdot8(d.x, ao.x, accL[r], false); accL[r] = __builtin_amdgcn_sdot8(d.y, ao.y, accL[r], false);
;                 }
;             }
;             asm volatile("s_waitcnt lgkmcnt(0)" ::: "memory");
;             if (q == 3) {
; #pragma unroll
;                 for (int r = 0; r < 4; ++r) STASH[256 * p + 16 * (grp + 4 * r) + pc] = f2bf(asc * (float)(2 * ((accH[r] << 4) + accL[r]) + sa));
;             }
;         }
	v_add_u32_e32 v143, 8, v139
	v_and_b32_e32 v142, 15, v143
	v_xor_b32_e32 v142, 8, v142
	v_bfe_u32 v144, v143, 4, 4
	v_mul_lo_u32 v142, v142, s92
	v_mul_lo_u32 v144, v144, s92
	v_mov_b32_e32 v143, v142
	v_mov_b32_e32 v145, v144
	ds_write2st64_b64 v159, v[142:143], v[144:145] offset1:2
	v_and_b32_e32 v78, 0xffff, v20
	v_lshrrev_b32_e32 v79, 16, v20
	v_lshl_add_u32 v78, v78, 7, v152
	v_lshl_add_u32 v79, v79, 7, v153
	s_mov_b32 m0, s78
	s_add_i32 s43, s78, 0x400
	global_load_lds_dwordx4 v78, s[50:51]
	s_mov_b32 m0, s43
	s_nop 0
	global_load_lds_dwordx4 v79, s[50:51]
	s_waitcnt vmcnt(8)
	v_add_u32_e32 v54, s98, v59
	v_add_u32_e32 v55, s98, v60
	v_add_u32_e32 v56, s98, v61
	v_add_u32_e32 v57, s98, v62
	ds_read_b64_tr_b4 v[46:47], v160 offset:768
	ds_read_b64_tr_b4 v[48:49], v160 offset:1792
	ds_read_b64_tr_b4 v[122:123], v54
	ds_read_b64_tr_b4 v[124:125], v55
	ds_read_b64_tr_b4 v[126:127], v56
	ds_read_b64_tr_b4 v[128:129], v57
	s_waitcnt lgkmcnt(7)
	v_dot8c_i32_i4_e32 v38, v130, v52
	v_dot8c_i32_i4_e32 v39, v130, v50
	v_dot8c_i32_i4_e32 v40, v132, v52
	v_dot8c_i32_i4_e32 v41, v132, v50
	v_dot8c_i32_i4_e32 v42, v134, v52
	v_dot8c_i32_i4_e32 v43, v134, v50
	v_dot8c_i32_i4_e32 v44, v136, v52
	v_dot8c_i32_i4_e32 v45, v136, v50
	v_dot8c_i32_i4_e32 v38, v131, v53
	v_dot8c_i32_i4_e32 v39, v131, v51
	v_dot8c_i32_i4_e32 v40, v133, v53
	v_dot8c_i32_i4_e32 v41, v133, v51
	v_dot8c_i32_i4_e32 v42, v135, v53
	v_dot8c_i32_i4_e32 v43, v135, v51
	v_dot8c_i32_i4_e32 v44, v137, v53
	v_dot8c_i32_i4_e32 v45, v137, v51
	v_and_b32_e32 v78, 0xffff, v21
	v_lshrrev_b32_e32 v79, 16, v21
	v_lshl_add_u32 v78, v78, 7, v152
	v_lshl_add_u32 v79, v79, 7, v153
	s_mov_b32 m0, s79
	s_add_i32 s43, s79, 0x400
	global_load_lds_dwordx4 v78, s[50:51]
	s_mov_b32 m0, s43
	s_nop 0
	global_load_lds_dwordx4 v79, s[50:51]
	s_waitcnt vmcnt(8)
	v_add_u32_e32 v54, s99, v59
	v_add_u32_e32 v55, s99, v60
	v_add_u32_e32 v56, s99, v61
	v_add_u32_e32 v57, s99, v62
	ds_read_b64_tr_b4 v[50:51], v160 offset:896
	ds_read_b64_tr_b4 v[52:53], v160 offset:1920
	ds_read_b64_tr_b4 v[130:131], v54
	ds_read_b64_tr_b4 v[132:133], v55
	ds_read_b64_tr_b4 v[134:135], v56
	ds_read_b64_tr_b4 v[136:137], v57
	s_waitcnt lgkmcnt(6)
	v_dot8c_i32_i4_e32 v38, v122, v48
	v_dot8c_i32_i4_e32 v39, v122, v46
	v_dot8c_i32_i4_e32 v40, v124, v48
	v_dot8c_i32_i4_e32 v41, v124, v46
	v_dot8c_i32_i4_e32 v42, v126, v48
	v_dot8c_i32_i4_e32 v43, v126, v46
	v_dot8c_i32_i4_e32 v44, v128, v48
	v_dot8c_i32_i4_e32 v45, v128, v46
	v_dot8c_i32_i4_e32 v38, v123, v49
	v_dot8c_i32_i4_e32 v39, v123, v47
	v_dot8c_i32_i4_e32 v40, v125, v49
	v_dot8c_i32_i4_e32 v41, v125, v47
	v_dot8c_i32_i4_e32 v42, v127, v49
	v_dot8c_i32_i4_e32 v43, v127, v47
	v_dot8c_i32_i4_e32 v44, v129, v49
	v_dot8c_i32_i4_e32 v45, v129, v47
	v_and_b32_e32 v78, 0xffff, v22
	v_lshrrev_b32_e32 v79, 16, v22
	v_lshl_add_u32 v78, v78, 7, v152
	v_lshl_add_u32 v79, v79, 7, v153
	s_mov_b32 m0, s98
	s_add_i32 s43, s98, 0x400
	global_load_lds_dwordx4 v78, s[50:51]
	s_mov_b32 m0, s43
	s_nop 0
	global_load_lds_dwordx4 v79, s[50:51]
	s_waitcnt vmcnt(8)
	v_add_u32_e32 v54, s76, v59
	v_add_u32_e32 v55, s76, v60
	v_add_u32_e32 v56, s76, v61
	v_add_u32_e32 v57, s76, v62
	ds_read_b64_tr_b4 v[46:47], v160
	ds_read_b64_tr_b4 v[48:49], v160 offset:1024
	ds_read_b64_tr_b4 v[122:123], v54
	ds_read_b64_tr_b4 v[124:125], v55
	ds_read_b64_tr_b4 v[126:127], v56
	ds_read_b64_tr_b4 v[128:129], v57
	s_waitcnt lgkmcnt(6)
	v_dot8c_i32_i4_e32 v38, v130, v52
	v_dot8c_i32_i4_e32 v39, v130, v50
	v_dot8c_i32_i4_e32 v40, v132, v52
	v_dot8c_i32_i4_e32 v41, v132, v50
	v_dot8c_i32_i4_e32 v42, v134, v52
	v_dot8c_i32_i4_e32 v43, v134, v50
	v_dot8c_i32_i4_e32 v44, v136, v52
	v_dot8c_i32_i4_e32 v45, v136, v50
	v_dot8c_i32_i4_e32 v38, v131, v53
	v_dot8c_i32_i4_e32 v39, v131, v51
	v_dot8c_i32_i4_e32 v40, v133, v53
	v_dot8c_i32_i4_e32 v41, v133, v51
	v_dot8c_i32_i4_e32 v42, v135, v53
	v_dot8c_i32_i4_e32 v43, v135, v51
	v_dot8c_i32_i4_e32 v44, v137, v53
	v_dot8c_i32_i4_e32 v45, v137, v51
	s_nop 3
	s_waitcnt lgkmcnt(15)
	v_lshlrev_b32_e32 v38, 5, v38
	v_lshlrev_b32_e32 v39, 1, v39
	v_add3_u32 v38, v39, v229, v38
	v_cvt_f32_i32_e32 v38, v38
	v_mul_f32_e32 v38, v228, v38
	v_lshlrev_b32_e32 v40, 5, v40
	v_lshlrev_b32_e32 v41, 1, v41
	v_add3_u32 v40, v41, v229, v40
	v_cvt_f32_i32_e32 v40, v40
	v_mul_f32_e32 v40, v228, v40
	v_lshlrev_b32_e32 v42, 5, v42
	v_lshlrev_b32_e32 v43, 1, v43
	v_add3_u32 v42, v43, v229, v42
	v_cvt_f32_i32_e32 v42, v42
	v_mul_f32_e32 v42, v228, v42
	v_lshlrev_b32_e32 v44, 5, v44
	v_lshlrev_b32_e32 v45, 1, v45
	v_add3_u32 v44, v45, v229, v44
	v_cvt_f32_i32_e32 v44, v44
	v_mul_f32_e32 v44, v228, v44
	v_cvt_pk_bf16_f32 v190, v38, v40
	v_cvt_pk_bf16_f32 v191, v42, v44
	v_add_u32_e32 v147, 8, v140
	v_and_b32_e32 v146, 15, v147
	v_xor_b32_e32 v146, 8, v146
	v_bfe_u32 v148, v147, 4, 4
	v_mul_lo_u32 v146, v146, s92
	v_mul_lo_u32 v148, v148, s92
	v_mov_b32_e32 v147, v146
	v_mov_b32_e32 v149, v148
	ds_write2st64_b64 v77, v[146:147], v[148:149] offset1:2
	v_add_u32_e32 v138, 0x400, v74
	ds_read_u8 v139, v138
	v_add_u32_e32 v141, 0x400, v73
	ds_read_u8 v140, v141
	s_mov_b32 s43, s67
	v_mov_b32_e32 v138, s43
	ds_read2st64_b32 v[228:229], v138 offset1:1
	ds_read_b128 v[26:29], v227 offset:2048
	ds_read_b128 v[30:33], v227 offset:2064
	v_mov_b32_e32 v38, 0
	v_mov_b32_e32 v39, 0
	v_mov_b32_e32 v40, 0
	v_mov_b32_e32 v41, 0
	v_mov_b32_e32 v42, 0
	v_mov_b32_e32 v43, 0
	v_mov_b32_e32 v44, 0
	v_mov_b32_e32 v45, 0
	v_and_b32_e32 v78, 0xffff, v23
	v_lshrrev_b32_e32 v79, 16, v23
	v_lshl_add_u32 v78, v78, 7, v152
	v_lshl_add_u32 v79, v79, 7, v153
	s_mov_b32 m0, s99
	s_add_i32 s43, s99, 0x400
	global_load_lds_dwordx4 v78, s[50:51]
	s_mov_b32 m0, s43
	s_nop 0
	global_load_lds_dwordx4 v79, s[50:51]
	s_waitcnt vmcnt(8)
; __device__ __forceinline__ bf16 f2bf(float f) { return (bf16)f2bfu(f); }
; #define TR4(p_) __builtin_amdgcn_ds_read_tr4_b64_v2i32((LAS v2i*)(p_))
; #define VDMA(st_, k_) do { _Pragma("unroll") for (int i_ = 0; i_ < 4; ++i_) { \
;         const unsigned off_ = (unsigned)((st_) >> 2) * (16384u * 128u) + (PE_ID(E, 4 * ((st_) & 3) + i_) << 7) + ((i_ & 1) ? cx1 : cx0); \
;         __builtin_amdgcn_global_load_lds((const unsigned*)(V4 + off_), (LAS unsigned*)(ldsb + BUF[k_] + 1024 * i_), 16, 0, 0); } } while (0)
; __device__ __forceinline__ void peer_v_tokens(int j, const LAS unsigned short* EL, const LAS unsigned char* AL  , const LAS float* ASC  , const LAS int* SAL  , ...
;     ...
;         for (int st = 0; st < 16; ++st) {
;             const int p = st >> 2, q = st & 3;
;             if (st < 14) VDMA(st + 2, (st + 2) % 3);
;             if (st < 14) asm volatile("s_waitcnt vmcnt(8)" ::: "memory");
;             else if (st == 14) asm volatile("s_waitcnt vmcnt(4)" ::: "memory");
;             else asm volatile("s_waitcnt vmcnt(0)" ::: "memory");
;             if (q == 0) {
; #pragma unroll
;                 for (int r = 0; r < 4; ++r) { accH[r] = 0; accL[r] = 0; } }
; #pragma unroll
;             for (int tp = 0; tp < 2; ++tp) {
;                 const v2i ao = TR4(ATL + (2 * q + tp) * 128 + 8 * s16), ah = TR4(ATL + 1024 + (2 * q + tp) * 128 + 8 * s16);
; #pragma unroll
;                 for (int r = 0; r < 4; ++r) {
;                     const v2i d = TR4(ldsb + BUF[st % 3] + 2048 * tp + roff[r]);
;                     accH[r] = __builtin_amdgcn_sdot8(d.x, ah.x, accH[r], false); accH[r] = __builtin_amdgcn_sdot8(d.y, ah.y, accH[r], false);
;                     accL[r] = __builtin_amdgcn_sdot8(d.x, ao.x, accL[r], false); accL[r] = __builtin_amdgcn_sdot8(d.y, ao.y, accL[r], false);
;                 }
;             }
;             asm volatile("s_waitcnt lgkmcnt(0)" ::: "memory");
;             if (q == 3) {
; #pragma unroll
;                 for (int r = 0; r < 4; ++r) STASH[256 * p + 16 * (grp + 4 * r) + pc] = f2bf(asc * (float)(2 * ((accH[r] << 4) + accL[r]) + sa));
;             }
;         }
	v_add_u32_e32 v54, s77, v59
	v_add_u32_e32 v55, s77, v60
	v_add_u32_e32 v56, s77, v61
	v_add_u32_e32 v57, s77, v62
	ds_read_b64_tr_b4 v[50:51], v160 offset:128
	ds_read_b64_tr_b4 v[52:53], v160 offset:1152
	ds_read_b64_tr_b4 v[130:131], v54
	ds_read_b64_tr_b4 v[132:133], v55
	ds_read_b64_tr_b4 v[134:135], v56
	ds_read_b64_tr_b4 v[136:137], v57
	s_waitcnt lgkmcnt(12)
	v_dot8c_i32_i4_e32 v38, v122, v48
	v_dot8c_i32_i4_e32 v39, v122, v46
	v_dot8c_i32_i4_e32 v40, v124, v48
	v_dot8c_i32_i4_e32 v41, v124, v46
	v_dot8c_i32_i4_e32 v42, v126, v48
	v_dot8c_i32_i4_e32 v43, v126, v46
	v_dot8c_i32_i4_e32 v44, v128, v48
	v_dot8c_i32_i4_e32 v45, v128, v46
	v_dot8c_i32_i4_e32 v38, v123, v49
	v_dot8c_i32_i4_e32 v39, v123, v47
	v_dot8c_i32_i4_e32 v40, v125, v49
	v_dot8c_i32_i4_e32 v41, v125, v47
	v_dot8c_i32_i4_e32 v42, v127, v49
	v_dot8c_i32_i4_e32 v43, v127, v47
	v_dot8c_i32_i4_e32 v44, v129, v49
	v_dot8c_i32_i4_e32 v45, v129, v47
	v_and_b32_e32 v78, 0xffff, v24
	v_lshrrev_b32_e32 v79, 16, v24
	v_lshl_add_u32 v78, v78, 7, v152
	v_lshl_add_u32 v79, v79, 7, v153
	s_mov_b32 m0, s76
	s_add_i32 s43, s76, 0x400
	global_load_lds_dwordx4 v78, s[50:51]
	s_mov_b32 m0, s43
	s_nop 0
	global_load_lds_dwordx4 v79, s[50:51]
	s_waitcnt vmcnt(8)
	v_add_u32_e32 v54, s78, v59
	v_add_u32_e32 v55, s78, v60
	v_add_u32_e32 v56, s78, v61
	v_add_u32_e32 v57, s78, v62
	ds_read_b64_tr_b4 v[46:47], v160 offset:256
	ds_read_b64_tr_b4 v[48:49], v160 offset:1280
	ds_read_b64_tr_b4 v[122:123], v54
	ds_read_b64_tr_b4 v[124:125], v55
	ds_read_b64_tr_b4 v[126:127], v56
	ds_read_b64_tr_b4 v[128:129], v57
	s_waitcnt lgkmcnt(6)
	v_dot8c_i32_i4_e32 v38, v130, v52
	v_dot8c_i32_i4_e32 v39, v130, v50
	v_dot8c_i32_i4_e32 v40, v132, v52
	v_dot8c_i32_i4_e32 v41, v132, v50
	v_dot8c_i32_i4_e32 v42, v134, v52
	v_dot8c_i32_i4_e32 v43, v134, v50
	v_dot8c_i32_i4_e32 v44, v136, v52
	v_dot8c_i32_i4_e32 v45, v136, v50
	v_dot8c_i32_i4_e32 v38, v131, v53
	v_dot8c_i32_i4_e32 v39, v131, v51
	v_dot8c_i32_i4_e32 v40, v133, v53
	v_dot8c_i32_i4_e32 v41, v133, v51
	v_dot8c_i32_i4_e32 v42, v135, v53
	v_dot8c_i32_i4_e32 v43, v135, v51
	v_dot8c_i32_i4_e32 v44, v137, v53
	v_dot8c_i32_i4_e32 v45, v137, v51
	v_and_b32_e32 v78, 0xffff, v25
	v_lshrrev_b32_e32 v79, 16, v25
	v_lshl_add_u32 v78, v78, 7, v152
	v_lshl_add_u32 v79, v79, 7, v153
	s_mov_b32 m0, s77
	s_add_i32 s43, s77, 0x400
	global_load_lds_dwordx4 v78, s[50:51]
	s_mov_b32 m0, s43
	s_nop 0
	global_load_lds_dwordx4 v79, s[50:51]
	s_waitcnt vmcnt(8)
	v_add_u32_e32 v54, s79, v59
	v_add_u32_e32 v55, s79, v60
	v_add_u32_e32 v56, s79, v61
	v_add_u32_e32 v57, s79, v62
	ds_read_b64_tr_b4 v[50:51], v160 offset:384
	ds_read_b64_tr_b4 v[52:53], v160 offset:1408
	ds_read_b64_tr_b4 v[130:131], v54
	ds_read_b64_tr_b4 v[132:133], v55
	ds_read_b64_tr_b4 v[134:135], v56
	ds_read_b64_tr_b4 v[136:137], v57
	s_waitcnt lgkmcnt(6)
	v_dot8c_i32_i4_e32 v38, v122, v48
	v_dot8c_i32_i4_e32 v39, v122, v46
	v_dot8c_i32_i4_e32 v40, v124, v48
	v_dot8c_i32_i4_e32 v41, v124, v46
	v_dot8c_i32_i4_e32 v42, v126, v48
	v_dot8c_i32_i4_e32 v43, v126, v46
	v_dot8c_i32_i4_e32 v44, v128, v48
	v_dot8c_i32_i4_e32 v45, v128, v46
	v_dot8c_i32_i4_e32 v38, v123, v49
	v_dot8c_i32_i4_e32 v39, v123, v47
	v_dot8c_i32_i4_e32 v40, v125, v49
	v_dot8c_i32_i4_e32 v41, v125, v47
	v_dot8c_i32_i4_e32 v42, v127, v49
	v_dot8c_i32_i4_e32 v43, v127, v47
	v_dot8c_i32_i4_e32 v44, v129, v49
	v_dot8c_i32_i4_e32 v45, v129, v47
	s_waitcnt lgkmcnt(15)
	v_and_b32_e32 v78, 0xffff, v26
	v_lshrrev_b32_e32 v79, 16, v26
	v_lshl_add_u32 v78, v78, 7, v152
	v_lshl_add_u32 v79, v79, 7, v153
	s_mov_b32 m0, s78
	s_add_i32 s43, s78, 0x400
	global_load_lds_dwordx4 v78, s[50:51]
	s_mov_b32 m0, s43
	s_nop 0
	global_load_lds_dwordx4 v79, s[50:51]
	s_waitcnt vmcnt(8)
	v_add_u32_e32 v54, s98, v59
	v_add_u32_e32 v55, s98, v60
	v_add_u32_e32 v56, s98, v61
	v_add_u32_e32 v57, s98, v62
	ds_read_b64_tr_b4 v[46:47], v160 offset:512
	ds_read_b64_tr_b4 v[48:49], v160 offset:1536
	ds_read_b64_tr_b4 v[122:123], v54
	ds_read_b64_tr_b4 v[124:125], v55
	ds_read_b64_tr_b4 v[126:127], v56
	ds_read_b64_tr_b4 v[128:129], v57
	s_waitcnt lgkmcnt(6)
	v_dot8c_i32_i4_e32 v38, v130, v52
	v_dot8c_i32_i4_e32 v39, v130, v50
	v_dot8c_i32_i4_e32 v40, v132, v52
	v_dot8c_i32_i4_e32 v41, v132, v50
	v_dot8c_i32_i4_e32 v42, v134, v52
	v_dot8c_i32_i4_e32 v43, v134, v50
	v_dot8c_i32_i4_e32 v44, v136, v52
	v_dot8c_i32_i4_e32 v45, v136, v50
	v_dot8c_i32_i4_e32 v38, v131, v53
	v_dot8c_i32_i4_e32 v39, v131, v51
	v_dot8c_i32_i4_e32 v40, v133, v53
	v_dot8c_i32_i4_e32 v41, v133, v51
	v_dot8c_i32_i4_e32 v42, v135, v53
	v_dot8c_i32_i4_e32 v43, v135, v51
	v_dot8c_i32_i4_e32 v44, v137, v53
	v_dot8c_i32_i4_e32 v45, v137, v51
	v_and_b32_e32 v78, 0xffff, v27
	v_lshrrev_b32_e32 v79, 16, v27
	v_lshl_add_u32 v78, v78, 7, v152
	v_lshl_add_u32 v79, v79, 7, v153
	s_mov_b32 m0, s79
	s_add_i32 s43, s79, 0x400
	global_load_lds_dwordx4 v78, s[50:51]
	s_mov_b32 m0, s43
	s_nop 0
	global_load_lds_dwordx4 v79, s[50:51]
	s_waitcnt vmcnt(8)
	v_add_u32_e32 v54, s99, v59
	v_add_u32_e32 v55, s99, v60
	v_add_u32_e32 v56, s99, v61
	v_add_u32_e32 v57, s99, v62
	ds_read_b64_tr_b4 v[50:51], v160 offset:640
	ds_read_b64_tr_b4 v[52:53], v160 offset:1664
	ds_read_b64_tr_b4 v[130:131], v54
	ds_read_b64_tr_b4 v[132:133], v55
	ds_read_b64_tr_b4 v[134:135], v56
	ds_read_b64_tr_b4 v[136:137], v57
	s_waitcnt lgkmcnt(6)
	v_dot8c_i32_i4_e32 v38, v122, v48
	v_dot8c_i32_i4_e32 v39, v122, v46
	v_dot8c_i32_i4_e32 v40, v124, v48
	v_dot8c_i32_i4_e32 v41, v124, v46
	v_dot8c_i32_i4_e32 v42, v126, v48
	v_dot8c_i32_i4_e32 v43, v126, v46
	v_dot8c_i32_i4_e32 v44, v128, v48
	v_dot8c_i32_i4_e32 v45, v128, v46
	v_dot8c_i32_i4_e32 v38, v123, v49
	v_dot8c_i32_i4_e32 v39, v123, v47
	v_dot8c_i32_i4_e32 v40, v125, v49
	v_dot8c_i32_i4_e32 v41, v125, v47
	v_dot8c_i32_i4_e32 v42, v127, v49
	v_dot8c_i32_i4_e32 v43, v127, v47
	v_dot8c_i32_i4_e32 v44, v129, v49
	v_dot8c_i32_i4_e32 v45, v129, v47
	s_waitcnt lgkmcnt(15)
; __device__ __forceinline__ bf16 f2bf(float f) { return (bf16)f2bfu(f); }
; #define TR4(p_) __builtin_amdgcn_ds_read_tr4_b64_v2i32((LAS v2i*)(p_))
; __device__ __forceinline__ void peer_v_tokens(int j, const LAS unsigned short* EL, const LAS unsigned char* AL  , const LAS float* ASC  , const LAS int* SAL  , ...
;     ...
;         uint2 hv[4]; float4 gv[4];
;         { unsigned ho = (unsigned)t * (D / 4) + (unsigned)lane; asm volatile("" : "+v"(ho)); const uint2* hp = (const uint2*)HB + ho; const float4* gp = (const float4*)fng + lane;
; #pragma unroll
;           for (int jq = 0; jq < 4; ++jq) { hv[jq] = hp[64 * jq]; gv[jq] = gp[64 * jq]; } }
;     ...
;         for (int st = 0; st < 16; ++st) {
;             const int p = st >> 2, q = st & 3;
;             if (st < 14) VDMA(st + 2, (st + 2) % 3);
;             if (st < 14) asm volatile("s_waitcnt vmcnt(8)" ::: "memory");
;             else if (st == 14) asm volatile("s_waitcnt vmcnt(4)" ::: "memory");
;             else asm volatile("s_waitcnt vmcnt(0)" ::: "memory");
;             if (q == 0) {
; #pragma unroll
;                 for (int r = 0; r < 4; ++r) { accH[r] = 0; accL[r] = 0; } }
; #pragma unroll
;             for (int tp = 0; tp < 2; ++tp) {
;                 const v2i ao = TR4(ATL + (2 * q + tp) * 128 + 8 * s16), ah = TR4(ATL + 1024 + (2 * q + tp) * 128 + 8 * s16);
; #pragma unroll
;                 for (int r = 0; r < 4; ++r) {
;                     const v2i d = TR4(ldsb + BUF[st % 3] + 2048 * tp + roff[r]);
;                     accH[r] = __builtin_amdgcn_sdot8(d.x, ah.x, accH[r], false); accH[r] = __builtin_amdgcn_sdot8(d.y, ah.y, accH[r], false);
;                     accL[r] = __builtin_amdgcn_sdot8(d.x, ao.x, accL[r], false); accL[r] = __builtin_amdgcn_sdot8(d.y, ao.y, accL[r], false);
;                 }
;             }
;             asm volatile("s_waitcnt lgkmcnt(0)" ::: "memory");
;             if (q == 3) {
; #pragma unroll
;                 for (int r = 0; r < 4; ++r) STASH[256 * p + 16 * (grp + 4 * r) + pc] = f2bf(asc * (float)(2 * ((accH[r] << 4) + accL[r]) + sa));
;             }
;         }
	v_add_u32_e32 v143, 8, v139
	v_and_b32_e32 v142, 15, v143
	v_xor_b32_e32 v142, 8, v142
	v_bfe_u32 v144, v143, 4, 4
	v_mul_lo_u32 v142, v142, s92
	v_mul_lo_u32 v144, v144, s92
	v_mov_b32_e32 v143, v142
	v_mov_b32_e32 v145, v144
	ds_write2st64_b64 v159, v[142:143], v[144:145] offset1:2
	v_and_b32_e32 v78, 0xffff, v28
	v_lshrrev_b32_e32 v79, 16, v28
	v_lshl_add_u32 v78, v78, 7, v152
	v_lshl_add_u32 v79, v79, 7, v153
	s_mov_b32 m0, s98
	s_add_i32 s43, s98, 0x400
	global_load_lds_dwordx4 v78, s[50:51]
	s_mov_b32 m0, s43
	s_nop 0
	global_load_lds_dwordx4 v79, s[50:51]
	s_waitcnt vmcnt(8)
	v_add_u32_e32 v54, s76, v59
	v_add_u32_e32 v55, s76, v60
	v_add_u32_e32 v56, s76, v61
	v_add_u32_e32 v57, s76, v62
	ds_read_b64_tr_b4 v[46:47], v160 offset:768
	ds_read_b64_tr_b4 v[48:49], v160 offset:1792
	ds_read_b64_tr_b4 v[122:123], v54
	ds_read_b64_tr_b4 v[124:125], v55
	ds_read_b64_tr_b4 v[126:127], v56
	ds_read_b64_tr_b4 v[128:129], v57
	s_waitcnt lgkmcnt(7)
	v_dot8c_i32_i4_e32 v38, v130, v52
	v_dot8c_i32_i4_e32 v39, v130, v50
	v_dot8c_i32_i4_e32 v40, v132, v52
	v_dot8c_i32_i4_e32 v41, v132, v50
	v_dot8c_i32_i4_e32 v42, v134, v52
	v_dot8c_i32_i4_e32 v43, v134, v50
	v_dot8c_i32_i4_e32 v44, v136, v52
	v_dot8c_i32_i4_e32 v45, v136, v50
	v_dot8c_i32_i4_e32 v38, v131, v53
	v_dot8c_i32_i4_e32 v39, v131, v51
	v_dot8c_i32_i4_e32 v40, v133, v53
	v_dot8c_i32_i4_e32 v41, v133, v51
	v_dot8c_i32_i4_e32 v42, v135, v53
	v_dot8c_i32_i4_e32 v43, v135, v51
	v_dot8c_i32_i4_e32 v44, v137, v53
	v_dot8c_i32_i4_e32 v45, v137, v51
	v_and_b32_e32 v78, 0xffff, v29
	v_lshrrev_b32_e32 v79, 16, v29
	v_lshl_add_u32 v78, v78, 7, v152
	v_lshl_add_u32 v79, v79, 7, v153
	s_mov_b32 m0, s99
	s_add_i32 s43, s99, 0x400
	global_load_lds_dwordx4 v78, s[50:51]
	s_mov_b32 m0, s43
	s_nop 0
	global_load_lds_dwordx4 v79, s[50:51]
	s_waitcnt vmcnt(8)
	v_add_u32_e32 v54, s77, v59
	v_add_u32_e32 v55, s77, v60
	v_add_u32_e32 v56, s77, v61
	v_add_u32_e32 v57, s77, v62
	ds_read_b64_tr_b4 v[50:51], v160 offset:896
	ds_read_b64_tr_b4 v[52:53], v160 offset:1920
	ds_read_b64_tr_b4 v[130:131], v54
	ds_read_b64_tr_b4 v[132:133], v55
	ds_read_b64_tr_b4 v[134:135], v56
	ds_read_b64_tr_b4 v[136:137], v57
	s_waitcnt lgkmcnt(6)
	v_dot8c_i32_i4_e32 v38, v122, v48
	v_dot8c_i32_i4_e32 v39, v122, v46
	v_dot8c_i32_i4_e32 v40, v124, v48
	v_dot8c_i32_i4_e32 v41, v124, v46
	v_dot8c_i32_i4_e32 v42, v126, v48
	v_dot8c_i32_i4_e32 v43, v126, v46
	v_dot8c_i32_i4_e32 v44, v128, v48
	v_dot8c_i32_i4_e32 v45, v128, v46
	v_dot8c_i32_i4_e32 v38, v123, v49
	v_dot8c_i32_i4_e32 v39, v123, v47
	v_dot8c_i32_i4_e32 v40, v125, v49
	v_dot8c_i32_i4_e32 v41, v125, v47
	v_dot8c_i32_i4_e32 v42, v127, v49
	v_dot8c_i32_i4_e32 v43, v127, v47
	v_dot8c_i32_i4_e32 v44, v129, v49
	v_dot8c_i32_i4_e32 v45, v129, v47
	v_and_b32_e32 v78, 0xffff, v30
	v_lshrrev_b32_e32 v79, 16, v30
	v_lshl_add_u32 v78, v78, 7, v152
	v_lshl_add_u32 v79, v79, 7, v153
	s_mov_b32 m0, s76
	s_add_i32 s43, s76, 0x400
	global_load_lds_dwordx4 v78, s[50:51]
	s_mov_b32 m0, s43
	s_nop 0
	global_load_lds_dwordx4 v79, s[50:51]
	s_waitcnt vmcnt(8)
	v_add_u32_e32 v54, s78, v59
	v_add_u32_e32 v55, s78, v60
	v_add_u32_e32 v56, s78, v61
	v_add_u32_e32 v57, s78, v62
	ds_read_b64_tr_b4 v[46:47], v160
	ds_read_b64_tr_b4 v[48:49], v160 offset:1024
	ds_read_b64_tr_b4 v[122:123], v54
	ds_read_b64_tr_b4 v[124:125], v55
	ds_read_b64_tr_b4 v[126:127], v56
	ds_read_b64_tr_b4 v[128:129], v57
	s_waitcnt lgkmcnt(6)
	v_dot8c_i32_i4_e32 v38, v130, v52
	v_dot8c_i32_i4_e32 v39, v130, v50
	v_dot8c_i32_i4_e32 v40, v132, v52
	v_dot8c_i32_i4_e32 v41, v132, v50
	v_dot8c_i32_i4_e32 v42, v134, v52
	v_dot8c_i32_i4_e32 v43, v134, v50
	v_dot8c_i32_i4_e32 v44, v136, v52
	v_dot8c_i32_i4_e32 v45, v136, v50
	v_dot8c_i32_i4_e32 v38, v131, v53
	v_dot8c_i32_i4_e32 v39, v131, v51
	v_dot8c_i32_i4_e32 v40, v133, v53
	v_dot8c_i32_i4_e32 v41, v133, v51
	v_dot8c_i32_i4_e32 v42, v135, v53
	v_dot8c_i32_i4_e32 v43, v135, v51
	v_dot8c_i32_i4_e32 v44, v137, v53
	v_dot8c_i32_i4_e32 v45, v137, v51
	s_nop 3
	s_waitcnt lgkmcnt(15)
	v_lshlrev_b32_e32 v38, 5, v38
	v_lshlrev_b32_e32 v39, 1, v39
	v_add3_u32 v38, v39, v229, v38
	v_cvt_f32_i32_e32 v38, v38
	v_mul_f32_e32 v38, v228, v38
	v_lshlrev_b32_e32 v40, 5, v40
	v_lshlrev_b32_e32 v41, 1, v41
	v_add3_u32 v40, v41, v229, v40
	v_cvt_f32_i32_e32 v40, v40
	v_mul_f32_e32 v40, v228, v40
	v_lshlrev_b32_e32 v42, 5, v42
	v_lshlrev_b32_e32 v43, 1, v43
	v_add3_u32 v42, v43, v229, v42
	v_cvt_f32_i32_e32 v42, v42
	v_mul_f32_e32 v42, v228, v42
	v_lshlrev_b32_e32 v44, 5, v44
	v_lshlrev_b32_e32 v45, 1, v45
	v_add3_u32 v44, v45, v229, v44
	v_cvt_f32_i32_e32 v44, v44
	v_mul_f32_e32 v44, v228, v44
	v_cvt_pk_bf16_f32 v168, v38, v40
	v_cvt_pk_bf16_f32 v169, v42, v44
	s_add_i32 s43, s40, 0
	s_lshl_b32 s43, s43, 11
	v_add_u32_e32 v138, s43, v66
	global_load_dwordx2 v[194:195], v138, s[70:71]
	global_load_dwordx2 v[196:197], v138, s[70:71] offset:512
	global_load_dwordx2 v[198:199], v138, s[70:71] offset:1024
	global_load_dwordx2 v[200:201], v138, s[70:71] offset:1536
	v_add_u32_e32 v147, 8, v140
	v_and_b32_e32 v146, 15, v147
	v_xor_b32_e32 v146, 8, v146
	v_bfe_u32 v148, v147, 4, 4
	v_mul_lo_u32 v146, v146, s92
	v_mul_lo_u32 v148, v148, s92
	v_mov_b32_e32 v147, v146
	v_mov_b32_e32 v149, v148
	ds_write2st64_b64 v77, v[146:147], v[148:149] offset1:2
	v_add_u32_e32 v138, 0x800, v74
	ds_read_u8 v139, v138
	v_add_u32_e32 v141, 0x800, v73
	ds_read_u8 v140, v141
	s_add_i32 s43, s67, 32
	v_mov_b32_e32 v138, s43
	ds_read2st64_b32 v[228:229], v138 offset1:1
	ds_read_b128 v[18:21], v227 offset:4096
	ds_read_b128 v[22:25], v227 offset:4112
	v_mov_b32_e32 v38, 0
	v_mov_b32_e32 v39, 0
	v_mov_b32_e32 v40, 0
	v_mov_b32_e32 v41, 0
	v_mov_b32_e32 v42, 0
	v_mov_b32_e32 v43, 0
	v_mov_b32_e32 v44, 0
	v_mov_b32_e32 v45, 0
	v_and_b32_e32 v78, 0xffff, v31
	v_lshrrev_b32_e32 v79, 16, v31
	v_lshl_add_u32 v78, v78, 7, v152
	v_lshl_add_u32 v79, v79, 7, v153
	s_mov_b32 m0, s77
	s_add_i32 s43, s77, 0x400
	global_load_lds_dwordx4 v78, s[50:51]
	s_mov_b32 m0, s43
	s_nop 0
	global_load_lds_dwordx4 v79, s[50:51]
	s_waitcnt vmcnt(12)
; __device__ __forceinline__ bf16 f2bf(float f) { return (bf16)f2bfu(f); }
; #define TR4(p_) __builtin_amdgcn_ds_read_tr4_b64_v2i32((LAS v2i*)(p_))
; #define VDMA(st_, k_) do { _Pragma("unroll") for (int i_ = 0; i_ < 4; ++i_) { \
;         const unsigned off_ = (unsigned)((st_) >> 2) * (16384u * 128u) + (PE_ID(E, 4 * ((st_) & 3) + i_) << 7) + ((i_ & 1) ? cx1 : cx0); \
;         __builtin_amdgcn_global_load_lds((const unsigned*)(V4 + off_), (LAS unsigned*)(ldsb + BUF[k_] + 1024 * i_), 16, 0, 0); } } while (0)
; __device__ __forceinline__ void peer_v_tokens(int j, const LAS unsigned short* EL, const LAS unsigned char* AL  , const LAS float* ASC  , const LAS int* SAL  , ...
;     ...
;         for (int st = 0; st < 16; ++st) {
;             const int p = st >> 2, q = st & 3;
;             if (st < 14) VDMA(st + 2, (st + 2) % 3);
;             if (st < 14) asm volatile("s_waitcnt vmcnt(8)" ::: "memory");
;             else if (st == 14) asm volatile("s_waitcnt vmcnt(4)" ::: "memory");
;             else asm volatile("s_waitcnt vmcnt(0)" ::: "memory");
;             if (q == 0) {
; #pragma unroll
;                 for (int r = 0; r < 4; ++r) { accH[r] = 0; accL[r] = 0; } }
; #pragma unroll
;             for (int tp = 0; tp < 2; ++tp) {
;                 const v2i ao = TR4(ATL + (2 * q + tp) * 128 + 8 * s16), ah = TR4(ATL + 1024 + (2 * q + tp) * 128 + 8 * s16);
; #pragma unroll
;                 for (int r = 0; r < 4; ++r) {
;                     const v2i d = TR4(ldsb + BUF[st % 3] + 2048 * tp + roff[r]);
;                     accH[r] = __builtin_amdgcn_sdot8(d.x, ah.x, accH[r], false); accH[r] = __builtin_amdgcn_sdot8(d.y, ah.y, accH[r], false);
;                     accL[r] = __builtin_amdgcn_sdot8(d.x, ao.x, accL[r], false); accL[r] = __builtin_amdgcn_sdot8(d.y, ao.y, accL[r], false);
;                 }
;             }
;             asm volatile("s_waitcnt lgkmcnt(0)" ::: "memory");
;             if (q == 3) {
; #pragma unroll
;                 for (int r = 0; r < 4; ++r) STASH[256 * p + 16 * (grp + 4 * r) + pc] = f2bf(asc * (float)(2 * ((accH[r] << 4) + accL[r]) + sa));
;             }
;         }
	v_add_u32_e32 v54, s79, v59
	v_add_u32_e32 v55, s79, v60
	v_add_u32_e32 v56, s79, v61
	v_add_u32_e32 v57, s79, v62
	ds_read_b64_tr_b4 v[50:51], v160 offset:128
	ds_read_b64_tr_b4 v[52:53], v160 offset:1152
	ds_read_b64_tr_b4 v[130:131], v54
	ds_read_b64_tr_b4 v[132:133], v55
	ds_read_b64_tr_b4 v[134:135], v56
	ds_read_b64_tr_b4 v[136:137], v57
	s_waitcnt lgkmcnt(12)
	v_dot8c_i32_i4_e32 v38, v122, v48
	v_dot8c_i32_i4_e32 v39, v122, v46
	v_dot8c_i32_i4_e32 v40, v124, v48
	v_dot8c_i32_i4_e32 v41, v124, v46
	v_dot8c_i32_i4_e32 v42, v126, v48
	v_dot8c_i32_i4_e32 v43, v126, v46
	v_dot8c_i32_i4_e32 v44, v128, v48
	v_dot8c_i32_i4_e32 v45, v128, v46
	v_dot8c_i32_i4_e32 v38, v123, v49
	v_dot8c_i32_i4_e32 v39, v123, v47
	v_dot8c_i32_i4_e32 v40, v125, v49
	v_dot8c_i32_i4_e32 v41, v125, v47
	v_dot8c_i32_i4_e32 v42, v127, v49
	v_dot8c_i32_i4_e32 v43, v127, v47
	v_dot8c_i32_i4_e32 v44, v129, v49
	v_dot8c_i32_i4_e32 v45, v129, v47
	v_and_b32_e32 v78, 0xffff, v32
	v_lshrrev_b32_e32 v79, 16, v32
	v_lshl_add_u32 v78, v78, 7, v152
	v_lshl_add_u32 v79, v79, 7, v153
	s_mov_b32 m0, s78
	s_add_i32 s43, s78, 0x400
	global_load_lds_dwordx4 v78, s[50:51]
	s_mov_b32 m0, s43
	s_nop 0
	global_load_lds_dwordx4 v79, s[50:51]
	s_waitcnt vmcnt(12)
	v_add_u32_e32 v54, s98, v59
	v_add_u32_e32 v55, s98, v60
	v_add_u32_e32 v56, s98, v61
	v_add_u32_e32 v57, s98, v62
	ds_read_b64_tr_b4 v[46:47], v160 offset:256
	ds_read_b64_tr_b4 v[48:49], v160 offset:1280
	ds_read_b64_tr_b4 v[122:123], v54
	ds_read_b64_tr_b4 v[124:125], v55
	ds_read_b64_tr_b4 v[126:127], v56
	ds_read_b64_tr_b4 v[128:129], v57
	s_waitcnt lgkmcnt(6)
	v_dot8c_i32_i4_e32 v38, v130, v52
	v_dot8c_i32_i4_e32 v39, v130, v50
	v_dot8c_i32_i4_e32 v40, v132, v52
	v_dot8c_i32_i4_e32 v41, v132, v50
	v_dot8c_i32_i4_e32 v42, v134, v52
	v_dot8c_i32_i4_e32 v43, v134, v50
	v_dot8c_i32_i4_e32 v44, v136, v52
	v_dot8c_i32_i4_e32 v45, v136, v50
	v_dot8c_i32_i4_e32 v38, v131, v53
	v_dot8c_i32_i4_e32 v39, v131, v51
	v_dot8c_i32_i4_e32 v40, v133, v53
	v_dot8c_i32_i4_e32 v41, v133, v51
	v_dot8c_i32_i4_e32 v42, v135, v53
	v_dot8c_i32_i4_e32 v43, v135, v51
	v_dot8c_i32_i4_e32 v44, v137, v53
	v_dot8c_i32_i4_e32 v45, v137, v51
	v_and_b32_e32 v78, 0xffff, v33
	v_lshrrev_b32_e32 v79, 16, v33
	v_lshl_add_u32 v78, v78, 7, v152
	v_lshl_add_u32 v79, v79, 7, v153
	s_mov_b32 m0, s79
	s_add_i32 s43, s79, 0x400
	global_load_lds_dwordx4 v78, s[50:51]
	s_mov_b32 m0, s43
	s_nop 0
	global_load_lds_dwordx4 v79, s[50:51]
	s_waitcnt vmcnt(12)
	v_add_u32_e32 v54, s99, v59
	v_add_u32_e32 v55, s99, v60
	v_add_u32_e32 v56, s99, v61
	v_add_u32_e32 v57, s99, v62
	ds_read_b64_tr_b4 v[50:51], v160 offset:384
	ds_read_b64_tr_b4 v[52:53], v160 offset:1408
	ds_read_b64_tr_b4 v[130:131], v54
	ds_read_b64_tr_b4 v[132:133], v55
	ds_read_b64_tr_b4 v[134:135], v56
	ds_read_b64_tr_b4 v[136:137], v57
	s_waitcnt lgkmcnt(6)
	v_dot8c_i32_i4_e32 v38, v122, v48
	v_dot8c_i32_i4_e32 v39, v122, v46
	v_dot8c_i32_i4_e32 v40, v124, v48
	v_dot8c_i32_i4_e32 v41, v124, v46
	v_dot8c_i32_i4_e32 v42, v126, v48
	v_dot8c_i32_i4_e32 v43, v126, v46
	v_dot8c_i32_i4_e32 v44, v128, v48
	v_dot8c_i32_i4_e32 v45, v128, v46
	v_dot8c_i32_i4_e32 v38, v123, v49
	v_dot8c_i32_i4_e32 v39, v123, v47
	v_dot8c_i32_i4_e32 v40, v125, v49
	v_dot8c_i32_i4_e32 v41, v125, v47
	v_dot8c_i32_i4_e32 v42, v127, v49
	v_dot8c_i32_i4_e32 v43, v127, v47
	v_dot8c_i32_i4_e32 v44, v129, v49
	v_dot8c_i32_i4_e32 v45, v129, v47
	s_waitcnt lgkmcnt(15)
	v_and_b32_e32 v78, 0xffff, v18
	v_lshrrev_b32_e32 v79, 16, v18
	v_lshl_add_u32 v78, v78, 7, v152
	v_lshl_add_u32 v79, v79, 7, v153
	s_mov_b32 m0, s98
	s_add_i32 s43, s98, 0x400
	global_load_lds_dwordx4 v78, s[50:51]
	s_mov_b32 m0, s43
	s_nop 0
	global_load_lds_dwordx4 v79, s[50:51]
	s_waitcnt vmcnt(12)
	v_add_u32_e32 v54, s76, v59
	v_add_u32_e32 v55, s76, v60
	v_add_u32_e32 v56, s76, v61
	v_add_u32_e32 v57, s76, v62
	ds_read_b64_tr_b4 v[46:47], v160 offset:512
	ds_read_b64_tr_b4 v[48:49], v160 offset:1536
	ds_read_b64_tr_b4 v[122:123], v54
	ds_read_b64_tr_b4 v[124:125], v55
	ds_read_b64_tr_b4 v[126:127], v56
	ds_read_b64_tr_b4 v[128:129], v57
	s_waitcnt lgkmcnt(6)
	v_dot8c_i32_i4_e32 v38, v130, v52
	v_dot8c_i32_i4_e32 v39, v130, v50
	v_dot8c_i32_i4_e32 v40, v132, v52
	v_dot8c_i32_i4_e32 v41, v132, v50
	v_dot8c_i32_i4_e32 v42, v134, v52
	v_dot8c_i32_i4_e32 v43, v134, v50
	v_dot8c_i32_i4_e32 v44, v136, v52
	v_dot8c_i32_i4_e32 v45, v136, v50
	v_dot8c_i32_i4_e32 v38, v131, v53
	v_dot8c_i32_i4_e32 v39, v131, v51
	v_dot8c_i32_i4_e32 v40, v133, v53
	v_dot8c_i32_i4_e32 v41, v133, v51
	v_dot8c_i32_i4_e32 v42, v135, v53
	v_dot8c_i32_i4_e32 v43, v135, v51
	v_dot8c_i32_i4_e32 v44, v137, v53
	v_dot8c_i32_i4_e32 v45, v137, v51
	v_and_b32_e32 v78, 0xffff, v19
	v_lshrrev_b32_e32 v79, 16, v19
	v_lshl_add_u32 v78, v78, 7, v152
	v_lshl_add_u32 v79, v79, 7, v153
	s_mov_b32 m0, s99
	s_add_i32 s43, s99, 0x400
	global_load_lds_dwordx4 v78, s[50:51]
	s_mov_b32 m0, s43
	s_nop 0
	global_load_lds_dwordx4 v79, s[50:51]
	s_waitcnt vmcnt(8)
	v_add_u32_e32 v54, s77, v59
	v_add_u32_e32 v55, s77, v60
	v_add_u32_e32 v56, s77, v61
	v_add_u32_e32 v57, s77, v62
	ds_read_b64_tr_b4 v[50:51], v160 offset:640
	ds_read_b64_tr_b4 v[52:53], v160 offset:1664
	ds_read_b64_tr_b4 v[130:131], v54
	ds_read_b64_tr_b4 v[132:133], v55
	ds_read_b64_tr_b4 v[134:135], v56
	ds_read_b64_tr_b4 v[136:137], v57
	s_waitcnt lgkmcnt(6)
	v_dot8c_i32_i4_e32 v38, v122, v48
	v_dot8c_i32_i4_e32 v39, v122, v46
	v_dot8c_i32_i4_e32 v40, v124, v48
	v_dot8c_i32_i4_e32 v41, v124, v46
	v_dot8c_i32_i4_e32 v42, v126, v48
	v_dot8c_i32_i4_e32 v43, v126, v46
	v_dot8c_i32_i4_e32 v44, v128, v48
	v_dot8c_i32_i4_e32 v45, v128, v46
	v_dot8c_i32_i4_e32 v38, v123, v49
	v_dot8c_i32_i4_e32 v39, v123, v47
	v_dot8c_i32_i4_e32 v40, v125, v49
	v_dot8c_i32_i4_e32 v41, v125, v47
	v_dot8c_i32_i4_e32 v42, v127, v49
	v_dot8c_i32_i4_e32 v43, v127, v47
	v_dot8c_i32_i4_e32 v44, v129, v49
	v_dot8c_i32_i4_e32 v45, v129, v47
	s_waitcnt lgkmcnt(15)
; #define LAS __attribute__((address_space(3)))
; __device__ __forceinline__ void peer_v_tokens(int j, const LAS unsigned short* EL, const LAS unsigned char* AL  , const LAS float* ASC  , const LAS int* SAL  , ...
;     ...
;         for (int m = 0; m < 2; ++m) {
;             const int idx = lane + 64 * m, tau = idx >> 4, sr = idx & 15, k = 16 * (sr & 7) + 2 * tau + (sr >> 3);
;             const int aq = (int)*(const LAS signed char*)(AL + tl * 128 + k); const int tq = aq + 8;
;             const unsigned lo = (((unsigned)tq & 15u) ^ 8u) * 0x11111111u, hi = ((unsigned)(tq >> 4) & 15u) * 0x11111111u;
;             typedef unsigned u2v __attribute__((ext_vector_type(2)));
;             u2v l2; l2.x = lo; l2.y = lo; u2v h2; h2.x = hi; h2.y = hi;
;             *(LAS u2v*)(ATL + 8 * idx) = l2; *(LAS u2v*)(ATL + 1024 + 8 * idx) = h2;
;         }
;         const float asc = ASC[tl]; const int sa = SAL[tl];
;     ...
;         for (int st = 0; st < 16; ++st) {
;             const int p = st >> 2, q = st & 3;
;             if (st < 14) VDMA(st + 2, (st + 2) % 3);
;             if (st < 14) asm volatile("s_waitcnt vmcnt(8)" ::: "memory");
;             else if (st == 14) asm volatile("s_waitcnt vmcnt(4)" ::: "memory");
;             else asm volatile("s_waitcnt vmcnt(0)" ::: "memory");
;             if (q == 0) {
; #pragma unroll
;                 for (int r = 0; r < 4; ++r) { accH[r] = 0; accL[r] = 0; } }
; #pragma unroll
;             for (int tp = 0; tp < 2; ++tp) {
;                 const v2i ao = TR4(ATL + (2 * q + tp) * 128 + 8 * s16), ah = TR4(ATL + 1024 + (2 * q + tp) * 128 + 8 * s16);
; #pragma unroll
;                 for (int r = 0; r < 4; ++r) {
;                     const v2i d = TR4(ldsb + BUF[st % 3] + 2048 * tp + roff[r]);
;                     accH[r] = __builtin_amdgcn_sdot8(d.x, ah.x, accH[r], false); accH[r] = __builtin_amdgcn_sdot8(d.y, ah.y, accH[r], false);
;                     accL[r] = __builtin_amdgcn_sdot8(d.x, ao.x, accL[r], false); accL[r] = __builtin_amdgcn_sdot8(d.y, ao.y, accL[r], false);
;                 }
;             }
;             asm volatile("s_waitcnt lgkmcnt(0)" ::: "memory");
;             if (q == 3) {
; #pragma unroll
;                 for (int r = 0; r < 4; ++r) STASH[256 * p + 16 * (grp + 4 * r) + pc] = f2bf(asc * (float)(2 * ((accH[r] << 4) + accL[r]) + sa));
;             }
;         }
	v_add_u32_e32 v143, 8, v139
	v_and_b32_e32 v142, 15, v143
	v_xor_b32_e32 v142, 8, v142
	v_bfe_u32 v144, v143, 4, 4
	v_mul_lo_u32 v142, v142, s92
	v_mul_lo_u32 v144, v144, s92
	v_mov_b32_e32 v143, v142
	v_mov_b32_e32 v145, v144
	ds_write2st64_b64 v159, v[142:143], v[144:145] offset1:2
	v_and_b32_e32 v78, 0xffff, v20
	v_lshrrev_b32_e32 v79, 16, v20
	v_lshl_add_u32 v78, v78, 7, v152
	v_lshl_add_u32 v79, v79, 7, v153
	s_mov_b32 m0, s76
	s_add_i32 s43, s76, 0x400
	global_load_lds_dwordx4 v78, s[50:51]
	s_mov_b32 m0, s43
	s_nop 0
	global_load_lds_dwordx4 v79, s[50:51]
	s_waitcnt vmcnt(8)
	v_add_u32_e32 v54, s78, v59
	v_add_u32_e32 v55, s78, v60
	v_add_u32_e32 v56, s78, v61
	v_add_u32_e32 v57, s78, v62
	ds_read_b64_tr_b4 v[46:47], v160 offset:768
	ds_read_b64_tr_b4 v[48:49], v160 offset:1792
	ds_read_b64_tr_b4 v[122:123], v54
	ds_read_b64_tr_b4 v[124:125], v55
	ds_read_b64_tr_b4 v[126:127], v56
	ds_read_b64_tr_b4 v[128:129], v57
	s_waitcnt lgkmcnt(7)
	v_dot8c_i32_i4_e32 v38, v130, v52
	v_dot8c_i32_i4_e32 v39, v130, v50
	v_dot8c_i32_i4_e32 v40, v132, v52
	v_dot8c_i32_i4_e32 v41, v132, v50
	v_dot8c_i32_i4_e32 v42, v134, v52
	v_dot8c_i32_i4_e32 v43, v134, v50
	v_dot8c_i32_i4_e32 v44, v136, v52
	v_dot8c_i32_i4_e32 v45, v136, v50
	v_dot8c_i32_i4_e32 v38, v131, v53
	v_dot8c_i32_i4_e32 v39, v131, v51
	v_dot8c_i32_i4_e32 v40, v133, v53
	v_dot8c_i32_i4_e32 v41, v133, v51
	v_dot8c_i32_i4_e32 v42, v135, v53
	v_dot8c_i32_i4_e32 v43, v135, v51
	v_dot8c_i32_i4_e32 v44, v137, v53
	v_dot8c_i32_i4_e32 v45, v137, v51
	v_and_b32_e32 v78, 0xffff, v21
	v_lshrrev_b32_e32 v79, 16, v21
	v_lshl_add_u32 v78, v78, 7, v152
	v_lshl_add_u32 v79, v79, 7, v153
	s_mov_b32 m0, s77
	s_add_i32 s43, s77, 0x400
	global_load_lds_dwordx4 v78, s[50:51]
	s_mov_b32 m0, s43
	s_nop 0
	global_load_lds_dwordx4 v79, s[50:51]
	s_waitcnt vmcnt(8)
	v_add_u32_e32 v54, s79, v59
	v_add_u32_e32 v55, s79, v60
	v_add_u32_e32 v56, s79, v61
	v_add_u32_e32 v57, s79, v62
	ds_read_b64_tr_b4 v[50:51], v160 offset:896
	ds_read_b64_tr_b4 v[52:53], v160 offset:1920
	ds_read_b64_tr_b4 v[130:131], v54
	ds_read_b64_tr_b4 v[132:133], v55
	ds_read_b64_tr_b4 v[134:135], v56
	ds_read_b64_tr_b4 v[136:137], v57
	s_waitcnt lgkmcnt(6)
	v_dot8c_i32_i4_e32 v38, v122, v48
	v_dot8c_i32_i4_e32 v39, v122, v46
	v_dot8c_i32_i4_e32 v40, v124, v48
	v_dot8c_i32_i4_e32 v41, v124, v46
	v_dot8c_i32_i4_e32 v42, v126, v48
	v_dot8c_i32_i4_e32 v43, v126, v46
	v_dot8c_i32_i4_e32 v44, v128, v48
	v_dot8c_i32_i4_e32 v45, v128, v46
	v_dot8c_i32_i4_e32 v38, v123, v49
	v_dot8c_i32_i4_e32 v39, v123, v47
	v_dot8c_i32_i4_e32 v40, v125, v49
	v_dot8c_i32_i4_e32 v41, v125, v47
	v_dot8c_i32_i4_e32 v42, v127, v49
	v_dot8c_i32_i4_e32 v43, v127, v47
	v_dot8c_i32_i4_e32 v44, v129, v49
	v_dot8c_i32_i4_e32 v45, v129, v47
	v_and_b32_e32 v78, 0xffff, v22
	v_lshrrev_b32_e32 v79, 16, v22
	v_lshl_add_u32 v78, v78, 7, v152
	v_lshl_add_u32 v79, v79, 7, v153
	s_mov_b32 m0, s78
	s_add_i32 s43, s78, 0x400
	global_load_lds_dwordx4 v78, s[50:51]
	s_mov_b32 m0, s43
	s_nop 0
	global_load_lds_dwordx4 v79, s[50:51]
	s_waitcnt vmcnt(8)
	v_add_u32_e32 v54, s98, v59
	v_add_u32_e32 v55, s98, v60
	v_add_u32_e32 v56, s98, v61
	v_add_u32_e32 v57, s98, v62
	ds_read_b64_tr_b4 v[46:47], v160
	ds_read_b64_tr_b4 v[48:49], v160 offset:1024
	ds_read_b64_tr_b4 v[122:123], v54
	ds_read_b64_tr_b4 v[124:125], v55
	ds_read_b64_tr_b4 v[126:127], v56
	ds_read_b64_tr_b4 v[128:129], v57
	s_waitcnt lgkmcnt(6)
	v_dot8c_i32_i4_e32 v38, v130, v52
	v_dot8c_i32_i4_e32 v39, v130, v50
	v_dot8c_i32_i4_e32 v40, v132, v52
	v_dot8c_i32_i4_e32 v41, v132, v50
	v_dot8c_i32_i4_e32 v42, v134, v52
	v_dot8c_i32_i4_e32 v43, v134, v50
	v_dot8c_i32_i4_e32 v44, v136, v52
	v_dot8c_i32_i4_e32 v45, v136, v50
	v_dot8c_i32_i4_e32 v38, v131, v53
	v_dot8c_i32_i4_e32 v39, v131, v51
	v_dot8c_i32_i4_e32 v40, v133, v53
	v_dot8c_i32_i4_e32 v41, v133, v51
	v_dot8c_i32_i4_e32 v42, v135, v53
	v_dot8c_i32_i4_e32 v43, v135, v51
	v_dot8c_i32_i4_e32 v44, v137, v53
	v_dot8c_i32_i4_e32 v45, v137, v51
	s_nop 3
	s_waitcnt lgkmcnt(15)
	v_lshlrev_b32_e32 v38, 5, v38
	v_lshlrev_b32_e32 v39, 1, v39
	v_add3_u32 v38, v39, v229, v38
	v_cvt_f32_i32_e32 v38, v38
	v_mul_f32_e32 v38, v228, v38
	v_lshlrev_b32_e32 v40, 5, v40
	v_lshlrev_b32_e32 v41, 1, v41
	v_add3_u32 v40, v41, v229, v40
	v_cvt_f32_i32_e32 v40, v40
	v_mul_f32_e32 v40, v228, v40
	v_lshlrev_b32_e32 v42, 5, v42
	v_lshlrev_b32_e32 v43, 1, v43
	v_add3_u32 v42, v43, v229, v42
	v_cvt_f32_i32_e32 v42, v42
	v_mul_f32_e32 v42, v228, v42
	v_lshlrev_b32_e32 v44, 5, v44
	v_lshlrev_b32_e32 v45, 1, v45
	v_add3_u32 v44, v45, v229, v44
	v_cvt_f32_i32_e32 v44, v44
	v_mul_f32_e32 v44, v228, v44
	v_cvt_pk_bf16_f32 v176, v38, v40
	v_cvt_pk_bf16_f32 v177, v42, v44
	v_add_u32_e32 v147, 8, v140
	v_and_b32_e32 v146, 15, v147
	v_xor_b32_e32 v146, 8, v146
	v_bfe_u32 v148, v147, 4, 4
	v_mul_lo_u32 v146, v146, s92
	v_mul_lo_u32 v148, v148, s92
	v_mov_b32_e32 v147, v146
	v_mov_b32_e32 v149, v148
	ds_write2st64_b64 v77, v[146:147], v[148:149] offset1:2
	v_add_u32_e32 v138, 0xc00, v74
	ds_read_u8 v139, v138
	v_add_u32_e32 v141, 0xc00, v73
	ds_read_u8 v140, v141
	s_add_i32 s43, s67, 64
	v_mov_b32_e32 v138, s43
	ds_read2st64_b32 v[228:229], v138 offset1:1
	ds_read_b128 v[26:29], v227 offset:6144
	ds_read_b128 v[30:33], v227 offset:6160
	v_mov_b32_e32 v38, 0
	v_mov_b32_e32 v39, 0
	v_mov_b32_e32 v40, 0
	v_mov_b32_e32 v41, 0
	v_mov_b32_e32 v42, 0
	v_mov_b32_e32 v43, 0
	v_mov_b32_e32 v44, 0
	v_mov_b32_e32 v45, 0
	v_and_b32_e32 v78, 0xffff, v23
	v_lshrrev_b32_e32 v79, 16, v23
	v_lshl_add_u32 v78, v78, 7, v152
	v_lshl_add_u32 v79, v79, 7, v153
	s_mov_b32 m0, s79
	s_add_i32 s43, s79, 0x400
	global_load_lds_dwordx4 v78, s[50:51]
	s_mov_b32 m0, s43
	s_nop 0
	global_load_lds_dwordx4 v79, s[50:51]
	s_waitcnt vmcnt(8)
; #define LAS __attribute__((address_space(3)))
; __device__ __forceinline__ bf16 f2bf(float f) { return (bf16)f2bfu(f); }
; #define TR4(p_) __builtin_amdgcn_ds_read_tr4_b64_v2i32((LAS v2i*)(p_))
; #define VDMA(st_, k_) do { _Pragma("unroll") for (int i_ = 0; i_ < 4; ++i_) { \
;         const unsigned off_ = (unsigned)((st_) >> 2) * (16384u * 128u) + (PE_ID(E, 4 * ((st_) & 3) + i_) << 7) + ((i_ & 1) ? cx1 : cx0); \
;         __builtin_amdgcn_global_load_lds((const unsigned*)(V4 + off_), (LAS unsigned*)(ldsb + BUF[k_] + 1024 * i_), 16, 0, 0); } } while (0)
; __device__ __forceinline__ void peer_v_tokens(int j, const LAS unsigned short* EL, const LAS unsigned char* AL  , const LAS float* ASC  , const LAS int* SAL  , ...
;     ...
;         for (int st = 0; st < 16; ++st) {
;             const int p = st >> 2, q = st & 3;
;             if (st < 14) VDMA(st + 2, (st + 2) % 3);
;             if (st < 14) asm volatile("s_waitcnt vmcnt(8)" ::: "memory");
;             else if (st == 14) asm volatile("s_waitcnt vmcnt(4)" ::: "memory");
;             else asm volatile("s_waitcnt vmcnt(0)" ::: "memory");
;             if (q == 0) {
; #pragma unroll
;                 for (int r = 0; r < 4; ++r) { accH[r] = 0; accL[r] = 0; } }
; #pragma unroll
;             for (int tp = 0; tp < 2; ++tp) {
;                 const v2i ao = TR4(ATL + (2 * q + tp) * 128 + 8 * s16), ah = TR4(ATL + 1024 + (2 * q + tp) * 128 + 8 * s16);
; #pragma unroll
;                 for (int r = 0; r < 4; ++r) {
;                     const v2i d = TR4(ldsb + BUF[st % 3] + 2048 * tp + roff[r]);
;                     accH[r] = __builtin_amdgcn_sdot8(d.x, ah.x, accH[r], false); accH[r] = __builtin_amdgcn_sdot8(d.y, ah.y, accH[r], false);
;                     accL[r] = __builtin_amdgcn_sdot8(d.x, ao.x, accL[r], false); accL[r] = __builtin_amdgcn_sdot8(d.y, ao.y, accL[r], false);
;                 }
;             }
;             asm volatile("s_waitcnt lgkmcnt(0)" ::: "memory");
;             if (q == 3) {
; #pragma unroll
;                 for (int r = 0; r < 4; ++r) STASH[256 * p + 16 * (grp + 4 * r) + pc] = f2bf(asc * (float)(2 * ((accH[r] << 4) + accL[r]) + sa));
;             }
;         }
;     ...
;             for (int jq = 0; jq < 4; ++jq) { typedef unsigned u2v __attribute__((ext_vector_type(2))); const u2v pw = *(const LAS u2v*)(STASH + 4 * lane + 256 * jq); const uint2 hw = hv[jq];
	v_add_u32_e32 v54, s99, v59
	v_add_u32_e32 v55, s99, v60
	v_add_u32_e32 v56, s99, v61
	v_add_u32_e32 v57, s99, v62
	ds_read_b64_tr_b4 v[50:51], v160 offset:128
	ds_read_b64_tr_b4 v[52:53], v160 offset:1152
	ds_read_b64_tr_b4 v[130:131], v54
	ds_read_b64_tr_b4 v[132:133], v55
	ds_read_b64_tr_b4 v[134:135], v56
	ds_read_b64_tr_b4 v[136:137], v57
	s_waitcnt lgkmcnt(12)
	v_dot8c_i32_i4_e32 v38, v122, v48
	v_dot8c_i32_i4_e32 v39, v122, v46
	v_dot8c_i32_i4_e32 v40, v124, v48
	v_dot8c_i32_i4_e32 v41, v124, v46
	v_dot8c_i32_i4_e32 v42, v126, v48
	v_dot8c_i32_i4_e32 v43, v126, v46
	v_dot8c_i32_i4_e32 v44, v128, v48
	v_dot8c_i32_i4_e32 v45, v128, v46
	v_dot8c_i32_i4_e32 v38, v123, v49
	v_dot8c_i32_i4_e32 v39, v123, v47
	v_dot8c_i32_i4_e32 v40, v125, v49
	v_dot8c_i32_i4_e32 v41, v125, v47
	v_dot8c_i32_i4_e32 v42, v127, v49
	v_dot8c_i32_i4_e32 v43, v127, v47
	v_dot8c_i32_i4_e32 v44, v129, v49
	v_dot8c_i32_i4_e32 v45, v129, v47
	v_and_b32_e32 v78, 0xffff, v24
	v_lshrrev_b32_e32 v79, 16, v24
	v_lshl_add_u32 v78, v78, 7, v152
	v_lshl_add_u32 v79, v79, 7, v153
	s_mov_b32 m0, s98
	s_add_i32 s43, s98, 0x400
	global_load_lds_dwordx4 v78, s[50:51]
	s_mov_b32 m0, s43
	s_nop 0
	global_load_lds_dwordx4 v79, s[50:51]
	s_waitcnt vmcnt(8)
	v_add_u32_e32 v54, s76, v59
	v_add_u32_e32 v55, s76, v60
	v_add_u32_e32 v56, s76, v61
	v_add_u32_e32 v57, s76, v62
	ds_read_b64_tr_b4 v[46:47], v160 offset:256
	ds_read_b64_tr_b4 v[48:49], v160 offset:1280
	ds_read_b64_tr_b4 v[122:123], v54
	ds_read_b64_tr_b4 v[124:125], v55
	ds_read_b64_tr_b4 v[126:127], v56
	ds_read_b64_tr_b4 v[128:129], v57
	s_waitcnt lgkmcnt(6)
	v_dot8c_i32_i4_e32 v38, v130, v52
	v_dot8c_i32_i4_e32 v39, v130, v50
	v_dot8c_i32_i4_e32 v40, v132, v52
	v_dot8c_i32_i4_e32 v41, v132, v50
	v_dot8c_i32_i4_e32 v42, v134, v52
	v_dot8c_i32_i4_e32 v43, v134, v50
	v_dot8c_i32_i4_e32 v44, v136, v52
	v_dot8c_i32_i4_e32 v45, v136, v50
	v_dot8c_i32_i4_e32 v38, v131, v53
	v_dot8c_i32_i4_e32 v39, v131, v51
	v_dot8c_i32_i4_e32 v40, v133, v53
	v_dot8c_i32_i4_e32 v41, v133, v51
	v_dot8c_i32_i4_e32 v42, v135, v53
	v_dot8c_i32_i4_e32 v43, v135, v51
	v_dot8c_i32_i4_e32 v44, v137, v53
	v_dot8c_i32_i4_e32 v45, v137, v51
	ds_write_b16 v65, v162
	ds_write_b16_d16_hi v65, v162 offset:128
	ds_write_b16 v65, v163 offset:256
	ds_write_b16_d16_hi v65, v163 offset:384
	ds_write_b16 v65, v164 offset:512
	ds_write_b16_d16_hi v65, v164 offset:640
	ds_write_b16 v65, v165 offset:768
	ds_write_b16_d16_hi v65, v165 offset:896
	ds_write_b16 v65, v166 offset:1024
	ds_write_b16_d16_hi v65, v166 offset:1152
	ds_write_b16 v65, v167 offset:1280
	ds_write_b16_d16_hi v65, v167 offset:1408
	ds_write_b16 v65, v168 offset:1536
	ds_write_b16_d16_hi v65, v168 offset:1664
	ds_write_b16 v65, v169 offset:1792
	ds_write_b16_d16_hi v65, v169 offset:1920
	ds_read_b64 v[202:203], v154
	ds_read_b64 v[204:205], v154 offset:512
	ds_read_b64 v[206:207], v154 offset:1024
	ds_read_b64 v[208:209], v154 offset:1536
	v_and_b32_e32 v78, 0xffff, v25
	v_lshrrev_b32_e32 v79, 16, v25
	v_lshl_add_u32 v78, v78, 7, v152
	v_lshl_add_u32 v79, v79, 7, v153
	s_mov_b32 m0, s99
	s_add_i32 s43, s99, 0x400
	global_load_lds_dwordx4 v78, s[50:51]
	s_mov_b32 m0, s43
	s_nop 0
	global_load_lds_dwordx4 v79, s[50:51]
	s_waitcnt vmcnt(8)
	v_add_u32_e32 v54, s77, v59
	v_add_u32_e32 v55, s77, v60
	v_add_u32_e32 v56, s77, v61
	v_add_u32_e32 v57, s77, v62
	ds_read_b64_tr_b4 v[50:51], v160 offset:384
	ds_read_b64_tr_b4 v[52:53], v160 offset:1408
	ds_read_b64_tr_b4 v[130:131], v54
	ds_read_b64_tr_b4 v[132:133], v55
	ds_read_b64_tr_b4 v[134:135], v56
	ds_read_b64_tr_b4 v[136:137], v57
	s_waitcnt lgkmcnt(15)
	v_dot8c_i32_i4_e32 v38, v122, v48
	v_dot8c_i32_i4_e32 v39, v122, v46
	v_dot8c_i32_i4_e32 v40, v124, v48
	v_dot8c_i32_i4_e32 v41, v124, v46
	v_dot8c_i32_i4_e32 v42, v126, v48
	v_dot8c_i32_i4_e32 v43, v126, v46
	v_dot8c_i32_i4_e32 v44, v128, v48
	v_dot8c_i32_i4_e32 v45, v128, v46
	v_dot8c_i32_i4_e32 v38, v123, v49
	v_dot8c_i32_i4_e32 v39, v123, v47
	v_dot8c_i32_i4_e32 v40, v125, v49
	v_dot8c_i32_i4_e32 v41, v125, v47
	v_dot8c_i32_i4_e32 v42, v127, v49
	v_dot8c_i32_i4_e32 v43, v127, v47
	v_dot8c_i32_i4_e32 v44, v129, v49
	v_dot8c_i32_i4_e32 v45, v129, v47
	s_waitcnt lgkmcnt(15)
	v_and_b32_e32 v78, 0xffff, v26
	v_lshrrev_b32_e32 v79, 16, v26
	v_lshl_add_u32 v78, v78, 7, v152
	v_lshl_add_u32 v79, v79, 7, v153
	s_mov_b32 m0, s76
	s_add_i32 s43, s76, 0x400
	global_load_lds_dwordx4 v78, s[50:51]
	s_mov_b32 m0, s43
	s_nop 0
	global_load_lds_dwordx4 v79, s[50:51]
	s_waitcnt vmcnt(8)
	v_add_u32_e32 v54, s78, v59
	v_add_u32_e32 v55, s78, v60
	v_add_u32_e32 v56, s78, v61
	v_add_u32_e32 v57, s78, v62
	ds_read_b64_tr_b4 v[46:47], v160 offset:512
	ds_read_b64_tr_b4 v[48:49], v160 offset:1536
	ds_read_b64_tr_b4 v[122:123], v54
	ds_read_b64_tr_b4 v[124:125], v55
	ds_read_b64_tr_b4 v[126:127], v56
	ds_read_b64_tr_b4 v[128:129], v57
	s_waitcnt lgkmcnt(6)
	v_dot8c_i32_i4_e32 v38, v130, v52
	v_dot8c_i32_i4_e32 v39, v130, v50
	v_dot8c_i32_i4_e32 v40, v132, v52
	v_dot8c_i32_i4_e32 v41, v132, v50
	v_dot8c_i32_i4_e32 v42, v134, v52
	v_dot8c_i32_i4_e32 v43, v134, v50
	v_dot8c_i32_i4_e32 v44, v136, v52
	v_dot8c_i32_i4_e32 v45, v136, v50
	v_dot8c_i32_i4_e32 v38, v131, v53
	v_dot8c_i32_i4_e32 v39, v131, v51
	v_dot8c_i32_i4_e32 v40, v133, v53
	v_dot8c_i32_i4_e32 v41, v133, v51
	v_dot8c_i32_i4_e32 v42, v135, v53
	v_dot8c_i32_i4_e32 v43, v135, v51
	v_dot8c_i32_i4_e32 v44, v137, v53
	v_dot8c_i32_i4_e32 v45, v137, v51
	v_and_b32_e32 v78, 0xffff, v27
	v_lshrrev_b32_e32 v79, 16, v27
	v_lshl_add_u32 v78, v78, 7, v152
	v_lshl_add_u32 v79, v79, 7, v153
	s_mov_b32 m0, s77
	s_add_i32 s43, s77, 0x400
	global_load_lds_dwordx4 v78, s[50:51]
	s_mov_b32 m0, s43
	s_nop 0
	global_load_lds_dwordx4 v79, s[50:51]
	s_waitcnt vmcnt(8)
; #define LAS __attribute__((address_space(3)))
; __device__ __forceinline__ bf16 f2bf(float f) { return (bf16)f2bfu(f); }
; __device__ __forceinline__ void peer_v_tokens(int j, const LAS unsigned short* EL, const LAS unsigned char* AL  , const LAS float* ASC  , const LAS int* SAL  , ...
;     ...
;         for (int m = 0; m < 2; ++m) {
;             const int idx = lane + 64 * m, tau = idx >> 4, sr = idx & 15, k = 16 * (sr & 7) + 2 * tau + (sr >> 3);
;             const int aq = (int)*(const LAS signed char*)(AL + tl * 128 + k); const int tq = aq + 8;
;             const unsigned lo = (((unsigned)tq & 15u) ^ 8u) * 0x11111111u, hi = ((unsigned)(tq >> 4) & 15u) * 0x11111111u;
;             typedef unsigned u2v __attribute__((ext_vector_type(2)));
;             u2v l2; l2.x = lo; l2.y = lo; u2v h2; h2.x = hi; h2.y = hi;
;             *(LAS u2v*)(ATL + 8 * idx) = l2; *(LAS u2v*)(ATL + 1024 + 8 * idx) = h2;
;         }
;     ...
;         for (int st = 0; st < 16; ++st) {
;             const int p = st >> 2, q = st & 3;
;             if (st < 14) VDMA(st + 2, (st + 2) % 3);
;             if (st < 14) asm volatile("s_waitcnt vmcnt(8)" ::: "memory");
;             else if (st == 14) asm volatile("s_waitcnt vmcnt(4)" ::: "memory");
;             else asm volatile("s_waitcnt vmcnt(0)" ::: "memory");
;             if (q == 0) {
; #pragma unroll
;                 for (int r = 0; r < 4; ++r) { accH[r] = 0; accL[r] = 0; } }
; #pragma unroll
;             for (int tp = 0; tp < 2; ++tp) {
;                 const v2i ao = TR4(ATL + (2 * q + tp) * 128 + 8 * s16), ah = TR4(ATL + 1024 + (2 * q + tp) * 128 + 8 * s16);
; #pragma unroll
;                 for (int r = 0; r < 4; ++r) {
;                     const v2i d = TR4(ldsb + BUF[st % 3] + 2048 * tp + roff[r]);
;                     accH[r] = __builtin_amdgcn_sdot8(d.x, ah.x, accH[r], false); accH[r] = __builtin_amdgcn_sdot8(d.y, ah.y, accH[r], false);
;                     accL[r] = __builtin_amdgcn_sdot8(d.x, ao.x, accL[r], false); accL[r] = __builtin_amdgcn_sdot8(d.y, ao.y, accL[r], false);
;                 }
;             }
;             asm volatile("s_waitcnt lgkmcnt(0)" ::: "memory");
;             if (q == 3) {
; #pragma unroll
;                 for (int r = 0; r < 4; ++r) STASH[256 * p + 16 * (grp + 4 * r) + pc] = f2bf(asc * (float)(2 * ((accH[r] << 4) + accL[r]) + sa));
;             }
;         }
	v_add_u32_e32 v54, s79, v59
	v_add_u32_e32 v55, s79, v60
	v_add_u32_e32 v56, s79, v61
	v_add_u32_e32 v57, s79, v62
	ds_read_b64_tr_b4 v[50:51], v160 offset:640
	ds_read_b64_tr_b4 v[52:53], v160 offset:1664
	ds_read_b64_tr_b4 v[130:131], v54
	ds_read_b64_tr_b4 v[132:133], v55
	ds_read_b64_tr_b4 v[134:135], v56
	ds_read_b64_tr_b4 v[136:137], v57
	s_waitcnt lgkmcnt(6)
	v_dot8c_i32_i4_e32 v38, v122, v48
	v_dot8c_i32_i4_e32 v39, v122, v46
	v_dot8c_i32_i4_e32 v40, v124, v48
	v_dot8c_i32_i4_e32 v41, v124, v46
	v_dot8c_i32_i4_e32 v42, v126, v48
	v_dot8c_i32_i4_e32 v43, v126, v46
	v_dot8c_i32_i4_e32 v44, v128, v48
	v_dot8c_i32_i4_e32 v45, v128, v46
	v_dot8c_i32_i4_e32 v38, v123, v49
	v_dot8c_i32_i4_e32 v39, v123, v47
	v_dot8c_i32_i4_e32 v40, v125, v49
	v_dot8c_i32_i4_e32 v41, v125, v47
	v_dot8c_i32_i4_e32 v42, v127, v49
	v_dot8c_i32_i4_e32 v43, v127, v47
	v_dot8c_i32_i4_e32 v44, v129, v49
	v_dot8c_i32_i4_e32 v45, v129, v47
	s_waitcnt lgkmcnt(15)
	v_add_u32_e32 v143, 8, v139
	v_and_b32_e32 v142, 15, v143
	v_xor_b32_e32 v142, 8, v142
	v_bfe_u32 v144, v143, 4, 4
	v_mul_lo_u32 v142, v142, s92
	v_mul_lo_u32 v144, v144, s92
	v_mov_b32_e32 v143, v142
	v_mov_b32_e32 v145, v144
	ds_write2st64_b64 v159, v[142:143], v[144:145] offset1:2
	v_and_b32_e32 v78, 0xffff, v28
	v_lshrrev_b32_e32 v79, 16, v28
	v_lshl_add_u32 v78, v78, 7, v152
	v_lshl_add_u32 v79, v79, 7, v153
	s_mov_b32 m0, s78
	s_add_i32 s43, s78, 0x400
	global_load_lds_dwordx4 v78, s[50:51]
	s_mov_b32 m0, s43
	s_nop 0
	global_load_lds_dwordx4 v79, s[50:51]
	s_waitcnt vmcnt(8)
	v_add_u32_e32 v54, s98, v59
	v_add_u32_e32 v55, s98, v60
	v_add_u32_e32 v56, s98, v61
	v_add_u32_e32 v57, s98, v62
	ds_read_b64_tr_b4 v[46:47], v160 offset:768
	ds_read_b64_tr_b4 v[48:49], v160 offset:1792
	ds_read_b64_tr_b4 v[122:123], v54
	ds_read_b64_tr_b4 v[124:125], v55
	ds_read_b64_tr_b4 v[126:127], v56
	ds_read_b64_tr_b4 v[128:129], v57
	s_waitcnt lgkmcnt(7)
	v_dot8c_i32_i4_e32 v38, v130, v52
	v_dot8c_i32_i4_e32 v39, v130, v50
	v_dot8c_i32_i4_e32 v40, v132, v52
	v_dot8c_i32_i4_e32 v41, v132, v50
	v_dot8c_i32_i4_e32 v42, v134, v52
	v_dot8c_i32_i4_e32 v43, v134, v50
	v_dot8c_i32_i4_e32 v44, v136, v52
	v_dot8c_i32_i4_e32 v45, v136, v50
	v_dot8c_i32_i4_e32 v38, v131, v53
	v_dot8c_i32_i4_e32 v39, v131, v51
	v_dot8c_i32_i4_e32 v40, v133, v53
	v_dot8c_i32_i4_e32 v41, v133, v51
	v_dot8c_i32_i4_e32 v42, v135, v53
	v_dot8c_i32_i4_e32 v43, v135, v51
	v_dot8c_i32_i4_e32 v44, v137, v53
	v_dot8c_i32_i4_e32 v45, v137, v51
	v_and_b32_e32 v78, 0xffff, v29
	v_lshrrev_b32_e32 v79, 16, v29
	v_lshl_add_u32 v78, v78, 7, v152
	v_lshl_add_u32 v79, v79, 7, v153
	s_mov_b32 m0, s79
	s_add_i32 s43, s79, 0x400
	global_load_lds_dwordx4 v78, s[50:51]
	s_mov_b32 m0, s43
	s_nop 0
	global_load_lds_dwordx4 v79, s[50:51]
	s_waitcnt vmcnt(8)
	v_add_u32_e32 v54, s99, v59
	v_add_u32_e32 v55, s99, v60
	v_add_u32_e32 v56, s99, v61
	v_add_u32_e32 v57, s99, v62
	ds_read_b64_tr_b4 v[50:51], v160 offset:896
	ds_read_b64_tr_b4 v[52:53], v160 offset:1920
	ds_read_b64_tr_b4 v[130:131], v54
	ds_read_b64_tr_b4 v[132:133], v55
	ds_read_b64_tr_b4 v[134:135], v56
	ds_read_b64_tr_b4 v[136:137], v57
	s_waitcnt lgkmcnt(6)
	v_dot8c_i32_i4_e32 v38, v122, v48
	v_dot8c_i32_i4_e32 v39, v122, v46
	v_dot8c_i32_i4_e32 v40, v124, v48
	v_dot8c_i32_i4_e32 v41, v124, v46
	v_dot8c_i32_i4_e32 v42, v126, v48
	v_dot8c_i32_i4_e32 v43, v126, v46
	v_dot8c_i32_i4_e32 v44, v128, v48
	v_dot8c_i32_i4_e32 v45, v128, v46
	v_dot8c_i32_i4_e32 v38, v123, v49
	v_dot8c_i32_i4_e32 v39, v123, v47
	v_dot8c_i32_i4_e32 v40, v125, v49
	v_dot8c_i32_i4_e32 v41, v125, v47
	v_dot8c_i32_i4_e32 v42, v127, v49
	v_dot8c_i32_i4_e32 v43, v127, v47
	v_dot8c_i32_i4_e32 v44, v129, v49
	v_dot8c_i32_i4_e32 v45, v129, v47
	v_and_b32_e32 v78, 0xffff, v30
	v_lshrrev_b32_e32 v79, 16, v30
	v_lshl_add_u32 v78, v78, 7, v152
	v_lshl_add_u32 v79, v79, 7, v153
	s_mov_b32 m0, s98
	s_add_i32 s43, s98, 0x400
	global_load_lds_dwordx4 v78, s[50:51]
	s_mov_b32 m0, s43
	s_nop 0
	global_load_lds_dwordx4 v79, s[50:51]
	s_waitcnt vmcnt(8)
	v_add_u32_e32 v54, s76, v59
	v_add_u32_e32 v55, s76, v60
	v_add_u32_e32 v56, s76, v61
	v_add_u32_e32 v57, s76, v62
	ds_read_b64_tr_b4 v[46:47], v160
	ds_read_b64_tr_b4 v[48:49], v160 offset:1024
	ds_read_b64_tr_b4 v[122:123], v54
	ds_read_b64_tr_b4 v[124:125], v55
	ds_read_b64_tr_b4 v[126:127], v56
	ds_read_b64_tr_b4 v[128:129], v57
	s_waitcnt lgkmcnt(6)
	v_dot8c_i32_i4_e32 v38, v130, v52
	v_dot8c_i32_i4_e32 v39, v130, v50
	v_dot8c_i32_i4_e32 v40, v132, v52
	v_dot8c_i32_i4_e32 v41, v132, v50
	v_dot8c_i32_i4_e32 v42, v134, v52
	v_dot8c_i32_i4_e32 v43, v134, v50
	v_dot8c_i32_i4_e32 v44, v136, v52
	v_dot8c_i32_i4_e32 v45, v136, v50
	v_dot8c_i32_i4_e32 v38, v131, v53
	v_dot8c_i32_i4_e32 v39, v131, v51
	v_dot8c_i32_i4_e32 v40, v133, v53
	v_dot8c_i32_i4_e32 v41, v133, v51
	v_dot8c_i32_i4_e32 v42, v135, v53
	v_dot8c_i32_i4_e32 v43, v135, v51
	v_dot8c_i32_i4_e32 v44, v137, v53
	v_dot8c_i32_i4_e32 v45, v137, v51
	s_nop 3
	s_waitcnt lgkmcnt(15)
; __device__ __forceinline__ void peer_v_tokens(int j, const LAS unsigned short* EL, const LAS unsigned char* AL  , const LAS float* ASC  , const LAS int* SAL  , ...
;     ...
;         for (int st = 0; st < 16; ++st) {
;             const int p = st >> 2, q = st & 3;
;             if (st < 14) VDMA(st + 2, (st + 2) % 3);
;             if (st < 14) asm volatile("s_waitcnt vmcnt(8)" ::: "memory");
;             else if (st == 14) asm volatile("s_waitcnt vmcnt(4)" ::: "memory");
;             else asm volatile("s_waitcnt vmcnt(0)" ::: "memory");
;             if (q == 0) {
; #pragma unroll
;                 for (int r = 0; r < 4; ++r) { accH[r] = 0; accL[r] = 0; } }
; #pragma unroll
;             for (int tp = 0; tp < 2; ++tp) {
;                 const v2i ao = TR4(ATL + (2 * q + tp) * 128 + 8 * s16), ah = TR4(ATL + 1024 + (2 * q + tp) * 128 + 8 * s16);
; #pragma unroll
;                 for (int r = 0; r < 4; ++r) {
;                     const v2i d = TR4(ldsb + BUF[st % 3] + 2048 * tp + roff[r]);
;                     accH[r] = __builtin_amdgcn_sdot8(d.x, ah.x, accH[r], false); accH[r] = __builtin_amdgcn_sdot8(d.y, ah.y, accH[r], false);
;                     accL[r] = __builtin_amdgcn_sdot8(d.x, ao.x, accL[r], false); accL[r] = __builtin_amdgcn_sdot8(d.y, ao.y, accL[r], false);
;                 }
;             }
;             asm volatile("s_waitcnt lgkmcnt(0)" ::: "memory");
;             if (q == 3) {
; #pragma unroll
;                 for (int r = 0; r < 4; ++r) STASH[256 * p + 16 * (grp + 4 * r) + pc] = f2bf(asc * (float)(2 * ((accH[r] << 4) + accL[r]) + sa));
;     ...
;         {
;             float4 v[4]; float ss = 0.f;
; #pragma unroll
;             for (int jq = 0; jq < 4; ++jq) { typedef unsigned u2v __attribute__((ext_vector_type(2))); const u2v pw = *(const LAS u2v*)(STASH + 4 * lane + 256 * jq); const uint2 hw = hv[jq];
;                 v[jq] = make_float4(__uint_as_float(hw.x << 16) + __uint_as_float(pw.x << 16), __uint_as_float(hw.x & 0xffff0000u) + __uint_as_float(pw.x & 0xffff0000u),
;                                     __uint_as_float(hw.y << 16) + __uint_as_float(pw.y << 16), __uint_as_float(hw.y & 0xffff0000u) + __uint_as_float(pw.y & 0xffff0000u));
;                 ss += v[jq].x * v[jq].x + v[jq].y * v[jq].y + v[jq].z * v[jq].z + v[jq].w * v[jq].w; }
;             ss = wave_sum(ss);
;             const float r3 = rsqrtf(ss * (1.f / D) + EPS);
	v_lshlrev_b32_e32 v38, 5, v38
	v_lshlrev_b32_e32 v39, 1, v39
	v_add3_u32 v38, v39, v229, v38
	v_cvt_f32_i32_e32 v38, v38
	v_mul_f32_e32 v38, v228, v38
	v_lshlrev_b32_e32 v40, 5, v40
	v_lshlrev_b32_e32 v41, 1, v41
	v_add3_u32 v40, v41, v229, v40
	v_cvt_f32_i32_e32 v40, v40
	v_mul_f32_e32 v40, v228, v40
	v_lshlrev_b32_e32 v42, 5, v42
	v_lshlrev_b32_e32 v43, 1, v43
	v_add3_u32 v42, v43, v229, v42
	v_cvt_f32_i32_e32 v42, v42
	v_mul_f32_e32 v42, v228, v42
	v_lshlrev_b32_e32 v44, 5, v44
	v_lshlrev_b32_e32 v45, 1, v45
	v_add3_u32 v44, v45, v229, v44
	v_cvt_f32_i32_e32 v44, v44
	v_mul_f32_e32 v44, v228, v44
	v_cvt_pk_bf16_f32 v184, v38, v40
	v_cvt_pk_bf16_f32 v185, v42, v44
	v_add_u32_e32 v147, 8, v140
	v_and_b32_e32 v146, 15, v147
	v_xor_b32_e32 v146, 8, v146
	v_bfe_u32 v148, v147, 4, 4
	v_mul_lo_u32 v146, v146, s92
	v_mul_lo_u32 v148, v148, s92
	v_mov_b32_e32 v147, v146
	v_mov_b32_e32 v149, v148
	ds_write2st64_b64 v77, v[146:147], v[148:149] offset1:2
	v_add_u32_e32 v138, 0x1000, v74
	ds_read_u8 v139, v138
	v_add_u32_e32 v141, 0x1000, v73
	ds_read_u8 v140, v141
	s_add_i32 s43, s67, 96
	v_mov_b32_e32 v138, s43
	ds_read2st64_b32 v[228:229], v138 offset1:1
	ds_read_b128 v[18:21], v227 offset:8192
	ds_read_b128 v[22:25], v227 offset:8208
	v_mov_b32_e32 v150, v63
	v_mov_b32_e32 v151, v64
	v_mov_b32_e32 v38, 0
	v_mov_b32_e32 v39, 0
	v_mov_b32_e32 v40, 0
	v_mov_b32_e32 v41, 0
	v_mov_b32_e32 v42, 0
	v_mov_b32_e32 v43, 0
	v_mov_b32_e32 v44, 0
	v_mov_b32_e32 v45, 0
	v_and_b32_e32 v78, 0xffff, v31
	v_lshrrev_b32_e32 v79, 16, v31
	v_lshl_add_u32 v78, v78, 7, v152
	v_lshl_add_u32 v79, v79, 7, v153
	s_mov_b32 m0, s99
	s_add_i32 s43, s99, 0x400
	global_load_lds_dwordx4 v78, s[50:51]
	s_mov_b32 m0, s43
	s_nop 0
	global_load_lds_dwordx4 v79, s[50:51]
	s_waitcnt vmcnt(8)
	v_add_u32_e32 v54, s77, v59
	v_add_u32_e32 v55, s77, v60
	v_add_u32_e32 v56, s77, v61
	v_add_u32_e32 v57, s77, v62
	ds_read_b64_tr_b4 v[50:51], v160 offset:128
	ds_read_b64_tr_b4 v[52:53], v160 offset:1152
	ds_read_b64_tr_b4 v[130:131], v54
	ds_read_b64_tr_b4 v[132:133], v55
	ds_read_b64_tr_b4 v[134:135], v56
	ds_read_b64_tr_b4 v[136:137], v57
	s_waitcnt lgkmcnt(12)
	s_waitcnt vmcnt(34) lgkmcnt(15)
	v_lshlrev_b32_e32 v210, 16, v194
	v_and_b32_e32 v211, 0xffff0000, v194
	v_lshlrev_b32_e32 v142, 16, v202
	v_and_b32_e32 v143, 0xffff0000, v202
	v_add_f32_e32 v210, v210, v142
	v_add_f32_e32 v211, v211, v143
	v_lshlrev_b32_e32 v212, 16, v195
	v_and_b32_e32 v213, 0xffff0000, v195
	v_lshlrev_b32_e32 v142, 16, v203
	v_and_b32_e32 v143, 0xffff0000, v203
	v_add_f32_e32 v212, v212, v142
	v_add_f32_e32 v213, v213, v143
	v_lshlrev_b32_e32 v214, 16, v196
	v_and_b32_e32 v215, 0xffff0000, v196
	v_lshlrev_b32_e32 v142, 16, v204
	v_and_b32_e32 v143, 0xffff0000, v204
	v_add_f32_e32 v214, v214, v142
	v_add_f32_e32 v215, v215, v143
	v_lshlrev_b32_e32 v216, 16, v197
	v_and_b32_e32 v217, 0xffff0000, v197
	v_lshlrev_b32_e32 v142, 16, v205
	v_and_b32_e32 v143, 0xffff0000, v205
	v_add_f32_e32 v216, v216, v142
	v_add_f32_e32 v217, v217, v143
	v_lshlrev_b32_e32 v218, 16, v198
	v_and_b32_e32 v219, 0xffff0000, v198
	v_lshlrev_b32_e32 v142, 16, v206
	v_and_b32_e32 v143, 0xffff0000, v206
	v_add_f32_e32 v218, v218, v142
	v_add_f32_e32 v219, v219, v143
	v_lshlrev_b32_e32 v220, 16, v199
	v_and_b32_e32 v221, 0xffff0000, v199
	v_lshlrev_b32_e32 v142, 16, v207
	v_and_b32_e32 v143, 0xffff0000, v207
	v_add_f32_e32 v220, v220, v142
	v_add_f32_e32 v221, v221, v143
	v_lshlrev_b32_e32 v222, 16, v200
	v_and_b32_e32 v223, 0xffff0000, v200
	v_lshlrev_b32_e32 v142, 16, v208
	v_and_b32_e32 v143, 0xffff0000, v208
	v_add_f32_e32 v222, v222, v142
	v_add_f32_e32 v223, v223, v143
	v_lshlrev_b32_e32 v224, 16, v201
	v_and_b32_e32 v225, 0xffff0000, v201
	v_lshlrev_b32_e32 v142, 16, v209
	v_and_b32_e32 v143, 0xffff0000, v209
	v_add_f32_e32 v224, v224, v142
	v_add_f32_e32 v225, v225, v143
	v_mov_b32_e32 v144, 0
	v_mul_f32_e32 v145, v210, v210
	v_fmac_f32_e32 v145, v211, v211
	v_fmac_f32_e32 v145, v212, v212
	v_fmac_f32_e32 v145, v213, v213
	v_add_f32_e32 v144, v144, v145
	v_mul_f32_e32 v145, v214, v214
	v_fmac_f32_e32 v145, v215, v215
	v_fmac_f32_e32 v145, v216, v216
	v_fmac_f32_e32 v145, v217, v217
	v_add_f32_e32 v144, v144, v145
	v_mul_f32_e32 v145, v218, v218
	v_fmac_f32_e32 v145, v219, v219
	v_fmac_f32_e32 v145, v220, v220
	v_fmac_f32_e32 v145, v221, v221
	v_add_f32_e32 v144, v144, v145
	v_mul_f32_e32 v145, v222, v222
	v_fmac_f32_e32 v145, v223, v223
	v_fmac_f32_e32 v145, v224, v224
	v_fmac_f32_e32 v145, v225, v225
	v_add_f32_e32 v144, v144, v145
	s_nop 1
	v_add_f32_dpp v144, v144, v144 quad_perm:[1,0,3,2] row_mask:0xf bank_mask:0xf bound_ctrl:1
	s_nop 1
	v_add_f32_dpp v144, v144, v144 quad_perm:[2,3,0,1] row_mask:0xf bank_mask:0xf bound_ctrl:1
	s_nop 1
	v_add_f32_dpp v144, v144, v144 row_half_mirror row_mask:0xf bank_mask:0xf bound_ctrl:1
	s_nop 1
	v_add_f32_dpp v144, v144, v144 row_mirror row_mask:0xf bank_mask:0xf bound_ctrl:1
	s_nop 1
	v_readlane_b32 s10, v144, 0
	v_readlane_b32 s11, v144, 16
	v_readlane_b32 s14, v144, 32
	v_readlane_b32 s15, v144, 48
	s_nop 3
	v_mov_b32_e32 v144, s11
	v_mov_b32_e32 v145, s15
	v_add_f32_e32 v144, s10, v144
	v_add_f32_e32 v145, s14, v145
	v_add_f32_e32 v144, v144, v145
	v_fmamk_f32 v144, v144, 0x3a800000, v111
	v_rsq_f32_e32 v144, v144
	s_nop 0
	v_mul_f32_e32 v210, v210, v144
	v_mul_f32_e32 v211, v211, v144
	v_mul_f32_e32 v212, v212, v144
	v_mul_f32_e32 v213, v213, v144
	v_mul_f32_e32 v214, v214, v144
	v_mul_f32_e32 v215, v215, v144
	v_mul_f32_e32 v216, v216, v144
	v_mul_f32_e32 v217, v217, v144
	v_mul_f32_e32 v218, v218, v144
	v_mul_f32_e32 v219, v219, v144
	v_mul_f32_e32 v220, v220, v144
	v_mul_f32_e32 v221, v221, v144
	v_mul_f32_e32 v222, v222, v144
	v_mul_f32_e32 v223, v223, v144
	v_mul_f32_e32 v224, v224, v144
	v_mul_f32_e32 v225, v225, v144
	v_dot8c_i32_i4_e32 v38, v122, v48
	v_dot8c_i32_i4_e32 v39, v122, v46
	v_dot8c_i32_i4_e32 v40, v124, v48
	v_dot8c_i32_i4_e32 v41, v124, v46
	v_dot8c_i32_i4_e32 v42, v126, v48
	v_dot8c_i32_i4_e32 v43, v126, v46
	v_dot8c_i32_i4_e32 v44, v128, v48
	v_dot8c_i32_i4_e32 v45, v128, v46
	v_dot8c_i32_i4_e32 v38, v123, v49
	v_dot8c_i32_i4_e32 v39, v123, v47
	v_dot8c_i32_i4_e32 v40, v125, v49
	v_dot8c_i32_i4_e32 v41, v125, v47
	v_dot8c_i32_i4_e32 v42, v127, v49
	v_dot8c_i32_i4_e32 v43, v127, v47
	v_dot8c_i32_i4_e32 v44, v129, v49
	v_dot8c_i32_i4_e32 v45, v129, v47
	v_and_b32_e32 v78, 0xffff, v32
	v_lshrrev_b32_e32 v79, 16, v32
	v_lshl_add_u32 v78, v78, 7, v152
	v_lshl_add_u32 v79, v79, 7, v153
	s_mov_b32 m0, s76
	s_add_i32 s43, s76, 0x400
	global_load_lds_dwordx4 v78, s[50:51]
	s_mov_b32 m0, s43
	s_nop 0
	global_load_lds_dwordx4 v79, s[50:51]
	s_waitcnt vmcnt(8)
; __device__ __forceinline__ bf16 f2bf(float f) { return (bf16)f2bfu(f); }
; #define TR4(p_) __builtin_amdgcn_ds_read_tr4_b64_v2i32((LAS v2i*)(p_))
; #define VDMA(st_, k_) do { _Pragma("unroll") for (int i_ = 0; i_ < 4; ++i_) { \
;         const unsigned off_ = (unsigned)((st_) >> 2) * (16384u * 128u) + (PE_ID(E, 4 * ((st_) & 3) + i_) << 7) + ((i_ & 1) ? cx1 : cx0); \
;         __builtin_amdgcn_global_load_lds((const unsigned*)(V4 + off_), (LAS unsigned*)(ldsb + BUF[k_] + 1024 * i_), 16, 0, 0); } } while (0)
; __device__ __forceinline__ void peer_v_tokens(int j, const LAS unsigned short* EL, const LAS unsigned char* AL  , const LAS float* ASC  , const LAS int* SAL  , ...
;     ...
;         for (int st = 0; st < 16; ++st) {
;             const int p = st >> 2, q = st & 3;
;             if (st < 14) VDMA(st + 2, (st + 2) % 3);
;             if (st < 14) asm volatile("s_waitcnt vmcnt(8)" ::: "memory");
;             else if (st == 14) asm volatile("s_waitcnt vmcnt(4)" ::: "memory");
;             else asm volatile("s_waitcnt vmcnt(0)" ::: "memory");
;             if (q == 0) {
; #pragma unroll
;                 for (int r = 0; r < 4; ++r) { accH[r] = 0; accL[r] = 0; } }
; #pragma unroll
;             for (int tp = 0; tp < 2; ++tp) {
;                 const v2i ao = TR4(ATL + (2 * q + tp) * 128 + 8 * s16), ah = TR4(ATL + 1024 + (2 * q + tp) * 128 + 8 * s16);
; #pragma unroll
;                 for (int r = 0; r < 4; ++r) {
;                     const v2i d = TR4(ldsb + BUF[st % 3] + 2048 * tp + roff[r]);
;                     accH[r] = __builtin_amdgcn_sdot8(d.x, ah.x, accH[r], false); accH[r] = __builtin_amdgcn_sdot8(d.y, ah.y, accH[r], false);
;                     accL[r] = __builtin_amdgcn_sdot8(d.x, ao.x, accL[r], false); accL[r] = __builtin_amdgcn_sdot8(d.y, ao.y, accL[r], false);
;                 }
;             }
;             asm volatile("s_waitcnt lgkmcnt(0)" ::: "memory");
;             if (q == 3) {
; #pragma unroll
;                 for (int r = 0; r < 4; ++r) STASH[256 * p + 16 * (grp + 4 * r) + pc] = f2bf(asc * (float)(2 * ((accH[r] << 4) + accL[r]) + sa));
;             }
;         }
	v_add_u32_e32 v54, s78, v59
	v_add_u32_e32 v55, s78, v60
	v_add_u32_e32 v56, s78, v61
	v_add_u32_e32 v57, s78, v62
	ds_read_b64_tr_b4 v[46:47], v160 offset:256
	ds_read_b64_tr_b4 v[48:49], v160 offset:1280
	ds_read_b64_tr_b4 v[122:123], v54
	ds_read_b64_tr_b4 v[124:125], v55
	ds_read_b64_tr_b4 v[126:127], v56
	ds_read_b64_tr_b4 v[128:129], v57
	s_waitcnt lgkmcnt(6)
	v_dot8c_i32_i4_e32 v38, v130, v52
	v_dot8c_i32_i4_e32 v39, v130, v50
	v_dot8c_i32_i4_e32 v40, v132, v52
	v_dot8c_i32_i4_e32 v41, v132, v50
	v_dot8c_i32_i4_e32 v42, v134, v52
	v_dot8c_i32_i4_e32 v43, v134, v50
	v_dot8c_i32_i4_e32 v44, v136, v52
	v_dot8c_i32_i4_e32 v45, v136, v50
	v_dot8c_i32_i4_e32 v38, v131, v53
	v_dot8c_i32_i4_e32 v39, v131, v51
	v_dot8c_i32_i4_e32 v40, v133, v53
	v_dot8c_i32_i4_e32 v41, v133, v51
	v_dot8c_i32_i4_e32 v42, v135, v53
	v_dot8c_i32_i4_e32 v43, v135, v51
	v_dot8c_i32_i4_e32 v44, v137, v53
	v_dot8c_i32_i4_e32 v45, v137, v51
	v_and_b32_e32 v78, 0xffff, v33
	v_lshrrev_b32_e32 v79, 16, v33
	v_lshl_add_u32 v78, v78, 7, v152
	v_lshl_add_u32 v79, v79, 7, v153
	s_mov_b32 m0, s77
	s_add_i32 s43, s77, 0x400
	global_load_lds_dwordx4 v78, s[50:51]
	s_mov_b32 m0, s43
	s_nop 0
	global_load_lds_dwordx4 v79, s[50:51]
	s_waitcnt vmcnt(8)
	v_add_u32_e32 v54, s79, v59
	v_add_u32_e32 v55, s79, v60
	v_add_u32_e32 v56, s79, v61
	v_add_u32_e32 v57, s79, v62
	ds_read_b64_tr_b4 v[50:51], v160 offset:384
	ds_read_b64_tr_b4 v[52:53], v160 offset:1408
	ds_read_b64_tr_b4 v[130:131], v54
	ds_read_b64_tr_b4 v[132:133], v55
	ds_read_b64_tr_b4 v[134:135], v56
	ds_read_b64_tr_b4 v[136:137], v57
	s_waitcnt lgkmcnt(6)
	v_dot8c_i32_i4_e32 v38, v122, v48
	v_dot8c_i32_i4_e32 v39, v122, v46
	v_dot8c_i32_i4_e32 v40, v124, v48
	v_dot8c_i32_i4_e32 v41, v124, v46
	v_dot8c_i32_i4_e32 v42, v126, v48
	v_dot8c_i32_i4_e32 v43, v126, v46
	v_dot8c_i32_i4_e32 v44, v128, v48
	v_dot8c_i32_i4_e32 v45, v128, v46
	v_dot8c_i32_i4_e32 v38, v123, v49
	v_dot8c_i32_i4_e32 v39, v123, v47
	v_dot8c_i32_i4_e32 v40, v125, v49
	v_dot8c_i32_i4_e32 v41, v125, v47
	v_dot8c_i32_i4_e32 v42, v127, v49
	v_dot8c_i32_i4_e32 v43, v127, v47
	v_dot8c_i32_i4_e32 v44, v129, v49
	v_dot8c_i32_i4_e32 v45, v129, v47
	s_waitcnt lgkmcnt(15)
	v_and_b32_e32 v78, 0xffff, v18
	v_lshrrev_b32_e32 v79, 16, v18
	v_lshl_add_u32 v78, v78, 7, v150
	v_lshl_add_u32 v79, v79, 7, v151
	s_mov_b32 m0, s78
	s_add_i32 s43, s78, 0x400
	global_load_lds_dwordx4 v78, s[50:51]
	s_mov_b32 m0, s43
	s_nop 0
	global_load_lds_dwordx4 v79, s[50:51]
	s_waitcnt vmcnt(8)
	v_add_u32_e32 v54, s98, v59
	v_add_u32_e32 v55, s98, v60
	v_add_u32_e32 v56, s98, v61
	v_add_u32_e32 v57, s98, v62
	ds_read_b64_tr_b4 v[46:47], v160 offset:512
	ds_read_b64_tr_b4 v[48:49], v160 offset:1536
	ds_read_b64_tr_b4 v[122:123], v54
	ds_read_b64_tr_b4 v[124:125], v55
	ds_read_b64_tr_b4 v[126:127], v56
	ds_read_b64_tr_b4 v[128:129], v57
	s_waitcnt lgkmcnt(6)
	v_dot8c_i32_i4_e32 v38, v130, v52
	v_dot8c_i32_i4_e32 v39, v130, v50
	v_dot8c_i32_i4_e32 v40, v132, v52
	v_dot8c_i32_i4_e32 v41, v132, v50
	v_dot8c_i32_i4_e32 v42, v134, v52
	v_dot8c_i32_i4_e32 v43, v134, v50
	v_dot8c_i32_i4_e32 v44, v136, v52
	v_dot8c_i32_i4_e32 v45, v136, v50
	v_dot8c_i32_i4_e32 v38, v131, v53
	v_dot8c_i32_i4_e32 v39, v131, v51
	v_dot8c_i32_i4_e32 v40, v133, v53
	v_dot8c_i32_i4_e32 v41, v133, v51
	v_dot8c_i32_i4_e32 v42, v135, v53
	v_dot8c_i32_i4_e32 v43, v135, v51
	v_dot8c_i32_i4_e32 v44, v137, v53
	v_dot8c_i32_i4_e32 v45, v137, v51
	v_and_b32_e32 v78, 0xffff, v19
	v_lshrrev_b32_e32 v79, 16, v19
	v_lshl_add_u32 v78, v78, 7, v150
	v_lshl_add_u32 v79, v79, 7, v151
	s_mov_b32 m0, s79
	s_add_i32 s43, s79, 0x400
	global_load_lds_dwordx4 v78, s[50:51]
	s_mov_b32 m0, s43
	s_nop 0
	global_load_lds_dwordx4 v79, s[50:51]
	s_waitcnt vmcnt(8)
	v_add_u32_e32 v54, s99, v59
	v_add_u32_e32 v55, s99, v60
	v_add_u32_e32 v56, s99, v61
	v_add_u32_e32 v57, s99, v62
	ds_read_b64_tr_b4 v[50:51], v160 offset:640
	ds_read_b64_tr_b4 v[52:53], v160 offset:1664
	ds_read_b64_tr_b4 v[130:131], v54
	ds_read_b64_tr_b4 v[132:133], v55
	ds_read_b64_tr_b4 v[134:135], v56
	ds_read_b64_tr_b4 v[136:137], v57
	s_waitcnt lgkmcnt(6)
	v_dot8c_i32_i4_e32 v38, v122, v48
	v_dot8c_i32_i4_e32 v39, v122, v46
	v_dot8c_i32_i4_e32 v40, v124, v48
	v_dot8c_i32_i4_e32 v41, v124, v46
	v_dot8c_i32_i4_e32 v42, v126, v48
	v_dot8c_i32_i4_e32 v43, v126, v46
	v_dot8c_i32_i4_e32 v44, v128, v48
	v_dot8c_i32_i4_e32 v45, v128, v46
	v_dot8c_i32_i4_e32 v38, v123, v49
	v_dot8c_i32_i4_e32 v39, v123, v47
	v_dot8c_i32_i4_e32 v40, v125, v49
	v_dot8c_i32_i4_e32 v41, v125, v47
	v_dot8c_i32_i4_e32 v42, v127, v49
	v_dot8c_i32_i4_e32 v43, v127, v47
	v_dot8c_i32_i4_e32 v44, v129, v49
	v_dot8c_i32_i4_e32 v45, v129, v47
	s_waitcnt lgkmcnt(15)
	v_add_u32_e32 v143, 8, v139
	v_and_b32_e32 v142, 15, v143
	v_xor_b32_e32 v142, 8, v142
	v_bfe_u32 v144, v143, 4, 4
	v_mul_lo_u32 v142, v142, s92
	v_mul_lo_u32 v144, v144, s92
	v_mov_b32_e32 v143, v142
	v_mov_b32_e32 v145, v144
	ds_write2st64_b64 v159, v[142:143], v[144:145] offset1:2
	v_and_b32_e32 v78, 0xffff, v20
	v_lshrrev_b32_e32 v79, 16, v20
	v_lshl_add_u32 v78, v78, 7, v150
	v_lshl_add_u32 v79, v79, 7, v151
	s_mov_b32 m0, s98
	s_add_i32 s43, s98, 0x400
	global_load_lds_dwordx4 v78, s[50:51]
	s_mov_b32 m0, s43
	s_nop 0
	global_load_lds_dwordx4 v79, s[50:51]
	s_waitcnt vmcnt(8)
	v_add_u32_e32 v54, s76, v59
	v_add_u32_e32 v55, s76, v60
	v_add_u32_e32 v56, s76, v61
	v_add_u32_e32 v57, s76, v62
	ds_read_b64_tr_b4 v[46:47], v160 offset:768
	ds_read_b64_tr_b4 v[48:49], v160 offset:1792
	ds_read_b64_tr_b4 v[122:123], v54
	ds_read_b64_tr_b4 v[124:125], v55
	ds_read_b64_tr_b4 v[126:127], v56
	ds_read_b64_tr_b4 v[128:129], v57
	s_waitcnt lgkmcnt(7)
; __device__ __forceinline__ void peer_v_tokens(int j, const LAS unsigned short* EL, const LAS unsigned char* AL  , const LAS float* ASC  , const LAS int* SAL  , ...
;     ...
;         uint2 hv[4]; float4 gv[4];
;         { unsigned ho = (unsigned)t * (D / 4) + (unsigned)lane; asm volatile("" : "+v"(ho)); const uint2* hp = (const uint2*)HB + ho; const float4* gp = (const float4*)fng + lane;
; #pragma unroll
;           for (int jq = 0; jq < 4; ++jq) { hv[jq] = hp[64 * jq]; gv[jq] = gp[64 * jq]; } }
;     ...
;         for (int st = 0; st < 16; ++st) {
;             const int p = st >> 2, q = st & 3;
;             if (st < 14) VDMA(st + 2, (st + 2) % 3);
;             if (st < 14) asm volatile("s_waitcnt vmcnt(8)" ::: "memory");
;             else if (st == 14) asm volatile("s_waitcnt vmcnt(4)" ::: "memory");
;             else asm volatile("s_waitcnt vmcnt(0)" ::: "memory");
;             if (q == 0) {
; #pragma unroll
;                 for (int r = 0; r < 4; ++r) { accH[r] = 0; accL[r] = 0; } }
; #pragma unroll
;             for (int tp = 0; tp < 2; ++tp) {
;                 const v2i ao = TR4(ATL + (2 * q + tp) * 128 + 8 * s16), ah = TR4(ATL + 1024 + (2 * q + tp) * 128 + 8 * s16);
; #pragma unroll
;                 for (int r = 0; r < 4; ++r) {
;                     const v2i d = TR4(ldsb + BUF[st % 3] + 2048 * tp + roff[r]);
;                     accH[r] = __builtin_amdgcn_sdot8(d.x, ah.x, accH[r], false); accH[r] = __builtin_amdgcn_sdot8(d.y, ah.y, accH[r], false);
;                     accL[r] = __builtin_amdgcn_sdot8(d.x, ao.x, accL[r], false); accL[r] = __builtin_amdgcn_sdot8(d.y, ao.y, accL[r], false);
;                 }
;             }
;             asm volatile("s_waitcnt lgkmcnt(0)" ::: "memory");
;             if (q == 3) {
; #pragma unroll
;                 for (int r = 0; r < 4; ++r) STASH[256 * p + 16 * (grp + 4 * r) + pc] = f2bf(asc * (float)(2 * ((accH[r] << 4) + accL[r]) + sa));
;             }
;         }
;     ...
;             float4* op = (float4*)(outp + (size_t)t * D) + lane;
; #pragma unroll
;             for (int jq = 0; jq < 4; ++jq) { typedef float f4v __attribute__((ext_vector_type(4))); f4v o4; o4.x = v[jq].x * r3 * gv[jq].x; o4.y = v[jq].y * r3 * gv[jq].y; o4.z = v[jq].z * r3 * gv[jq].z; o4.w = v[jq].w * r3 * gv[jq].w;
;                 __builtin_nontemporal_store(o4, (f4v*)op + 64 * jq); }
	v_dot8c_i32_i4_e32 v38, v130, v52
	v_dot8c_i32_i4_e32 v39, v130, v50
	v_dot8c_i32_i4_e32 v40, v132, v52
	v_dot8c_i32_i4_e32 v41, v132, v50
	v_dot8c_i32_i4_e32 v42, v134, v52
	v_dot8c_i32_i4_e32 v43, v134, v50
	v_dot8c_i32_i4_e32 v44, v136, v52
	v_dot8c_i32_i4_e32 v45, v136, v50
	v_dot8c_i32_i4_e32 v38, v131, v53
	v_dot8c_i32_i4_e32 v39, v131, v51
	v_dot8c_i32_i4_e32 v40, v133, v53
	v_dot8c_i32_i4_e32 v41, v133, v51
	v_dot8c_i32_i4_e32 v42, v135, v53
	v_dot8c_i32_i4_e32 v43, v135, v51
	v_dot8c_i32_i4_e32 v44, v137, v53
	v_dot8c_i32_i4_e32 v45, v137, v51
	v_and_b32_e32 v78, 0xffff, v21
	v_lshrrev_b32_e32 v79, 16, v21
	v_lshl_add_u32 v78, v78, 7, v150
	v_lshl_add_u32 v79, v79, 7, v151
	s_mov_b32 m0, s99
	s_add_i32 s43, s99, 0x400
	global_load_lds_dwordx4 v78, s[50:51]
	s_mov_b32 m0, s43
	s_nop 0
	global_load_lds_dwordx4 v79, s[50:51]
	s_waitcnt vmcnt(8)
	v_add_u32_e32 v54, s77, v59
	v_add_u32_e32 v55, s77, v60
	v_add_u32_e32 v56, s77, v61
	v_add_u32_e32 v57, s77, v62
	ds_read_b64_tr_b4 v[50:51], v160 offset:896
	ds_read_b64_tr_b4 v[52:53], v160 offset:1920
	ds_read_b64_tr_b4 v[130:131], v54
	ds_read_b64_tr_b4 v[132:133], v55
	ds_read_b64_tr_b4 v[134:135], v56
	ds_read_b64_tr_b4 v[136:137], v57
	s_waitcnt lgkmcnt(6)
	v_dot8c_i32_i4_e32 v38, v122, v48
	v_dot8c_i32_i4_e32 v39, v122, v46
	v_dot8c_i32_i4_e32 v40, v124, v48
	v_dot8c_i32_i4_e32 v41, v124, v46
	v_dot8c_i32_i4_e32 v42, v126, v48
	v_dot8c_i32_i4_e32 v43, v126, v46
	v_dot8c_i32_i4_e32 v44, v128, v48
	v_dot8c_i32_i4_e32 v45, v128, v46
	v_dot8c_i32_i4_e32 v38, v123, v49
	v_dot8c_i32_i4_e32 v39, v123, v47
	v_dot8c_i32_i4_e32 v40, v125, v49
	v_dot8c_i32_i4_e32 v41, v125, v47
	v_dot8c_i32_i4_e32 v42, v127, v49
	v_dot8c_i32_i4_e32 v43, v127, v47
	v_dot8c_i32_i4_e32 v44, v129, v49
	v_dot8c_i32_i4_e32 v45, v129, v47
	v_and_b32_e32 v78, 0xffff, v22
	v_lshrrev_b32_e32 v79, 16, v22
	v_lshl_add_u32 v78, v78, 7, v150
	v_lshl_add_u32 v79, v79, 7, v151
	s_mov_b32 m0, s76
	s_add_i32 s43, s76, 0x400
	global_load_lds_dwordx4 v78, s[50:51]
	s_mov_b32 m0, s43
	s_nop 0
	global_load_lds_dwordx4 v79, s[50:51]
	s_waitcnt vmcnt(8)
	v_add_u32_e32 v54, s78, v59
	v_add_u32_e32 v55, s78, v60
	v_add_u32_e32 v56, s78, v61
	v_add_u32_e32 v57, s78, v62
	ds_read_b64_tr_b4 v[46:47], v160
	ds_read_b64_tr_b4 v[48:49], v160 offset:1024
	ds_read_b64_tr_b4 v[122:123], v54
	ds_read_b64_tr_b4 v[124:125], v55
	ds_read_b64_tr_b4 v[126:127], v56
	ds_read_b64_tr_b4 v[128:129], v57
	s_waitcnt lgkmcnt(6)
	v_dot8c_i32_i4_e32 v38, v130, v52
	v_dot8c_i32_i4_e32 v39, v130, v50
	v_dot8c_i32_i4_e32 v40, v132, v52
	v_dot8c_i32_i4_e32 v41, v132, v50
	v_dot8c_i32_i4_e32 v42, v134, v52
	v_dot8c_i32_i4_e32 v43, v134, v50
	v_dot8c_i32_i4_e32 v44, v136, v52
	v_dot8c_i32_i4_e32 v45, v136, v50
	v_dot8c_i32_i4_e32 v38, v131, v53
	v_dot8c_i32_i4_e32 v39, v131, v51
	v_dot8c_i32_i4_e32 v40, v133, v53
	v_dot8c_i32_i4_e32 v41, v133, v51
	v_dot8c_i32_i4_e32 v42, v135, v53
	v_dot8c_i32_i4_e32 v43, v135, v51
	v_dot8c_i32_i4_e32 v44, v137, v53
	v_dot8c_i32_i4_e32 v45, v137, v51
	s_nop 3
	s_waitcnt lgkmcnt(15)
	v_lshlrev_b32_e32 v38, 5, v38
	v_lshlrev_b32_e32 v39, 1, v39
	v_add3_u32 v38, v39, v229, v38
	v_cvt_f32_i32_e32 v38, v38
	v_mul_f32_e32 v38, v228, v38
	v_lshlrev_b32_e32 v40, 5, v40
	v_lshlrev_b32_e32 v41, 1, v41
	v_add3_u32 v40, v41, v229, v40
	v_cvt_f32_i32_e32 v40, v40
	v_mul_f32_e32 v40, v228, v40
	v_lshlrev_b32_e32 v42, 5, v42
	v_lshlrev_b32_e32 v43, 1, v43
	v_add3_u32 v42, v43, v229, v42
	v_cvt_f32_i32_e32 v42, v42
	v_mul_f32_e32 v42, v228, v42
	v_lshlrev_b32_e32 v44, 5, v44
	v_lshlrev_b32_e32 v45, 1, v45
	v_add3_u32 v44, v45, v229, v44
	v_cvt_f32_i32_e32 v44, v44
	v_mul_f32_e32 v44, v228, v44
	v_cvt_pk_bf16_f32 v192, v38, v40
	v_cvt_pk_bf16_f32 v193, v42, v44
	ds_read_b128 v[252:255], v155
	s_add_i32 s44, s40, 0
	s_ashr_i32 s45, s44, 31
	s_lshl_b64 s[44:45], s[44:45], 12
	v_lshl_add_u64 v[80:81], v[36:37], 0, s[44:45]
	s_waitcnt lgkmcnt(0)
	v_mul_f32_e32 v210, v210, v252
	v_mul_f32_e32 v211, v211, v253
	v_mul_f32_e32 v212, v212, v254
	v_mul_f32_e32 v213, v213, v255
	global_store_dwordx4 v[80:81], v[210:213], off nt
	ds_read_b128 v[252:255], v155 offset:1024
	s_add_i32 s44, s40, 0
	s_ashr_i32 s45, s44, 31
	s_lshl_b64 s[44:45], s[44:45], 12
	v_lshl_add_u64 v[80:81], v[36:37], 0, s[44:45]
	s_waitcnt lgkmcnt(0)
	v_mul_f32_e32 v214, v214, v252
	v_mul_f32_e32 v215, v215, v253
	v_mul_f32_e32 v216, v216, v254
	v_mul_f32_e32 v217, v217, v255
	global_store_dwordx4 v[80:81], v[214:217], off offset:1024 nt
	s_add_i32 s43, s40, 8
	s_lshl_b32 s43, s43, 11
	v_add_u32_e32 v138, s43, v66
	global_load_dwordx2 v[194:195], v138, s[70:71]
	global_load_dwordx2 v[196:197], v138, s[70:71] offset:512
	global_load_dwordx2 v[198:199], v138, s[70:71] offset:1024
	global_load_dwordx2 v[200:201], v138, s[70:71] offset:1536
	v_add_u32_e32 v147, 8, v140
	v_and_b32_e32 v146, 15, v147
	v_xor_b32_e32 v146, 8, v146
	v_bfe_u32 v148, v147, 4, 4
	v_mul_lo_u32 v146, v146, s92
	v_mul_lo_u32 v148, v148, s92
	v_mov_b32_e32 v147, v146
	v_mov_b32_e32 v149, v148
	ds_write2st64_b64 v77, v[146:147], v[148:149] offset1:2
	v_add_u32_e32 v138, 0x1400, v74
	ds_read_u8 v139, v138
	v_add_u32_e32 v141, 0x1400, v73
	ds_read_u8 v140, v141
	s_add_i32 s43, s67, 128
	v_mov_b32_e32 v138, s43
	ds_read2st64_b32 v[228:229], v138 offset1:1
	ds_read_b128 v[26:29], v227 offset:10240
	ds_read_b128 v[30:33], v227 offset:10256
	v_mov_b32_e32 v38, 0
	v_mov_b32_e32 v39, 0
	v_mov_b32_e32 v40, 0
	v_mov_b32_e32 v41, 0
	v_mov_b32_e32 v42, 0
	v_mov_b32_e32 v43, 0
	v_mov_b32_e32 v44, 0
	v_mov_b32_e32 v45, 0
	v_and_b32_e32 v78, 0xffff, v23
	v_lshrrev_b32_e32 v79, 16, v23
	v_lshl_add_u32 v78, v78, 7, v150
	v_lshl_add_u32 v79, v79, 7, v151
	s_mov_b32 m0, s77
	s_add_i32 s43, s77, 0x400
	global_load_lds_dwordx4 v78, s[50:51]
	s_mov_b32 m0, s43
	s_nop 0
	global_load_lds_dwordx4 v79, s[50:51]
	s_waitcnt vmcnt(14)
; __device__ __forceinline__ bf16 f2bf(float f) { return (bf16)f2bfu(f); }
; #define TR4(p_) __builtin_amdgcn_ds_read_tr4_b64_v2i32((LAS v2i*)(p_))
; #define VDMA(st_, k_) do { _Pragma("unroll") for (int i_ = 0; i_ < 4; ++i_) { \
;         const unsigned off_ = (unsigned)((st_) >> 2) * (16384u * 128u) + (PE_ID(E, 4 * ((st_) & 3) + i_) << 7) + ((i_ & 1) ? cx1 : cx0); \
;         __builtin_amdgcn_global_load_lds((const unsigned*)(V4 + off_), (LAS unsigned*)(ldsb + BUF[k_] + 1024 * i_), 16, 0, 0); } } while (0)
; __device__ __forceinline__ void peer_v_tokens(int j, const LAS unsigned short* EL, const LAS unsigned char* AL  , const LAS float* ASC  , const LAS int* SAL  , ...
;     ...
;         for (int st = 0; st < 16; ++st) {
;             const int p = st >> 2, q = st & 3;
;             if (st < 14) VDMA(st + 2, (st + 2) % 3);
;             if (st < 14) asm volatile("s_waitcnt vmcnt(8)" ::: "memory");
;             else if (st == 14) asm volatile("s_waitcnt vmcnt(4)" ::: "memory");
;             else asm volatile("s_waitcnt vmcnt(0)" ::: "memory");
;             if (q == 0) {
; #pragma unroll
;                 for (int r = 0; r < 4; ++r) { accH[r] = 0; accL[r] = 0; } }
; #pragma unroll
;             for (int tp = 0; tp < 2; ++tp) {
;                 const v2i ao = TR4(ATL + (2 * q + tp) * 128 + 8 * s16), ah = TR4(ATL + 1024 + (2 * q + tp) * 128 + 8 * s16);
; #pragma unroll
;                 for (int r = 0; r < 4; ++r) {
;                     const v2i d = TR4(ldsb + BUF[st % 3] + 2048 * tp + roff[r]);
;                     accH[r] = __builtin_amdgcn_sdot8(d.x, ah.x, accH[r], false); accH[r] = __builtin_amdgcn_sdot8(d.y, ah.y, accH[r], false);
;                     accL[r] = __builtin_amdgcn_sdot8(d.x, ao.x, accL[r], false); accL[r] = __builtin_amdgcn_sdot8(d.y, ao.y, accL[r], false);
;                 }
;             }
;             asm volatile("s_waitcnt lgkmcnt(0)" ::: "memory");
;             if (q == 3) {
; #pragma unroll
;                 for (int r = 0; r < 4; ++r) STASH[256 * p + 16 * (grp + 4 * r) + pc] = f2bf(asc * (float)(2 * ((accH[r] << 4) + accL[r]) + sa));
;             }
;         }
	v_add_u32_e32 v54, s79, v59
	v_add_u32_e32 v55, s79, v60
	v_add_u32_e32 v56, s79, v61
	v_add_u32_e32 v57, s79, v62
	ds_read_b64_tr_b4 v[50:51], v160 offset:128
	ds_read_b64_tr_b4 v[52:53], v160 offset:1152
	ds_read_b64_tr_b4 v[130:131], v54
	ds_read_b64_tr_b4 v[132:133], v55
	ds_read_b64_tr_b4 v[134:135], v56
	ds_read_b64_tr_b4 v[136:137], v57
	s_waitcnt lgkmcnt(14)
	v_dot8c_i32_i4_e32 v38, v122, v48
	v_dot8c_i32_i4_e32 v39, v122, v46
	v_dot8c_i32_i4_e32 v40, v124, v48
	v_dot8c_i32_i4_e32 v41, v124, v46
	v_dot8c_i32_i4_e32 v42, v126, v48
	v_dot8c_i32_i4_e32 v43, v126, v46
	v_dot8c_i32_i4_e32 v44, v128, v48
	v_dot8c_i32_i4_e32 v45, v128, v46
	v_dot8c_i32_i4_e32 v38, v123, v49
	v_dot8c_i32_i4_e32 v39, v123, v47
	v_dot8c_i32_i4_e32 v40, v125, v49
	v_dot8c_i32_i4_e32 v41, v125, v47
	v_dot8c_i32_i4_e32 v42, v127, v49
	v_dot8c_i32_i4_e32 v43, v127, v47
	v_dot8c_i32_i4_e32 v44, v129, v49
	v_dot8c_i32_i4_e32 v45, v129, v47
	v_and_b32_e32 v78, 0xffff, v24
	v_lshrrev_b32_e32 v79, 16, v24
	v_lshl_add_u32 v78, v78, 7, v150
	v_lshl_add_u32 v79, v79, 7, v151
	s_mov_b32 m0, s78
	s_add_i32 s43, s78, 0x400
	global_load_lds_dwordx4 v78, s[50:51]
	s_mov_b32 m0, s43
	s_nop 0
	global_load_lds_dwordx4 v79, s[50:51]
	s_waitcnt vmcnt(14)
	v_add_u32_e32 v54, s98, v59
	v_add_u32_e32 v55, s98, v60
	v_add_u32_e32 v56, s98, v61
	v_add_u32_e32 v57, s98, v62
	ds_read_b64_tr_b4 v[46:47], v160 offset:256
	ds_read_b64_tr_b4 v[48:49], v160 offset:1280
	ds_read_b64_tr_b4 v[122:123], v54
	ds_read_b64_tr_b4 v[124:125], v55
	ds_read_b64_tr_b4 v[126:127], v56
	ds_read_b64_tr_b4 v[128:129], v57
	s_waitcnt lgkmcnt(6)
	v_dot8c_i32_i4_e32 v38, v130, v52
	v_dot8c_i32_i4_e32 v39, v130, v50
	v_dot8c_i32_i4_e32 v40, v132, v52
	v_dot8c_i32_i4_e32 v41, v132, v50
	v_dot8c_i32_i4_e32 v42, v134, v52
	v_dot8c_i32_i4_e32 v43, v134, v50
	v_dot8c_i32_i4_e32 v44, v136, v52
	v_dot8c_i32_i4_e32 v45, v136, v50
	v_dot8c_i32_i4_e32 v38, v131, v53
	v_dot8c_i32_i4_e32 v39, v131, v51
	v_dot8c_i32_i4_e32 v40, v133, v53
	v_dot8c_i32_i4_e32 v41, v133, v51
	v_dot8c_i32_i4_e32 v42, v135, v53
	v_dot8c_i32_i4_e32 v43, v135, v51
	v_dot8c_i32_i4_e32 v44, v137, v53
	v_dot8c_i32_i4_e32 v45, v137, v51
	v_and_b32_e32 v78, 0xffff, v25
	v_lshrrev_b32_e32 v79, 16, v25
	v_lshl_add_u32 v78, v78, 7, v150
	v_lshl_add_u32 v79, v79, 7, v151
	s_mov_b32 m0, s79
	s_add_i32 s43, s79, 0x400
	global_load_lds_dwordx4 v78, s[50:51]
	s_mov_b32 m0, s43
	s_nop 0
	global_load_lds_dwordx4 v79, s[50:51]
	s_waitcnt vmcnt(14)
	v_add_u32_e32 v54, s99, v59
	v_add_u32_e32 v55, s99, v60
	v_add_u32_e32 v56, s99, v61
	v_add_u32_e32 v57, s99, v62
	ds_read_b64_tr_b4 v[50:51], v160 offset:384
	ds_read_b64_tr_b4 v[52:53], v160 offset:1408
	ds_read_b64_tr_b4 v[130:131], v54
	ds_read_b64_tr_b4 v[132:133], v55
	ds_read_b64_tr_b4 v[134:135], v56
	ds_read_b64_tr_b4 v[136:137], v57
	s_waitcnt lgkmcnt(6)
	v_dot8c_i32_i4_e32 v38, v122, v48
	v_dot8c_i32_i4_e32 v39, v122, v46
	v_dot8c_i32_i4_e32 v40, v124, v48
	v_dot8c_i32_i4_e32 v41, v124, v46
	v_dot8c_i32_i4_e32 v42, v126, v48
	v_dot8c_i32_i4_e32 v43, v126, v46
	v_dot8c_i32_i4_e32 v44, v128, v48
	v_dot8c_i32_i4_e32 v45, v128, v46
	v_dot8c_i32_i4_e32 v38, v123, v49
	v_dot8c_i32_i4_e32 v39, v123, v47
	v_dot8c_i32_i4_e32 v40, v125, v49
	v_dot8c_i32_i4_e32 v41, v125, v47
	v_dot8c_i32_i4_e32 v42, v127, v49
	v_dot8c_i32_i4_e32 v43, v127, v47
	v_dot8c_i32_i4_e32 v44, v129, v49
	v_dot8c_i32_i4_e32 v45, v129, v47
	s_waitcnt lgkmcnt(15)
	v_and_b32_e32 v78, 0xffff, v26
	v_lshrrev_b32_e32 v79, 16, v26
	v_lshl_add_u32 v78, v78, 7, v150
	v_lshl_add_u32 v79, v79, 7, v151
	s_mov_b32 m0, s98
	s_add_i32 s43, s98, 0x400
	global_load_lds_dwordx4 v78, s[50:51]
	s_mov_b32 m0, s43
	s_nop 0
	global_load_lds_dwordx4 v79, s[50:51]
	s_waitcnt vmcnt(14)
	v_add_u32_e32 v54, s76, v59
	v_add_u32_e32 v55, s76, v60
	v_add_u32_e32 v56, s76, v61
	v_add_u32_e32 v57, s76, v62
	ds_read_b64_tr_b4 v[46:47], v160 offset:512
	ds_read_b64_tr_b4 v[48:49], v160 offset:1536
	ds_read_b64_tr_b4 v[122:123], v54
	ds_read_b64_tr_b4 v[124:125], v55
	ds_read_b64_tr_b4 v[126:127], v56
	ds_read_b64_tr_b4 v[128:129], v57
	s_waitcnt lgkmcnt(6)
	v_dot8c_i32_i4_e32 v38, v130, v52
	v_dot8c_i32_i4_e32 v39, v130, v50
	v_dot8c_i32_i4_e32 v40, v132, v52
	v_dot8c_i32_i4_e32 v41, v132, v50
	v_dot8c_i32_i4_e32 v42, v134, v52
	v_dot8c_i32_i4_e32 v43, v134, v50
	v_dot8c_i32_i4_e32 v44, v136, v52
	v_dot8c_i32_i4_e32 v45, v136, v50
	v_dot8c_i32_i4_e32 v38, v131, v53
	v_dot8c_i32_i4_e32 v39, v131, v51
	v_dot8c_i32_i4_e32 v40, v133, v53
	v_dot8c_i32_i4_e32 v41, v133, v51
	v_dot8c_i32_i4_e32 v42, v135, v53
	v_dot8c_i32_i4_e32 v43, v135, v51
	v_dot8c_i32_i4_e32 v44, v137, v53
	v_dot8c_i32_i4_e32 v45, v137, v51
	v_and_b32_e32 v78, 0xffff, v27
	v_lshrrev_b32_e32 v79, 16, v27
	v_lshl_add_u32 v78, v78, 7, v150
	v_lshl_add_u32 v79, v79, 7, v151
	s_mov_b32 m0, s99
	s_add_i32 s43, s99, 0x400
	global_load_lds_dwordx4 v78, s[50:51]
	s_mov_b32 m0, s43
	s_nop 0
	global_load_lds_dwordx4 v79, s[50:51]
	s_waitcnt vmcnt(8)
	v_add_u32_e32 v54, s77, v59
	v_add_u32_e32 v55, s77, v60
	v_add_u32_e32 v56, s77, v61
	v_add_u32_e32 v57, s77, v62
	ds_read_b64_tr_b4 v[50:51], v160 offset:640
	ds_read_b64_tr_b4 v[52:53], v160 offset:1664
	ds_read_b64_tr_b4 v[130:131], v54
	ds_read_b64_tr_b4 v[132:133], v55
	ds_read_b64_tr_b4 v[134:135], v56
	ds_read_b64_tr_b4 v[136:137], v57
	s_waitcnt lgkmcnt(6)
	v_dot8c_i32_i4_e32 v38, v122, v48
	v_dot8c_i32_i4_e32 v39, v122, v46
	v_dot8c_i32_i4_e32 v40, v124, v48
	v_dot8c_i32_i4_e32 v41, v124, v46
	v_dot8c_i32_i4_e32 v42, v126, v48
	v_dot8c_i32_i4_e32 v43, v126, v46
	v_dot8c_i32_i4_e32 v44, v128, v48
	v_dot8c_i32_i4_e32 v45, v128, v46
	v_dot8c_i32_i4_e32 v38, v123, v49
	v_dot8c_i32_i4_e32 v39, v123, v47
	v_dot8c_i32_i4_e32 v40, v125, v49
	v_dot8c_i32_i4_e32 v41, v125, v47
	v_dot8c_i32_i4_e32 v42, v127, v49
	v_dot8c_i32_i4_e32 v43, v127, v47
	v_dot8c_i32_i4_e32 v44, v129, v49
	v_dot8c_i32_i4_e32 v45, v129, v47
	s_waitcnt lgkmcnt(15)
; __device__ __forceinline__ bf16 f2bf(float f) { return (bf16)f2bfu(f); }
; #define TR4(p_) __builtin_amdgcn_ds_read_tr4_b64_v2i32((LAS v2i*)(p_))
; __device__ __forceinline__ void peer_v_tokens(int j, const LAS unsigned short* EL, const LAS unsigned char* AL  , const LAS float* ASC  , const LAS int* SAL  , ...
;     ...
;         for (int st = 0; st < 16; ++st) {
;             const int p = st >> 2, q = st & 3;
;             if (st < 14) VDMA(st + 2, (st + 2) % 3);
;             if (st < 14) asm volatile("s_waitcnt vmcnt(8)" ::: "memory");
;             else if (st == 14) asm volatile("s_waitcnt vmcnt(4)" ::: "memory");
;             else asm volatile("s_waitcnt vmcnt(0)" ::: "memory");
;             if (q == 0) {
; #pragma unroll
;                 for (int r = 0; r < 4; ++r) { accH[r] = 0; accL[r] = 0; } }
; #pragma unroll
;             for (int tp = 0; tp < 2; ++tp) {
;                 const v2i ao = TR4(ATL + (2 * q + tp) * 128 + 8 * s16), ah = TR4(ATL + 1024 + (2 * q + tp) * 128 + 8 * s16);
; #pragma unroll
;                 for (int r = 0; r < 4; ++r) {
;                     const v2i d = TR4(ldsb + BUF[st % 3] + 2048 * tp + roff[r]);
;                     accH[r] = __builtin_amdgcn_sdot8(d.x, ah.x, accH[r], false); accH[r] = __builtin_amdgcn_sdot8(d.y, ah.y, accH[r], false);
;                     accL[r] = __builtin_amdgcn_sdot8(d.x, ao.x, accL[r], false); accL[r] = __builtin_amdgcn_sdot8(d.y, ao.y, accL[r], false);
;                 }
;             }
;             asm volatile("s_waitcnt lgkmcnt(0)" ::: "memory");
;             if (q == 3) {
; #pragma unroll
;                 for (int r = 0; r < 4; ++r) STASH[256 * p + 16 * (grp + 4 * r) + pc] = f2bf(asc * (float)(2 * ((accH[r] << 4) + accL[r]) + sa));
;             }
;         }
;     ...
;             float4* op = (float4*)(outp + (size_t)t * D) + lane;
; #pragma unroll
;             for (int jq = 0; jq < 4; ++jq) { typedef float f4v __attribute__((ext_vector_type(4))); f4v o4; o4.x = v[jq].x * r3 * gv[jq].x; o4.y = v[jq].y * r3 * gv[jq].y; o4.z = v[jq].z * r3 * gv[jq].z; o4.w = v[jq].w * r3 * gv[jq].w;
;                 __builtin_nontemporal_store(o4, (f4v*)op + 64 * jq); }
	v_add_u32_e32 v143, 8, v139
	v_and_b32_e32 v142, 15, v143
	v_xor_b32_e32 v142, 8, v142
	v_bfe_u32 v144, v143, 4, 4
	v_mul_lo_u32 v142, v142, s92
	v_mul_lo_u32 v144, v144, s92
	v_mov_b32_e32 v143, v142
	v_mov_b32_e32 v145, v144
	ds_write2st64_b64 v159, v[142:143], v[144:145] offset1:2
	v_and_b32_e32 v78, 0xffff, v28
	v_lshrrev_b32_e32 v79, 16, v28
	v_lshl_add_u32 v78, v78, 7, v150
	v_lshl_add_u32 v79, v79, 7, v151
	s_mov_b32 m0, s76
	s_add_i32 s43, s76, 0x400
	global_load_lds_dwordx4 v78, s[50:51]
	s_mov_b32 m0, s43
	s_nop 0
	global_load_lds_dwordx4 v79, s[50:51]
	s_waitcnt vmcnt(8)
	v_add_u32_e32 v54, s78, v59
	v_add_u32_e32 v55, s78, v60
	v_add_u32_e32 v56, s78, v61
	v_add_u32_e32 v57, s78, v62
	ds_read_b64_tr_b4 v[46:47], v160 offset:768
	ds_read_b64_tr_b4 v[48:49], v160 offset:1792
	ds_read_b64_tr_b4 v[122:123], v54
	ds_read_b64_tr_b4 v[124:125], v55
	ds_read_b64_tr_b4 v[126:127], v56
	ds_read_b64_tr_b4 v[128:129], v57
	s_waitcnt lgkmcnt(7)
	v_dot8c_i32_i4_e32 v38, v130, v52
	v_dot8c_i32_i4_e32 v39, v130, v50
	v_dot8c_i32_i4_e32 v40, v132, v52
	v_dot8c_i32_i4_e32 v41, v132, v50
	v_dot8c_i32_i4_e32 v42, v134, v52
	v_dot8c_i32_i4_e32 v43, v134, v50
	v_dot8c_i32_i4_e32 v44, v136, v52
	v_dot8c_i32_i4_e32 v45, v136, v50
	v_dot8c_i32_i4_e32 v38, v131, v53
	v_dot8c_i32_i4_e32 v39, v131, v51
	v_dot8c_i32_i4_e32 v40, v133, v53
	v_dot8c_i32_i4_e32 v41, v133, v51
	v_dot8c_i32_i4_e32 v42, v135, v53
	v_dot8c_i32_i4_e32 v43, v135, v51
	v_dot8c_i32_i4_e32 v44, v137, v53
	v_dot8c_i32_i4_e32 v45, v137, v51
	v_and_b32_e32 v78, 0xffff, v29
	v_lshrrev_b32_e32 v79, 16, v29
	v_lshl_add_u32 v78, v78, 7, v150
	v_lshl_add_u32 v79, v79, 7, v151
	s_mov_b32 m0, s77
	s_add_i32 s43, s77, 0x400
	global_load_lds_dwordx4 v78, s[50:51]
	s_mov_b32 m0, s43
	s_nop 0
	global_load_lds_dwordx4 v79, s[50:51]
	s_waitcnt vmcnt(8)
	v_add_u32_e32 v54, s79, v59
	v_add_u32_e32 v55, s79, v60
	v_add_u32_e32 v56, s79, v61
	v_add_u32_e32 v57, s79, v62
	ds_read_b64_tr_b4 v[50:51], v160 offset:896
	ds_read_b64_tr_b4 v[52:53], v160 offset:1920
	ds_read_b64_tr_b4 v[130:131], v54
	ds_read_b64_tr_b4 v[132:133], v55
	ds_read_b64_tr_b4 v[134:135], v56
	ds_read_b64_tr_b4 v[136:137], v57
	s_waitcnt lgkmcnt(6)
	v_dot8c_i32_i4_e32 v38, v122, v48
	v_dot8c_i32_i4_e32 v39, v122, v46
	v_dot8c_i32_i4_e32 v40, v124, v48
	v_dot8c_i32_i4_e32 v41, v124, v46
	v_dot8c_i32_i4_e32 v42, v126, v48
	v_dot8c_i32_i4_e32 v43, v126, v46
	v_dot8c_i32_i4_e32 v44, v128, v48
	v_dot8c_i32_i4_e32 v45, v128, v46
	v_dot8c_i32_i4_e32 v38, v123, v49
	v_dot8c_i32_i4_e32 v39, v123, v47
	v_dot8c_i32_i4_e32 v40, v125, v49
	v_dot8c_i32_i4_e32 v41, v125, v47
	v_dot8c_i32_i4_e32 v42, v127, v49
	v_dot8c_i32_i4_e32 v43, v127, v47
	v_dot8c_i32_i4_e32 v44, v129, v49
	v_dot8c_i32_i4_e32 v45, v129, v47
	v_and_b32_e32 v78, 0xffff, v30
	v_lshrrev_b32_e32 v79, 16, v30
	v_lshl_add_u32 v78, v78, 7, v150
	v_lshl_add_u32 v79, v79, 7, v151
	s_mov_b32 m0, s78
	s_add_i32 s43, s78, 0x400
	global_load_lds_dwordx4 v78, s[50:51]
	s_mov_b32 m0, s43
	s_nop 0
	global_load_lds_dwordx4 v79, s[50:51]
	s_waitcnt vmcnt(8)
	v_add_u32_e32 v54, s98, v59
	v_add_u32_e32 v55, s98, v60
	v_add_u32_e32 v56, s98, v61
	v_add_u32_e32 v57, s98, v62
	ds_read_b64_tr_b4 v[46:47], v160
	ds_read_b64_tr_b4 v[48:49], v160 offset:1024
	ds_read_b64_tr_b4 v[122:123], v54
	ds_read_b64_tr_b4 v[124:125], v55
	ds_read_b64_tr_b4 v[126:127], v56
	ds_read_b64_tr_b4 v[128:129], v57
	s_waitcnt lgkmcnt(6)
	v_dot8c_i32_i4_e32 v38, v130, v52
	v_dot8c_i32_i4_e32 v39, v130, v50
	v_dot8c_i32_i4_e32 v40, v132, v52
	v_dot8c_i32_i4_e32 v41, v132, v50
	v_dot8c_i32_i4_e32 v42, v134, v52
	v_dot8c_i32_i4_e32 v43, v134, v50
	v_dot8c_i32_i4_e32 v44, v136, v52
	v_dot8c_i32_i4_e32 v45, v136, v50
	v_dot8c_i32_i4_e32 v38, v131, v53
	v_dot8c_i32_i4_e32 v39, v131, v51
	v_dot8c_i32_i4_e32 v40, v133, v53
	v_dot8c_i32_i4_e32 v41, v133, v51
	v_dot8c_i32_i4_e32 v42, v135, v53
	v_dot8c_i32_i4_e32 v43, v135, v51
	v_dot8c_i32_i4_e32 v44, v137, v53
	v_dot8c_i32_i4_e32 v45, v137, v51
	s_nop 3
	s_waitcnt lgkmcnt(15)
	v_lshlrev_b32_e32 v38, 5, v38
	v_lshlrev_b32_e32 v39, 1, v39
	v_add3_u32 v38, v39, v229, v38
	v_cvt_f32_i32_e32 v38, v38
	v_mul_f32_e32 v38, v228, v38
	v_lshlrev_b32_e32 v40, 5, v40
	v_lshlrev_b32_e32 v41, 1, v41
	v_add3_u32 v40, v41, v229, v40
	v_cvt_f32_i32_e32 v40, v40
	v_mul_f32_e32 v40, v228, v40
	v_lshlrev_b32_e32 v42, 5, v42
	v_lshlrev_b32_e32 v43, 1, v43
	v_add3_u32 v42, v43, v229, v42
	v_cvt_f32_i32_e32 v42, v42
	v_mul_f32_e32 v42, v228, v42
	v_lshlrev_b32_e32 v44, 5, v44
	v_lshlrev_b32_e32 v45, 1, v45
	v_add3_u32 v44, v45, v229, v44
	v_cvt_f32_i32_e32 v44, v44
	v_mul_f32_e32 v44, v228, v44
	v_cvt_pk_bf16_f32 v236, v38, v40
	v_cvt_pk_bf16_f32 v237, v42, v44
	ds_read_b128 v[252:255], v156
	s_add_i32 s44, s40, 0
	s_ashr_i32 s45, s44, 31
	s_lshl_b64 s[44:45], s[44:45], 12
	v_lshl_add_u64 v[80:81], v[36:37], 0, s[44:45]
	s_waitcnt lgkmcnt(0)
	v_mul_f32_e32 v218, v218, v252
	v_mul_f32_e32 v219, v219, v253
	v_mul_f32_e32 v220, v220, v254
	v_mul_f32_e32 v221, v221, v255
	global_store_dwordx4 v[80:81], v[218:221], off offset:2048 nt
	ds_read_b128 v[252:255], v156 offset:1024
	s_add_i32 s44, s40, 0
	s_ashr_i32 s45, s44, 31
	s_lshl_b64 s[44:45], s[44:45], 12
	v_lshl_add_u64 v[80:81], v[36:37], 0, s[44:45]
	s_waitcnt lgkmcnt(0)
; #define LAS __attribute__((address_space(3)))
; __device__ __forceinline__ bf16 f2bf(float f) { return (bf16)f2bfu(f); }
; __device__ __forceinline__ void peer_v_tokens(int j, const LAS unsigned short* EL, const LAS unsigned char* AL  , const LAS float* ASC  , const LAS int* SAL  , ...
;     ...
;         for (int m = 0; m < 2; ++m) {
;             const int idx = lane + 64 * m, tau = idx >> 4, sr = idx & 15, k = 16 * (sr & 7) + 2 * tau + (sr >> 3);
;             const int aq = (int)*(const LAS signed char*)(AL + tl * 128 + k); const int tq = aq + 8;
;             const unsigned lo = (((unsigned)tq & 15u) ^ 8u) * 0x11111111u, hi = ((unsigned)(tq >> 4) & 15u) * 0x11111111u;
;             typedef unsigned u2v __attribute__((ext_vector_type(2)));
;             u2v l2; l2.x = lo; l2.y = lo; u2v h2; h2.x = hi; h2.y = hi;
;             *(LAS u2v*)(ATL + 8 * idx) = l2; *(LAS u2v*)(ATL + 1024 + 8 * idx) = h2;
;         }
;     ...
;                 for (int r = 0; r < 4; ++r) STASH[256 * p + 16 * (grp + 4 * r) + pc] = f2bf(asc * (float)(2 * ((accH[r] << 4) + accL[r]) + sa));
;     ...
;             for (int jq = 0; jq < 4; ++jq) { typedef unsigned u2v __attribute__((ext_vector_type(2))); const u2v pw = *(const LAS u2v*)(STASH + 4 * lane + 256 * jq); const uint2 hw = hv[jq];
;     ...
;             float4* op = (float4*)(outp + (size_t)t * D) + lane;
; #pragma unroll
;             for (int jq = 0; jq < 4; ++jq) { typedef float f4v __attribute__((ext_vector_type(4))); f4v o4; o4.x = v[jq].x * r3 * gv[jq].x; o4.y = v[jq].y * r3 * gv[jq].y; o4.z = v[jq].z * r3 * gv[jq].z; o4.w = v[jq].w * r3 * gv[jq].w;
;                 __builtin_nontemporal_store(o4, (f4v*)op + 64 * jq); }
	v_mul_f32_e32 v222, v222, v252
	v_mul_f32_e32 v223, v223, v253
	v_mul_f32_e32 v224, v224, v254
	v_mul_f32_e32 v225, v225, v255
	global_store_dwordx4 v[80:81], v[222:225], off offset:3072 nt
	v_add_u32_e32 v147, 8, v140
	v_and_b32_e32 v146, 15, v147
	v_xor_b32_e32 v146, 8, v146
	v_bfe_u32 v148, v147, 4, 4
	v_mul_lo_u32 v146, v146, s92
	v_mul_lo_u32 v148, v148, s92
	v_mov_b32_e32 v147, v146
	v_mov_b32_e32 v149, v148
	ds_write2st64_b64 v77, v[146:147], v[148:149] offset1:2
	v_add_u32_e32 v138, 0x1800, v74
	ds_read_u8 v139, v138
	v_add_u32_e32 v141, 0x1800, v73
	ds_read_u8 v140, v141
	s_add_i32 s43, s67, 160
	v_mov_b32_e32 v138, s43
	ds_read2st64_b32 v[228:229], v138 offset1:1
	ds_read_b128 v[18:21], v227 offset:12288
	ds_read_b128 v[22:25], v227 offset:12304
	v_mov_b32_e32 v38, 0
	v_mov_b32_e32 v39, 0
	v_mov_b32_e32 v40, 0
	v_mov_b32_e32 v41, 0
	v_mov_b32_e32 v42, 0
	v_mov_b32_e32 v43, 0
	v_mov_b32_e32 v44, 0
	v_mov_b32_e32 v45, 0
	v_and_b32_e32 v78, 0xffff, v31
	v_lshrrev_b32_e32 v79, 16, v31
	v_lshl_add_u32 v78, v78, 7, v150
	v_lshl_add_u32 v79, v79, 7, v151
	s_mov_b32 m0, s79
	s_add_i32 s43, s79, 0x400
	global_load_lds_dwordx4 v78, s[50:51]
	s_mov_b32 m0, s43
	s_nop 0
	global_load_lds_dwordx4 v79, s[50:51]
	s_waitcnt vmcnt(10)
	v_add_u32_e32 v54, s99, v59
	v_add_u32_e32 v55, s99, v60
	v_add_u32_e32 v56, s99, v61
	v_add_u32_e32 v57, s99, v62
	ds_read_b64_tr_b4 v[50:51], v160 offset:128
	ds_read_b64_tr_b4 v[52:53], v160 offset:1152
	ds_read_b64_tr_b4 v[130:131], v54
	ds_read_b64_tr_b4 v[132:133], v55
	ds_read_b64_tr_b4 v[134:135], v56
	ds_read_b64_tr_b4 v[136:137], v57
	s_waitcnt lgkmcnt(14)
	v_dot8c_i32_i4_e32 v38, v122, v48
	v_dot8c_i32_i4_e32 v39, v122, v46
	v_dot8c_i32_i4_e32 v40, v124, v48
	v_dot8c_i32_i4_e32 v41, v124, v46
	v_dot8c_i32_i4_e32 v42, v126, v48
	v_dot8c_i32_i4_e32 v43, v126, v46
	v_dot8c_i32_i4_e32 v44, v128, v48
	v_dot8c_i32_i4_e32 v45, v128, v46
	v_dot8c_i32_i4_e32 v38, v123, v49
	v_dot8c_i32_i4_e32 v39, v123, v47
	v_dot8c_i32_i4_e32 v40, v125, v49
	v_dot8c_i32_i4_e32 v41, v125, v47
	v_dot8c_i32_i4_e32 v42, v127, v49
	v_dot8c_i32_i4_e32 v43, v127, v47
	v_dot8c_i32_i4_e32 v44, v129, v49
	v_dot8c_i32_i4_e32 v45, v129, v47
	v_and_b32_e32 v78, 0xffff, v32
	v_lshrrev_b32_e32 v79, 16, v32
	v_lshl_add_u32 v78, v78, 7, v150
	v_lshl_add_u32 v79, v79, 7, v151
	s_mov_b32 m0, s98
	s_add_i32 s43, s98, 0x400
	global_load_lds_dwordx4 v78, s[50:51]
	s_mov_b32 m0, s43
	s_nop 0
	global_load_lds_dwordx4 v79, s[50:51]
	s_waitcnt vmcnt(10)
	v_add_u32_e32 v54, s76, v59
	v_add_u32_e32 v55, s76, v60
	v_add_u32_e32 v56, s76, v61
	v_add_u32_e32 v57, s76, v62
	ds_read_b64_tr_b4 v[46:47], v160 offset:256
	ds_read_b64_tr_b4 v[48:49], v160 offset:1280
	ds_read_b64_tr_b4 v[122:123], v54
	ds_read_b64_tr_b4 v[124:125], v55
	ds_read_b64_tr_b4 v[126:127], v56
	ds_read_b64_tr_b4 v[128:129], v57
	s_waitcnt lgkmcnt(6)
	v_dot8c_i32_i4_e32 v38, v130, v52
	v_dot8c_i32_i4_e32 v39, v130, v50
	v_dot8c_i32_i4_e32 v40, v132, v52
	v_dot8c_i32_i4_e32 v41, v132, v50
	v_dot8c_i32_i4_e32 v42, v134, v52
	v_dot8c_i32_i4_e32 v43, v134, v50
	v_dot8c_i32_i4_e32 v44, v136, v52
	v_dot8c_i32_i4_e32 v45, v136, v50
	v_dot8c_i32_i4_e32 v38, v131, v53
	v_dot8c_i32_i4_e32 v39, v131, v51
	v_dot8c_i32_i4_e32 v40, v133, v53
	v_dot8c_i32_i4_e32 v41, v133, v51
	v_dot8c_i32_i4_e32 v42, v135, v53
	v_dot8c_i32_i4_e32 v43, v135, v51
	v_dot8c_i32_i4_e32 v44, v137, v53
	v_dot8c_i32_i4_e32 v45, v137, v51
	ds_write_b16 v65, v170
	ds_write_b16_d16_hi v65, v170 offset:128
	ds_write_b16 v65, v171 offset:256
	ds_write_b16_d16_hi v65, v171 offset:384
	ds_write_b16 v65, v172 offset:512
	ds_write_b16_d16_hi v65, v172 offset:640
	ds_write_b16 v65, v173 offset:768
	ds_write_b16_d16_hi v65, v173 offset:896
	ds_write_b16 v65, v174 offset:1024
	ds_write_b16_d16_hi v65, v174 offset:1152
	ds_write_b16 v65, v175 offset:1280
	ds_write_b16_d16_hi v65, v175 offset:1408
	ds_write_b16 v65, v176 offset:1536
	ds_write_b16_d16_hi v65, v176 offset:1664
	ds_write_b16 v65, v177 offset:1792
	ds_write_b16_d16_hi v65, v177 offset:1920
	ds_read_b64 v[202:203], v154
	ds_read_b64 v[204:205], v154 offset:512
	ds_read_b64 v[206:207], v154 offset:1024
	ds_read_b64 v[208:209], v154 offset:1536
	v_and_b32_e32 v78, 0xffff, v33
	v_lshrrev_b32_e32 v79, 16, v33
	v_lshl_add_u32 v78, v78, 7, v150
	v_lshl_add_u32 v79, v79, 7, v151
	s_mov_b32 m0, s99
	s_add_i32 s43, s99, 0x400
	global_load_lds_dwordx4 v78, s[50:51]
	s_mov_b32 m0, s43
	s_nop 0
	global_load_lds_dwordx4 v79, s[50:51]
	s_waitcnt vmcnt(10)
	v_add_u32_e32 v54, s77, v59
	v_add_u32_e32 v55, s77, v60
	v_add_u32_e32 v56, s77, v61
	v_add_u32_e32 v57, s77, v62
	ds_read_b64_tr_b4 v[50:51], v160 offset:384
	ds_read_b64_tr_b4 v[52:53], v160 offset:1408
	ds_read_b64_tr_b4 v[130:131], v54
	ds_read_b64_tr_b4 v[132:133], v55
	ds_read_b64_tr_b4 v[134:135], v56
	ds_read_b64_tr_b4 v[136:137], v57
	s_waitcnt lgkmcnt(15)
	v_dot8c_i32_i4_e32 v38, v122, v48
	v_dot8c_i32_i4_e32 v39, v122, v46
	v_dot8c_i32_i4_e32 v40, v124, v48
	v_dot8c_i32_i4_e32 v41, v124, v46
	v_dot8c_i32_i4_e32 v42, v126, v48
	v_dot8c_i32_i4_e32 v43, v126, v46
	v_dot8c_i32_i4_e32 v44, v128, v48
	v_dot8c_i32_i4_e32 v45, v128, v46
	v_dot8c_i32_i4_e32 v38, v123, v49
	v_dot8c_i32_i4_e32 v39, v123, v47
	v_dot8c_i32_i4_e32 v40, v125, v49
	v_dot8c_i32_i4_e32 v41, v125, v47
	v_dot8c_i32_i4_e32 v42, v127, v49
	v_dot8c_i32_i4_e32 v43, v127, v47
	v_dot8c_i32_i4_e32 v44, v129, v49
	v_dot8c_i32_i4_e32 v45, v129, v47
	s_waitcnt lgkmcnt(15)
	v_and_b32_e32 v78, 0xffff, v18
	v_lshrrev_b32_e32 v79, 16, v18
	v_lshl_add_u32 v78, v78, 7, v150
	v_lshl_add_u32 v79, v79, 7, v151
	s_mov_b32 m0, s76
	s_add_i32 s43, s76, 0x400
	global_load_lds_dwordx4 v78, s[50:51]
	s_mov_b32 m0, s43
	s_nop 0
	global_load_lds_dwordx4 v79, s[50:51]
	s_waitcnt vmcnt(10)
; #define LAS __attribute__((address_space(3)))
; __device__ __forceinline__ bf16 f2bf(float f) { return (bf16)f2bfu(f); }
; __device__ __forceinline__ void peer_v_tokens(int j, const LAS unsigned short* EL, const LAS unsigned char* AL  , const LAS float* ASC  , const LAS int* SAL  , ...
;     ...
;         for (int m = 0; m < 2; ++m) {
;             const int idx = lane + 64 * m, tau = idx >> 4, sr = idx & 15, k = 16 * (sr & 7) + 2 * tau + (sr >> 3);
;             const int aq = (int)*(const LAS signed char*)(AL + tl * 128 + k); const int tq = aq + 8;
;             const unsigned lo = (((unsigned)tq & 15u) ^ 8u) * 0x11111111u, hi = ((unsigned)(tq >> 4) & 15u) * 0x11111111u;
;             typedef unsigned u2v __attribute__((ext_vector_type(2)));
;             u2v l2; l2.x = lo; l2.y = lo; u2v h2; h2.x = hi; h2.y = hi;
;             *(LAS u2v*)(ATL + 8 * idx) = l2; *(LAS u2v*)(ATL + 1024 + 8 * idx) = h2;
;         }
;     ...
;         for (int st = 0; st < 16; ++st) {
;             const int p = st >> 2, q = st & 3;
;             if (st < 14) VDMA(st + 2, (st + 2) % 3);
;             if (st < 14) asm volatile("s_waitcnt vmcnt(8)" ::: "memory");
;             else if (st == 14) asm volatile("s_waitcnt vmcnt(4)" ::: "memory");
;             else asm volatile("s_waitcnt vmcnt(0)" ::: "memory");
;             if (q == 0) {
; #pragma unroll
;                 for (int r = 0; r < 4; ++r) { accH[r] = 0; accL[r] = 0; } }
; #pragma unroll
;             for (int tp = 0; tp < 2; ++tp) {
;                 const v2i ao = TR4(ATL + (2 * q + tp) * 128 + 8 * s16), ah = TR4(ATL + 1024 + (2 * q + tp) * 128 + 8 * s16);
; #pragma unroll
;                 for (int r = 0; r < 4; ++r) {
;                     const v2i d = TR4(ldsb + BUF[st % 3] + 2048 * tp + roff[r]);
;                     accH[r] = __builtin_amdgcn_sdot8(d.x, ah.x, accH[r], false); accH[r] = __builtin_amdgcn_sdot8(d.y, ah.y, accH[r], false);
;                     accL[r] = __builtin_amdgcn_sdot8(d.x, ao.x, accL[r], false); accL[r] = __builtin_amdgcn_sdot8(d.y, ao.y, accL[r], false);
;                 }
;             }
;             asm volatile("s_waitcnt lgkmcnt(0)" ::: "memory");
;             if (q == 3) {
; #pragma unroll
;                 for (int r = 0; r < 4; ++r) STASH[256 * p + 16 * (grp + 4 * r) + pc] = f2bf(asc * (float)(2 * ((accH[r] << 4) + accL[r]) + sa));
;             }
;         }
	v_add_u32_e32 v54, s78, v59
	v_add_u32_e32 v55, s78, v60
	v_add_u32_e32 v56, s78, v61
	v_add_u32_e32 v57, s78, v62
	ds_read_b64_tr_b4 v[46:47], v160 offset:512
	ds_read_b64_tr_b4 v[48:49], v160 offset:1536
	ds_read_b64_tr_b4 v[122:123], v54
	ds_read_b64_tr_b4 v[124:125], v55
	ds_read_b64_tr_b4 v[126:127], v56
	ds_read_b64_tr_b4 v[128:129], v57
	s_waitcnt lgkmcnt(6)
	v_dot8c_i32_i4_e32 v38, v130, v52
	v_dot8c_i32_i4_e32 v39, v130, v50
	v_dot8c_i32_i4_e32 v40, v132, v52
	v_dot8c_i32_i4_e32 v41, v132, v50
	v_dot8c_i32_i4_e32 v42, v134, v52
	v_dot8c_i32_i4_e32 v43, v134, v50
	v_dot8c_i32_i4_e32 v44, v136, v52
	v_dot8c_i32_i4_e32 v45, v136, v50
	v_dot8c_i32_i4_e32 v38, v131, v53
	v_dot8c_i32_i4_e32 v39, v131, v51
	v_dot8c_i32_i4_e32 v40, v133, v53
	v_dot8c_i32_i4_e32 v41, v133, v51
	v_dot8c_i32_i4_e32 v42, v135, v53
	v_dot8c_i32_i4_e32 v43, v135, v51
	v_dot8c_i32_i4_e32 v44, v137, v53
	v_dot8c_i32_i4_e32 v45, v137, v51
	v_and_b32_e32 v78, 0xffff, v19
	v_lshrrev_b32_e32 v79, 16, v19
	v_lshl_add_u32 v78, v78, 7, v150
	v_lshl_add_u32 v79, v79, 7, v151
	s_mov_b32 m0, s77
	s_add_i32 s43, s77, 0x400
	global_load_lds_dwordx4 v78, s[50:51]
	s_mov_b32 m0, s43
	s_nop 0
	global_load_lds_dwordx4 v79, s[50:51]
	s_waitcnt vmcnt(8)
	v_add_u32_e32 v54, s79, v59
	v_add_u32_e32 v55, s79, v60
	v_add_u32_e32 v56, s79, v61
	v_add_u32_e32 v57, s79, v62
	ds_read_b64_tr_b4 v[50:51], v160 offset:640
	ds_read_b64_tr_b4 v[52:53], v160 offset:1664
	ds_read_b64_tr_b4 v[130:131], v54
	ds_read_b64_tr_b4 v[132:133], v55
	ds_read_b64_tr_b4 v[134:135], v56
	ds_read_b64_tr_b4 v[136:137], v57
	s_waitcnt lgkmcnt(6)
	v_dot8c_i32_i4_e32 v38, v122, v48
	v_dot8c_i32_i4_e32 v39, v122, v46
	v_dot8c_i32_i4_e32 v40, v124, v48
	v_dot8c_i32_i4_e32 v41, v124, v46
	v_dot8c_i32_i4_e32 v42, v126, v48
	v_dot8c_i32_i4_e32 v43, v126, v46
	v_dot8c_i32_i4_e32 v44, v128, v48
	v_dot8c_i32_i4_e32 v45, v128, v46
	v_dot8c_i32_i4_e32 v38, v123, v49
	v_dot8c_i32_i4_e32 v39, v123, v47
	v_dot8c_i32_i4_e32 v40, v125, v49
	v_dot8c_i32_i4_e32 v41, v125, v47
	v_dot8c_i32_i4_e32 v42, v127, v49
	v_dot8c_i32_i4_e32 v43, v127, v47
	v_dot8c_i32_i4_e32 v44, v129, v49
	v_dot8c_i32_i4_e32 v45, v129, v47
	s_waitcnt lgkmcnt(15)
	v_add_u32_e32 v143, 8, v139
	v_and_b32_e32 v142, 15, v143
	v_xor_b32_e32 v142, 8, v142
	v_bfe_u32 v144, v143, 4, 4
	v_mul_lo_u32 v142, v142, s92
	v_mul_lo_u32 v144, v144, s92
	v_mov_b32_e32 v143, v142
	v_mov_b32_e32 v145, v144
	ds_write2st64_b64 v159, v[142:143], v[144:145] offset1:2
	v_and_b32_e32 v78, 0xffff, v20
	v_lshrrev_b32_e32 v79, 16, v20
	v_lshl_add_u32 v78, v78, 7, v150
	v_lshl_add_u32 v79, v79, 7, v151
	s_mov_b32 m0, s78
	s_add_i32 s43, s78, 0x400
	global_load_lds_dwordx4 v78, s[50:51]
	s_mov_b32 m0, s43
	s_nop 0
	global_load_lds_dwordx4 v79, s[50:51]
	s_waitcnt vmcnt(8)
	v_add_u32_e32 v54, s98, v59
	v_add_u32_e32 v55, s98, v60
	v_add_u32_e32 v56, s98, v61
	v_add_u32_e32 v57, s98, v62
	ds_read_b64_tr_b4 v[46:47], v160 offset:768
	ds_read_b64_tr_b4 v[48:49], v160 offset:1792
	ds_read_b64_tr_b4 v[122:123], v54
	ds_read_b64_tr_b4 v[124:125], v55
	ds_read_b64_tr_b4 v[126:127], v56
	ds_read_b64_tr_b4 v[128:129], v57
	s_waitcnt lgkmcnt(7)
	v_dot8c_i32_i4_e32 v38, v130, v52
	v_dot8c_i32_i4_e32 v39, v130, v50
	v_dot8c_i32_i4_e32 v40, v132, v52
	v_dot8c_i32_i4_e32 v41, v132, v50
	v_dot8c_i32_i4_e32 v42, v134, v52
	v_dot8c_i32_i4_e32 v43, v134, v50
	v_dot8c_i32_i4_e32 v44, v136, v52
	v_dot8c_i32_i4_e32 v45, v136, v50
	v_dot8c_i32_i4_e32 v38, v131, v53
	v_dot8c_i32_i4_e32 v39, v131, v51
	v_dot8c_i32_i4_e32 v40, v133, v53
	v_dot8c_i32_i4_e32 v41, v133, v51
	v_dot8c_i32_i4_e32 v42, v135, v53
	v_dot8c_i32_i4_e32 v43, v135, v51
	v_dot8c_i32_i4_e32 v44, v137, v53
	v_dot8c_i32_i4_e32 v45, v137, v51
	v_and_b32_e32 v78, 0xffff, v21
	v_lshrrev_b32_e32 v79, 16, v21
	v_lshl_add_u32 v78, v78, 7, v150
	v_lshl_add_u32 v79, v79, 7, v151
	s_mov_b32 m0, s79
	s_add_i32 s43, s79, 0x400
	global_load_lds_dwordx4 v78, s[50:51]
	s_mov_b32 m0, s43
	s_nop 0
	global_load_lds_dwordx4 v79, s[50:51]
	s_waitcnt vmcnt(8)
	v_add_u32_e32 v54, s99, v59
	v_add_u32_e32 v55, s99, v60
	v_add_u32_e32 v56, s99, v61
	v_add_u32_e32 v57, s99, v62
	ds_read_b64_tr_b4 v[50:51], v160 offset:896
	ds_read_b64_tr_b4 v[52:53], v160 offset:1920
	ds_read_b64_tr_b4 v[130:131], v54
	ds_read_b64_tr_b4 v[132:133], v55
	ds_read_b64_tr_b4 v[134:135], v56
	ds_read_b64_tr_b4 v[136:137], v57
	s_waitcnt lgkmcnt(6)
	v_dot8c_i32_i4_e32 v38, v122, v48
	v_dot8c_i32_i4_e32 v39, v122, v46
	v_dot8c_i32_i4_e32 v40, v124, v48
	v_dot8c_i32_i4_e32 v41, v124, v46
	v_dot8c_i32_i4_e32 v42, v126, v48
	v_dot8c_i32_i4_e32 v43, v126, v46
	v_dot8c_i32_i4_e32 v44, v128, v48
	v_dot8c_i32_i4_e32 v45, v128, v46
	v_dot8c_i32_i4_e32 v38, v123, v49
	v_dot8c_i32_i4_e32 v39, v123, v47
	v_dot8c_i32_i4_e32 v40, v125, v49
	v_dot8c_i32_i4_e32 v41, v125, v47
	v_dot8c_i32_i4_e32 v42, v127, v49
	v_dot8c_i32_i4_e32 v43, v127, v47
	v_dot8c_i32_i4_e32 v44, v129, v49
	v_dot8c_i32_i4_e32 v45, v129, v47
	v_and_b32_e32 v78, 0xffff, v22
	v_lshrrev_b32_e32 v79, 16, v22
	v_lshl_add_u32 v78, v78, 7, v150
	v_lshl_add_u32 v79, v79, 7, v151
	s_mov_b32 m0, s98
	s_add_i32 s43, s98, 0x400
	global_load_lds_dwordx4 v78, s[50:51]
	s_mov_b32 m0, s43
	s_nop 0
	global_load_lds_dwordx4 v79, s[50:51]
	s_waitcnt vmcnt(8)
	v_add_u32_e32 v54, s76, v59
	v_add_u32_e32 v55, s76, v60
	v_add_u32_e32 v56, s76, v61
	v_add_u32_e32 v57, s76, v62
	ds_read_b64_tr_b4 v[46:47], v160
	ds_read_b64_tr_b4 v[48:49], v160 offset:1024
	ds_read_b64_tr_b4 v[122:123], v54
	ds_read_b64_tr_b4 v[124:125], v55
	ds_read_b64_tr_b4 v[126:127], v56
	ds_read_b64_tr_b4 v[128:129], v57
	s_waitcnt lgkmcnt(6)
; __device__ __forceinline__ void peer_v_tokens(int j, const LAS unsigned short* EL, const LAS unsigned char* AL  , const LAS float* ASC  , const LAS int* SAL  , ...
;     ...
; #pragma unroll
;         for (int m = 0; m < 2; ++m) {
;             const int idx = lane + 64 * m, tau = idx >> 4, sr = idx & 15, k = 16 * (sr & 7) + 2 * tau + (sr >> 3);
;             const int aq = (int)*(const LAS signed char*)(AL + tl * 128 + k); const int tq = aq + 8;
;             const unsigned lo = (((unsigned)tq & 15u) ^ 8u) * 0x11111111u, hi = ((unsigned)(tq >> 4) & 15u) * 0x11111111u;
;             typedef unsigned u2v __attribute__((ext_vector_type(2)));
;             u2v l2; l2.x = lo; l2.y = lo; u2v h2; h2.x = hi; h2.y = hi;
;             *(LAS u2v*)(ATL + 8 * idx) = l2; *(LAS u2v*)(ATL + 1024 + 8 * idx) = h2;
;         }
;         const float asc = ASC[tl]; const int sa = SAL[tl];
;         CFENCE();
;         int accH[4], accL[4];
; #pragma unroll
;         for (int st = 0; st < 16; ++st) {
;             const int p = st >> 2, q = st & 3;
;             if (st < 14) VDMA(st + 2, (st + 2) % 3);
;             if (st < 14) asm volatile("s_waitcnt vmcnt(8)" ::: "memory");
;             else if (st == 14) asm volatile("s_waitcnt vmcnt(4)" ::: "memory");
;             else asm volatile("s_waitcnt vmcnt(0)" ::: "memory");
;             if (q == 0) {
; #pragma unroll
;                 for (int r = 0; r < 4; ++r) { accH[r] = 0; accL[r] = 0; } }
; #pragma unroll
;             for (int tp = 0; tp < 2; ++tp) {
;                 const v2i ao = TR4(ATL + (2 * q + tp) * 128 + 8 * s16), ah = TR4(ATL + 1024 + (2 * q + tp) * 128 + 8 * s16);
; #pragma unroll
;                 for (int r = 0; r < 4; ++r) {
;                     const v2i d = TR4(ldsb + BUF[st % 3] + 2048 * tp + roff[r]);
;                     accH[r] = __builtin_amdgcn_sdot8(d.x, ah.x, accH[r], false); accH[r] = __builtin_amdgcn_sdot8(d.y, ah.y, accH[r], false);
;                     accL[r] = __builtin_amdgcn_sdot8(d.x, ao.x, accL[r], false); accL[r] = __builtin_amdgcn_sdot8(d.y, ao.y, accL[r], false);
;                 }
;             }
;             asm volatile("s_waitcnt lgkmcnt(0)" ::: "memory");
;             if (q == 3) {
; #pragma unroll
;                 for (int r = 0; r < 4; ++r) STASH[256 * p + 16 * (grp + 4 * r) + pc] = f2bf(asc * (float)(2 * ((accH[r] << 4) + accL[r]) + sa));
;             }
;         }
	v_dot8c_i32_i4_e32 v38, v130, v52
	v_dot8c_i32_i4_e32 v39, v130, v50
	v_dot8c_i32_i4_e32 v40, v132, v52
	v_dot8c_i32_i4_e32 v41, v132, v50
	v_dot8c_i32_i4_e32 v42, v134, v52
	v_dot8c_i32_i4_e32 v43, v134, v50
	v_dot8c_i32_i4_e32 v44, v136, v52
	v_dot8c_i32_i4_e32 v45, v136, v50
	v_dot8c_i32_i4_e32 v38, v131, v53
	v_dot8c_i32_i4_e32 v39, v131, v51
	v_dot8c_i32_i4_e32 v40, v133, v53
	v_dot8c_i32_i4_e32 v41, v133, v51
	v_dot8c_i32_i4_e32 v42, v135, v53
	v_dot8c_i32_i4_e32 v43, v135, v51
	v_dot8c_i32_i4_e32 v44, v137, v53
	v_dot8c_i32_i4_e32 v45, v137, v51
	s_nop 3
	s_waitcnt lgkmcnt(15)
	v_lshlrev_b32_e32 v38, 5, v38
	v_lshlrev_b32_e32 v39, 1, v39
	v_add3_u32 v38, v39, v229, v38
	v_cvt_f32_i32_e32 v38, v38
	v_mul_f32_e32 v38, v228, v38
	v_lshlrev_b32_e32 v40, 5, v40
	v_lshlrev_b32_e32 v41, 1, v41
	v_add3_u32 v40, v41, v229, v40
	v_cvt_f32_i32_e32 v40, v40
	v_mul_f32_e32 v40, v228, v40
	v_lshlrev_b32_e32 v42, 5, v42
	v_lshlrev_b32_e32 v43, 1, v43
	v_add3_u32 v42, v43, v229, v42
	v_cvt_f32_i32_e32 v42, v42
	v_mul_f32_e32 v42, v228, v42
	v_lshlrev_b32_e32 v44, 5, v44
	v_lshlrev_b32_e32 v45, 1, v45
	v_add3_u32 v44, v45, v229, v44
	v_cvt_f32_i32_e32 v44, v44
	v_mul_f32_e32 v44, v228, v44
	v_cvt_pk_bf16_f32 v244, v38, v40
	v_cvt_pk_bf16_f32 v245, v42, v44
	v_add_u32_e32 v147, 8, v140
	v_and_b32_e32 v146, 15, v147
	v_xor_b32_e32 v146, 8, v146
	v_bfe_u32 v148, v147, 4, 4
	v_mul_lo_u32 v146, v146, s92
	v_mul_lo_u32 v148, v148, s92
	v_mov_b32_e32 v147, v146
	v_mov_b32_e32 v149, v148
	ds_write2st64_b64 v77, v[146:147], v[148:149] offset1:2
	v_add_u32_e32 v138, 0x1c00, v74
	ds_read_u8 v139, v138
	v_add_u32_e32 v141, 0x1c00, v73
	ds_read_u8 v140, v141
	s_add_i32 s43, s67, 192
	v_mov_b32_e32 v138, s43
	ds_read2st64_b32 v[228:229], v138 offset1:1
	ds_read_b128 v[26:29], v227 offset:14336
	ds_read_b128 v[30:33], v227 offset:14352
	v_mov_b32_e32 v38, 0
	v_mov_b32_e32 v39, 0
	v_mov_b32_e32 v40, 0
	v_mov_b32_e32 v41, 0
	v_mov_b32_e32 v42, 0
	v_mov_b32_e32 v43, 0
	v_mov_b32_e32 v44, 0
	v_mov_b32_e32 v45, 0
	v_and_b32_e32 v78, 0xffff, v23
	v_lshrrev_b32_e32 v79, 16, v23
	v_lshl_add_u32 v78, v78, 7, v150
	v_lshl_add_u32 v79, v79, 7, v151
	s_mov_b32 m0, s99
	s_add_i32 s43, s99, 0x400
	global_load_lds_dwordx4 v78, s[50:51]
	s_mov_b32 m0, s43
	s_nop 0
	global_load_lds_dwordx4 v79, s[50:51]
	s_waitcnt vmcnt(8)
	v_add_u32_e32 v54, s77, v59
	v_add_u32_e32 v55, s77, v60
	v_add_u32_e32 v56, s77, v61
	v_add_u32_e32 v57, s77, v62
	ds_read_b64_tr_b4 v[50:51], v160 offset:128
	ds_read_b64_tr_b4 v[52:53], v160 offset:1152
	ds_read_b64_tr_b4 v[130:131], v54
	ds_read_b64_tr_b4 v[132:133], v55
	ds_read_b64_tr_b4 v[134:135], v56
	ds_read_b64_tr_b4 v[136:137], v57
	s_waitcnt lgkmcnt(12)
	s_waitcnt vmcnt(36) lgkmcnt(15)
	v_lshlrev_b32_e32 v210, 16, v194
	v_and_b32_e32 v211, 0xffff0000, v194
	v_lshlrev_b32_e32 v142, 16, v202
	v_and_b32_e32 v143, 0xffff0000, v202
	v_add_f32_e32 v210, v210, v142
	v_add_f32_e32 v211, v211, v143
	v_lshlrev_b32_e32 v212, 16, v195
	v_and_b32_e32 v213, 0xffff0000, v195
	v_lshlrev_b32_e32 v142, 16, v203
	v_and_b32_e32 v143, 0xffff0000, v203
	v_add_f32_e32 v212, v212, v142
	v_add_f32_e32 v213, v213, v143
	v_lshlrev_b32_e32 v214, 16, v196
	v_and_b32_e32 v215, 0xffff0000, v196
	v_lshlrev_b32_e32 v142, 16, v204
	v_and_b32_e32 v143, 0xffff0000, v204
	v_add_f32_e32 v214, v214, v142
	v_add_f32_e32 v215, v215, v143
	v_lshlrev_b32_e32 v216, 16, v197
	v_and_b32_e32 v217, 0xffff0000, v197
	v_lshlrev_b32_e32 v142, 16, v205
	v_and_b32_e32 v143, 0xffff0000, v205
	v_add_f32_e32 v216, v216, v142
	v_add_f32_e32 v217, v217, v143
	v_lshlrev_b32_e32 v218, 16, v198
	v_and_b32_e32 v219, 0xffff0000, v198
	v_lshlrev_b32_e32 v142, 16, v206
	v_and_b32_e32 v143, 0xffff0000, v206
	v_add_f32_e32 v218, v218, v142
	v_add_f32_e32 v219, v219, v143
	v_lshlrev_b32_e32 v220, 16, v199
	v_and_b32_e32 v221, 0xffff0000, v199
	v_lshlrev_b32_e32 v142, 16, v207
	v_and_b32_e32 v143, 0xffff0000, v207
	v_add_f32_e32 v220, v220, v142
	v_add_f32_e32 v221, v221, v143
	v_lshlrev_b32_e32 v222, 16, v200
	v_and_b32_e32 v223, 0xffff0000, v200
	v_lshlrev_b32_e32 v142, 16, v208
	v_and_b32_e32 v143, 0xffff0000, v208
	v_add_f32_e32 v222, v222, v142
	v_add_f32_e32 v223, v223, v143
	v_lshlrev_b32_e32 v224, 16, v201
	v_and_b32_e32 v225, 0xffff0000, v201
	v_lshlrev_b32_e32 v142, 16, v209
	v_and_b32_e32 v143, 0xffff0000, v209
	v_add_f32_e32 v224, v224, v142
	v_add_f32_e32 v225, v225, v143
	v_mov_b32_e32 v144, 0
	v_mul_f32_e32 v145, v210, v210
	v_fmac_f32_e32 v145, v211, v211
	v_fmac_f32_e32 v145, v212, v212
	v_fmac_f32_e32 v145, v213, v213
	v_add_f32_e32 v144, v144, v145
	v_mul_f32_e32 v145, v214, v214
	v_fmac_f32_e32 v145, v215, v215
	v_fmac_f32_e32 v145, v216, v216
	v_fmac_f32_e32 v145, v217, v217
	v_add_f32_e32 v144, v144, v145
	v_mul_f32_e32 v145, v218, v218
	v_fmac_f32_e32 v145, v219, v219
	v_fmac_f32_e32 v145, v220, v220
	v_fmac_f32_e32 v145, v221, v221
	v_add_f32_e32 v144, v144, v145
	v_mul_f32_e32 v145, v222, v222
	v_fmac_f32_e32 v145, v223, v223
	v_fmac_f32_e32 v145, v224, v224
	v_fmac_f32_e32 v145, v225, v225
	v_add_f32_e32 v144, v144, v145
	s_nop 1
	v_add_f32_dpp v144, v144, v144 quad_perm:[1,0,3,2] row_mask:0xf bank_mask:0xf bound_ctrl:1
	s_nop 1
	v_add_f32_dpp v144, v144, v144 quad_perm:[2,3,0,1] row_mask:0xf bank_mask:0xf bound_ctrl:1
	s_nop 1
	v_add_f32_dpp v144, v144, v144 row_half_mirror row_mask:0xf bank_mask:0xf bound_ctrl:1
	s_nop 1
	v_add_f32_dpp v144, v144, v144 row_mirror row_mask:0xf bank_mask:0xf bound_ctrl:1
	s_nop 1
	v_readlane_b32 s10, v144, 0
	v_readlane_b32 s11, v144, 16
	v_readlane_b32 s14, v144, 32
	v_readlane_b32 s15, v144, 48
	s_nop 3
	v_mov_b32_e32 v144, s11
	v_mov_b32_e32 v145, s15
; __device__ __forceinline__ void peer_v_tokens(int j, const LAS unsigned short* EL, const LAS unsigned char* AL  , const LAS float* ASC  , const LAS int* SAL  , ...
;     ...
;         for (int st = 0; st < 16; ++st) {
;             const int p = st >> 2, q = st & 3;
;             if (st < 14) VDMA(st + 2, (st + 2) % 3);
;             if (st < 14) asm volatile("s_waitcnt vmcnt(8)" ::: "memory");
;             else if (st == 14) asm volatile("s_waitcnt vmcnt(4)" ::: "memory");
;             else asm volatile("s_waitcnt vmcnt(0)" ::: "memory");
;             if (q == 0) {
; #pragma unroll
;                 for (int r = 0; r < 4; ++r) { accH[r] = 0; accL[r] = 0; } }
; #pragma unroll
;             for (int tp = 0; tp < 2; ++tp) {
;                 const v2i ao = TR4(ATL + (2 * q + tp) * 128 + 8 * s16), ah = TR4(ATL + 1024 + (2 * q + tp) * 128 + 8 * s16);
; #pragma unroll
;                 for (int r = 0; r < 4; ++r) {
;                     const v2i d = TR4(ldsb + BUF[st % 3] + 2048 * tp + roff[r]);
;                     accH[r] = __builtin_amdgcn_sdot8(d.x, ah.x, accH[r], false); accH[r] = __builtin_amdgcn_sdot8(d.y, ah.y, accH[r], false);
;                     accL[r] = __builtin_amdgcn_sdot8(d.x, ao.x, accL[r], false); accL[r] = __builtin_amdgcn_sdot8(d.y, ao.y, accL[r], false);
;                 }
;             }
;             asm volatile("s_waitcnt lgkmcnt(0)" ::: "memory");
;             if (q == 3) {
; #pragma unroll
;                 for (int r = 0; r < 4; ++r) STASH[256 * p + 16 * (grp + 4 * r) + pc] = f2bf(asc * (float)(2 * ((accH[r] << 4) + accL[r]) + sa));
;             }
;         }
;         CFENCE();
;         {
;             float4 v[4]; float ss = 0.f;
; #pragma unroll
;             for (int jq = 0; jq < 4; ++jq) { typedef unsigned u2v __attribute__((ext_vector_type(2))); const u2v pw = *(const LAS u2v*)(STASH + 4 * lane + 256 * jq); const uint2 hw = hv[jq];
;                 v[jq] = make_float4(__uint_as_float(hw.x << 16) + __uint_as_float(pw.x << 16), __uint_as_float(hw.x & 0xffff0000u) + __uint_as_float(pw.x & 0xffff0000u),
;                                     __uint_as_float(hw.y << 16) + __uint_as_float(pw.y << 16), __uint_as_float(hw.y & 0xffff0000u) + __uint_as_float(pw.y & 0xffff0000u));
;                 ss += v[jq].x * v[jq].x + v[jq].y * v[jq].y + v[jq].z * v[jq].z + v[jq].w * v[jq].w; }
;             ss = wave_sum(ss);
	v_add_f32_e32 v144, s10, v144
	v_add_f32_e32 v145, s14, v145
	v_add_f32_e32 v144, v144, v145
	v_fmamk_f32 v144, v144, 0x3a800000, v111
	v_rsq_f32_e32 v144, v144
	s_nop 0
	v_mul_f32_e32 v210, v210, v144
	v_mul_f32_e32 v211, v211, v144
	v_mul_f32_e32 v212, v212, v144
	v_mul_f32_e32 v213, v213, v144
	v_mul_f32_e32 v214, v214, v144
	v_mul_f32_e32 v215, v215, v144
	v_mul_f32_e32 v216, v216, v144
	v_mul_f32_e32 v217, v217, v144
	v_mul_f32_e32 v218, v218, v144
	v_mul_f32_e32 v219, v219, v144
	v_mul_f32_e32 v220, v220, v144
	v_mul_f32_e32 v221, v221, v144
	v_mul_f32_e32 v222, v222, v144
	v_mul_f32_e32 v223, v223, v144
	v_mul_f32_e32 v224, v224, v144
	v_mul_f32_e32 v225, v225, v144
	v_dot8c_i32_i4_e32 v38, v122, v48
	v_dot8c_i32_i4_e32 v39, v122, v46
	v_dot8c_i32_i4_e32 v40, v124, v48
	v_dot8c_i32_i4_e32 v41, v124, v46
	v_dot8c_i32_i4_e32 v42, v126, v48
	v_dot8c_i32_i4_e32 v43, v126, v46
	v_dot8c_i32_i4_e32 v44, v128, v48
	v_dot8c_i32_i4_e32 v45, v128, v46
	v_dot8c_i32_i4_e32 v38, v123, v49
	v_dot8c_i32_i4_e32 v39, v123, v47
	v_dot8c_i32_i4_e32 v40, v125, v49
	v_dot8c_i32_i4_e32 v41, v125, v47
	v_dot8c_i32_i4_e32 v42, v127, v49
	v_dot8c_i32_i4_e32 v43, v127, v47
	v_dot8c_i32_i4_e32 v44, v129, v49
	v_dot8c_i32_i4_e32 v45, v129, v47
	v_and_b32_e32 v78, 0xffff, v24
	v_lshrrev_b32_e32 v79, 16, v24
	v_lshl_add_u32 v78, v78, 7, v150
	v_lshl_add_u32 v79, v79, 7, v151
	s_mov_b32 m0, s76
	s_add_i32 s43, s76, 0x400
	global_load_lds_dwordx4 v78, s[50:51]
	s_mov_b32 m0, s43
	s_nop 0
	global_load_lds_dwordx4 v79, s[50:51]
	s_waitcnt vmcnt(8)
	v_add_u32_e32 v54, s78, v59
	v_add_u32_e32 v55, s78, v60
	v_add_u32_e32 v56, s78, v61
	v_add_u32_e32 v57, s78, v62
	ds_read_b64_tr_b4 v[46:47], v160 offset:256
	ds_read_b64_tr_b4 v[48:49], v160 offset:1280
	ds_read_b64_tr_b4 v[122:123], v54
	ds_read_b64_tr_b4 v[124:125], v55
	ds_read_b64_tr_b4 v[126:127], v56
	ds_read_b64_tr_b4 v[128:129], v57
	s_waitcnt lgkmcnt(6)
	v_dot8c_i32_i4_e32 v38, v130, v52
	v_dot8c_i32_i4_e32 v39, v130, v50
	v_dot8c_i32_i4_e32 v40, v132, v52
	v_dot8c_i32_i4_e32 v41, v132, v50
	v_dot8c_i32_i4_e32 v42, v134, v52
	v_dot8c_i32_i4_e32 v43, v134, v50
	v_dot8c_i32_i4_e32 v44, v136, v52
	v_dot8c_i32_i4_e32 v45, v136, v50
	v_dot8c_i32_i4_e32 v38, v131, v53
	v_dot8c_i32_i4_e32 v39, v131, v51
	v_dot8c_i32_i4_e32 v40, v133, v53
	v_dot8c_i32_i4_e32 v41, v133, v51
	v_dot8c_i32_i4_e32 v42, v135, v53
	v_dot8c_i32_i4_e32 v43, v135, v51
	v_dot8c_i32_i4_e32 v44, v137, v53
	v_dot8c_i32_i4_e32 v45, v137, v51
	v_and_b32_e32 v78, 0xffff, v25
	v_lshrrev_b32_e32 v79, 16, v25
	v_lshl_add_u32 v78, v78, 7, v150
	v_lshl_add_u32 v79, v79, 7, v151
	s_mov_b32 m0, s77
	s_add_i32 s43, s77, 0x400
	global_load_lds_dwordx4 v78, s[50:51]
	s_mov_b32 m0, s43
	s_nop 0
	global_load_lds_dwordx4 v79, s[50:51]
	s_waitcnt vmcnt(8)
	v_add_u32_e32 v54, s79, v59
	v_add_u32_e32 v55, s79, v60
	v_add_u32_e32 v56, s79, v61
	v_add_u32_e32 v57, s79, v62
	ds_read_b64_tr_b4 v[50:51], v160 offset:384
	ds_read_b64_tr_b4 v[52:53], v160 offset:1408
	ds_read_b64_tr_b4 v[130:131], v54
	ds_read_b64_tr_b4 v[132:133], v55
	ds_read_b64_tr_b4 v[134:135], v56
	ds_read_b64_tr_b4 v[136:137], v57
	s_waitcnt lgkmcnt(6)
	v_dot8c_i32_i4_e32 v38, v122, v48
	v_dot8c_i32_i4_e32 v39, v122, v46
	v_dot8c_i32_i4_e32 v40, v124, v48
	v_dot8c_i32_i4_e32 v41, v124, v46
	v_dot8c_i32_i4_e32 v42, v126, v48
	v_dot8c_i32_i4_e32 v43, v126, v46
	v_dot8c_i32_i4_e32 v44, v128, v48
	v_dot8c_i32_i4_e32 v45, v128, v46
	v_dot8c_i32_i4_e32 v38, v123, v49
	v_dot8c_i32_i4_e32 v39, v123, v47
	v_dot8c_i32_i4_e32 v40, v125, v49
	v_dot8c_i32_i4_e32 v41, v125, v47
	v_dot8c_i32_i4_e32 v42, v127, v49
	v_dot8c_i32_i4_e32 v43, v127, v47
	v_dot8c_i32_i4_e32 v44, v129, v49
	v_dot8c_i32_i4_e32 v45, v129, v47
	s_waitcnt lgkmcnt(15)
	v_and_b32_e32 v78, 0xffff, v26
	v_lshrrev_b32_e32 v79, 16, v26
	v_lshl_add_u32 v78, v78, 7, v150
	v_lshl_add_u32 v79, v79, 7, v151
	s_mov_b32 m0, s78
	s_add_i32 s43, s78, 0x400
	global_load_lds_dwordx4 v78, s[50:51]
	s_mov_b32 m0, s43
	s_nop 0
	global_load_lds_dwordx4 v79, s[50:51]
	s_waitcnt vmcnt(8)
	v_add_u32_e32 v54, s98, v59
	v_add_u32_e32 v55, s98, v60
	v_add_u32_e32 v56, s98, v61
	v_add_u32_e32 v57, s98, v62
	ds_read_b64_tr_b4 v[46:47], v160 offset:512
	ds_read_b64_tr_b4 v[48:49], v160 offset:1536
	ds_read_b64_tr_b4 v[122:123], v54
	ds_read_b64_tr_b4 v[124:125], v55
	ds_read_b64_tr_b4 v[126:127], v56
	ds_read_b64_tr_b4 v[128:129], v57
	s_waitcnt lgkmcnt(6)
	v_dot8c_i32_i4_e32 v38, v130, v52
	v_dot8c_i32_i4_e32 v39, v130, v50
	v_dot8c_i32_i4_e32 v40, v132, v52
	v_dot8c_i32_i4_e32 v41, v132, v50
	v_dot8c_i32_i4_e32 v42, v134, v52
	v_dot8c_i32_i4_e32 v43, v134, v50
	v_dot8c_i32_i4_e32 v44, v136, v52
	v_dot8c_i32_i4_e32 v45, v136, v50
	v_dot8c_i32_i4_e32 v38, v131, v53
	v_dot8c_i32_i4_e32 v39, v131, v51
	v_dot8c_i32_i4_e32 v40, v133, v53
	v_dot8c_i32_i4_e32 v41, v133, v51
	v_dot8c_i32_i4_e32 v42, v135, v53
	v_dot8c_i32_i4_e32 v43, v135, v51
	v_dot8c_i32_i4_e32 v44, v137, v53
	v_dot8c_i32_i4_e32 v45, v137, v51
	v_and_b32_e32 v78, 0xffff, v27
	v_lshrrev_b32_e32 v79, 16, v27
	v_lshl_add_u32 v78, v78, 7, v150
	v_lshl_add_u32 v79, v79, 7, v151
	s_mov_b32 m0, s79
	s_add_i32 s43, s79, 0x400
	global_load_lds_dwordx4 v78, s[50:51]
	s_mov_b32 m0, s43
	s_nop 0
	global_load_lds_dwordx4 v79, s[50:51]
	s_waitcnt vmcnt(8)
	v_add_u32_e32 v54, s99, v59
	v_add_u32_e32 v55, s99, v60
	v_add_u32_e32 v56, s99, v61
	v_add_u32_e32 v57, s99, v62
	ds_read_b64_tr_b4 v[50:51], v160 offset:640
	ds_read_b64_tr_b4 v[52:53], v160 offset:1664
	ds_read_b64_tr_b4 v[130:131], v54
	ds_read_b64_tr_b4 v[132:133], v55
	ds_read_b64_tr_b4 v[134:135], v56
	ds_read_b64_tr_b4 v[136:137], v57
	s_waitcnt lgkmcnt(6)
; __device__ __forceinline__ void peer_v_tokens(int j, const LAS unsigned short* EL, const LAS unsigned char* AL  , const LAS float* ASC  , const LAS int* SAL  , ...
;     ...
;         for (int st = 0; st < 16; ++st) {
;             const int p = st >> 2, q = st & 3;
;             if (st < 14) VDMA(st + 2, (st + 2) % 3);
;             if (st < 14) asm volatile("s_waitcnt vmcnt(8)" ::: "memory");
;             else if (st == 14) asm volatile("s_waitcnt vmcnt(4)" ::: "memory");
;             else asm volatile("s_waitcnt vmcnt(0)" ::: "memory");
;             if (q == 0) {
; #pragma unroll
;                 for (int r = 0; r < 4; ++r) { accH[r] = 0; accL[r] = 0; } }
; #pragma unroll
;             for (int tp = 0; tp < 2; ++tp) {
;                 const v2i ao = TR4(ATL + (2 * q + tp) * 128 + 8 * s16), ah = TR4(ATL + 1024 + (2 * q + tp) * 128 + 8 * s16);
; #pragma unroll
;                 for (int r = 0; r < 4; ++r) {
;                     const v2i d = TR4(ldsb + BUF[st % 3] + 2048 * tp + roff[r]);
;                     accH[r] = __builtin_amdgcn_sdot8(d.x, ah.x, accH[r], false); accH[r] = __builtin_amdgcn_sdot8(d.y, ah.y, accH[r], false);
;                     accL[r] = __builtin_amdgcn_sdot8(d.x, ao.x, accL[r], false); accL[r] = __builtin_amdgcn_sdot8(d.y, ao.y, accL[r], false);
;                 }
;             }
;             asm volatile("s_waitcnt lgkmcnt(0)" ::: "memory");
;             if (q == 3) {
; #pragma unroll
;                 for (int r = 0; r < 4; ++r) STASH[256 * p + 16 * (grp + 4 * r) + pc] = f2bf(asc * (float)(2 * ((accH[r] << 4) + accL[r]) + sa));
;             }
;         }
;         CFENCE();
;         {
;             float4 v[4]; float ss = 0.f;
; #pragma unroll
;             for (int jq = 0; jq < 4; ++jq) { typedef unsigned u2v __attribute__((ext_vector_type(2))); const u2v pw = *(const LAS u2v*)(STASH + 4 * lane + 256 * jq); const uint2 hw = hv[jq];
;                 v[jq] = make_float4(__uint_as_float(hw.x << 16) + __uint_as_float(pw.x << 16), __uint_as_float(hw.x & 0xffff0000u) + __uint_as_float(pw.x & 0xffff0000u),
;                                     __uint_as_float(hw.y << 16) + __uint_as_float(pw.y << 16), __uint_as_float(hw.y & 0xffff0000u) + __uint_as_float(pw.y & 0xffff0000u));
;                 ss += v[jq].x * v[jq].x + v[jq].y * v[jq].y + v[jq].z * v[jq].z + v[jq].w * v[jq].w; }
;             ss = wave_sum(ss);
	v_dot8c_i32_i4_e32 v38, v122, v48
	v_dot8c_i32_i4_e32 v39, v122, v46
	v_dot8c_i32_i4_e32 v40, v124, v48
	v_dot8c_i32_i4_e32 v41, v124, v46
	v_dot8c_i32_i4_e32 v42, v126, v48
	v_dot8c_i32_i4_e32 v43, v126, v46
	v_dot8c_i32_i4_e32 v44, v128, v48
	v_dot8c_i32_i4_e32 v45, v128, v46
	v_dot8c_i32_i4_e32 v38, v123, v49
	v_dot8c_i32_i4_e32 v39, v123, v47
	v_dot8c_i32_i4_e32 v40, v125, v49
	v_dot8c_i32_i4_e32 v41, v125, v47
	v_dot8c_i32_i4_e32 v42, v127, v49
	v_dot8c_i32_i4_e32 v43, v127, v47
	v_dot8c_i32_i4_e32 v44, v129, v49
	v_dot8c_i32_i4_e32 v45, v129, v47
	s_waitcnt lgkmcnt(15)
	v_add_u32_e32 v143, 8, v139
	v_and_b32_e32 v142, 15, v143
	v_xor_b32_e32 v142, 8, v142
	v_bfe_u32 v144, v143, 4, 4
	v_mul_lo_u32 v142, v142, s92
	v_mul_lo_u32 v144, v144, s92
	v_mov_b32_e32 v143, v142
	v_mov_b32_e32 v145, v144
	ds_write2st64_b64 v159, v[142:143], v[144:145] offset1:2
	v_and_b32_e32 v78, 0xffff, v28
	v_lshrrev_b32_e32 v79, 16, v28
	v_lshl_add_u32 v78, v78, 7, v150
	v_lshl_add_u32 v79, v79, 7, v151
	s_mov_b32 m0, s98
	s_add_i32 s43, s98, 0x400
	global_load_lds_dwordx4 v78, s[50:51]
	s_mov_b32 m0, s43
	s_nop 0
	global_load_lds_dwordx4 v79, s[50:51]
	s_waitcnt vmcnt(8)
	v_add_u32_e32 v54, s76, v59
	v_add_u32_e32 v55, s76, v60
	v_add_u32_e32 v56, s76, v61
	v_add_u32_e32 v57, s76, v62
	ds_read_b64_tr_b4 v[46:47], v160 offset:768
	ds_read_b64_tr_b4 v[48:49], v160 offset:1792
	ds_read_b64_tr_b4 v[122:123], v54
	ds_read_b64_tr_b4 v[124:125], v55
	ds_read_b64_tr_b4 v[126:127], v56
	ds_read_b64_tr_b4 v[128:129], v57
	s_waitcnt lgkmcnt(7)
	v_dot8c_i32_i4_e32 v38, v130, v52
	v_dot8c_i32_i4_e32 v39, v130, v50
	v_dot8c_i32_i4_e32 v40, v132, v52
	v_dot8c_i32_i4_e32 v41, v132, v50
	v_dot8c_i32_i4_e32 v42, v134, v52
	v_dot8c_i32_i4_e32 v43, v134, v50
	v_dot8c_i32_i4_e32 v44, v136, v52
	v_dot8c_i32_i4_e32 v45, v136, v50
	v_dot8c_i32_i4_e32 v38, v131, v53
	v_dot8c_i32_i4_e32 v39, v131, v51
	v_dot8c_i32_i4_e32 v40, v133, v53
	v_dot8c_i32_i4_e32 v41, v133, v51
	v_dot8c_i32_i4_e32 v42, v135, v53
	v_dot8c_i32_i4_e32 v43, v135, v51
	v_dot8c_i32_i4_e32 v44, v137, v53
	v_dot8c_i32_i4_e32 v45, v137, v51
	v_and_b32_e32 v78, 0xffff, v29
	v_lshrrev_b32_e32 v79, 16, v29
	v_lshl_add_u32 v78, v78, 7, v150
	v_lshl_add_u32 v79, v79, 7, v151
	s_mov_b32 m0, s99
	s_add_i32 s43, s99, 0x400
	global_load_lds_dwordx4 v78, s[50:51]
	s_mov_b32 m0, s43
	s_nop 0
	global_load_lds_dwordx4 v79, s[50:51]
	s_waitcnt vmcnt(8)
	v_add_u32_e32 v54, s77, v59
	v_add_u32_e32 v55, s77, v60
	v_add_u32_e32 v56, s77, v61
	v_add_u32_e32 v57, s77, v62
	ds_read_b64_tr_b4 v[50:51], v160 offset:896
	ds_read_b64_tr_b4 v[52:53], v160 offset:1920
	ds_read_b64_tr_b4 v[130:131], v54
	ds_read_b64_tr_b4 v[132:133], v55
	ds_read_b64_tr_b4 v[134:135], v56
	ds_read_b64_tr_b4 v[136:137], v57
	s_waitcnt lgkmcnt(6)
	v_dot8c_i32_i4_e32 v38, v122, v48
	v_dot8c_i32_i4_e32 v39, v122, v46
	v_dot8c_i32_i4_e32 v40, v124, v48
	v_dot8c_i32_i4_e32 v41, v124, v46
	v_dot8c_i32_i4_e32 v42, v126, v48
	v_dot8c_i32_i4_e32 v43, v126, v46
	v_dot8c_i32_i4_e32 v44, v128, v48
	v_dot8c_i32_i4_e32 v45, v128, v46
	v_dot8c_i32_i4_e32 v38, v123, v49
	v_dot8c_i32_i4_e32 v39, v123, v47
	v_dot8c_i32_i4_e32 v40, v125, v49
	v_dot8c_i32_i4_e32 v41, v125, v47
	v_dot8c_i32_i4_e32 v42, v127, v49
	v_dot8c_i32_i4_e32 v43, v127, v47
	v_dot8c_i32_i4_e32 v44, v129, v49
	v_dot8c_i32_i4_e32 v45, v129, v47
	v_and_b32_e32 v78, 0xffff, v30
	v_lshrrev_b32_e32 v79, 16, v30
	v_lshl_add_u32 v78, v78, 7, v150
	v_lshl_add_u32 v79, v79, 7, v151
	s_mov_b32 m0, s76
	s_add_i32 s43, s76, 0x400
	global_load_lds_dwordx4 v78, s[50:51]
	s_mov_b32 m0, s43
	s_nop 0
	global_load_lds_dwordx4 v79, s[50:51]
	s_waitcnt vmcnt(8)
	v_add_u32_e32 v54, s78, v59
	v_add_u32_e32 v55, s78, v60
	v_add_u32_e32 v56, s78, v61
	v_add_u32_e32 v57, s78, v62
	ds_read_b64_tr_b4 v[46:47], v160
	ds_read_b64_tr_b4 v[48:49], v160 offset:1024
	ds_read_b64_tr_b4 v[122:123], v54
	ds_read_b64_tr_b4 v[124:125], v55
	ds_read_b64_tr_b4 v[126:127], v56
	ds_read_b64_tr_b4 v[128:129], v57
	s_waitcnt lgkmcnt(6)
	v_dot8c_i32_i4_e32 v38, v130, v52
	v_dot8c_i32_i4_e32 v39, v130, v50
	v_dot8c_i32_i4_e32 v40, v132, v52
	v_dot8c_i32_i4_e32 v41, v132, v50
	v_dot8c_i32_i4_e32 v42, v134, v52
	v_dot8c_i32_i4_e32 v43, v134, v50
	v_dot8c_i32_i4_e32 v44, v136, v52
	v_dot8c_i32_i4_e32 v45, v136, v50
	v_dot8c_i32_i4_e32 v38, v131, v53
	v_dot8c_i32_i4_e32 v39, v131, v51
	v_dot8c_i32_i4_e32 v40, v133, v53
	v_dot8c_i32_i4_e32 v41, v133, v51
	v_dot8c_i32_i4_e32 v42, v135, v53
	v_dot8c_i32_i4_e32 v43, v135, v51
	v_dot8c_i32_i4_e32 v44, v137, v53
	v_dot8c_i32_i4_e32 v45, v137, v51
	s_nop 3
	s_waitcnt lgkmcnt(15)
	v_lshlrev_b32_e32 v38, 5, v38
	v_lshlrev_b32_e32 v39, 1, v39
	v_add3_u32 v38, v39, v229, v38
	v_cvt_f32_i32_e32 v38, v38
	v_mul_f32_e32 v38, v228, v38
	v_lshlrev_b32_e32 v40, 5, v40
	v_lshlrev_b32_e32 v41, 1, v41
	v_add3_u32 v40, v41, v229, v40
	v_cvt_f32_i32_e32 v40, v40
	v_mul_f32_e32 v40, v228, v40
	v_lshlrev_b32_e32 v42, 5, v42
	v_lshlrev_b32_e32 v43, 1, v43
	v_add3_u32 v42, v43, v229, v42
	v_cvt_f32_i32_e32 v42, v42
	v_mul_f32_e32 v42, v228, v42
	v_lshlrev_b32_e32 v44, 5, v44
	v_lshlrev_b32_e32 v45, 1, v45
	v_add3_u32 v44, v45, v229, v44
	v_cvt_f32_i32_e32 v44, v44
	v_mul_f32_e32 v44, v228, v44
	v_cvt_pk_bf16_f32 v67, v38, v40
	v_cvt_pk_bf16_f32 v68, v42, v44
	ds_read_b128 v[252:255], v155
	s_add_i32 s44, s40, 8
	s_ashr_i32 s45, s44, 31
	s_lshl_b64 s[44:45], s[44:45], 12
	v_lshl_add_u64 v[80:81], v[36:37], 0, s[44:45]
	s_waitcnt lgkmcnt(0)
	v_mul_f32_e32 v210, v210, v252
	v_mul_f32_e32 v211, v211, v253
	v_mul_f32_e32 v212, v212, v254
	v_mul_f32_e32 v213, v213, v255
	global_store_dwordx4 v[80:81], v[210:213], off nt
	ds_read_b128 v[252:255], v155 offset:1024
	s_add_i32 s44, s40, 8
	s_ashr_i32 s45, s44, 31
	s_lshl_b64 s[44:45], s[44:45], 12
	v_lshl_add_u64 v[80:81], v[36:37], 0, s[44:45]
	s_waitcnt lgkmcnt(0)
; #define LAS __attribute__((address_space(3)))
; #define CFENCE() asm volatile("" ::: "memory")
; __device__ __forceinline__ void peer_v_tokens(int j, const LAS unsigned short* EL, const LAS unsigned char* AL  , const LAS float* ASC  , const LAS int* SAL  , ...
;     ...
;         uint2 hv[4]; float4 gv[4];
;         { unsigned ho = (unsigned)t * (D / 4) + (unsigned)lane; asm volatile("" : "+v"(ho)); const uint2* hp = (const uint2*)HB + ho; const float4* gp = (const float4*)fng + lane;
; #pragma unroll
;           for (int jq = 0; jq < 4; ++jq) { hv[jq] = hp[64 * jq]; gv[jq] = gp[64 * jq]; } }
;         VDMA(0, 0); VDMA(1, 1);
; #pragma unroll
;         for (int m = 0; m < 2; ++m) {
;             const int idx = lane + 64 * m, tau = idx >> 4, sr = idx & 15, k = 16 * (sr & 7) + 2 * tau + (sr >> 3);
;             const int aq = (int)*(const LAS signed char*)(AL + tl * 128 + k); const int tq = aq + 8;
;             const unsigned lo = (((unsigned)tq & 15u) ^ 8u) * 0x11111111u, hi = ((unsigned)(tq >> 4) & 15u) * 0x11111111u;
;             typedef unsigned u2v __attribute__((ext_vector_type(2)));
;             u2v l2; l2.x = lo; l2.y = lo; u2v h2; h2.x = hi; h2.y = hi;
;             *(LAS u2v*)(ATL + 8 * idx) = l2; *(LAS u2v*)(ATL + 1024 + 8 * idx) = h2;
;         }
;         const float asc = ASC[tl]; const int sa = SAL[tl];
;         CFENCE();
;         int accH[4], accL[4];
; #pragma unroll
;         for (int st = 0; st < 16; ++st) {
;             const int p = st >> 2, q = st & 3;
;             if (st < 14) VDMA(st + 2, (st + 2) % 3);
;             if (st < 14) asm volatile("s_waitcnt vmcnt(8)" ::: "memory");
;             else if (st == 14) asm volatile("s_waitcnt vmcnt(4)" ::: "memory");
;             else asm volatile("s_waitcnt vmcnt(0)" ::: "memory");
;             if (q == 0) {
; #pragma unroll
;                 for (int r = 0; r < 4; ++r) { accH[r] = 0; accL[r] = 0; } }
; #pragma unroll
;             for (int tp = 0; tp < 2; ++tp) {
;                 const v2i ao = TR4(ATL + (2 * q + tp) * 128 + 8 * s16), ah = TR4(ATL + 1024 + (2 * q + tp) * 128 + 8 * s16);
; #pragma unroll
;                 for (int r = 0; r < 4; ++r) {
;                     const v2i d = TR4(ldsb + BUF[st % 3] + 2048 * tp + roff[r]);
;                     accH[r] = __builtin_amdgcn_sdot8(d.x, ah.x, accH[r], false); accH[r] = __builtin_amdgcn_sdot8(d.y, ah.y, accH[r], false);
	v_mul_f32_e32 v214, v214, v252
	v_mul_f32_e32 v215, v215, v253
	v_mul_f32_e32 v216, v216, v254
	v_mul_f32_e32 v217, v217, v255
	global_store_dwordx4 v[80:81], v[214:217], off offset:1024 nt
	s_add_i32 s43, s40, 16
	s_lshl_b32 s43, s43, 11
	v_add_u32_e32 v138, s43, v66
	global_load_dwordx2 v[194:195], v138, s[70:71]
	global_load_dwordx2 v[196:197], v138, s[70:71] offset:512
	global_load_dwordx2 v[198:199], v138, s[70:71] offset:1024
	global_load_dwordx2 v[200:201], v138, s[70:71] offset:1536
	v_add_u32_e32 v147, 8, v140
	v_and_b32_e32 v146, 15, v147
	v_xor_b32_e32 v146, 8, v146
	v_bfe_u32 v148, v147, 4, 4
	v_mul_lo_u32 v146, v146, s92
	v_mul_lo_u32 v148, v148, s92
	v_mov_b32_e32 v147, v146
	v_mov_b32_e32 v149, v148
	ds_write2st64_b64 v77, v[146:147], v[148:149] offset1:2
	v_add_u32_e32 v138, 0x1000, v74
	ds_read_u8 v139, v138
	v_add_u32_e32 v141, 0x1000, v73
	ds_read_u8 v140, v141
	s_add_i32 s43, s67, 224
	v_mov_b32_e32 v138, s43
	ds_read2st64_b32 v[228:229], v138 offset1:1
	ds_read_b128 v[18:21], v227 offset:8192
	ds_read_b128 v[22:25], v227 offset:8208
	v_add_u32_e32 v152, 0x200000, v63
	v_add_u32_e32 v153, 0x200000, v64
	v_mov_b32_e32 v38, 0
	v_mov_b32_e32 v39, 0
	v_mov_b32_e32 v40, 0
	v_mov_b32_e32 v41, 0
	v_mov_b32_e32 v42, 0
	v_mov_b32_e32 v43, 0
	v_mov_b32_e32 v44, 0
	v_mov_b32_e32 v45, 0
	v_and_b32_e32 v78, 0xffff, v31
	v_lshrrev_b32_e32 v79, 16, v31
	v_lshl_add_u32 v78, v78, 7, v150
	v_lshl_add_u32 v79, v79, 7, v151
	s_mov_b32 m0, s77
	s_add_i32 s43, s77, 0x400
	global_load_lds_dwordx4 v78, s[50:51]
	s_mov_b32 m0, s43
	s_nop 0
	global_load_lds_dwordx4 v79, s[50:51]
	s_waitcnt vmcnt(14)
	v_add_u32_e32 v54, s79, v59
	v_add_u32_e32 v55, s79, v60
	v_add_u32_e32 v56, s79, v61
	v_add_u32_e32 v57, s79, v62
	ds_read_b64_tr_b4 v[50:51], v160 offset:128
	ds_read_b64_tr_b4 v[52:53], v160 offset:1152
	ds_read_b64_tr_b4 v[130:131], v54
	ds_read_b64_tr_b4 v[132:133], v55
	ds_read_b64_tr_b4 v[134:135], v56
	ds_read_b64_tr_b4 v[136:137], v57
	s_waitcnt lgkmcnt(14)
	v_dot8c_i32_i4_e32 v38, v122, v48
	v_dot8c_i32_i4_e32 v39, v122, v46
	v_dot8c_i32_i4_e32 v40, v124, v48
	v_dot8c_i32_i4_e32 v41, v124, v46
	v_dot8c_i32_i4_e32 v42, v126, v48
	v_dot8c_i32_i4_e32 v43, v126, v46
	v_dot8c_i32_i4_e32 v44, v128, v48
	v_dot8c_i32_i4_e32 v45, v128, v46
	v_dot8c_i32_i4_e32 v38, v123, v49
	v_dot8c_i32_i4_e32 v39, v123, v47
	v_dot8c_i32_i4_e32 v40, v125, v49
	v_dot8c_i32_i4_e32 v41, v125, v47
	v_dot8c_i32_i4_e32 v42, v127, v49
	v_dot8c_i32_i4_e32 v43, v127, v47
	v_dot8c_i32_i4_e32 v44, v129, v49
	v_dot8c_i32_i4_e32 v45, v129, v47
	v_and_b32_e32 v78, 0xffff, v32
	v_lshrrev_b32_e32 v79, 16, v32
	v_lshl_add_u32 v78, v78, 7, v150
	v_lshl_add_u32 v79, v79, 7, v151
	s_mov_b32 m0, s78
	s_add_i32 s43, s78, 0x400
	global_load_lds_dwordx4 v78, s[50:51]
	s_mov_b32 m0, s43
	s_nop 0
	global_load_lds_dwordx4 v79, s[50:51]
	s_waitcnt vmcnt(14)
	v_add_u32_e32 v54, s98, v59
	v_add_u32_e32 v55, s98, v60
	v_add_u32_e32 v56, s98, v61
	v_add_u32_e32 v57, s98, v62
	ds_read_b64_tr_b4 v[46:47], v160 offset:256
	ds_read_b64_tr_b4 v[48:49], v160 offset:1280
	ds_read_b64_tr_b4 v[122:123], v54
	ds_read_b64_tr_b4 v[124:125], v55
	ds_read_b64_tr_b4 v[126:127], v56
	ds_read_b64_tr_b4 v[128:129], v57
	s_waitcnt lgkmcnt(6)
	v_dot8c_i32_i4_e32 v38, v130, v52
	v_dot8c_i32_i4_e32 v39, v130, v50
	v_dot8c_i32_i4_e32 v40, v132, v52
	v_dot8c_i32_i4_e32 v41, v132, v50
	v_dot8c_i32_i4_e32 v42, v134, v52
	v_dot8c_i32_i4_e32 v43, v134, v50
	v_dot8c_i32_i4_e32 v44, v136, v52
	v_dot8c_i32_i4_e32 v45, v136, v50
	v_dot8c_i32_i4_e32 v38, v131, v53
	v_dot8c_i32_i4_e32 v39, v131, v51
	v_dot8c_i32_i4_e32 v40, v133, v53
	v_dot8c_i32_i4_e32 v41, v133, v51
	v_dot8c_i32_i4_e32 v42, v135, v53
	v_dot8c_i32_i4_e32 v43, v135, v51
	v_dot8c_i32_i4_e32 v44, v137, v53
	v_dot8c_i32_i4_e32 v45, v137, v51
	v_and_b32_e32 v78, 0xffff, v33
	v_lshrrev_b32_e32 v79, 16, v33
	v_lshl_add_u32 v78, v78, 7, v150
	v_lshl_add_u32 v79, v79, 7, v151
	s_mov_b32 m0, s79
	s_add_i32 s43, s79, 0x400
	global_load_lds_dwordx4 v78, s[50:51]
	s_mov_b32 m0, s43
	s_nop 0
	global_load_lds_dwordx4 v79, s[50:51]
	s_waitcnt vmcnt(14)
	v_add_u32_e32 v54, s99, v59
	v_add_u32_e32 v55, s99, v60
	v_add_u32_e32 v56, s99, v61
	v_add_u32_e32 v57, s99, v62
	ds_read_b64_tr_b4 v[50:51], v160 offset:384
	ds_read_b64_tr_b4 v[52:53], v160 offset:1408
	ds_read_b64_tr_b4 v[130:131], v54
	ds_read_b64_tr_b4 v[132:133], v55
	ds_read_b64_tr_b4 v[134:135], v56
	ds_read_b64_tr_b4 v[136:137], v57
	s_waitcnt lgkmcnt(6)
	v_dot8c_i32_i4_e32 v38, v122, v48
	v_dot8c_i32_i4_e32 v39, v122, v46
	v_dot8c_i32_i4_e32 v40, v124, v48
	v_dot8c_i32_i4_e32 v41, v124, v46
	v_dot8c_i32_i4_e32 v42, v126, v48
	v_dot8c_i32_i4_e32 v43, v126, v46
	v_dot8c_i32_i4_e32 v44, v128, v48
	v_dot8c_i32_i4_e32 v45, v128, v46
	v_dot8c_i32_i4_e32 v38, v123, v49
	v_dot8c_i32_i4_e32 v39, v123, v47
	v_dot8c_i32_i4_e32 v40, v125, v49
	v_dot8c_i32_i4_e32 v41, v125, v47
	v_dot8c_i32_i4_e32 v42, v127, v49
	v_dot8c_i32_i4_e32 v43, v127, v47
	v_dot8c_i32_i4_e32 v44, v129, v49
	v_dot8c_i32_i4_e32 v45, v129, v47
	s_waitcnt lgkmcnt(15)
	v_and_b32_e32 v78, 0xffff, v18
	v_lshrrev_b32_e32 v79, 16, v18
	v_lshl_add_u32 v78, v78, 7, v152
	v_lshl_add_u32 v79, v79, 7, v153
	s_mov_b32 m0, s98
	s_add_i32 s43, s98, 0x400
	global_load_lds_dwordx4 v78, s[50:51]
	s_mov_b32 m0, s43
	s_nop 0
	global_load_lds_dwordx4 v79, s[50:51]
	s_waitcnt vmcnt(14)
	v_add_u32_e32 v54, s76, v59
	v_add_u32_e32 v55, s76, v60
	v_add_u32_e32 v56, s76, v61
	v_add_u32_e32 v57, s76, v62
	ds_read_b64_tr_b4 v[46:47], v160 offset:512
	ds_read_b64_tr_b4 v[48:49], v160 offset:1536
	ds_read_b64_tr_b4 v[122:123], v54
	ds_read_b64_tr_b4 v[124:125], v55
	ds_read_b64_tr_b4 v[126:127], v56
	ds_read_b64_tr_b4 v[128:129], v57
	s_waitcnt lgkmcnt(6)
; #define LAS __attribute__((address_space(3)))
; #define TR4(p_) __builtin_amdgcn_ds_read_tr4_b64_v2i32((LAS v2i*)(p_))
; #define CFENCE() asm volatile("" ::: "memory")
; __device__ __forceinline__ void peer_v_tokens(int j, const LAS unsigned short* EL, const LAS unsigned char* AL  , const LAS float* ASC  , const LAS int* SAL  , ...
;     ...
;         for (int m = 0; m < 2; ++m) {
;             const int idx = lane + 64 * m, tau = idx >> 4, sr = idx & 15, k = 16 * (sr & 7) + 2 * tau + (sr >> 3);
;             const int aq = (int)*(const LAS signed char*)(AL + tl * 128 + k); const int tq = aq + 8;
;             const unsigned lo = (((unsigned)tq & 15u) ^ 8u) * 0x11111111u, hi = ((unsigned)(tq >> 4) & 15u) * 0x11111111u;
;             typedef unsigned u2v __attribute__((ext_vector_type(2)));
;             u2v l2; l2.x = lo; l2.y = lo; u2v h2; h2.x = hi; h2.y = hi;
;             *(LAS u2v*)(ATL + 8 * idx) = l2; *(LAS u2v*)(ATL + 1024 + 8 * idx) = h2;
;         }
;         const float asc = ASC[tl]; const int sa = SAL[tl];
;         CFENCE();
;         int accH[4], accL[4];
; #pragma unroll
;         for (int st = 0; st < 16; ++st) {
;             const int p = st >> 2, q = st & 3;
;             if (st < 14) VDMA(st + 2, (st + 2) % 3);
;             if (st < 14) asm volatile("s_waitcnt vmcnt(8)" ::: "memory");
;             else if (st == 14) asm volatile("s_waitcnt vmcnt(4)" ::: "memory");
;             else asm volatile("s_waitcnt vmcnt(0)" ::: "memory");
;             if (q == 0) {
; #pragma unroll
;                 for (int r = 0; r < 4; ++r) { accH[r] = 0; accL[r] = 0; } }
; #pragma unroll
;             for (int tp = 0; tp < 2; ++tp) {
;                 const v2i ao = TR4(ATL + (2 * q + tp) * 128 + 8 * s16), ah = TR4(ATL + 1024 + (2 * q + tp) * 128 + 8 * s16);
; #pragma unroll
;                 for (int r = 0; r < 4; ++r) {
;                     const v2i d = TR4(ldsb + BUF[st % 3] + 2048 * tp + roff[r]);
;                     accH[r] = __builtin_amdgcn_sdot8(d.x, ah.x, accH[r], false); accH[r] = __builtin_amdgcn_sdot8(d.y, ah.y, accH[r], false);
;                     accL[r] = __builtin_amdgcn_sdot8(d.x, ao.x, accL[r], false); accL[r] = __builtin_amdgcn_sdot8(d.y, ao.y, accL[r], false);
;                 }
;             }
	v_dot8c_i32_i4_e32 v38, v130, v52
	v_dot8c_i32_i4_e32 v39, v130, v50
	v_dot8c_i32_i4_e32 v40, v132, v52
	v_dot8c_i32_i4_e32 v41, v132, v50
	v_dot8c_i32_i4_e32 v42, v134, v52
	v_dot8c_i32_i4_e32 v43, v134, v50
	v_dot8c_i32_i4_e32 v44, v136, v52
	v_dot8c_i32_i4_e32 v45, v136, v50
	v_dot8c_i32_i4_e32 v38, v131, v53
	v_dot8c_i32_i4_e32 v39, v131, v51
	v_dot8c_i32_i4_e32 v40, v133, v53
	v_dot8c_i32_i4_e32 v41, v133, v51
	v_dot8c_i32_i4_e32 v42, v135, v53
	v_dot8c_i32_i4_e32 v43, v135, v51
	v_dot8c_i32_i4_e32 v44, v137, v53
	v_dot8c_i32_i4_e32 v45, v137, v51
	v_and_b32_e32 v78, 0xffff, v19
	v_lshrrev_b32_e32 v79, 16, v19
	v_lshl_add_u32 v78, v78, 7, v152
	v_lshl_add_u32 v79, v79, 7, v153
	s_mov_b32 m0, s99
	s_add_i32 s43, s99, 0x400
	global_load_lds_dwordx4 v78, s[50:51]
	s_mov_b32 m0, s43
	s_nop 0
	global_load_lds_dwordx4 v79, s[50:51]
	s_waitcnt vmcnt(8)
	v_add_u32_e32 v54, s77, v59
	v_add_u32_e32 v55, s77, v60
	v_add_u32_e32 v56, s77, v61
	v_add_u32_e32 v57, s77, v62
	ds_read_b64_tr_b4 v[50:51], v160 offset:640
	ds_read_b64_tr_b4 v[52:53], v160 offset:1664
	ds_read_b64_tr_b4 v[130:131], v54
	ds_read_b64_tr_b4 v[132:133], v55
	ds_read_b64_tr_b4 v[134:135], v56
	ds_read_b64_tr_b4 v[136:137], v57
	s_waitcnt lgkmcnt(6)
	v_dot8c_i32_i4_e32 v38, v122, v48
	v_dot8c_i32_i4_e32 v39, v122, v46
	v_dot8c_i32_i4_e32 v40, v124, v48
	v_dot8c_i32_i4_e32 v41, v124, v46
	v_dot8c_i32_i4_e32 v42, v126, v48
	v_dot8c_i32_i4_e32 v43, v126, v46
	v_dot8c_i32_i4_e32 v44, v128, v48
	v_dot8c_i32_i4_e32 v45, v128, v46
	v_dot8c_i32_i4_e32 v38, v123, v49
	v_dot8c_i32_i4_e32 v39, v123, v47
	v_dot8c_i32_i4_e32 v40, v125, v49
	v_dot8c_i32_i4_e32 v41, v125, v47
	v_dot8c_i32_i4_e32 v42, v127, v49
	v_dot8c_i32_i4_e32 v43, v127, v47
	v_dot8c_i32_i4_e32 v44, v129, v49
	v_dot8c_i32_i4_e32 v45, v129, v47
	s_waitcnt lgkmcnt(15)
	v_add_u32_e32 v143, 8, v139
	v_and_b32_e32 v142, 15, v143
	v_xor_b32_e32 v142, 8, v142
	v_bfe_u32 v144, v143, 4, 4
	v_mul_lo_u32 v142, v142, s92
	v_mul_lo_u32 v144, v144, s92
	v_mov_b32_e32 v143, v142
	v_mov_b32_e32 v145, v144
	ds_write2st64_b64 v159, v[142:143], v[144:145] offset1:2
	v_and_b32_e32 v78, 0xffff, v20
	v_lshrrev_b32_e32 v79, 16, v20
	v_lshl_add_u32 v78, v78, 7, v152
	v_lshl_add_u32 v79, v79, 7, v153
	s_mov_b32 m0, s76
	s_add_i32 s43, s76, 0x400
	global_load_lds_dwordx4 v78, s[50:51]
	s_mov_b32 m0, s43
	s_nop 0
	global_load_lds_dwordx4 v79, s[50:51]
	s_waitcnt vmcnt(8)
	v_add_u32_e32 v54, s78, v59
	v_add_u32_e32 v55, s78, v60
	v_add_u32_e32 v56, s78, v61
	v_add_u32_e32 v57, s78, v62
	ds_read_b64_tr_b4 v[46:47], v160 offset:768
	ds_read_b64_tr_b4 v[48:49], v160 offset:1792
	ds_read_b64_tr_b4 v[122:123], v54
	ds_read_b64_tr_b4 v[124:125], v55
	ds_read_b64_tr_b4 v[126:127], v56
	ds_read_b64_tr_b4 v[128:129], v57
	s_waitcnt lgkmcnt(7)
	v_dot8c_i32_i4_e32 v38, v130, v52
	v_dot8c_i32_i4_e32 v39, v130, v50
	v_dot8c_i32_i4_e32 v40, v132, v52
	v_dot8c_i32_i4_e32 v41, v132, v50
	v_dot8c_i32_i4_e32 v42, v134, v52
	v_dot8c_i32_i4_e32 v43, v134, v50
	v_dot8c_i32_i4_e32 v44, v136, v52
	v_dot8c_i32_i4_e32 v45, v136, v50
	v_dot8c_i32_i4_e32 v38, v131, v53
	v_dot8c_i32_i4_e32 v39, v131, v51
	v_dot8c_i32_i4_e32 v40, v133, v53
	v_dot8c_i32_i4_e32 v41, v133, v51
	v_dot8c_i32_i4_e32 v42, v135, v53
	v_dot8c_i32_i4_e32 v43, v135, v51
	v_dot8c_i32_i4_e32 v44, v137, v53
	v_dot8c_i32_i4_e32 v45, v137, v51
	v_and_b32_e32 v78, 0xffff, v21
	v_lshrrev_b32_e32 v79, 16, v21
	v_lshl_add_u32 v78, v78, 7, v152
	v_lshl_add_u32 v79, v79, 7, v153
	s_mov_b32 m0, s77
	s_add_i32 s43, s77, 0x400
	global_load_lds_dwordx4 v78, s[50:51]
	s_mov_b32 m0, s43
	s_nop 0
	global_load_lds_dwordx4 v79, s[50:51]
	s_waitcnt vmcnt(8)
	v_add_u32_e32 v54, s79, v59
	v_add_u32_e32 v55, s79, v60
	v_add_u32_e32 v56, s79, v61
	v_add_u32_e32 v57, s79, v62
	ds_read_b64_tr_b4 v[50:51], v160 offset:896
	ds_read_b64_tr_b4 v[52:53], v160 offset:1920
	ds_read_b64_tr_b4 v[130:131], v54
	ds_read_b64_tr_b4 v[132:133], v55
	ds_read_b64_tr_b4 v[134:135], v56
	ds_read_b64_tr_b4 v[136:137], v57
	s_waitcnt lgkmcnt(6)
	v_dot8c_i32_i4_e32 v38, v122, v48
	v_dot8c_i32_i4_e32 v39, v122, v46
	v_dot8c_i32_i4_e32 v40, v124, v48
	v_dot8c_i32_i4_e32 v41, v124, v46
	v_dot8c_i32_i4_e32 v42, v126, v48
	v_dot8c_i32_i4_e32 v43, v126, v46
	v_dot8c_i32_i4_e32 v44, v128, v48
	v_dot8c_i32_i4_e32 v45, v128, v46
	v_dot8c_i32_i4_e32 v38, v123, v49
	v_dot8c_i32_i4_e32 v39, v123, v47
	v_dot8c_i32_i4_e32 v40, v125, v49
	v_dot8c_i32_i4_e32 v41, v125, v47
	v_dot8c_i32_i4_e32 v42, v127, v49
	v_dot8c_i32_i4_e32 v43, v127, v47
	v_dot8c_i32_i4_e32 v44, v129, v49
	v_dot8c_i32_i4_e32 v45, v129, v47
	v_and_b32_e32 v78, 0xffff, v22
	v_lshrrev_b32_e32 v79, 16, v22
	v_lshl_add_u32 v78, v78, 7, v152
	v_lshl_add_u32 v79, v79, 7, v153
	s_mov_b32 m0, s78
	s_add_i32 s43, s78, 0x400
	global_load_lds_dwordx4 v78, s[50:51]
	s_mov_b32 m0, s43
	s_nop 0
	global_load_lds_dwordx4 v79, s[50:51]
	s_waitcnt vmcnt(8)
	v_add_u32_e32 v54, s98, v59
	v_add_u32_e32 v55, s98, v60
	v_add_u32_e32 v56, s98, v61
	v_add_u32_e32 v57, s98, v62
	ds_read_b64_tr_b4 v[46:47], v160
	ds_read_b64_tr_b4 v[48:49], v160 offset:1024
	ds_read_b64_tr_b4 v[122:123], v54
	ds_read_b64_tr_b4 v[124:125], v55
	ds_read_b64_tr_b4 v[126:127], v56
	ds_read_b64_tr_b4 v[128:129], v57
	s_waitcnt lgkmcnt(6)
	v_dot8c_i32_i4_e32 v38, v130, v52
	v_dot8c_i32_i4_e32 v39, v130, v50
	v_dot8c_i32_i4_e32 v40, v132, v52
	v_dot8c_i32_i4_e32 v41, v132, v50
	v_dot8c_i32_i4_e32 v42, v134, v52
	v_dot8c_i32_i4_e32 v43, v134, v50
	v_dot8c_i32_i4_e32 v44, v136, v52
	v_dot8c_i32_i4_e32 v45, v136, v50
	v_dot8c_i32_i4_e32 v38, v131, v53
	v_dot8c_i32_i4_e32 v39, v131, v51
	v_dot8c_i32_i4_e32 v40, v133, v53
	v_dot8c_i32_i4_e32 v41, v133, v51
	v_dot8c_i32_i4_e32 v42, v135, v53
	v_dot8c_i32_i4_e32 v43, v135, v51
	v_dot8c_i32_i4_e32 v44, v137, v53
	v_dot8c_i32_i4_e32 v45, v137, v51
	s_nop 3
	s_waitcnt lgkmcnt(15)
; __device__ __forceinline__ void peer_v_tokens(int j, const LAS unsigned short* EL, const LAS unsigned char* AL  , const LAS float* ASC  , const LAS int* SAL  , ...
;     ...
;         for (int m = 0; m < 2; ++m) {
;             const int idx = lane + 64 * m, tau = idx >> 4, sr = idx & 15, k = 16 * (sr & 7) + 2 * tau + (sr >> 3);
;             const int aq = (int)*(const LAS signed char*)(AL + tl * 128 + k); const int tq = aq + 8;
;             const unsigned lo = (((unsigned)tq & 15u) ^ 8u) * 0x11111111u, hi = ((unsigned)(tq >> 4) & 15u) * 0x11111111u;
;             typedef unsigned u2v __attribute__((ext_vector_type(2)));
;             u2v l2; l2.x = lo; l2.y = lo; u2v h2; h2.x = hi; h2.y = hi;
;             *(LAS u2v*)(ATL + 8 * idx) = l2; *(LAS u2v*)(ATL + 1024 + 8 * idx) = h2;
;         }
;         const float asc = ASC[tl]; const int sa = SAL[tl];
;         CFENCE();
;         int accH[4], accL[4];
; #pragma unroll
;         for (int st = 0; st < 16; ++st) {
;             const int p = st >> 2, q = st & 3;
;             if (st < 14) VDMA(st + 2, (st + 2) % 3);
;             if (st < 14) asm volatile("s_waitcnt vmcnt(8)" ::: "memory");
;             else if (st == 14) asm volatile("s_waitcnt vmcnt(4)" ::: "memory");
;             else asm volatile("s_waitcnt vmcnt(0)" ::: "memory");
;             if (q == 0) {
; #pragma unroll
;                 for (int r = 0; r < 4; ++r) { accH[r] = 0; accL[r] = 0; } }
; #pragma unroll
;             for (int tp = 0; tp < 2; ++tp) {
;                 const v2i ao = TR4(ATL + (2 * q + tp) * 128 + 8 * s16), ah = TR4(ATL + 1024 + (2 * q + tp) * 128 + 8 * s16);
; #pragma unroll
;                 for (int r = 0; r < 4; ++r) {
;                     const v2i d = TR4(ldsb + BUF[st % 3] + 2048 * tp + roff[r]);
;                     accH[r] = __builtin_amdgcn_sdot8(d.x, ah.x, accH[r], false); accH[r] = __builtin_amdgcn_sdot8(d.y, ah.y, accH[r], false);
;                     accL[r] = __builtin_amdgcn_sdot8(d.x, ao.x, accL[r], false); accL[r] = __builtin_amdgcn_sdot8(d.y, ao.y, accL[r], false);
;                 }
;             }
;             asm volatile("s_waitcnt lgkmcnt(0)" ::: "memory");
;             if (q == 3) {
; #pragma unroll
;                 for (int r = 0; r < 4; ++r) STASH[256 * p + 16 * (grp + 4 * r) + pc] = f2bf(asc * (float)(2 * ((accH[r] << 4) + accL[r]) + sa));
;             }
;         }
;         CFENCE();
	v_lshlrev_b32_e32 v38, 5, v38
	v_lshlrev_b32_e32 v39, 1, v39
	v_add3_u32 v38, v39, v229, v38
	v_cvt_f32_i32_e32 v38, v38
	v_mul_f32_e32 v38, v228, v38
	v_lshlrev_b32_e32 v40, 5, v40
	v_lshlrev_b32_e32 v41, 1, v41
	v_add3_u32 v40, v41, v229, v40
	v_cvt_f32_i32_e32 v40, v40
	v_mul_f32_e32 v40, v228, v40
	v_lshlrev_b32_e32 v42, 5, v42
	v_lshlrev_b32_e32 v43, 1, v43
	v_add3_u32 v42, v43, v229, v42
	v_cvt_f32_i32_e32 v42, v42
	v_mul_f32_e32 v42, v228, v42
	v_lshlrev_b32_e32 v44, 5, v44
	v_lshlrev_b32_e32 v45, 1, v45
	v_add3_u32 v44, v45, v229, v44
	v_cvt_f32_i32_e32 v44, v44
	v_mul_f32_e32 v44, v228, v44
	v_cvt_pk_bf16_f32 v158, v38, v40
	v_cvt_pk_bf16_f32 v161, v42, v44
	ds_read_b128 v[252:255], v156
	s_add_i32 s44, s40, 8
	s_ashr_i32 s45, s44, 31
	s_lshl_b64 s[44:45], s[44:45], 12
	v_lshl_add_u64 v[80:81], v[36:37], 0, s[44:45]
	s_waitcnt lgkmcnt(0)
	v_mul_f32_e32 v218, v218, v252
	v_mul_f32_e32 v219, v219, v253
	v_mul_f32_e32 v220, v220, v254
	v_mul_f32_e32 v221, v221, v255
	global_store_dwordx4 v[80:81], v[218:221], off offset:2048 nt
	ds_read_b128 v[252:255], v156 offset:1024
	s_add_i32 s44, s40, 8
	s_ashr_i32 s45, s44, 31
	s_lshl_b64 s[44:45], s[44:45], 12
	v_lshl_add_u64 v[80:81], v[36:37], 0, s[44:45]
	s_waitcnt lgkmcnt(0)
	v_mul_f32_e32 v222, v222, v252
	v_mul_f32_e32 v223, v223, v253
	v_mul_f32_e32 v224, v224, v254
	v_mul_f32_e32 v225, v225, v255
	global_store_dwordx4 v[80:81], v[222:225], off offset:3072 nt
	v_add_u32_e32 v147, 8, v140
	v_and_b32_e32 v146, 15, v147
	v_xor_b32_e32 v146, 8, v146
	v_bfe_u32 v148, v147, 4, 4
	v_mul_lo_u32 v146, v146, s92
	v_mul_lo_u32 v148, v148, s92
	v_mov_b32_e32 v147, v146
	v_mov_b32_e32 v149, v148
	ds_write2st64_b64 v77, v[146:147], v[148:149] offset1:2
	v_add_u32_e32 v138, 0x1400, v74
	ds_read_u8 v139, v138
	v_add_u32_e32 v141, 0x1400, v73
	ds_read_u8 v140, v141
	s_add_i32 s43, s67, 128
	v_mov_b32_e32 v138, s43
	ds_read2st64_b32 v[228:229], v138 offset1:1
	ds_read_b128 v[26:29], v227 offset:10240
	ds_read_b128 v[30:33], v227 offset:10256
	v_mov_b32_e32 v38, 0
	v_mov_b32_e32 v39, 0
	v_mov_b32_e32 v40, 0
	v_mov_b32_e32 v41, 0
	v_mov_b32_e32 v42, 0
	v_mov_b32_e32 v43, 0
	v_mov_b32_e32 v44, 0
	v_mov_b32_e32 v45, 0
	v_and_b32_e32 v78, 0xffff, v23
	v_lshrrev_b32_e32 v79, 16, v23
	v_lshl_add_u32 v78, v78, 7, v152
	v_lshl_add_u32 v79, v79, 7, v153
	s_mov_b32 m0, s79
	s_add_i32 s43, s79, 0x400
	global_load_lds_dwordx4 v78, s[50:51]
	s_mov_b32 m0, s43
	s_nop 0
	global_load_lds_dwordx4 v79, s[50:51]
	s_waitcnt vmcnt(10)
	v_add_u32_e32 v54, s99, v59
	v_add_u32_e32 v55, s99, v60
	v_add_u32_e32 v56, s99, v61
	v_add_u32_e32 v57, s99, v62
	ds_read_b64_tr_b4 v[50:51], v160 offset:128
	ds_read_b64_tr_b4 v[52:53], v160 offset:1152
	ds_read_b64_tr_b4 v[130:131], v54
	ds_read_b64_tr_b4 v[132:133], v55
	ds_read_b64_tr_b4 v[134:135], v56
	ds_read_b64_tr_b4 v[136:137], v57
	s_waitcnt lgkmcnt(14)
	v_dot8c_i32_i4_e32 v38, v122, v48
	v_dot8c_i32_i4_e32 v39, v122, v46
	v_dot8c_i32_i4_e32 v40, v124, v48
	v_dot8c_i32_i4_e32 v41, v124, v46
	v_dot8c_i32_i4_e32 v42, v126, v48
	v_dot8c_i32_i4_e32 v43, v126, v46
	v_dot8c_i32_i4_e32 v44, v128, v48
	v_dot8c_i32_i4_e32 v45, v128, v46
	v_dot8c_i32_i4_e32 v38, v123, v49
	v_dot8c_i32_i4_e32 v39, v123, v47
	v_dot8c_i32_i4_e32 v40, v125, v49
	v_dot8c_i32_i4_e32 v41, v125, v47
	v_dot8c_i32_i4_e32 v42, v127, v49
	v_dot8c_i32_i4_e32 v43, v127, v47
	v_dot8c_i32_i4_e32 v44, v129, v49
	v_dot8c_i32_i4_e32 v45, v129, v47
	v_and_b32_e32 v78, 0xffff, v24
	v_lshrrev_b32_e32 v79, 16, v24
	v_lshl_add_u32 v78, v78, 7, v152
	v_lshl_add_u32 v79, v79, 7, v153
	s_mov_b32 m0, s98
	s_add_i32 s43, s98, 0x400
	global_load_lds_dwordx4 v78, s[50:51]
	s_mov_b32 m0, s43
	s_nop 0
	global_load_lds_dwordx4 v79, s[50:51]
	s_waitcnt vmcnt(10)
	v_add_u32_e32 v54, s76, v59
	v_add_u32_e32 v55, s76, v60
	v_add_u32_e32 v56, s76, v61
	v_add_u32_e32 v57, s76, v62
	ds_read_b64_tr_b4 v[46:47], v160 offset:256
	ds_read_b64_tr_b4 v[48:49], v160 offset:1280
	ds_read_b64_tr_b4 v[122:123], v54
	ds_read_b64_tr_b4 v[124:125], v55
	ds_read_b64_tr_b4 v[126:127], v56
	ds_read_b64_tr_b4 v[128:129], v57
	s_waitcnt lgkmcnt(6)
	v_dot8c_i32_i4_e32 v38, v130, v52
	v_dot8c_i32_i4_e32 v39, v130, v50
	v_dot8c_i32_i4_e32 v40, v132, v52
	v_dot8c_i32_i4_e32 v41, v132, v50
	v_dot8c_i32_i4_e32 v42, v134, v52
	v_dot8c_i32_i4_e32 v43, v134, v50
	v_dot8c_i32_i4_e32 v44, v136, v52
	v_dot8c_i32_i4_e32 v45, v136, v50
	v_dot8c_i32_i4_e32 v38, v131, v53
	v_dot8c_i32_i4_e32 v39, v131, v51
	v_dot8c_i32_i4_e32 v40, v133, v53
	v_dot8c_i32_i4_e32 v41, v133, v51
	v_dot8c_i32_i4_e32 v42, v135, v53
	v_dot8c_i32_i4_e32 v43, v135, v51
	v_dot8c_i32_i4_e32 v44, v137, v53
	v_dot8c_i32_i4_e32 v45, v137, v51
	ds_write_b16 v65, v178
	ds_write_b16_d16_hi v65, v178 offset:128
	ds_write_b16 v65, v179 offset:256
	ds_write_b16_d16_hi v65, v179 offset:384
	ds_write_b16 v65, v180 offset:512
	ds_write_b16_d16_hi v65, v180 offset:640
	ds_write_b16 v65, v181 offset:768
	ds_write_b16_d16_hi v65, v181 offset:896
	ds_write_b16 v65, v182 offset:1024
	ds_write_b16_d16_hi v65, v182 offset:1152
	ds_write_b16 v65, v183 offset:1280
	ds_write_b16_d16_hi v65, v183 offset:1408
	ds_write_b16 v65, v184 offset:1536
	ds_write_b16_d16_hi v65, v184 offset:1664
	ds_write_b16 v65, v185 offset:1792
	ds_write_b16_d16_hi v65, v185 offset:1920
	ds_read_b64 v[202:203], v154
	ds_read_b64 v[204:205], v154 offset:512
	ds_read_b64 v[206:207], v154 offset:1024
	ds_read_b64 v[208:209], v154 offset:1536
	v_and_b32_e32 v78, 0xffff, v25
	v_lshrrev_b32_e32 v79, 16, v25
	v_lshl_add_u32 v78, v78, 7, v152
	v_lshl_add_u32 v79, v79, 7, v153
	s_mov_b32 m0, s99
	s_add_i32 s43, s99, 0x400
	global_load_lds_dwordx4 v78, s[50:51]
	s_mov_b32 m0, s43
	s_nop 0
	global_load_lds_dwordx4 v79, s[50:51]
	s_waitcnt vmcnt(10)
; #define LAS __attribute__((address_space(3)))
; #define TR4(p_) __builtin_amdgcn_ds_read_tr4_b64_v2i32((LAS v2i*)(p_))
; #define CFENCE() asm volatile("" ::: "memory")
; __device__ __forceinline__ void peer_v_tokens(int j, const LAS unsigned short* EL, const LAS unsigned char* AL  , const LAS float* ASC  , const LAS int* SAL  , ...
;     ...
;         for (int m = 0; m < 2; ++m) {
;             const int idx = lane + 64 * m, tau = idx >> 4, sr = idx & 15, k = 16 * (sr & 7) + 2 * tau + (sr >> 3);
;             const int aq = (int)*(const LAS signed char*)(AL + tl * 128 + k); const int tq = aq + 8;
;             const unsigned lo = (((unsigned)tq & 15u) ^ 8u) * 0x11111111u, hi = ((unsigned)(tq >> 4) & 15u) * 0x11111111u;
;             typedef unsigned u2v __attribute__((ext_vector_type(2)));
;             u2v l2; l2.x = lo; l2.y = lo; u2v h2; h2.x = hi; h2.y = hi;
;             *(LAS u2v*)(ATL + 8 * idx) = l2; *(LAS u2v*)(ATL + 1024 + 8 * idx) = h2;
;         }
;         const float asc = ASC[tl]; const int sa = SAL[tl];
;         CFENCE();
;         int accH[4], accL[4];
; #pragma unroll
;         for (int st = 0; st < 16; ++st) {
;             const int p = st >> 2, q = st & 3;
;             if (st < 14) VDMA(st + 2, (st + 2) % 3);
;             if (st < 14) asm volatile("s_waitcnt vmcnt(8)" ::: "memory");
;             else if (st == 14) asm volatile("s_waitcnt vmcnt(4)" ::: "memory");
;             else asm volatile("s_waitcnt vmcnt(0)" ::: "memory");
;             if (q == 0) {
; #pragma unroll
;                 for (int r = 0; r < 4; ++r) { accH[r] = 0; accL[r] = 0; } }
; #pragma unroll
;             for (int tp = 0; tp < 2; ++tp) {
;                 const v2i ao = TR4(ATL + (2 * q + tp) * 128 + 8 * s16), ah = TR4(ATL + 1024 + (2 * q + tp) * 128 + 8 * s16);
; #pragma unroll
;                 for (int r = 0; r < 4; ++r) {
;                     const v2i d = TR4(ldsb + BUF[st % 3] + 2048 * tp + roff[r]);
;                     accH[r] = __builtin_amdgcn_sdot8(d.x, ah.x, accH[r], false); accH[r] = __builtin_amdgcn_sdot8(d.y, ah.y, accH[r], false);
;                     accL[r] = __builtin_amdgcn_sdot8(d.x, ao.x, accL[r], false); accL[r] = __builtin_amdgcn_sdot8(d.y, ao.y, accL[r], false);
;                 }
;             }
	v_add_u32_e32 v54, s77, v59
	v_add_u32_e32 v55, s77, v60
	v_add_u32_e32 v56, s77, v61
	v_add_u32_e32 v57, s77, v62
	ds_read_b64_tr_b4 v[50:51], v160 offset:384
	ds_read_b64_tr_b4 v[52:53], v160 offset:1408
	ds_read_b64_tr_b4 v[130:131], v54
	ds_read_b64_tr_b4 v[132:133], v55
	ds_read_b64_tr_b4 v[134:135], v56
	ds_read_b64_tr_b4 v[136:137], v57
	s_waitcnt lgkmcnt(15)
	v_dot8c_i32_i4_e32 v38, v122, v48
	v_dot8c_i32_i4_e32 v39, v122, v46
	v_dot8c_i32_i4_e32 v40, v124, v48
	v_dot8c_i32_i4_e32 v41, v124, v46
	v_dot8c_i32_i4_e32 v42, v126, v48
	v_dot8c_i32_i4_e32 v43, v126, v46
	v_dot8c_i32_i4_e32 v44, v128, v48
	v_dot8c_i32_i4_e32 v45, v128, v46
	v_dot8c_i32_i4_e32 v38, v123, v49
	v_dot8c_i32_i4_e32 v39, v123, v47
	v_dot8c_i32_i4_e32 v40, v125, v49
	v_dot8c_i32_i4_e32 v41, v125, v47
	v_dot8c_i32_i4_e32 v42, v127, v49
	v_dot8c_i32_i4_e32 v43, v127, v47
	v_dot8c_i32_i4_e32 v44, v129, v49
	v_dot8c_i32_i4_e32 v45, v129, v47
	s_waitcnt lgkmcnt(15)
	v_and_b32_e32 v78, 0xffff, v26
	v_lshrrev_b32_e32 v79, 16, v26
	v_lshl_add_u32 v78, v78, 7, v152
	v_lshl_add_u32 v79, v79, 7, v153
	s_mov_b32 m0, s76
	s_add_i32 s43, s76, 0x400
	global_load_lds_dwordx4 v78, s[50:51]
	s_mov_b32 m0, s43
	s_nop 0
	global_load_lds_dwordx4 v79, s[50:51]
	s_waitcnt vmcnt(10)
	v_add_u32_e32 v54, s78, v59
	v_add_u32_e32 v55, s78, v60
	v_add_u32_e32 v56, s78, v61
	v_add_u32_e32 v57, s78, v62
	ds_read_b64_tr_b4 v[46:47], v160 offset:512
	ds_read_b64_tr_b4 v[48:49], v160 offset:1536
	ds_read_b64_tr_b4 v[122:123], v54
	ds_read_b64_tr_b4 v[124:125], v55
	ds_read_b64_tr_b4 v[126:127], v56
	ds_read_b64_tr_b4 v[128:129], v57
	s_waitcnt lgkmcnt(6)
	v_dot8c_i32_i4_e32 v38, v130, v52
	v_dot8c_i32_i4_e32 v39, v130, v50
	v_dot8c_i32_i4_e32 v40, v132, v52
	v_dot8c_i32_i4_e32 v41, v132, v50
	v_dot8c_i32_i4_e32 v42, v134, v52
	v_dot8c_i32_i4_e32 v43, v134, v50
	v_dot8c_i32_i4_e32 v44, v136, v52
	v_dot8c_i32_i4_e32 v45, v136, v50
	v_dot8c_i32_i4_e32 v38, v131, v53
	v_dot8c_i32_i4_e32 v39, v131, v51
	v_dot8c_i32_i4_e32 v40, v133, v53
	v_dot8c_i32_i4_e32 v41, v133, v51
	v_dot8c_i32_i4_e32 v42, v135, v53
	v_dot8c_i32_i4_e32 v43, v135, v51
	v_dot8c_i32_i4_e32 v44, v137, v53
	v_dot8c_i32_i4_e32 v45, v137, v51
	v_and_b32_e32 v78, 0xffff, v27
	v_lshrrev_b32_e32 v79, 16, v27
	v_lshl_add_u32 v78, v78, 7, v152
	v_lshl_add_u32 v79, v79, 7, v153
	s_mov_b32 m0, s77
	s_add_i32 s43, s77, 0x400
	global_load_lds_dwordx4 v78, s[50:51]
	s_mov_b32 m0, s43
	s_nop 0
	global_load_lds_dwordx4 v79, s[50:51]
	s_waitcnt vmcnt(8)
	v_add_u32_e32 v54, s79, v59
	v_add_u32_e32 v55, s79, v60
	v_add_u32_e32 v56, s79, v61
	v_add_u32_e32 v57, s79, v62
	ds_read_b64_tr_b4 v[50:51], v160 offset:640
	ds_read_b64_tr_b4 v[52:53], v160 offset:1664
	ds_read_b64_tr_b4 v[130:131], v54
	ds_read_b64_tr_b4 v[132:133], v55
	ds_read_b64_tr_b4 v[134:135], v56
	ds_read_b64_tr_b4 v[136:137], v57
	s_waitcnt lgkmcnt(6)
	v_dot8c_i32_i4_e32 v38, v122, v48
	v_dot8c_i32_i4_e32 v39, v122, v46
	v_dot8c_i32_i4_e32 v40, v124, v48
	v_dot8c_i32_i4_e32 v41, v124, v46
	v_dot8c_i32_i4_e32 v42, v126, v48
	v_dot8c_i32_i4_e32 v43, v126, v46
	v_dot8c_i32_i4_e32 v44, v128, v48
	v_dot8c_i32_i4_e32 v45, v128, v46
	v_dot8c_i32_i4_e32 v38, v123, v49
	v_dot8c_i32_i4_e32 v39, v123, v47
	v_dot8c_i32_i4_e32 v40, v125, v49
	v_dot8c_i32_i4_e32 v41, v125, v47
	v_dot8c_i32_i4_e32 v42, v127, v49
	v_dot8c_i32_i4_e32 v43, v127, v47
	v_dot8c_i32_i4_e32 v44, v129, v49
	v_dot8c_i32_i4_e32 v45, v129, v47
	s_waitcnt lgkmcnt(15)
	v_add_u32_e32 v143, 8, v139
	v_and_b32_e32 v142, 15, v143
	v_xor_b32_e32 v142, 8, v142
	v_bfe_u32 v144, v143, 4, 4
	v_mul_lo_u32 v142, v142, s92
	v_mul_lo_u32 v144, v144, s92
	v_mov_b32_e32 v143, v142
	v_mov_b32_e32 v145, v144
	ds_write2st64_b64 v159, v[142:143], v[144:145] offset1:2
	v_and_b32_e32 v78, 0xffff, v28
	v_lshrrev_b32_e32 v79, 16, v28
	v_lshl_add_u32 v78, v78, 7, v152
	v_lshl_add_u32 v79, v79, 7, v153
	s_mov_b32 m0, s78
	s_add_i32 s43, s78, 0x400
	global_load_lds_dwordx4 v78, s[50:51]
	s_mov_b32 m0, s43
	s_nop 0
	global_load_lds_dwordx4 v79, s[50:51]
	s_waitcnt vmcnt(8)
	v_add_u32_e32 v54, s98, v59
	v_add_u32_e32 v55, s98, v60
	v_add_u32_e32 v56, s98, v61
	v_add_u32_e32 v57, s98, v62
	ds_read_b64_tr_b4 v[46:47], v160 offset:768
	ds_read_b64_tr_b4 v[48:49], v160 offset:1792
	ds_read_b64_tr_b4 v[122:123], v54
	ds_read_b64_tr_b4 v[124:125], v55
	ds_read_b64_tr_b4 v[126:127], v56
	ds_read_b64_tr_b4 v[128:129], v57
	s_waitcnt lgkmcnt(7)
	v_dot8c_i32_i4_e32 v38, v130, v52
	v_dot8c_i32_i4_e32 v39, v130, v50
	v_dot8c_i32_i4_e32 v40, v132, v52
	v_dot8c_i32_i4_e32 v41, v132, v50
	v_dot8c_i32_i4_e32 v42, v134, v52
	v_dot8c_i32_i4_e32 v43, v134, v50
	v_dot8c_i32_i4_e32 v44, v136, v52
	v_dot8c_i32_i4_e32 v45, v136, v50
	v_dot8c_i32_i4_e32 v38, v131, v53
	v_dot8c_i32_i4_e32 v39, v131, v51
	v_dot8c_i32_i4_e32 v40, v133, v53
	v_dot8c_i32_i4_e32 v41, v133, v51
	v_dot8c_i32_i4_e32 v42, v135, v53
	v_dot8c_i32_i4_e32 v43, v135, v51
	v_dot8c_i32_i4_e32 v44, v137, v53
	v_dot8c_i32_i4_e32 v45, v137, v51
	v_and_b32_e32 v78, 0xffff, v29
	v_lshrrev_b32_e32 v79, 16, v29
	v_lshl_add_u32 v78, v78, 7, v152
	v_lshl_add_u32 v79, v79, 7, v153
	s_mov_b32 m0, s79
	s_add_i32 s43, s79, 0x400
	global_load_lds_dwordx4 v78, s[50:51]
	s_mov_b32 m0, s43
	s_nop 0
	global_load_lds_dwordx4 v79, s[50:51]
	s_waitcnt vmcnt(8)
	v_add_u32_e32 v54, s99, v59
	v_add_u32_e32 v55, s99, v60
	v_add_u32_e32 v56, s99, v61
	v_add_u32_e32 v57, s99, v62
	ds_read_b64_tr_b4 v[50:51], v160 offset:896
	ds_read_b64_tr_b4 v[52:53], v160 offset:1920
	ds_read_b64_tr_b4 v[130:131], v54
	ds_read_b64_tr_b4 v[132:133], v55
	ds_read_b64_tr_b4 v[134:135], v56
	ds_read_b64_tr_b4 v[136:137], v57
	s_waitcnt lgkmcnt(6)
; __device__ __forceinline__ void peer_v_tokens(int j, const LAS unsigned short* EL, const LAS unsigned char* AL  , const LAS float* ASC  , const LAS int* SAL  , ...
;     ...
;         for (int m = 0; m < 2; ++m) {
;             const int idx = lane + 64 * m, tau = idx >> 4, sr = idx & 15, k = 16 * (sr & 7) + 2 * tau + (sr >> 3);
;             const int aq = (int)*(const LAS signed char*)(AL + tl * 128 + k); const int tq = aq + 8;
;             const unsigned lo = (((unsigned)tq & 15u) ^ 8u) * 0x11111111u, hi = ((unsigned)(tq >> 4) & 15u) * 0x11111111u;
;             typedef unsigned u2v __attribute__((ext_vector_type(2)));
;             u2v l2; l2.x = lo; l2.y = lo; u2v h2; h2.x = hi; h2.y = hi;
;             *(LAS u2v*)(ATL + 8 * idx) = l2; *(LAS u2v*)(ATL + 1024 + 8 * idx) = h2;
;         }
;         const float asc = ASC[tl]; const int sa = SAL[tl];
;         CFENCE();
;         int accH[4], accL[4];
; #pragma unroll
;         for (int st = 0; st < 16; ++st) {
;             const int p = st >> 2, q = st & 3;
;             if (st < 14) VDMA(st + 2, (st + 2) % 3);
;             if (st < 14) asm volatile("s_waitcnt vmcnt(8)" ::: "memory");
;             else if (st == 14) asm volatile("s_waitcnt vmcnt(4)" ::: "memory");
;             else asm volatile("s_waitcnt vmcnt(0)" ::: "memory");
;             if (q == 0) {
; #pragma unroll
;                 for (int r = 0; r < 4; ++r) { accH[r] = 0; accL[r] = 0; } }
; #pragma unroll
;             for (int tp = 0; tp < 2; ++tp) {
;                 const v2i ao = TR4(ATL + (2 * q + tp) * 128 + 8 * s16), ah = TR4(ATL + 1024 + (2 * q + tp) * 128 + 8 * s16);
; #pragma unroll
;                 for (int r = 0; r < 4; ++r) {
;                     const v2i d = TR4(ldsb + BUF[st % 3] + 2048 * tp + roff[r]);
;                     accH[r] = __builtin_amdgcn_sdot8(d.x, ah.x, accH[r], false); accH[r] = __builtin_amdgcn_sdot8(d.y, ah.y, accH[r], false);
;                     accL[r] = __builtin_amdgcn_sdot8(d.x, ao.x, accL[r], false); accL[r] = __builtin_amdgcn_sdot8(d.y, ao.y, accL[r], false);
;                 }
;             }
;             asm volatile("s_waitcnt lgkmcnt(0)" ::: "memory");
;             if (q == 3) {
; #pragma unroll
;                 for (int r = 0; r < 4; ++r) STASH[256 * p + 16 * (grp + 4 * r) + pc] = f2bf(asc * (float)(2 * ((accH[r] << 4) + accL[r]) + sa));
;             }
;         }
;         CFENCE();
	v_dot8c_i32_i4_e32 v38, v122, v48
	v_dot8c_i32_i4_e32 v39, v122, v46
	v_dot8c_i32_i4_e32 v40, v124, v48
	v_dot8c_i32_i4_e32 v41, v124, v46
	v_dot8c_i32_i4_e32 v42, v126, v48
	v_dot8c_i32_i4_e32 v43, v126, v46
	v_dot8c_i32_i4_e32 v44, v128, v48
	v_dot8c_i32_i4_e32 v45, v128, v46
	v_dot8c_i32_i4_e32 v38, v123, v49
	v_dot8c_i32_i4_e32 v39, v123, v47
	v_dot8c_i32_i4_e32 v40, v125, v49
	v_dot8c_i32_i4_e32 v41, v125, v47
	v_dot8c_i32_i4_e32 v42, v127, v49
	v_dot8c_i32_i4_e32 v43, v127, v47
	v_dot8c_i32_i4_e32 v44, v129, v49
	v_dot8c_i32_i4_e32 v45, v129, v47
	v_and_b32_e32 v78, 0xffff, v30
	v_lshrrev_b32_e32 v79, 16, v30
	v_lshl_add_u32 v78, v78, 7, v152
	v_lshl_add_u32 v79, v79, 7, v153
	s_mov_b32 m0, s98
	s_add_i32 s43, s98, 0x400
	global_load_lds_dwordx4 v78, s[50:51]
	s_mov_b32 m0, s43
	s_nop 0
	global_load_lds_dwordx4 v79, s[50:51]
	s_waitcnt vmcnt(8)
	v_add_u32_e32 v54, s76, v59
	v_add_u32_e32 v55, s76, v60
	v_add_u32_e32 v56, s76, v61
	v_add_u32_e32 v57, s76, v62
	ds_read_b64_tr_b4 v[46:47], v160
	ds_read_b64_tr_b4 v[48:49], v160 offset:1024
	ds_read_b64_tr_b4 v[122:123], v54
	ds_read_b64_tr_b4 v[124:125], v55
	ds_read_b64_tr_b4 v[126:127], v56
	ds_read_b64_tr_b4 v[128:129], v57
	s_waitcnt lgkmcnt(6)
	v_dot8c_i32_i4_e32 v38, v130, v52
	v_dot8c_i32_i4_e32 v39, v130, v50
	v_dot8c_i32_i4_e32 v40, v132, v52
	v_dot8c_i32_i4_e32 v41, v132, v50
	v_dot8c_i32_i4_e32 v42, v134, v52
	v_dot8c_i32_i4_e32 v43, v134, v50
	v_dot8c_i32_i4_e32 v44, v136, v52
	v_dot8c_i32_i4_e32 v45, v136, v50
	v_dot8c_i32_i4_e32 v38, v131, v53
	v_dot8c_i32_i4_e32 v39, v131, v51
	v_dot8c_i32_i4_e32 v40, v133, v53
	v_dot8c_i32_i4_e32 v41, v133, v51
	v_dot8c_i32_i4_e32 v42, v135, v53
	v_dot8c_i32_i4_e32 v43, v135, v51
	v_dot8c_i32_i4_e32 v44, v137, v53
	v_dot8c_i32_i4_e32 v45, v137, v51
	s_nop 3
	s_waitcnt lgkmcnt(15)
	v_lshlrev_b32_e32 v38, 5, v38
	v_lshlrev_b32_e32 v39, 1, v39
	v_add3_u32 v38, v39, v229, v38
	v_cvt_f32_i32_e32 v38, v38
	v_mul_f32_e32 v38, v228, v38
	v_lshlrev_b32_e32 v40, 5, v40
	v_lshlrev_b32_e32 v41, 1, v41
	v_add3_u32 v40, v41, v229, v40
	v_cvt_f32_i32_e32 v40, v40
	v_mul_f32_e32 v40, v228, v40
	v_lshlrev_b32_e32 v42, 5, v42
	v_lshlrev_b32_e32 v43, 1, v43
	v_add3_u32 v42, v43, v229, v42
	v_cvt_f32_i32_e32 v42, v42
	v_mul_f32_e32 v42, v228, v42
	v_lshlrev_b32_e32 v44, 5, v44
	v_lshlrev_b32_e32 v45, 1, v45
	v_add3_u32 v44, v45, v229, v44
	v_cvt_f32_i32_e32 v44, v44
	v_mul_f32_e32 v44, v228, v44
	v_cvt_pk_bf16_f32 v238, v38, v40
	v_cvt_pk_bf16_f32 v239, v42, v44
	v_add_u32_e32 v147, 8, v140
	v_and_b32_e32 v146, 15, v147
	v_xor_b32_e32 v146, 8, v146
	v_bfe_u32 v148, v147, 4, 4
	v_mul_lo_u32 v146, v146, s92
	v_mul_lo_u32 v148, v148, s92
	v_mov_b32_e32 v147, v146
	v_mov_b32_e32 v149, v148
	ds_write2st64_b64 v77, v[146:147], v[148:149] offset1:2
	v_add_u32_e32 v138, 0x1800, v74
	ds_read_u8 v139, v138
	v_add_u32_e32 v141, 0x1800, v73
	ds_read_u8 v140, v141
	s_add_i32 s43, s67, 160
	v_mov_b32_e32 v138, s43
	ds_read2st64_b32 v[228:229], v138 offset1:1
	ds_read_b128 v[18:21], v227 offset:12288
	ds_read_b128 v[22:25], v227 offset:12304
	v_mov_b32_e32 v38, 0
	v_mov_b32_e32 v39, 0
	v_mov_b32_e32 v40, 0
	v_mov_b32_e32 v41, 0
	v_mov_b32_e32 v42, 0
	v_mov_b32_e32 v43, 0
	v_mov_b32_e32 v44, 0
	v_mov_b32_e32 v45, 0
	v_and_b32_e32 v78, 0xffff, v31
	v_lshrrev_b32_e32 v79, 16, v31
	v_lshl_add_u32 v78, v78, 7, v152
	v_lshl_add_u32 v79, v79, 7, v153
	s_mov_b32 m0, s99
	s_add_i32 s43, s99, 0x400
	global_load_lds_dwordx4 v78, s[50:51]
	s_mov_b32 m0, s43
	s_nop 0
	global_load_lds_dwordx4 v79, s[50:51]
	s_waitcnt vmcnt(8)
	v_add_u32_e32 v54, s77, v59
	v_add_u32_e32 v55, s77, v60
	v_add_u32_e32 v56, s77, v61
	v_add_u32_e32 v57, s77, v62
	ds_read_b64_tr_b4 v[50:51], v160 offset:128
	ds_read_b64_tr_b4 v[52:53], v160 offset:1152
	ds_read_b64_tr_b4 v[130:131], v54
	ds_read_b64_tr_b4 v[132:133], v55
	ds_read_b64_tr_b4 v[134:135], v56
	ds_read_b64_tr_b4 v[136:137], v57
	s_waitcnt lgkmcnt(12)
	s_waitcnt vmcnt(36) lgkmcnt(15)
	v_lshlrev_b32_e32 v210, 16, v194
	v_and_b32_e32 v211, 0xffff0000, v194
	v_lshlrev_b32_e32 v142, 16, v202
	v_and_b32_e32 v143, 0xffff0000, v202
	v_add_f32_e32 v210, v210, v142
	v_add_f32_e32 v211, v211, v143
	v_lshlrev_b32_e32 v212, 16, v195
	v_and_b32_e32 v213, 0xffff0000, v195
	v_lshlrev_b32_e32 v142, 16, v203
	v_and_b32_e32 v143, 0xffff0000, v203
	v_add_f32_e32 v212, v212, v142
	v_add_f32_e32 v213, v213, v143
	v_lshlrev_b32_e32 v214, 16, v196
	v_and_b32_e32 v215, 0xffff0000, v196
	v_lshlrev_b32_e32 v142, 16, v204
	v_and_b32_e32 v143, 0xffff0000, v204
	v_add_f32_e32 v214, v214, v142
	v_add_f32_e32 v215, v215, v143
	v_lshlrev_b32_e32 v216, 16, v197
	v_and_b32_e32 v217, 0xffff0000, v197
	v_lshlrev_b32_e32 v142, 16, v205
	v_and_b32_e32 v143, 0xffff0000, v205
	v_add_f32_e32 v216, v216, v142
	v_add_f32_e32 v217, v217, v143
	v_lshlrev_b32_e32 v218, 16, v198
	v_and_b32_e32 v219, 0xffff0000, v198
	v_lshlrev_b32_e32 v142, 16, v206
	v_and_b32_e32 v143, 0xffff0000, v206
	v_add_f32_e32 v218, v218, v142
	v_add_f32_e32 v219, v219, v143
	v_lshlrev_b32_e32 v220, 16, v199
	v_and_b32_e32 v221, 0xffff0000, v199
	v_lshlrev_b32_e32 v142, 16, v207
	v_and_b32_e32 v143, 0xffff0000, v207
	v_add_f32_e32 v220, v220, v142
	v_add_f32_e32 v221, v221, v143
	v_lshlrev_b32_e32 v222, 16, v200
	v_and_b32_e32 v223, 0xffff0000, v200
	v_lshlrev_b32_e32 v142, 16, v208
	v_and_b32_e32 v143, 0xffff0000, v208
	v_add_f32_e32 v222, v222, v142
	v_add_f32_e32 v223, v223, v143
	v_lshlrev_b32_e32 v224, 16, v201
	v_and_b32_e32 v225, 0xffff0000, v201
	v_lshlrev_b32_e32 v142, 16, v209
	v_and_b32_e32 v143, 0xffff0000, v209
	v_add_f32_e32 v224, v224, v142
	v_add_f32_e32 v225, v225, v143
	v_mov_b32_e32 v144, 0
; __device__ __forceinline__ void peer_v_tokens(int j, const LAS unsigned short* EL, const LAS unsigned char* AL  , const LAS float* ASC  , const LAS int* SAL  , ...
;     ...
;         for (int st = 0; st < 16; ++st) {
;             const int p = st >> 2, q = st & 3;
;             if (st < 14) VDMA(st + 2, (st + 2) % 3);
;             if (st < 14) asm volatile("s_waitcnt vmcnt(8)" ::: "memory");
;             else if (st == 14) asm volatile("s_waitcnt vmcnt(4)" ::: "memory");
;             else asm volatile("s_waitcnt vmcnt(0)" ::: "memory");
;             if (q == 0) {
; #pragma unroll
;                 for (int r = 0; r < 4; ++r) { accH[r] = 0; accL[r] = 0; } }
; #pragma unroll
;             for (int tp = 0; tp < 2; ++tp) {
;                 const v2i ao = TR4(ATL + (2 * q + tp) * 128 + 8 * s16), ah = TR4(ATL + 1024 + (2 * q + tp) * 128 + 8 * s16);
; #pragma unroll
;                 for (int r = 0; r < 4; ++r) {
;                     const v2i d = TR4(ldsb + BUF[st % 3] + 2048 * tp + roff[r]);
;                     accH[r] = __builtin_amdgcn_sdot8(d.x, ah.x, accH[r], false); accH[r] = __builtin_amdgcn_sdot8(d.y, ah.y, accH[r], false);
;                     accL[r] = __builtin_amdgcn_sdot8(d.x, ao.x, accL[r], false); accL[r] = __builtin_amdgcn_sdot8(d.y, ao.y, accL[r], false);
;                 }
;             }
;             asm volatile("s_waitcnt lgkmcnt(0)" ::: "memory");
;             if (q == 3) {
; #pragma unroll
;                 for (int r = 0; r < 4; ++r) STASH[256 * p + 16 * (grp + 4 * r) + pc] = f2bf(asc * (float)(2 * ((accH[r] << 4) + accL[r]) + sa));
;             }
;         }
;         CFENCE();
;         {
;             float4 v[4]; float ss = 0.f;
; #pragma unroll
;             for (int jq = 0; jq < 4; ++jq) { typedef unsigned u2v __attribute__((ext_vector_type(2))); const u2v pw = *(const LAS u2v*)(STASH + 4 * lane + 256 * jq); const uint2 hw = hv[jq];
;                 v[jq] = make_float4(__uint_as_float(hw.x << 16) + __uint_as_float(pw.x << 16), __uint_as_float(hw.x & 0xffff0000u) + __uint_as_float(pw.x & 0xffff0000u),
;                                     __uint_as_float(hw.y << 16) + __uint_as_float(pw.y << 16), __uint_as_float(hw.y & 0xffff0000u) + __uint_as_float(pw.y & 0xffff0000u));
;                 ss += v[jq].x * v[jq].x + v[jq].y * v[jq].y + v[jq].z * v[jq].z + v[jq].w * v[jq].w; }
;             ss = wave_sum(ss);
	v_mul_f32_e32 v145, v210, v210
	v_fmac_f32_e32 v145, v211, v211
	v_fmac_f32_e32 v145, v212, v212
	v_fmac_f32_e32 v145, v213, v213
	v_add_f32_e32 v144, v144, v145
	v_mul_f32_e32 v145, v214, v214
	v_fmac_f32_e32 v145, v215, v215
	v_fmac_f32_e32 v145, v216, v216
	v_fmac_f32_e32 v145, v217, v217
	v_add_f32_e32 v144, v144, v145
	v_mul_f32_e32 v145, v218, v218
	v_fmac_f32_e32 v145, v219, v219
	v_fmac_f32_e32 v145, v220, v220
	v_fmac_f32_e32 v145, v221, v221
	v_add_f32_e32 v144, v144, v145
	v_mul_f32_e32 v145, v222, v222
	v_fmac_f32_e32 v145, v223, v223
	v_fmac_f32_e32 v145, v224, v224
	v_fmac_f32_e32 v145, v225, v225
	v_add_f32_e32 v144, v144, v145
	s_nop 1
	v_add_f32_dpp v144, v144, v144 quad_perm:[1,0,3,2] row_mask:0xf bank_mask:0xf bound_ctrl:1
	s_nop 1
	v_add_f32_dpp v144, v144, v144 quad_perm:[2,3,0,1] row_mask:0xf bank_mask:0xf bound_ctrl:1
	s_nop 1
	v_add_f32_dpp v144, v144, v144 row_half_mirror row_mask:0xf bank_mask:0xf bound_ctrl:1
	s_nop 1
	v_add_f32_dpp v144, v144, v144 row_mirror row_mask:0xf bank_mask:0xf bound_ctrl:1
	s_nop 1
	v_readlane_b32 s10, v144, 0
	v_readlane_b32 s11, v144, 16
	v_readlane_b32 s14, v144, 32
	v_readlane_b32 s15, v144, 48
	s_nop 3
	v_mov_b32_e32 v144, s11
	v_mov_b32_e32 v145, s15
	v_add_f32_e32 v144, s10, v144
	v_add_f32_e32 v145, s14, v145
	v_add_f32_e32 v144, v144, v145
	v_fmamk_f32 v144, v144, 0x3a800000, v111
	v_rsq_f32_e32 v144, v144
	s_nop 0
	v_mul_f32_e32 v210, v210, v144
	v_mul_f32_e32 v211, v211, v144
	v_mul_f32_e32 v212, v212, v144
	v_mul_f32_e32 v213, v213, v144
	v_mul_f32_e32 v214, v214, v144
	v_mul_f32_e32 v215, v215, v144
	v_mul_f32_e32 v216, v216, v144
	v_mul_f32_e32 v217, v217, v144
	v_mul_f32_e32 v218, v218, v144
	v_mul_f32_e32 v219, v219, v144
	v_mul_f32_e32 v220, v220, v144
	v_mul_f32_e32 v221, v221, v144
	v_mul_f32_e32 v222, v222, v144
	v_mul_f32_e32 v223, v223, v144
	v_mul_f32_e32 v224, v224, v144
	v_mul_f32_e32 v225, v225, v144
	v_dot8c_i32_i4_e32 v38, v122, v48
	v_dot8c_i32_i4_e32 v39, v122, v46
	v_dot8c_i32_i4_e32 v40, v124, v48
	v_dot8c_i32_i4_e32 v41, v124, v46
	v_dot8c_i32_i4_e32 v42, v126, v48
	v_dot8c_i32_i4_e32 v43, v126, v46
	v_dot8c_i32_i4_e32 v44, v128, v48
	v_dot8c_i32_i4_e32 v45, v128, v46
	v_dot8c_i32_i4_e32 v38, v123, v49
	v_dot8c_i32_i4_e32 v39, v123, v47
	v_dot8c_i32_i4_e32 v40, v125, v49
	v_dot8c_i32_i4_e32 v41, v125, v47
	v_dot8c_i32_i4_e32 v42, v127, v49
	v_dot8c_i32_i4_e32 v43, v127, v47
	v_dot8c_i32_i4_e32 v44, v129, v49
	v_dot8c_i32_i4_e32 v45, v129, v47
	v_and_b32_e32 v78, 0xffff, v32
	v_lshrrev_b32_e32 v79, 16, v32
	v_lshl_add_u32 v78, v78, 7, v152
	v_lshl_add_u32 v79, v79, 7, v153
	s_mov_b32 m0, s76
	s_add_i32 s43, s76, 0x400
	global_load_lds_dwordx4 v78, s[50:51]
	s_mov_b32 m0, s43
	s_nop 0
	global_load_lds_dwordx4 v79, s[50:51]
	s_waitcnt vmcnt(8)
	v_add_u32_e32 v54, s78, v59
	v_add_u32_e32 v55, s78, v60
	v_add_u32_e32 v56, s78, v61
	v_add_u32_e32 v57, s78, v62
	ds_read_b64_tr_b4 v[46:47], v160 offset:256
	ds_read_b64_tr_b4 v[48:49], v160 offset:1280
	ds_read_b64_tr_b4 v[122:123], v54
	ds_read_b64_tr_b4 v[124:125], v55
	ds_read_b64_tr_b4 v[126:127], v56
	ds_read_b64_tr_b4 v[128:129], v57
	s_waitcnt lgkmcnt(6)
	v_dot8c_i32_i4_e32 v38, v130, v52
	v_dot8c_i32_i4_e32 v39, v130, v50
	v_dot8c_i32_i4_e32 v40, v132, v52
	v_dot8c_i32_i4_e32 v41, v132, v50
	v_dot8c_i32_i4_e32 v42, v134, v52
	v_dot8c_i32_i4_e32 v43, v134, v50
	v_dot8c_i32_i4_e32 v44, v136, v52
	v_dot8c_i32_i4_e32 v45, v136, v50
	v_dot8c_i32_i4_e32 v38, v131, v53
	v_dot8c_i32_i4_e32 v39, v131, v51
	v_dot8c_i32_i4_e32 v40, v133, v53
	v_dot8c_i32_i4_e32 v41, v133, v51
	v_dot8c_i32_i4_e32 v42, v135, v53
	v_dot8c_i32_i4_e32 v43, v135, v51
	v_dot8c_i32_i4_e32 v44, v137, v53
	v_dot8c_i32_i4_e32 v45, v137, v51
	v_and_b32_e32 v78, 0xffff, v33
	v_lshrrev_b32_e32 v79, 16, v33
	v_lshl_add_u32 v78, v78, 7, v152
	v_lshl_add_u32 v79, v79, 7, v153
	s_mov_b32 m0, s77
	s_add_i32 s43, s77, 0x400
	global_load_lds_dwordx4 v78, s[50:51]
	s_mov_b32 m0, s43
	s_nop 0
	global_load_lds_dwordx4 v79, s[50:51]
	s_waitcnt vmcnt(8)
	v_add_u32_e32 v54, s79, v59
	v_add_u32_e32 v55, s79, v60
	v_add_u32_e32 v56, s79, v61
	v_add_u32_e32 v57, s79, v62
	ds_read_b64_tr_b4 v[50:51], v160 offset:384
	ds_read_b64_tr_b4 v[52:53], v160 offset:1408
	ds_read_b64_tr_b4 v[130:131], v54
	ds_read_b64_tr_b4 v[132:133], v55
	ds_read_b64_tr_b4 v[134:135], v56
	ds_read_b64_tr_b4 v[136:137], v57
	s_waitcnt lgkmcnt(6)
	v_dot8c_i32_i4_e32 v38, v122, v48
	v_dot8c_i32_i4_e32 v39, v122, v46
	v_dot8c_i32_i4_e32 v40, v124, v48
	v_dot8c_i32_i4_e32 v41, v124, v46
	v_dot8c_i32_i4_e32 v42, v126, v48
	v_dot8c_i32_i4_e32 v43, v126, v46
	v_dot8c_i32_i4_e32 v44, v128, v48
	v_dot8c_i32_i4_e32 v45, v128, v46
	v_dot8c_i32_i4_e32 v38, v123, v49
	v_dot8c_i32_i4_e32 v39, v123, v47
	v_dot8c_i32_i4_e32 v40, v125, v49
	v_dot8c_i32_i4_e32 v41, v125, v47
	v_dot8c_i32_i4_e32 v42, v127, v49
	v_dot8c_i32_i4_e32 v43, v127, v47
	v_dot8c_i32_i4_e32 v44, v129, v49
	v_dot8c_i32_i4_e32 v45, v129, v47
	s_waitcnt lgkmcnt(15)
	v_and_b32_e32 v78, 0xffff, v18
	v_lshrrev_b32_e32 v79, 16, v18
	v_lshl_add_u32 v78, v78, 7, v152
	v_lshl_add_u32 v79, v79, 7, v153
	s_mov_b32 m0, s78
	s_add_i32 s43, s78, 0x400
	global_load_lds_dwordx4 v78, s[50:51]
	s_mov_b32 m0, s43
	s_nop 0
	global_load_lds_dwordx4 v79, s[50:51]
	s_waitcnt vmcnt(8)
	v_add_u32_e32 v54, s98, v59
	v_add_u32_e32 v55, s98, v60
	v_add_u32_e32 v56, s98, v61
	v_add_u32_e32 v57, s98, v62
	ds_read_b64_tr_b4 v[46:47], v160 offset:512
	ds_read_b64_tr_b4 v[48:49], v160 offset:1536
	ds_read_b64_tr_b4 v[122:123], v54
	ds_read_b64_tr_b4 v[124:125], v55
	ds_read_b64_tr_b4 v[126:127], v56
	ds_read_b64_tr_b4 v[128:129], v57
	s_waitcnt lgkmcnt(6)
; #define LAS __attribute__((address_space(3)))
; #define TR4(p_) __builtin_amdgcn_ds_read_tr4_b64_v2i32((LAS v2i*)(p_))
; #define CFENCE() asm volatile("" ::: "memory")
; __device__ __forceinline__ void peer_v_tokens(int j, const LAS unsigned short* EL, const LAS unsigned char* AL  , const LAS float* ASC  , const LAS int* SAL  , ...
;     ...
;         for (int m = 0; m < 2; ++m) {
;             const int idx = lane + 64 * m, tau = idx >> 4, sr = idx & 15, k = 16 * (sr & 7) + 2 * tau + (sr >> 3);
;             const int aq = (int)*(const LAS signed char*)(AL + tl * 128 + k); const int tq = aq + 8;
;             const unsigned lo = (((unsigned)tq & 15u) ^ 8u) * 0x11111111u, hi = ((unsigned)(tq >> 4) & 15u) * 0x11111111u;
;             typedef unsigned u2v __attribute__((ext_vector_type(2)));
;             u2v l2; l2.x = lo; l2.y = lo; u2v h2; h2.x = hi; h2.y = hi;
;             *(LAS u2v*)(ATL + 8 * idx) = l2; *(LAS u2v*)(ATL + 1024 + 8 * idx) = h2;
;         }
;         const float asc = ASC[tl]; const int sa = SAL[tl];
;         CFENCE();
;         int accH[4], accL[4];
; #pragma unroll
;         for (int st = 0; st < 16; ++st) {
;             const int p = st >> 2, q = st & 3;
;             if (st < 14) VDMA(st + 2, (st + 2) % 3);
;             if (st < 14) asm volatile("s_waitcnt vmcnt(8)" ::: "memory");
;             else if (st == 14) asm volatile("s_waitcnt vmcnt(4)" ::: "memory");
;             else asm volatile("s_waitcnt vmcnt(0)" ::: "memory");
;             if (q == 0) {
; #pragma unroll
;                 for (int r = 0; r < 4; ++r) { accH[r] = 0; accL[r] = 0; } }
; #pragma unroll
;             for (int tp = 0; tp < 2; ++tp) {
;                 const v2i ao = TR4(ATL + (2 * q + tp) * 128 + 8 * s16), ah = TR4(ATL + 1024 + (2 * q + tp) * 128 + 8 * s16);
; #pragma unroll
;                 for (int r = 0; r < 4; ++r) {
;                     const v2i d = TR4(ldsb + BUF[st % 3] + 2048 * tp + roff[r]);
;                     accH[r] = __builtin_amdgcn_sdot8(d.x, ah.x, accH[r], false); accH[r] = __builtin_amdgcn_sdot8(d.y, ah.y, accH[r], false);
;                     accL[r] = __builtin_amdgcn_sdot8(d.x, ao.x, accL[r], false); accL[r] = __builtin_amdgcn_sdot8(d.y, ao.y, accL[r], false);
;                 }
;             }
	v_dot8c_i32_i4_e32 v38, v130, v52
	v_dot8c_i32_i4_e32 v39, v130, v50
	v_dot8c_i32_i4_e32 v40, v132, v52
	v_dot8c_i32_i4_e32 v41, v132, v50
	v_dot8c_i32_i4_e32 v42, v134, v52
	v_dot8c_i32_i4_e32 v43, v134, v50
	v_dot8c_i32_i4_e32 v44, v136, v52
	v_dot8c_i32_i4_e32 v45, v136, v50
	v_dot8c_i32_i4_e32 v38, v131, v53
	v_dot8c_i32_i4_e32 v39, v131, v51
	v_dot8c_i32_i4_e32 v40, v133, v53
	v_dot8c_i32_i4_e32 v41, v133, v51
	v_dot8c_i32_i4_e32 v42, v135, v53
	v_dot8c_i32_i4_e32 v43, v135, v51
	v_dot8c_i32_i4_e32 v44, v137, v53
	v_dot8c_i32_i4_e32 v45, v137, v51
	v_and_b32_e32 v78, 0xffff, v19
	v_lshrrev_b32_e32 v79, 16, v19
	v_lshl_add_u32 v78, v78, 7, v152
	v_lshl_add_u32 v79, v79, 7, v153
	s_mov_b32 m0, s79
	s_add_i32 s43, s79, 0x400
	global_load_lds_dwordx4 v78, s[50:51]
	s_mov_b32 m0, s43
	s_nop 0
	global_load_lds_dwordx4 v79, s[50:51]
	s_waitcnt vmcnt(8)
	v_add_u32_e32 v54, s99, v59
	v_add_u32_e32 v55, s99, v60
	v_add_u32_e32 v56, s99, v61
	v_add_u32_e32 v57, s99, v62
	ds_read_b64_tr_b4 v[50:51], v160 offset:640
	ds_read_b64_tr_b4 v[52:53], v160 offset:1664
	ds_read_b64_tr_b4 v[130:131], v54
	ds_read_b64_tr_b4 v[132:133], v55
	ds_read_b64_tr_b4 v[134:135], v56
	ds_read_b64_tr_b4 v[136:137], v57
	s_waitcnt lgkmcnt(6)
	v_dot8c_i32_i4_e32 v38, v122, v48
	v_dot8c_i32_i4_e32 v39, v122, v46
	v_dot8c_i32_i4_e32 v40, v124, v48
	v_dot8c_i32_i4_e32 v41, v124, v46
	v_dot8c_i32_i4_e32 v42, v126, v48
	v_dot8c_i32_i4_e32 v43, v126, v46
	v_dot8c_i32_i4_e32 v44, v128, v48
	v_dot8c_i32_i4_e32 v45, v128, v46
	v_dot8c_i32_i4_e32 v38, v123, v49
	v_dot8c_i32_i4_e32 v39, v123, v47
	v_dot8c_i32_i4_e32 v40, v125, v49
	v_dot8c_i32_i4_e32 v41, v125, v47
	v_dot8c_i32_i4_e32 v42, v127, v49
	v_dot8c_i32_i4_e32 v43, v127, v47
	v_dot8c_i32_i4_e32 v44, v129, v49
	v_dot8c_i32_i4_e32 v45, v129, v47
	s_waitcnt lgkmcnt(15)
	v_add_u32_e32 v143, 8, v139
	v_and_b32_e32 v142, 15, v143
	v_xor_b32_e32 v142, 8, v142
	v_bfe_u32 v144, v143, 4, 4
	v_mul_lo_u32 v142, v142, s92
	v_mul_lo_u32 v144, v144, s92
	v_mov_b32_e32 v143, v142
	v_mov_b32_e32 v145, v144
	ds_write2st64_b64 v159, v[142:143], v[144:145] offset1:2
	v_and_b32_e32 v78, 0xffff, v20
	v_lshrrev_b32_e32 v79, 16, v20
	v_lshl_add_u32 v78, v78, 7, v152
	v_lshl_add_u32 v79, v79, 7, v153
	s_mov_b32 m0, s98
	s_add_i32 s43, s98, 0x400
	global_load_lds_dwordx4 v78, s[50:51]
	s_mov_b32 m0, s43
	s_nop 0
	global_load_lds_dwordx4 v79, s[50:51]
	s_waitcnt vmcnt(8)
	v_add_u32_e32 v54, s76, v59
	v_add_u32_e32 v55, s76, v60
	v_add_u32_e32 v56, s76, v61
	v_add_u32_e32 v57, s76, v62
	ds_read_b64_tr_b4 v[46:47], v160 offset:768
	ds_read_b64_tr_b4 v[48:49], v160 offset:1792
	ds_read_b64_tr_b4 v[122:123], v54
	ds_read_b64_tr_b4 v[124:125], v55
	ds_read_b64_tr_b4 v[126:127], v56
	ds_read_b64_tr_b4 v[128:129], v57
	s_waitcnt lgkmcnt(7)
	v_dot8c_i32_i4_e32 v38, v130, v52
	v_dot8c_i32_i4_e32 v39, v130, v50
	v_dot8c_i32_i4_e32 v40, v132, v52
	v_dot8c_i32_i4_e32 v41, v132, v50
	v_dot8c_i32_i4_e32 v42, v134, v52
	v_dot8c_i32_i4_e32 v43, v134, v50
	v_dot8c_i32_i4_e32 v44, v136, v52
	v_dot8c_i32_i4_e32 v45, v136, v50
	v_dot8c_i32_i4_e32 v38, v131, v53
	v_dot8c_i32_i4_e32 v39, v131, v51
	v_dot8c_i32_i4_e32 v40, v133, v53
	v_dot8c_i32_i4_e32 v41, v133, v51
	v_dot8c_i32_i4_e32 v42, v135, v53
	v_dot8c_i32_i4_e32 v43, v135, v51
	v_dot8c_i32_i4_e32 v44, v137, v53
	v_dot8c_i32_i4_e32 v45, v137, v51
	v_and_b32_e32 v78, 0xffff, v21
	v_lshrrev_b32_e32 v79, 16, v21
	v_lshl_add_u32 v78, v78, 7, v152
	v_lshl_add_u32 v79, v79, 7, v153
	s_mov_b32 m0, s99
	s_add_i32 s43, s99, 0x400
	global_load_lds_dwordx4 v78, s[50:51]
	s_mov_b32 m0, s43
	s_nop 0
	global_load_lds_dwordx4 v79, s[50:51]
	s_waitcnt vmcnt(8)
	v_add_u32_e32 v54, s77, v59
	v_add_u32_e32 v55, s77, v60
	v_add_u32_e32 v56, s77, v61
	v_add_u32_e32 v57, s77, v62
	ds_read_b64_tr_b4 v[50:51], v160 offset:896
	ds_read_b64_tr_b4 v[52:53], v160 offset:1920
	ds_read_b64_tr_b4 v[130:131], v54
	ds_read_b64_tr_b4 v[132:133], v55
	ds_read_b64_tr_b4 v[134:135], v56
	ds_read_b64_tr_b4 v[136:137], v57
	s_waitcnt lgkmcnt(6)
	v_dot8c_i32_i4_e32 v38, v122, v48
	v_dot8c_i32_i4_e32 v39, v122, v46
	v_dot8c_i32_i4_e32 v40, v124, v48
	v_dot8c_i32_i4_e32 v41, v124, v46
	v_dot8c_i32_i4_e32 v42, v126, v48
	v_dot8c_i32_i4_e32 v43, v126, v46
	v_dot8c_i32_i4_e32 v44, v128, v48
	v_dot8c_i32_i4_e32 v45, v128, v46
	v_dot8c_i32_i4_e32 v38, v123, v49
	v_dot8c_i32_i4_e32 v39, v123, v47
	v_dot8c_i32_i4_e32 v40, v125, v49
	v_dot8c_i32_i4_e32 v41, v125, v47
	v_dot8c_i32_i4_e32 v42, v127, v49
	v_dot8c_i32_i4_e32 v43, v127, v47
	v_dot8c_i32_i4_e32 v44, v129, v49
	v_dot8c_i32_i4_e32 v45, v129, v47
	v_and_b32_e32 v78, 0xffff, v22
	v_lshrrev_b32_e32 v79, 16, v22
	v_lshl_add_u32 v78, v78, 7, v152
	v_lshl_add_u32 v79, v79, 7, v153
	s_mov_b32 m0, s76
	s_add_i32 s43, s76, 0x400
	global_load_lds_dwordx4 v78, s[50:51]
	s_mov_b32 m0, s43
	s_nop 0
	global_load_lds_dwordx4 v79, s[50:51]
	s_waitcnt vmcnt(8)
	v_add_u32_e32 v54, s78, v59
	v_add_u32_e32 v55, s78, v60
	v_add_u32_e32 v56, s78, v61
	v_add_u32_e32 v57, s78, v62
	ds_read_b64_tr_b4 v[46:47], v160
	ds_read_b64_tr_b4 v[48:49], v160 offset:1024
	ds_read_b64_tr_b4 v[122:123], v54
	ds_read_b64_tr_b4 v[124:125], v55
	ds_read_b64_tr_b4 v[126:127], v56
	ds_read_b64_tr_b4 v[128:129], v57
	s_waitcnt lgkmcnt(6)
	v_dot8c_i32_i4_e32 v38, v130, v52
	v_dot8c_i32_i4_e32 v39, v130, v50
	v_dot8c_i32_i4_e32 v40, v132, v52
	v_dot8c_i32_i4_e32 v41, v132, v50
	v_dot8c_i32_i4_e32 v42, v134, v52
	v_dot8c_i32_i4_e32 v43, v134, v50
	v_dot8c_i32_i4_e32 v44, v136, v52
	v_dot8c_i32_i4_e32 v45, v136, v50
	v_dot8c_i32_i4_e32 v38, v131, v53
	v_dot8c_i32_i4_e32 v39, v131, v51
	v_dot8c_i32_i4_e32 v40, v133, v53
	v_dot8c_i32_i4_e32 v41, v133, v51
	v_dot8c_i32_i4_e32 v42, v135, v53
	v_dot8c_i32_i4_e32 v43, v135, v51
	v_dot8c_i32_i4_e32 v44, v137, v53
	v_dot8c_i32_i4_e32 v45, v137, v51
	s_nop 3
	s_waitcnt lgkmcnt(15)
; #define LAS __attribute__((address_space(3)))
; #define CFENCE() asm volatile("" ::: "memory")
; __device__ __forceinline__ void peer_v_tokens(int j, const LAS unsigned short* EL, const LAS unsigned char* AL  , const LAS float* ASC  , const LAS int* SAL  , ...
;     ...
;         uint2 hv[4]; float4 gv[4];
;         { unsigned ho = (unsigned)t * (D / 4) + (unsigned)lane; asm volatile("" : "+v"(ho)); const uint2* hp = (const uint2*)HB + ho; const float4* gp = (const float4*)fng + lane;
; #pragma unroll
;           for (int jq = 0; jq < 4; ++jq) { hv[jq] = hp[64 * jq]; gv[jq] = gp[64 * jq]; } }
;         VDMA(0, 0); VDMA(1, 1);
; #pragma unroll
;         for (int m = 0; m < 2; ++m) {
;             const int idx = lane + 64 * m, tau = idx >> 4, sr = idx & 15, k = 16 * (sr & 7) + 2 * tau + (sr >> 3);
;             const int aq = (int)*(const LAS signed char*)(AL + tl * 128 + k); const int tq = aq + 8;
;             const unsigned lo = (((unsigned)tq & 15u) ^ 8u) * 0x11111111u, hi = ((unsigned)(tq >> 4) & 15u) * 0x11111111u;
;             typedef unsigned u2v __attribute__((ext_vector_type(2)));
;             u2v l2; l2.x = lo; l2.y = lo; u2v h2; h2.x = hi; h2.y = hi;
;             *(LAS u2v*)(ATL + 8 * idx) = l2; *(LAS u2v*)(ATL + 1024 + 8 * idx) = h2;
;         }
;         const float asc = ASC[tl]; const int sa = SAL[tl];
;         CFENCE();
;         int accH[4], accL[4];
; #pragma unroll
;         for (int st = 0; st < 16; ++st) {
;             const int p = st >> 2, q = st & 3;
;             if (st < 14) VDMA(st + 2, (st + 2) % 3);
;             if (st < 14) asm volatile("s_waitcnt vmcnt(8)" ::: "memory");
;             else if (st == 14) asm volatile("s_waitcnt vmcnt(4)" ::: "memory");
;             else asm volatile("s_waitcnt vmcnt(0)" ::: "memory");
;             if (q == 0) {
; #pragma unroll
;                 for (int r = 0; r < 4; ++r) { accH[r] = 0; accL[r] = 0; } }
; #pragma unroll
;             for (int tp = 0; tp < 2; ++tp) {
;                 const v2i ao = TR4(ATL + (2 * q + tp) * 128 + 8 * s16), ah = TR4(ATL + 1024 + (2 * q + tp) * 128 + 8 * s16);
; #pragma unroll
;                 for (int r = 0; r < 4; ++r) {
;                     const v2i d = TR4(ldsb + BUF[st % 3] + 2048 * tp + roff[r]);
;                     accH[r] = __builtin_amdgcn_sdot8(d.x, ah.x, accH[r], false); accH[r] = __builtin_amdgcn_sdot8(d.y, ah.y, accH[r], false);
	v_lshlrev_b32_e32 v38, 5, v38
	v_lshlrev_b32_e32 v39, 1, v39
	v_add3_u32 v38, v39, v229, v38
	v_cvt_f32_i32_e32 v38, v38
	v_mul_f32_e32 v38, v228, v38
	v_lshlrev_b32_e32 v40, 5, v40
	v_lshlrev_b32_e32 v41, 1, v41
	v_add3_u32 v40, v41, v229, v40
	v_cvt_f32_i32_e32 v40, v40
	v_mul_f32_e32 v40, v228, v40
	v_lshlrev_b32_e32 v42, 5, v42
	v_lshlrev_b32_e32 v43, 1, v43
	v_add3_u32 v42, v43, v229, v42
	v_cvt_f32_i32_e32 v42, v42
	v_mul_f32_e32 v42, v228, v42
	v_lshlrev_b32_e32 v44, 5, v44
	v_lshlrev_b32_e32 v45, 1, v45
	v_add3_u32 v44, v45, v229, v44
	v_cvt_f32_i32_e32 v44, v44
	v_mul_f32_e32 v44, v228, v44
	v_cvt_pk_bf16_f32 v246, v38, v40
	v_cvt_pk_bf16_f32 v247, v42, v44
	ds_read_b128 v[252:255], v155
	s_add_i32 s44, s40, 16
	s_ashr_i32 s45, s44, 31
	s_lshl_b64 s[44:45], s[44:45], 12
	v_lshl_add_u64 v[80:81], v[36:37], 0, s[44:45]
	s_waitcnt lgkmcnt(0)
	v_mul_f32_e32 v210, v210, v252
	v_mul_f32_e32 v211, v211, v253
	v_mul_f32_e32 v212, v212, v254
	v_mul_f32_e32 v213, v213, v255
	global_store_dwordx4 v[80:81], v[210:213], off nt
	ds_read_b128 v[252:255], v155 offset:1024
	s_add_i32 s44, s40, 16
	s_ashr_i32 s45, s44, 31
	s_lshl_b64 s[44:45], s[44:45], 12
	v_lshl_add_u64 v[80:81], v[36:37], 0, s[44:45]
	s_waitcnt lgkmcnt(0)
	v_mul_f32_e32 v214, v214, v252
	v_mul_f32_e32 v215, v215, v253
	v_mul_f32_e32 v216, v216, v254
	v_mul_f32_e32 v217, v217, v255
	global_store_dwordx4 v[80:81], v[214:217], off offset:1024 nt
	s_add_i32 s43, s40, 24
	s_lshl_b32 s43, s43, 11
	v_add_u32_e32 v138, s43, v66
	global_load_dwordx2 v[194:195], v138, s[70:71]
	global_load_dwordx2 v[196:197], v138, s[70:71] offset:512
	global_load_dwordx2 v[198:199], v138, s[70:71] offset:1024
	global_load_dwordx2 v[200:201], v138, s[70:71] offset:1536
	v_add_u32_e32 v147, 8, v140
	v_and_b32_e32 v146, 15, v147
	v_xor_b32_e32 v146, 8, v146
	v_bfe_u32 v148, v147, 4, 4
	v_mul_lo_u32 v146, v146, s92
	v_mul_lo_u32 v148, v148, s92
	v_mov_b32_e32 v147, v146
	v_mov_b32_e32 v149, v148
	ds_write2st64_b64 v77, v[146:147], v[148:149] offset1:2
	v_add_u32_e32 v138, 0x1c00, v74
	ds_read_u8 v139, v138
	v_add_u32_e32 v141, 0x1c00, v73
	ds_read_u8 v140, v141
	s_add_i32 s43, s67, 192
	v_mov_b32_e32 v138, s43
	ds_read2st64_b32 v[228:229], v138 offset1:1
	ds_read_b128 v[26:29], v227 offset:14336
	ds_read_b128 v[30:33], v227 offset:14352
	v_mov_b32_e32 v38, 0
	v_mov_b32_e32 v39, 0
	v_mov_b32_e32 v40, 0
	v_mov_b32_e32 v41, 0
	v_mov_b32_e32 v42, 0
	v_mov_b32_e32 v43, 0
	v_mov_b32_e32 v44, 0
	v_mov_b32_e32 v45, 0
	v_and_b32_e32 v78, 0xffff, v23
	v_lshrrev_b32_e32 v79, 16, v23
	v_lshl_add_u32 v78, v78, 7, v152
	v_lshl_add_u32 v79, v79, 7, v153
	s_mov_b32 m0, s77
	s_add_i32 s43, s77, 0x400
	global_load_lds_dwordx4 v78, s[50:51]
	s_mov_b32 m0, s43
	s_nop 0
	global_load_lds_dwordx4 v79, s[50:51]
	s_waitcnt vmcnt(14)
	v_add_u32_e32 v54, s79, v59
	v_add_u32_e32 v55, s79, v60
	v_add_u32_e32 v56, s79, v61
	v_add_u32_e32 v57, s79, v62
	ds_read_b64_tr_b4 v[50:51], v160 offset:128
	ds_read_b64_tr_b4 v[52:53], v160 offset:1152
	ds_read_b64_tr_b4 v[130:131], v54
	ds_read_b64_tr_b4 v[132:133], v55
	ds_read_b64_tr_b4 v[134:135], v56
	ds_read_b64_tr_b4 v[136:137], v57
	s_waitcnt lgkmcnt(14)
	v_dot8c_i32_i4_e32 v38, v122, v48
	v_dot8c_i32_i4_e32 v39, v122, v46
	v_dot8c_i32_i4_e32 v40, v124, v48
	v_dot8c_i32_i4_e32 v41, v124, v46
	v_dot8c_i32_i4_e32 v42, v126, v48
	v_dot8c_i32_i4_e32 v43, v126, v46
	v_dot8c_i32_i4_e32 v44, v128, v48
	v_dot8c_i32_i4_e32 v45, v128, v46
	v_dot8c_i32_i4_e32 v38, v123, v49
	v_dot8c_i32_i4_e32 v39, v123, v47
	v_dot8c_i32_i4_e32 v40, v125, v49
	v_dot8c_i32_i4_e32 v41, v125, v47
	v_dot8c_i32_i4_e32 v42, v127, v49
	v_dot8c_i32_i4_e32 v43, v127, v47
	v_dot8c_i32_i4_e32 v44, v129, v49
	v_dot8c_i32_i4_e32 v45, v129, v47
	v_and_b32_e32 v78, 0xffff, v24
	v_lshrrev_b32_e32 v79, 16, v24
	v_lshl_add_u32 v78, v78, 7, v152
	v_lshl_add_u32 v79, v79, 7, v153
	s_mov_b32 m0, s78
	s_add_i32 s43, s78, 0x400
	global_load_lds_dwordx4 v78, s[50:51]
	s_mov_b32 m0, s43
	s_nop 0
	global_load_lds_dwordx4 v79, s[50:51]
	s_waitcnt vmcnt(14)
	v_add_u32_e32 v54, s98, v59
	v_add_u32_e32 v55, s98, v60
	v_add_u32_e32 v56, s98, v61
	v_add_u32_e32 v57, s98, v62
	ds_read_b64_tr_b4 v[46:47], v160 offset:256
	ds_read_b64_tr_b4 v[48:49], v160 offset:1280
	ds_read_b64_tr_b4 v[122:123], v54
	ds_read_b64_tr_b4 v[124:125], v55
	ds_read_b64_tr_b4 v[126:127], v56
	ds_read_b64_tr_b4 v[128:129], v57
	s_waitcnt lgkmcnt(6)
	v_dot8c_i32_i4_e32 v38, v130, v52
	v_dot8c_i32_i4_e32 v39, v130, v50
	v_dot8c_i32_i4_e32 v40, v132, v52
	v_dot8c_i32_i4_e32 v41, v132, v50
	v_dot8c_i32_i4_e32 v42, v134, v52
	v_dot8c_i32_i4_e32 v43, v134, v50
	v_dot8c_i32_i4_e32 v44, v136, v52
	v_dot8c_i32_i4_e32 v45, v136, v50
	v_dot8c_i32_i4_e32 v38, v131, v53
	v_dot8c_i32_i4_e32 v39, v131, v51
	v_dot8c_i32_i4_e32 v40, v133, v53
	v_dot8c_i32_i4_e32 v41, v133, v51
	v_dot8c_i32_i4_e32 v42, v135, v53
	v_dot8c_i32_i4_e32 v43, v135, v51
	v_dot8c_i32_i4_e32 v44, v137, v53
	v_dot8c_i32_i4_e32 v45, v137, v51
	v_and_b32_e32 v78, 0xffff, v25
	v_lshrrev_b32_e32 v79, 16, v25
	v_lshl_add_u32 v78, v78, 7, v152
	v_lshl_add_u32 v79, v79, 7, v153
	s_mov_b32 m0, s79
	s_add_i32 s43, s79, 0x400
	global_load_lds_dwordx4 v78, s[50:51]
	s_mov_b32 m0, s43
	s_nop 0
	global_load_lds_dwordx4 v79, s[50:51]
	s_waitcnt vmcnt(14)
	v_add_u32_e32 v54, s99, v59
	v_add_u32_e32 v55, s99, v60
	v_add_u32_e32 v56, s99, v61
	v_add_u32_e32 v57, s99, v62
	ds_read_b64_tr_b4 v[50:51], v160 offset:384
	ds_read_b64_tr_b4 v[52:53], v160 offset:1408
	ds_read_b64_tr_b4 v[130:131], v54
	ds_read_b64_tr_b4 v[132:133], v55
	ds_read_b64_tr_b4 v[134:135], v56
	ds_read_b64_tr_b4 v[136:137], v57
	s_waitcnt lgkmcnt(6)
; #define LAS __attribute__((address_space(3)))
; #define TR4(p_) __builtin_amdgcn_ds_read_tr4_b64_v2i32((LAS v2i*)(p_))
; #define CFENCE() asm volatile("" ::: "memory")
; __device__ __forceinline__ void peer_v_tokens(int j, const LAS unsigned short* EL, const LAS unsigned char* AL  , const LAS float* ASC  , const LAS int* SAL  , ...
;     ...
;         for (int m = 0; m < 2; ++m) {
;             const int idx = lane + 64 * m, tau = idx >> 4, sr = idx & 15, k = 16 * (sr & 7) + 2 * tau + (sr >> 3);
;             const int aq = (int)*(const LAS signed char*)(AL + tl * 128 + k); const int tq = aq + 8;
;             const unsigned lo = (((unsigned)tq & 15u) ^ 8u) * 0x11111111u, hi = ((unsigned)(tq >> 4) & 15u) * 0x11111111u;
;             typedef unsigned u2v __attribute__((ext_vector_type(2)));
;             u2v l2; l2.x = lo; l2.y = lo; u2v h2; h2.x = hi; h2.y = hi;
;             *(LAS u2v*)(ATL + 8 * idx) = l2; *(LAS u2v*)(ATL + 1024 + 8 * idx) = h2;
;         }
;         const float asc = ASC[tl]; const int sa = SAL[tl];
;         CFENCE();
;         int accH[4], accL[4];
; #pragma unroll
;         for (int st = 0; st < 16; ++st) {
;             const int p = st >> 2, q = st & 3;
;             if (st < 14) VDMA(st + 2, (st + 2) % 3);
;             if (st < 14) asm volatile("s_waitcnt vmcnt(8)" ::: "memory");
;             else if (st == 14) asm volatile("s_waitcnt vmcnt(4)" ::: "memory");
;             else asm volatile("s_waitcnt vmcnt(0)" ::: "memory");
;             if (q == 0) {
; #pragma unroll
;                 for (int r = 0; r < 4; ++r) { accH[r] = 0; accL[r] = 0; } }
; #pragma unroll
;             for (int tp = 0; tp < 2; ++tp) {
;                 const v2i ao = TR4(ATL + (2 * q + tp) * 128 + 8 * s16), ah = TR4(ATL + 1024 + (2 * q + tp) * 128 + 8 * s16);
; #pragma unroll
;                 for (int r = 0; r < 4; ++r) {
;                     const v2i d = TR4(ldsb + BUF[st % 3] + 2048 * tp + roff[r]);
;                     accH[r] = __builtin_amdgcn_sdot8(d.x, ah.x, accH[r], false); accH[r] = __builtin_amdgcn_sdot8(d.y, ah.y, accH[r], false);
;                     accL[r] = __builtin_amdgcn_sdot8(d.x, ao.x, accL[r], false); accL[r] = __builtin_amdgcn_sdot8(d.y, ao.y, accL[r], false);
;                 }
;             }
	v_dot8c_i32_i4_e32 v38, v122, v48
	v_dot8c_i32_i4_e32 v39, v122, v46
	v_dot8c_i32_i4_e32 v40, v124, v48
	v_dot8c_i32_i4_e32 v41, v124, v46
	v_dot8c_i32_i4_e32 v42, v126, v48
	v_dot8c_i32_i4_e32 v43, v126, v46
	v_dot8c_i32_i4_e32 v44, v128, v48
	v_dot8c_i32_i4_e32 v45, v128, v46
	v_dot8c_i32_i4_e32 v38, v123, v49
	v_dot8c_i32_i4_e32 v39, v123, v47
	v_dot8c_i32_i4_e32 v40, v125, v49
	v_dot8c_i32_i4_e32 v41, v125, v47
	v_dot8c_i32_i4_e32 v42, v127, v49
	v_dot8c_i32_i4_e32 v43, v127, v47
	v_dot8c_i32_i4_e32 v44, v129, v49
	v_dot8c_i32_i4_e32 v45, v129, v47
	s_waitcnt lgkmcnt(15)
	v_and_b32_e32 v78, 0xffff, v26
	v_lshrrev_b32_e32 v79, 16, v26
	v_lshl_add_u32 v78, v78, 7, v152
	v_lshl_add_u32 v79, v79, 7, v153
	s_mov_b32 m0, s98
	s_add_i32 s43, s98, 0x400
	global_load_lds_dwordx4 v78, s[50:51]
	s_mov_b32 m0, s43
	s_nop 0
	global_load_lds_dwordx4 v79, s[50:51]
	s_waitcnt vmcnt(14)
	v_add_u32_e32 v54, s76, v59
	v_add_u32_e32 v55, s76, v60
	v_add_u32_e32 v56, s76, v61
	v_add_u32_e32 v57, s76, v62
	ds_read_b64_tr_b4 v[46:47], v160 offset:512
	ds_read_b64_tr_b4 v[48:49], v160 offset:1536
	ds_read_b64_tr_b4 v[122:123], v54
	ds_read_b64_tr_b4 v[124:125], v55
	ds_read_b64_tr_b4 v[126:127], v56
	ds_read_b64_tr_b4 v[128:129], v57
	s_waitcnt lgkmcnt(6)
	v_dot8c_i32_i4_e32 v38, v130, v52
	v_dot8c_i32_i4_e32 v39, v130, v50
	v_dot8c_i32_i4_e32 v40, v132, v52
	v_dot8c_i32_i4_e32 v41, v132, v50
	v_dot8c_i32_i4_e32 v42, v134, v52
	v_dot8c_i32_i4_e32 v43, v134, v50
	v_dot8c_i32_i4_e32 v44, v136, v52
	v_dot8c_i32_i4_e32 v45, v136, v50
	v_dot8c_i32_i4_e32 v38, v131, v53
	v_dot8c_i32_i4_e32 v39, v131, v51
	v_dot8c_i32_i4_e32 v40, v133, v53
	v_dot8c_i32_i4_e32 v41, v133, v51
	v_dot8c_i32_i4_e32 v42, v135, v53
	v_dot8c_i32_i4_e32 v43, v135, v51
	v_dot8c_i32_i4_e32 v44, v137, v53
	v_dot8c_i32_i4_e32 v45, v137, v51
	v_and_b32_e32 v78, 0xffff, v27
	v_lshrrev_b32_e32 v79, 16, v27
	v_lshl_add_u32 v78, v78, 7, v152
	v_lshl_add_u32 v79, v79, 7, v153
	s_mov_b32 m0, s99
	s_add_i32 s43, s99, 0x400
	global_load_lds_dwordx4 v78, s[50:51]
	s_mov_b32 m0, s43
	s_nop 0
	global_load_lds_dwordx4 v79, s[50:51]
	s_waitcnt vmcnt(8)
	v_add_u32_e32 v54, s77, v59
	v_add_u32_e32 v55, s77, v60
	v_add_u32_e32 v56, s77, v61
	v_add_u32_e32 v57, s77, v62
	ds_read_b64_tr_b4 v[50:51], v160 offset:640
	ds_read_b64_tr_b4 v[52:53], v160 offset:1664
	ds_read_b64_tr_b4 v[130:131], v54
	ds_read_b64_tr_b4 v[132:133], v55
	ds_read_b64_tr_b4 v[134:135], v56
	ds_read_b64_tr_b4 v[136:137], v57
	s_waitcnt lgkmcnt(6)
	v_dot8c_i32_i4_e32 v38, v122, v48
	v_dot8c_i32_i4_e32 v39, v122, v46
	v_dot8c_i32_i4_e32 v40, v124, v48
	v_dot8c_i32_i4_e32 v41, v124, v46
	v_dot8c_i32_i4_e32 v42, v126, v48
	v_dot8c_i32_i4_e32 v43, v126, v46
	v_dot8c_i32_i4_e32 v44, v128, v48
	v_dot8c_i32_i4_e32 v45, v128, v46
	v_dot8c_i32_i4_e32 v38, v123, v49
	v_dot8c_i32_i4_e32 v39, v123, v47
	v_dot8c_i32_i4_e32 v40, v125, v49
	v_dot8c_i32_i4_e32 v41, v125, v47
	v_dot8c_i32_i4_e32 v42, v127, v49
	v_dot8c_i32_i4_e32 v43, v127, v47
	v_dot8c_i32_i4_e32 v44, v129, v49
	v_dot8c_i32_i4_e32 v45, v129, v47
	s_waitcnt lgkmcnt(15)
	v_add_u32_e32 v143, 8, v139
	v_and_b32_e32 v142, 15, v143
	v_xor_b32_e32 v142, 8, v142
	v_bfe_u32 v144, v143, 4, 4
	v_mul_lo_u32 v142, v142, s92
	v_mul_lo_u32 v144, v144, s92
	v_mov_b32_e32 v143, v142
	v_mov_b32_e32 v145, v144
	ds_write2st64_b64 v159, v[142:143], v[144:145] offset1:2
	v_and_b32_e32 v78, 0xffff, v28
	v_lshrrev_b32_e32 v79, 16, v28
	v_lshl_add_u32 v78, v78, 7, v152
	v_lshl_add_u32 v79, v79, 7, v153
	s_mov_b32 m0, s76
	s_add_i32 s43, s76, 0x400
	global_load_lds_dwordx4 v78, s[50:51]
	s_mov_b32 m0, s43
	s_nop 0
	global_load_lds_dwordx4 v79, s[50:51]
	s_waitcnt vmcnt(8)
	v_add_u32_e32 v54, s78, v59
	v_add_u32_e32 v55, s78, v60
	v_add_u32_e32 v56, s78, v61
	v_add_u32_e32 v57, s78, v62
	ds_read_b64_tr_b4 v[46:47], v160 offset:768
	ds_read_b64_tr_b4 v[48:49], v160 offset:1792
	ds_read_b64_tr_b4 v[122:123], v54
	ds_read_b64_tr_b4 v[124:125], v55
	ds_read_b64_tr_b4 v[126:127], v56
	ds_read_b64_tr_b4 v[128:129], v57
	s_waitcnt lgkmcnt(7)
	v_dot8c_i32_i4_e32 v38, v130, v52
	v_dot8c_i32_i4_e32 v39, v130, v50
	v_dot8c_i32_i4_e32 v40, v132, v52
	v_dot8c_i32_i4_e32 v41, v132, v50
	v_dot8c_i32_i4_e32 v42, v134, v52
	v_dot8c_i32_i4_e32 v43, v134, v50
	v_dot8c_i32_i4_e32 v44, v136, v52
	v_dot8c_i32_i4_e32 v45, v136, v50
	v_dot8c_i32_i4_e32 v38, v131, v53
	v_dot8c_i32_i4_e32 v39, v131, v51
	v_dot8c_i32_i4_e32 v40, v133, v53
	v_dot8c_i32_i4_e32 v41, v133, v51
	v_dot8c_i32_i4_e32 v42, v135, v53
	v_dot8c_i32_i4_e32 v43, v135, v51
	v_dot8c_i32_i4_e32 v44, v137, v53
	v_dot8c_i32_i4_e32 v45, v137, v51
	v_and_b32_e32 v78, 0xffff, v29
	v_lshrrev_b32_e32 v79, 16, v29
	v_lshl_add_u32 v78, v78, 7, v152
	v_lshl_add_u32 v79, v79, 7, v153
	s_mov_b32 m0, s77
	s_add_i32 s43, s77, 0x400
	global_load_lds_dwordx4 v78, s[50:51]
	s_mov_b32 m0, s43
	s_nop 0
	global_load_lds_dwordx4 v79, s[50:51]
	s_waitcnt vmcnt(8)
	v_add_u32_e32 v54, s79, v59
	v_add_u32_e32 v55, s79, v60
	v_add_u32_e32 v56, s79, v61
	v_add_u32_e32 v57, s79, v62
	ds_read_b64_tr_b4 v[50:51], v160 offset:896
	ds_read_b64_tr_b4 v[52:53], v160 offset:1920
	ds_read_b64_tr_b4 v[130:131], v54
	ds_read_b64_tr_b4 v[132:133], v55
	ds_read_b64_tr_b4 v[134:135], v56
	ds_read_b64_tr_b4 v[136:137], v57
	s_waitcnt lgkmcnt(6)
; __device__ __forceinline__ void peer_v_tokens(int j, const LAS unsigned short* EL, const LAS unsigned char* AL  , const LAS float* ASC  , const LAS int* SAL  , ...
;     ...
;         for (int m = 0; m < 2; ++m) {
;             const int idx = lane + 64 * m, tau = idx >> 4, sr = idx & 15, k = 16 * (sr & 7) + 2 * tau + (sr >> 3);
;             const int aq = (int)*(const LAS signed char*)(AL + tl * 128 + k); const int tq = aq + 8;
;             const unsigned lo = (((unsigned)tq & 15u) ^ 8u) * 0x11111111u, hi = ((unsigned)(tq >> 4) & 15u) * 0x11111111u;
;             typedef unsigned u2v __attribute__((ext_vector_type(2)));
;             u2v l2; l2.x = lo; l2.y = lo; u2v h2; h2.x = hi; h2.y = hi;
;             *(LAS u2v*)(ATL + 8 * idx) = l2; *(LAS u2v*)(ATL + 1024 + 8 * idx) = h2;
;         }
;         const float asc = ASC[tl]; const int sa = SAL[tl];
;         CFENCE();
;         int accH[4], accL[4];
; #pragma unroll
;         for (int st = 0; st < 16; ++st) {
;             const int p = st >> 2, q = st & 3;
;             if (st < 14) VDMA(st + 2, (st + 2) % 3);
;             if (st < 14) asm volatile("s_waitcnt vmcnt(8)" ::: "memory");
;             else if (st == 14) asm volatile("s_waitcnt vmcnt(4)" ::: "memory");
;             else asm volatile("s_waitcnt vmcnt(0)" ::: "memory");
;             if (q == 0) {
; #pragma unroll
;                 for (int r = 0; r < 4; ++r) { accH[r] = 0; accL[r] = 0; } }
; #pragma unroll
;             for (int tp = 0; tp < 2; ++tp) {
;                 const v2i ao = TR4(ATL + (2 * q + tp) * 128 + 8 * s16), ah = TR4(ATL + 1024 + (2 * q + tp) * 128 + 8 * s16);
; #pragma unroll
;                 for (int r = 0; r < 4; ++r) {
;                     const v2i d = TR4(ldsb + BUF[st % 3] + 2048 * tp + roff[r]);
;                     accH[r] = __builtin_amdgcn_sdot8(d.x, ah.x, accH[r], false); accH[r] = __builtin_amdgcn_sdot8(d.y, ah.y, accH[r], false);
;                     accL[r] = __builtin_amdgcn_sdot8(d.x, ao.x, accL[r], false); accL[r] = __builtin_amdgcn_sdot8(d.y, ao.y, accL[r], false);
;                 }
;             }
;             asm volatile("s_waitcnt lgkmcnt(0)" ::: "memory");
;             if (q == 3) {
; #pragma unroll
;                 for (int r = 0; r < 4; ++r) STASH[256 * p + 16 * (grp + 4 * r) + pc] = f2bf(asc * (float)(2 * ((accH[r] << 4) + accL[r]) + sa));
;             }
;         }
;         CFENCE();
	v_dot8c_i32_i4_e32 v38, v122, v48
	v_dot8c_i32_i4_e32 v39, v122, v46
	v_dot8c_i32_i4_e32 v40, v124, v48
	v_dot8c_i32_i4_e32 v41, v124, v46
	v_dot8c_i32_i4_e32 v42, v126, v48
	v_dot8c_i32_i4_e32 v43, v126, v46
	v_dot8c_i32_i4_e32 v44, v128, v48
	v_dot8c_i32_i4_e32 v45, v128, v46
	v_dot8c_i32_i4_e32 v38, v123, v49
	v_dot8c_i32_i4_e32 v39, v123, v47
	v_dot8c_i32_i4_e32 v40, v125, v49
	v_dot8c_i32_i4_e32 v41, v125, v47
	v_dot8c_i32_i4_e32 v42, v127, v49
	v_dot8c_i32_i4_e32 v43, v127, v47
	v_dot8c_i32_i4_e32 v44, v129, v49
	v_dot8c_i32_i4_e32 v45, v129, v47
	v_and_b32_e32 v78, 0xffff, v30
	v_lshrrev_b32_e32 v79, 16, v30
	v_lshl_add_u32 v78, v78, 7, v152
	v_lshl_add_u32 v79, v79, 7, v153
	s_mov_b32 m0, s78
	s_add_i32 s43, s78, 0x400
	global_load_lds_dwordx4 v78, s[50:51]
	s_mov_b32 m0, s43
	s_nop 0
	global_load_lds_dwordx4 v79, s[50:51]
	s_waitcnt vmcnt(8)
	v_add_u32_e32 v54, s98, v59
	v_add_u32_e32 v55, s98, v60
	v_add_u32_e32 v56, s98, v61
	v_add_u32_e32 v57, s98, v62
	ds_read_b64_tr_b4 v[46:47], v160
	ds_read_b64_tr_b4 v[48:49], v160 offset:1024
	ds_read_b64_tr_b4 v[122:123], v54
	ds_read_b64_tr_b4 v[124:125], v55
	ds_read_b64_tr_b4 v[126:127], v56
	ds_read_b64_tr_b4 v[128:129], v57
	s_waitcnt lgkmcnt(6)
	v_dot8c_i32_i4_e32 v38, v130, v52
	v_dot8c_i32_i4_e32 v39, v130, v50
	v_dot8c_i32_i4_e32 v40, v132, v52
	v_dot8c_i32_i4_e32 v41, v132, v50
	v_dot8c_i32_i4_e32 v42, v134, v52
	v_dot8c_i32_i4_e32 v43, v134, v50
	v_dot8c_i32_i4_e32 v44, v136, v52
	v_dot8c_i32_i4_e32 v45, v136, v50
	v_dot8c_i32_i4_e32 v38, v131, v53
	v_dot8c_i32_i4_e32 v39, v131, v51
	v_dot8c_i32_i4_e32 v40, v133, v53
	v_dot8c_i32_i4_e32 v41, v133, v51
	v_dot8c_i32_i4_e32 v42, v135, v53
	v_dot8c_i32_i4_e32 v43, v135, v51
	v_dot8c_i32_i4_e32 v44, v137, v53
	v_dot8c_i32_i4_e32 v45, v137, v51
	s_nop 3
	s_waitcnt lgkmcnt(15)
	v_lshlrev_b32_e32 v38, 5, v38
	v_lshlrev_b32_e32 v39, 1, v39
	v_add3_u32 v38, v39, v229, v38
	v_cvt_f32_i32_e32 v38, v38
	v_mul_f32_e32 v38, v228, v38
	v_lshlrev_b32_e32 v40, 5, v40
	v_lshlrev_b32_e32 v41, 1, v41
	v_add3_u32 v40, v41, v229, v40
	v_cvt_f32_i32_e32 v40, v40
	v_mul_f32_e32 v40, v228, v40
	v_lshlrev_b32_e32 v42, 5, v42
	v_lshlrev_b32_e32 v43, 1, v43
	v_add3_u32 v42, v43, v229, v42
	v_cvt_f32_i32_e32 v42, v42
	v_mul_f32_e32 v42, v228, v42
	v_lshlrev_b32_e32 v44, 5, v44
	v_lshlrev_b32_e32 v45, 1, v45
	v_add3_u32 v44, v45, v229, v44
	v_cvt_f32_i32_e32 v44, v44
	v_mul_f32_e32 v44, v228, v44
	v_cvt_pk_bf16_f32 v69, v38, v40
	v_cvt_pk_bf16_f32 v70, v42, v44
	ds_read_b128 v[252:255], v156
	s_add_i32 s44, s40, 16
	s_ashr_i32 s45, s44, 31
	s_lshl_b64 s[44:45], s[44:45], 12
	v_lshl_add_u64 v[80:81], v[36:37], 0, s[44:45]
	s_waitcnt lgkmcnt(0)
	v_mul_f32_e32 v218, v218, v252
	v_mul_f32_e32 v219, v219, v253
	v_mul_f32_e32 v220, v220, v254
	v_mul_f32_e32 v221, v221, v255
	global_store_dwordx4 v[80:81], v[218:221], off offset:2048 nt
	ds_read_b128 v[252:255], v156 offset:1024
	s_add_i32 s44, s40, 16
	s_ashr_i32 s45, s44, 31
	s_lshl_b64 s[44:45], s[44:45], 12
	v_lshl_add_u64 v[80:81], v[36:37], 0, s[44:45]
	s_waitcnt lgkmcnt(0)
	v_mul_f32_e32 v222, v222, v252
	v_mul_f32_e32 v223, v223, v253
	v_mul_f32_e32 v224, v224, v254
	v_mul_f32_e32 v225, v225, v255
	global_store_dwordx4 v[80:81], v[222:225], off offset:3072 nt
	v_add_u32_e32 v147, 8, v140
	v_and_b32_e32 v146, 15, v147
	v_xor_b32_e32 v146, 8, v146
	v_bfe_u32 v148, v147, 4, 4
	v_mul_lo_u32 v146, v146, s92
	v_mul_lo_u32 v148, v148, s92
	v_mov_b32_e32 v147, v146
	v_mov_b32_e32 v149, v148
	ds_write2st64_b64 v77, v[146:147], v[148:149] offset1:2
	v_add_u32_e32 v138, 0x1000, v74
	ds_read_u8 v139, v138
	v_add_u32_e32 v141, 0x1000, v73
	ds_read_u8 v140, v141
	s_add_i32 s43, s67, 224
	v_mov_b32_e32 v138, s43
	ds_read2st64_b32 v[228:229], v138 offset1:1
	ds_read_b128 v[18:21], v227 offset:8192
	ds_read_b128 v[22:25], v227 offset:8208
	v_add_u32_e32 v150, 0x400000, v63
	v_add_u32_e32 v151, 0x400000, v64
	v_mov_b32_e32 v38, 0
	v_mov_b32_e32 v39, 0
	v_mov_b32_e32 v40, 0
	v_mov_b32_e32 v41, 0
	v_mov_b32_e32 v42, 0
	v_mov_b32_e32 v43, 0
	v_mov_b32_e32 v44, 0
	v_mov_b32_e32 v45, 0
	v_and_b32_e32 v78, 0xffff, v31
	v_lshrrev_b32_e32 v79, 16, v31
	v_lshl_add_u32 v78, v78, 7, v152
	v_lshl_add_u32 v79, v79, 7, v153
	s_mov_b32 m0, s79
	s_add_i32 s43, s79, 0x400
	global_load_lds_dwordx4 v78, s[50:51]
	s_mov_b32 m0, s43
	s_nop 0
	global_load_lds_dwordx4 v79, s[50:51]
	s_waitcnt vmcnt(10)
	v_add_u32_e32 v54, s99, v59
	v_add_u32_e32 v55, s99, v60
	v_add_u32_e32 v56, s99, v61
	v_add_u32_e32 v57, s99, v62
	ds_read_b64_tr_b4 v[50:51], v160 offset:128
	ds_read_b64_tr_b4 v[52:53], v160 offset:1152
	ds_read_b64_tr_b4 v[130:131], v54
	ds_read_b64_tr_b4 v[132:133], v55
	ds_read_b64_tr_b4 v[134:135], v56
	ds_read_b64_tr_b4 v[136:137], v57
	s_waitcnt lgkmcnt(14)
	v_dot8c_i32_i4_e32 v38, v122, v48
	v_dot8c_i32_i4_e32 v39, v122, v46
	v_dot8c_i32_i4_e32 v40, v124, v48
	v_dot8c_i32_i4_e32 v41, v124, v46
	v_dot8c_i32_i4_e32 v42, v126, v48
	v_dot8c_i32_i4_e32 v43, v126, v46
	v_dot8c_i32_i4_e32 v44, v128, v48
	v_dot8c_i32_i4_e32 v45, v128, v46
	v_dot8c_i32_i4_e32 v38, v123, v49
	v_dot8c_i32_i4_e32 v39, v123, v47
	v_dot8c_i32_i4_e32 v40, v125, v49
	v_dot8c_i32_i4_e32 v41, v125, v47
	v_dot8c_i32_i4_e32 v42, v127, v49
	v_dot8c_i32_i4_e32 v43, v127, v47
	v_dot8c_i32_i4_e32 v44, v129, v49
	v_dot8c_i32_i4_e32 v45, v129, v47
	v_and_b32_e32 v78, 0xffff, v32
	v_lshrrev_b32_e32 v79, 16, v32
	v_lshl_add_u32 v78, v78, 7, v152
	v_lshl_add_u32 v79, v79, 7, v153
	s_mov_b32 m0, s98
	s_add_i32 s43, s98, 0x400
	global_load_lds_dwordx4 v78, s[50:51]
	s_mov_b32 m0, s43
	s_nop 0
	global_load_lds_dwordx4 v79, s[50:51]
	s_waitcnt vmcnt(10)
; #define LAS __attribute__((address_space(3)))
; __device__ __forceinline__ bf16 f2bf(float f) { return (bf16)f2bfu(f); }
; #define TR4(p_) __builtin_amdgcn_ds_read_tr4_b64_v2i32((LAS v2i*)(p_))
; #define CFENCE() asm volatile("" ::: "memory")
; __device__ __forceinline__ void peer_v_tokens(int j, const LAS unsigned short* EL, const LAS unsigned char* AL  , const LAS float* ASC  , const LAS int* SAL  , ...
;     ...
;         for (int st = 0; st < 16; ++st) {
;             const int p = st >> 2, q = st & 3;
;             if (st < 14) VDMA(st + 2, (st + 2) % 3);
;             if (st < 14) asm volatile("s_waitcnt vmcnt(8)" ::: "memory");
;             else if (st == 14) asm volatile("s_waitcnt vmcnt(4)" ::: "memory");
;             else asm volatile("s_waitcnt vmcnt(0)" ::: "memory");
;             if (q == 0) {
; #pragma unroll
;                 for (int r = 0; r < 4; ++r) { accH[r] = 0; accL[r] = 0; } }
; #pragma unroll
;             for (int tp = 0; tp < 2; ++tp) {
;                 const v2i ao = TR4(ATL + (2 * q + tp) * 128 + 8 * s16), ah = TR4(ATL + 1024 + (2 * q + tp) * 128 + 8 * s16);
; #pragma unroll
;                 for (int r = 0; r < 4; ++r) {
;                     const v2i d = TR4(ldsb + BUF[st % 3] + 2048 * tp + roff[r]);
;                     accH[r] = __builtin_amdgcn_sdot8(d.x, ah.x, accH[r], false); accH[r] = __builtin_amdgcn_sdot8(d.y, ah.y, accH[r], false);
;                     accL[r] = __builtin_amdgcn_sdot8(d.x, ao.x, accL[r], false); accL[r] = __builtin_amdgcn_sdot8(d.y, ao.y, accL[r], false);
;                 }
;             }
;             asm volatile("s_waitcnt lgkmcnt(0)" ::: "memory");
;             if (q == 3) {
; #pragma unroll
;                 for (int r = 0; r < 4; ++r) STASH[256 * p + 16 * (grp + 4 * r) + pc] = f2bf(asc * (float)(2 * ((accH[r] << 4) + accL[r]) + sa));
;             }
;         }
;         CFENCE();
;         {
;             float4 v[4]; float ss = 0.f;
; #pragma unroll
;             for (int jq = 0; jq < 4; ++jq) { typedef unsigned u2v __attribute__((ext_vector_type(2))); const u2v pw = *(const LAS u2v*)(STASH + 4 * lane + 256 * jq); const uint2 hw = hv[jq];
	v_add_u32_e32 v54, s76, v59
	v_add_u32_e32 v55, s76, v60
	v_add_u32_e32 v56, s76, v61
	v_add_u32_e32 v57, s76, v62
	ds_read_b64_tr_b4 v[46:47], v160 offset:256
	ds_read_b64_tr_b4 v[48:49], v160 offset:1280
	ds_read_b64_tr_b4 v[122:123], v54
	ds_read_b64_tr_b4 v[124:125], v55
	ds_read_b64_tr_b4 v[126:127], v56
	ds_read_b64_tr_b4 v[128:129], v57
	s_waitcnt lgkmcnt(6)
	v_dot8c_i32_i4_e32 v38, v130, v52
	v_dot8c_i32_i4_e32 v39, v130, v50
	v_dot8c_i32_i4_e32 v40, v132, v52
	v_dot8c_i32_i4_e32 v41, v132, v50
	v_dot8c_i32_i4_e32 v42, v134, v52
	v_dot8c_i32_i4_e32 v43, v134, v50
	v_dot8c_i32_i4_e32 v44, v136, v52
	v_dot8c_i32_i4_e32 v45, v136, v50
	v_dot8c_i32_i4_e32 v38, v131, v53
	v_dot8c_i32_i4_e32 v39, v131, v51
	v_dot8c_i32_i4_e32 v40, v133, v53
	v_dot8c_i32_i4_e32 v41, v133, v51
	v_dot8c_i32_i4_e32 v42, v135, v53
	v_dot8c_i32_i4_e32 v43, v135, v51
	v_dot8c_i32_i4_e32 v44, v137, v53
	v_dot8c_i32_i4_e32 v45, v137, v51
	ds_write_b16 v65, v186
	ds_write_b16_d16_hi v65, v186 offset:128
	ds_write_b16 v65, v187 offset:256
	ds_write_b16_d16_hi v65, v187 offset:384
	ds_write_b16 v65, v188 offset:512
	ds_write_b16_d16_hi v65, v188 offset:640
	ds_write_b16 v65, v189 offset:768
	ds_write_b16_d16_hi v65, v189 offset:896
	ds_write_b16 v65, v190 offset:1024
	ds_write_b16_d16_hi v65, v190 offset:1152
	ds_write_b16 v65, v191 offset:1280
	ds_write_b16_d16_hi v65, v191 offset:1408
	ds_write_b16 v65, v192 offset:1536
	ds_write_b16_d16_hi v65, v192 offset:1664
	ds_write_b16 v65, v193 offset:1792
	ds_write_b16_d16_hi v65, v193 offset:1920
	ds_read_b64 v[202:203], v154
	ds_read_b64 v[204:205], v154 offset:512
	ds_read_b64 v[206:207], v154 offset:1024
	ds_read_b64 v[208:209], v154 offset:1536
	v_and_b32_e32 v78, 0xffff, v33
	v_lshrrev_b32_e32 v79, 16, v33
	v_lshl_add_u32 v78, v78, 7, v152
	v_lshl_add_u32 v79, v79, 7, v153
	s_mov_b32 m0, s99
	s_add_i32 s43, s99, 0x400
	global_load_lds_dwordx4 v78, s[50:51]
	s_mov_b32 m0, s43
	s_nop 0
	global_load_lds_dwordx4 v79, s[50:51]
	s_waitcnt vmcnt(10)
	v_add_u32_e32 v54, s77, v59
	v_add_u32_e32 v55, s77, v60
	v_add_u32_e32 v56, s77, v61
	v_add_u32_e32 v57, s77, v62
	ds_read_b64_tr_b4 v[50:51], v160 offset:384
	ds_read_b64_tr_b4 v[52:53], v160 offset:1408
	ds_read_b64_tr_b4 v[130:131], v54
	ds_read_b64_tr_b4 v[132:133], v55
	ds_read_b64_tr_b4 v[134:135], v56
	ds_read_b64_tr_b4 v[136:137], v57
	s_waitcnt lgkmcnt(15)
	v_dot8c_i32_i4_e32 v38, v122, v48
	v_dot8c_i32_i4_e32 v39, v122, v46
	v_dot8c_i32_i4_e32 v40, v124, v48
	v_dot8c_i32_i4_e32 v41, v124, v46
	v_dot8c_i32_i4_e32 v42, v126, v48
	v_dot8c_i32_i4_e32 v43, v126, v46
	v_dot8c_i32_i4_e32 v44, v128, v48
	v_dot8c_i32_i4_e32 v45, v128, v46
	v_dot8c_i32_i4_e32 v38, v123, v49
	v_dot8c_i32_i4_e32 v39, v123, v47
	v_dot8c_i32_i4_e32 v40, v125, v49
	v_dot8c_i32_i4_e32 v41, v125, v47
	v_dot8c_i32_i4_e32 v42, v127, v49
	v_dot8c_i32_i4_e32 v43, v127, v47
	v_dot8c_i32_i4_e32 v44, v129, v49
	v_dot8c_i32_i4_e32 v45, v129, v47
	s_waitcnt lgkmcnt(15)
	v_and_b32_e32 v78, 0xffff, v18
	v_lshrrev_b32_e32 v79, 16, v18
	v_lshl_add_u32 v78, v78, 7, v150
	v_lshl_add_u32 v79, v79, 7, v151
	s_mov_b32 m0, s76
	s_add_i32 s43, s76, 0x400
	global_load_lds_dwordx4 v78, s[50:51]
	s_mov_b32 m0, s43
	s_nop 0
	global_load_lds_dwordx4 v79, s[50:51]
	s_waitcnt vmcnt(10)
	v_add_u32_e32 v54, s78, v59
	v_add_u32_e32 v55, s78, v60
	v_add_u32_e32 v56, s78, v61
	v_add_u32_e32 v57, s78, v62
	ds_read_b64_tr_b4 v[46:47], v160 offset:512
	ds_read_b64_tr_b4 v[48:49], v160 offset:1536
	ds_read_b64_tr_b4 v[122:123], v54
	ds_read_b64_tr_b4 v[124:125], v55
	ds_read_b64_tr_b4 v[126:127], v56
	ds_read_b64_tr_b4 v[128:129], v57
	s_waitcnt lgkmcnt(6)
	v_dot8c_i32_i4_e32 v38, v130, v52
	v_dot8c_i32_i4_e32 v39, v130, v50
	v_dot8c_i32_i4_e32 v40, v132, v52
	v_dot8c_i32_i4_e32 v41, v132, v50
	v_dot8c_i32_i4_e32 v42, v134, v52
	v_dot8c_i32_i4_e32 v43, v134, v50
	v_dot8c_i32_i4_e32 v44, v136, v52
	v_dot8c_i32_i4_e32 v45, v136, v50
	v_dot8c_i32_i4_e32 v38, v131, v53
	v_dot8c_i32_i4_e32 v39, v131, v51
	v_dot8c_i32_i4_e32 v40, v133, v53
	v_dot8c_i32_i4_e32 v41, v133, v51
	v_dot8c_i32_i4_e32 v42, v135, v53
	v_dot8c_i32_i4_e32 v43, v135, v51
	v_dot8c_i32_i4_e32 v44, v137, v53
	v_dot8c_i32_i4_e32 v45, v137, v51
	v_and_b32_e32 v78, 0xffff, v19
	v_lshrrev_b32_e32 v79, 16, v19
	v_lshl_add_u32 v78, v78, 7, v150
	v_lshl_add_u32 v79, v79, 7, v151
	s_mov_b32 m0, s77
	s_add_i32 s43, s77, 0x400
	global_load_lds_dwordx4 v78, s[50:51]
	s_mov_b32 m0, s43
	s_nop 0
	global_load_lds_dwordx4 v79, s[50:51]
	s_waitcnt vmcnt(8)
	v_add_u32_e32 v54, s79, v59
	v_add_u32_e32 v55, s79, v60
	v_add_u32_e32 v56, s79, v61
	v_add_u32_e32 v57, s79, v62
	ds_read_b64_tr_b4 v[50:51], v160 offset:640
	ds_read_b64_tr_b4 v[52:53], v160 offset:1664
	ds_read_b64_tr_b4 v[130:131], v54
	ds_read_b64_tr_b4 v[132:133], v55
	ds_read_b64_tr_b4 v[134:135], v56
	ds_read_b64_tr_b4 v[136:137], v57
	s_waitcnt lgkmcnt(6)
	v_dot8c_i32_i4_e32 v38, v122, v48
	v_dot8c_i32_i4_e32 v39, v122, v46
	v_dot8c_i32_i4_e32 v40, v124, v48
	v_dot8c_i32_i4_e32 v41, v124, v46
	v_dot8c_i32_i4_e32 v42, v126, v48
	v_dot8c_i32_i4_e32 v43, v126, v46
	v_dot8c_i32_i4_e32 v44, v128, v48
	v_dot8c_i32_i4_e32 v45, v128, v46
	v_dot8c_i32_i4_e32 v38, v123, v49
	v_dot8c_i32_i4_e32 v39, v123, v47
	v_dot8c_i32_i4_e32 v40, v125, v49
	v_dot8c_i32_i4_e32 v41, v125, v47
	v_dot8c_i32_i4_e32 v42, v127, v49
	v_dot8c_i32_i4_e32 v43, v127, v47
	v_dot8c_i32_i4_e32 v44, v129, v49
	v_dot8c_i32_i4_e32 v45, v129, v47
	s_waitcnt lgkmcnt(15)
; #define LAS __attribute__((address_space(3)))
; __device__ __forceinline__ void peer_v_tokens(int j, const LAS unsigned short* EL, const LAS unsigned char* AL  , const LAS float* ASC  , const LAS int* SAL  , ...
;     ...
;         for (int m = 0; m < 2; ++m) {
;             const int idx = lane + 64 * m, tau = idx >> 4, sr = idx & 15, k = 16 * (sr & 7) + 2 * tau + (sr >> 3);
;             const int aq = (int)*(const LAS signed char*)(AL + tl * 128 + k); const int tq = aq + 8;
;             const unsigned lo = (((unsigned)tq & 15u) ^ 8u) * 0x11111111u, hi = ((unsigned)(tq >> 4) & 15u) * 0x11111111u;
;             typedef unsigned u2v __attribute__((ext_vector_type(2)));
;             u2v l2; l2.x = lo; l2.y = lo; u2v h2; h2.x = hi; h2.y = hi;
;             *(LAS u2v*)(ATL + 8 * idx) = l2; *(LAS u2v*)(ATL + 1024 + 8 * idx) = h2;
;         }
;         const float asc = ASC[tl]; const int sa = SAL[tl];
;         CFENCE();
;         int accH[4], accL[4];
; #pragma unroll
;         for (int st = 0; st < 16; ++st) {
;             const int p = st >> 2, q = st & 3;
;             if (st < 14) VDMA(st + 2, (st + 2) % 3);
;             if (st < 14) asm volatile("s_waitcnt vmcnt(8)" ::: "memory");
;             else if (st == 14) asm volatile("s_waitcnt vmcnt(4)" ::: "memory");
;             else asm volatile("s_waitcnt vmcnt(0)" ::: "memory");
;             if (q == 0) {
; #pragma unroll
;                 for (int r = 0; r < 4; ++r) { accH[r] = 0; accL[r] = 0; } }
; #pragma unroll
;             for (int tp = 0; tp < 2; ++tp) {
;                 const v2i ao = TR4(ATL + (2 * q + tp) * 128 + 8 * s16), ah = TR4(ATL + 1024 + (2 * q + tp) * 128 + 8 * s16);
; #pragma unroll
;                 for (int r = 0; r < 4; ++r) {
;                     const v2i d = TR4(ldsb + BUF[st % 3] + 2048 * tp + roff[r]);
;                     accH[r] = __builtin_amdgcn_sdot8(d.x, ah.x, accH[r], false); accH[r] = __builtin_amdgcn_sdot8(d.y, ah.y, accH[r], false);
;                     accL[r] = __builtin_amdgcn_sdot8(d.x, ao.x, accL[r], false); accL[r] = __builtin_amdgcn_sdot8(d.y, ao.y, accL[r], false);
;                 }
;             }
;             asm volatile("s_waitcnt lgkmcnt(0)" ::: "memory");
;             if (q == 3) {
; #pragma unroll
;                 for (int r = 0; r < 4; ++r) STASH[256 * p + 16 * (grp + 4 * r) + pc] = f2bf(asc * (float)(2 * ((accH[r] << 4) + accL[r]) + sa));
	v_add_u32_e32 v143, 8, v139
	v_and_b32_e32 v142, 15, v143
	v_xor_b32_e32 v142, 8, v142
	v_bfe_u32 v144, v143, 4, 4
	v_mul_lo_u32 v142, v142, s92
	v_mul_lo_u32 v144, v144, s92
	v_mov_b32_e32 v143, v142
	v_mov_b32_e32 v145, v144
	ds_write2st64_b64 v159, v[142:143], v[144:145] offset1:2
	v_and_b32_e32 v78, 0xffff, v20
	v_lshrrev_b32_e32 v79, 16, v20
	v_lshl_add_u32 v78, v78, 7, v150
	v_lshl_add_u32 v79, v79, 7, v151
	s_mov_b32 m0, s78
	s_add_i32 s43, s78, 0x400
	global_load_lds_dwordx4 v78, s[50:51]
	s_mov_b32 m0, s43
	s_nop 0
	global_load_lds_dwordx4 v79, s[50:51]
	s_waitcnt vmcnt(8)
	v_add_u32_e32 v54, s98, v59
	v_add_u32_e32 v55, s98, v60
	v_add_u32_e32 v56, s98, v61
	v_add_u32_e32 v57, s98, v62
	ds_read_b64_tr_b4 v[46:47], v160 offset:768
	ds_read_b64_tr_b4 v[48:49], v160 offset:1792
	ds_read_b64_tr_b4 v[122:123], v54
	ds_read_b64_tr_b4 v[124:125], v55
	ds_read_b64_tr_b4 v[126:127], v56
	ds_read_b64_tr_b4 v[128:129], v57
	s_waitcnt lgkmcnt(7)
	v_dot8c_i32_i4_e32 v38, v130, v52
	v_dot8c_i32_i4_e32 v39, v130, v50
	v_dot8c_i32_i4_e32 v40, v132, v52
	v_dot8c_i32_i4_e32 v41, v132, v50
	v_dot8c_i32_i4_e32 v42, v134, v52
	v_dot8c_i32_i4_e32 v43, v134, v50
	v_dot8c_i32_i4_e32 v44, v136, v52
	v_dot8c_i32_i4_e32 v45, v136, v50
	v_dot8c_i32_i4_e32 v38, v131, v53
	v_dot8c_i32_i4_e32 v39, v131, v51
	v_dot8c_i32_i4_e32 v40, v133, v53
	v_dot8c_i32_i4_e32 v41, v133, v51
	v_dot8c_i32_i4_e32 v42, v135, v53
	v_dot8c_i32_i4_e32 v43, v135, v51
	v_dot8c_i32_i4_e32 v44, v137, v53
	v_dot8c_i32_i4_e32 v45, v137, v51
	v_and_b32_e32 v78, 0xffff, v21
	v_lshrrev_b32_e32 v79, 16, v21
	v_lshl_add_u32 v78, v78, 7, v150
	v_lshl_add_u32 v79, v79, 7, v151
	s_mov_b32 m0, s79
	s_add_i32 s43, s79, 0x400
	global_load_lds_dwordx4 v78, s[50:51]
	s_mov_b32 m0, s43
	s_nop 0
	global_load_lds_dwordx4 v79, s[50:51]
	s_waitcnt vmcnt(8)
	v_add_u32_e32 v54, s99, v59
	v_add_u32_e32 v55, s99, v60
	v_add_u32_e32 v56, s99, v61
	v_add_u32_e32 v57, s99, v62
	ds_read_b64_tr_b4 v[50:51], v160 offset:896
	ds_read_b64_tr_b4 v[52:53], v160 offset:1920
	ds_read_b64_tr_b4 v[130:131], v54
	ds_read_b64_tr_b4 v[132:133], v55
	ds_read_b64_tr_b4 v[134:135], v56
	ds_read_b64_tr_b4 v[136:137], v57
	s_waitcnt lgkmcnt(6)
	v_dot8c_i32_i4_e32 v38, v122, v48
	v_dot8c_i32_i4_e32 v39, v122, v46
	v_dot8c_i32_i4_e32 v40, v124, v48
	v_dot8c_i32_i4_e32 v41, v124, v46
	v_dot8c_i32_i4_e32 v42, v126, v48
	v_dot8c_i32_i4_e32 v43, v126, v46
	v_dot8c_i32_i4_e32 v44, v128, v48
	v_dot8c_i32_i4_e32 v45, v128, v46
	v_dot8c_i32_i4_e32 v38, v123, v49
	v_dot8c_i32_i4_e32 v39, v123, v47
	v_dot8c_i32_i4_e32 v40, v125, v49
	v_dot8c_i32_i4_e32 v41, v125, v47
	v_dot8c_i32_i4_e32 v42, v127, v49
	v_dot8c_i32_i4_e32 v43, v127, v47
	v_dot8c_i32_i4_e32 v44, v129, v49
	v_dot8c_i32_i4_e32 v45, v129, v47
	v_and_b32_e32 v78, 0xffff, v22
	v_lshrrev_b32_e32 v79, 16, v22
	v_lshl_add_u32 v78, v78, 7, v150
	v_lshl_add_u32 v79, v79, 7, v151
	s_mov_b32 m0, s98
	s_add_i32 s43, s98, 0x400
	global_load_lds_dwordx4 v78, s[50:51]
	s_mov_b32 m0, s43
	s_nop 0
	global_load_lds_dwordx4 v79, s[50:51]
	s_waitcnt vmcnt(8)
	v_add_u32_e32 v54, s76, v59
	v_add_u32_e32 v55, s76, v60
	v_add_u32_e32 v56, s76, v61
	v_add_u32_e32 v57, s76, v62
	ds_read_b64_tr_b4 v[46:47], v160
	ds_read_b64_tr_b4 v[48:49], v160 offset:1024
	ds_read_b64_tr_b4 v[122:123], v54
	ds_read_b64_tr_b4 v[124:125], v55
	ds_read_b64_tr_b4 v[126:127], v56
	ds_read_b64_tr_b4 v[128:129], v57
	s_waitcnt lgkmcnt(6)
	v_dot8c_i32_i4_e32 v38, v130, v52
	v_dot8c_i32_i4_e32 v39, v130, v50
	v_dot8c_i32_i4_e32 v40, v132, v52
	v_dot8c_i32_i4_e32 v41, v132, v50
	v_dot8c_i32_i4_e32 v42, v134, v52
	v_dot8c_i32_i4_e32 v43, v134, v50
	v_dot8c_i32_i4_e32 v44, v136, v52
	v_dot8c_i32_i4_e32 v45, v136, v50
	v_dot8c_i32_i4_e32 v38, v131, v53
	v_dot8c_i32_i4_e32 v39, v131, v51
	v_dot8c_i32_i4_e32 v40, v133, v53
	v_dot8c_i32_i4_e32 v41, v133, v51
	v_dot8c_i32_i4_e32 v42, v135, v53
	v_dot8c_i32_i4_e32 v43, v135, v51
	v_dot8c_i32_i4_e32 v44, v137, v53
	v_dot8c_i32_i4_e32 v45, v137, v51
	s_nop 3
	s_waitcnt lgkmcnt(15)
	v_lshlrev_b32_e32 v38, 5, v38
	v_lshlrev_b32_e32 v39, 1, v39
	v_add3_u32 v38, v39, v229, v38
	v_cvt_f32_i32_e32 v38, v38
	v_mul_f32_e32 v38, v228, v38
	v_lshlrev_b32_e32 v40, 5, v40
	v_lshlrev_b32_e32 v41, 1, v41
	v_add3_u32 v40, v41, v229, v40
	v_cvt_f32_i32_e32 v40, v40
	v_mul_f32_e32 v40, v228, v40
	v_lshlrev_b32_e32 v42, 5, v42
	v_lshlrev_b32_e32 v43, 1, v43
	v_add3_u32 v42, v43, v229, v42
	v_cvt_f32_i32_e32 v42, v42
	v_mul_f32_e32 v42, v228, v42
	v_lshlrev_b32_e32 v44, 5, v44
	v_lshlrev_b32_e32 v45, 1, v45
	v_add3_u32 v44, v45, v229, v44
	v_cvt_f32_i32_e32 v44, v44
	v_mul_f32_e32 v44, v228, v44
	v_cvt_pk_bf16_f32 v226, v38, v40
	v_cvt_pk_bf16_f32 v230, v42, v44
	v_add_u32_e32 v147, 8, v140
	v_and_b32_e32 v146, 15, v147
	v_xor_b32_e32 v146, 8, v146
	v_bfe_u32 v148, v147, 4, 4
	v_mul_lo_u32 v146, v146, s92
	v_mul_lo_u32 v148, v148, s92
	v_mov_b32_e32 v147, v146
	v_mov_b32_e32 v149, v148
	ds_write2st64_b64 v77, v[146:147], v[148:149] offset1:2
	v_add_u32_e32 v138, 0x1400, v74
	ds_read_u8 v139, v138
	v_add_u32_e32 v141, 0x1400, v73
	ds_read_u8 v140, v141
	s_add_i32 s43, s67, 128
	v_mov_b32_e32 v138, s43
	ds_read2st64_b32 v[228:229], v138 offset1:1
	ds_read_b128 v[26:29], v227 offset:10240
	ds_read_b128 v[30:33], v227 offset:10256
	v_mov_b32_e32 v38, 0
	v_mov_b32_e32 v39, 0
	v_mov_b32_e32 v40, 0
	v_mov_b32_e32 v41, 0
	v_mov_b32_e32 v42, 0
	v_mov_b32_e32 v43, 0
	v_mov_b32_e32 v44, 0
	v_mov_b32_e32 v45, 0
	v_and_b32_e32 v78, 0xffff, v23
	v_lshrrev_b32_e32 v79, 16, v23
	v_lshl_add_u32 v78, v78, 7, v150
	v_lshl_add_u32 v79, v79, 7, v151
	s_mov_b32 m0, s99
	s_add_i32 s43, s99, 0x400
	global_load_lds_dwordx4 v78, s[50:51]
	s_mov_b32 m0, s43
	s_nop 0
	global_load_lds_dwordx4 v79, s[50:51]
	s_waitcnt vmcnt(8)
; __device__ __forceinline__ void peer_v_tokens(int j, const LAS unsigned short* EL, const LAS unsigned char* AL  , const LAS float* ASC  , const LAS int* SAL  , ...
;     ...
;         for (int st = 0; st < 16; ++st) {
;             const int p = st >> 2, q = st & 3;
;             if (st < 14) VDMA(st + 2, (st + 2) % 3);
;             if (st < 14) asm volatile("s_waitcnt vmcnt(8)" ::: "memory");
;             else if (st == 14) asm volatile("s_waitcnt vmcnt(4)" ::: "memory");
;             else asm volatile("s_waitcnt vmcnt(0)" ::: "memory");
;             if (q == 0) {
; #pragma unroll
;                 for (int r = 0; r < 4; ++r) { accH[r] = 0; accL[r] = 0; } }
; #pragma unroll
;             for (int tp = 0; tp < 2; ++tp) {
;                 const v2i ao = TR4(ATL + (2 * q + tp) * 128 + 8 * s16), ah = TR4(ATL + 1024 + (2 * q + tp) * 128 + 8 * s16);
; #pragma unroll
;                 for (int r = 0; r < 4; ++r) {
;                     const v2i d = TR4(ldsb + BUF[st % 3] + 2048 * tp + roff[r]);
;                     accH[r] = __builtin_amdgcn_sdot8(d.x, ah.x, accH[r], false); accH[r] = __builtin_amdgcn_sdot8(d.y, ah.y, accH[r], false);
;                     accL[r] = __builtin_amdgcn_sdot8(d.x, ao.x, accL[r], false); accL[r] = __builtin_amdgcn_sdot8(d.y, ao.y, accL[r], false);
;                 }
;             }
;             asm volatile("s_waitcnt lgkmcnt(0)" ::: "memory");
;             if (q == 3) {
; #pragma unroll
;                 for (int r = 0; r < 4; ++r) STASH[256 * p + 16 * (grp + 4 * r) + pc] = f2bf(asc * (float)(2 * ((accH[r] << 4) + accL[r]) + sa));
;             }
;         }
;         CFENCE();
;         {
;             float4 v[4]; float ss = 0.f;
; #pragma unroll
;             for (int jq = 0; jq < 4; ++jq) { typedef unsigned u2v __attribute__((ext_vector_type(2))); const u2v pw = *(const LAS u2v*)(STASH + 4 * lane + 256 * jq); const uint2 hw = hv[jq];
;                 v[jq] = make_float4(__uint_as_float(hw.x << 16) + __uint_as_float(pw.x << 16), __uint_as_float(hw.x & 0xffff0000u) + __uint_as_float(pw.x & 0xffff0000u),
;                                     __uint_as_float(hw.y << 16) + __uint_as_float(pw.y << 16), __uint_as_float(hw.y & 0xffff0000u) + __uint_as_float(pw.y & 0xffff0000u));
;                 ss += v[jq].x * v[jq].x + v[jq].y * v[jq].y + v[jq].z * v[jq].z + v[jq].w * v[jq].w; }
;             ss = wave_sum(ss);
	v_add_u32_e32 v54, s77, v59
	v_add_u32_e32 v55, s77, v60
	v_add_u32_e32 v56, s77, v61
	v_add_u32_e32 v57, s77, v62
	ds_read_b64_tr_b4 v[50:51], v160 offset:128
	ds_read_b64_tr_b4 v[52:53], v160 offset:1152
	ds_read_b64_tr_b4 v[130:131], v54
	ds_read_b64_tr_b4 v[132:133], v55
	ds_read_b64_tr_b4 v[134:135], v56
	ds_read_b64_tr_b4 v[136:137], v57
	s_waitcnt lgkmcnt(12)
	s_waitcnt vmcnt(36) lgkmcnt(15)
	v_lshlrev_b32_e32 v210, 16, v194
	v_and_b32_e32 v211, 0xffff0000, v194
	v_lshlrev_b32_e32 v142, 16, v202
	v_and_b32_e32 v143, 0xffff0000, v202
	v_add_f32_e32 v210, v210, v142
	v_add_f32_e32 v211, v211, v143
	v_lshlrev_b32_e32 v212, 16, v195
	v_and_b32_e32 v213, 0xffff0000, v195
	v_lshlrev_b32_e32 v142, 16, v203
	v_and_b32_e32 v143, 0xffff0000, v203
	v_add_f32_e32 v212, v212, v142
	v_add_f32_e32 v213, v213, v143
	v_lshlrev_b32_e32 v214, 16, v196
	v_and_b32_e32 v215, 0xffff0000, v196
	v_lshlrev_b32_e32 v142, 16, v204
	v_and_b32_e32 v143, 0xffff0000, v204
	v_add_f32_e32 v214, v214, v142
	v_add_f32_e32 v215, v215, v143
	v_lshlrev_b32_e32 v216, 16, v197
	v_and_b32_e32 v217, 0xffff0000, v197
	v_lshlrev_b32_e32 v142, 16, v205
	v_and_b32_e32 v143, 0xffff0000, v205
	v_add_f32_e32 v216, v216, v142
	v_add_f32_e32 v217, v217, v143
	v_lshlrev_b32_e32 v218, 16, v198
	v_and_b32_e32 v219, 0xffff0000, v198
	v_lshlrev_b32_e32 v142, 16, v206
	v_and_b32_e32 v143, 0xffff0000, v206
	v_add_f32_e32 v218, v218, v142
	v_add_f32_e32 v219, v219, v143
	v_lshlrev_b32_e32 v220, 16, v199
	v_and_b32_e32 v221, 0xffff0000, v199
	v_lshlrev_b32_e32 v142, 16, v207
	v_and_b32_e32 v143, 0xffff0000, v207
	v_add_f32_e32 v220, v220, v142
	v_add_f32_e32 v221, v221, v143
	v_lshlrev_b32_e32 v222, 16, v200
	v_and_b32_e32 v223, 0xffff0000, v200
	v_lshlrev_b32_e32 v142, 16, v208
	v_and_b32_e32 v143, 0xffff0000, v208
	v_add_f32_e32 v222, v222, v142
	v_add_f32_e32 v223, v223, v143
	v_lshlrev_b32_e32 v224, 16, v201
	v_and_b32_e32 v225, 0xffff0000, v201
	v_lshlrev_b32_e32 v142, 16, v209
	v_and_b32_e32 v143, 0xffff0000, v209
	v_add_f32_e32 v224, v224, v142
	v_add_f32_e32 v225, v225, v143
	v_mov_b32_e32 v144, 0
	v_mul_f32_e32 v145, v210, v210
	v_fmac_f32_e32 v145, v211, v211
	v_fmac_f32_e32 v145, v212, v212
	v_fmac_f32_e32 v145, v213, v213
	v_add_f32_e32 v144, v144, v145
	v_mul_f32_e32 v145, v214, v214
	v_fmac_f32_e32 v145, v215, v215
	v_fmac_f32_e32 v145, v216, v216
	v_fmac_f32_e32 v145, v217, v217
	v_add_f32_e32 v144, v144, v145
	v_mul_f32_e32 v145, v218, v218
	v_fmac_f32_e32 v145, v219, v219
	v_fmac_f32_e32 v145, v220, v220
	v_fmac_f32_e32 v145, v221, v221
	v_add_f32_e32 v144, v144, v145
	v_mul_f32_e32 v145, v222, v222
	v_fmac_f32_e32 v145, v223, v223
	v_fmac_f32_e32 v145, v224, v224
	v_fmac_f32_e32 v145, v225, v225
	v_add_f32_e32 v144, v144, v145
	s_nop 1
	v_add_f32_dpp v144, v144, v144 quad_perm:[1,0,3,2] row_mask:0xf bank_mask:0xf bound_ctrl:1
	s_nop 1
	v_add_f32_dpp v144, v144, v144 quad_perm:[2,3,0,1] row_mask:0xf bank_mask:0xf bound_ctrl:1
	s_nop 1
	v_add_f32_dpp v144, v144, v144 row_half_mirror row_mask:0xf bank_mask:0xf bound_ctrl:1
	s_nop 1
	v_add_f32_dpp v144, v144, v144 row_mirror row_mask:0xf bank_mask:0xf bound_ctrl:1
	s_nop 1
	v_readlane_b32 s10, v144, 0
	v_readlane_b32 s11, v144, 16
	v_readlane_b32 s14, v144, 32
	v_readlane_b32 s15, v144, 48
	s_nop 3
	v_mov_b32_e32 v144, s11
	v_mov_b32_e32 v145, s15
	v_add_f32_e32 v144, s10, v144
	v_add_f32_e32 v145, s14, v145
	v_add_f32_e32 v144, v144, v145
	v_fmamk_f32 v144, v144, 0x3a800000, v111
	v_rsq_f32_e32 v144, v144
	s_nop 0
	v_mul_f32_e32 v210, v210, v144
	v_mul_f32_e32 v211, v211, v144
	v_mul_f32_e32 v212, v212, v144
	v_mul_f32_e32 v213, v213, v144
	v_mul_f32_e32 v214, v214, v144
	v_mul_f32_e32 v215, v215, v144
	v_mul_f32_e32 v216, v216, v144
	v_mul_f32_e32 v217, v217, v144
	v_mul_f32_e32 v218, v218, v144
	v_mul_f32_e32 v219, v219, v144
	v_mul_f32_e32 v220, v220, v144
	v_mul_f32_e32 v221, v221, v144
	v_mul_f32_e32 v222, v222, v144
	v_mul_f32_e32 v223, v223, v144
	v_mul_f32_e32 v224, v224, v144
	v_mul_f32_e32 v225, v225, v144
	v_dot8c_i32_i4_e32 v38, v122, v48
	v_dot8c_i32_i4_e32 v39, v122, v46
	v_dot8c_i32_i4_e32 v40, v124, v48
	v_dot8c_i32_i4_e32 v41, v124, v46
	v_dot8c_i32_i4_e32 v42, v126, v48
	v_dot8c_i32_i4_e32 v43, v126, v46
	v_dot8c_i32_i4_e32 v44, v128, v48
	v_dot8c_i32_i4_e32 v45, v128, v46
	v_dot8c_i32_i4_e32 v38, v123, v49
	v_dot8c_i32_i4_e32 v39, v123, v47
	v_dot8c_i32_i4_e32 v40, v125, v49
	v_dot8c_i32_i4_e32 v41, v125, v47
	v_dot8c_i32_i4_e32 v42, v127, v49
	v_dot8c_i32_i4_e32 v43, v127, v47
	v_dot8c_i32_i4_e32 v44, v129, v49
	v_dot8c_i32_i4_e32 v45, v129, v47
	v_and_b32_e32 v78, 0xffff, v24
	v_lshrrev_b32_e32 v79, 16, v24
	v_lshl_add_u32 v78, v78, 7, v150
	v_lshl_add_u32 v79, v79, 7, v151
	s_mov_b32 m0, s76
	s_add_i32 s43, s76, 0x400
	global_load_lds_dwordx4 v78, s[50:51]
	s_mov_b32 m0, s43
	s_nop 0
	global_load_lds_dwordx4 v79, s[50:51]
	s_waitcnt vmcnt(8)
	v_add_u32_e32 v54, s78, v59
	v_add_u32_e32 v55, s78, v60
	v_add_u32_e32 v56, s78, v61
	v_add_u32_e32 v57, s78, v62
	ds_read_b64_tr_b4 v[46:47], v160 offset:256
	ds_read_b64_tr_b4 v[48:49], v160 offset:1280
	ds_read_b64_tr_b4 v[122:123], v54
	ds_read_b64_tr_b4 v[124:125], v55
	ds_read_b64_tr_b4 v[126:127], v56
	ds_read_b64_tr_b4 v[128:129], v57
	s_waitcnt lgkmcnt(6)
; #define LAS __attribute__((address_space(3)))
; #define TR4(p_) __builtin_amdgcn_ds_read_tr4_b64_v2i32((LAS v2i*)(p_))
; #define CFENCE() asm volatile("" ::: "memory")
; __device__ __forceinline__ void peer_v_tokens(int j, const LAS unsigned short* EL, const LAS unsigned char* AL  , const LAS float* ASC  , const LAS int* SAL  , ...
;     ...
;         for (int m = 0; m < 2; ++m) {
;             const int idx = lane + 64 * m, tau = idx >> 4, sr = idx & 15, k = 16 * (sr & 7) + 2 * tau + (sr >> 3);
;             const int aq = (int)*(const LAS signed char*)(AL + tl * 128 + k); const int tq = aq + 8;
;             const unsigned lo = (((unsigned)tq & 15u) ^ 8u) * 0x11111111u, hi = ((unsigned)(tq >> 4) & 15u) * 0x11111111u;
;             typedef unsigned u2v __attribute__((ext_vector_type(2)));
;             u2v l2; l2.x = lo; l2.y = lo; u2v h2; h2.x = hi; h2.y = hi;
;             *(LAS u2v*)(ATL + 8 * idx) = l2; *(LAS u2v*)(ATL + 1024 + 8 * idx) = h2;
;         }
;         const float asc = ASC[tl]; const int sa = SAL[tl];
;         CFENCE();
;         int accH[4], accL[4];
; #pragma unroll
;         for (int st = 0; st < 16; ++st) {
;             const int p = st >> 2, q = st & 3;
;             if (st < 14) VDMA(st + 2, (st + 2) % 3);
;             if (st < 14) asm volatile("s_waitcnt vmcnt(8)" ::: "memory");
;             else if (st == 14) asm volatile("s_waitcnt vmcnt(4)" ::: "memory");
;             else asm volatile("s_waitcnt vmcnt(0)" ::: "memory");
;             if (q == 0) {
; #pragma unroll
;                 for (int r = 0; r < 4; ++r) { accH[r] = 0; accL[r] = 0; } }
; #pragma unroll
;             for (int tp = 0; tp < 2; ++tp) {
;                 const v2i ao = TR4(ATL + (2 * q + tp) * 128 + 8 * s16), ah = TR4(ATL + 1024 + (2 * q + tp) * 128 + 8 * s16);
; #pragma unroll
;                 for (int r = 0; r < 4; ++r) {
;                     const v2i d = TR4(ldsb + BUF[st % 3] + 2048 * tp + roff[r]);
;                     accH[r] = __builtin_amdgcn_sdot8(d.x, ah.x, accH[r], false); accH[r] = __builtin_amdgcn_sdot8(d.y, ah.y, accH[r], false);
;                     accL[r] = __builtin_amdgcn_sdot8(d.x, ao.x, accL[r], false); accL[r] = __builtin_amdgcn_sdot8(d.y, ao.y, accL[r], false);
;                 }
;             }
	v_dot8c_i32_i4_e32 v38, v130, v52
	v_dot8c_i32_i4_e32 v39, v130, v50
	v_dot8c_i32_i4_e32 v40, v132, v52
	v_dot8c_i32_i4_e32 v41, v132, v50
	v_dot8c_i32_i4_e32 v42, v134, v52
	v_dot8c_i32_i4_e32 v43, v134, v50
	v_dot8c_i32_i4_e32 v44, v136, v52
	v_dot8c_i32_i4_e32 v45, v136, v50
	v_dot8c_i32_i4_e32 v38, v131, v53
	v_dot8c_i32_i4_e32 v39, v131, v51
	v_dot8c_i32_i4_e32 v40, v133, v53
	v_dot8c_i32_i4_e32 v41, v133, v51
	v_dot8c_i32_i4_e32 v42, v135, v53
	v_dot8c_i32_i4_e32 v43, v135, v51
	v_dot8c_i32_i4_e32 v44, v137, v53
	v_dot8c_i32_i4_e32 v45, v137, v51
	v_and_b32_e32 v78, 0xffff, v25
	v_lshrrev_b32_e32 v79, 16, v25
	v_lshl_add_u32 v78, v78, 7, v150
	v_lshl_add_u32 v79, v79, 7, v151
	s_mov_b32 m0, s77
	s_add_i32 s43, s77, 0x400
	global_load_lds_dwordx4 v78, s[50:51]
	s_mov_b32 m0, s43
	s_nop 0
	global_load_lds_dwordx4 v79, s[50:51]
	s_waitcnt vmcnt(8)
	v_add_u32_e32 v54, s79, v59
	v_add_u32_e32 v55, s79, v60
	v_add_u32_e32 v56, s79, v61
	v_add_u32_e32 v57, s79, v62
	ds_read_b64_tr_b4 v[50:51], v160 offset:384
	ds_read_b64_tr_b4 v[52:53], v160 offset:1408
	ds_read_b64_tr_b4 v[130:131], v54
	ds_read_b64_tr_b4 v[132:133], v55
	ds_read_b64_tr_b4 v[134:135], v56
	ds_read_b64_tr_b4 v[136:137], v57
	s_waitcnt lgkmcnt(6)
	v_dot8c_i32_i4_e32 v38, v122, v48
	v_dot8c_i32_i4_e32 v39, v122, v46
	v_dot8c_i32_i4_e32 v40, v124, v48
	v_dot8c_i32_i4_e32 v41, v124, v46
	v_dot8c_i32_i4_e32 v42, v126, v48
	v_dot8c_i32_i4_e32 v43, v126, v46
	v_dot8c_i32_i4_e32 v44, v128, v48
	v_dot8c_i32_i4_e32 v45, v128, v46
	v_dot8c_i32_i4_e32 v38, v123, v49
	v_dot8c_i32_i4_e32 v39, v123, v47
	v_dot8c_i32_i4_e32 v40, v125, v49
	v_dot8c_i32_i4_e32 v41, v125, v47
	v_dot8c_i32_i4_e32 v42, v127, v49
	v_dot8c_i32_i4_e32 v43, v127, v47
	v_dot8c_i32_i4_e32 v44, v129, v49
	v_dot8c_i32_i4_e32 v45, v129, v47
	s_waitcnt lgkmcnt(15)
	v_and_b32_e32 v78, 0xffff, v26
	v_lshrrev_b32_e32 v79, 16, v26
	v_lshl_add_u32 v78, v78, 7, v150
	v_lshl_add_u32 v79, v79, 7, v151
	s_mov_b32 m0, s78
	s_add_i32 s43, s78, 0x400
	global_load_lds_dwordx4 v78, s[50:51]
	s_mov_b32 m0, s43
	s_nop 0
	global_load_lds_dwordx4 v79, s[50:51]
	s_waitcnt vmcnt(8)
	v_add_u32_e32 v54, s98, v59
	v_add_u32_e32 v55, s98, v60
	v_add_u32_e32 v56, s98, v61
	v_add_u32_e32 v57, s98, v62
	ds_read_b64_tr_b4 v[46:47], v160 offset:512
	ds_read_b64_tr_b4 v[48:49], v160 offset:1536
	ds_read_b64_tr_b4 v[122:123], v54
	ds_read_b64_tr_b4 v[124:125], v55
	ds_read_b64_tr_b4 v[126:127], v56
	ds_read_b64_tr_b4 v[128:129], v57
	s_waitcnt lgkmcnt(6)
	v_dot8c_i32_i4_e32 v38, v130, v52
	v_dot8c_i32_i4_e32 v39, v130, v50
	v_dot8c_i32_i4_e32 v40, v132, v52
	v_dot8c_i32_i4_e32 v41, v132, v50
	v_dot8c_i32_i4_e32 v42, v134, v52
	v_dot8c_i32_i4_e32 v43, v134, v50
	v_dot8c_i32_i4_e32 v44, v136, v52
	v_dot8c_i32_i4_e32 v45, v136, v50
	v_dot8c_i32_i4_e32 v38, v131, v53
	v_dot8c_i32_i4_e32 v39, v131, v51
	v_dot8c_i32_i4_e32 v40, v133, v53
	v_dot8c_i32_i4_e32 v41, v133, v51
	v_dot8c_i32_i4_e32 v42, v135, v53
	v_dot8c_i32_i4_e32 v43, v135, v51
	v_dot8c_i32_i4_e32 v44, v137, v53
	v_dot8c_i32_i4_e32 v45, v137, v51
	v_and_b32_e32 v78, 0xffff, v27
	v_lshrrev_b32_e32 v79, 16, v27
	v_lshl_add_u32 v78, v78, 7, v150
	v_lshl_add_u32 v79, v79, 7, v151
	s_mov_b32 m0, s79
	s_add_i32 s43, s79, 0x400
	global_load_lds_dwordx4 v78, s[50:51]
	s_mov_b32 m0, s43
	s_nop 0
	global_load_lds_dwordx4 v79, s[50:51]
	s_waitcnt vmcnt(8)
	v_add_u32_e32 v54, s99, v59
	v_add_u32_e32 v55, s99, v60
	v_add_u32_e32 v56, s99, v61
	v_add_u32_e32 v57, s99, v62
	ds_read_b64_tr_b4 v[50:51], v160 offset:640
	ds_read_b64_tr_b4 v[52:53], v160 offset:1664
	ds_read_b64_tr_b4 v[130:131], v54
	ds_read_b64_tr_b4 v[132:133], v55
	ds_read_b64_tr_b4 v[134:135], v56
	ds_read_b64_tr_b4 v[136:137], v57
	s_waitcnt lgkmcnt(6)
	v_dot8c_i32_i4_e32 v38, v122, v48
	v_dot8c_i32_i4_e32 v39, v122, v46
	v_dot8c_i32_i4_e32 v40, v124, v48
	v_dot8c_i32_i4_e32 v41, v124, v46
	v_dot8c_i32_i4_e32 v42, v126, v48
	v_dot8c_i32_i4_e32 v43, v126, v46
	v_dot8c_i32_i4_e32 v44, v128, v48
	v_dot8c_i32_i4_e32 v45, v128, v46
	v_dot8c_i32_i4_e32 v38, v123, v49
	v_dot8c_i32_i4_e32 v39, v123, v47
	v_dot8c_i32_i4_e32 v40, v125, v49
	v_dot8c_i32_i4_e32 v41, v125, v47
	v_dot8c_i32_i4_e32 v42, v127, v49
	v_dot8c_i32_i4_e32 v43, v127, v47
	v_dot8c_i32_i4_e32 v44, v129, v49
	v_dot8c_i32_i4_e32 v45, v129, v47
	s_waitcnt lgkmcnt(15)
	v_add_u32_e32 v143, 8, v139
	v_and_b32_e32 v142, 15, v143
	v_xor_b32_e32 v142, 8, v142
	v_bfe_u32 v144, v143, 4, 4
	v_mul_lo_u32 v142, v142, s92
	v_mul_lo_u32 v144, v144, s92
	v_mov_b32_e32 v143, v142
	v_mov_b32_e32 v145, v144
	ds_write2st64_b64 v159, v[142:143], v[144:145] offset1:2
	v_and_b32_e32 v78, 0xffff, v28
	v_lshrrev_b32_e32 v79, 16, v28
	v_lshl_add_u32 v78, v78, 7, v150
	v_lshl_add_u32 v79, v79, 7, v151
	s_mov_b32 m0, s98
	s_add_i32 s43, s98, 0x400
	global_load_lds_dwordx4 v78, s[50:51]
	s_mov_b32 m0, s43
	s_nop 0
	global_load_lds_dwordx4 v79, s[50:51]
	s_waitcnt vmcnt(8)
	v_add_u32_e32 v54, s76, v59
	v_add_u32_e32 v55, s76, v60
	v_add_u32_e32 v56, s76, v61
	v_add_u32_e32 v57, s76, v62
	ds_read_b64_tr_b4 v[46:47], v160 offset:768
	ds_read_b64_tr_b4 v[48:49], v160 offset:1792
	ds_read_b64_tr_b4 v[122:123], v54
	ds_read_b64_tr_b4 v[124:125], v55
	ds_read_b64_tr_b4 v[126:127], v56
	ds_read_b64_tr_b4 v[128:129], v57
	s_waitcnt lgkmcnt(7)
; __device__ __forceinline__ void peer_v_tokens(int j, const LAS unsigned short* EL, const LAS unsigned char* AL  , const LAS float* ASC  , const LAS int* SAL  , ...
;     ...
;         for (int m = 0; m < 2; ++m) {
;             const int idx = lane + 64 * m, tau = idx >> 4, sr = idx & 15, k = 16 * (sr & 7) + 2 * tau + (sr >> 3);
;             const int aq = (int)*(const LAS signed char*)(AL + tl * 128 + k); const int tq = aq + 8;
;             const unsigned lo = (((unsigned)tq & 15u) ^ 8u) * 0x11111111u, hi = ((unsigned)(tq >> 4) & 15u) * 0x11111111u;
;             typedef unsigned u2v __attribute__((ext_vector_type(2)));
;             u2v l2; l2.x = lo; l2.y = lo; u2v h2; h2.x = hi; h2.y = hi;
;             *(LAS u2v*)(ATL + 8 * idx) = l2; *(LAS u2v*)(ATL + 1024 + 8 * idx) = h2;
;         }
;         const float asc = ASC[tl]; const int sa = SAL[tl];
;         CFENCE();
;         int accH[4], accL[4];
; #pragma unroll
;         for (int st = 0; st < 16; ++st) {
;             const int p = st >> 2, q = st & 3;
;             if (st < 14) VDMA(st + 2, (st + 2) % 3);
;             if (st < 14) asm volatile("s_waitcnt vmcnt(8)" ::: "memory");
;             else if (st == 14) asm volatile("s_waitcnt vmcnt(4)" ::: "memory");
;             else asm volatile("s_waitcnt vmcnt(0)" ::: "memory");
;             if (q == 0) {
; #pragma unroll
;                 for (int r = 0; r < 4; ++r) { accH[r] = 0; accL[r] = 0; } }
; #pragma unroll
;             for (int tp = 0; tp < 2; ++tp) {
;                 const v2i ao = TR4(ATL + (2 * q + tp) * 128 + 8 * s16), ah = TR4(ATL + 1024 + (2 * q + tp) * 128 + 8 * s16);
; #pragma unroll
;                 for (int r = 0; r < 4; ++r) {
;                     const v2i d = TR4(ldsb + BUF[st % 3] + 2048 * tp + roff[r]);
;                     accH[r] = __builtin_amdgcn_sdot8(d.x, ah.x, accH[r], false); accH[r] = __builtin_amdgcn_sdot8(d.y, ah.y, accH[r], false);
;                     accL[r] = __builtin_amdgcn_sdot8(d.x, ao.x, accL[r], false); accL[r] = __builtin_amdgcn_sdot8(d.y, ao.y, accL[r], false);
;                 }
;             }
;             asm volatile("s_waitcnt lgkmcnt(0)" ::: "memory");
;             if (q == 3) {
; #pragma unroll
;                 for (int r = 0; r < 4; ++r) STASH[256 * p + 16 * (grp + 4 * r) + pc] = f2bf(asc * (float)(2 * ((accH[r] << 4) + accL[r]) + sa));
;             }
;         }
;         CFENCE();
	v_dot8c_i32_i4_e32 v38, v130, v52
	v_dot8c_i32_i4_e32 v39, v130, v50
	v_dot8c_i32_i4_e32 v40, v132, v52
	v_dot8c_i32_i4_e32 v41, v132, v50
	v_dot8c_i32_i4_e32 v42, v134, v52
	v_dot8c_i32_i4_e32 v43, v134, v50
	v_dot8c_i32_i4_e32 v44, v136, v52
	v_dot8c_i32_i4_e32 v45, v136, v50
	v_dot8c_i32_i4_e32 v38, v131, v53
	v_dot8c_i32_i4_e32 v39, v131, v51
	v_dot8c_i32_i4_e32 v40, v133, v53
	v_dot8c_i32_i4_e32 v41, v133, v51
	v_dot8c_i32_i4_e32 v42, v135, v53
	v_dot8c_i32_i4_e32 v43, v135, v51
	v_dot8c_i32_i4_e32 v44, v137, v53
	v_dot8c_i32_i4_e32 v45, v137, v51
	v_and_b32_e32 v78, 0xffff, v29
	v_lshrrev_b32_e32 v79, 16, v29
	v_lshl_add_u32 v78, v78, 7, v150
	v_lshl_add_u32 v79, v79, 7, v151
	s_mov_b32 m0, s99
	s_add_i32 s43, s99, 0x400
	global_load_lds_dwordx4 v78, s[50:51]
	s_mov_b32 m0, s43
	s_nop 0
	global_load_lds_dwordx4 v79, s[50:51]
	s_waitcnt vmcnt(8)
	v_add_u32_e32 v54, s77, v59
	v_add_u32_e32 v55, s77, v60
	v_add_u32_e32 v56, s77, v61
	v_add_u32_e32 v57, s77, v62
	ds_read_b64_tr_b4 v[50:51], v160 offset:896
	ds_read_b64_tr_b4 v[52:53], v160 offset:1920
	ds_read_b64_tr_b4 v[130:131], v54
	ds_read_b64_tr_b4 v[132:133], v55
	ds_read_b64_tr_b4 v[134:135], v56
	ds_read_b64_tr_b4 v[136:137], v57
	s_waitcnt lgkmcnt(6)
	v_dot8c_i32_i4_e32 v38, v122, v48
	v_dot8c_i32_i4_e32 v39, v122, v46
	v_dot8c_i32_i4_e32 v40, v124, v48
	v_dot8c_i32_i4_e32 v41, v124, v46
	v_dot8c_i32_i4_e32 v42, v126, v48
	v_dot8c_i32_i4_e32 v43, v126, v46
	v_dot8c_i32_i4_e32 v44, v128, v48
	v_dot8c_i32_i4_e32 v45, v128, v46
	v_dot8c_i32_i4_e32 v38, v123, v49
	v_dot8c_i32_i4_e32 v39, v123, v47
	v_dot8c_i32_i4_e32 v40, v125, v49
	v_dot8c_i32_i4_e32 v41, v125, v47
	v_dot8c_i32_i4_e32 v42, v127, v49
	v_dot8c_i32_i4_e32 v43, v127, v47
	v_dot8c_i32_i4_e32 v44, v129, v49
	v_dot8c_i32_i4_e32 v45, v129, v47
	v_and_b32_e32 v78, 0xffff, v30
	v_lshrrev_b32_e32 v79, 16, v30
	v_lshl_add_u32 v78, v78, 7, v150
	v_lshl_add_u32 v79, v79, 7, v151
	s_mov_b32 m0, s76
	s_add_i32 s43, s76, 0x400
	global_load_lds_dwordx4 v78, s[50:51]
	s_mov_b32 m0, s43
	s_nop 0
	global_load_lds_dwordx4 v79, s[50:51]
	s_waitcnt vmcnt(8)
	v_add_u32_e32 v54, s78, v59
	v_add_u32_e32 v55, s78, v60
	v_add_u32_e32 v56, s78, v61
	v_add_u32_e32 v57, s78, v62
	ds_read_b64_tr_b4 v[46:47], v160
	ds_read_b64_tr_b4 v[48:49], v160 offset:1024
	ds_read_b64_tr_b4 v[122:123], v54
	ds_read_b64_tr_b4 v[124:125], v55
	ds_read_b64_tr_b4 v[126:127], v56
	ds_read_b64_tr_b4 v[128:129], v57
	s_waitcnt lgkmcnt(6)
	v_dot8c_i32_i4_e32 v38, v130, v52
	v_dot8c_i32_i4_e32 v39, v130, v50
	v_dot8c_i32_i4_e32 v40, v132, v52
	v_dot8c_i32_i4_e32 v41, v132, v50
	v_dot8c_i32_i4_e32 v42, v134, v52
	v_dot8c_i32_i4_e32 v43, v134, v50
	v_dot8c_i32_i4_e32 v44, v136, v52
	v_dot8c_i32_i4_e32 v45, v136, v50
	v_dot8c_i32_i4_e32 v38, v131, v53
	v_dot8c_i32_i4_e32 v39, v131, v51
	v_dot8c_i32_i4_e32 v40, v133, v53
	v_dot8c_i32_i4_e32 v41, v133, v51
	v_dot8c_i32_i4_e32 v42, v135, v53
	v_dot8c_i32_i4_e32 v43, v135, v51
	v_dot8c_i32_i4_e32 v44, v137, v53
	v_dot8c_i32_i4_e32 v45, v137, v51
	s_nop 3
	s_waitcnt lgkmcnt(15)
	v_lshlrev_b32_e32 v38, 5, v38
	v_lshlrev_b32_e32 v39, 1, v39
	v_add3_u32 v38, v39, v229, v38
	v_cvt_f32_i32_e32 v38, v38
	v_mul_f32_e32 v38, v228, v38
	v_lshlrev_b32_e32 v40, 5, v40
	v_lshlrev_b32_e32 v41, 1, v41
	v_add3_u32 v40, v41, v229, v40
	v_cvt_f32_i32_e32 v40, v40
	v_mul_f32_e32 v40, v228, v40
	v_lshlrev_b32_e32 v42, 5, v42
	v_lshlrev_b32_e32 v43, 1, v43
	v_add3_u32 v42, v43, v229, v42
	v_cvt_f32_i32_e32 v42, v42
	v_mul_f32_e32 v42, v228, v42
	v_lshlrev_b32_e32 v44, 5, v44
	v_lshlrev_b32_e32 v45, 1, v45
	v_add3_u32 v44, v45, v229, v44
	v_cvt_f32_i32_e32 v44, v44
	v_mul_f32_e32 v44, v228, v44
	v_cvt_pk_bf16_f32 v240, v38, v40
	v_cvt_pk_bf16_f32 v241, v42, v44
	ds_read_b128 v[252:255], v155
	s_add_i32 s44, s40, 24
	s_ashr_i32 s45, s44, 31
	s_lshl_b64 s[44:45], s[44:45], 12
	v_lshl_add_u64 v[80:81], v[36:37], 0, s[44:45]
	s_waitcnt lgkmcnt(0)
	v_mul_f32_e32 v210, v210, v252
	v_mul_f32_e32 v211, v211, v253
	v_mul_f32_e32 v212, v212, v254
	v_mul_f32_e32 v213, v213, v255
	global_store_dwordx4 v[80:81], v[210:213], off nt
	ds_read_b128 v[252:255], v155 offset:1024
	s_add_i32 s44, s40, 24
	s_ashr_i32 s45, s44, 31
	s_lshl_b64 s[44:45], s[44:45], 12
	v_lshl_add_u64 v[80:81], v[36:37], 0, s[44:45]
	s_waitcnt lgkmcnt(0)
	v_mul_f32_e32 v214, v214, v252
	v_mul_f32_e32 v215, v215, v253
	v_mul_f32_e32 v216, v216, v254
	v_mul_f32_e32 v217, v217, v255
	global_store_dwordx4 v[80:81], v[214:217], off offset:1024 nt
	v_add_u32_e32 v147, 8, v140
	v_and_b32_e32 v146, 15, v147
	v_xor_b32_e32 v146, 8, v146
	v_bfe_u32 v148, v147, 4, 4
	v_mul_lo_u32 v146, v146, s92
	v_mul_lo_u32 v148, v148, s92
	v_mov_b32_e32 v147, v146
	v_mov_b32_e32 v149, v148
	ds_write2st64_b64 v77, v[146:147], v[148:149] offset1:2
	v_add_u32_e32 v138, 0x1800, v74
	ds_read_u8 v139, v138
	v_add_u32_e32 v141, 0x1800, v73
	ds_read_u8 v140, v141
	s_add_i32 s43, s67, 160
	v_mov_b32_e32 v138, s43
	ds_read2st64_b32 v[228:229], v138 offset1:1
	ds_read_b128 v[18:21], v227 offset:12288
	ds_read_b128 v[22:25], v227 offset:12304
	v_mov_b32_e32 v38, 0
	v_mov_b32_e32 v39, 0
	v_mov_b32_e32 v40, 0
	v_mov_b32_e32 v41, 0
	v_mov_b32_e32 v42, 0
	v_mov_b32_e32 v43, 0
	v_mov_b32_e32 v44, 0
	v_mov_b32_e32 v45, 0
	v_and_b32_e32 v78, 0xffff, v31
	v_lshrrev_b32_e32 v79, 16, v31
	v_lshl_add_u32 v78, v78, 7, v150
	v_lshl_add_u32 v79, v79, 7, v151
	s_mov_b32 m0, s77
	s_add_i32 s43, s77, 0x400
	global_load_lds_dwordx4 v78, s[50:51]
	s_mov_b32 m0, s43
	s_nop 0
	global_load_lds_dwordx4 v79, s[50:51]
	s_waitcnt vmcnt(10)
; #define TR4(p_) __builtin_amdgcn_ds_read_tr4_b64_v2i32((LAS v2i*)(p_))
; #define VDMA(st_, k_) do { _Pragma("unroll") for (int i_ = 0; i_ < 4; ++i_) { \
;         const unsigned off_ = (unsigned)((st_) >> 2) * (16384u * 128u) + (PE_ID(E, 4 * ((st_) & 3) + i_) << 7) + ((i_ & 1) ? cx1 : cx0); \
;         __builtin_amdgcn_global_load_lds((const unsigned*)(V4 + off_), (LAS unsigned*)(ldsb + BUF[k_] + 1024 * i_), 16, 0, 0); } } while (0)
; __device__ __forceinline__ void peer_v_tokens(int j, const LAS unsigned short* EL, const LAS unsigned char* AL  , const LAS float* ASC  , const LAS int* SAL  , ...
;     ...
;         for (int st = 0; st < 16; ++st) {
;             const int p = st >> 2, q = st & 3;
;             if (st < 14) VDMA(st + 2, (st + 2) % 3);
;             if (st < 14) asm volatile("s_waitcnt vmcnt(8)" ::: "memory");
;             else if (st == 14) asm volatile("s_waitcnt vmcnt(4)" ::: "memory");
;             else asm volatile("s_waitcnt vmcnt(0)" ::: "memory");
;             if (q == 0) {
; #pragma unroll
;                 for (int r = 0; r < 4; ++r) { accH[r] = 0; accL[r] = 0; } }
; #pragma unroll
;             for (int tp = 0; tp < 2; ++tp) {
;                 const v2i ao = TR4(ATL + (2 * q + tp) * 128 + 8 * s16), ah = TR4(ATL + 1024 + (2 * q + tp) * 128 + 8 * s16);
; #pragma unroll
;                 for (int r = 0; r < 4; ++r) {
;                     const v2i d = TR4(ldsb + BUF[st % 3] + 2048 * tp + roff[r]);
;                     accH[r] = __builtin_amdgcn_sdot8(d.x, ah.x, accH[r], false); accH[r] = __builtin_amdgcn_sdot8(d.y, ah.y, accH[r], false);
;                     accL[r] = __builtin_amdgcn_sdot8(d.x, ao.x, accL[r], false); accL[r] = __builtin_amdgcn_sdot8(d.y, ao.y, accL[r], false);
;                 }
;             }
	v_add_u32_e32 v54, s79, v59
	v_add_u32_e32 v55, s79, v60
	v_add_u32_e32 v56, s79, v61
	v_add_u32_e32 v57, s79, v62
	ds_read_b64_tr_b4 v[50:51], v160 offset:128
	ds_read_b64_tr_b4 v[52:53], v160 offset:1152
	ds_read_b64_tr_b4 v[130:131], v54
	ds_read_b64_tr_b4 v[132:133], v55
	ds_read_b64_tr_b4 v[134:135], v56
	ds_read_b64_tr_b4 v[136:137], v57
	s_waitcnt lgkmcnt(14)
	v_dot8c_i32_i4_e32 v38, v122, v48
	v_dot8c_i32_i4_e32 v39, v122, v46
	v_dot8c_i32_i4_e32 v40, v124, v48
	v_dot8c_i32_i4_e32 v41, v124, v46
	v_dot8c_i32_i4_e32 v42, v126, v48
	v_dot8c_i32_i4_e32 v43, v126, v46
	v_dot8c_i32_i4_e32 v44, v128, v48
	v_dot8c_i32_i4_e32 v45, v128, v46
	v_dot8c_i32_i4_e32 v38, v123, v49
	v_dot8c_i32_i4_e32 v39, v123, v47
	v_dot8c_i32_i4_e32 v40, v125, v49
	v_dot8c_i32_i4_e32 v41, v125, v47
	v_dot8c_i32_i4_e32 v42, v127, v49
	v_dot8c_i32_i4_e32 v43, v127, v47
	v_dot8c_i32_i4_e32 v44, v129, v49
	v_dot8c_i32_i4_e32 v45, v129, v47
	v_and_b32_e32 v78, 0xffff, v32
	v_lshrrev_b32_e32 v79, 16, v32
	v_lshl_add_u32 v78, v78, 7, v150
	v_lshl_add_u32 v79, v79, 7, v151
	s_mov_b32 m0, s78
	s_add_i32 s43, s78, 0x400
	global_load_lds_dwordx4 v78, s[50:51]
	s_mov_b32 m0, s43
	s_nop 0
	global_load_lds_dwordx4 v79, s[50:51]
	s_waitcnt vmcnt(10)
	v_add_u32_e32 v54, s98, v59
	v_add_u32_e32 v55, s98, v60
	v_add_u32_e32 v56, s98, v61
	v_add_u32_e32 v57, s98, v62
	ds_read_b64_tr_b4 v[46:47], v160 offset:256
	ds_read_b64_tr_b4 v[48:49], v160 offset:1280
	ds_read_b64_tr_b4 v[122:123], v54
	ds_read_b64_tr_b4 v[124:125], v55
	ds_read_b64_tr_b4 v[126:127], v56
	ds_read_b64_tr_b4 v[128:129], v57
	s_waitcnt lgkmcnt(6)
	v_dot8c_i32_i4_e32 v38, v130, v52
	v_dot8c_i32_i4_e32 v39, v130, v50
	v_dot8c_i32_i4_e32 v40, v132, v52
	v_dot8c_i32_i4_e32 v41, v132, v50
	v_dot8c_i32_i4_e32 v42, v134, v52
	v_dot8c_i32_i4_e32 v43, v134, v50
	v_dot8c_i32_i4_e32 v44, v136, v52
	v_dot8c_i32_i4_e32 v45, v136, v50
	v_dot8c_i32_i4_e32 v38, v131, v53
	v_dot8c_i32_i4_e32 v39, v131, v51
	v_dot8c_i32_i4_e32 v40, v133, v53
	v_dot8c_i32_i4_e32 v41, v133, v51
	v_dot8c_i32_i4_e32 v42, v135, v53
	v_dot8c_i32_i4_e32 v43, v135, v51
	v_dot8c_i32_i4_e32 v44, v137, v53
	v_dot8c_i32_i4_e32 v45, v137, v51
	v_and_b32_e32 v78, 0xffff, v33
	v_lshrrev_b32_e32 v79, 16, v33
	v_lshl_add_u32 v78, v78, 7, v150
	v_lshl_add_u32 v79, v79, 7, v151
	s_mov_b32 m0, s79
	s_add_i32 s43, s79, 0x400
	global_load_lds_dwordx4 v78, s[50:51]
	s_mov_b32 m0, s43
	s_nop 0
	global_load_lds_dwordx4 v79, s[50:51]
	s_waitcnt vmcnt(10)
	v_add_u32_e32 v54, s99, v59
	v_add_u32_e32 v55, s99, v60
	v_add_u32_e32 v56, s99, v61
	v_add_u32_e32 v57, s99, v62
	ds_read_b64_tr_b4 v[50:51], v160 offset:384
	ds_read_b64_tr_b4 v[52:53], v160 offset:1408
	ds_read_b64_tr_b4 v[130:131], v54
	ds_read_b64_tr_b4 v[132:133], v55
	ds_read_b64_tr_b4 v[134:135], v56
	ds_read_b64_tr_b4 v[136:137], v57
	s_waitcnt lgkmcnt(6)
	v_dot8c_i32_i4_e32 v38, v122, v48
	v_dot8c_i32_i4_e32 v39, v122, v46
	v_dot8c_i32_i4_e32 v40, v124, v48
	v_dot8c_i32_i4_e32 v41, v124, v46
	v_dot8c_i32_i4_e32 v42, v126, v48
	v_dot8c_i32_i4_e32 v43, v126, v46
	v_dot8c_i32_i4_e32 v44, v128, v48
	v_dot8c_i32_i4_e32 v45, v128, v46
	v_dot8c_i32_i4_e32 v38, v123, v49
	v_dot8c_i32_i4_e32 v39, v123, v47
	v_dot8c_i32_i4_e32 v40, v125, v49
	v_dot8c_i32_i4_e32 v41, v125, v47
	v_dot8c_i32_i4_e32 v42, v127, v49
	v_dot8c_i32_i4_e32 v43, v127, v47
	v_dot8c_i32_i4_e32 v44, v129, v49
	v_dot8c_i32_i4_e32 v45, v129, v47
	s_waitcnt lgkmcnt(15)
	v_and_b32_e32 v78, 0xffff, v18
	v_lshrrev_b32_e32 v79, 16, v18
	v_lshl_add_u32 v78, v78, 7, v150
	v_lshl_add_u32 v79, v79, 7, v151
	s_mov_b32 m0, s98
	s_add_i32 s43, s98, 0x400
	global_load_lds_dwordx4 v78, s[50:51]
	s_mov_b32 m0, s43
	s_nop 0
	global_load_lds_dwordx4 v79, s[50:51]
	s_waitcnt vmcnt(10)
	v_add_u32_e32 v54, s76, v59
	v_add_u32_e32 v55, s76, v60
	v_add_u32_e32 v56, s76, v61
	v_add_u32_e32 v57, s76, v62
	ds_read_b64_tr_b4 v[46:47], v160 offset:512
	ds_read_b64_tr_b4 v[48:49], v160 offset:1536
	ds_read_b64_tr_b4 v[122:123], v54
	ds_read_b64_tr_b4 v[124:125], v55
	ds_read_b64_tr_b4 v[126:127], v56
	ds_read_b64_tr_b4 v[128:129], v57
	s_waitcnt lgkmcnt(6)
	v_dot8c_i32_i4_e32 v38, v130, v52
	v_dot8c_i32_i4_e32 v39, v130, v50
	v_dot8c_i32_i4_e32 v40, v132, v52
	v_dot8c_i32_i4_e32 v41, v132, v50
	v_dot8c_i32_i4_e32 v42, v134, v52
	v_dot8c_i32_i4_e32 v43, v134, v50
	v_dot8c_i32_i4_e32 v44, v136, v52
	v_dot8c_i32_i4_e32 v45, v136, v50
	v_dot8c_i32_i4_e32 v38, v131, v53
	v_dot8c_i32_i4_e32 v39, v131, v51
	v_dot8c_i32_i4_e32 v40, v133, v53
	v_dot8c_i32_i4_e32 v41, v133, v51
	v_dot8c_i32_i4_e32 v42, v135, v53
	v_dot8c_i32_i4_e32 v43, v135, v51
	v_dot8c_i32_i4_e32 v44, v137, v53
	v_dot8c_i32_i4_e32 v45, v137, v51
	v_and_b32_e32 v78, 0xffff, v19
	v_lshrrev_b32_e32 v79, 16, v19
	v_lshl_add_u32 v78, v78, 7, v150
	v_lshl_add_u32 v79, v79, 7, v151
	s_mov_b32 m0, s99
	s_add_i32 s43, s99, 0x400
	global_load_lds_dwordx4 v78, s[50:51]
	s_mov_b32 m0, s43
	s_nop 0
	global_load_lds_dwordx4 v79, s[50:51]
	s_waitcnt vmcnt(8)
	v_add_u32_e32 v54, s77, v59
	v_add_u32_e32 v55, s77, v60
	v_add_u32_e32 v56, s77, v61
	v_add_u32_e32 v57, s77, v62
	ds_read_b64_tr_b4 v[50:51], v160 offset:640
	ds_read_b64_tr_b4 v[52:53], v160 offset:1664
	ds_read_b64_tr_b4 v[130:131], v54
	ds_read_b64_tr_b4 v[132:133], v55
	ds_read_b64_tr_b4 v[134:135], v56
	ds_read_b64_tr_b4 v[136:137], v57
	s_waitcnt lgkmcnt(6)
	v_dot8c_i32_i4_e32 v38, v122, v48
	v_dot8c_i32_i4_e32 v39, v122, v46
	v_dot8c_i32_i4_e32 v40, v124, v48
	v_dot8c_i32_i4_e32 v41, v124, v46
	v_dot8c_i32_i4_e32 v42, v126, v48
	v_dot8c_i32_i4_e32 v43, v126, v46
	v_dot8c_i32_i4_e32 v44, v128, v48
	v_dot8c_i32_i4_e32 v45, v128, v46
	v_dot8c_i32_i4_e32 v38, v123, v49
	v_dot8c_i32_i4_e32 v39, v123, v47
	v_dot8c_i32_i4_e32 v40, v125, v49
	v_dot8c_i32_i4_e32 v41, v125, v47
	v_dot8c_i32_i4_e32 v42, v127, v49
	v_dot8c_i32_i4_e32 v43, v127, v47
	v_dot8c_i32_i4_e32 v44, v129, v49
	v_dot8c_i32_i4_e32 v45, v129, v47
	s_waitcnt lgkmcnt(15)
; __device__ __forceinline__ void peer_v_tokens(int j, const LAS unsigned short* EL, const LAS unsigned char* AL  , const LAS float* ASC  , const LAS int* SAL  , ...
;     ...
;         for (int m = 0; m < 2; ++m) {
;             const int idx = lane + 64 * m, tau = idx >> 4, sr = idx & 15, k = 16 * (sr & 7) + 2 * tau + (sr >> 3);
;             const int aq = (int)*(const LAS signed char*)(AL + tl * 128 + k); const int tq = aq + 8;
;             const unsigned lo = (((unsigned)tq & 15u) ^ 8u) * 0x11111111u, hi = ((unsigned)(tq >> 4) & 15u) * 0x11111111u;
;             typedef unsigned u2v __attribute__((ext_vector_type(2)));
;             u2v l2; l2.x = lo; l2.y = lo; u2v h2; h2.x = hi; h2.y = hi;
;             *(LAS u2v*)(ATL + 8 * idx) = l2; *(LAS u2v*)(ATL + 1024 + 8 * idx) = h2;
;         }
;         const float asc = ASC[tl]; const int sa = SAL[tl];
;         CFENCE();
;         int accH[4], accL[4];
; #pragma unroll
;         for (int st = 0; st < 16; ++st) {
;             const int p = st >> 2, q = st & 3;
;             if (st < 14) VDMA(st + 2, (st + 2) % 3);
;             if (st < 14) asm volatile("s_waitcnt vmcnt(8)" ::: "memory");
;             else if (st == 14) asm volatile("s_waitcnt vmcnt(4)" ::: "memory");
;             else asm volatile("s_waitcnt vmcnt(0)" ::: "memory");
;             if (q == 0) {
; #pragma unroll
;                 for (int r = 0; r < 4; ++r) { accH[r] = 0; accL[r] = 0; } }
; #pragma unroll
;             for (int tp = 0; tp < 2; ++tp) {
;                 const v2i ao = TR4(ATL + (2 * q + tp) * 128 + 8 * s16), ah = TR4(ATL + 1024 + (2 * q + tp) * 128 + 8 * s16);
; #pragma unroll
;                 for (int r = 0; r < 4; ++r) {
;                     const v2i d = TR4(ldsb + BUF[st % 3] + 2048 * tp + roff[r]);
;                     accH[r] = __builtin_amdgcn_sdot8(d.x, ah.x, accH[r], false); accH[r] = __builtin_amdgcn_sdot8(d.y, ah.y, accH[r], false);
;                     accL[r] = __builtin_amdgcn_sdot8(d.x, ao.x, accL[r], false); accL[r] = __builtin_amdgcn_sdot8(d.y, ao.y, accL[r], false);
;                 }
;             }
;             asm volatile("s_waitcnt lgkmcnt(0)" ::: "memory");
;             if (q == 3) {
; #pragma unroll
;                 for (int r = 0; r < 4; ++r) STASH[256 * p + 16 * (grp + 4 * r) + pc] = f2bf(asc * (float)(2 * ((accH[r] << 4) + accL[r]) + sa));
;             }
;         }
;         CFENCE();
	v_add_u32_e32 v143, 8, v139
	v_and_b32_e32 v142, 15, v143
	v_xor_b32_e32 v142, 8, v142
	v_bfe_u32 v144, v143, 4, 4
	v_mul_lo_u32 v142, v142, s92
	v_mul_lo_u32 v144, v144, s92
	v_mov_b32_e32 v143, v142
	v_mov_b32_e32 v145, v144
	ds_write2st64_b64 v159, v[142:143], v[144:145] offset1:2
	v_and_b32_e32 v78, 0xffff, v20
	v_lshrrev_b32_e32 v79, 16, v20
	v_lshl_add_u32 v78, v78, 7, v150
	v_lshl_add_u32 v79, v79, 7, v151
	s_mov_b32 m0, s76
	s_add_i32 s43, s76, 0x400
	global_load_lds_dwordx4 v78, s[50:51]
	s_mov_b32 m0, s43
	s_nop 0
	global_load_lds_dwordx4 v79, s[50:51]
	s_waitcnt vmcnt(8)
	v_add_u32_e32 v54, s78, v59
	v_add_u32_e32 v55, s78, v60
	v_add_u32_e32 v56, s78, v61
	v_add_u32_e32 v57, s78, v62
	ds_read_b64_tr_b4 v[46:47], v160 offset:768
	ds_read_b64_tr_b4 v[48:49], v160 offset:1792
	ds_read_b64_tr_b4 v[122:123], v54
	ds_read_b64_tr_b4 v[124:125], v55
	ds_read_b64_tr_b4 v[126:127], v56
	ds_read_b64_tr_b4 v[128:129], v57
	s_waitcnt lgkmcnt(7)
	v_dot8c_i32_i4_e32 v38, v130, v52
	v_dot8c_i32_i4_e32 v39, v130, v50
	v_dot8c_i32_i4_e32 v40, v132, v52
	v_dot8c_i32_i4_e32 v41, v132, v50
	v_dot8c_i32_i4_e32 v42, v134, v52
	v_dot8c_i32_i4_e32 v43, v134, v50
	v_dot8c_i32_i4_e32 v44, v136, v52
	v_dot8c_i32_i4_e32 v45, v136, v50
	v_dot8c_i32_i4_e32 v38, v131, v53
	v_dot8c_i32_i4_e32 v39, v131, v51
	v_dot8c_i32_i4_e32 v40, v133, v53
	v_dot8c_i32_i4_e32 v41, v133, v51
	v_dot8c_i32_i4_e32 v42, v135, v53
	v_dot8c_i32_i4_e32 v43, v135, v51
	v_dot8c_i32_i4_e32 v44, v137, v53
	v_dot8c_i32_i4_e32 v45, v137, v51
	v_and_b32_e32 v78, 0xffff, v21
	v_lshrrev_b32_e32 v79, 16, v21
	v_lshl_add_u32 v78, v78, 7, v150
	v_lshl_add_u32 v79, v79, 7, v151
	s_mov_b32 m0, s77
	s_add_i32 s43, s77, 0x400
	global_load_lds_dwordx4 v78, s[50:51]
	s_mov_b32 m0, s43
	s_nop 0
	global_load_lds_dwordx4 v79, s[50:51]
	s_waitcnt vmcnt(8)
	v_add_u32_e32 v54, s79, v59
	v_add_u32_e32 v55, s79, v60
	v_add_u32_e32 v56, s79, v61
	v_add_u32_e32 v57, s79, v62
	ds_read_b64_tr_b4 v[50:51], v160 offset:896
	ds_read_b64_tr_b4 v[52:53], v160 offset:1920
	ds_read_b64_tr_b4 v[130:131], v54
	ds_read_b64_tr_b4 v[132:133], v55
	ds_read_b64_tr_b4 v[134:135], v56
	ds_read_b64_tr_b4 v[136:137], v57
	s_waitcnt lgkmcnt(6)
	v_dot8c_i32_i4_e32 v38, v122, v48
	v_dot8c_i32_i4_e32 v39, v122, v46
	v_dot8c_i32_i4_e32 v40, v124, v48
	v_dot8c_i32_i4_e32 v41, v124, v46
	v_dot8c_i32_i4_e32 v42, v126, v48
	v_dot8c_i32_i4_e32 v43, v126, v46
	v_dot8c_i32_i4_e32 v44, v128, v48
	v_dot8c_i32_i4_e32 v45, v128, v46
	v_dot8c_i32_i4_e32 v38, v123, v49
	v_dot8c_i32_i4_e32 v39, v123, v47
	v_dot8c_i32_i4_e32 v40, v125, v49
	v_dot8c_i32_i4_e32 v41, v125, v47
	v_dot8c_i32_i4_e32 v42, v127, v49
	v_dot8c_i32_i4_e32 v43, v127, v47
	v_dot8c_i32_i4_e32 v44, v129, v49
	v_dot8c_i32_i4_e32 v45, v129, v47
	v_and_b32_e32 v78, 0xffff, v22
	v_lshrrev_b32_e32 v79, 16, v22
	v_lshl_add_u32 v78, v78, 7, v150
	v_lshl_add_u32 v79, v79, 7, v151
	s_mov_b32 m0, s78
	s_add_i32 s43, s78, 0x400
	global_load_lds_dwordx4 v78, s[50:51]
	s_mov_b32 m0, s43
	s_nop 0
	global_load_lds_dwordx4 v79, s[50:51]
	s_waitcnt vmcnt(8)
	v_add_u32_e32 v54, s98, v59
	v_add_u32_e32 v55, s98, v60
	v_add_u32_e32 v56, s98, v61
	v_add_u32_e32 v57, s98, v62
	ds_read_b64_tr_b4 v[46:47], v160
	ds_read_b64_tr_b4 v[48:49], v160 offset:1024
	ds_read_b64_tr_b4 v[122:123], v54
	ds_read_b64_tr_b4 v[124:125], v55
	ds_read_b64_tr_b4 v[126:127], v56
	ds_read_b64_tr_b4 v[128:129], v57
	s_waitcnt lgkmcnt(6)
	v_dot8c_i32_i4_e32 v38, v130, v52
	v_dot8c_i32_i4_e32 v39, v130, v50
	v_dot8c_i32_i4_e32 v40, v132, v52
	v_dot8c_i32_i4_e32 v41, v132, v50
	v_dot8c_i32_i4_e32 v42, v134, v52
	v_dot8c_i32_i4_e32 v43, v134, v50
	v_dot8c_i32_i4_e32 v44, v136, v52
	v_dot8c_i32_i4_e32 v45, v136, v50
	v_dot8c_i32_i4_e32 v38, v131, v53
	v_dot8c_i32_i4_e32 v39, v131, v51
	v_dot8c_i32_i4_e32 v40, v133, v53
	v_dot8c_i32_i4_e32 v41, v133, v51
	v_dot8c_i32_i4_e32 v42, v135, v53
	v_dot8c_i32_i4_e32 v43, v135, v51
	v_dot8c_i32_i4_e32 v44, v137, v53
	v_dot8c_i32_i4_e32 v45, v137, v51
	s_nop 3
	s_waitcnt lgkmcnt(15)
	v_lshlrev_b32_e32 v38, 5, v38
	v_lshlrev_b32_e32 v39, 1, v39
	v_add3_u32 v38, v39, v229, v38
	v_cvt_f32_i32_e32 v38, v38
	v_mul_f32_e32 v38, v228, v38
	v_lshlrev_b32_e32 v40, 5, v40
	v_lshlrev_b32_e32 v41, 1, v41
	v_add3_u32 v40, v41, v229, v40
	v_cvt_f32_i32_e32 v40, v40
	v_mul_f32_e32 v40, v228, v40
	v_lshlrev_b32_e32 v42, 5, v42
	v_lshlrev_b32_e32 v43, 1, v43
	v_add3_u32 v42, v43, v229, v42
	v_cvt_f32_i32_e32 v42, v42
	v_mul_f32_e32 v42, v228, v42
	v_lshlrev_b32_e32 v44, 5, v44
	v_lshlrev_b32_e32 v45, 1, v45
	v_add3_u32 v44, v45, v229, v44
	v_cvt_f32_i32_e32 v44, v44
	v_mul_f32_e32 v44, v228, v44
	v_cvt_pk_bf16_f32 v248, v38, v40
	v_cvt_pk_bf16_f32 v249, v42, v44
	ds_read_b128 v[252:255], v156
	s_add_i32 s44, s40, 24
	s_ashr_i32 s45, s44, 31
	s_lshl_b64 s[44:45], s[44:45], 12
	v_lshl_add_u64 v[80:81], v[36:37], 0, s[44:45]
	s_waitcnt lgkmcnt(0)
	v_mul_f32_e32 v218, v218, v252
	v_mul_f32_e32 v219, v219, v253
	v_mul_f32_e32 v220, v220, v254
	v_mul_f32_e32 v221, v221, v255
	global_store_dwordx4 v[80:81], v[218:221], off offset:2048 nt
	ds_read_b128 v[252:255], v156 offset:1024
	s_add_i32 s44, s40, 24
	s_ashr_i32 s45, s44, 31
	s_lshl_b64 s[44:45], s[44:45], 12
	v_lshl_add_u64 v[80:81], v[36:37], 0, s[44:45]
	s_waitcnt lgkmcnt(0)
; __device__ __forceinline__ void peer_v_tokens(int j, const LAS unsigned short* EL, const LAS unsigned char* AL  , const LAS float* ASC  , const LAS int* SAL  , ...
;     ...
;         for (int m = 0; m < 2; ++m) {
;             const int idx = lane + 64 * m, tau = idx >> 4, sr = idx & 15, k = 16 * (sr & 7) + 2 * tau + (sr >> 3);
;             const int aq = (int)*(const LAS signed char*)(AL + tl * 128 + k); const int tq = aq + 8;
;             const unsigned lo = (((unsigned)tq & 15u) ^ 8u) * 0x11111111u, hi = ((unsigned)(tq >> 4) & 15u) * 0x11111111u;
;             typedef unsigned u2v __attribute__((ext_vector_type(2)));
;             u2v l2; l2.x = lo; l2.y = lo; u2v h2; h2.x = hi; h2.y = hi;
;             *(LAS u2v*)(ATL + 8 * idx) = l2; *(LAS u2v*)(ATL + 1024 + 8 * idx) = h2;
;         }
;         const float asc = ASC[tl]; const int sa = SAL[tl];
;         CFENCE();
;         int accH[4], accL[4];
; #pragma unroll
;         for (int st = 0; st < 16; ++st) {
;             const int p = st >> 2, q = st & 3;
;             if (st < 14) VDMA(st + 2, (st + 2) % 3);
;             if (st < 14) asm volatile("s_waitcnt vmcnt(8)" ::: "memory");
;             else if (st == 14) asm volatile("s_waitcnt vmcnt(4)" ::: "memory");
;             else asm volatile("s_waitcnt vmcnt(0)" ::: "memory");
;             if (q == 0) {
; #pragma unroll
;                 for (int r = 0; r < 4; ++r) { accH[r] = 0; accL[r] = 0; } }
; #pragma unroll
;             for (int tp = 0; tp < 2; ++tp) {
;                 const v2i ao = TR4(ATL + (2 * q + tp) * 128 + 8 * s16), ah = TR4(ATL + 1024 + (2 * q + tp) * 128 + 8 * s16);
; #pragma unroll
;                 for (int r = 0; r < 4; ++r) {
;                     const v2i d = TR4(ldsb + BUF[st % 3] + 2048 * tp + roff[r]);
;                     accH[r] = __builtin_amdgcn_sdot8(d.x, ah.x, accH[r], false); accH[r] = __builtin_amdgcn_sdot8(d.y, ah.y, accH[r], false);
;                     accL[r] = __builtin_amdgcn_sdot8(d.x, ao.x, accL[r], false); accL[r] = __builtin_amdgcn_sdot8(d.y, ao.y, accL[r], false);
;                 }
;             }
;             asm volatile("s_waitcnt lgkmcnt(0)" ::: "memory");
;             if (q == 3) {
; #pragma unroll
;                 for (int r = 0; r < 4; ++r) STASH[256 * p + 16 * (grp + 4 * r) + pc] = f2bf(asc * (float)(2 * ((accH[r] << 4) + accL[r]) + sa));
;             }
;         }
;         CFENCE();
	v_mul_f32_e32 v222, v222, v252
	v_mul_f32_e32 v223, v223, v253
	v_mul_f32_e32 v224, v224, v254
	v_mul_f32_e32 v225, v225, v255
	global_store_dwordx4 v[80:81], v[222:225], off offset:3072 nt
	v_add_u32_e32 v147, 8, v140
	v_and_b32_e32 v146, 15, v147
	v_xor_b32_e32 v146, 8, v146
	v_bfe_u32 v148, v147, 4, 4
	v_mul_lo_u32 v146, v146, s92
	v_mul_lo_u32 v148, v148, s92
	v_mov_b32_e32 v147, v146
	v_mov_b32_e32 v149, v148
	ds_write2st64_b64 v77, v[146:147], v[148:149] offset1:2
	v_add_u32_e32 v138, 0x1c00, v74
	ds_read_u8 v139, v138
	v_add_u32_e32 v141, 0x1c00, v73
	ds_read_u8 v140, v141
	s_add_i32 s43, s67, 192
	v_mov_b32_e32 v138, s43
	ds_read2st64_b32 v[228:229], v138 offset1:1
	ds_read_b128 v[26:29], v227 offset:14336
	ds_read_b128 v[30:33], v227 offset:14352
	v_mov_b32_e32 v38, 0
	v_mov_b32_e32 v39, 0
	v_mov_b32_e32 v40, 0
	v_mov_b32_e32 v41, 0
	v_mov_b32_e32 v42, 0
	v_mov_b32_e32 v43, 0
	v_mov_b32_e32 v44, 0
	v_mov_b32_e32 v45, 0
	v_and_b32_e32 v78, 0xffff, v23
	v_lshrrev_b32_e32 v79, 16, v23
	v_lshl_add_u32 v78, v78, 7, v150
	v_lshl_add_u32 v79, v79, 7, v151
	s_mov_b32 m0, s79
	s_add_i32 s43, s79, 0x400
	global_load_lds_dwordx4 v78, s[50:51]
	s_mov_b32 m0, s43
	s_nop 0
	global_load_lds_dwordx4 v79, s[50:51]
	s_waitcnt vmcnt(10)
	v_add_u32_e32 v54, s99, v59
	v_add_u32_e32 v55, s99, v60
	v_add_u32_e32 v56, s99, v61
	v_add_u32_e32 v57, s99, v62
	ds_read_b64_tr_b4 v[50:51], v160 offset:128
	ds_read_b64_tr_b4 v[52:53], v160 offset:1152
	ds_read_b64_tr_b4 v[130:131], v54
	ds_read_b64_tr_b4 v[132:133], v55
	ds_read_b64_tr_b4 v[134:135], v56
	ds_read_b64_tr_b4 v[136:137], v57
	s_waitcnt lgkmcnt(14)
	v_dot8c_i32_i4_e32 v38, v122, v48
	v_dot8c_i32_i4_e32 v39, v122, v46
	v_dot8c_i32_i4_e32 v40, v124, v48
	v_dot8c_i32_i4_e32 v41, v124, v46
	v_dot8c_i32_i4_e32 v42, v126, v48
	v_dot8c_i32_i4_e32 v43, v126, v46
	v_dot8c_i32_i4_e32 v44, v128, v48
	v_dot8c_i32_i4_e32 v45, v128, v46
	v_dot8c_i32_i4_e32 v38, v123, v49
	v_dot8c_i32_i4_e32 v39, v123, v47
	v_dot8c_i32_i4_e32 v40, v125, v49
	v_dot8c_i32_i4_e32 v41, v125, v47
	v_dot8c_i32_i4_e32 v42, v127, v49
	v_dot8c_i32_i4_e32 v43, v127, v47
	v_dot8c_i32_i4_e32 v44, v129, v49
	v_dot8c_i32_i4_e32 v45, v129, v47
	v_and_b32_e32 v78, 0xffff, v24
	v_lshrrev_b32_e32 v79, 16, v24
	v_lshl_add_u32 v78, v78, 7, v150
	v_lshl_add_u32 v79, v79, 7, v151
	s_mov_b32 m0, s98
	s_add_i32 s43, s98, 0x400
	global_load_lds_dwordx4 v78, s[50:51]
	s_mov_b32 m0, s43
	s_nop 0
	global_load_lds_dwordx4 v79, s[50:51]
	s_waitcnt vmcnt(10)
	v_add_u32_e32 v54, s76, v59
	v_add_u32_e32 v55, s76, v60
	v_add_u32_e32 v56, s76, v61
	v_add_u32_e32 v57, s76, v62
	ds_read_b64_tr_b4 v[46:47], v160 offset:256
	ds_read_b64_tr_b4 v[48:49], v160 offset:1280
	ds_read_b64_tr_b4 v[122:123], v54
	ds_read_b64_tr_b4 v[124:125], v55
	ds_read_b64_tr_b4 v[126:127], v56
	ds_read_b64_tr_b4 v[128:129], v57
	s_waitcnt lgkmcnt(6)
	v_dot8c_i32_i4_e32 v38, v130, v52
	v_dot8c_i32_i4_e32 v39, v130, v50
	v_dot8c_i32_i4_e32 v40, v132, v52
	v_dot8c_i32_i4_e32 v41, v132, v50
	v_dot8c_i32_i4_e32 v42, v134, v52
	v_dot8c_i32_i4_e32 v43, v134, v50
	v_dot8c_i32_i4_e32 v44, v136, v52
	v_dot8c_i32_i4_e32 v45, v136, v50
	v_dot8c_i32_i4_e32 v38, v131, v53
	v_dot8c_i32_i4_e32 v39, v131, v51
	v_dot8c_i32_i4_e32 v40, v133, v53
	v_dot8c_i32_i4_e32 v41, v133, v51
	v_dot8c_i32_i4_e32 v42, v135, v53
	v_dot8c_i32_i4_e32 v43, v135, v51
	v_dot8c_i32_i4_e32 v44, v137, v53
	v_dot8c_i32_i4_e32 v45, v137, v51
	v_and_b32_e32 v78, 0xffff, v25
	v_lshrrev_b32_e32 v79, 16, v25
	v_lshl_add_u32 v78, v78, 7, v150
	v_lshl_add_u32 v79, v79, 7, v151
	s_mov_b32 m0, s99
	s_add_i32 s43, s99, 0x400
	global_load_lds_dwordx4 v78, s[50:51]
	s_mov_b32 m0, s43
	s_nop 0
	global_load_lds_dwordx4 v79, s[50:51]
	s_waitcnt vmcnt(10)
	v_add_u32_e32 v54, s77, v59
	v_add_u32_e32 v55, s77, v60
	v_add_u32_e32 v56, s77, v61
	v_add_u32_e32 v57, s77, v62
	ds_read_b64_tr_b4 v[50:51], v160 offset:384
	ds_read_b64_tr_b4 v[52:53], v160 offset:1408
	ds_read_b64_tr_b4 v[130:131], v54
	ds_read_b64_tr_b4 v[132:133], v55
	ds_read_b64_tr_b4 v[134:135], v56
	ds_read_b64_tr_b4 v[136:137], v57
	s_waitcnt lgkmcnt(6)
	v_dot8c_i32_i4_e32 v38, v122, v48
	v_dot8c_i32_i4_e32 v39, v122, v46
	v_dot8c_i32_i4_e32 v40, v124, v48
	v_dot8c_i32_i4_e32 v41, v124, v46
	v_dot8c_i32_i4_e32 v42, v126, v48
	v_dot8c_i32_i4_e32 v43, v126, v46
	v_dot8c_i32_i4_e32 v44, v128, v48
	v_dot8c_i32_i4_e32 v45, v128, v46
	v_dot8c_i32_i4_e32 v38, v123, v49
	v_dot8c_i32_i4_e32 v39, v123, v47
	v_dot8c_i32_i4_e32 v40, v125, v49
	v_dot8c_i32_i4_e32 v41, v125, v47
	v_dot8c_i32_i4_e32 v42, v127, v49
	v_dot8c_i32_i4_e32 v43, v127, v47
	v_dot8c_i32_i4_e32 v44, v129, v49
	v_dot8c_i32_i4_e32 v45, v129, v47
	s_waitcnt lgkmcnt(15)
	v_and_b32_e32 v78, 0xffff, v26
	v_lshrrev_b32_e32 v79, 16, v26
	v_lshl_add_u32 v78, v78, 7, v150
	v_lshl_add_u32 v79, v79, 7, v151
	s_mov_b32 m0, s76
	s_add_i32 s43, s76, 0x400
	global_load_lds_dwordx4 v78, s[50:51]
	s_mov_b32 m0, s43
	s_nop 0
	global_load_lds_dwordx4 v79, s[50:51]
	s_waitcnt vmcnt(10)
	v_add_u32_e32 v54, s78, v59
	v_add_u32_e32 v55, s78, v60
	v_add_u32_e32 v56, s78, v61
	v_add_u32_e32 v57, s78, v62
	ds_read_b64_tr_b4 v[46:47], v160 offset:512
	ds_read_b64_tr_b4 v[48:49], v160 offset:1536
	ds_read_b64_tr_b4 v[122:123], v54
	ds_read_b64_tr_b4 v[124:125], v55
	ds_read_b64_tr_b4 v[126:127], v56
	ds_read_b64_tr_b4 v[128:129], v57
	s_waitcnt lgkmcnt(6)
; #define TR4(p_) __builtin_amdgcn_ds_read_tr4_b64_v2i32((LAS v2i*)(p_))
; #define VDMA(st_, k_) do { _Pragma("unroll") for (int i_ = 0; i_ < 4; ++i_) { \
;         const unsigned off_ = (unsigned)((st_) >> 2) * (16384u * 128u) + (PE_ID(E, 4 * ((st_) & 3) + i_) << 7) + ((i_ & 1) ? cx1 : cx0); \
;         __builtin_amdgcn_global_load_lds((const unsigned*)(V4 + off_), (LAS unsigned*)(ldsb + BUF[k_] + 1024 * i_), 16, 0, 0); } } while (0)
; __device__ __forceinline__ void peer_v_tokens(int j, const LAS unsigned short* EL, const LAS unsigned char* AL  , const LAS float* ASC  , const LAS int* SAL  , ...
;     ...
;         for (int st = 0; st < 16; ++st) {
;             const int p = st >> 2, q = st & 3;
;             if (st < 14) VDMA(st + 2, (st + 2) % 3);
;             if (st < 14) asm volatile("s_waitcnt vmcnt(8)" ::: "memory");
;             else if (st == 14) asm volatile("s_waitcnt vmcnt(4)" ::: "memory");
;             else asm volatile("s_waitcnt vmcnt(0)" ::: "memory");
;             if (q == 0) {
; #pragma unroll
;                 for (int r = 0; r < 4; ++r) { accH[r] = 0; accL[r] = 0; } }
; #pragma unroll
;             for (int tp = 0; tp < 2; ++tp) {
;                 const v2i ao = TR4(ATL + (2 * q + tp) * 128 + 8 * s16), ah = TR4(ATL + 1024 + (2 * q + tp) * 128 + 8 * s16);
; #pragma unroll
;                 for (int r = 0; r < 4; ++r) {
;                     const v2i d = TR4(ldsb + BUF[st % 3] + 2048 * tp + roff[r]);
;                     accH[r] = __builtin_amdgcn_sdot8(d.x, ah.x, accH[r], false); accH[r] = __builtin_amdgcn_sdot8(d.y, ah.y, accH[r], false);
;                     accL[r] = __builtin_amdgcn_sdot8(d.x, ao.x, accL[r], false); accL[r] = __builtin_amdgcn_sdot8(d.y, ao.y, accL[r], false);
;                 }
;             }
	v_dot8c_i32_i4_e32 v38, v130, v52
	v_dot8c_i32_i4_e32 v39, v130, v50
	v_dot8c_i32_i4_e32 v40, v132, v52
	v_dot8c_i32_i4_e32 v41, v132, v50
	v_dot8c_i32_i4_e32 v42, v134, v52
	v_dot8c_i32_i4_e32 v43, v134, v50
	v_dot8c_i32_i4_e32 v44, v136, v52
	v_dot8c_i32_i4_e32 v45, v136, v50
	v_dot8c_i32_i4_e32 v38, v131, v53
	v_dot8c_i32_i4_e32 v39, v131, v51
	v_dot8c_i32_i4_e32 v40, v133, v53
	v_dot8c_i32_i4_e32 v41, v133, v51
	v_dot8c_i32_i4_e32 v42, v135, v53
	v_dot8c_i32_i4_e32 v43, v135, v51
	v_dot8c_i32_i4_e32 v44, v137, v53
	v_dot8c_i32_i4_e32 v45, v137, v51
	v_and_b32_e32 v78, 0xffff, v27
	v_lshrrev_b32_e32 v79, 16, v27
	v_lshl_add_u32 v78, v78, 7, v150
	v_lshl_add_u32 v79, v79, 7, v151
	s_mov_b32 m0, s77
	s_add_i32 s43, s77, 0x400
	global_load_lds_dwordx4 v78, s[50:51]
	s_mov_b32 m0, s43
	s_nop 0
	global_load_lds_dwordx4 v79, s[50:51]
	s_waitcnt vmcnt(8)
	v_add_u32_e32 v54, s79, v59
	v_add_u32_e32 v55, s79, v60
	v_add_u32_e32 v56, s79, v61
	v_add_u32_e32 v57, s79, v62
	ds_read_b64_tr_b4 v[50:51], v160 offset:640
	ds_read_b64_tr_b4 v[52:53], v160 offset:1664
	ds_read_b64_tr_b4 v[130:131], v54
	ds_read_b64_tr_b4 v[132:133], v55
	ds_read_b64_tr_b4 v[134:135], v56
	ds_read_b64_tr_b4 v[136:137], v57
	s_waitcnt lgkmcnt(6)
	v_dot8c_i32_i4_e32 v38, v122, v48
	v_dot8c_i32_i4_e32 v39, v122, v46
	v_dot8c_i32_i4_e32 v40, v124, v48
	v_dot8c_i32_i4_e32 v41, v124, v46
	v_dot8c_i32_i4_e32 v42, v126, v48
	v_dot8c_i32_i4_e32 v43, v126, v46
	v_dot8c_i32_i4_e32 v44, v128, v48
	v_dot8c_i32_i4_e32 v45, v128, v46
	v_dot8c_i32_i4_e32 v38, v123, v49
	v_dot8c_i32_i4_e32 v39, v123, v47
	v_dot8c_i32_i4_e32 v40, v125, v49
	v_dot8c_i32_i4_e32 v41, v125, v47
	v_dot8c_i32_i4_e32 v42, v127, v49
	v_dot8c_i32_i4_e32 v43, v127, v47
	v_dot8c_i32_i4_e32 v44, v129, v49
	v_dot8c_i32_i4_e32 v45, v129, v47
	s_waitcnt lgkmcnt(15)
	v_add_u32_e32 v143, 8, v139
	v_and_b32_e32 v142, 15, v143
	v_xor_b32_e32 v142, 8, v142
	v_bfe_u32 v144, v143, 4, 4
	v_mul_lo_u32 v142, v142, s92
	v_mul_lo_u32 v144, v144, s92
	v_mov_b32_e32 v143, v142
	v_mov_b32_e32 v145, v144
	ds_write2st64_b64 v159, v[142:143], v[144:145] offset1:2
	v_and_b32_e32 v78, 0xffff, v28
	v_lshrrev_b32_e32 v79, 16, v28
	v_lshl_add_u32 v78, v78, 7, v150
	v_lshl_add_u32 v79, v79, 7, v151
	s_mov_b32 m0, s78
	s_add_i32 s43, s78, 0x400
	global_load_lds_dwordx4 v78, s[50:51]
	s_mov_b32 m0, s43
	s_nop 0
	global_load_lds_dwordx4 v79, s[50:51]
	s_waitcnt vmcnt(8)
	v_add_u32_e32 v54, s98, v59
	v_add_u32_e32 v55, s98, v60
	v_add_u32_e32 v56, s98, v61
	v_add_u32_e32 v57, s98, v62
	ds_read_b64_tr_b4 v[46:47], v160 offset:768
	ds_read_b64_tr_b4 v[48:49], v160 offset:1792
	ds_read_b64_tr_b4 v[122:123], v54
	ds_read_b64_tr_b4 v[124:125], v55
	ds_read_b64_tr_b4 v[126:127], v56
	ds_read_b64_tr_b4 v[128:129], v57
	s_waitcnt lgkmcnt(7)
	v_dot8c_i32_i4_e32 v38, v130, v52
	v_dot8c_i32_i4_e32 v39, v130, v50
	v_dot8c_i32_i4_e32 v40, v132, v52
	v_dot8c_i32_i4_e32 v41, v132, v50
	v_dot8c_i32_i4_e32 v42, v134, v52
	v_dot8c_i32_i4_e32 v43, v134, v50
	v_dot8c_i32_i4_e32 v44, v136, v52
	v_dot8c_i32_i4_e32 v45, v136, v50
	v_dot8c_i32_i4_e32 v38, v131, v53
	v_dot8c_i32_i4_e32 v39, v131, v51
	v_dot8c_i32_i4_e32 v40, v133, v53
	v_dot8c_i32_i4_e32 v41, v133, v51
	v_dot8c_i32_i4_e32 v42, v135, v53
	v_dot8c_i32_i4_e32 v43, v135, v51
	v_dot8c_i32_i4_e32 v44, v137, v53
	v_dot8c_i32_i4_e32 v45, v137, v51
	v_and_b32_e32 v78, 0xffff, v29
	v_lshrrev_b32_e32 v79, 16, v29
	v_lshl_add_u32 v78, v78, 7, v150
	v_lshl_add_u32 v79, v79, 7, v151
	s_mov_b32 m0, s79
	s_add_i32 s43, s79, 0x400
	global_load_lds_dwordx4 v78, s[50:51]
	s_mov_b32 m0, s43
	s_nop 0
	global_load_lds_dwordx4 v79, s[50:51]
	s_waitcnt vmcnt(8)
	v_add_u32_e32 v54, s99, v59
	v_add_u32_e32 v55, s99, v60
	v_add_u32_e32 v56, s99, v61
	v_add_u32_e32 v57, s99, v62
	ds_read_b64_tr_b4 v[50:51], v160 offset:896
	ds_read_b64_tr_b4 v[52:53], v160 offset:1920
	ds_read_b64_tr_b4 v[130:131], v54
	ds_read_b64_tr_b4 v[132:133], v55
	ds_read_b64_tr_b4 v[134:135], v56
	ds_read_b64_tr_b4 v[136:137], v57
	s_waitcnt lgkmcnt(6)
	v_dot8c_i32_i4_e32 v38, v122, v48
	v_dot8c_i32_i4_e32 v39, v122, v46
	v_dot8c_i32_i4_e32 v40, v124, v48
	v_dot8c_i32_i4_e32 v41, v124, v46
	v_dot8c_i32_i4_e32 v42, v126, v48
	v_dot8c_i32_i4_e32 v43, v126, v46
	v_dot8c_i32_i4_e32 v44, v128, v48
	v_dot8c_i32_i4_e32 v45, v128, v46
	v_dot8c_i32_i4_e32 v38, v123, v49
	v_dot8c_i32_i4_e32 v39, v123, v47
	v_dot8c_i32_i4_e32 v40, v125, v49
	v_dot8c_i32_i4_e32 v41, v125, v47
	v_dot8c_i32_i4_e32 v42, v127, v49
	v_dot8c_i32_i4_e32 v43, v127, v47
	v_dot8c_i32_i4_e32 v44, v129, v49
	v_dot8c_i32_i4_e32 v45, v129, v47
	v_and_b32_e32 v78, 0xffff, v30
	v_lshrrev_b32_e32 v79, 16, v30
	v_lshl_add_u32 v78, v78, 7, v150
	v_lshl_add_u32 v79, v79, 7, v151
	s_mov_b32 m0, s98
	s_add_i32 s43, s98, 0x400
	global_load_lds_dwordx4 v78, s[50:51]
	s_mov_b32 m0, s43
	s_nop 0
	global_load_lds_dwordx4 v79, s[50:51]
	s_waitcnt vmcnt(8)
	v_add_u32_e32 v54, s76, v59
	v_add_u32_e32 v55, s76, v60
	v_add_u32_e32 v56, s76, v61
	v_add_u32_e32 v57, s76, v62
	ds_read_b64_tr_b4 v[46:47], v160
	ds_read_b64_tr_b4 v[48:49], v160 offset:1024
	ds_read_b64_tr_b4 v[122:123], v54
	ds_read_b64_tr_b4 v[124:125], v55
	ds_read_b64_tr_b4 v[126:127], v56
	ds_read_b64_tr_b4 v[128:129], v57
	s_waitcnt lgkmcnt(6)
	v_dot8c_i32_i4_e32 v38, v130, v52
	v_dot8c_i32_i4_e32 v39, v130, v50
	v_dot8c_i32_i4_e32 v40, v132, v52
	v_dot8c_i32_i4_e32 v41, v132, v50
	v_dot8c_i32_i4_e32 v42, v134, v52
	v_dot8c_i32_i4_e32 v43, v134, v50
	v_dot8c_i32_i4_e32 v44, v136, v52
	v_dot8c_i32_i4_e32 v45, v136, v50
	v_dot8c_i32_i4_e32 v38, v131, v53
	v_dot8c_i32_i4_e32 v39, v131, v51
	v_dot8c_i32_i4_e32 v40, v133, v53
	v_dot8c_i32_i4_e32 v41, v133, v51
	v_dot8c_i32_i4_e32 v42, v135, v53
	v_dot8c_i32_i4_e32 v43, v135, v51
	v_dot8c_i32_i4_e32 v44, v137, v53
	v_dot8c_i32_i4_e32 v45, v137, v51
	s_nop 3
	s_waitcnt lgkmcnt(15)
; #define LAS __attribute__((address_space(3)))
; __device__ __forceinline__ void peer_v_tokens(int j, const LAS unsigned short* EL, const LAS unsigned char* AL  , const LAS float* ASC  , const LAS int* SAL  , ...
;     ...
;         for (int m = 0; m < 2; ++m) {
;             const int idx = lane + 64 * m, tau = idx >> 4, sr = idx & 15, k = 16 * (sr & 7) + 2 * tau + (sr >> 3);
;             const int aq = (int)*(const LAS signed char*)(AL + tl * 128 + k); const int tq = aq + 8;
;             const unsigned lo = (((unsigned)tq & 15u) ^ 8u) * 0x11111111u, hi = ((unsigned)(tq >> 4) & 15u) * 0x11111111u;
;             typedef unsigned u2v __attribute__((ext_vector_type(2)));
;             u2v l2; l2.x = lo; l2.y = lo; u2v h2; h2.x = hi; h2.y = hi;
;             *(LAS u2v*)(ATL + 8 * idx) = l2; *(LAS u2v*)(ATL + 1024 + 8 * idx) = h2;
;         }
;         const float asc = ASC[tl]; const int sa = SAL[tl];
;     ...
;         for (int st = 0; st < 16; ++st) {
;             const int p = st >> 2, q = st & 3;
;             if (st < 14) VDMA(st + 2, (st + 2) % 3);
;             if (st < 14) asm volatile("s_waitcnt vmcnt(8)" ::: "memory");
;             else if (st == 14) asm volatile("s_waitcnt vmcnt(4)" ::: "memory");
;             else asm volatile("s_waitcnt vmcnt(0)" ::: "memory");
;             if (q == 0) {
; #pragma unroll
;                 for (int r = 0; r < 4; ++r) { accH[r] = 0; accL[r] = 0; } }
; #pragma unroll
;             for (int tp = 0; tp < 2; ++tp) {
;                 const v2i ao = TR4(ATL + (2 * q + tp) * 128 + 8 * s16), ah = TR4(ATL + 1024 + (2 * q + tp) * 128 + 8 * s16);
; #pragma unroll
;                 for (int r = 0; r < 4; ++r) {
;                     const v2i d = TR4(ldsb + BUF[st % 3] + 2048 * tp + roff[r]);
;                     accH[r] = __builtin_amdgcn_sdot8(d.x, ah.x, accH[r], false); accH[r] = __builtin_amdgcn_sdot8(d.y, ah.y, accH[r], false);
;                     accL[r] = __builtin_amdgcn_sdot8(d.x, ao.x, accL[r], false); accL[r] = __builtin_amdgcn_sdot8(d.y, ao.y, accL[r], false);
;                 }
;             }
;             asm volatile("s_waitcnt lgkmcnt(0)" ::: "memory");
;             if (q == 3) {
; #pragma unroll
;                 for (int r = 0; r < 4; ++r) STASH[256 * p + 16 * (grp + 4 * r) + pc] = f2bf(asc * (float)(2 * ((accH[r] << 4) + accL[r]) + sa));
;             }
	v_lshlrev_b32_e32 v38, 5, v38
	v_lshlrev_b32_e32 v39, 1, v39
	v_add3_u32 v38, v39, v229, v38
	v_cvt_f32_i32_e32 v38, v38
	v_mul_f32_e32 v38, v228, v38
	v_lshlrev_b32_e32 v40, 5, v40
	v_lshlrev_b32_e32 v41, 1, v41
	v_add3_u32 v40, v41, v229, v40
	v_cvt_f32_i32_e32 v40, v40
	v_mul_f32_e32 v40, v228, v40
	v_lshlrev_b32_e32 v42, 5, v42
	v_lshlrev_b32_e32 v43, 1, v43
	v_add3_u32 v42, v43, v229, v42
	v_cvt_f32_i32_e32 v42, v42
	v_mul_f32_e32 v42, v228, v42
	v_lshlrev_b32_e32 v44, 5, v44
	v_lshlrev_b32_e32 v45, 1, v45
	v_add3_u32 v44, v45, v229, v44
	v_cvt_f32_i32_e32 v44, v44
	v_mul_f32_e32 v44, v228, v44
	v_cvt_pk_bf16_f32 v71, v38, v40
	v_cvt_pk_bf16_f32 v72, v42, v44
	v_add_u32_e32 v147, 8, v140
	v_and_b32_e32 v146, 15, v147
	v_xor_b32_e32 v146, 8, v146
	v_bfe_u32 v148, v147, 4, 4
	v_mul_lo_u32 v146, v146, s92
	v_mul_lo_u32 v148, v148, s92
	v_mov_b32_e32 v147, v146
	v_mov_b32_e32 v149, v148
	ds_write2st64_b64 v77, v[146:147], v[148:149] offset1:2
	v_add_u32_e32 v138, 0x1000, v74
	ds_read_u8 v139, v138
	v_add_u32_e32 v141, 0x1000, v73
	ds_read_u8 v140, v141
	s_add_i32 s43, s67, 224
	v_mov_b32_e32 v138, s43
	ds_read2st64_b32 v[228:229], v138 offset1:1
	ds_read_b128 v[18:21], v227 offset:8192
	ds_read_b128 v[22:25], v227 offset:8208
	v_add_u32_e32 v152, 0x600000, v63
	v_add_u32_e32 v153, 0x600000, v64
	v_mov_b32_e32 v38, 0
	v_mov_b32_e32 v39, 0
	v_mov_b32_e32 v40, 0
	v_mov_b32_e32 v41, 0
	v_mov_b32_e32 v42, 0
	v_mov_b32_e32 v43, 0
	v_mov_b32_e32 v44, 0
	v_mov_b32_e32 v45, 0
	v_and_b32_e32 v78, 0xffff, v31
	v_lshrrev_b32_e32 v79, 16, v31
	v_lshl_add_u32 v78, v78, 7, v150
	v_lshl_add_u32 v79, v79, 7, v151
	s_mov_b32 m0, s99
	s_add_i32 s43, s99, 0x400
	global_load_lds_dwordx4 v78, s[50:51]
	s_mov_b32 m0, s43
	s_nop 0
	global_load_lds_dwordx4 v79, s[50:51]
	s_waitcnt vmcnt(8)
	v_add_u32_e32 v54, s77, v59
	v_add_u32_e32 v55, s77, v60
	v_add_u32_e32 v56, s77, v61
	v_add_u32_e32 v57, s77, v62
	ds_read_b64_tr_b4 v[50:51], v160 offset:128
	ds_read_b64_tr_b4 v[52:53], v160 offset:1152
	ds_read_b64_tr_b4 v[130:131], v54
	ds_read_b64_tr_b4 v[132:133], v55
	ds_read_b64_tr_b4 v[134:135], v56
	ds_read_b64_tr_b4 v[136:137], v57
	s_waitcnt lgkmcnt(12)
	v_dot8c_i32_i4_e32 v38, v122, v48
	v_dot8c_i32_i4_e32 v39, v122, v46
	v_dot8c_i32_i4_e32 v40, v124, v48
	v_dot8c_i32_i4_e32 v41, v124, v46
	v_dot8c_i32_i4_e32 v42, v126, v48
	v_dot8c_i32_i4_e32 v43, v126, v46
	v_dot8c_i32_i4_e32 v44, v128, v48
	v_dot8c_i32_i4_e32 v45, v128, v46
	v_dot8c_i32_i4_e32 v38, v123, v49
	v_dot8c_i32_i4_e32 v39, v123, v47
	v_dot8c_i32_i4_e32 v40, v125, v49
	v_dot8c_i32_i4_e32 v41, v125, v47
	v_dot8c_i32_i4_e32 v42, v127, v49
	v_dot8c_i32_i4_e32 v43, v127, v47
	v_dot8c_i32_i4_e32 v44, v129, v49
	v_dot8c_i32_i4_e32 v45, v129, v47
	v_and_b32_e32 v78, 0xffff, v32
	v_lshrrev_b32_e32 v79, 16, v32
	v_lshl_add_u32 v78, v78, 7, v150
	v_lshl_add_u32 v79, v79, 7, v151
	s_mov_b32 m0, s76
	s_add_i32 s43, s76, 0x400
	global_load_lds_dwordx4 v78, s[50:51]
	s_mov_b32 m0, s43
	s_nop 0
	global_load_lds_dwordx4 v79, s[50:51]
	s_waitcnt vmcnt(8)
	v_add_u32_e32 v54, s78, v59
	v_add_u32_e32 v55, s78, v60
	v_add_u32_e32 v56, s78, v61
	v_add_u32_e32 v57, s78, v62
	ds_read_b64_tr_b4 v[46:47], v160 offset:256
	ds_read_b64_tr_b4 v[48:49], v160 offset:1280
	ds_read_b64_tr_b4 v[122:123], v54
	ds_read_b64_tr_b4 v[124:125], v55
	ds_read_b64_tr_b4 v[126:127], v56
	ds_read_b64_tr_b4 v[128:129], v57
	s_waitcnt lgkmcnt(6)
	v_dot8c_i32_i4_e32 v38, v130, v52
	v_dot8c_i32_i4_e32 v39, v130, v50
	v_dot8c_i32_i4_e32 v40, v132, v52
	v_dot8c_i32_i4_e32 v41, v132, v50
	v_dot8c_i32_i4_e32 v42, v134, v52
	v_dot8c_i32_i4_e32 v43, v134, v50
	v_dot8c_i32_i4_e32 v44, v136, v52
	v_dot8c_i32_i4_e32 v45, v136, v50
	v_dot8c_i32_i4_e32 v38, v131, v53
	v_dot8c_i32_i4_e32 v39, v131, v51
	v_dot8c_i32_i4_e32 v40, v133, v53
	v_dot8c_i32_i4_e32 v41, v133, v51
	v_dot8c_i32_i4_e32 v42, v135, v53
	v_dot8c_i32_i4_e32 v43, v135, v51
	v_dot8c_i32_i4_e32 v44, v137, v53
	v_dot8c_i32_i4_e32 v45, v137, v51
	v_and_b32_e32 v78, 0xffff, v33
	v_lshrrev_b32_e32 v79, 16, v33
	v_lshl_add_u32 v78, v78, 7, v150
	v_lshl_add_u32 v79, v79, 7, v151
	s_mov_b32 m0, s77
	s_add_i32 s43, s77, 0x400
	global_load_lds_dwordx4 v78, s[50:51]
	s_mov_b32 m0, s43
	s_nop 0
	global_load_lds_dwordx4 v79, s[50:51]
	s_waitcnt vmcnt(8)
	v_add_u32_e32 v54, s79, v59
	v_add_u32_e32 v55, s79, v60
	v_add_u32_e32 v56, s79, v61
	v_add_u32_e32 v57, s79, v62
	ds_read_b64_tr_b4 v[50:51], v160 offset:384
	ds_read_b64_tr_b4 v[52:53], v160 offset:1408
	ds_read_b64_tr_b4 v[130:131], v54
	ds_read_b64_tr_b4 v[132:133], v55
	ds_read_b64_tr_b4 v[134:135], v56
	ds_read_b64_tr_b4 v[136:137], v57
	s_waitcnt lgkmcnt(6)
	v_dot8c_i32_i4_e32 v38, v122, v48
	v_dot8c_i32_i4_e32 v39, v122, v46
	v_dot8c_i32_i4_e32 v40, v124, v48
	v_dot8c_i32_i4_e32 v41, v124, v46
	v_dot8c_i32_i4_e32 v42, v126, v48
	v_dot8c_i32_i4_e32 v43, v126, v46
	v_dot8c_i32_i4_e32 v44, v128, v48
	v_dot8c_i32_i4_e32 v45, v128, v46
	v_dot8c_i32_i4_e32 v38, v123, v49
	v_dot8c_i32_i4_e32 v39, v123, v47
	v_dot8c_i32_i4_e32 v40, v125, v49
	v_dot8c_i32_i4_e32 v41, v125, v47
	v_dot8c_i32_i4_e32 v42, v127, v49
	v_dot8c_i32_i4_e32 v43, v127, v47
	v_dot8c_i32_i4_e32 v44, v129, v49
	v_dot8c_i32_i4_e32 v45, v129, v47
	s_waitcnt lgkmcnt(15)
	v_and_b32_e32 v78, 0xffff, v18
	v_lshrrev_b32_e32 v79, 16, v18
	v_lshl_add_u32 v78, v78, 7, v152
	v_lshl_add_u32 v79, v79, 7, v153
	s_mov_b32 m0, s78
	s_add_i32 s43, s78, 0x400
	global_load_lds_dwordx4 v78, s[50:51]
	s_mov_b32 m0, s43
	s_nop 0
	global_load_lds_dwordx4 v79, s[50:51]
	s_waitcnt vmcnt(8)
; #define TR4(p_) __builtin_amdgcn_ds_read_tr4_b64_v2i32((LAS v2i*)(p_))
; #define VDMA(st_, k_) do { _Pragma("unroll") for (int i_ = 0; i_ < 4; ++i_) { \
;         const unsigned off_ = (unsigned)((st_) >> 2) * (16384u * 128u) + (PE_ID(E, 4 * ((st_) & 3) + i_) << 7) + ((i_ & 1) ? cx1 : cx0); \
;         __builtin_amdgcn_global_load_lds((const unsigned*)(V4 + off_), (LAS unsigned*)(ldsb + BUF[k_] + 1024 * i_), 16, 0, 0); } } while (0)
; __device__ __forceinline__ void peer_v_tokens(int j, const LAS unsigned short* EL, const LAS unsigned char* AL  , const LAS float* ASC  , const LAS int* SAL  , ...
;     ...
;         for (int st = 0; st < 16; ++st) {
;             const int p = st >> 2, q = st & 3;
;             if (st < 14) VDMA(st + 2, (st + 2) % 3);
;             if (st < 14) asm volatile("s_waitcnt vmcnt(8)" ::: "memory");
;             else if (st == 14) asm volatile("s_waitcnt vmcnt(4)" ::: "memory");
;             else asm volatile("s_waitcnt vmcnt(0)" ::: "memory");
;             if (q == 0) {
; #pragma unroll
;                 for (int r = 0; r < 4; ++r) { accH[r] = 0; accL[r] = 0; } }
; #pragma unroll
;             for (int tp = 0; tp < 2; ++tp) {
;                 const v2i ao = TR4(ATL + (2 * q + tp) * 128 + 8 * s16), ah = TR4(ATL + 1024 + (2 * q + tp) * 128 + 8 * s16);
; #pragma unroll
;                 for (int r = 0; r < 4; ++r) {
;                     const v2i d = TR4(ldsb + BUF[st % 3] + 2048 * tp + roff[r]);
;                     accH[r] = __builtin_amdgcn_sdot8(d.x, ah.x, accH[r], false); accH[r] = __builtin_amdgcn_sdot8(d.y, ah.y, accH[r], false);
;                     accL[r] = __builtin_amdgcn_sdot8(d.x, ao.x, accL[r], false); accL[r] = __builtin_amdgcn_sdot8(d.y, ao.y, accL[r], false);
;                 }
;             }
	v_add_u32_e32 v54, s98, v59
	v_add_u32_e32 v55, s98, v60
	v_add_u32_e32 v56, s98, v61
	v_add_u32_e32 v57, s98, v62
	ds_read_b64_tr_b4 v[46:47], v160 offset:512
	ds_read_b64_tr_b4 v[48:49], v160 offset:1536
	ds_read_b64_tr_b4 v[122:123], v54
	ds_read_b64_tr_b4 v[124:125], v55
	ds_read_b64_tr_b4 v[126:127], v56
	ds_read_b64_tr_b4 v[128:129], v57
	s_waitcnt lgkmcnt(6)
	v_dot8c_i32_i4_e32 v38, v130, v52
	v_dot8c_i32_i4_e32 v39, v130, v50
	v_dot8c_i32_i4_e32 v40, v132, v52
	v_dot8c_i32_i4_e32 v41, v132, v50
	v_dot8c_i32_i4_e32 v42, v134, v52
	v_dot8c_i32_i4_e32 v43, v134, v50
	v_dot8c_i32_i4_e32 v44, v136, v52
	v_dot8c_i32_i4_e32 v45, v136, v50
	v_dot8c_i32_i4_e32 v38, v131, v53
	v_dot8c_i32_i4_e32 v39, v131, v51
	v_dot8c_i32_i4_e32 v40, v133, v53
	v_dot8c_i32_i4_e32 v41, v133, v51
	v_dot8c_i32_i4_e32 v42, v135, v53
	v_dot8c_i32_i4_e32 v43, v135, v51
	v_dot8c_i32_i4_e32 v44, v137, v53
	v_dot8c_i32_i4_e32 v45, v137, v51
	v_and_b32_e32 v78, 0xffff, v19
	v_lshrrev_b32_e32 v79, 16, v19
	v_lshl_add_u32 v78, v78, 7, v152
	v_lshl_add_u32 v79, v79, 7, v153
	s_mov_b32 m0, s79
	s_add_i32 s43, s79, 0x400
	global_load_lds_dwordx4 v78, s[50:51]
	s_mov_b32 m0, s43
	s_nop 0
	global_load_lds_dwordx4 v79, s[50:51]
	s_waitcnt vmcnt(8)
	v_add_u32_e32 v54, s99, v59
	v_add_u32_e32 v55, s99, v60
	v_add_u32_e32 v56, s99, v61
	v_add_u32_e32 v57, s99, v62
	ds_read_b64_tr_b4 v[50:51], v160 offset:640
	ds_read_b64_tr_b4 v[52:53], v160 offset:1664
	ds_read_b64_tr_b4 v[130:131], v54
	ds_read_b64_tr_b4 v[132:133], v55
	ds_read_b64_tr_b4 v[134:135], v56
	ds_read_b64_tr_b4 v[136:137], v57
	s_waitcnt lgkmcnt(6)
	v_dot8c_i32_i4_e32 v38, v122, v48
	v_dot8c_i32_i4_e32 v39, v122, v46
	v_dot8c_i32_i4_e32 v40, v124, v48
	v_dot8c_i32_i4_e32 v41, v124, v46
	v_dot8c_i32_i4_e32 v42, v126, v48
	v_dot8c_i32_i4_e32 v43, v126, v46
	v_dot8c_i32_i4_e32 v44, v128, v48
	v_dot8c_i32_i4_e32 v45, v128, v46
	v_dot8c_i32_i4_e32 v38, v123, v49
	v_dot8c_i32_i4_e32 v39, v123, v47
	v_dot8c_i32_i4_e32 v40, v125, v49
	v_dot8c_i32_i4_e32 v41, v125, v47
	v_dot8c_i32_i4_e32 v42, v127, v49
	v_dot8c_i32_i4_e32 v43, v127, v47
	v_dot8c_i32_i4_e32 v44, v129, v49
	v_dot8c_i32_i4_e32 v45, v129, v47
	s_waitcnt lgkmcnt(15)
	v_add_u32_e32 v143, 8, v139
	v_and_b32_e32 v142, 15, v143
	v_xor_b32_e32 v142, 8, v142
	v_bfe_u32 v144, v143, 4, 4
	v_mul_lo_u32 v142, v142, s92
	v_mul_lo_u32 v144, v144, s92
	v_mov_b32_e32 v143, v142
	v_mov_b32_e32 v145, v144
	ds_write2st64_b64 v159, v[142:143], v[144:145] offset1:2
	v_and_b32_e32 v78, 0xffff, v20
	v_lshrrev_b32_e32 v79, 16, v20
	v_lshl_add_u32 v78, v78, 7, v152
	v_lshl_add_u32 v79, v79, 7, v153
	s_mov_b32 m0, s98
	s_add_i32 s43, s98, 0x400
	global_load_lds_dwordx4 v78, s[50:51]
	s_mov_b32 m0, s43
	s_nop 0
	global_load_lds_dwordx4 v79, s[50:51]
	s_waitcnt vmcnt(8)
	v_add_u32_e32 v54, s76, v59
	v_add_u32_e32 v55, s76, v60
	v_add_u32_e32 v56, s76, v61
	v_add_u32_e32 v57, s76, v62
	ds_read_b64_tr_b4 v[46:47], v160 offset:768
	ds_read_b64_tr_b4 v[48:49], v160 offset:1792
	ds_read_b64_tr_b4 v[122:123], v54
	ds_read_b64_tr_b4 v[124:125], v55
	ds_read_b64_tr_b4 v[126:127], v56
	ds_read_b64_tr_b4 v[128:129], v57
	s_waitcnt lgkmcnt(7)
	v_dot8c_i32_i4_e32 v38, v130, v52
	v_dot8c_i32_i4_e32 v39, v130, v50
	v_dot8c_i32_i4_e32 v40, v132, v52
	v_dot8c_i32_i4_e32 v41, v132, v50
	v_dot8c_i32_i4_e32 v42, v134, v52
	v_dot8c_i32_i4_e32 v43, v134, v50
	v_dot8c_i32_i4_e32 v44, v136, v52
	v_dot8c_i32_i4_e32 v45, v136, v50
	v_dot8c_i32_i4_e32 v38, v131, v53
	v_dot8c_i32_i4_e32 v39, v131, v51
	v_dot8c_i32_i4_e32 v40, v133, v53
	v_dot8c_i32_i4_e32 v41, v133, v51
	v_dot8c_i32_i4_e32 v42, v135, v53
	v_dot8c_i32_i4_e32 v43, v135, v51
	v_dot8c_i32_i4_e32 v44, v137, v53
	v_dot8c_i32_i4_e32 v45, v137, v51
	v_and_b32_e32 v78, 0xffff, v21
	v_lshrrev_b32_e32 v79, 16, v21
	v_lshl_add_u32 v78, v78, 7, v152
	v_lshl_add_u32 v79, v79, 7, v153
	s_mov_b32 m0, s99
	s_add_i32 s43, s99, 0x400
	global_load_lds_dwordx4 v78, s[50:51]
	s_mov_b32 m0, s43
	s_nop 0
	global_load_lds_dwordx4 v79, s[50:51]
	s_waitcnt vmcnt(8)
	v_add_u32_e32 v54, s77, v59
	v_add_u32_e32 v55, s77, v60
	v_add_u32_e32 v56, s77, v61
	v_add_u32_e32 v57, s77, v62
	ds_read_b64_tr_b4 v[50:51], v160 offset:896
	ds_read_b64_tr_b4 v[52:53], v160 offset:1920
	ds_read_b64_tr_b4 v[130:131], v54
	ds_read_b64_tr_b4 v[132:133], v55
	ds_read_b64_tr_b4 v[134:135], v56
	ds_read_b64_tr_b4 v[136:137], v57
	s_waitcnt lgkmcnt(6)
	v_dot8c_i32_i4_e32 v38, v122, v48
	v_dot8c_i32_i4_e32 v39, v122, v46
	v_dot8c_i32_i4_e32 v40, v124, v48
	v_dot8c_i32_i4_e32 v41, v124, v46
	v_dot8c_i32_i4_e32 v42, v126, v48
	v_dot8c_i32_i4_e32 v43, v126, v46
	v_dot8c_i32_i4_e32 v44, v128, v48
	v_dot8c_i32_i4_e32 v45, v128, v46
	v_dot8c_i32_i4_e32 v38, v123, v49
	v_dot8c_i32_i4_e32 v39, v123, v47
	v_dot8c_i32_i4_e32 v40, v125, v49
	v_dot8c_i32_i4_e32 v41, v125, v47
	v_dot8c_i32_i4_e32 v42, v127, v49
	v_dot8c_i32_i4_e32 v43, v127, v47
	v_dot8c_i32_i4_e32 v44, v129, v49
	v_dot8c_i32_i4_e32 v45, v129, v47
	v_and_b32_e32 v78, 0xffff, v22
	v_lshrrev_b32_e32 v79, 16, v22
	v_lshl_add_u32 v78, v78, 7, v152
	v_lshl_add_u32 v79, v79, 7, v153
	s_mov_b32 m0, s76
	s_add_i32 s43, s76, 0x400
	global_load_lds_dwordx4 v78, s[50:51]
	s_mov_b32 m0, s43
	s_nop 0
	global_load_lds_dwordx4 v79, s[50:51]
	s_waitcnt vmcnt(8)
	v_add_u32_e32 v54, s78, v59
	v_add_u32_e32 v55, s78, v60
	v_add_u32_e32 v56, s78, v61
	v_add_u32_e32 v57, s78, v62
	ds_read_b64_tr_b4 v[46:47], v160
	ds_read_b64_tr_b4 v[48:49], v160 offset:1024
	ds_read_b64_tr_b4 v[122:123], v54
	ds_read_b64_tr_b4 v[124:125], v55
	ds_read_b64_tr_b4 v[126:127], v56
	ds_read_b64_tr_b4 v[128:129], v57
	s_waitcnt lgkmcnt(6)
; #define LAS __attribute__((address_space(3)))
; __device__ __forceinline__ bf16 f2bf(float f) { return (bf16)f2bfu(f); }
; #define TR4(p_) __builtin_amdgcn_ds_read_tr4_b64_v2i32((LAS v2i*)(p_))
; __device__ __forceinline__ void peer_v_tokens(int j, const LAS unsigned short* EL, const LAS unsigned char* AL  , const LAS float* ASC  , const LAS int* SAL  , ...
;     ...
;         for (int m = 0; m < 2; ++m) {
;             const int idx = lane + 64 * m, tau = idx >> 4, sr = idx & 15, k = 16 * (sr & 7) + 2 * tau + (sr >> 3);
;             const int aq = (int)*(const LAS signed char*)(AL + tl * 128 + k); const int tq = aq + 8;
;             const unsigned lo = (((unsigned)tq & 15u) ^ 8u) * 0x11111111u, hi = ((unsigned)(tq >> 4) & 15u) * 0x11111111u;
;             typedef unsigned u2v __attribute__((ext_vector_type(2)));
;             u2v l2; l2.x = lo; l2.y = lo; u2v h2; h2.x = hi; h2.y = hi;
;             *(LAS u2v*)(ATL + 8 * idx) = l2; *(LAS u2v*)(ATL + 1024 + 8 * idx) = h2;
;         }
;         const float asc = ASC[tl]; const int sa = SAL[tl];
;     ...
;                 for (int r = 0; r < 4; ++r) {
;                     const v2i d = TR4(ldsb + BUF[st % 3] + 2048 * tp + roff[r]);
;                     accH[r] = __builtin_amdgcn_sdot8(d.x, ah.x, accH[r], false); accH[r] = __builtin_amdgcn_sdot8(d.y, ah.y, accH[r], false);
;                     accL[r] = __builtin_amdgcn_sdot8(d.x, ao.x, accL[r], false); accL[r] = __builtin_amdgcn_sdot8(d.y, ao.y, accL[r], false);
;                 }
;             }
;             asm volatile("s_waitcnt lgkmcnt(0)" ::: "memory");
;             if (q == 3) {
; #pragma unroll
;                 for (int r = 0; r < 4; ++r) STASH[256 * p + 16 * (grp + 4 * r) + pc] = f2bf(asc * (float)(2 * ((accH[r] << 4) + accL[r]) + sa));
	v_dot8c_i32_i4_e32 v38, v130, v52
	v_dot8c_i32_i4_e32 v39, v130, v50
	v_dot8c_i32_i4_e32 v40, v132, v52
	v_dot8c_i32_i4_e32 v41, v132, v50
	v_dot8c_i32_i4_e32 v42, v134, v52
	v_dot8c_i32_i4_e32 v43, v134, v50
	v_dot8c_i32_i4_e32 v44, v136, v52
	v_dot8c_i32_i4_e32 v45, v136, v50
	v_dot8c_i32_i4_e32 v38, v131, v53
	v_dot8c_i32_i4_e32 v39, v131, v51
	v_dot8c_i32_i4_e32 v40, v133, v53
	v_dot8c_i32_i4_e32 v41, v133, v51
	v_dot8c_i32_i4_e32 v42, v135, v53
	v_dot8c_i32_i4_e32 v43, v135, v51
	v_dot8c_i32_i4_e32 v44, v137, v53
	v_dot8c_i32_i4_e32 v45, v137, v51
	s_nop 3
	s_waitcnt lgkmcnt(15)
	v_lshlrev_b32_e32 v38, 5, v38
	v_lshlrev_b32_e32 v39, 1, v39
	v_add3_u32 v38, v39, v229, v38
	v_cvt_f32_i32_e32 v38, v38
	v_mul_f32_e32 v38, v228, v38
	v_lshlrev_b32_e32 v40, 5, v40
	v_lshlrev_b32_e32 v41, 1, v41
	v_add3_u32 v40, v41, v229, v40
	v_cvt_f32_i32_e32 v40, v40
	v_mul_f32_e32 v40, v228, v40
	v_lshlrev_b32_e32 v42, 5, v42
	v_lshlrev_b32_e32 v43, 1, v43
	v_add3_u32 v42, v43, v229, v42
	v_cvt_f32_i32_e32 v42, v42
	v_mul_f32_e32 v42, v228, v42
	v_lshlrev_b32_e32 v44, 5, v44
	v_lshlrev_b32_e32 v45, 1, v45
	v_add3_u32 v44, v45, v229, v44
	v_cvt_f32_i32_e32 v44, v44
	v_mul_f32_e32 v44, v228, v44
	v_cvt_pk_bf16_f32 v231, v38, v40
	v_cvt_pk_bf16_f32 v232, v42, v44
	v_add_u32_e32 v147, 8, v140
	v_and_b32_e32 v146, 15, v147
	v_xor_b32_e32 v146, 8, v146
	v_bfe_u32 v148, v147, 4, 4
	v_mul_lo_u32 v146, v146, s92
	v_mul_lo_u32 v148, v148, s92
	v_mov_b32_e32 v147, v146
	v_mov_b32_e32 v149, v148
	ds_write2st64_b64 v77, v[146:147], v[148:149] offset1:2
	v_add_u32_e32 v138, 0x1400, v74
	ds_read_u8 v139, v138
	v_add_u32_e32 v141, 0x1400, v73
	ds_read_u8 v140, v141
	s_add_i32 s43, s67, 128
	v_mov_b32_e32 v138, s43
	ds_read2st64_b32 v[228:229], v138 offset1:1
	ds_read_b128 v[26:29], v227 offset:10240
	ds_read_b128 v[30:33], v227 offset:10256
	v_mov_b32_e32 v38, 0
	v_mov_b32_e32 v39, 0
	v_mov_b32_e32 v40, 0
	v_mov_b32_e32 v41, 0
	v_mov_b32_e32 v42, 0
	v_mov_b32_e32 v43, 0
	v_mov_b32_e32 v44, 0
	v_mov_b32_e32 v45, 0
	v_and_b32_e32 v78, 0xffff, v23
	v_lshrrev_b32_e32 v79, 16, v23
	v_lshl_add_u32 v78, v78, 7, v152
	v_lshl_add_u32 v79, v79, 7, v153
	s_mov_b32 m0, s77
	s_add_i32 s43, s77, 0x400
	global_load_lds_dwordx4 v78, s[50:51]
	s_mov_b32 m0, s43
	s_nop 0
	global_load_lds_dwordx4 v79, s[50:51]
	s_waitcnt vmcnt(8)
	v_add_u32_e32 v54, s79, v59
	v_add_u32_e32 v55, s79, v60
	v_add_u32_e32 v56, s79, v61
	v_add_u32_e32 v57, s79, v62
	ds_read_b64_tr_b4 v[50:51], v160 offset:128
	ds_read_b64_tr_b4 v[52:53], v160 offset:1152
	ds_read_b64_tr_b4 v[130:131], v54
	ds_read_b64_tr_b4 v[132:133], v55
	ds_read_b64_tr_b4 v[134:135], v56
	ds_read_b64_tr_b4 v[136:137], v57
	s_waitcnt lgkmcnt(12)
	v_dot8c_i32_i4_e32 v38, v122, v48
	v_dot8c_i32_i4_e32 v39, v122, v46
	v_dot8c_i32_i4_e32 v40, v124, v48
	v_dot8c_i32_i4_e32 v41, v124, v46
	v_dot8c_i32_i4_e32 v42, v126, v48
	v_dot8c_i32_i4_e32 v43, v126, v46
	v_dot8c_i32_i4_e32 v44, v128, v48
	v_dot8c_i32_i4_e32 v45, v128, v46
	v_dot8c_i32_i4_e32 v38, v123, v49
	v_dot8c_i32_i4_e32 v39, v123, v47
	v_dot8c_i32_i4_e32 v40, v125, v49
	v_dot8c_i32_i4_e32 v41, v125, v47
	v_dot8c_i32_i4_e32 v42, v127, v49
	v_dot8c_i32_i4_e32 v43, v127, v47
	v_dot8c_i32_i4_e32 v44, v129, v49
	v_dot8c_i32_i4_e32 v45, v129, v47
	v_and_b32_e32 v78, 0xffff, v24
	v_lshrrev_b32_e32 v79, 16, v24
	v_lshl_add_u32 v78, v78, 7, v152
	v_lshl_add_u32 v79, v79, 7, v153
	s_mov_b32 m0, s78
	s_add_i32 s43, s78, 0x400
	global_load_lds_dwordx4 v78, s[50:51]
	s_mov_b32 m0, s43
	s_nop 0
	global_load_lds_dwordx4 v79, s[50:51]
	s_waitcnt vmcnt(8)
	v_add_u32_e32 v54, s98, v59
	v_add_u32_e32 v55, s98, v60
	v_add_u32_e32 v56, s98, v61
	v_add_u32_e32 v57, s98, v62
	ds_read_b64_tr_b4 v[46:47], v160 offset:256
	ds_read_b64_tr_b4 v[48:49], v160 offset:1280
	ds_read_b64_tr_b4 v[122:123], v54
	ds_read_b64_tr_b4 v[124:125], v55
	ds_read_b64_tr_b4 v[126:127], v56
	ds_read_b64_tr_b4 v[128:129], v57
	s_waitcnt lgkmcnt(6)
	v_dot8c_i32_i4_e32 v38, v130, v52
	v_dot8c_i32_i4_e32 v39, v130, v50
	v_dot8c_i32_i4_e32 v40, v132, v52
	v_dot8c_i32_i4_e32 v41, v132, v50
	v_dot8c_i32_i4_e32 v42, v134, v52
	v_dot8c_i32_i4_e32 v43, v134, v50
	v_dot8c_i32_i4_e32 v44, v136, v52
	v_dot8c_i32_i4_e32 v45, v136, v50
	v_dot8c_i32_i4_e32 v38, v131, v53
	v_dot8c_i32_i4_e32 v39, v131, v51
	v_dot8c_i32_i4_e32 v40, v133, v53
	v_dot8c_i32_i4_e32 v41, v133, v51
	v_dot8c_i32_i4_e32 v42, v135, v53
	v_dot8c_i32_i4_e32 v43, v135, v51
	v_dot8c_i32_i4_e32 v44, v137, v53
	v_dot8c_i32_i4_e32 v45, v137, v51
	v_and_b32_e32 v78, 0xffff, v25
	v_lshrrev_b32_e32 v79, 16, v25
	v_lshl_add_u32 v78, v78, 7, v152
	v_lshl_add_u32 v79, v79, 7, v153
	s_mov_b32 m0, s79
	s_add_i32 s43, s79, 0x400
	global_load_lds_dwordx4 v78, s[50:51]
	s_mov_b32 m0, s43
	s_nop 0
	global_load_lds_dwordx4 v79, s[50:51]
	s_waitcnt vmcnt(8)
	v_add_u32_e32 v54, s99, v59
	v_add_u32_e32 v55, s99, v60
	v_add_u32_e32 v56, s99, v61
	v_add_u32_e32 v57, s99, v62
	ds_read_b64_tr_b4 v[50:51], v160 offset:384
	ds_read_b64_tr_b4 v[52:53], v160 offset:1408
	ds_read_b64_tr_b4 v[130:131], v54
	ds_read_b64_tr_b4 v[132:133], v55
	ds_read_b64_tr_b4 v[134:135], v56
	ds_read_b64_tr_b4 v[136:137], v57
	s_waitcnt lgkmcnt(6)
	v_dot8c_i32_i4_e32 v38, v122, v48
	v_dot8c_i32_i4_e32 v39, v122, v46
	v_dot8c_i32_i4_e32 v40, v124, v48
	v_dot8c_i32_i4_e32 v41, v124, v46
	v_dot8c_i32_i4_e32 v42, v126, v48
	v_dot8c_i32_i4_e32 v43, v126, v46
	v_dot8c_i32_i4_e32 v44, v128, v48
	v_dot8c_i32_i4_e32 v45, v128, v46
	v_dot8c_i32_i4_e32 v38, v123, v49
	v_dot8c_i32_i4_e32 v39, v123, v47
	v_dot8c_i32_i4_e32 v40, v125, v49
	v_dot8c_i32_i4_e32 v41, v125, v47
	v_dot8c_i32_i4_e32 v42, v127, v49
	v_dot8c_i32_i4_e32 v43, v127, v47
	v_dot8c_i32_i4_e32 v44, v129, v49
	v_dot8c_i32_i4_e32 v45, v129, v47
	s_waitcnt lgkmcnt(15)
; #define TR4(p_) __builtin_amdgcn_ds_read_tr4_b64_v2i32((LAS v2i*)(p_))
; #define VDMA(st_, k_) do { _Pragma("unroll") for (int i_ = 0; i_ < 4; ++i_) { \
;         const unsigned off_ = (unsigned)((st_) >> 2) * (16384u * 128u) + (PE_ID(E, 4 * ((st_) & 3) + i_) << 7) + ((i_ & 1) ? cx1 : cx0); \
;         __builtin_amdgcn_global_load_lds((const unsigned*)(V4 + off_), (LAS unsigned*)(ldsb + BUF[k_] + 1024 * i_), 16, 0, 0); } } while (0)
; __device__ __forceinline__ void peer_v_tokens(int j, const LAS unsigned short* EL, const LAS unsigned char* AL  , const LAS float* ASC  , const LAS int* SAL  , ...
;     ...
;         for (int st = 0; st < 16; ++st) {
;             const int p = st >> 2, q = st & 3;
;             if (st < 14) VDMA(st + 2, (st + 2) % 3);
;             if (st < 14) asm volatile("s_waitcnt vmcnt(8)" ::: "memory");
;             else if (st == 14) asm volatile("s_waitcnt vmcnt(4)" ::: "memory");
;             else asm volatile("s_waitcnt vmcnt(0)" ::: "memory");
;             if (q == 0) {
; #pragma unroll
;                 for (int r = 0; r < 4; ++r) { accH[r] = 0; accL[r] = 0; } }
; #pragma unroll
;             for (int tp = 0; tp < 2; ++tp) {
;                 const v2i ao = TR4(ATL + (2 * q + tp) * 128 + 8 * s16), ah = TR4(ATL + 1024 + (2 * q + tp) * 128 + 8 * s16);
; #pragma unroll
;                 for (int r = 0; r < 4; ++r) {
;                     const v2i d = TR4(ldsb + BUF[st % 3] + 2048 * tp + roff[r]);
;                     accH[r] = __builtin_amdgcn_sdot8(d.x, ah.x, accH[r], false); accH[r] = __builtin_amdgcn_sdot8(d.y, ah.y, accH[r], false);
;                     accL[r] = __builtin_amdgcn_sdot8(d.x, ao.x, accL[r], false); accL[r] = __builtin_amdgcn_sdot8(d.y, ao.y, accL[r], false);
;                 }
;             }
	v_and_b32_e32 v78, 0xffff, v26
	v_lshrrev_b32_e32 v79, 16, v26
	v_lshl_add_u32 v78, v78, 7, v152
	v_lshl_add_u32 v79, v79, 7, v153
	s_mov_b32 m0, s98
	s_add_i32 s43, s98, 0x400
	global_load_lds_dwordx4 v78, s[50:51]
	s_mov_b32 m0, s43
	s_nop 0
	global_load_lds_dwordx4 v79, s[50:51]
	s_waitcnt vmcnt(8)
	v_add_u32_e32 v54, s76, v59
	v_add_u32_e32 v55, s76, v60
	v_add_u32_e32 v56, s76, v61
	v_add_u32_e32 v57, s76, v62
	ds_read_b64_tr_b4 v[46:47], v160 offset:512
	ds_read_b64_tr_b4 v[48:49], v160 offset:1536
	ds_read_b64_tr_b4 v[122:123], v54
	ds_read_b64_tr_b4 v[124:125], v55
	ds_read_b64_tr_b4 v[126:127], v56
	ds_read_b64_tr_b4 v[128:129], v57
	s_waitcnt lgkmcnt(6)
	v_dot8c_i32_i4_e32 v38, v130, v52
	v_dot8c_i32_i4_e32 v39, v130, v50
	v_dot8c_i32_i4_e32 v40, v132, v52
	v_dot8c_i32_i4_e32 v41, v132, v50
	v_dot8c_i32_i4_e32 v42, v134, v52
	v_dot8c_i32_i4_e32 v43, v134, v50
	v_dot8c_i32_i4_e32 v44, v136, v52
	v_dot8c_i32_i4_e32 v45, v136, v50
	v_dot8c_i32_i4_e32 v38, v131, v53
	v_dot8c_i32_i4_e32 v39, v131, v51
	v_dot8c_i32_i4_e32 v40, v133, v53
	v_dot8c_i32_i4_e32 v41, v133, v51
	v_dot8c_i32_i4_e32 v42, v135, v53
	v_dot8c_i32_i4_e32 v43, v135, v51
	v_dot8c_i32_i4_e32 v44, v137, v53
	v_dot8c_i32_i4_e32 v45, v137, v51
	v_and_b32_e32 v78, 0xffff, v27
	v_lshrrev_b32_e32 v79, 16, v27
	v_lshl_add_u32 v78, v78, 7, v152
	v_lshl_add_u32 v79, v79, 7, v153
	s_mov_b32 m0, s99
	s_add_i32 s43, s99, 0x400
	global_load_lds_dwordx4 v78, s[50:51]
	s_mov_b32 m0, s43
	s_nop 0
	global_load_lds_dwordx4 v79, s[50:51]
	s_waitcnt vmcnt(8)
	v_add_u32_e32 v54, s77, v59
	v_add_u32_e32 v55, s77, v60
	v_add_u32_e32 v56, s77, v61
	v_add_u32_e32 v57, s77, v62
	ds_read_b64_tr_b4 v[50:51], v160 offset:640
	ds_read_b64_tr_b4 v[52:53], v160 offset:1664
	ds_read_b64_tr_b4 v[130:131], v54
	ds_read_b64_tr_b4 v[132:133], v55
	ds_read_b64_tr_b4 v[134:135], v56
	ds_read_b64_tr_b4 v[136:137], v57
	s_waitcnt lgkmcnt(6)
	v_dot8c_i32_i4_e32 v38, v122, v48
	v_dot8c_i32_i4_e32 v39, v122, v46
	v_dot8c_i32_i4_e32 v40, v124, v48
	v_dot8c_i32_i4_e32 v41, v124, v46
	v_dot8c_i32_i4_e32 v42, v126, v48
	v_dot8c_i32_i4_e32 v43, v126, v46
	v_dot8c_i32_i4_e32 v44, v128, v48
	v_dot8c_i32_i4_e32 v45, v128, v46
	v_dot8c_i32_i4_e32 v38, v123, v49
	v_dot8c_i32_i4_e32 v39, v123, v47
	v_dot8c_i32_i4_e32 v40, v125, v49
	v_dot8c_i32_i4_e32 v41, v125, v47
	v_dot8c_i32_i4_e32 v42, v127, v49
	v_dot8c_i32_i4_e32 v43, v127, v47
	v_dot8c_i32_i4_e32 v44, v129, v49
	v_dot8c_i32_i4_e32 v45, v129, v47
	s_waitcnt lgkmcnt(15)
	v_add_u32_e32 v143, 8, v139
	v_and_b32_e32 v142, 15, v143
	v_xor_b32_e32 v142, 8, v142
	v_bfe_u32 v144, v143, 4, 4
	v_mul_lo_u32 v142, v142, s92
	v_mul_lo_u32 v144, v144, s92
	v_mov_b32_e32 v143, v142
	v_mov_b32_e32 v145, v144
	ds_write2st64_b64 v159, v[142:143], v[144:145] offset1:2
	v_and_b32_e32 v78, 0xffff, v28
	v_lshrrev_b32_e32 v79, 16, v28
	v_lshl_add_u32 v78, v78, 7, v152
	v_lshl_add_u32 v79, v79, 7, v153
	s_mov_b32 m0, s76
	s_add_i32 s43, s76, 0x400
	global_load_lds_dwordx4 v78, s[50:51]
	s_mov_b32 m0, s43
	s_nop 0
	global_load_lds_dwordx4 v79, s[50:51]
	s_waitcnt vmcnt(8)
	v_add_u32_e32 v54, s78, v59
	v_add_u32_e32 v55, s78, v60
	v_add_u32_e32 v56, s78, v61
	v_add_u32_e32 v57, s78, v62
	ds_read_b64_tr_b4 v[46:47], v160 offset:768
	ds_read_b64_tr_b4 v[48:49], v160 offset:1792
	ds_read_b64_tr_b4 v[122:123], v54
	ds_read_b64_tr_b4 v[124:125], v55
	ds_read_b64_tr_b4 v[126:127], v56
	ds_read_b64_tr_b4 v[128:129], v57
	s_waitcnt lgkmcnt(7)
	v_dot8c_i32_i4_e32 v38, v130, v52
	v_dot8c_i32_i4_e32 v39, v130, v50
	v_dot8c_i32_i4_e32 v40, v132, v52
	v_dot8c_i32_i4_e32 v41, v132, v50
	v_dot8c_i32_i4_e32 v42, v134, v52
	v_dot8c_i32_i4_e32 v43, v134, v50
	v_dot8c_i32_i4_e32 v44, v136, v52
	v_dot8c_i32_i4_e32 v45, v136, v50
	v_dot8c_i32_i4_e32 v38, v131, v53
	v_dot8c_i32_i4_e32 v39, v131, v51
	v_dot8c_i32_i4_e32 v40, v133, v53
	v_dot8c_i32_i4_e32 v41, v133, v51
	v_dot8c_i32_i4_e32 v42, v135, v53
	v_dot8c_i32_i4_e32 v43, v135, v51
	v_dot8c_i32_i4_e32 v44, v137, v53
	v_dot8c_i32_i4_e32 v45, v137, v51
	v_and_b32_e32 v78, 0xffff, v29
	v_lshrrev_b32_e32 v79, 16, v29
	v_lshl_add_u32 v78, v78, 7, v152
	v_lshl_add_u32 v79, v79, 7, v153
	s_mov_b32 m0, s77
	s_add_i32 s43, s77, 0x400
	global_load_lds_dwordx4 v78, s[50:51]
	s_mov_b32 m0, s43
	s_nop 0
	global_load_lds_dwordx4 v79, s[50:51]
	s_waitcnt vmcnt(8)
	v_add_u32_e32 v54, s79, v59
	v_add_u32_e32 v55, s79, v60
	v_add_u32_e32 v56, s79, v61
	v_add_u32_e32 v57, s79, v62
	ds_read_b64_tr_b4 v[50:51], v160 offset:896
	ds_read_b64_tr_b4 v[52:53], v160 offset:1920
	ds_read_b64_tr_b4 v[130:131], v54
	ds_read_b64_tr_b4 v[132:133], v55
	ds_read_b64_tr_b4 v[134:135], v56
	ds_read_b64_tr_b4 v[136:137], v57
	s_waitcnt lgkmcnt(6)
	v_dot8c_i32_i4_e32 v38, v122, v48
	v_dot8c_i32_i4_e32 v39, v122, v46
	v_dot8c_i32_i4_e32 v40, v124, v48
	v_dot8c_i32_i4_e32 v41, v124, v46
	v_dot8c_i32_i4_e32 v42, v126, v48
	v_dot8c_i32_i4_e32 v43, v126, v46
	v_dot8c_i32_i4_e32 v44, v128, v48
	v_dot8c_i32_i4_e32 v45, v128, v46
	v_dot8c_i32_i4_e32 v38, v123, v49
	v_dot8c_i32_i4_e32 v39, v123, v47
	v_dot8c_i32_i4_e32 v40, v125, v49
	v_dot8c_i32_i4_e32 v41, v125, v47
	v_dot8c_i32_i4_e32 v42, v127, v49
	v_dot8c_i32_i4_e32 v43, v127, v47
	v_dot8c_i32_i4_e32 v44, v129, v49
	v_dot8c_i32_i4_e32 v45, v129, v47
	v_and_b32_e32 v78, 0xffff, v30
	v_lshrrev_b32_e32 v79, 16, v30
	v_lshl_add_u32 v78, v78, 7, v152
	v_lshl_add_u32 v79, v79, 7, v153
	s_mov_b32 m0, s78
	s_add_i32 s43, s78, 0x400
	global_load_lds_dwordx4 v78, s[50:51]
	s_mov_b32 m0, s43
	s_nop 0
	global_load_lds_dwordx4 v79, s[50:51]
	s_waitcnt vmcnt(8)
; __device__ __forceinline__ void peer_v_tokens(int j, const LAS unsigned short* EL, const LAS unsigned char* AL  , const LAS float* ASC  , const LAS int* SAL  , ...
;     ...
;         { unsigned ho = (unsigned)t * (D / 4) + (unsigned)lane; asm volatile("" : "+v"(ho)); const uint2* hp = (const uint2*)HB + ho; const float4* gp = (const float4*)fng + lane;
; #pragma unroll
;           for (int jq = 0; jq < 4; ++jq) { hv[jq] = hp[64 * jq]; gv[jq] = gp[64 * jq]; } }
;         VDMA(0, 0); VDMA(1, 1);
; #pragma unroll
;         for (int m = 0; m < 2; ++m) {
;             const int idx = lane + 64 * m, tau = idx >> 4, sr = idx & 15, k = 16 * (sr & 7) + 2 * tau + (sr >> 3);
;             const int aq = (int)*(const LAS signed char*)(AL + tl * 128 + k); const int tq = aq + 8;
;             const unsigned lo = (((unsigned)tq & 15u) ^ 8u) * 0x11111111u, hi = ((unsigned)(tq >> 4) & 15u) * 0x11111111u;
;             typedef unsigned u2v __attribute__((ext_vector_type(2)));
;             u2v l2; l2.x = lo; l2.y = lo; u2v h2; h2.x = hi; h2.y = hi;
;             *(LAS u2v*)(ATL + 8 * idx) = l2; *(LAS u2v*)(ATL + 1024 + 8 * idx) = h2;
;         }
;         const float asc = ASC[tl]; const int sa = SAL[tl];
;         CFENCE();
;         int accH[4], accL[4];
; #pragma unroll
;         for (int st = 0; st < 16; ++st) {
;             const int p = st >> 2, q = st & 3;
;             if (st < 14) VDMA(st + 2, (st + 2) % 3);
;             if (st < 14) asm volatile("s_waitcnt vmcnt(8)" ::: "memory");
;             else if (st == 14) asm volatile("s_waitcnt vmcnt(4)" ::: "memory");
;             else asm volatile("s_waitcnt vmcnt(0)" ::: "memory");
;             if (q == 0) {
; #pragma unroll
;                 for (int r = 0; r < 4; ++r) { accH[r] = 0; accL[r] = 0; } }
; #pragma unroll
;             for (int tp = 0; tp < 2; ++tp) {
;                 const v2i ao = TR4(ATL + (2 * q + tp) * 128 + 8 * s16), ah = TR4(ATL + 1024 + (2 * q + tp) * 128 + 8 * s16);
; #pragma unroll
;                 for (int r = 0; r < 4; ++r) {
;                     const v2i d = TR4(ldsb + BUF[st % 3] + 2048 * tp + roff[r]);
;                     accH[r] = __builtin_amdgcn_sdot8(d.x, ah.x, accH[r], false); accH[r] = __builtin_amdgcn_sdot8(d.y, ah.y, accH[r], false);
;                     accL[r] = __builtin_amdgcn_sdot8(d.x, ao.x, accL[r], false); accL[r] = __builtin_amdgcn_sdot8(d.y, ao.y, accL[r], false);
	v_add_u32_e32 v54, s98, v59
	v_add_u32_e32 v55, s98, v60
	v_add_u32_e32 v56, s98, v61
	v_add_u32_e32 v57, s98, v62
	ds_read_b64_tr_b4 v[46:47], v160
	ds_read_b64_tr_b4 v[48:49], v160 offset:1024
	ds_read_b64_tr_b4 v[122:123], v54
	ds_read_b64_tr_b4 v[124:125], v55
	ds_read_b64_tr_b4 v[126:127], v56
	ds_read_b64_tr_b4 v[128:129], v57
	s_waitcnt lgkmcnt(6)
	v_dot8c_i32_i4_e32 v38, v130, v52
	v_dot8c_i32_i4_e32 v39, v130, v50
	v_dot8c_i32_i4_e32 v40, v132, v52
	v_dot8c_i32_i4_e32 v41, v132, v50
	v_dot8c_i32_i4_e32 v42, v134, v52
	v_dot8c_i32_i4_e32 v43, v134, v50
	v_dot8c_i32_i4_e32 v44, v136, v52
	v_dot8c_i32_i4_e32 v45, v136, v50
	v_dot8c_i32_i4_e32 v38, v131, v53
	v_dot8c_i32_i4_e32 v39, v131, v51
	v_dot8c_i32_i4_e32 v40, v133, v53
	v_dot8c_i32_i4_e32 v41, v133, v51
	v_dot8c_i32_i4_e32 v42, v135, v53
	v_dot8c_i32_i4_e32 v43, v135, v51
	v_dot8c_i32_i4_e32 v44, v137, v53
	v_dot8c_i32_i4_e32 v45, v137, v51
	s_nop 3
	s_waitcnt lgkmcnt(15)
	v_lshlrev_b32_e32 v38, 5, v38
	v_lshlrev_b32_e32 v39, 1, v39
	v_add3_u32 v38, v39, v229, v38
	v_cvt_f32_i32_e32 v38, v38
	v_mul_f32_e32 v38, v228, v38
	v_lshlrev_b32_e32 v40, 5, v40
	v_lshlrev_b32_e32 v41, 1, v41
	v_add3_u32 v40, v41, v229, v40
	v_cvt_f32_i32_e32 v40, v40
	v_mul_f32_e32 v40, v228, v40
	v_lshlrev_b32_e32 v42, 5, v42
	v_lshlrev_b32_e32 v43, 1, v43
	v_add3_u32 v42, v43, v229, v42
	v_cvt_f32_i32_e32 v42, v42
	v_mul_f32_e32 v42, v228, v42
	v_lshlrev_b32_e32 v44, 5, v44
	v_lshlrev_b32_e32 v45, 1, v45
	v_add3_u32 v44, v45, v229, v44
	v_cvt_f32_i32_e32 v44, v44
	v_mul_f32_e32 v44, v228, v44
	v_cvt_pk_bf16_f32 v242, v38, v40
	v_cvt_pk_bf16_f32 v243, v42, v44
	s_add_i32 s43, s40, 32
	s_lshl_b32 s43, s43, 11
	v_add_u32_e32 v138, s43, v66
	global_load_dwordx2 v[194:195], v138, s[70:71]
	global_load_dwordx2 v[196:197], v138, s[70:71] offset:512
	global_load_dwordx2 v[198:199], v138, s[70:71] offset:1024
	global_load_dwordx2 v[200:201], v138, s[70:71] offset:1536
	v_add_u32_e32 v147, 8, v140
	v_and_b32_e32 v146, 15, v147
	v_xor_b32_e32 v146, 8, v146
	v_bfe_u32 v148, v147, 4, 4
	v_mul_lo_u32 v146, v146, s92
	v_mul_lo_u32 v148, v148, s92
	v_mov_b32_e32 v147, v146
	v_mov_b32_e32 v149, v148
	ds_write2st64_b64 v77, v[146:147], v[148:149] offset1:2
	v_add_u32_e32 v138, 0x1800, v74
	ds_read_u8 v139, v138
	v_add_u32_e32 v141, 0x1800, v73
	ds_read_u8 v140, v141
	s_add_i32 s43, s67, 160
	v_mov_b32_e32 v138, s43
	ds_read2st64_b32 v[228:229], v138 offset1:1
	ds_read_b128 v[18:21], v227 offset:12288
	ds_read_b128 v[22:25], v227 offset:12304
	v_mov_b32_e32 v38, 0
	v_mov_b32_e32 v39, 0
	v_mov_b32_e32 v40, 0
	v_mov_b32_e32 v41, 0
	v_mov_b32_e32 v42, 0
	v_mov_b32_e32 v43, 0
	v_mov_b32_e32 v44, 0
	v_mov_b32_e32 v45, 0
	v_and_b32_e32 v78, 0xffff, v31
	v_lshrrev_b32_e32 v79, 16, v31
	v_lshl_add_u32 v78, v78, 7, v152
	v_lshl_add_u32 v79, v79, 7, v153
	s_mov_b32 m0, s79
	s_add_i32 s43, s79, 0x400
	global_load_lds_dwordx4 v78, s[50:51]
	s_mov_b32 m0, s43
	s_nop 0
	global_load_lds_dwordx4 v79, s[50:51]
	s_waitcnt vmcnt(12)
	v_add_u32_e32 v54, s99, v59
	v_add_u32_e32 v55, s99, v60
	v_add_u32_e32 v56, s99, v61
	v_add_u32_e32 v57, s99, v62
	ds_read_b64_tr_b4 v[50:51], v160 offset:128
	ds_read_b64_tr_b4 v[52:53], v160 offset:1152
	ds_read_b64_tr_b4 v[130:131], v54
	ds_read_b64_tr_b4 v[132:133], v55
	ds_read_b64_tr_b4 v[134:135], v56
	ds_read_b64_tr_b4 v[136:137], v57
	s_waitcnt lgkmcnt(12)
	v_dot8c_i32_i4_e32 v38, v122, v48
	v_dot8c_i32_i4_e32 v39, v122, v46
	v_dot8c_i32_i4_e32 v40, v124, v48
	v_dot8c_i32_i4_e32 v41, v124, v46
	v_dot8c_i32_i4_e32 v42, v126, v48
	v_dot8c_i32_i4_e32 v43, v126, v46
	v_dot8c_i32_i4_e32 v44, v128, v48
	v_dot8c_i32_i4_e32 v45, v128, v46
	v_dot8c_i32_i4_e32 v38, v123, v49
	v_dot8c_i32_i4_e32 v39, v123, v47
	v_dot8c_i32_i4_e32 v40, v125, v49
	v_dot8c_i32_i4_e32 v41, v125, v47
	v_dot8c_i32_i4_e32 v42, v127, v49
	v_dot8c_i32_i4_e32 v43, v127, v47
	v_dot8c_i32_i4_e32 v44, v129, v49
	v_dot8c_i32_i4_e32 v45, v129, v47
	v_and_b32_e32 v78, 0xffff, v32
	v_lshrrev_b32_e32 v79, 16, v32
	v_lshl_add_u32 v78, v78, 7, v152
	v_lshl_add_u32 v79, v79, 7, v153
	s_mov_b32 m0, s98
	s_add_i32 s43, s98, 0x400
	global_load_lds_dwordx4 v78, s[50:51]
	s_mov_b32 m0, s43
	s_nop 0
	global_load_lds_dwordx4 v79, s[50:51]
	s_waitcnt vmcnt(12)
	v_add_u32_e32 v54, s76, v59
	v_add_u32_e32 v55, s76, v60
	v_add_u32_e32 v56, s76, v61
	v_add_u32_e32 v57, s76, v62
	ds_read_b64_tr_b4 v[46:47], v160 offset:256
	ds_read_b64_tr_b4 v[48:49], v160 offset:1280
	ds_read_b64_tr_b4 v[122:123], v54
	ds_read_b64_tr_b4 v[124:125], v55
	ds_read_b64_tr_b4 v[126:127], v56
	ds_read_b64_tr_b4 v[128:129], v57
	s_waitcnt lgkmcnt(6)
	v_dot8c_i32_i4_e32 v38, v130, v52
	v_dot8c_i32_i4_e32 v39, v130, v50
	v_dot8c_i32_i4_e32 v40, v132, v52
	v_dot8c_i32_i4_e32 v41, v132, v50
	v_dot8c_i32_i4_e32 v42, v134, v52
	v_dot8c_i32_i4_e32 v43, v134, v50
	v_dot8c_i32_i4_e32 v44, v136, v52
	v_dot8c_i32_i4_e32 v45, v136, v50
	v_dot8c_i32_i4_e32 v38, v131, v53
	v_dot8c_i32_i4_e32 v39, v131, v51
	v_dot8c_i32_i4_e32 v40, v133, v53
	v_dot8c_i32_i4_e32 v41, v133, v51
	v_dot8c_i32_i4_e32 v42, v135, v53
	v_dot8c_i32_i4_e32 v43, v135, v51
	v_dot8c_i32_i4_e32 v44, v137, v53
	v_dot8c_i32_i4_e32 v45, v137, v51
	v_and_b32_e32 v78, 0xffff, v33
	v_lshrrev_b32_e32 v79, 16, v33
	v_lshl_add_u32 v78, v78, 7, v152
	v_lshl_add_u32 v79, v79, 7, v153
	s_mov_b32 m0, s99
	s_add_i32 s43, s99, 0x400
	global_load_lds_dwordx4 v78, s[50:51]
	s_mov_b32 m0, s43
	s_nop 0
	global_load_lds_dwordx4 v79, s[50:51]
	s_waitcnt vmcnt(12)
; #define TR4(p_) __builtin_amdgcn_ds_read_tr4_b64_v2i32((LAS v2i*)(p_))
; #define VDMA(st_, k_) do { _Pragma("unroll") for (int i_ = 0; i_ < 4; ++i_) { \
;         const unsigned off_ = (unsigned)((st_) >> 2) * (16384u * 128u) + (PE_ID(E, 4 * ((st_) & 3) + i_) << 7) + ((i_ & 1) ? cx1 : cx0); \
;         __builtin_amdgcn_global_load_lds((const unsigned*)(V4 + off_), (LAS unsigned*)(ldsb + BUF[k_] + 1024 * i_), 16, 0, 0); } } while (0)
; __device__ __forceinline__ void peer_v_tokens(int j, const LAS unsigned short* EL, const LAS unsigned char* AL  , const LAS float* ASC  , const LAS int* SAL  , ...
;     ...
;         for (int st = 0; st < 16; ++st) {
;             const int p = st >> 2, q = st & 3;
;             if (st < 14) VDMA(st + 2, (st + 2) % 3);
;             if (st < 14) asm volatile("s_waitcnt vmcnt(8)" ::: "memory");
;             else if (st == 14) asm volatile("s_waitcnt vmcnt(4)" ::: "memory");
;             else asm volatile("s_waitcnt vmcnt(0)" ::: "memory");
;             if (q == 0) {
; #pragma unroll
;                 for (int r = 0; r < 4; ++r) { accH[r] = 0; accL[r] = 0; } }
; #pragma unroll
;             for (int tp = 0; tp < 2; ++tp) {
;                 const v2i ao = TR4(ATL + (2 * q + tp) * 128 + 8 * s16), ah = TR4(ATL + 1024 + (2 * q + tp) * 128 + 8 * s16);
; #pragma unroll
;                 for (int r = 0; r < 4; ++r) {
;                     const v2i d = TR4(ldsb + BUF[st % 3] + 2048 * tp + roff[r]);
;                     accH[r] = __builtin_amdgcn_sdot8(d.x, ah.x, accH[r], false); accH[r] = __builtin_amdgcn_sdot8(d.y, ah.y, accH[r], false);
;                     accL[r] = __builtin_amdgcn_sdot8(d.x, ao.x, accL[r], false); accL[r] = __builtin_amdgcn_sdot8(d.y, ao.y, accL[r], false);
;                 }
;             }
	v_add_u32_e32 v54, s77, v59
	v_add_u32_e32 v55, s77, v60
	v_add_u32_e32 v56, s77, v61
	v_add_u32_e32 v57, s77, v62
	ds_read_b64_tr_b4 v[50:51], v160 offset:384
	ds_read_b64_tr_b4 v[52:53], v160 offset:1408
	ds_read_b64_tr_b4 v[130:131], v54
	ds_read_b64_tr_b4 v[132:133], v55
	ds_read_b64_tr_b4 v[134:135], v56
	ds_read_b64_tr_b4 v[136:137], v57
	s_waitcnt lgkmcnt(6)
	v_dot8c_i32_i4_e32 v38, v122, v48
	v_dot8c_i32_i4_e32 v39, v122, v46
	v_dot8c_i32_i4_e32 v40, v124, v48
	v_dot8c_i32_i4_e32 v41, v124, v46
	v_dot8c_i32_i4_e32 v42, v126, v48
	v_dot8c_i32_i4_e32 v43, v126, v46
	v_dot8c_i32_i4_e32 v44, v128, v48
	v_dot8c_i32_i4_e32 v45, v128, v46
	v_dot8c_i32_i4_e32 v38, v123, v49
	v_dot8c_i32_i4_e32 v39, v123, v47
	v_dot8c_i32_i4_e32 v40, v125, v49
	v_dot8c_i32_i4_e32 v41, v125, v47
	v_dot8c_i32_i4_e32 v42, v127, v49
	v_dot8c_i32_i4_e32 v43, v127, v47
	v_dot8c_i32_i4_e32 v44, v129, v49
	v_dot8c_i32_i4_e32 v45, v129, v47
	s_waitcnt lgkmcnt(15)
	v_and_b32_e32 v78, 0xffff, v18
	v_lshrrev_b32_e32 v79, 16, v18
	v_lshl_add_u32 v78, v78, 7, v152
	v_lshl_add_u32 v79, v79, 7, v153
	s_mov_b32 m0, s76
	s_add_i32 s43, s76, 0x400
	global_load_lds_dwordx4 v78, s[50:51]
	s_mov_b32 m0, s43
	s_nop 0
	global_load_lds_dwordx4 v79, s[50:51]
	s_waitcnt vmcnt(12)
	v_add_u32_e32 v54, s78, v59
	v_add_u32_e32 v55, s78, v60
	v_add_u32_e32 v56, s78, v61
	v_add_u32_e32 v57, s78, v62
	ds_read_b64_tr_b4 v[46:47], v160 offset:512
	ds_read_b64_tr_b4 v[48:49], v160 offset:1536
	ds_read_b64_tr_b4 v[122:123], v54
	ds_read_b64_tr_b4 v[124:125], v55
	ds_read_b64_tr_b4 v[126:127], v56
	ds_read_b64_tr_b4 v[128:129], v57
	s_waitcnt lgkmcnt(6)
	v_dot8c_i32_i4_e32 v38, v130, v52
	v_dot8c_i32_i4_e32 v39, v130, v50
	v_dot8c_i32_i4_e32 v40, v132, v52
	v_dot8c_i32_i4_e32 v41, v132, v50
	v_dot8c_i32_i4_e32 v42, v134, v52
	v_dot8c_i32_i4_e32 v43, v134, v50
	v_dot8c_i32_i4_e32 v44, v136, v52
	v_dot8c_i32_i4_e32 v45, v136, v50
	v_dot8c_i32_i4_e32 v38, v131, v53
	v_dot8c_i32_i4_e32 v39, v131, v51
	v_dot8c_i32_i4_e32 v40, v133, v53
	v_dot8c_i32_i4_e32 v41, v133, v51
	v_dot8c_i32_i4_e32 v42, v135, v53
	v_dot8c_i32_i4_e32 v43, v135, v51
	v_dot8c_i32_i4_e32 v44, v137, v53
	v_dot8c_i32_i4_e32 v45, v137, v51
	v_and_b32_e32 v78, 0xffff, v19
	v_lshrrev_b32_e32 v79, 16, v19
	v_lshl_add_u32 v78, v78, 7, v152
	v_lshl_add_u32 v79, v79, 7, v153
	s_mov_b32 m0, s77
	s_add_i32 s43, s77, 0x400
	global_load_lds_dwordx4 v78, s[50:51]
	s_mov_b32 m0, s43
	s_nop 0
	global_load_lds_dwordx4 v79, s[50:51]
	s_waitcnt vmcnt(8)
	v_add_u32_e32 v54, s79, v59
	v_add_u32_e32 v55, s79, v60
	v_add_u32_e32 v56, s79, v61
	v_add_u32_e32 v57, s79, v62
	ds_read_b64_tr_b4 v[50:51], v160 offset:640
	ds_read_b64_tr_b4 v[52:53], v160 offset:1664
	ds_read_b64_tr_b4 v[130:131], v54
	ds_read_b64_tr_b4 v[132:133], v55
	ds_read_b64_tr_b4 v[134:135], v56
	ds_read_b64_tr_b4 v[136:137], v57
	s_waitcnt lgkmcnt(6)
	v_dot8c_i32_i4_e32 v38, v122, v48
	v_dot8c_i32_i4_e32 v39, v122, v46
	v_dot8c_i32_i4_e32 v40, v124, v48
	v_dot8c_i32_i4_e32 v41, v124, v46
	v_dot8c_i32_i4_e32 v42, v126, v48
	v_dot8c_i32_i4_e32 v43, v126, v46
	v_dot8c_i32_i4_e32 v44, v128, v48
	v_dot8c_i32_i4_e32 v45, v128, v46
	v_dot8c_i32_i4_e32 v38, v123, v49
	v_dot8c_i32_i4_e32 v39, v123, v47
	v_dot8c_i32_i4_e32 v40, v125, v49
	v_dot8c_i32_i4_e32 v41, v125, v47
	v_dot8c_i32_i4_e32 v42, v127, v49
	v_dot8c_i32_i4_e32 v43, v127, v47
	v_dot8c_i32_i4_e32 v44, v129, v49
	v_dot8c_i32_i4_e32 v45, v129, v47
	s_waitcnt lgkmcnt(15)
	v_add_u32_e32 v143, 8, v139
	v_and_b32_e32 v142, 15, v143
	v_xor_b32_e32 v142, 8, v142
	v_bfe_u32 v144, v143, 4, 4
	v_mul_lo_u32 v142, v142, s92
	v_mul_lo_u32 v144, v144, s92
	v_mov_b32_e32 v143, v142
	v_mov_b32_e32 v145, v144
	ds_write2st64_b64 v159, v[142:143], v[144:145] offset1:2
	v_and_b32_e32 v78, 0xffff, v20
	v_lshrrev_b32_e32 v79, 16, v20
	v_lshl_add_u32 v78, v78, 7, v152
	v_lshl_add_u32 v79, v79, 7, v153
	s_mov_b32 m0, s78
	s_add_i32 s43, s78, 0x400
	global_load_lds_dwordx4 v78, s[50:51]
	s_mov_b32 m0, s43
	s_nop 0
	global_load_lds_dwordx4 v79, s[50:51]
	s_waitcnt vmcnt(8)
	v_add_u32_e32 v54, s98, v59
	v_add_u32_e32 v55, s98, v60
	v_add_u32_e32 v56, s98, v61
	v_add_u32_e32 v57, s98, v62
	ds_read_b64_tr_b4 v[46:47], v160 offset:768
	ds_read_b64_tr_b4 v[48:49], v160 offset:1792
	ds_read_b64_tr_b4 v[122:123], v54
	ds_read_b64_tr_b4 v[124:125], v55
	ds_read_b64_tr_b4 v[126:127], v56
	ds_read_b64_tr_b4 v[128:129], v57
	s_waitcnt lgkmcnt(7)
	v_dot8c_i32_i4_e32 v38, v130, v52
	v_dot8c_i32_i4_e32 v39, v130, v50
	v_dot8c_i32_i4_e32 v40, v132, v52
	v_dot8c_i32_i4_e32 v41, v132, v50
	v_dot8c_i32_i4_e32 v42, v134, v52
	v_dot8c_i32_i4_e32 v43, v134, v50
	v_dot8c_i32_i4_e32 v44, v136, v52
	v_dot8c_i32_i4_e32 v45, v136, v50
	v_dot8c_i32_i4_e32 v38, v131, v53
	v_dot8c_i32_i4_e32 v39, v131, v51
	v_dot8c_i32_i4_e32 v40, v133, v53
	v_dot8c_i32_i4_e32 v41, v133, v51
	v_dot8c_i32_i4_e32 v42, v135, v53
	v_dot8c_i32_i4_e32 v43, v135, v51
	v_dot8c_i32_i4_e32 v44, v137, v53
	v_dot8c_i32_i4_e32 v45, v137, v51
	v_and_b32_e32 v78, 0xffff, v21
	v_lshrrev_b32_e32 v79, 16, v21
	v_lshl_add_u32 v78, v78, 7, v152
	v_lshl_add_u32 v79, v79, 7, v153
	s_mov_b32 m0, s79
	s_add_i32 s43, s79, 0x400
	global_load_lds_dwordx4 v78, s[50:51]
	s_mov_b32 m0, s43
	s_nop 0
	global_load_lds_dwordx4 v79, s[50:51]
	s_waitcnt vmcnt(8)
	v_add_u32_e32 v54, s99, v59
	v_add_u32_e32 v55, s99, v60
	v_add_u32_e32 v56, s99, v61
	v_add_u32_e32 v57, s99, v62
	ds_read_b64_tr_b4 v[50:51], v160 offset:896
	ds_read_b64_tr_b4 v[52:53], v160 offset:1920
	ds_read_b64_tr_b4 v[130:131], v54
	ds_read_b64_tr_b4 v[132:133], v55
	ds_read_b64_tr_b4 v[134:135], v56
	ds_read_b64_tr_b4 v[136:137], v57
	s_waitcnt lgkmcnt(6)
; __device__ __forceinline__ bf16 f2bf(float f) { return (bf16)f2bfu(f); }
; #define TR4(p_) __builtin_amdgcn_ds_read_tr4_b64_v2i32((LAS v2i*)(p_))
; #define VDMA(st_, k_) do { _Pragma("unroll") for (int i_ = 0; i_ < 4; ++i_) { \
;         const unsigned off_ = (unsigned)((st_) >> 2) * (16384u * 128u) + (PE_ID(E, 4 * ((st_) & 3) + i_) << 7) + ((i_ & 1) ? cx1 : cx0); \
;         __builtin_amdgcn_global_load_lds((const unsigned*)(V4 + off_), (LAS unsigned*)(ldsb + BUF[k_] + 1024 * i_), 16, 0, 0); } } while (0)
; __device__ __forceinline__ void peer_v_tokens(int j, const LAS unsigned short* EL, const LAS unsigned char* AL  , const LAS float* ASC  , const LAS int* SAL  , ...
;     ...
;         for (int st = 0; st < 16; ++st) {
;             const int p = st >> 2, q = st & 3;
;             if (st < 14) VDMA(st + 2, (st + 2) % 3);
;             if (st < 14) asm volatile("s_waitcnt vmcnt(8)" ::: "memory");
;             else if (st == 14) asm volatile("s_waitcnt vmcnt(4)" ::: "memory");
;             else asm volatile("s_waitcnt vmcnt(0)" ::: "memory");
;             if (q == 0) {
; #pragma unroll
;                 for (int r = 0; r < 4; ++r) { accH[r] = 0; accL[r] = 0; } }
; #pragma unroll
;             for (int tp = 0; tp < 2; ++tp) {
;                 const v2i ao = TR4(ATL + (2 * q + tp) * 128 + 8 * s16), ah = TR4(ATL + 1024 + (2 * q + tp) * 128 + 8 * s16);
; #pragma unroll
;                 for (int r = 0; r < 4; ++r) {
;                     const v2i d = TR4(ldsb + BUF[st % 3] + 2048 * tp + roff[r]);
;                     accH[r] = __builtin_amdgcn_sdot8(d.x, ah.x, accH[r], false); accH[r] = __builtin_amdgcn_sdot8(d.y, ah.y, accH[r], false);
;                     accL[r] = __builtin_amdgcn_sdot8(d.x, ao.x, accL[r], false); accL[r] = __builtin_amdgcn_sdot8(d.y, ao.y, accL[r], false);
;                 }
;             }
;             asm volatile("s_waitcnt lgkmcnt(0)" ::: "memory");
;             if (q == 3) {
; #pragma unroll
;                 for (int r = 0; r < 4; ++r) STASH[256 * p + 16 * (grp + 4 * r) + pc] = f2bf(asc * (float)(2 * ((accH[r] << 4) + accL[r]) + sa));
	v_dot8c_i32_i4_e32 v38, v122, v48
	v_dot8c_i32_i4_e32 v39, v122, v46
	v_dot8c_i32_i4_e32 v40, v124, v48
	v_dot8c_i32_i4_e32 v41, v124, v46
	v_dot8c_i32_i4_e32 v42, v126, v48
	v_dot8c_i32_i4_e32 v43, v126, v46
	v_dot8c_i32_i4_e32 v44, v128, v48
	v_dot8c_i32_i4_e32 v45, v128, v46
	v_dot8c_i32_i4_e32 v38, v123, v49
	v_dot8c_i32_i4_e32 v39, v123, v47
	v_dot8c_i32_i4_e32 v40, v125, v49
	v_dot8c_i32_i4_e32 v41, v125, v47
	v_dot8c_i32_i4_e32 v42, v127, v49
	v_dot8c_i32_i4_e32 v43, v127, v47
	v_dot8c_i32_i4_e32 v44, v129, v49
	v_dot8c_i32_i4_e32 v45, v129, v47
	v_and_b32_e32 v78, 0xffff, v22
	v_lshrrev_b32_e32 v79, 16, v22
	v_lshl_add_u32 v78, v78, 7, v152
	v_lshl_add_u32 v79, v79, 7, v153
	s_mov_b32 m0, s98
	s_add_i32 s43, s98, 0x400
	global_load_lds_dwordx4 v78, s[50:51]
	s_mov_b32 m0, s43
	s_nop 0
	global_load_lds_dwordx4 v79, s[50:51]
	s_waitcnt vmcnt(8)
	v_add_u32_e32 v54, s76, v59
	v_add_u32_e32 v55, s76, v60
	v_add_u32_e32 v56, s76, v61
	v_add_u32_e32 v57, s76, v62
	ds_read_b64_tr_b4 v[46:47], v160
	ds_read_b64_tr_b4 v[48:49], v160 offset:1024
	ds_read_b64_tr_b4 v[122:123], v54
	ds_read_b64_tr_b4 v[124:125], v55
	ds_read_b64_tr_b4 v[126:127], v56
	ds_read_b64_tr_b4 v[128:129], v57
	s_waitcnt lgkmcnt(6)
	v_dot8c_i32_i4_e32 v38, v130, v52
	v_dot8c_i32_i4_e32 v39, v130, v50
	v_dot8c_i32_i4_e32 v40, v132, v52
	v_dot8c_i32_i4_e32 v41, v132, v50
	v_dot8c_i32_i4_e32 v42, v134, v52
	v_dot8c_i32_i4_e32 v43, v134, v50
	v_dot8c_i32_i4_e32 v44, v136, v52
	v_dot8c_i32_i4_e32 v45, v136, v50
	v_dot8c_i32_i4_e32 v38, v131, v53
	v_dot8c_i32_i4_e32 v39, v131, v51
	v_dot8c_i32_i4_e32 v40, v133, v53
	v_dot8c_i32_i4_e32 v41, v133, v51
	v_dot8c_i32_i4_e32 v42, v135, v53
	v_dot8c_i32_i4_e32 v43, v135, v51
	v_dot8c_i32_i4_e32 v44, v137, v53
	v_dot8c_i32_i4_e32 v45, v137, v51
	s_nop 3
	s_waitcnt lgkmcnt(15)
	v_lshlrev_b32_e32 v38, 5, v38
	v_lshlrev_b32_e32 v39, 1, v39
	v_add3_u32 v38, v39, v229, v38
	v_cvt_f32_i32_e32 v38, v38
	v_mul_f32_e32 v38, v228, v38
	v_lshlrev_b32_e32 v40, 5, v40
	v_lshlrev_b32_e32 v41, 1, v41
	v_add3_u32 v40, v41, v229, v40
	v_cvt_f32_i32_e32 v40, v40
	v_mul_f32_e32 v40, v228, v40
	v_lshlrev_b32_e32 v42, 5, v42
	v_lshlrev_b32_e32 v43, 1, v43
	v_add3_u32 v42, v43, v229, v42
	v_cvt_f32_i32_e32 v42, v42
	v_mul_f32_e32 v42, v228, v42
	v_lshlrev_b32_e32 v44, 5, v44
	v_lshlrev_b32_e32 v45, 1, v45
	v_add3_u32 v44, v45, v229, v44
	v_cvt_f32_i32_e32 v44, v44
	v_mul_f32_e32 v44, v228, v44
	v_cvt_pk_bf16_f32 v250, v38, v40
	v_cvt_pk_bf16_f32 v251, v42, v44
	v_add_u32_e32 v147, 8, v140
	v_and_b32_e32 v146, 15, v147
	v_xor_b32_e32 v146, 8, v146
	v_bfe_u32 v148, v147, 4, 4
	v_mul_lo_u32 v146, v146, s92
	v_mul_lo_u32 v148, v148, s92
	v_mov_b32_e32 v147, v146
	v_mov_b32_e32 v149, v148
	ds_write2st64_b64 v77, v[146:147], v[148:149] offset1:2
	v_add_u32_e32 v138, 0x1c00, v74
	ds_read_u8 v139, v138
	v_add_u32_e32 v141, 0x1c00, v73
	ds_read_u8 v140, v141
	s_add_i32 s43, s67, 192
	v_mov_b32_e32 v138, s43
	ds_read2st64_b32 v[228:229], v138 offset1:1
	ds_read_b128 v[26:29], v227 offset:14336
	ds_read_b128 v[30:33], v227 offset:14352
	v_mov_b32_e32 v38, 0
	v_mov_b32_e32 v39, 0
	v_mov_b32_e32 v40, 0
	v_mov_b32_e32 v41, 0
	v_mov_b32_e32 v42, 0
	v_mov_b32_e32 v43, 0
	v_mov_b32_e32 v44, 0
	v_mov_b32_e32 v45, 0
	v_and_b32_e32 v78, 0xffff, v23
	v_lshrrev_b32_e32 v79, 16, v23
	v_lshl_add_u32 v78, v78, 7, v152
	v_lshl_add_u32 v79, v79, 7, v153
	s_mov_b32 m0, s99
	s_add_i32 s43, s99, 0x400
	global_load_lds_dwordx4 v78, s[50:51]
	s_mov_b32 m0, s43
	s_nop 0
	global_load_lds_dwordx4 v79, s[50:51]
	s_waitcnt vmcnt(8)
	v_add_u32_e32 v54, s77, v59
	v_add_u32_e32 v55, s77, v60
	v_add_u32_e32 v56, s77, v61
	v_add_u32_e32 v57, s77, v62
	ds_read_b64_tr_b4 v[50:51], v160 offset:128
	ds_read_b64_tr_b4 v[52:53], v160 offset:1152
	ds_read_b64_tr_b4 v[130:131], v54
	ds_read_b64_tr_b4 v[132:133], v55
	ds_read_b64_tr_b4 v[134:135], v56
	ds_read_b64_tr_b4 v[136:137], v57
	s_waitcnt lgkmcnt(12)
	v_dot8c_i32_i4_e32 v38, v122, v48
	v_dot8c_i32_i4_e32 v39, v122, v46
	v_dot8c_i32_i4_e32 v40, v124, v48
	v_dot8c_i32_i4_e32 v41, v124, v46
	v_dot8c_i32_i4_e32 v42, v126, v48
	v_dot8c_i32_i4_e32 v43, v126, v46
	v_dot8c_i32_i4_e32 v44, v128, v48
	v_dot8c_i32_i4_e32 v45, v128, v46
	v_dot8c_i32_i4_e32 v38, v123, v49
	v_dot8c_i32_i4_e32 v39, v123, v47
	v_dot8c_i32_i4_e32 v40, v125, v49
	v_dot8c_i32_i4_e32 v41, v125, v47
	v_dot8c_i32_i4_e32 v42, v127, v49
	v_dot8c_i32_i4_e32 v43, v127, v47
	v_dot8c_i32_i4_e32 v44, v129, v49
	v_dot8c_i32_i4_e32 v45, v129, v47
	v_and_b32_e32 v78, 0xffff, v24
	v_lshrrev_b32_e32 v79, 16, v24
	v_lshl_add_u32 v78, v78, 7, v152
	v_lshl_add_u32 v79, v79, 7, v153
	s_mov_b32 m0, s76
	s_add_i32 s43, s76, 0x400
	global_load_lds_dwordx4 v78, s[50:51]
	s_mov_b32 m0, s43
	s_nop 0
	global_load_lds_dwordx4 v79, s[50:51]
	s_waitcnt vmcnt(8)
	v_add_u32_e32 v54, s78, v59
	v_add_u32_e32 v55, s78, v60
	v_add_u32_e32 v56, s78, v61
	v_add_u32_e32 v57, s78, v62
	ds_read_b64_tr_b4 v[46:47], v160 offset:256
	ds_read_b64_tr_b4 v[48:49], v160 offset:1280
	ds_read_b64_tr_b4 v[122:123], v54
	ds_read_b64_tr_b4 v[124:125], v55
	ds_read_b64_tr_b4 v[126:127], v56
	ds_read_b64_tr_b4 v[128:129], v57
	s_waitcnt lgkmcnt(6)
; #define LAS __attribute__((address_space(3)))
; __device__ __forceinline__ bf16 f2bf(float f) { return (bf16)f2bfu(f); }
; #define TR4(p_) __builtin_amdgcn_ds_read_tr4_b64_v2i32((LAS v2i*)(p_))
; #define CFENCE() asm volatile("" ::: "memory")
; __device__ __forceinline__ void peer_v_tokens(int j, const LAS unsigned short* EL, const LAS unsigned char* AL  , const LAS float* ASC  , const LAS int* SAL  , ...
;     ...
;             for (int tp = 0; tp < 2; ++tp) {
;                 const v2i ao = TR4(ATL + (2 * q + tp) * 128 + 8 * s16), ah = TR4(ATL + 1024 + (2 * q + tp) * 128 + 8 * s16);
; #pragma unroll
;                 for (int r = 0; r < 4; ++r) {
;                     const v2i d = TR4(ldsb + BUF[st % 3] + 2048 * tp + roff[r]);
;                     accH[r] = __builtin_amdgcn_sdot8(d.x, ah.x, accH[r], false); accH[r] = __builtin_amdgcn_sdot8(d.y, ah.y, accH[r], false);
;                     accL[r] = __builtin_amdgcn_sdot8(d.x, ao.x, accL[r], false); accL[r] = __builtin_amdgcn_sdot8(d.y, ao.y, accL[r], false);
;                 }
;             }
;             asm volatile("s_waitcnt lgkmcnt(0)" ::: "memory");
;             if (q == 3) {
; #pragma unroll
;                 for (int r = 0; r < 4; ++r) STASH[256 * p + 16 * (grp + 4 * r) + pc] = f2bf(asc * (float)(2 * ((accH[r] << 4) + accL[r]) + sa));
;             }
;         }
;         CFENCE();
;         {
;             float4 v[4]; float ss = 0.f;
; #pragma unroll
;             for (int jq = 0; jq < 4; ++jq) { typedef unsigned u2v __attribute__((ext_vector_type(2))); const u2v pw = *(const LAS u2v*)(STASH + 4 * lane + 256 * jq); const uint2 hw = hv[jq];
;                 v[jq] = make_float4(__uint_as_float(hw.x << 16) + __uint_as_float(pw.x << 16), __uint_as_float(hw.x & 0xffff0000u) + __uint_as_float(pw.x & 0xffff0000u),
	v_dot8c_i32_i4_e32 v38, v130, v52
	v_dot8c_i32_i4_e32 v39, v130, v50
	v_dot8c_i32_i4_e32 v40, v132, v52
	v_dot8c_i32_i4_e32 v41, v132, v50
	v_dot8c_i32_i4_e32 v42, v134, v52
	v_dot8c_i32_i4_e32 v43, v134, v50
	v_dot8c_i32_i4_e32 v44, v136, v52
	v_dot8c_i32_i4_e32 v45, v136, v50
	v_dot8c_i32_i4_e32 v38, v131, v53
	v_dot8c_i32_i4_e32 v39, v131, v51
	v_dot8c_i32_i4_e32 v40, v133, v53
	v_dot8c_i32_i4_e32 v41, v133, v51
	v_dot8c_i32_i4_e32 v42, v135, v53
	v_dot8c_i32_i4_e32 v43, v135, v51
	v_dot8c_i32_i4_e32 v44, v137, v53
	v_dot8c_i32_i4_e32 v45, v137, v51
	ds_write_b16 v65, v236
	ds_write_b16_d16_hi v65, v236 offset:128
	ds_write_b16 v65, v237 offset:256
	ds_write_b16_d16_hi v65, v237 offset:384
	ds_write_b16 v65, v238 offset:512
	ds_write_b16_d16_hi v65, v238 offset:640
	ds_write_b16 v65, v239 offset:768
	ds_write_b16_d16_hi v65, v239 offset:896
	ds_write_b16 v65, v240 offset:1024
	ds_write_b16_d16_hi v65, v240 offset:1152
	ds_write_b16 v65, v241 offset:1280
	ds_write_b16_d16_hi v65, v241 offset:1408
	ds_write_b16 v65, v242 offset:1536
	ds_write_b16_d16_hi v65, v242 offset:1664
	ds_write_b16 v65, v243 offset:1792
	ds_write_b16_d16_hi v65, v243 offset:1920
	ds_read_b64 v[202:203], v154
	ds_read_b64 v[204:205], v154 offset:512
	ds_read_b64 v[206:207], v154 offset:1024
	ds_read_b64 v[208:209], v154 offset:1536
	v_and_b32_e32 v78, 0xffff, v25
	v_lshrrev_b32_e32 v79, 16, v25
	v_lshl_add_u32 v78, v78, 7, v152
	v_lshl_add_u32 v79, v79, 7, v153
	s_mov_b32 m0, s77
	s_add_i32 s43, s77, 0x400
	global_load_lds_dwordx4 v78, s[50:51]
	s_mov_b32 m0, s43
	s_nop 0
	global_load_lds_dwordx4 v79, s[50:51]
	s_waitcnt vmcnt(8)
	v_add_u32_e32 v54, s79, v59
	v_add_u32_e32 v55, s79, v60
	v_add_u32_e32 v56, s79, v61
	v_add_u32_e32 v57, s79, v62
	ds_read_b64_tr_b4 v[50:51], v160 offset:384
	ds_read_b64_tr_b4 v[52:53], v160 offset:1408
	ds_read_b64_tr_b4 v[130:131], v54
	ds_read_b64_tr_b4 v[132:133], v55
	ds_read_b64_tr_b4 v[134:135], v56
	ds_read_b64_tr_b4 v[136:137], v57
	s_waitcnt lgkmcnt(15)
	v_dot8c_i32_i4_e32 v38, v122, v48
	v_dot8c_i32_i4_e32 v39, v122, v46
	v_dot8c_i32_i4_e32 v40, v124, v48
	v_dot8c_i32_i4_e32 v41, v124, v46
	v_dot8c_i32_i4_e32 v42, v126, v48
	v_dot8c_i32_i4_e32 v43, v126, v46
	v_dot8c_i32_i4_e32 v44, v128, v48
	v_dot8c_i32_i4_e32 v45, v128, v46
	v_dot8c_i32_i4_e32 v38, v123, v49
	v_dot8c_i32_i4_e32 v39, v123, v47
	v_dot8c_i32_i4_e32 v40, v125, v49
	v_dot8c_i32_i4_e32 v41, v125, v47
	v_dot8c_i32_i4_e32 v42, v127, v49
	v_dot8c_i32_i4_e32 v43, v127, v47
	v_dot8c_i32_i4_e32 v44, v129, v49
	v_dot8c_i32_i4_e32 v45, v129, v47
	s_waitcnt lgkmcnt(15)
	v_and_b32_e32 v78, 0xffff, v26
	v_lshrrev_b32_e32 v79, 16, v26
	v_lshl_add_u32 v78, v78, 7, v152
	v_lshl_add_u32 v79, v79, 7, v153
	s_mov_b32 m0, s78
	s_add_i32 s43, s78, 0x400
	global_load_lds_dwordx4 v78, s[50:51]
	s_mov_b32 m0, s43
	s_nop 0
	global_load_lds_dwordx4 v79, s[50:51]
	s_waitcnt vmcnt(8)
	v_add_u32_e32 v54, s98, v59
	v_add_u32_e32 v55, s98, v60
	v_add_u32_e32 v56, s98, v61
	v_add_u32_e32 v57, s98, v62
	ds_read_b64_tr_b4 v[46:47], v160 offset:512
	ds_read_b64_tr_b4 v[48:49], v160 offset:1536
	ds_read_b64_tr_b4 v[122:123], v54
	ds_read_b64_tr_b4 v[124:125], v55
	ds_read_b64_tr_b4 v[126:127], v56
	ds_read_b64_tr_b4 v[128:129], v57
	s_waitcnt lgkmcnt(6)
	v_dot8c_i32_i4_e32 v38, v130, v52
	v_dot8c_i32_i4_e32 v39, v130, v50
	v_dot8c_i32_i4_e32 v40, v132, v52
	v_dot8c_i32_i4_e32 v41, v132, v50
	v_dot8c_i32_i4_e32 v42, v134, v52
	v_dot8c_i32_i4_e32 v43, v134, v50
	v_dot8c_i32_i4_e32 v44, v136, v52
	v_dot8c_i32_i4_e32 v45, v136, v50
	v_dot8c_i32_i4_e32 v38, v131, v53
	v_dot8c_i32_i4_e32 v39, v131, v51
	v_dot8c_i32_i4_e32 v40, v133, v53
	v_dot8c_i32_i4_e32 v41, v133, v51
	v_dot8c_i32_i4_e32 v42, v135, v53
	v_dot8c_i32_i4_e32 v43, v135, v51
	v_dot8c_i32_i4_e32 v44, v137, v53
	v_dot8c_i32_i4_e32 v45, v137, v51
	v_and_b32_e32 v78, 0xffff, v27
	v_lshrrev_b32_e32 v79, 16, v27
	v_lshl_add_u32 v78, v78, 7, v152
	v_lshl_add_u32 v79, v79, 7, v153
	s_mov_b32 m0, s79
	s_add_i32 s43, s79, 0x400
	global_load_lds_dwordx4 v78, s[50:51]
	s_mov_b32 m0, s43
	s_nop 0
	global_load_lds_dwordx4 v79, s[50:51]
	s_waitcnt vmcnt(8)
	v_add_u32_e32 v54, s99, v59
	v_add_u32_e32 v55, s99, v60
	v_add_u32_e32 v56, s99, v61
	v_add_u32_e32 v57, s99, v62
	ds_read_b64_tr_b4 v[50:51], v160 offset:640
	ds_read_b64_tr_b4 v[52:53], v160 offset:1664
	ds_read_b64_tr_b4 v[130:131], v54
	ds_read_b64_tr_b4 v[132:133], v55
	ds_read_b64_tr_b4 v[134:135], v56
	ds_read_b64_tr_b4 v[136:137], v57
	s_waitcnt lgkmcnt(6)
	v_dot8c_i32_i4_e32 v38, v122, v48
	v_dot8c_i32_i4_e32 v39, v122, v46
	v_dot8c_i32_i4_e32 v40, v124, v48
	v_dot8c_i32_i4_e32 v41, v124, v46
	v_dot8c_i32_i4_e32 v42, v126, v48
	v_dot8c_i32_i4_e32 v43, v126, v46
	v_dot8c_i32_i4_e32 v44, v128, v48
	v_dot8c_i32_i4_e32 v45, v128, v46
	v_dot8c_i32_i4_e32 v38, v123, v49
	v_dot8c_i32_i4_e32 v39, v123, v47
	v_dot8c_i32_i4_e32 v40, v125, v49
	v_dot8c_i32_i4_e32 v41, v125, v47
	v_dot8c_i32_i4_e32 v42, v127, v49
	v_dot8c_i32_i4_e32 v43, v127, v47
	v_dot8c_i32_i4_e32 v44, v129, v49
	v_dot8c_i32_i4_e32 v45, v129, v47
	s_waitcnt lgkmcnt(15)
	v_add_u32_e32 v143, 8, v139
	v_and_b32_e32 v142, 15, v143
	v_xor_b32_e32 v142, 8, v142
	v_bfe_u32 v144, v143, 4, 4
	v_mul_lo_u32 v142, v142, s92
	v_mul_lo_u32 v144, v144, s92
	v_mov_b32_e32 v143, v142
	v_mov_b32_e32 v145, v144
	ds_write2st64_b64 v159, v[142:143], v[144:145] offset1:2
	v_and_b32_e32 v78, 0xffff, v28
	v_lshrrev_b32_e32 v79, 16, v28
	v_lshl_add_u32 v78, v78, 7, v152
	v_lshl_add_u32 v79, v79, 7, v153
	s_mov_b32 m0, s98
	s_add_i32 s43, s98, 0x400
	global_load_lds_dwordx4 v78, s[50:51]
	s_mov_b32 m0, s43
	s_nop 0
	global_load_lds_dwordx4 v79, s[50:51]
	s_waitcnt vmcnt(8)
; __device__ __forceinline__ void peer_v_tokens(int j, const LAS unsigned short* EL, const LAS unsigned char* AL  , const LAS float* ASC  , const LAS int* SAL  , ...
;     ...
;         { unsigned ho = (unsigned)t * (D / 4) + (unsigned)lane; asm volatile("" : "+v"(ho)); const uint2* hp = (const uint2*)HB + ho; const float4* gp = (const float4*)fng + lane;
; #pragma unroll
;           for (int jq = 0; jq < 4; ++jq) { hv[jq] = hp[64 * jq]; gv[jq] = gp[64 * jq]; } }
;         VDMA(0, 0); VDMA(1, 1);
; #pragma unroll
;         for (int m = 0; m < 2; ++m) {
;             const int idx = lane + 64 * m, tau = idx >> 4, sr = idx & 15, k = 16 * (sr & 7) + 2 * tau + (sr >> 3);
;             const int aq = (int)*(const LAS signed char*)(AL + tl * 128 + k); const int tq = aq + 8;
;             const unsigned lo = (((unsigned)tq & 15u) ^ 8u) * 0x11111111u, hi = ((unsigned)(tq >> 4) & 15u) * 0x11111111u;
;             typedef unsigned u2v __attribute__((ext_vector_type(2)));
;             u2v l2; l2.x = lo; l2.y = lo; u2v h2; h2.x = hi; h2.y = hi;
;             *(LAS u2v*)(ATL + 8 * idx) = l2; *(LAS u2v*)(ATL + 1024 + 8 * idx) = h2;
;         }
;         const float asc = ASC[tl]; const int sa = SAL[tl];
;         CFENCE();
;         int accH[4], accL[4];
; #pragma unroll
;         for (int st = 0; st < 16; ++st) {
;             const int p = st >> 2, q = st & 3;
;             if (st < 14) VDMA(st + 2, (st + 2) % 3);
;             if (st < 14) asm volatile("s_waitcnt vmcnt(8)" ::: "memory");
;             else if (st == 14) asm volatile("s_waitcnt vmcnt(4)" ::: "memory");
;             else asm volatile("s_waitcnt vmcnt(0)" ::: "memory");
;             if (q == 0) {
; #pragma unroll
;                 for (int r = 0; r < 4; ++r) { accH[r] = 0; accL[r] = 0; } }
; #pragma unroll
;             for (int tp = 0; tp < 2; ++tp) {
;                 const v2i ao = TR4(ATL + (2 * q + tp) * 128 + 8 * s16), ah = TR4(ATL + 1024 + (2 * q + tp) * 128 + 8 * s16);
; #pragma unroll
;                 for (int r = 0; r < 4; ++r) {
;                     const v2i d = TR4(ldsb + BUF[st % 3] + 2048 * tp + roff[r]);
;                     accH[r] = __builtin_amdgcn_sdot8(d.x, ah.x, accH[r], false); accH[r] = __builtin_amdgcn_sdot8(d.y, ah.y, accH[r], false);
;                     accL[r] = __builtin_amdgcn_sdot8(d.x, ao.x, accL[r], false); accL[r] = __builtin_amdgcn_sdot8(d.y, ao.y, accL[r], false);
	v_add_u32_e32 v54, s76, v59
	v_add_u32_e32 v55, s76, v60
	v_add_u32_e32 v56, s76, v61
	v_add_u32_e32 v57, s76, v62
	ds_read_b64_tr_b4 v[46:47], v160 offset:768
	ds_read_b64_tr_b4 v[48:49], v160 offset:1792
	ds_read_b64_tr_b4 v[122:123], v54
	ds_read_b64_tr_b4 v[124:125], v55
	ds_read_b64_tr_b4 v[126:127], v56
	ds_read_b64_tr_b4 v[128:129], v57
	s_waitcnt lgkmcnt(7)
	v_dot8c_i32_i4_e32 v38, v130, v52
	v_dot8c_i32_i4_e32 v39, v130, v50
	v_dot8c_i32_i4_e32 v40, v132, v52
	v_dot8c_i32_i4_e32 v41, v132, v50
	v_dot8c_i32_i4_e32 v42, v134, v52
	v_dot8c_i32_i4_e32 v43, v134, v50
	v_dot8c_i32_i4_e32 v44, v136, v52
	v_dot8c_i32_i4_e32 v45, v136, v50
	v_dot8c_i32_i4_e32 v38, v131, v53
	v_dot8c_i32_i4_e32 v39, v131, v51
	v_dot8c_i32_i4_e32 v40, v133, v53
	v_dot8c_i32_i4_e32 v41, v133, v51
	v_dot8c_i32_i4_e32 v42, v135, v53
	v_dot8c_i32_i4_e32 v43, v135, v51
	v_dot8c_i32_i4_e32 v44, v137, v53
	v_dot8c_i32_i4_e32 v45, v137, v51
	v_and_b32_e32 v78, 0xffff, v29
	v_lshrrev_b32_e32 v79, 16, v29
	v_lshl_add_u32 v78, v78, 7, v152
	v_lshl_add_u32 v79, v79, 7, v153
	s_mov_b32 m0, s99
	s_add_i32 s43, s99, 0x400
	global_load_lds_dwordx4 v78, s[50:51]
	s_mov_b32 m0, s43
	s_nop 0
	global_load_lds_dwordx4 v79, s[50:51]
	s_waitcnt vmcnt(8)
	v_add_u32_e32 v54, s77, v59
	v_add_u32_e32 v55, s77, v60
	v_add_u32_e32 v56, s77, v61
	v_add_u32_e32 v57, s77, v62
	ds_read_b64_tr_b4 v[50:51], v160 offset:896
	ds_read_b64_tr_b4 v[52:53], v160 offset:1920
	ds_read_b64_tr_b4 v[130:131], v54
	ds_read_b64_tr_b4 v[132:133], v55
	ds_read_b64_tr_b4 v[134:135], v56
	ds_read_b64_tr_b4 v[136:137], v57
	s_waitcnt lgkmcnt(6)
	v_dot8c_i32_i4_e32 v38, v122, v48
	v_dot8c_i32_i4_e32 v39, v122, v46
	v_dot8c_i32_i4_e32 v40, v124, v48
	v_dot8c_i32_i4_e32 v41, v124, v46
	v_dot8c_i32_i4_e32 v42, v126, v48
	v_dot8c_i32_i4_e32 v43, v126, v46
	v_dot8c_i32_i4_e32 v44, v128, v48
	v_dot8c_i32_i4_e32 v45, v128, v46
	v_dot8c_i32_i4_e32 v38, v123, v49
	v_dot8c_i32_i4_e32 v39, v123, v47
	v_dot8c_i32_i4_e32 v40, v125, v49
	v_dot8c_i32_i4_e32 v41, v125, v47
	v_dot8c_i32_i4_e32 v42, v127, v49
	v_dot8c_i32_i4_e32 v43, v127, v47
	v_dot8c_i32_i4_e32 v44, v129, v49
	v_dot8c_i32_i4_e32 v45, v129, v47
	v_and_b32_e32 v78, 0xffff, v30
	v_lshrrev_b32_e32 v79, 16, v30
	v_lshl_add_u32 v78, v78, 7, v152
	v_lshl_add_u32 v79, v79, 7, v153
	s_mov_b32 m0, s76
	s_add_i32 s43, s76, 0x400
	global_load_lds_dwordx4 v78, s[50:51]
	s_mov_b32 m0, s43
	s_nop 0
	global_load_lds_dwordx4 v79, s[50:51]
	s_waitcnt vmcnt(8)
	v_add_u32_e32 v54, s78, v59
	v_add_u32_e32 v55, s78, v60
	v_add_u32_e32 v56, s78, v61
	v_add_u32_e32 v57, s78, v62
	ds_read_b64_tr_b4 v[46:47], v160
	ds_read_b64_tr_b4 v[48:49], v160 offset:1024
	ds_read_b64_tr_b4 v[122:123], v54
	ds_read_b64_tr_b4 v[124:125], v55
	ds_read_b64_tr_b4 v[126:127], v56
	ds_read_b64_tr_b4 v[128:129], v57
	s_waitcnt lgkmcnt(6)
	v_dot8c_i32_i4_e32 v38, v130, v52
	v_dot8c_i32_i4_e32 v39, v130, v50
	v_dot8c_i32_i4_e32 v40, v132, v52
	v_dot8c_i32_i4_e32 v41, v132, v50
	v_dot8c_i32_i4_e32 v42, v134, v52
	v_dot8c_i32_i4_e32 v43, v134, v50
	v_dot8c_i32_i4_e32 v44, v136, v52
	v_dot8c_i32_i4_e32 v45, v136, v50
	v_dot8c_i32_i4_e32 v38, v131, v53
	v_dot8c_i32_i4_e32 v39, v131, v51
	v_dot8c_i32_i4_e32 v40, v133, v53
	v_dot8c_i32_i4_e32 v41, v133, v51
	v_dot8c_i32_i4_e32 v42, v135, v53
	v_dot8c_i32_i4_e32 v43, v135, v51
	v_dot8c_i32_i4_e32 v44, v137, v53
	v_dot8c_i32_i4_e32 v45, v137, v51
	s_nop 3
	s_waitcnt lgkmcnt(15)
	v_lshlrev_b32_e32 v38, 5, v38
	v_lshlrev_b32_e32 v39, 1, v39
	v_add3_u32 v38, v39, v229, v38
	v_cvt_f32_i32_e32 v38, v38
	v_mul_f32_e32 v38, v228, v38
	v_lshlrev_b32_e32 v40, 5, v40
	v_lshlrev_b32_e32 v41, 1, v41
	v_add3_u32 v40, v41, v229, v40
	v_cvt_f32_i32_e32 v40, v40
	v_mul_f32_e32 v40, v228, v40
	v_lshlrev_b32_e32 v42, 5, v42
	v_lshlrev_b32_e32 v43, 1, v43
	v_add3_u32 v42, v43, v229, v42
	v_cvt_f32_i32_e32 v42, v42
	v_mul_f32_e32 v42, v228, v42
	v_lshlrev_b32_e32 v44, 5, v44
	v_lshlrev_b32_e32 v45, 1, v45
	v_add3_u32 v44, v45, v229, v44
	v_cvt_f32_i32_e32 v44, v44
	v_mul_f32_e32 v44, v228, v44
	v_cvt_pk_bf16_f32 v76, v38, v40
	v_cvt_pk_bf16_f32 v157, v42, v44
	s_add_i32 s43, s40, 48
	s_lshl_b32 s43, s43, 11
	v_add_u32_e32 v138, s43, v66
	global_load_dwordx2 v[18:19], v138, s[70:71]
	global_load_dwordx2 v[20:21], v138, s[70:71] offset:512
	global_load_dwordx2 v[22:23], v138, s[70:71] offset:1024
	global_load_dwordx2 v[24:25], v138, s[70:71] offset:1536
	v_add_u32_e32 v147, 8, v140
	v_and_b32_e32 v146, 15, v147
	v_xor_b32_e32 v146, 8, v146
	v_bfe_u32 v148, v147, 4, 4
	v_mul_lo_u32 v146, v146, s92
	v_mul_lo_u32 v148, v148, s92
	v_mov_b32_e32 v147, v146
	v_mov_b32_e32 v149, v148
	ds_write2st64_b64 v77, v[146:147], v[148:149] offset1:2
	s_add_i32 s43, s67, 224
	v_mov_b32_e32 v138, s43
	ds_read2st64_b32 v[228:229], v138 offset1:1
	v_mov_b32_e32 v38, 0
	v_mov_b32_e32 v39, 0
	v_mov_b32_e32 v40, 0
	v_mov_b32_e32 v41, 0
	v_mov_b32_e32 v42, 0
	v_mov_b32_e32 v43, 0
	v_mov_b32_e32 v44, 0
	v_mov_b32_e32 v45, 0
	v_and_b32_e32 v78, 0xffff, v31
	v_lshrrev_b32_e32 v79, 16, v31
	v_lshl_add_u32 v78, v78, 7, v152
	v_lshl_add_u32 v79, v79, 7, v153
	s_mov_b32 m0, s77
	s_add_i32 s43, s77, 0x400
	global_load_lds_dwordx4 v78, s[50:51]
	s_mov_b32 m0, s43
	s_nop 0
	global_load_lds_dwordx4 v79, s[50:51]
	s_waitcnt vmcnt(12)
	v_add_u32_e32 v54, s79, v59
	v_add_u32_e32 v55, s79, v60
	v_add_u32_e32 v56, s79, v61
	v_add_u32_e32 v57, s79, v62
	ds_read_b64_tr_b4 v[50:51], v160 offset:128
	ds_read_b64_tr_b4 v[52:53], v160 offset:1152
	ds_read_b64_tr_b4 v[130:131], v54
	ds_read_b64_tr_b4 v[132:133], v55
	ds_read_b64_tr_b4 v[134:135], v56
	ds_read_b64_tr_b4 v[136:137], v57
	s_waitcnt lgkmcnt(8)
	s_waitcnt vmcnt(38) lgkmcnt(15)
; __device__ __forceinline__ void peer_v_tokens(int j, const LAS unsigned short* EL, const LAS unsigned char* AL  , const LAS float* ASC  , const LAS int* SAL  , ...
;     ...
;         for (int st = 0; st < 16; ++st) {
;             const int p = st >> 2, q = st & 3;
;             if (st < 14) VDMA(st + 2, (st + 2) % 3);
;             if (st < 14) asm volatile("s_waitcnt vmcnt(8)" ::: "memory");
;             else if (st == 14) asm volatile("s_waitcnt vmcnt(4)" ::: "memory");
;             else asm volatile("s_waitcnt vmcnt(0)" ::: "memory");
;             if (q == 0) {
; #pragma unroll
;                 for (int r = 0; r < 4; ++r) { accH[r] = 0; accL[r] = 0; } }
; #pragma unroll
;             for (int tp = 0; tp < 2; ++tp) {
;                 const v2i ao = TR4(ATL + (2 * q + tp) * 128 + 8 * s16), ah = TR4(ATL + 1024 + (2 * q + tp) * 128 + 8 * s16);
; #pragma unroll
;                 for (int r = 0; r < 4; ++r) {
;                     const v2i d = TR4(ldsb + BUF[st % 3] + 2048 * tp + roff[r]);
;                     accH[r] = __builtin_amdgcn_sdot8(d.x, ah.x, accH[r], false); accH[r] = __builtin_amdgcn_sdot8(d.y, ah.y, accH[r], false);
;     ...
;         {
;             float4 v[4]; float ss = 0.f;
; #pragma unroll
;             for (int jq = 0; jq < 4; ++jq) { typedef unsigned u2v __attribute__((ext_vector_type(2))); const u2v pw = *(const LAS u2v*)(STASH + 4 * lane + 256 * jq); const uint2 hw = hv[jq];
;                 v[jq] = make_float4(__uint_as_float(hw.x << 16) + __uint_as_float(pw.x << 16), __uint_as_float(hw.x & 0xffff0000u) + __uint_as_float(pw.x & 0xffff0000u),
;                                     __uint_as_float(hw.y << 16) + __uint_as_float(pw.y << 16), __uint_as_float(hw.y & 0xffff0000u) + __uint_as_float(pw.y & 0xffff0000u));
;                 ss += v[jq].x * v[jq].x + v[jq].y * v[jq].y + v[jq].z * v[jq].z + v[jq].w * v[jq].w; }
;             ss = wave_sum(ss);
;             const float r3 = rsqrtf(ss * (1.f / D) + EPS);
;             float4* op = (float4*)(outp + (size_t)t * D) + lane;
; #pragma unroll
;             for (int jq = 0; jq < 4; ++jq) { typedef float f4v __attribute__((ext_vector_type(4))); f4v o4; o4.x = v[jq].x * r3 * gv[jq].x; o4.y = v[jq].y * r3 * gv[jq].y; o4.z = v[jq].z * r3 * gv[jq].z; o4.w = v[jq].w * r3 * gv[jq].w;
;                 __builtin_nontemporal_store(o4, (f4v*)op + 64 * jq); }
;         }
	v_lshlrev_b32_e32 v210, 16, v194
	v_and_b32_e32 v211, 0xffff0000, v194
	v_lshlrev_b32_e32 v142, 16, v202
	v_and_b32_e32 v143, 0xffff0000, v202
	v_add_f32_e32 v210, v210, v142
	v_add_f32_e32 v211, v211, v143
	v_lshlrev_b32_e32 v212, 16, v195
	v_and_b32_e32 v213, 0xffff0000, v195
	v_lshlrev_b32_e32 v142, 16, v203
	v_and_b32_e32 v143, 0xffff0000, v203
	v_add_f32_e32 v212, v212, v142
	v_add_f32_e32 v213, v213, v143
	v_lshlrev_b32_e32 v214, 16, v196
	v_and_b32_e32 v215, 0xffff0000, v196
	v_lshlrev_b32_e32 v142, 16, v204
	v_and_b32_e32 v143, 0xffff0000, v204
	v_add_f32_e32 v214, v214, v142
	v_add_f32_e32 v215, v215, v143
	v_lshlrev_b32_e32 v216, 16, v197
	v_and_b32_e32 v217, 0xffff0000, v197
	v_lshlrev_b32_e32 v142, 16, v205
	v_and_b32_e32 v143, 0xffff0000, v205
	v_add_f32_e32 v216, v216, v142
	v_add_f32_e32 v217, v217, v143
	v_lshlrev_b32_e32 v218, 16, v198
	v_and_b32_e32 v219, 0xffff0000, v198
	v_lshlrev_b32_e32 v142, 16, v206
	v_and_b32_e32 v143, 0xffff0000, v206
	v_add_f32_e32 v218, v218, v142
	v_add_f32_e32 v219, v219, v143
	v_lshlrev_b32_e32 v220, 16, v199
	v_and_b32_e32 v221, 0xffff0000, v199
	v_lshlrev_b32_e32 v142, 16, v207
	v_and_b32_e32 v143, 0xffff0000, v207
	v_add_f32_e32 v220, v220, v142
	v_add_f32_e32 v221, v221, v143
	v_lshlrev_b32_e32 v222, 16, v200
	v_and_b32_e32 v223, 0xffff0000, v200
	v_lshlrev_b32_e32 v142, 16, v208
	v_and_b32_e32 v143, 0xffff0000, v208
	v_add_f32_e32 v222, v222, v142
	v_add_f32_e32 v223, v223, v143
	v_lshlrev_b32_e32 v224, 16, v201
	v_and_b32_e32 v225, 0xffff0000, v201
	v_lshlrev_b32_e32 v142, 16, v209
	v_and_b32_e32 v143, 0xffff0000, v209
	v_add_f32_e32 v224, v224, v142
	v_add_f32_e32 v225, v225, v143
	v_mov_b32_e32 v144, 0
	v_mul_f32_e32 v145, v210, v210
	v_fmac_f32_e32 v145, v211, v211
	v_fmac_f32_e32 v145, v212, v212
	v_fmac_f32_e32 v145, v213, v213
	v_add_f32_e32 v144, v144, v145
	v_mul_f32_e32 v145, v214, v214
	v_fmac_f32_e32 v145, v215, v215
	v_fmac_f32_e32 v145, v216, v216
	v_fmac_f32_e32 v145, v217, v217
	v_add_f32_e32 v144, v144, v145
	v_mul_f32_e32 v145, v218, v218
	v_fmac_f32_e32 v145, v219, v219
	v_fmac_f32_e32 v145, v220, v220
	v_fmac_f32_e32 v145, v221, v221
	v_add_f32_e32 v144, v144, v145
	v_mul_f32_e32 v145, v222, v222
	v_fmac_f32_e32 v145, v223, v223
	v_fmac_f32_e32 v145, v224, v224
	v_fmac_f32_e32 v145, v225, v225
	v_add_f32_e32 v144, v144, v145
	s_nop 1
	v_add_f32_dpp v144, v144, v144 quad_perm:[1,0,3,2] row_mask:0xf bank_mask:0xf bound_ctrl:1
	s_nop 1
	v_add_f32_dpp v144, v144, v144 quad_perm:[2,3,0,1] row_mask:0xf bank_mask:0xf bound_ctrl:1
	s_nop 1
	v_add_f32_dpp v144, v144, v144 row_half_mirror row_mask:0xf bank_mask:0xf bound_ctrl:1
	s_nop 1
	v_add_f32_dpp v144, v144, v144 row_mirror row_mask:0xf bank_mask:0xf bound_ctrl:1
	s_nop 1
	v_readlane_b32 s10, v144, 0
	v_readlane_b32 s11, v144, 16
	v_readlane_b32 s14, v144, 32
	v_readlane_b32 s15, v144, 48
	s_nop 3
	v_mov_b32_e32 v144, s11
	v_mov_b32_e32 v145, s15
	v_add_f32_e32 v144, s10, v144
	v_add_f32_e32 v145, s14, v145
	v_add_f32_e32 v144, v144, v145
	v_fmamk_f32 v144, v144, 0x3a800000, v111
	v_rsq_f32_e32 v144, v144
	s_nop 0
	v_mul_f32_e32 v210, v210, v144
	v_mul_f32_e32 v211, v211, v144
	v_mul_f32_e32 v212, v212, v144
	v_mul_f32_e32 v213, v213, v144
	v_mul_f32_e32 v214, v214, v144
	v_mul_f32_e32 v215, v215, v144
	v_mul_f32_e32 v216, v216, v144
	v_mul_f32_e32 v217, v217, v144
	v_mul_f32_e32 v218, v218, v144
	v_mul_f32_e32 v219, v219, v144
	v_mul_f32_e32 v220, v220, v144
	v_mul_f32_e32 v221, v221, v144
	v_mul_f32_e32 v222, v222, v144
	v_mul_f32_e32 v223, v223, v144
	v_mul_f32_e32 v224, v224, v144
	v_mul_f32_e32 v225, v225, v144
	s_add_i32 s43, s40, 40
	s_lshl_b32 s43, s43, 11
	v_add_u32_e32 v138, s43, v66
	global_load_dwordx2 v[194:195], v138, s[70:71]
	global_load_dwordx2 v[196:197], v138, s[70:71] offset:512
	global_load_dwordx2 v[198:199], v138, s[70:71] offset:1024
	global_load_dwordx2 v[200:201], v138, s[70:71] offset:1536
	v_dot8c_i32_i4_e32 v38, v122, v48
	v_dot8c_i32_i4_e32 v39, v122, v46
	v_dot8c_i32_i4_e32 v40, v124, v48
	v_dot8c_i32_i4_e32 v41, v124, v46
	v_dot8c_i32_i4_e32 v42, v126, v48
	v_dot8c_i32_i4_e32 v43, v126, v46
	v_dot8c_i32_i4_e32 v44, v128, v48
	v_dot8c_i32_i4_e32 v45, v128, v46
	v_dot8c_i32_i4_e32 v38, v123, v49
	v_dot8c_i32_i4_e32 v39, v123, v47
	v_dot8c_i32_i4_e32 v40, v125, v49
	v_dot8c_i32_i4_e32 v41, v125, v47
	v_dot8c_i32_i4_e32 v42, v127, v49
	v_dot8c_i32_i4_e32 v43, v127, v47
	v_dot8c_i32_i4_e32 v44, v129, v49
	v_dot8c_i32_i4_e32 v45, v129, v47
	v_and_b32_e32 v78, 0xffff, v32
	v_lshrrev_b32_e32 v79, 16, v32
	v_lshl_add_u32 v78, v78, 7, v152
	v_lshl_add_u32 v79, v79, 7, v153
	s_mov_b32 m0, s78
	s_add_i32 s43, s78, 0x400
	global_load_lds_dwordx4 v78, s[50:51]
	s_mov_b32 m0, s43
	s_nop 0
	global_load_lds_dwordx4 v79, s[50:51]
	s_waitcnt vmcnt(16)
	v_add_u32_e32 v54, s98, v59
	v_add_u32_e32 v55, s98, v60
	v_add_u32_e32 v56, s98, v61
	v_add_u32_e32 v57, s98, v62
	ds_read_b64_tr_b4 v[46:47], v160 offset:256
	ds_read_b64_tr_b4 v[48:49], v160 offset:1280
	ds_read_b64_tr_b4 v[122:123], v54
	ds_read_b64_tr_b4 v[124:125], v55
	ds_read_b64_tr_b4 v[126:127], v56
	ds_read_b64_tr_b4 v[128:129], v57
	s_waitcnt lgkmcnt(6)
	v_dot8c_i32_i4_e32 v38, v130, v52
	v_dot8c_i32_i4_e32 v39, v130, v50
	v_dot8c_i32_i4_e32 v40, v132, v52
	v_dot8c_i32_i4_e32 v41, v132, v50
	v_dot8c_i32_i4_e32 v42, v134, v52
	v_dot8c_i32_i4_e32 v43, v134, v50
	v_dot8c_i32_i4_e32 v44, v136, v52
	v_dot8c_i32_i4_e32 v45, v136, v50
	v_dot8c_i32_i4_e32 v38, v131, v53
	v_dot8c_i32_i4_e32 v39, v131, v51
	v_dot8c_i32_i4_e32 v40, v133, v53
	v_dot8c_i32_i4_e32 v41, v133, v51
	v_dot8c_i32_i4_e32 v42, v135, v53
	v_dot8c_i32_i4_e32 v43, v135, v51
	v_dot8c_i32_i4_e32 v44, v137, v53
	v_dot8c_i32_i4_e32 v45, v137, v51
	v_and_b32_e32 v78, 0xffff, v33
	v_lshrrev_b32_e32 v79, 16, v33
	v_lshl_add_u32 v78, v78, 7, v152
	v_lshl_add_u32 v79, v79, 7, v153
	s_mov_b32 m0, s79
	s_add_i32 s43, s79, 0x400
	global_load_lds_dwordx4 v78, s[50:51]
	s_mov_b32 m0, s43
	s_nop 0
	global_load_lds_dwordx4 v79, s[50:51]
	s_waitcnt vmcnt(16)
; #define TR4(p_) __builtin_amdgcn_ds_read_tr4_b64_v2i32((LAS v2i*)(p_))
; #define VDMA(st_, k_) do { _Pragma("unroll") for (int i_ = 0; i_ < 4; ++i_) { \
;         const unsigned off_ = (unsigned)((st_) >> 2) * (16384u * 128u) + (PE_ID(E, 4 * ((st_) & 3) + i_) << 7) + ((i_ & 1) ? cx1 : cx0); \
;         __builtin_amdgcn_global_load_lds((const unsigned*)(V4 + off_), (LAS unsigned*)(ldsb + BUF[k_] + 1024 * i_), 16, 0, 0); } } while (0)
; __device__ __forceinline__ void peer_v_tokens(int j, const LAS unsigned short* EL, const LAS unsigned char* AL  , const LAS float* ASC  , const LAS int* SAL  , ...
;     ...
;         for (int st = 0; st < 16; ++st) {
;             const int p = st >> 2, q = st & 3;
;             if (st < 14) VDMA(st + 2, (st + 2) % 3);
;             if (st < 14) asm volatile("s_waitcnt vmcnt(8)" ::: "memory");
;             else if (st == 14) asm volatile("s_waitcnt vmcnt(4)" ::: "memory");
;             else asm volatile("s_waitcnt vmcnt(0)" ::: "memory");
;             if (q == 0) {
; #pragma unroll
;                 for (int r = 0; r < 4; ++r) { accH[r] = 0; accL[r] = 0; } }
; #pragma unroll
;             for (int tp = 0; tp < 2; ++tp) {
;                 const v2i ao = TR4(ATL + (2 * q + tp) * 128 + 8 * s16), ah = TR4(ATL + 1024 + (2 * q + tp) * 128 + 8 * s16);
; #pragma unroll
;                 for (int r = 0; r < 4; ++r) {
;                     const v2i d = TR4(ldsb + BUF[st % 3] + 2048 * tp + roff[r]);
;                     accH[r] = __builtin_amdgcn_sdot8(d.x, ah.x, accH[r], false); accH[r] = __builtin_amdgcn_sdot8(d.y, ah.y, accH[r], false);
;                     accL[r] = __builtin_amdgcn_sdot8(d.x, ao.x, accL[r], false); accL[r] = __builtin_amdgcn_sdot8(d.y, ao.y, accL[r], false);
;                 }
;             }
;             asm volatile("s_waitcnt lgkmcnt(0)" ::: "memory");
	v_add_u32_e32 v54, s99, v59
	v_add_u32_e32 v55, s99, v60
	v_add_u32_e32 v56, s99, v61
	v_add_u32_e32 v57, s99, v62
	ds_read_b64_tr_b4 v[50:51], v160 offset:384
	ds_read_b64_tr_b4 v[52:53], v160 offset:1408
	ds_read_b64_tr_b4 v[130:131], v54
	ds_read_b64_tr_b4 v[132:133], v55
	ds_read_b64_tr_b4 v[134:135], v56
	ds_read_b64_tr_b4 v[136:137], v57
	s_waitcnt lgkmcnt(6)
	v_dot8c_i32_i4_e32 v38, v122, v48
	v_dot8c_i32_i4_e32 v39, v122, v46
	v_dot8c_i32_i4_e32 v40, v124, v48
	v_dot8c_i32_i4_e32 v41, v124, v46
	v_dot8c_i32_i4_e32 v42, v126, v48
	v_dot8c_i32_i4_e32 v43, v126, v46
	v_dot8c_i32_i4_e32 v44, v128, v48
	v_dot8c_i32_i4_e32 v45, v128, v46
	v_dot8c_i32_i4_e32 v38, v123, v49
	v_dot8c_i32_i4_e32 v39, v123, v47
	v_dot8c_i32_i4_e32 v40, v125, v49
	v_dot8c_i32_i4_e32 v41, v125, v47
	v_dot8c_i32_i4_e32 v42, v127, v49
	v_dot8c_i32_i4_e32 v43, v127, v47
	v_dot8c_i32_i4_e32 v44, v129, v49
	v_dot8c_i32_i4_e32 v45, v129, v47
	s_waitcnt vmcnt(14)
	v_add_u32_e32 v54, s76, v59
	v_add_u32_e32 v55, s76, v60
	v_add_u32_e32 v56, s76, v61
	v_add_u32_e32 v57, s76, v62
	ds_read_b64_tr_b4 v[46:47], v160 offset:512
	ds_read_b64_tr_b4 v[48:49], v160 offset:1536
	ds_read_b64_tr_b4 v[122:123], v54
	ds_read_b64_tr_b4 v[124:125], v55
	ds_read_b64_tr_b4 v[126:127], v56
	ds_read_b64_tr_b4 v[128:129], v57
	s_waitcnt lgkmcnt(6)
	v_dot8c_i32_i4_e32 v38, v130, v52
	v_dot8c_i32_i4_e32 v39, v130, v50
	v_dot8c_i32_i4_e32 v40, v132, v52
	v_dot8c_i32_i4_e32 v41, v132, v50
	v_dot8c_i32_i4_e32 v42, v134, v52
	v_dot8c_i32_i4_e32 v43, v134, v50
	v_dot8c_i32_i4_e32 v44, v136, v52
	v_dot8c_i32_i4_e32 v45, v136, v50
	v_dot8c_i32_i4_e32 v38, v131, v53
	v_dot8c_i32_i4_e32 v39, v131, v51
	v_dot8c_i32_i4_e32 v40, v133, v53
	v_dot8c_i32_i4_e32 v41, v133, v51
	v_dot8c_i32_i4_e32 v42, v135, v53
	v_dot8c_i32_i4_e32 v43, v135, v51
	v_dot8c_i32_i4_e32 v44, v137, v53
	v_dot8c_i32_i4_e32 v45, v137, v51
	s_waitcnt vmcnt(8)
	v_add_u32_e32 v54, s77, v59
	v_add_u32_e32 v55, s77, v60
	v_add_u32_e32 v56, s77, v61
	v_add_u32_e32 v57, s77, v62
	ds_read_b64_tr_b4 v[50:51], v160 offset:640
	ds_read_b64_tr_b4 v[52:53], v160 offset:1664
	ds_read_b64_tr_b4 v[130:131], v54
	ds_read_b64_tr_b4 v[132:133], v55
	ds_read_b64_tr_b4 v[134:135], v56
	ds_read_b64_tr_b4 v[136:137], v57
	s_waitcnt lgkmcnt(6)
	v_dot8c_i32_i4_e32 v38, v122, v48
	v_dot8c_i32_i4_e32 v39, v122, v46
	v_dot8c_i32_i4_e32 v40, v124, v48
	v_dot8c_i32_i4_e32 v41, v124, v46
	v_dot8c_i32_i4_e32 v42, v126, v48
	v_dot8c_i32_i4_e32 v43, v126, v46
	v_dot8c_i32_i4_e32 v44, v128, v48
	v_dot8c_i32_i4_e32 v45, v128, v46
	v_dot8c_i32_i4_e32 v38, v123, v49
	v_dot8c_i32_i4_e32 v39, v123, v47
	v_dot8c_i32_i4_e32 v40, v125, v49
	v_dot8c_i32_i4_e32 v41, v125, v47
	v_dot8c_i32_i4_e32 v42, v127, v49
	v_dot8c_i32_i4_e32 v43, v127, v47
	v_dot8c_i32_i4_e32 v44, v129, v49
	v_dot8c_i32_i4_e32 v45, v129, v47
	s_waitcnt vmcnt(2)
	v_add_u32_e32 v54, s78, v59
	v_add_u32_e32 v55, s78, v60
	v_add_u32_e32 v56, s78, v61
	v_add_u32_e32 v57, s78, v62
	ds_read_b64_tr_b4 v[46:47], v160 offset:768
	ds_read_b64_tr_b4 v[48:49], v160 offset:1792
	ds_read_b64_tr_b4 v[122:123], v54
	ds_read_b64_tr_b4 v[124:125], v55
	ds_read_b64_tr_b4 v[126:127], v56
	ds_read_b64_tr_b4 v[128:129], v57
	s_waitcnt lgkmcnt(6)
	v_dot8c_i32_i4_e32 v38, v130, v52
	v_dot8c_i32_i4_e32 v39, v130, v50
	v_dot8c_i32_i4_e32 v40, v132, v52
	v_dot8c_i32_i4_e32 v41, v132, v50
	v_dot8c_i32_i4_e32 v42, v134, v52
	v_dot8c_i32_i4_e32 v43, v134, v50
	v_dot8c_i32_i4_e32 v44, v136, v52
	v_dot8c_i32_i4_e32 v45, v136, v50
	v_dot8c_i32_i4_e32 v38, v131, v53
	v_dot8c_i32_i4_e32 v39, v131, v51
	v_dot8c_i32_i4_e32 v40, v133, v53
	v_dot8c_i32_i4_e32 v41, v133, v51
	v_dot8c_i32_i4_e32 v42, v135, v53
	v_dot8c_i32_i4_e32 v43, v135, v51
	v_dot8c_i32_i4_e32 v44, v137, v53
	v_dot8c_i32_i4_e32 v45, v137, v51
	s_waitcnt vmcnt(0)
	v_add_u32_e32 v54, s79, v59
	v_add_u32_e32 v55, s79, v60
	v_add_u32_e32 v56, s79, v61
	v_add_u32_e32 v57, s79, v62
	ds_read_b64_tr_b4 v[50:51], v160 offset:896
	ds_read_b64_tr_b4 v[52:53], v160 offset:1920
	ds_read_b64_tr_b4 v[130:131], v54
	ds_read_b64_tr_b4 v[132:133], v55
	ds_read_b64_tr_b4 v[134:135], v56
	ds_read_b64_tr_b4 v[136:137], v57
	s_waitcnt lgkmcnt(6)
	v_dot8c_i32_i4_e32 v38, v122, v48
	v_dot8c_i32_i4_e32 v39, v122, v46
	v_dot8c_i32_i4_e32 v40, v124, v48
	v_dot8c_i32_i4_e32 v41, v124, v46
	v_dot8c_i32_i4_e32 v42, v126, v48
	v_dot8c_i32_i4_e32 v43, v126, v46
	v_dot8c_i32_i4_e32 v44, v128, v48
	v_dot8c_i32_i4_e32 v45, v128, v46
	v_dot8c_i32_i4_e32 v38, v123, v49
	v_dot8c_i32_i4_e32 v39, v123, v47
	v_dot8c_i32_i4_e32 v40, v125, v49
	v_dot8c_i32_i4_e32 v41, v125, v47
	v_dot8c_i32_i4_e32 v42, v127, v49
	v_dot8c_i32_i4_e32 v43, v127, v47
	v_dot8c_i32_i4_e32 v44, v129, v49
	v_dot8c_i32_i4_e32 v45, v129, v47
	s_waitcnt lgkmcnt(0)
	v_dot8c_i32_i4_e32 v38, v130, v52
	v_dot8c_i32_i4_e32 v39, v130, v50
	v_dot8c_i32_i4_e32 v40, v132, v52
	v_dot8c_i32_i4_e32 v41, v132, v50
	v_dot8c_i32_i4_e32 v42, v134, v52
	v_dot8c_i32_i4_e32 v43, v134, v50
	v_dot8c_i32_i4_e32 v44, v136, v52
	v_dot8c_i32_i4_e32 v45, v136, v50
	v_dot8c_i32_i4_e32 v38, v131, v53
	v_dot8c_i32_i4_e32 v39, v131, v51
	v_dot8c_i32_i4_e32 v40, v133, v53
	v_dot8c_i32_i4_e32 v41, v133, v51
	v_dot8c_i32_i4_e32 v42, v135, v53
	v_dot8c_i32_i4_e32 v43, v135, v51
	v_dot8c_i32_i4_e32 v44, v137, v53
	v_dot8c_i32_i4_e32 v45, v137, v51
	s_nop 3
	s_waitcnt lgkmcnt(15)
; #define LAS __attribute__((address_space(3)))
; __device__ __forceinline__ bf16 f2bf(float f) { return (bf16)f2bfu(f); }
; #define CFENCE() asm volatile("" ::: "memory")
; __device__ __forceinline__ void peer_v_tokens(int j, const LAS unsigned short* EL, const LAS unsigned char* AL  , const LAS float* ASC  , const LAS int* SAL  , ...
;     ...
;             if (q == 3) {
; #pragma unroll
;                 for (int r = 0; r < 4; ++r) STASH[256 * p + 16 * (grp + 4 * r) + pc] = f2bf(asc * (float)(2 * ((accH[r] << 4) + accL[r]) + sa));
;             }
;         }
;         CFENCE();
;         {
;             float4 v[4]; float ss = 0.f;
; #pragma unroll
;             for (int jq = 0; jq < 4; ++jq) { typedef unsigned u2v __attribute__((ext_vector_type(2))); const u2v pw = *(const LAS u2v*)(STASH + 4 * lane + 256 * jq); const uint2 hw = hv[jq];
;                 v[jq] = make_float4(__uint_as_float(hw.x << 16) + __uint_as_float(pw.x << 16), __uint_as_float(hw.x & 0xffff0000u) + __uint_as_float(pw.x & 0xffff0000u),
;                                     __uint_as_float(hw.y << 16) + __uint_as_float(pw.y << 16), __uint_as_float(hw.y & 0xffff0000u) + __uint_as_float(pw.y & 0xffff0000u));
;                 ss += v[jq].x * v[jq].x + v[jq].y * v[jq].y + v[jq].z * v[jq].z + v[jq].w * v[jq].w; }
;             ss = wave_sum(ss);
;             const float r3 = rsqrtf(ss * (1.f / D) + EPS);
;             float4* op = (float4*)(outp + (size_t)t * D) + lane;
; #pragma unroll
;             for (int jq = 0; jq < 4; ++jq) { typedef float f4v __attribute__((ext_vector_type(4))); f4v o4; o4.x = v[jq].x * r3 * gv[jq].x; o4.y = v[jq].y * r3 * gv[jq].y; o4.z = v[jq].z * r3 * gv[jq].z; o4.w = v[jq].w * r3 * gv[jq].w;
;                 __builtin_nontemporal_store(o4, (f4v*)op + 64 * jq); }
;         }
	v_lshlrev_b32_e32 v38, 5, v38
	v_lshlrev_b32_e32 v39, 1, v39
	v_add3_u32 v38, v39, v229, v38
	v_cvt_f32_i32_e32 v38, v38
	v_mul_f32_e32 v38, v228, v38
	v_lshlrev_b32_e32 v40, 5, v40
	v_lshlrev_b32_e32 v41, 1, v41
	v_add3_u32 v40, v41, v229, v40
	v_cvt_f32_i32_e32 v40, v40
	v_mul_f32_e32 v40, v228, v40
	v_lshlrev_b32_e32 v42, 5, v42
	v_lshlrev_b32_e32 v43, 1, v43
	v_add3_u32 v42, v43, v229, v42
	v_cvt_f32_i32_e32 v42, v42
	v_mul_f32_e32 v42, v228, v42
	v_lshlrev_b32_e32 v44, 5, v44
	v_lshlrev_b32_e32 v45, 1, v45
	v_add3_u32 v44, v45, v229, v44
	v_cvt_f32_i32_e32 v44, v44
	v_mul_f32_e32 v44, v228, v44
	v_cvt_pk_bf16_f32 v233, v38, v40
	v_cvt_pk_bf16_f32 v234, v42, v44
	s_add_i32 s43, s40, 56
	s_lshl_b32 s43, s43, 11
	v_add_u32_e32 v138, s43, v66
	global_load_dwordx2 v[122:123], v138, s[70:71]
	global_load_dwordx2 v[124:125], v138, s[70:71] offset:512
	global_load_dwordx2 v[126:127], v138, s[70:71] offset:1024
	global_load_dwordx2 v[128:129], v138, s[70:71] offset:1536
	ds_read_b128 v[252:255], v155
	s_add_i32 s44, s40, 32
	s_ashr_i32 s45, s44, 31
	s_lshl_b64 s[44:45], s[44:45], 12
	v_lshl_add_u64 v[80:81], v[36:37], 0, s[44:45]
	s_waitcnt lgkmcnt(0)
	v_mul_f32_e32 v210, v210, v252
	v_mul_f32_e32 v211, v211, v253
	v_mul_f32_e32 v212, v212, v254
	v_mul_f32_e32 v213, v213, v255
	global_store_dwordx4 v[80:81], v[210:213], off nt
	ds_read_b128 v[252:255], v155 offset:1024
	s_add_i32 s44, s40, 32
	s_ashr_i32 s45, s44, 31
	s_lshl_b64 s[44:45], s[44:45], 12
	v_lshl_add_u64 v[80:81], v[36:37], 0, s[44:45]
	s_waitcnt lgkmcnt(0)
	v_mul_f32_e32 v214, v214, v252
	v_mul_f32_e32 v215, v215, v253
	v_mul_f32_e32 v216, v216, v254
	v_mul_f32_e32 v217, v217, v255
	global_store_dwordx4 v[80:81], v[214:217], off offset:1024 nt
	ds_read_b128 v[252:255], v156
	s_add_i32 s44, s40, 32
	s_ashr_i32 s45, s44, 31
	s_lshl_b64 s[44:45], s[44:45], 12
	v_lshl_add_u64 v[80:81], v[36:37], 0, s[44:45]
	s_waitcnt lgkmcnt(0)
	v_mul_f32_e32 v218, v218, v252
	v_mul_f32_e32 v219, v219, v253
	v_mul_f32_e32 v220, v220, v254
	v_mul_f32_e32 v221, v221, v255
	global_store_dwordx4 v[80:81], v[218:221], off offset:2048 nt
	ds_read_b128 v[252:255], v156 offset:1024
	s_add_i32 s44, s40, 32
	s_ashr_i32 s45, s44, 31
	s_lshl_b64 s[44:45], s[44:45], 12
	v_lshl_add_u64 v[80:81], v[36:37], 0, s[44:45]
	s_waitcnt lgkmcnt(0)
	v_mul_f32_e32 v222, v222, v252
	v_mul_f32_e32 v223, v223, v253
	v_mul_f32_e32 v224, v224, v254
	v_mul_f32_e32 v225, v225, v255
	global_store_dwordx4 v[80:81], v[222:225], off offset:3072 nt
	ds_write_b16 v65, v244
	ds_write_b16_d16_hi v65, v244 offset:128
	ds_write_b16 v65, v245 offset:256
	ds_write_b16_d16_hi v65, v245 offset:384
	ds_write_b16 v65, v246 offset:512
	ds_write_b16_d16_hi v65, v246 offset:640
	ds_write_b16 v65, v247 offset:768
	ds_write_b16_d16_hi v65, v247 offset:896
	ds_write_b16 v65, v248 offset:1024
	ds_write_b16_d16_hi v65, v248 offset:1152
	ds_write_b16 v65, v249 offset:1280
	ds_write_b16_d16_hi v65, v249 offset:1408
	ds_write_b16 v65, v250 offset:1536
	ds_write_b16_d16_hi v65, v250 offset:1664
	ds_write_b16 v65, v251 offset:1792
	ds_write_b16_d16_hi v65, v251 offset:1920
	ds_read_b64 v[202:203], v154
	ds_read_b64 v[204:205], v154 offset:512
	ds_read_b64 v[206:207], v154 offset:1024
	ds_read_b64 v[208:209], v154 offset:1536
	s_waitcnt vmcnt(12) lgkmcnt(0)
	v_lshlrev_b32_e32 v210, 16, v194
	v_and_b32_e32 v211, 0xffff0000, v194
	v_lshlrev_b32_e32 v142, 16, v202
	v_and_b32_e32 v143, 0xffff0000, v202
	v_add_f32_e32 v210, v210, v142
	v_add_f32_e32 v211, v211, v143
	v_lshlrev_b32_e32 v212, 16, v195
	v_and_b32_e32 v213, 0xffff0000, v195
	v_lshlrev_b32_e32 v142, 16, v203
	v_and_b32_e32 v143, 0xffff0000, v203
	v_add_f32_e32 v212, v212, v142
	v_add_f32_e32 v213, v213, v143
	v_lshlrev_b32_e32 v214, 16, v196
	v_and_b32_e32 v215, 0xffff0000, v196
	v_lshlrev_b32_e32 v142, 16, v204
	v_and_b32_e32 v143, 0xffff0000, v204
	v_add_f32_e32 v214, v214, v142
	v_add_f32_e32 v215, v215, v143
	v_lshlrev_b32_e32 v216, 16, v197
	v_and_b32_e32 v217, 0xffff0000, v197
	v_lshlrev_b32_e32 v142, 16, v205
	v_and_b32_e32 v143, 0xffff0000, v205
	v_add_f32_e32 v216, v216, v142
	v_add_f32_e32 v217, v217, v143
	v_lshlrev_b32_e32 v218, 16, v198
	v_and_b32_e32 v219, 0xffff0000, v198
	v_lshlrev_b32_e32 v142, 16, v206
	v_and_b32_e32 v143, 0xffff0000, v206
	v_add_f32_e32 v218, v218, v142
	v_add_f32_e32 v219, v219, v143
	v_lshlrev_b32_e32 v220, 16, v199
	v_and_b32_e32 v221, 0xffff0000, v199
	v_lshlrev_b32_e32 v142, 16, v207
	v_and_b32_e32 v143, 0xffff0000, v207
	v_add_f32_e32 v220, v220, v142
	v_add_f32_e32 v221, v221, v143
	v_lshlrev_b32_e32 v222, 16, v200
	v_and_b32_e32 v223, 0xffff0000, v200
	v_lshlrev_b32_e32 v142, 16, v208
	v_and_b32_e32 v143, 0xffff0000, v208
	v_add_f32_e32 v222, v222, v142
	v_add_f32_e32 v223, v223, v143
	v_lshlrev_b32_e32 v224, 16, v201
	v_and_b32_e32 v225, 0xffff0000, v201
	v_lshlrev_b32_e32 v142, 16, v209
	v_and_b32_e32 v143, 0xffff0000, v209
	v_add_f32_e32 v224, v224, v142
	v_add_f32_e32 v225, v225, v143
	v_mov_b32_e32 v144, 0
	v_mul_f32_e32 v145, v210, v210
	v_fmac_f32_e32 v145, v211, v211
	v_fmac_f32_e32 v145, v212, v212
	v_fmac_f32_e32 v145, v213, v213
	v_add_f32_e32 v144, v144, v145
	v_mul_f32_e32 v145, v214, v214
	v_fmac_f32_e32 v145, v215, v215
	v_fmac_f32_e32 v145, v216, v216
	v_fmac_f32_e32 v145, v217, v217
	v_add_f32_e32 v144, v144, v145
	v_mul_f32_e32 v145, v218, v218
	v_fmac_f32_e32 v145, v219, v219
	v_fmac_f32_e32 v145, v220, v220
	v_fmac_f32_e32 v145, v221, v221
	v_add_f32_e32 v144, v144, v145
	v_mul_f32_e32 v145, v222, v222
	v_fmac_f32_e32 v145, v223, v223
	v_fmac_f32_e32 v145, v224, v224
	v_fmac_f32_e32 v145, v225, v225
	v_add_f32_e32 v144, v144, v145
; #define LAS __attribute__((address_space(3)))
; __device__ __forceinline__ bf16 f2bf(float f) { return (bf16)f2bfu(f); }
; #define CFENCE() asm volatile("" ::: "memory")
; __device__ __forceinline__ void peer_v_tokens(int j, const LAS unsigned short* EL, const LAS unsigned char* AL  , const LAS float* ASC  , const LAS int* SAL  , ...
;     ...
;                 for (int r = 0; r < 4; ++r) STASH[256 * p + 16 * (grp + 4 * r) + pc] = f2bf(asc * (float)(2 * ((accH[r] << 4) + accL[r]) + sa));
;             }
;         }
;         CFENCE();
;         {
;             float4 v[4]; float ss = 0.f;
; #pragma unroll
;             for (int jq = 0; jq < 4; ++jq) { typedef unsigned u2v __attribute__((ext_vector_type(2))); const u2v pw = *(const LAS u2v*)(STASH + 4 * lane + 256 * jq); const uint2 hw = hv[jq];
;                 v[jq] = make_float4(__uint_as_float(hw.x << 16) + __uint_as_float(pw.x << 16), __uint_as_float(hw.x & 0xffff0000u) + __uint_as_float(pw.x & 0xffff0000u),
;                                     __uint_as_float(hw.y << 16) + __uint_as_float(pw.y << 16), __uint_as_float(hw.y & 0xffff0000u) + __uint_as_float(pw.y & 0xffff0000u));
;                 ss += v[jq].x * v[jq].x + v[jq].y * v[jq].y + v[jq].z * v[jq].z + v[jq].w * v[jq].w; }
;             ss = wave_sum(ss);
;             const float r3 = rsqrtf(ss * (1.f / D) + EPS);
;             float4* op = (float4*)(outp + (size_t)t * D) + lane;
; #pragma unroll
;             for (int jq = 0; jq < 4; ++jq) { typedef float f4v __attribute__((ext_vector_type(4))); f4v o4; o4.x = v[jq].x * r3 * gv[jq].x; o4.y = v[jq].y * r3 * gv[jq].y; o4.z = v[jq].z * r3 * gv[jq].z; o4.w = v[jq].w * r3 * gv[jq].w;
;                 __builtin_nontemporal_store(o4, (f4v*)op + 64 * jq); }
;         }
	s_nop 1
	v_add_f32_dpp v144, v144, v144 quad_perm:[1,0,3,2] row_mask:0xf bank_mask:0xf bound_ctrl:1
	s_nop 1
	v_add_f32_dpp v144, v144, v144 quad_perm:[2,3,0,1] row_mask:0xf bank_mask:0xf bound_ctrl:1
	s_nop 1
	v_add_f32_dpp v144, v144, v144 row_half_mirror row_mask:0xf bank_mask:0xf bound_ctrl:1
	s_nop 1
	v_add_f32_dpp v144, v144, v144 row_mirror row_mask:0xf bank_mask:0xf bound_ctrl:1
	s_nop 1
	v_readlane_b32 s10, v144, 0
	v_readlane_b32 s11, v144, 16
	v_readlane_b32 s14, v144, 32
	v_readlane_b32 s15, v144, 48
	s_nop 3
	v_mov_b32_e32 v144, s11
	v_mov_b32_e32 v145, s15
	v_add_f32_e32 v144, s10, v144
	v_add_f32_e32 v145, s14, v145
	v_add_f32_e32 v144, v144, v145
	v_fmamk_f32 v144, v144, 0x3a800000, v111
	v_rsq_f32_e32 v144, v144
	s_nop 0
	v_mul_f32_e32 v210, v210, v144
	v_mul_f32_e32 v211, v211, v144
	v_mul_f32_e32 v212, v212, v144
	v_mul_f32_e32 v213, v213, v144
	v_mul_f32_e32 v214, v214, v144
	v_mul_f32_e32 v215, v215, v144
	v_mul_f32_e32 v216, v216, v144
	v_mul_f32_e32 v217, v217, v144
	v_mul_f32_e32 v218, v218, v144
	v_mul_f32_e32 v219, v219, v144
	v_mul_f32_e32 v220, v220, v144
	v_mul_f32_e32 v221, v221, v144
	v_mul_f32_e32 v222, v222, v144
	v_mul_f32_e32 v223, v223, v144
	v_mul_f32_e32 v224, v224, v144
	v_mul_f32_e32 v225, v225, v144
	ds_read_b128 v[252:255], v155
	s_add_i32 s44, s40, 40
	s_ashr_i32 s45, s44, 31
	s_lshl_b64 s[44:45], s[44:45], 12
	v_lshl_add_u64 v[80:81], v[36:37], 0, s[44:45]
	s_waitcnt lgkmcnt(0)
	v_mul_f32_e32 v210, v210, v252
	v_mul_f32_e32 v211, v211, v253
	v_mul_f32_e32 v212, v212, v254
	v_mul_f32_e32 v213, v213, v255
	global_store_dwordx4 v[80:81], v[210:213], off nt
	ds_read_b128 v[252:255], v155 offset:1024
	s_add_i32 s44, s40, 40
	s_ashr_i32 s45, s44, 31
	s_lshl_b64 s[44:45], s[44:45], 12
	v_lshl_add_u64 v[80:81], v[36:37], 0, s[44:45]
	s_waitcnt lgkmcnt(0)
	v_mul_f32_e32 v214, v214, v252
	v_mul_f32_e32 v215, v215, v253
	v_mul_f32_e32 v216, v216, v254
	v_mul_f32_e32 v217, v217, v255
	global_store_dwordx4 v[80:81], v[214:217], off offset:1024 nt
	ds_read_b128 v[252:255], v156
	s_add_i32 s44, s40, 40
	s_ashr_i32 s45, s44, 31
	s_lshl_b64 s[44:45], s[44:45], 12
	v_lshl_add_u64 v[80:81], v[36:37], 0, s[44:45]
	s_waitcnt lgkmcnt(0)
	v_mul_f32_e32 v218, v218, v252
	v_mul_f32_e32 v219, v219, v253
	v_mul_f32_e32 v220, v220, v254
	v_mul_f32_e32 v221, v221, v255
	global_store_dwordx4 v[80:81], v[218:221], off offset:2048 nt
	ds_read_b128 v[252:255], v156 offset:1024
	s_add_i32 s44, s40, 40
	s_ashr_i32 s45, s44, 31
	s_lshl_b64 s[44:45], s[44:45], 12
	v_lshl_add_u64 v[80:81], v[36:37], 0, s[44:45]
	s_waitcnt lgkmcnt(0)
	v_mul_f32_e32 v222, v222, v252
	v_mul_f32_e32 v223, v223, v253
	v_mul_f32_e32 v224, v224, v254
	v_mul_f32_e32 v225, v225, v255
	global_store_dwordx4 v[80:81], v[222:225], off offset:3072 nt
	ds_write_b16 v65, v67
	ds_write_b16_d16_hi v65, v67 offset:128
	ds_write_b16 v65, v68 offset:256
	ds_write_b16_d16_hi v65, v68 offset:384
	ds_write_b16 v65, v69 offset:512
	ds_write_b16_d16_hi v65, v69 offset:640
	ds_write_b16 v65, v70 offset:768
	ds_write_b16_d16_hi v65, v70 offset:896
	ds_write_b16 v65, v71 offset:1024
	ds_write_b16_d16_hi v65, v71 offset:1152
	ds_write_b16 v65, v72 offset:1280
	ds_write_b16_d16_hi v65, v72 offset:1408
	ds_write_b16 v65, v76 offset:1536
	ds_write_b16_d16_hi v65, v76 offset:1664
	ds_write_b16 v65, v157 offset:1792
	ds_write_b16_d16_hi v65, v157 offset:1920
	ds_read_b64 v[202:203], v154
	ds_read_b64 v[204:205], v154 offset:512
	ds_read_b64 v[206:207], v154 offset:1024
	ds_read_b64 v[208:209], v154 offset:1536
	s_waitcnt vmcnt(22) lgkmcnt(0)
	v_lshlrev_b32_e32 v210, 16, v18
	v_and_b32_e32 v211, 0xffff0000, v18
	v_lshlrev_b32_e32 v142, 16, v202
	v_and_b32_e32 v143, 0xffff0000, v202
	v_add_f32_e32 v210, v210, v142
	v_add_f32_e32 v211, v211, v143
	v_lshlrev_b32_e32 v212, 16, v19
	v_and_b32_e32 v213, 0xffff0000, v19
	v_lshlrev_b32_e32 v142, 16, v203
	v_and_b32_e32 v143, 0xffff0000, v203
	v_add_f32_e32 v212, v212, v142
	v_add_f32_e32 v213, v213, v143
	v_lshlrev_b32_e32 v214, 16, v20
	v_and_b32_e32 v215, 0xffff0000, v20
	v_lshlrev_b32_e32 v142, 16, v204
	v_and_b32_e32 v143, 0xffff0000, v204
	v_add_f32_e32 v214, v214, v142
	v_add_f32_e32 v215, v215, v143
	v_lshlrev_b32_e32 v216, 16, v21
	v_and_b32_e32 v217, 0xffff0000, v21
	v_lshlrev_b32_e32 v142, 16, v205
	v_and_b32_e32 v143, 0xffff0000, v205
	v_add_f32_e32 v216, v216, v142
	v_add_f32_e32 v217, v217, v143
	v_lshlrev_b32_e32 v218, 16, v22
	v_and_b32_e32 v219, 0xffff0000, v22
	v_lshlrev_b32_e32 v142, 16, v206
	v_and_b32_e32 v143, 0xffff0000, v206
	v_add_f32_e32 v218, v218, v142
	v_add_f32_e32 v219, v219, v143
	v_lshlrev_b32_e32 v220, 16, v23
	v_and_b32_e32 v221, 0xffff0000, v23
	v_lshlrev_b32_e32 v142, 16, v207
	v_and_b32_e32 v143, 0xffff0000, v207
	v_add_f32_e32 v220, v220, v142
	v_add_f32_e32 v221, v221, v143
	v_lshlrev_b32_e32 v222, 16, v24
	v_and_b32_e32 v223, 0xffff0000, v24
	v_lshlrev_b32_e32 v142, 16, v208
	v_and_b32_e32 v143, 0xffff0000, v208
	v_add_f32_e32 v222, v222, v142
	v_add_f32_e32 v223, v223, v143
	v_lshlrev_b32_e32 v224, 16, v25
	v_and_b32_e32 v225, 0xffff0000, v25
	v_lshlrev_b32_e32 v142, 16, v209
	v_and_b32_e32 v143, 0xffff0000, v209
	v_add_f32_e32 v224, v224, v142
	v_add_f32_e32 v225, v225, v143
	v_mov_b32_e32 v144, 0
	v_mul_f32_e32 v145, v210, v210
	v_fmac_f32_e32 v145, v211, v211
	v_fmac_f32_e32 v145, v212, v212
	v_fmac_f32_e32 v145, v213, v213
	v_add_f32_e32 v144, v144, v145
	v_mul_f32_e32 v145, v214, v214
	v_fmac_f32_e32 v145, v215, v215
	v_fmac_f32_e32 v145, v216, v216
	v_fmac_f32_e32 v145, v217, v217
	v_add_f32_e32 v144, v144, v145
	v_mul_f32_e32 v145, v218, v218
	v_fmac_f32_e32 v145, v219, v219
; #define LAS __attribute__((address_space(3)))
; __device__ __forceinline__ bf16 f2bf(float f) { return (bf16)f2bfu(f); }
; #define CFENCE() asm volatile("" ::: "memory")
; __device__ __forceinline__ void peer_v_tokens(int j, const LAS unsigned short* EL, const LAS unsigned char* AL  , const LAS float* ASC  , const LAS int* SAL  , ...
;     ...
;                 for (int r = 0; r < 4; ++r) STASH[256 * p + 16 * (grp + 4 * r) + pc] = f2bf(asc * (float)(2 * ((accH[r] << 4) + accL[r]) + sa));
;             }
;         }
;         CFENCE();
;         {
;             float4 v[4]; float ss = 0.f;
; #pragma unroll
;             for (int jq = 0; jq < 4; ++jq) { typedef unsigned u2v __attribute__((ext_vector_type(2))); const u2v pw = *(const LAS u2v*)(STASH + 4 * lane + 256 * jq); const uint2 hw = hv[jq];
;                 v[jq] = make_float4(__uint_as_float(hw.x << 16) + __uint_as_float(pw.x << 16), __uint_as_float(hw.x & 0xffff0000u) + __uint_as_float(pw.x & 0xffff0000u),
;                                     __uint_as_float(hw.y << 16) + __uint_as_float(pw.y << 16), __uint_as_float(hw.y & 0xffff0000u) + __uint_as_float(pw.y & 0xffff0000u));
;                 ss += v[jq].x * v[jq].x + v[jq].y * v[jq].y + v[jq].z * v[jq].z + v[jq].w * v[jq].w; }
;             ss = wave_sum(ss);
;             const float r3 = rsqrtf(ss * (1.f / D) + EPS);
;             float4* op = (float4*)(outp + (size_t)t * D) + lane;
; #pragma unroll
;             for (int jq = 0; jq < 4; ++jq) { typedef float f4v __attribute__((ext_vector_type(4))); f4v o4; o4.x = v[jq].x * r3 * gv[jq].x; o4.y = v[jq].y * r3 * gv[jq].y; o4.z = v[jq].z * r3 * gv[jq].z; o4.w = v[jq].w * r3 * gv[jq].w;
;                 __builtin_nontemporal_store(o4, (f4v*)op + 64 * jq); }
;         }
	v_fmac_f32_e32 v145, v220, v220
	v_fmac_f32_e32 v145, v221, v221
	v_add_f32_e32 v144, v144, v145
	v_mul_f32_e32 v145, v222, v222
	v_fmac_f32_e32 v145, v223, v223
	v_fmac_f32_e32 v145, v224, v224
	v_fmac_f32_e32 v145, v225, v225
	v_add_f32_e32 v144, v144, v145
	s_nop 1
	v_add_f32_dpp v144, v144, v144 quad_perm:[1,0,3,2] row_mask:0xf bank_mask:0xf bound_ctrl:1
	s_nop 1
	v_add_f32_dpp v144, v144, v144 quad_perm:[2,3,0,1] row_mask:0xf bank_mask:0xf bound_ctrl:1
	s_nop 1
	v_add_f32_dpp v144, v144, v144 row_half_mirror row_mask:0xf bank_mask:0xf bound_ctrl:1
	s_nop 1
	v_add_f32_dpp v144, v144, v144 row_mirror row_mask:0xf bank_mask:0xf bound_ctrl:1
	s_nop 1
	v_readlane_b32 s10, v144, 0
	v_readlane_b32 s11, v144, 16
	v_readlane_b32 s14, v144, 32
	v_readlane_b32 s15, v144, 48
	s_nop 3
	v_mov_b32_e32 v144, s11
	v_mov_b32_e32 v145, s15
	v_add_f32_e32 v144, s10, v144
	v_add_f32_e32 v145, s14, v145
	v_add_f32_e32 v144, v144, v145
	v_fmamk_f32 v144, v144, 0x3a800000, v111
	v_rsq_f32_e32 v144, v144
	s_nop 0
	v_mul_f32_e32 v210, v210, v144
	v_mul_f32_e32 v211, v211, v144
	v_mul_f32_e32 v212, v212, v144
	v_mul_f32_e32 v213, v213, v144
	v_mul_f32_e32 v214, v214, v144
	v_mul_f32_e32 v215, v215, v144
	v_mul_f32_e32 v216, v216, v144
	v_mul_f32_e32 v217, v217, v144
	v_mul_f32_e32 v218, v218, v144
	v_mul_f32_e32 v219, v219, v144
	v_mul_f32_e32 v220, v220, v144
	v_mul_f32_e32 v221, v221, v144
	v_mul_f32_e32 v222, v222, v144
	v_mul_f32_e32 v223, v223, v144
	v_mul_f32_e32 v224, v224, v144
	v_mul_f32_e32 v225, v225, v144
	ds_read_b128 v[252:255], v155
	s_add_i32 s44, s40, 48
	s_ashr_i32 s45, s44, 31
	s_lshl_b64 s[44:45], s[44:45], 12
	v_lshl_add_u64 v[80:81], v[36:37], 0, s[44:45]
	s_waitcnt lgkmcnt(0)
	v_mul_f32_e32 v210, v210, v252
	v_mul_f32_e32 v211, v211, v253
	v_mul_f32_e32 v212, v212, v254
	v_mul_f32_e32 v213, v213, v255
	global_store_dwordx4 v[80:81], v[210:213], off nt
	ds_read_b128 v[252:255], v155 offset:1024
	s_add_i32 s44, s40, 48
	s_ashr_i32 s45, s44, 31
	s_lshl_b64 s[44:45], s[44:45], 12
	v_lshl_add_u64 v[80:81], v[36:37], 0, s[44:45]
	s_waitcnt lgkmcnt(0)
	v_mul_f32_e32 v214, v214, v252
	v_mul_f32_e32 v215, v215, v253
	v_mul_f32_e32 v216, v216, v254
	v_mul_f32_e32 v217, v217, v255
	global_store_dwordx4 v[80:81], v[214:217], off offset:1024 nt
	ds_read_b128 v[252:255], v156
	s_add_i32 s44, s40, 48
	s_ashr_i32 s45, s44, 31
	s_lshl_b64 s[44:45], s[44:45], 12
	v_lshl_add_u64 v[80:81], v[36:37], 0, s[44:45]
	s_waitcnt lgkmcnt(0)
	v_mul_f32_e32 v218, v218, v252
	v_mul_f32_e32 v219, v219, v253
	v_mul_f32_e32 v220, v220, v254
	v_mul_f32_e32 v221, v221, v255
	global_store_dwordx4 v[80:81], v[218:221], off offset:2048 nt
	ds_read_b128 v[252:255], v156 offset:1024
	s_add_i32 s44, s40, 48
	s_ashr_i32 s45, s44, 31
	s_lshl_b64 s[44:45], s[44:45], 12
	v_lshl_add_u64 v[80:81], v[36:37], 0, s[44:45]
	s_waitcnt lgkmcnt(0)
	v_mul_f32_e32 v222, v222, v252
	v_mul_f32_e32 v223, v223, v253
	v_mul_f32_e32 v224, v224, v254
	v_mul_f32_e32 v225, v225, v255
	global_store_dwordx4 v[80:81], v[222:225], off offset:3072 nt
	ds_write_b16 v65, v158
	ds_write_b16_d16_hi v65, v158 offset:128
	ds_write_b16 v65, v161 offset:256
	ds_write_b16_d16_hi v65, v161 offset:384
	ds_write_b16 v65, v226 offset:512
	ds_write_b16_d16_hi v65, v226 offset:640
	ds_write_b16 v65, v230 offset:768
	ds_write_b16_d16_hi v65, v230 offset:896
	ds_write_b16 v65, v231 offset:1024
	ds_write_b16_d16_hi v65, v231 offset:1152
	ds_write_b16 v65, v232 offset:1280
	ds_write_b16_d16_hi v65, v232 offset:1408
	ds_write_b16 v65, v233 offset:1536
	ds_write_b16_d16_hi v65, v233 offset:1664
	ds_write_b16 v65, v234 offset:1792
	ds_write_b16_d16_hi v65, v234 offset:1920
	ds_read_b64 v[202:203], v154
	ds_read_b64 v[204:205], v154 offset:512
	ds_read_b64 v[206:207], v154 offset:1024
	ds_read_b64 v[208:209], v154 offset:1536
	s_waitcnt vmcnt(12) lgkmcnt(0)
; #define LAS __attribute__((address_space(3)))
; __device__ __forceinline__ void peer_v_tokens(int j, const LAS unsigned short* EL, const LAS unsigned char* AL  , const LAS float* ASC  , const LAS int* SAL  , ...
;     ...
;         {
;             float4 v[4]; float ss = 0.f;
; #pragma unroll
;             for (int jq = 0; jq < 4; ++jq) { typedef unsigned u2v __attribute__((ext_vector_type(2))); const u2v pw = *(const LAS u2v*)(STASH + 4 * lane + 256 * jq); const uint2 hw = hv[jq];
;                 v[jq] = make_float4(__uint_as_float(hw.x << 16) + __uint_as_float(pw.x << 16), __uint_as_float(hw.x & 0xffff0000u) + __uint_as_float(pw.x & 0xffff0000u),
;                                     __uint_as_float(hw.y << 16) + __uint_as_float(pw.y << 16), __uint_as_float(hw.y & 0xffff0000u) + __uint_as_float(pw.y & 0xffff0000u));
;                 ss += v[jq].x * v[jq].x + v[jq].y * v[jq].y + v[jq].z * v[jq].z + v[jq].w * v[jq].w; }
;             ss = wave_sum(ss);
;             const float r3 = rsqrtf(ss * (1.f / D) + EPS);
;             float4* op = (float4*)(outp + (size_t)t * D) + lane;
; #pragma unroll
;             for (int jq = 0; jq < 4; ++jq) { typedef float f4v __attribute__((ext_vector_type(4))); f4v o4; o4.x = v[jq].x * r3 * gv[jq].x; o4.y = v[jq].y * r3 * gv[jq].y; o4.z = v[jq].z * r3 * gv[jq].z; o4.w = v[jq].w * r3 * gv[jq].w;
;                 __builtin_nontemporal_store(o4, (f4v*)op + 64 * jq); }
;         }
	v_lshlrev_b32_e32 v210, 16, v122
	v_and_b32_e32 v211, 0xffff0000, v122
	v_lshlrev_b32_e32 v142, 16, v202
	v_and_b32_e32 v143, 0xffff0000, v202
	v_add_f32_e32 v210, v210, v142
	v_add_f32_e32 v211, v211, v143
	v_lshlrev_b32_e32 v212, 16, v123
	v_and_b32_e32 v213, 0xffff0000, v123
	v_lshlrev_b32_e32 v142, 16, v203
	v_and_b32_e32 v143, 0xffff0000, v203
	v_add_f32_e32 v212, v212, v142
	v_add_f32_e32 v213, v213, v143
	v_lshlrev_b32_e32 v214, 16, v124
	v_and_b32_e32 v215, 0xffff0000, v124
	v_lshlrev_b32_e32 v142, 16, v204
	v_and_b32_e32 v143, 0xffff0000, v204
	v_add_f32_e32 v214, v214, v142
	v_add_f32_e32 v215, v215, v143
	v_lshlrev_b32_e32 v216, 16, v125
	v_and_b32_e32 v217, 0xffff0000, v125
	v_lshlrev_b32_e32 v142, 16, v205
	v_and_b32_e32 v143, 0xffff0000, v205
	v_add_f32_e32 v216, v216, v142
	v_add_f32_e32 v217, v217, v143
	v_lshlrev_b32_e32 v218, 16, v126
	v_and_b32_e32 v219, 0xffff0000, v126
	v_lshlrev_b32_e32 v142, 16, v206
	v_and_b32_e32 v143, 0xffff0000, v206
	v_add_f32_e32 v218, v218, v142
	v_add_f32_e32 v219, v219, v143
	v_lshlrev_b32_e32 v220, 16, v127
	v_and_b32_e32 v221, 0xffff0000, v127
	v_lshlrev_b32_e32 v142, 16, v207
	v_and_b32_e32 v143, 0xffff0000, v207
	v_add_f32_e32 v220, v220, v142
	v_add_f32_e32 v221, v221, v143
	v_lshlrev_b32_e32 v222, 16, v128
	v_and_b32_e32 v223, 0xffff0000, v128
	v_lshlrev_b32_e32 v142, 16, v208
	v_and_b32_e32 v143, 0xffff0000, v208
	v_add_f32_e32 v222, v222, v142
	v_add_f32_e32 v223, v223, v143
	v_lshlrev_b32_e32 v224, 16, v129
	v_and_b32_e32 v225, 0xffff0000, v129
	v_lshlrev_b32_e32 v142, 16, v209
	v_and_b32_e32 v143, 0xffff0000, v209
	v_add_f32_e32 v224, v224, v142
	v_add_f32_e32 v225, v225, v143
	v_mov_b32_e32 v144, 0
	v_mul_f32_e32 v145, v210, v210
	v_fmac_f32_e32 v145, v211, v211
	v_fmac_f32_e32 v145, v212, v212
	v_fmac_f32_e32 v145, v213, v213
	v_add_f32_e32 v144, v144, v145
	v_mul_f32_e32 v145, v214, v214
	v_fmac_f32_e32 v145, v215, v215
	v_fmac_f32_e32 v145, v216, v216
	v_fmac_f32_e32 v145, v217, v217
	v_add_f32_e32 v144, v144, v145
	v_mul_f32_e32 v145, v218, v218
	v_fmac_f32_e32 v145, v219, v219
	v_fmac_f32_e32 v145, v220, v220
	v_fmac_f32_e32 v145, v221, v221
	v_add_f32_e32 v144, v144, v145
	v_mul_f32_e32 v145, v222, v222
	v_fmac_f32_e32 v145, v223, v223
	v_fmac_f32_e32 v145, v224, v224
	v_fmac_f32_e32 v145, v225, v225
	v_add_f32_e32 v144, v144, v145
	s_nop 1
	v_add_f32_dpp v144, v144, v144 quad_perm:[1,0,3,2] row_mask:0xf bank_mask:0xf bound_ctrl:1
	s_nop 1
	v_add_f32_dpp v144, v144, v144 quad_perm:[2,3,0,1] row_mask:0xf bank_mask:0xf bound_ctrl:1
	s_nop 1
	v_add_f32_dpp v144, v144, v144 row_half_mirror row_mask:0xf bank_mask:0xf bound_ctrl:1
	s_nop 1
	v_add_f32_dpp v144, v144, v144 row_mirror row_mask:0xf bank_mask:0xf bound_ctrl:1
	s_nop 1
	v_readlane_b32 s10, v144, 0
	v_readlane_b32 s11, v144, 16
	v_readlane_b32 s14, v144, 32
	v_readlane_b32 s15, v144, 48
	s_nop 3
	v_mov_b32_e32 v144, s11
	v_mov_b32_e32 v145, s15
	v_add_f32_e32 v144, s10, v144
	v_add_f32_e32 v145, s14, v145
	v_add_f32_e32 v144, v144, v145
	v_fmamk_f32 v144, v144, 0x3a800000, v111
	v_rsq_f32_e32 v144, v144
	s_nop 0
	v_mul_f32_e32 v210, v210, v144
	v_mul_f32_e32 v211, v211, v144
	v_mul_f32_e32 v212, v212, v144
	v_mul_f32_e32 v213, v213, v144
	v_mul_f32_e32 v214, v214, v144
	v_mul_f32_e32 v215, v215, v144
	v_mul_f32_e32 v216, v216, v144
	v_mul_f32_e32 v217, v217, v144
	v_mul_f32_e32 v218, v218, v144
	v_mul_f32_e32 v219, v219, v144
	v_mul_f32_e32 v220, v220, v144
	v_mul_f32_e32 v221, v221, v144
	v_mul_f32_e32 v222, v222, v144
	v_mul_f32_e32 v223, v223, v144
	v_mul_f32_e32 v224, v224, v144
	v_mul_f32_e32 v225, v225, v144
	ds_read_b128 v[252:255], v155
	s_add_i32 s44, s40, 56
	s_ashr_i32 s45, s44, 31
	s_lshl_b64 s[44:45], s[44:45], 12
	v_lshl_add_u64 v[80:81], v[36:37], 0, s[44:45]
	s_waitcnt lgkmcnt(0)
	v_mul_f32_e32 v210, v210, v252
	v_mul_f32_e32 v211, v211, v253
	v_mul_f32_e32 v212, v212, v254
	v_mul_f32_e32 v213, v213, v255
	global_store_dwordx4 v[80:81], v[210:213], off nt
	ds_read_b128 v[252:255], v155 offset:1024
	s_add_i32 s44, s40, 56
	s_ashr_i32 s45, s44, 31
	s_lshl_b64 s[44:45], s[44:45], 12
	v_lshl_add_u64 v[80:81], v[36:37], 0, s[44:45]
	s_waitcnt lgkmcnt(0)
	v_mul_f32_e32 v214, v214, v252
	v_mul_f32_e32 v215, v215, v253
	v_mul_f32_e32 v216, v216, v254
	v_mul_f32_e32 v217, v217, v255
	global_store_dwordx4 v[80:81], v[214:217], off offset:1024 nt
	ds_read_b128 v[252:255], v156
	s_add_i32 s44, s40, 56
	s_ashr_i32 s45, s44, 31
	s_lshl_b64 s[44:45], s[44:45], 12
	v_lshl_add_u64 v[80:81], v[36:37], 0, s[44:45]
	s_waitcnt lgkmcnt(0)
	v_mul_f32_e32 v218, v218, v252
	v_mul_f32_e32 v219, v219, v253
	v_mul_f32_e32 v220, v220, v254
	v_mul_f32_e32 v221, v221, v255
	global_store_dwordx4 v[80:81], v[218:221], off offset:2048 nt
	ds_read_b128 v[252:255], v156 offset:1024
	s_add_i32 s44, s40, 56
	s_ashr_i32 s45, s44, 31
	s_lshl_b64 s[44:45], s[44:45], 12
	v_lshl_add_u64 v[80:81], v[36:37], 0, s[44:45]
	s_waitcnt lgkmcnt(0)
	v_mul_f32_e32 v222, v222, v252
	v_mul_f32_e32 v223, v223, v253
	v_mul_f32_e32 v224, v224, v254
	v_mul_f32_e32 v225, v225, v255
	global_store_dwordx4 v[80:81], v[222:225], off offset:3072 nt
	s_add_i32 s2, s2, s33
	s_add_i32 s40, s40, s63
	s_add_i32 s73, s73, s74
	s_cmpk_lt_i32 s2, 0x100
	s_cbranch_scc1 .LBB0_648
